# speedup vs baseline: 1.0067x; 1.0004x over previous
; #define WAIT_V(n) asm volatile("s_waitcnt vmcnt(" #n ")" ::: "memory")
; #define BAR __builtin_amdgcn_s_barrier()
;     ...
;     if (wr == 1) BAR;
;     if (first_tile) { WAIT_V(0); }
;     else if constexpr (mode == MODE_RESID_LN) { WAIT_V(0); }
;     else if constexpr (mode == MODE_SWIGLU) { WAIT_V(6); }
;     else if constexpr (mode == MODE_V) { WAIT_V(24); }
;     else { WAIT_V(12); }
;     first_tile = false;
;     BAR;
.LBB0_143:
	s_or_b64 exec, exec, s[6:7]
	s_xor_b64 s[6:7], s[4:5], -1
	s_mov_b64 s[4:5], -1
	s_and_b64 vcc, exec, s[6:7]
	s_cbranch_vccz .LBB0_145
	s_waitcnt vmcnt(12)
	s_mov_b64 s[4:5], 0

;     ...
;       const int tid3 = opaque_tid(wave);
;       const int wr3 = tid3 >> 8, wc3 = (tid3 >> 6) & 3, fr3 = tid3 & 15, fq3 = (tid3 & 63) >> 4;
;       const int ebase3 = (brow + wr3 * 64 + fr3) * DM + pn * BM + wc3 * 32 + fq3 * 4;
;       const int vo4b = ebase3 * 4, vo2 = ebase3 * 2, vo1 = ebase3;
;       (void)vo4b; (void)vo2; (void)vo1;
;       if constexpr (OUTF) {
;         _Pragma("unroll") for (int bj = 0; bj < 2; ++bj) _Pragma("unroll") for (int n = 0; n < 2; ++n) {
;           const int col = pn * BM + bj * HALF + wc3 * 32 + n * 16 + fq3 * 4;
;           const float4 gm = *reinterpret_cast<const float4*>(g.gam + col), bt = *reinterpret_cast<const float4*>(g.bet + col);
;           _Pragma("unroll") for (int ai = 0; ai < 2; ++ai) _Pragma("unroll") for (int m = 0; m < 4; ++m) {
;             const int rl = ai * HALF + wr3 * 64 + m * 16 + fr3;
;             const float2 ms = *reinterpret_cast<const float2*>(mr + rl * 2);
;             f32x4 y = acc[ai][bj][m][n];
;             u32x4 o;
;             o[0] = __float_as_uint((y[0] - ms.x) * ms.y * gm.x + bt.x); o[1] = __float_as_uint((y[1] - ms.x) * ms.y * gm.y + bt.y);
;             o[2] = __float_as_uint((y[2] - ms.x) * ms.y * gm.z + bt.z); o[3] = __float_as_uint((y[3] - ms.x) * ms.y * gm.w + bt.w);
;             __builtin_amdgcn_raw_buffer_store_b128(o, rsO, vo4b + ((ai * HALF + m * 16) * DM + bj * HALF + n * 16) * 4, 0, 0);
;           }
;         }
;       } else {
;         constexpr int PIECE = 1024 + 16, LOBASE = 64 * PIECE;
;         const int lane3 = tid3 & 63;
;         const int hvo = (lane3 >> 5) * (DM * 2) + (lane3 & 31) * 16;
;         const int lvo = (lane3 >> 4) * DM + (lane3 & 15) * 16;
;         _Pragma("unroll") for (int ai = 0; ai < 2; ++ai) {
;           _Pragma("unroll") for (int bj = 0; bj < 2; ++bj) _Pragma("unroll") for (int n = 0; n < 2; ++n) {
;             const int cc = bj * HALF + wc3 * 32 + n * 16 + fq3 * 4;
;             const float4 gm = *reinterpret_cast<const float4*>(g.gam + pn * BM + cc), bt = *reinterpret_cast<const float4*>(g.bet + pn * BM + cc);
;             _Pragma("unroll") for (int m = 0; m < 4; ++m) {
;               const int rr = wr3 * 64 + m * 16 + fr3;
;               const float2 ms = *reinterpret_cast<const float2*>(mr + (ai * HALF + rr) * 2);
;               f32x4 y = acc[ai][bj][m][n];
.LBB0_177:
	s_or_b64 exec, exec, s[6:7]
	s_waitcnt lgkmcnt(0)
	s_barrier
	v_mbcnt_lo_u32_b32 v0, -1, 0
	v_mbcnt_hi_u32_b32 v0, -1, v0
	s_movk_i32 s4, 0x1000
	v_add_u32_e32 v1, s29, v0
	v_ashrrev_i32_e32 v5, 2, v1
	v_lshrrev_b32_e32 v6, 1, v1
	v_lshlrev_b32_e32 v1, 4, v1
	v_lshlrev_b32_e32 v12, 7, v0
	v_and_b32_e32 v13, 0x1f0, v1
	v_and_b32_e32 v2, 15, v0
	v_and_or_b32 v70, v12, s4, v13
	s_lshl_b32 s4, s0, 8
	s_movk_i32 s0, 0xffc0
	v_and_or_b32 v97, v5, s0, v2
	s_lshl_b32 s0, s18, 19
	v_bfe_u32 v4, v0, 4, 2
	s_ashr_i32 s5, s4, 31
	s_add_i32 s0, s0, s42
	v_lshlrev_b32_e32 v7, 2, v4
	s_add_i32 s0, s0, s4
	s_lshl_b64 s[4:5], s[4:5], 2
	v_and_or_b32 v12, v6, s61, v7
	s_add_u32 s6, s78, s4
	v_and_b32_e32 v3, 63, v0
	v_and_b32_e32 v1, 0xf0, v1
	v_lshlrev_b32_e32 v13, 9, v0
	v_lshlrev_b32_e32 v0, 8, v0
	s_addc_u32 s7, s79, s5
	v_lshlrev_b32_e32 v72, 2, v12
	v_lshl_or_b32 v68, v4, 11, v1
	v_and_b32_e32 v14, 0x300, v0
	v_lshlrev_b32_e32 v74, 4, v3
	global_load_dwordx4 v[196:199], v72, s[6:7]
	global_load_dwordx4 v[200:203], v72, s[6:7] offset:64
	global_load_dwordx4 v[204:207], v72, s[6:7] offset:512
	global_load_dwordx4 v[208:211], v72, s[6:7] offset:576
	s_add_u32 s4, s80, s4
	s_addc_u32 s5, s81, s5
	global_load_dwordx4 v[212:215], v72, s[4:5]
	global_load_dwordx4 v[220:223], v72, s[4:5] offset:64
	global_load_dwordx4 v[240:243], v72, s[4:5] offset:512
	global_load_dwordx4 v[248:251], v72, s[4:5] offset:576
	v_lshl_add_u32 v71, v97, 3, v246
	s_mov_b32 s18, 0x10400
	v_lshrrev_b32_e32 v67, 1, v97
	v_mul_lo_u32 v105, v67, s68
	v_add_u32_e32 v69, s59, v74
	s_lshl_b32 s22, s0, 1
	s_mov_b32 s23, s75
	s_andn2_b64 vcc, exec, s[14:15]
	s_waitcnt vmcnt(0)
	v_mov_b32_e32 v0, v196
	v_mov_b32_e32 v1, v197
	v_mov_b32_e32 v2, v198
	v_mov_b32_e32 v3, v199
	v_mov_b32_e32 v4, v212
	v_mov_b32_e32 v5, v213
	v_mov_b32_e32 v6, v214
	v_mov_b32_e32 v7, v215
	v_mov_b32_e32 v22, v1
	v_lshlrev_b32_e32 v1, 1, v12
	v_mov_b32_e32 v23, v2
	v_and_or_b32 v109, v13, s66, v1
	v_or3_b32 v2, v14, v12, s18
	ds_read_b64 v[12:13], v71
	v_mov_b32_e32 v64, v5
	v_mov_b32_e32 v65, v6
	v_mov_b32_e32 v1, v3
	v_mov_b32_e32 v5, v7
	s_waitcnt lgkmcnt(0)
	v_pk_add_f32 v[14:15], v[238:239], v[12:13] op_sel_hi:[1,0] neg_lo:[0,1] neg_hi:[0,1]
	v_pk_add_f32 v[20:21], v[236:237], v[12:13] op_sel_hi:[1,0] neg_lo:[0,1] neg_hi:[0,1]
	v_pk_mul_f32 v[14:15], v[12:13], v[14:15] op_sel:[1,0]
	v_pk_mul_f32 v[12:13], v[12:13], v[20:21] op_sel:[1,0]
	v_pk_fma_f32 v[14:15], v[22:23], v[14:15], v[64:65]
	v_pk_fma_f32 v[6:7], v[0:1], v[12:13], v[4:5]
	v_and_b32_sdwa v12, v14, v244 dst_sel:DWORD dst_unused:UNUSED_PAD src0_sel:WORD_1 src1_sel:DWORD
	v_add3_u32 v12, v14, v12, s67
	v_and_b32_e32 v20, 0xffff0000, v12
	v_and_b32_sdwa v12, v7, v244 dst_sel:DWORD dst_unused:UNUSED_PAD src0_sel:WORD_1 src1_sel:DWORD
	v_and_b32_sdwa v3, v15, v244 dst_sel:DWORD dst_unused:UNUSED_PAD src0_sel:WORD_1 src1_sel:DWORD
	v_and_b32_sdwa v13, v6, v244 dst_sel:DWORD dst_unused:UNUSED_PAD src0_sel:WORD_1 src1_sel:DWORD
	v_add3_u32 v12, v7, v12, s67
	v_add3_u32 v3, v15, v3, s67
	v_add3_u32 v21, v6, v13, s67
	v_and_b32_e32 v66, 0xffff0000, v12
	v_or_b32_sdwa v13, v66, v3 dst_sel:DWORD dst_unused:UNUSED_PAD src0_sel:DWORD src1_sel:WORD_1
	v_or_b32_sdwa v12, v21, v20 dst_sel:DWORD dst_unused:UNUSED_PAD src0_sel:WORD_1 src1_sel:DWORD
	v_add_u32_e32 v73, v109, v105
	ds_write_b64 v73, v[12:13]
	v_and_b32_e32 v12, 0xffff0000, v21
	v_sub_u32_e32 v6, v6, v12
	v_sub_u32_e32 v12, v14, v20
	v_and_b32_e32 v3, 0xffff0000, v3
	v_add_u32_e32 v12, 0x80, v12
	v_sub_u32_e32 v3, v15, v3
	v_sub_u32_e32 v7, v7, v66
	v_add_u32_e32 v6, 0x80, v6
	v_ashrrev_i32_e32 v12, 8, v12
	v_add_u32_e32 v3, 0x80, v3
	v_add_u32_e32 v7, 0x80, v7
	v_ashrrev_i32_e32 v6, 8, v6
	v_min_i32_e32 v12, 0x7f, v12
	v_ashrrev_i32_e32 v3, 8, v3
	v_ashrrev_i32_e32 v7, 8, v7
	v_min_i32_e32 v6, 0x7f, v6
	v_min_i32_sdwa v3, v3, s69 dst_sel:WORD_1 dst_unused:UNUSED_PAD src0_sel:DWORD src1_sel:DWORD
	v_min_i32_e32 v7, 0x7f, v7
	v_lshlrev_b32_e32 v12, 8, v12
	v_and_b32_e32 v12, 0xff00, v12
	v_and_b32_e32 v3, 0xff0000, v3
	v_perm_b32 v6, v7, v6, s76
	v_or3_b32 v3, v6, v12, v3
	v_lshrrev_b32_e32 v6, 2, v97
	v_mad_u64_u32 v[12:13], s[18:19], v6, s68, v[2:3]
	ds_write_b32 v12, v3
	v_or_b32_e32 v3, 16, v97
	v_lshl_add_u32 v13, v3, 3, v246
	ds_read_b64 v[6:7], v13
	v_lshrrev_b32_e32 v75, 1, v3
	v_mul_lo_u32 v106, v75, s68
	v_add_u32_e32 v75, v109, v106
	v_lshrrev_b32_e32 v3, 2, v3
	s_waitcnt lgkmcnt(0)
	v_pk_add_f32 v[14:15], v[218:219], v[6:7] op_sel_hi:[1,0] neg_lo:[0,1] neg_hi:[0,1]
	v_pk_add_f32 v[20:21], v[216:217], v[6:7] op_sel_hi:[1,0] neg_lo:[0,1] neg_hi:[0,1]
	v_pk_mul_f32 v[14:15], v[6:7], v[14:15] op_sel:[1,0]
	v_pk_mul_f32 v[6:7], v[6:7], v[20:21] op_sel:[1,0]
	v_pk_fma_f32 v[14:15], v[22:23], v[14:15], v[64:65]
	v_pk_fma_f32 v[6:7], v[0:1], v[6:7], v[4:5]
	v_and_b32_sdwa v20, v15, v244 dst_sel:DWORD dst_unused:UNUSED_PAD src0_sel:WORD_1 src1_sel:DWORD
	v_and_b32_sdwa v21, v14, v244 dst_sel:DWORD dst_unused:UNUSED_PAD src0_sel:WORD_1 src1_sel:DWORD
	v_add3_u32 v66, v15, v20, s67
	v_add3_u32 v20, v14, v21, s67
	v_and_b32_e32 v67, 0xffff0000, v20
	v_and_b32_sdwa v20, v7, v244 dst_sel:DWORD dst_unused:UNUSED_PAD src0_sel:WORD_1 src1_sel:DWORD
	v_and_b32_sdwa v21, v6, v244 dst_sel:DWORD dst_unused:UNUSED_PAD src0_sel:WORD_1 src1_sel:DWORD
	v_add3_u32 v20, v7, v20, s67
	v_add3_u32 v96, v6, v21, s67
	v_and_b32_e32 v98, 0xffff0000, v20
	v_or_b32_sdwa v21, v98, v66 dst_sel:DWORD dst_unused:UNUSED_PAD src0_sel:DWORD src1_sel:WORD_1
	v_or_b32_sdwa v20, v96, v67 dst_sel:DWORD dst_unused:UNUSED_PAD src0_sel:WORD_1 src1_sel:DWORD
	ds_write_b64 v75, v[20:21]
	v_and_b32_e32 v20, 0xffff0000, v96
	v_sub_u32_e32 v6, v6, v20
	v_sub_u32_e32 v14, v14, v67
	v_and_b32_e32 v20, 0xffff0000, v66
	v_add_u32_e32 v14, 0x80, v14
	v_sub_u32_e32 v15, v15, v20
	v_sub_u32_e32 v7, v7, v98
	v_add_u32_e32 v6, 0x80, v6
	v_ashrrev_i32_e32 v14, 8, v14
	v_add_u32_e32 v15, 0x80, v15
	v_add_u32_e32 v7, 0x80, v7
	v_ashrrev_i32_e32 v6, 8, v6
	v_min_i32_e32 v14, 0x7f, v14
	v_ashrrev_i32_e32 v15, 8, v15
	v_ashrrev_i32_e32 v7, 8, v7
	v_min_i32_e32 v6, 0x7f, v6
	v_min_i32_sdwa v15, v15, s69 dst_sel:WORD_1 dst_unused:UNUSED_PAD src0_sel:DWORD src1_sel:DWORD
	v_min_i32_e32 v7, 0x7f, v7
	v_lshlrev_b32_e32 v14, 8, v14
	v_and_b32_e32 v14, 0xff00, v14
	v_and_b32_e32 v15, 0xff0000, v15
	v_perm_b32 v6, v7, v6, s76
	v_or3_b32 v6, v6, v14, v15
	v_mad_u64_u32 v[14:15], s[18:19], v3, s68, v[2:3]
	v_or_b32_e32 v3, 32, v97
	ds_write_b32 v14, v6
	v_lshl_add_u32 v15, v3, 3, v246
	ds_read_b64 v[6:7], v15
	v_lshrrev_b32_e32 v96, 1, v3
	v_mul_lo_u32 v107, v96, s68
	v_add_u32_e32 v96, v109, v107
	v_lshrrev_b32_e32 v3, 2, v3
	s_waitcnt lgkmcnt(0)
;     ...
;             _Pragma("unroll") for (int m = 0; m < 4; ++m) {
;               const int rr = wr3 * 64 + m * 16 + fr3;
;               const float2 ms = *reinterpret_cast<const float2*>(mr + (ai * HALF + rr) * 2);
;               f32x4 y = acc[ai][bj][m][n];
;               const float o0 = (y[0] - ms.x) * ms.y * gm.x + bt.x, o1 = (y[1] - ms.x) * ms.y * gm.y + bt.y;
;               const float o2 = (y[2] - ms.x) * ms.y * gm.z + bt.z, o3 = (y[3] - ms.x) * ms.y * gm.w + bt.w;
;               const unsigned h0 = f2bf(o0), h1 = f2bf(o1), h2 = f2bf(o2), h3 = f2bf(o3);
;               u32x2 ob; ob[0] = h0 | (h1 << 16); ob[1] = h2 | (h3 << 16);
;               *reinterpret_cast<u32x2*>(smem + (rr >> 1) * PIECE + (rr & 1) * 512 + cc * 2) = ob;
;               const int l0 = min(((int)__float_as_uint(o0) - (int)(h0 << 16) + 128) >> 8, 127);
;               const int l1 = min(((int)__float_as_uint(o1) - (int)(h1 << 16) + 128) >> 8, 127);
;               const int l2 = min(((int)__float_as_uint(o2) - (int)(h2 << 16) + 128) >> 8, 127);
;               const int l3 = min(((int)__float_as_uint(o3) - (int)(h3 << 16) + 128) >> 8, 127);
;               *reinterpret_cast<unsigned*>(smem + LOBASE + (rr >> 2) * PIECE + (rr & 3) * 256 + cc) =
;                   (unsigned)(l0 & 255) | ((unsigned)(l1 & 255) << 8) | ((unsigned)(l2 & 255) << 16) | ((unsigned)l3 << 24);
;             }
	v_pk_add_f32 v[20:21], v[194:195], v[6:7] op_sel_hi:[1,0] neg_lo:[0,1] neg_hi:[0,1]
	v_pk_add_f32 v[66:67], v[192:193], v[6:7] op_sel_hi:[1,0] neg_lo:[0,1] neg_hi:[0,1]
	v_pk_mul_f32 v[20:21], v[6:7], v[20:21] op_sel:[1,0]
	v_pk_mul_f32 v[6:7], v[6:7], v[66:67] op_sel:[1,0]
	v_pk_fma_f32 v[20:21], v[22:23], v[20:21], v[64:65]
	v_pk_fma_f32 v[6:7], v[0:1], v[6:7], v[4:5]
	v_and_b32_sdwa v66, v21, v244 dst_sel:DWORD dst_unused:UNUSED_PAD src0_sel:WORD_1 src1_sel:DWORD
	v_and_b32_sdwa v67, v20, v244 dst_sel:DWORD dst_unused:UNUSED_PAD src0_sel:WORD_1 src1_sel:DWORD
	v_add3_u32 v98, v21, v66, s67
	v_add3_u32 v66, v20, v67, s67
	v_and_b32_e32 v99, 0xffff0000, v66
	v_and_b32_sdwa v66, v7, v244 dst_sel:DWORD dst_unused:UNUSED_PAD src0_sel:WORD_1 src1_sel:DWORD
	v_and_b32_sdwa v67, v6, v244 dst_sel:DWORD dst_unused:UNUSED_PAD src0_sel:WORD_1 src1_sel:DWORD
	v_add3_u32 v66, v7, v66, s67
	v_add3_u32 v100, v6, v67, s67
	v_and_b32_e32 v101, 0xffff0000, v66
	v_or_b32_sdwa v67, v101, v98 dst_sel:DWORD dst_unused:UNUSED_PAD src0_sel:DWORD src1_sel:WORD_1
	v_or_b32_sdwa v66, v100, v99 dst_sel:DWORD dst_unused:UNUSED_PAD src0_sel:WORD_1 src1_sel:DWORD
	ds_write_b64 v96, v[66:67]
	v_and_b32_e32 v66, 0xffff0000, v100
	v_sub_u32_e32 v6, v6, v66
	v_sub_u32_e32 v20, v20, v99
	v_and_b32_e32 v66, 0xffff0000, v98
	v_add_u32_e32 v20, 0x80, v20
	v_sub_u32_e32 v21, v21, v66
	v_sub_u32_e32 v7, v7, v101
	v_add_u32_e32 v6, 0x80, v6
	v_ashrrev_i32_e32 v20, 8, v20
	v_add_u32_e32 v21, 0x80, v21
	v_add_u32_e32 v7, 0x80, v7
	v_ashrrev_i32_e32 v6, 8, v6
	v_min_i32_e32 v20, 0x7f, v20
	v_ashrrev_i32_e32 v21, 8, v21
	v_ashrrev_i32_e32 v7, 8, v7
	v_min_i32_e32 v6, 0x7f, v6
	v_min_i32_sdwa v21, v21, s69 dst_sel:WORD_1 dst_unused:UNUSED_PAD src0_sel:DWORD src1_sel:DWORD
	v_min_i32_e32 v7, 0x7f, v7
	v_lshlrev_b32_e32 v20, 8, v20
	v_and_b32_e32 v20, 0xff00, v20
	v_and_b32_e32 v21, 0xff0000, v21
	v_perm_b32 v6, v7, v6, s76
	v_or3_b32 v6, v6, v20, v21
	v_mad_u64_u32 v[20:21], s[18:19], v3, s68, v[2:3]
	v_or_b32_e32 v3, 48, v97
	ds_write_b32 v20, v6
	v_lshl_add_u32 v21, v3, 3, v246
	ds_read_b64 v[6:7], v21
	s_waitcnt lgkmcnt(0)
	v_pk_add_f32 v[66:67], v[190:191], v[6:7] op_sel_hi:[1,0] neg_lo:[0,1] neg_hi:[0,1]
	s_nop 0
	v_pk_mul_f32 v[66:67], v[6:7], v[66:67] op_sel:[1,0]
	s_nop 0
	v_pk_fma_f32 v[22:23], v[22:23], v[66:67], v[64:65]
	v_pk_add_f32 v[64:65], v[188:189], v[6:7] op_sel_hi:[1,0] neg_lo:[0,1] neg_hi:[0,1]
	v_lshrrev_b32_e32 v66, 1, v3
	v_pk_mul_f32 v[6:7], v[6:7], v[64:65] op_sel:[1,0]
	v_mul_lo_u32 v108, v66, s68
	v_pk_fma_f32 v[0:1], v[0:1], v[6:7], v[4:5]
	v_and_b32_sdwa v4, v23, v244 dst_sel:DWORD dst_unused:UNUSED_PAD src0_sel:WORD_1 src1_sel:DWORD
	v_and_b32_sdwa v5, v22, v244 dst_sel:DWORD dst_unused:UNUSED_PAD src0_sel:WORD_1 src1_sel:DWORD
	v_add3_u32 v6, v23, v4, s67
	v_add3_u32 v4, v22, v5, s67
	v_and_b32_e32 v7, 0xffff0000, v4
	v_and_b32_sdwa v4, v1, v244 dst_sel:DWORD dst_unused:UNUSED_PAD src0_sel:WORD_1 src1_sel:DWORD
	v_and_b32_sdwa v5, v0, v244 dst_sel:DWORD dst_unused:UNUSED_PAD src0_sel:WORD_1 src1_sel:DWORD
	v_add3_u32 v4, v1, v4, s67
	v_add3_u32 v64, v0, v5, s67
	v_and_b32_e32 v65, 0xffff0000, v4
	v_or_b32_sdwa v5, v65, v6 dst_sel:DWORD dst_unused:UNUSED_PAD src0_sel:DWORD src1_sel:WORD_1
	v_or_b32_sdwa v4, v64, v7 dst_sel:DWORD dst_unused:UNUSED_PAD src0_sel:WORD_1 src1_sel:DWORD
	v_add_u32_e32 v97, v109, v108
	ds_write_b64 v97, v[4:5]
	v_and_b32_e32 v4, 0xffff0000, v64
	v_sub_u32_e32 v0, v0, v4
	v_sub_u32_e32 v4, v22, v7
	v_and_b32_e32 v5, 0xffff0000, v6
	v_add_u32_e32 v4, 0x80, v4
	v_sub_u32_e32 v5, v23, v5
	v_sub_u32_e32 v1, v1, v65
	v_add_u32_e32 v0, 0x80, v0
	v_ashrrev_i32_e32 v4, 8, v4
	v_add_u32_e32 v5, 0x80, v5
	v_add_u32_e32 v1, 0x80, v1
	v_ashrrev_i32_e32 v0, 8, v0
	v_min_i32_e32 v4, 0x7f, v4
	v_ashrrev_i32_e32 v5, 8, v5
	v_ashrrev_i32_e32 v1, 8, v1
	v_min_i32_e32 v0, 0x7f, v0
	v_min_i32_sdwa v5, v5, s69 dst_sel:WORD_1 dst_unused:UNUSED_PAD src0_sel:DWORD src1_sel:DWORD
	v_min_i32_e32 v1, 0x7f, v1
	v_lshlrev_b32_e32 v4, 8, v4
	v_and_b32_e32 v4, 0xff00, v4
	v_and_b32_e32 v5, 0xff0000, v5
	v_perm_b32 v0, v1, v0, s76
	v_lshrrev_b32_e32 v1, 2, v3
	v_or3_b32 v0, v0, v4, v5
	v_mad_u64_u32 v[22:23], s[18:19], v1, s68, v[2:3]
	ds_write_b32 v22, v0
	v_mov_b32_e32 v0, v200
	v_mov_b32_e32 v1, v201
	v_mov_b32_e32 v2, v202
	v_mov_b32_e32 v3, v203
	v_mov_b32_e32 v4, v220
	v_mov_b32_e32 v5, v221
	v_mov_b32_e32 v6, v222
	v_mov_b32_e32 v7, v223
	ds_read_b64 v[98:99], v71
	s_mul_i32 s18, s52, 0x2080
	v_add_u32_e32 v74, s18, v74
	s_mov_b32 s18, s74
	s_mov_b32 s19, s75
	s_waitcnt lgkmcnt(0)
;     ...
;           _Pragma("unroll") for (int bj = 0; bj < 2; ++bj) _Pragma("unroll") for (int n = 0; n < 2; ++n) {
;             const int cc = bj * HALF + wc3 * 32 + n * 16 + fq3 * 4;
;             const float4 gm = *reinterpret_cast<const float4*>(g.gam + pn * BM + cc), bt = *reinterpret_cast<const float4*>(g.bet + pn * BM + cc);
;             _Pragma("unroll") for (int m = 0; m < 4; ++m) {
;               const int rr = wr3 * 64 + m * 16 + fr3;
;               const float2 ms = *reinterpret_cast<const float2*>(mr + (ai * HALF + rr) * 2);
;               f32x4 y = acc[ai][bj][m][n];
;               const float o0 = (y[0] - ms.x) * ms.y * gm.x + bt.x, o1 = (y[1] - ms.x) * ms.y * gm.y + bt.y;
;               const float o2 = (y[2] - ms.x) * ms.y * gm.z + bt.z, o3 = (y[3] - ms.x) * ms.y * gm.w + bt.w;
;               const unsigned h0 = f2bf(o0), h1 = f2bf(o1), h2 = f2bf(o2), h3 = f2bf(o3);
;               u32x2 ob; ob[0] = h0 | (h1 << 16); ob[1] = h2 | (h3 << 16);
;               *reinterpret_cast<u32x2*>(smem + (rr >> 1) * PIECE + (rr & 1) * 512 + cc * 2) = ob;
;               const int l0 = min(((int)__float_as_uint(o0) - (int)(h0 << 16) + 128) >> 8, 127);
;               const int l1 = min(((int)__float_as_uint(o1) - (int)(h1 << 16) + 128) >> 8, 127);
;               const int l2 = min(((int)__float_as_uint(o2) - (int)(h2 << 16) + 128) >> 8, 127);
;               const int l3 = min(((int)__float_as_uint(o3) - (int)(h3 << 16) + 128) >> 8, 127);
;               *reinterpret_cast<unsigned*>(smem + LOBASE + (rr >> 2) * PIECE + (rr & 3) * 256 + cc) =
;                   (unsigned)(l0 & 255) | ((unsigned)(l1 & 255) << 8) | ((unsigned)(l2 & 255) << 16) | ((unsigned)l3 << 24);
;             }
	v_pk_add_f32 v[100:101], v[234:235], v[98:99] op_sel_hi:[1,0] neg_lo:[0,1] neg_hi:[0,1]
	v_pk_add_f32 v[102:103], v[232:233], v[98:99] op_sel_hi:[1,0] neg_lo:[0,1] neg_hi:[0,1]
	v_pk_mul_f32 v[100:101], v[98:99], v[100:101] op_sel:[1,0]
	v_pk_mul_f32 v[98:99], v[98:99], v[102:103] op_sel:[1,0]
	v_mov_b32_e32 v64, v1
	v_mov_b32_e32 v65, v2
	v_mov_b32_e32 v66, v5
	v_mov_b32_e32 v67, v6
	v_pk_fma_f32 v[100:101], v[64:65], v[100:101], v[66:67]
	v_mov_b32_e32 v1, v3
	v_mov_b32_e32 v5, v7
	v_and_b32_sdwa v23, v100, v244 dst_sel:DWORD dst_unused:UNUSED_PAD src0_sel:WORD_1 src1_sel:DWORD
	v_pk_fma_f32 v[6:7], v[0:1], v[98:99], v[4:5]
	v_add3_u32 v23, v100, v23, s67
	v_and_b32_e32 v102, 0xffff0000, v23
	v_and_b32_sdwa v23, v7, v244 dst_sel:DWORD dst_unused:UNUSED_PAD src0_sel:WORD_1 src1_sel:DWORD
	v_and_b32_sdwa v3, v101, v244 dst_sel:DWORD dst_unused:UNUSED_PAD src0_sel:WORD_1 src1_sel:DWORD
	v_and_b32_sdwa v98, v6, v244 dst_sel:DWORD dst_unused:UNUSED_PAD src0_sel:WORD_1 src1_sel:DWORD
	v_add3_u32 v23, v7, v23, s67
	v_or_b32_e32 v2, 32, v109
	v_add3_u32 v3, v101, v3, s67
	v_add3_u32 v103, v6, v98, s67
	v_and_b32_e32 v104, 0xffff0000, v23
	v_or_b32_sdwa v99, v104, v3 dst_sel:DWORD dst_unused:UNUSED_PAD src0_sel:DWORD src1_sel:WORD_1
	v_or_b32_sdwa v98, v103, v102 dst_sel:DWORD dst_unused:UNUSED_PAD src0_sel:WORD_1 src1_sel:DWORD
	v_add_u32_e32 v23, v2, v105
	ds_write_b64 v23, v[98:99]
	v_and_b32_e32 v98, 0xffff0000, v103
	v_sub_u32_e32 v6, v6, v98
	v_sub_u32_e32 v98, v100, v102
	v_and_b32_e32 v3, 0xffff0000, v3
	v_add_u32_e32 v98, 0x80, v98
	v_sub_u32_e32 v3, v101, v3
	v_sub_u32_e32 v7, v7, v104
	v_add_u32_e32 v6, 0x80, v6
	v_ashrrev_i32_e32 v98, 8, v98
	v_add_u32_e32 v3, 0x80, v3
	v_add_u32_e32 v7, 0x80, v7
	v_ashrrev_i32_e32 v6, 8, v6
	v_min_i32_e32 v98, 0x7f, v98
	v_ashrrev_i32_e32 v3, 8, v3
	v_ashrrev_i32_e32 v7, 8, v7
	v_min_i32_e32 v6, 0x7f, v6
	v_min_i32_sdwa v3, v3, s69 dst_sel:WORD_1 dst_unused:UNUSED_PAD src0_sel:DWORD src1_sel:DWORD
	v_min_i32_e32 v7, 0x7f, v7
	v_lshlrev_b32_e32 v98, 8, v98
	v_and_b32_e32 v98, 0xff00, v98
	v_and_b32_e32 v3, 0xff0000, v3
	v_perm_b32 v6, v7, v6, s76
	v_or3_b32 v3, v6, v98, v3
	ds_write_b32 v12, v3 offset:16
	ds_read_b64 v[6:7], v13
	s_waitcnt lgkmcnt(0)
	v_pk_add_f32 v[98:99], v[158:159], v[6:7] op_sel_hi:[1,0] neg_lo:[0,1] neg_hi:[0,1]
	s_nop 0
	v_pk_mul_f32 v[98:99], v[6:7], v[98:99] op_sel:[1,0]
	s_nop 0
	v_pk_fma_f32 v[100:101], v[64:65], v[98:99], v[66:67]
	v_pk_add_f32 v[98:99], v[156:157], v[6:7] op_sel_hi:[1,0] neg_lo:[0,1] neg_hi:[0,1]
	v_and_b32_sdwa v3, v101, v244 dst_sel:DWORD dst_unused:UNUSED_PAD src0_sel:WORD_1 src1_sel:DWORD
	v_pk_mul_f32 v[6:7], v[6:7], v[98:99] op_sel:[1,0]
	v_and_b32_sdwa v98, v100, v244 dst_sel:DWORD dst_unused:UNUSED_PAD src0_sel:WORD_1 src1_sel:DWORD
	v_pk_fma_f32 v[6:7], v[0:1], v[6:7], v[4:5]
	v_add3_u32 v98, v100, v98, s67
	v_and_b32_e32 v99, 0xffff0000, v98
	v_and_b32_sdwa v98, v7, v244 dst_sel:DWORD dst_unused:UNUSED_PAD src0_sel:WORD_1 src1_sel:DWORD
	v_and_b32_sdwa v102, v6, v244 dst_sel:DWORD dst_unused:UNUSED_PAD src0_sel:WORD_1 src1_sel:DWORD
	v_add3_u32 v98, v7, v98, s67
	v_add3_u32 v3, v101, v3, s67
	v_add3_u32 v104, v6, v102, s67
	v_and_b32_e32 v110, 0xffff0000, v98
	v_or_b32_sdwa v103, v110, v3 dst_sel:DWORD dst_unused:UNUSED_PAD src0_sel:DWORD src1_sel:WORD_1
	v_or_b32_sdwa v102, v104, v99 dst_sel:DWORD dst_unused:UNUSED_PAD src0_sel:WORD_1 src1_sel:DWORD
	v_add_u32_e32 v98, v2, v106
	ds_write_b64 v98, v[102:103]
	v_and_b32_e32 v102, 0xffff0000, v104
	v_sub_u32_e32 v99, v100, v99
	v_and_b32_e32 v3, 0xffff0000, v3
	v_sub_u32_e32 v6, v6, v102
	v_add_u32_e32 v99, 0x80, v99
	v_sub_u32_e32 v3, v101, v3
	v_sub_u32_e32 v7, v7, v110
	v_add_u32_e32 v6, 0x80, v6
	v_ashrrev_i32_e32 v99, 8, v99
	v_add_u32_e32 v3, 0x80, v3
	v_add_u32_e32 v7, 0x80, v7
	v_ashrrev_i32_e32 v6, 8, v6
	v_min_i32_e32 v99, 0x7f, v99
	v_ashrrev_i32_e32 v3, 8, v3
	v_ashrrev_i32_e32 v7, 8, v7
	v_min_i32_e32 v6, 0x7f, v6
	v_min_i32_sdwa v3, v3, s69 dst_sel:WORD_1 dst_unused:UNUSED_PAD src0_sel:DWORD src1_sel:DWORD
	v_min_i32_e32 v7, 0x7f, v7
	v_lshlrev_b32_e32 v99, 8, v99
	v_and_b32_e32 v99, 0xff00, v99
	v_and_b32_e32 v3, 0xff0000, v3
	v_perm_b32 v6, v7, v6, s76
	v_or3_b32 v3, v6, v99, v3
	ds_write_b32 v14, v3 offset:16
	ds_read_b64 v[6:7], v15
	s_waitcnt lgkmcnt(0)
	v_pk_add_f32 v[100:101], v[126:127], v[6:7] op_sel_hi:[1,0] neg_lo:[0,1] neg_hi:[0,1]
	s_nop 0
	v_pk_mul_f32 v[100:101], v[6:7], v[100:101] op_sel:[1,0]
	v_pk_add_f32 v[102:103], v[124:125], v[6:7] op_sel_hi:[1,0] neg_lo:[0,1] neg_hi:[0,1]
	v_pk_fma_f32 v[100:101], v[64:65], v[100:101], v[66:67]
	v_pk_mul_f32 v[6:7], v[6:7], v[102:103] op_sel:[1,0]
	v_and_b32_sdwa v99, v100, v244 dst_sel:DWORD dst_unused:UNUSED_PAD src0_sel:WORD_1 src1_sel:DWORD
	v_pk_fma_f32 v[6:7], v[0:1], v[6:7], v[4:5]
	v_add3_u32 v99, v100, v99, s67
	v_and_b32_e32 v104, 0xffff0000, v99
	v_and_b32_sdwa v99, v7, v244 dst_sel:DWORD dst_unused:UNUSED_PAD src0_sel:WORD_1 src1_sel:DWORD
	v_and_b32_sdwa v3, v101, v244 dst_sel:DWORD dst_unused:UNUSED_PAD src0_sel:WORD_1 src1_sel:DWORD
	v_and_b32_sdwa v102, v6, v244 dst_sel:DWORD dst_unused:UNUSED_PAD src0_sel:WORD_1 src1_sel:DWORD
	v_add3_u32 v99, v7, v99, s67
	v_add3_u32 v3, v101, v3, s67
	v_add3_u32 v110, v6, v102, s67
	v_and_b32_e32 v111, 0xffff0000, v99
	v_or_b32_sdwa v103, v111, v3 dst_sel:DWORD dst_unused:UNUSED_PAD src0_sel:DWORD src1_sel:WORD_1
	v_or_b32_sdwa v102, v110, v104 dst_sel:DWORD dst_unused:UNUSED_PAD src0_sel:WORD_1 src1_sel:DWORD
	v_add_u32_e32 v99, v2, v107
	ds_write_b64 v99, v[102:103]
	v_and_b32_e32 v102, 0xffff0000, v110
	v_sub_u32_e32 v100, v100, v104
	v_and_b32_e32 v3, 0xffff0000, v3
	v_sub_u32_e32 v6, v6, v102
	v_add_u32_e32 v100, 0x80, v100
	v_sub_u32_e32 v3, v101, v3
	v_sub_u32_e32 v7, v7, v111
	v_add_u32_e32 v6, 0x80, v6
	v_ashrrev_i32_e32 v100, 8, v100
	v_add_u32_e32 v3, 0x80, v3
	v_add_u32_e32 v7, 0x80, v7
	v_ashrrev_i32_e32 v6, 8, v6
	v_min_i32_e32 v100, 0x7f, v100
	v_ashrrev_i32_e32 v3, 8, v3
	v_ashrrev_i32_e32 v7, 8, v7
	v_min_i32_e32 v6, 0x7f, v6
	v_min_i32_sdwa v3, v3, s69 dst_sel:WORD_1 dst_unused:UNUSED_PAD src0_sel:DWORD src1_sel:DWORD
	v_min_i32_e32 v7, 0x7f, v7
	v_lshlrev_b32_e32 v100, 8, v100
	v_and_b32_e32 v100, 0xff00, v100
	v_and_b32_e32 v3, 0xff0000, v3
	v_perm_b32 v6, v7, v6, s76
	v_or3_b32 v3, v6, v100, v3
	ds_write_b32 v20, v3 offset:16
	ds_read_b64 v[6:7], v21
	v_or_b32_e32 v104, 0x100, v109
	s_waitcnt lgkmcnt(0)
;     ...
;           _Pragma("unroll") for (int bj = 0; bj < 2; ++bj) _Pragma("unroll") for (int n = 0; n < 2; ++n) {
;             const int cc = bj * HALF + wc3 * 32 + n * 16 + fq3 * 4;
;             const float4 gm = *reinterpret_cast<const float4*>(g.gam + pn * BM + cc), bt = *reinterpret_cast<const float4*>(g.bet + pn * BM + cc);
;             _Pragma("unroll") for (int m = 0; m < 4; ++m) {
;               const int rr = wr3 * 64 + m * 16 + fr3;
;               const float2 ms = *reinterpret_cast<const float2*>(mr + (ai * HALF + rr) * 2);
;               f32x4 y = acc[ai][bj][m][n];
;               const float o0 = (y[0] - ms.x) * ms.y * gm.x + bt.x, o1 = (y[1] - ms.x) * ms.y * gm.y + bt.y;
;               const float o2 = (y[2] - ms.x) * ms.y * gm.z + bt.z, o3 = (y[3] - ms.x) * ms.y * gm.w + bt.w;
;               const unsigned h0 = f2bf(o0), h1 = f2bf(o1), h2 = f2bf(o2), h3 = f2bf(o3);
;               u32x2 ob; ob[0] = h0 | (h1 << 16); ob[1] = h2 | (h3 << 16);
;               *reinterpret_cast<u32x2*>(smem + (rr >> 1) * PIECE + (rr & 1) * 512 + cc * 2) = ob;
;               const int l0 = min(((int)__float_as_uint(o0) - (int)(h0 << 16) + 128) >> 8, 127);
;               const int l1 = min(((int)__float_as_uint(o1) - (int)(h1 << 16) + 128) >> 8, 127);
;               const int l2 = min(((int)__float_as_uint(o2) - (int)(h2 << 16) + 128) >> 8, 127);
;               const int l3 = min(((int)__float_as_uint(o3) - (int)(h3 << 16) + 128) >> 8, 127);
;               *reinterpret_cast<unsigned*>(smem + LOBASE + (rr >> 2) * PIECE + (rr & 3) * 256 + cc) =
;                   (unsigned)(l0 & 255) | ((unsigned)(l1 & 255) << 8) | ((unsigned)(l2 & 255) << 16) | ((unsigned)l3 << 24);
;             }
	v_pk_add_f32 v[100:101], v[154:155], v[6:7] op_sel_hi:[1,0] neg_lo:[0,1] neg_hi:[0,1]
	s_nop 0
	v_pk_mul_f32 v[100:101], v[6:7], v[100:101] op_sel:[1,0]
	s_nop 0
	v_pk_fma_f32 v[64:65], v[64:65], v[100:101], v[66:67]
	v_pk_add_f32 v[66:67], v[152:153], v[6:7] op_sel_hi:[1,0] neg_lo:[0,1] neg_hi:[0,1]
	v_and_b32_sdwa v3, v65, v244 dst_sel:DWORD dst_unused:UNUSED_PAD src0_sel:WORD_1 src1_sel:DWORD
	v_pk_mul_f32 v[6:7], v[6:7], v[66:67] op_sel:[1,0]
	v_add3_u32 v3, v65, v3, s67
	v_pk_fma_f32 v[0:1], v[0:1], v[6:7], v[4:5]
	v_and_b32_sdwa v4, v64, v244 dst_sel:DWORD dst_unused:UNUSED_PAD src0_sel:WORD_1 src1_sel:DWORD
	v_add3_u32 v4, v64, v4, s67
	v_and_b32_e32 v6, 0xffff0000, v4
	v_and_b32_sdwa v4, v1, v244 dst_sel:DWORD dst_unused:UNUSED_PAD src0_sel:WORD_1 src1_sel:DWORD
	v_and_b32_sdwa v5, v0, v244 dst_sel:DWORD dst_unused:UNUSED_PAD src0_sel:WORD_1 src1_sel:DWORD
	v_add3_u32 v4, v1, v4, s67
	v_add3_u32 v7, v0, v5, s67
	v_and_b32_e32 v66, 0xffff0000, v4
	v_add_u32_e32 v100, v2, v108
	v_and_b32_e32 v2, 0xffff0000, v7
	v_or_b32_sdwa v5, v66, v3 dst_sel:DWORD dst_unused:UNUSED_PAD src0_sel:DWORD src1_sel:WORD_1
	v_sub_u32_e32 v0, v0, v2
	v_sub_u32_e32 v2, v64, v6
	v_and_b32_e32 v3, 0xffff0000, v3
	v_add_u32_e32 v2, 0x80, v2
	v_sub_u32_e32 v3, v65, v3
	v_sub_u32_e32 v1, v1, v66
	v_add_u32_e32 v0, 0x80, v0
	v_ashrrev_i32_e32 v2, 8, v2
	v_add_u32_e32 v3, 0x80, v3
	v_add_u32_e32 v1, 0x80, v1
	v_ashrrev_i32_e32 v0, 8, v0
	v_min_i32_e32 v2, 0x7f, v2
	v_ashrrev_i32_e32 v3, 8, v3
	v_ashrrev_i32_e32 v1, 8, v1
	v_min_i32_e32 v0, 0x7f, v0
	v_min_i32_sdwa v3, v3, s69 dst_sel:WORD_1 dst_unused:UNUSED_PAD src0_sel:DWORD src1_sel:DWORD
	v_min_i32_e32 v1, 0x7f, v1
	v_lshlrev_b32_e32 v2, 8, v2
	v_and_b32_e32 v2, 0xff00, v2
	v_and_b32_e32 v3, 0xff0000, v3
	v_perm_b32 v0, v1, v0, s76
	v_or_b32_sdwa v4, v7, v6 dst_sel:DWORD dst_unused:UNUSED_PAD src0_sel:WORD_1 src1_sel:DWORD
	v_or3_b32 v0, v0, v2, v3
	ds_write_b64 v100, v[4:5]
	ds_write_b32 v22, v0 offset:16
	v_mov_b32_e32 v0, v204
	v_mov_b32_e32 v1, v205
	v_mov_b32_e32 v2, v206
	v_mov_b32_e32 v3, v207
	v_mov_b32_e32 v4, v240
	v_mov_b32_e32 v5, v241
	v_mov_b32_e32 v6, v242
	v_mov_b32_e32 v7, v243
	ds_read_b64 v[102:103], v71
	v_add_u32_e32 v101, v104, v105
	s_waitcnt lgkmcnt(0)
	v_pk_add_f32 v[110:111], v[230:231], v[102:103] op_sel_hi:[1,0] neg_lo:[0,1] neg_hi:[0,1]
	s_nop 0
	v_pk_mul_f32 v[110:111], v[102:103], v[110:111] op_sel:[1,0]
	v_pk_add_f32 v[124:125], v[228:229], v[102:103] op_sel_hi:[1,0] neg_lo:[0,1] neg_hi:[0,1]
	v_mov_b32_e32 v64, v1
	v_mov_b32_e32 v65, v2
	v_mov_b32_e32 v66, v5
	v_mov_b32_e32 v67, v6
	v_pk_fma_f32 v[110:111], v[64:65], v[110:111], v[66:67]
	v_pk_mul_f32 v[102:103], v[102:103], v[124:125] op_sel:[1,0]
	v_mov_b32_e32 v1, v3
	v_mov_b32_e32 v5, v7
	v_and_b32_sdwa v6, v111, v244 dst_sel:DWORD dst_unused:UNUSED_PAD src0_sel:WORD_1 src1_sel:DWORD
	v_and_b32_sdwa v7, v110, v244 dst_sel:DWORD dst_unused:UNUSED_PAD src0_sel:WORD_1 src1_sel:DWORD
	v_pk_fma_f32 v[2:3], v[0:1], v[102:103], v[4:5]
	v_add3_u32 v102, v111, v6, s67
	v_add3_u32 v6, v110, v7, s67
	v_and_b32_e32 v103, 0xffff0000, v6
	v_and_b32_sdwa v6, v3, v244 dst_sel:DWORD dst_unused:UNUSED_PAD src0_sel:WORD_1 src1_sel:DWORD
	v_and_b32_sdwa v7, v2, v244 dst_sel:DWORD dst_unused:UNUSED_PAD src0_sel:WORD_1 src1_sel:DWORD
	v_add3_u32 v6, v3, v6, s67
	v_add3_u32 v124, v2, v7, s67
	v_and_b32_e32 v125, 0xffff0000, v6
	v_or_b32_sdwa v7, v125, v102 dst_sel:DWORD dst_unused:UNUSED_PAD src0_sel:DWORD src1_sel:WORD_1
	v_or_b32_sdwa v6, v124, v103 dst_sel:DWORD dst_unused:UNUSED_PAD src0_sel:WORD_1 src1_sel:DWORD
	ds_write_b64 v101, v[6:7]
	v_and_b32_e32 v6, 0xffff0000, v124
	v_sub_u32_e32 v2, v2, v6
	v_sub_u32_e32 v6, v110, v103
	v_and_b32_e32 v7, 0xffff0000, v102
	v_add_u32_e32 v6, 0x80, v6
	v_sub_u32_e32 v7, v111, v7
	v_sub_u32_e32 v3, v3, v125
	v_add_u32_e32 v2, 0x80, v2
	v_ashrrev_i32_e32 v6, 8, v6
	v_add_u32_e32 v7, 0x80, v7
	v_add_u32_e32 v3, 0x80, v3
	v_ashrrev_i32_e32 v2, 8, v2
	v_min_i32_e32 v6, 0x7f, v6
	v_ashrrev_i32_e32 v7, 8, v7
	v_ashrrev_i32_e32 v3, 8, v3
	v_min_i32_e32 v2, 0x7f, v2
	v_min_i32_sdwa v7, v7, s69 dst_sel:WORD_1 dst_unused:UNUSED_PAD src0_sel:DWORD src1_sel:DWORD
	v_min_i32_e32 v3, 0x7f, v3
	v_lshlrev_b32_e32 v6, 8, v6
	v_and_b32_e32 v6, 0xff00, v6
	v_and_b32_e32 v7, 0xff0000, v7
	v_perm_b32 v2, v3, v2, s76
	v_or3_b32 v2, v2, v6, v7
	ds_write_b32 v12, v2 offset:128
	ds_read_b64 v[2:3], v13
	s_waitcnt lgkmcnt(0)
	v_pk_add_f32 v[6:7], v[150:151], v[2:3] op_sel_hi:[1,0] neg_lo:[0,1] neg_hi:[0,1]
	s_nop 0
	v_pk_mul_f32 v[6:7], v[2:3], v[6:7] op_sel:[1,0]
	v_pk_add_f32 v[102:103], v[148:149], v[2:3] op_sel_hi:[1,0] neg_lo:[0,1] neg_hi:[0,1]
	v_pk_fma_f32 v[6:7], v[64:65], v[6:7], v[66:67]
	v_pk_mul_f32 v[2:3], v[2:3], v[102:103] op_sel:[1,0]
	v_and_b32_sdwa v102, v7, v244 dst_sel:DWORD dst_unused:UNUSED_PAD src0_sel:WORD_1 src1_sel:DWORD
	v_and_b32_sdwa v103, v6, v244 dst_sel:DWORD dst_unused:UNUSED_PAD src0_sel:WORD_1 src1_sel:DWORD
	v_pk_fma_f32 v[2:3], v[0:1], v[2:3], v[4:5]
	v_add3_u32 v124, v7, v102, s67
	v_add3_u32 v102, v6, v103, s67
	v_and_b32_e32 v103, 0xffff0000, v102
	v_and_b32_sdwa v102, v3, v244 dst_sel:DWORD dst_unused:UNUSED_PAD src0_sel:WORD_1 src1_sel:DWORD
	v_and_b32_sdwa v110, v2, v244 dst_sel:DWORD dst_unused:UNUSED_PAD src0_sel:WORD_1 src1_sel:DWORD
	v_add3_u32 v102, v3, v102, s67
	v_add3_u32 v125, v2, v110, s67
	v_and_b32_e32 v126, 0xffff0000, v102
	v_or_b32_sdwa v111, v126, v124 dst_sel:DWORD dst_unused:UNUSED_PAD src0_sel:DWORD src1_sel:WORD_1
	v_or_b32_sdwa v110, v125, v103 dst_sel:DWORD dst_unused:UNUSED_PAD src0_sel:WORD_1 src1_sel:DWORD
	v_add_u32_e32 v102, v104, v106
	ds_write_b64 v102, v[110:111]
	v_and_b32_e32 v110, 0xffff0000, v125
	v_sub_u32_e32 v6, v6, v103
	v_and_b32_e32 v103, 0xffff0000, v124
	v_sub_u32_e32 v2, v2, v110
	v_add_u32_e32 v6, 0x80, v6
	v_sub_u32_e32 v7, v7, v103
	v_sub_u32_e32 v3, v3, v126
	v_add_u32_e32 v2, 0x80, v2
	v_ashrrev_i32_e32 v6, 8, v6
	v_add_u32_e32 v7, 0x80, v7
	v_add_u32_e32 v3, 0x80, v3
	v_ashrrev_i32_e32 v2, 8, v2
	v_min_i32_e32 v6, 0x7f, v6
	v_ashrrev_i32_e32 v7, 8, v7
	v_ashrrev_i32_e32 v3, 8, v3
	v_min_i32_e32 v2, 0x7f, v2
	v_min_i32_sdwa v7, v7, s69 dst_sel:WORD_1 dst_unused:UNUSED_PAD src0_sel:DWORD src1_sel:DWORD
	v_min_i32_e32 v3, 0x7f, v3
	v_lshlrev_b32_e32 v6, 8, v6
	v_and_b32_e32 v6, 0xff00, v6
	v_and_b32_e32 v7, 0xff0000, v7
	v_perm_b32 v2, v3, v2, s76
	v_or3_b32 v2, v2, v6, v7
	ds_write_b32 v14, v2 offset:128
	ds_read_b64 v[2:3], v15
	s_waitcnt lgkmcnt(0)
;     ...
;           _Pragma("unroll") for (int bj = 0; bj < 2; ++bj) _Pragma("unroll") for (int n = 0; n < 2; ++n) {
;             const int cc = bj * HALF + wc3 * 32 + n * 16 + fq3 * 4;
;             const float4 gm = *reinterpret_cast<const float4*>(g.gam + pn * BM + cc), bt = *reinterpret_cast<const float4*>(g.bet + pn * BM + cc);
;             _Pragma("unroll") for (int m = 0; m < 4; ++m) {
;               const int rr = wr3 * 64 + m * 16 + fr3;
;               const float2 ms = *reinterpret_cast<const float2*>(mr + (ai * HALF + rr) * 2);
;               f32x4 y = acc[ai][bj][m][n];
;               const float o0 = (y[0] - ms.x) * ms.y * gm.x + bt.x, o1 = (y[1] - ms.x) * ms.y * gm.y + bt.y;
;               const float o2 = (y[2] - ms.x) * ms.y * gm.z + bt.z, o3 = (y[3] - ms.x) * ms.y * gm.w + bt.w;
;               const unsigned h0 = f2bf(o0), h1 = f2bf(o1), h2 = f2bf(o2), h3 = f2bf(o3);
;               u32x2 ob; ob[0] = h0 | (h1 << 16); ob[1] = h2 | (h3 << 16);
;               *reinterpret_cast<u32x2*>(smem + (rr >> 1) * PIECE + (rr & 1) * 512 + cc * 2) = ob;
;               const int l0 = min(((int)__float_as_uint(o0) - (int)(h0 << 16) + 128) >> 8, 127);
;               const int l1 = min(((int)__float_as_uint(o1) - (int)(h1 << 16) + 128) >> 8, 127);
;               const int l2 = min(((int)__float_as_uint(o2) - (int)(h2 << 16) + 128) >> 8, 127);
;               const int l3 = min(((int)__float_as_uint(o3) - (int)(h3 << 16) + 128) >> 8, 127);
;               *reinterpret_cast<unsigned*>(smem + LOBASE + (rr >> 2) * PIECE + (rr & 3) * 256 + cc) =
;                   (unsigned)(l0 & 255) | ((unsigned)(l1 & 255) << 8) | ((unsigned)(l2 & 255) << 16) | ((unsigned)l3 << 24);
;             }
	v_pk_add_f32 v[6:7], v[118:119], v[2:3] op_sel_hi:[1,0] neg_lo:[0,1] neg_hi:[0,1]
	s_nop 0
	v_pk_mul_f32 v[6:7], v[2:3], v[6:7] op_sel:[1,0]
	v_pk_add_f32 v[110:111], v[116:117], v[2:3] op_sel_hi:[1,0] neg_lo:[0,1] neg_hi:[0,1]
	v_pk_fma_f32 v[6:7], v[64:65], v[6:7], v[66:67]
	v_pk_mul_f32 v[2:3], v[2:3], v[110:111] op_sel:[1,0]
	v_and_b32_sdwa v103, v7, v244 dst_sel:DWORD dst_unused:UNUSED_PAD src0_sel:WORD_1 src1_sel:DWORD
	v_and_b32_sdwa v110, v6, v244 dst_sel:DWORD dst_unused:UNUSED_PAD src0_sel:WORD_1 src1_sel:DWORD
	v_pk_fma_f32 v[2:3], v[0:1], v[2:3], v[4:5]
	v_add3_u32 v116, v7, v103, s67
	v_add3_u32 v103, v6, v110, s67
	v_and_b32_e32 v117, 0xffff0000, v103
	v_and_b32_sdwa v103, v3, v244 dst_sel:DWORD dst_unused:UNUSED_PAD src0_sel:WORD_1 src1_sel:DWORD
	v_and_b32_sdwa v110, v2, v244 dst_sel:DWORD dst_unused:UNUSED_PAD src0_sel:WORD_1 src1_sel:DWORD
	v_add3_u32 v103, v3, v103, s67
	v_add3_u32 v118, v2, v110, s67
	v_and_b32_e32 v119, 0xffff0000, v103
	v_or_b32_sdwa v111, v119, v116 dst_sel:DWORD dst_unused:UNUSED_PAD src0_sel:DWORD src1_sel:WORD_1
	v_or_b32_sdwa v110, v118, v117 dst_sel:DWORD dst_unused:UNUSED_PAD src0_sel:WORD_1 src1_sel:DWORD
	v_add_u32_e32 v103, v104, v107
	ds_write_b64 v103, v[110:111]
	v_and_b32_e32 v110, 0xffff0000, v118
	v_sub_u32_e32 v2, v2, v110
	v_sub_u32_e32 v6, v6, v117
	v_and_b32_e32 v110, 0xffff0000, v116
	v_add_u32_e32 v6, 0x80, v6
	v_sub_u32_e32 v7, v7, v110
	v_sub_u32_e32 v3, v3, v119
	v_add_u32_e32 v2, 0x80, v2
	v_ashrrev_i32_e32 v6, 8, v6
	v_add_u32_e32 v7, 0x80, v7
	v_add_u32_e32 v3, 0x80, v3
	v_ashrrev_i32_e32 v2, 8, v2
	v_min_i32_e32 v6, 0x7f, v6
	v_ashrrev_i32_e32 v7, 8, v7
	v_ashrrev_i32_e32 v3, 8, v3
	v_min_i32_e32 v2, 0x7f, v2
	v_min_i32_sdwa v7, v7, s69 dst_sel:WORD_1 dst_unused:UNUSED_PAD src0_sel:DWORD src1_sel:DWORD
	v_min_i32_e32 v3, 0x7f, v3
	v_lshlrev_b32_e32 v6, 8, v6
	v_and_b32_e32 v6, 0xff00, v6
	v_and_b32_e32 v7, 0xff0000, v7
	v_perm_b32 v2, v3, v2, s76
	v_or3_b32 v2, v2, v6, v7
	ds_write_b32 v20, v2 offset:128
	ds_read_b64 v[2:3], v21
	v_add_u32_e32 v104, v104, v108
	s_waitcnt lgkmcnt(0)
	v_pk_add_f32 v[6:7], v[122:123], v[2:3] op_sel_hi:[1,0] neg_lo:[0,1] neg_hi:[0,1]
	s_nop 0
	v_pk_mul_f32 v[6:7], v[2:3], v[6:7] op_sel:[1,0]
	s_nop 0
	v_pk_fma_f32 v[6:7], v[64:65], v[6:7], v[66:67]
	v_pk_add_f32 v[64:65], v[120:121], v[2:3] op_sel_hi:[1,0] neg_lo:[0,1] neg_hi:[0,1]
	s_nop 0
	v_pk_mul_f32 v[2:3], v[2:3], v[64:65] op_sel:[1,0]
	s_nop 0
	v_pk_fma_f32 v[0:1], v[0:1], v[2:3], v[4:5]
	v_and_b32_sdwa v2, v7, v244 dst_sel:DWORD dst_unused:UNUSED_PAD src0_sel:WORD_1 src1_sel:DWORD
	v_and_b32_sdwa v3, v6, v244 dst_sel:DWORD dst_unused:UNUSED_PAD src0_sel:WORD_1 src1_sel:DWORD
	v_add3_u32 v4, v7, v2, s67
	v_add3_u32 v2, v6, v3, s67
	v_and_b32_e32 v5, 0xffff0000, v2
	v_and_b32_sdwa v2, v1, v244 dst_sel:DWORD dst_unused:UNUSED_PAD src0_sel:WORD_1 src1_sel:DWORD
	v_and_b32_sdwa v3, v0, v244 dst_sel:DWORD dst_unused:UNUSED_PAD src0_sel:WORD_1 src1_sel:DWORD
	v_add3_u32 v2, v1, v2, s67
	v_add3_u32 v64, v0, v3, s67
	v_and_b32_e32 v65, 0xffff0000, v2
	v_or_b32_sdwa v3, v65, v4 dst_sel:DWORD dst_unused:UNUSED_PAD src0_sel:DWORD src1_sel:WORD_1
	v_or_b32_sdwa v2, v64, v5 dst_sel:DWORD dst_unused:UNUSED_PAD src0_sel:WORD_1 src1_sel:DWORD
	ds_write_b64 v104, v[2:3]
	v_and_b32_e32 v2, 0xffff0000, v64
	v_sub_u32_e32 v0, v0, v2
	v_sub_u32_e32 v2, v6, v5
	v_and_b32_e32 v3, 0xffff0000, v4
	v_add_u32_e32 v2, 0x80, v2
	v_sub_u32_e32 v3, v7, v3
	v_sub_u32_e32 v1, v1, v65
	v_add_u32_e32 v0, 0x80, v0
	v_ashrrev_i32_e32 v2, 8, v2
	v_add_u32_e32 v3, 0x80, v3
	v_add_u32_e32 v1, 0x80, v1
	v_ashrrev_i32_e32 v0, 8, v0
	v_min_i32_e32 v2, 0x7f, v2
	v_ashrrev_i32_e32 v3, 8, v3
	v_ashrrev_i32_e32 v1, 8, v1
	v_min_i32_e32 v0, 0x7f, v0
	v_min_i32_sdwa v3, v3, s69 dst_sel:WORD_1 dst_unused:UNUSED_PAD src0_sel:DWORD src1_sel:DWORD
	v_min_i32_e32 v1, 0x7f, v1
	v_lshlrev_b32_e32 v2, 8, v2
	v_and_b32_e32 v2, 0xff00, v2
	v_and_b32_e32 v3, 0xff0000, v3
	v_perm_b32 v0, v1, v0, s76
	v_or3_b32 v0, v0, v2, v3
	ds_write_b32 v22, v0 offset:128
	v_mov_b32_e32 v0, v208
	v_mov_b32_e32 v1, v209
	v_mov_b32_e32 v2, v210
	v_mov_b32_e32 v3, v211
	v_mov_b32_e32 v4, v248
	v_mov_b32_e32 v5, v249
	v_mov_b32_e32 v6, v250
	v_mov_b32_e32 v7, v251
	ds_read_b64 v[110:111], v71
	s_waitcnt lgkmcnt(0)
	v_pk_add_f32 v[116:117], v[226:227], v[110:111] op_sel_hi:[1,0] neg_lo:[0,1] neg_hi:[0,1]
	v_pk_add_f32 v[118:119], v[224:225], v[110:111] op_sel_hi:[1,0] neg_lo:[0,1] neg_hi:[0,1]
	v_pk_mul_f32 v[116:117], v[110:111], v[116:117] op_sel:[1,0]
	v_pk_mul_f32 v[110:111], v[110:111], v[118:119] op_sel:[1,0]
	v_mov_b32_e32 v64, v1
	v_mov_b32_e32 v65, v2
	v_mov_b32_e32 v66, v5
	v_mov_b32_e32 v67, v6
	v_mov_b32_e32 v1, v3
	v_mov_b32_e32 v5, v7
	v_pk_fma_f32 v[116:117], v[64:65], v[116:117], v[66:67]
	v_pk_fma_f32 v[6:7], v[0:1], v[110:111], v[4:5]
	v_or_b32_e32 v2, 0x120, v109
	v_and_b32_sdwa v109, v116, v244 dst_sel:DWORD dst_unused:UNUSED_PAD src0_sel:WORD_1 src1_sel:DWORD
	v_and_b32_sdwa v110, v7, v244 dst_sel:DWORD dst_unused:UNUSED_PAD src0_sel:WORD_1 src1_sel:DWORD
	v_and_b32_sdwa v3, v117, v244 dst_sel:DWORD dst_unused:UNUSED_PAD src0_sel:WORD_1 src1_sel:DWORD
	v_add3_u32 v109, v116, v109, s67
	v_and_b32_sdwa v111, v6, v244 dst_sel:DWORD dst_unused:UNUSED_PAD src0_sel:WORD_1 src1_sel:DWORD
	v_add3_u32 v110, v7, v110, s67
	v_add3_u32 v3, v117, v3, s67
	v_and_b32_e32 v109, 0xffff0000, v109
	v_add3_u32 v118, v6, v111, s67
	v_and_b32_e32 v119, 0xffff0000, v110
	v_or_b32_sdwa v111, v119, v3 dst_sel:DWORD dst_unused:UNUSED_PAD src0_sel:DWORD src1_sel:WORD_1
	v_or_b32_sdwa v110, v118, v109 dst_sel:DWORD dst_unused:UNUSED_PAD src0_sel:WORD_1 src1_sel:DWORD
	v_add_u32_e32 v105, v2, v105
	ds_write_b64 v105, v[110:111]
	v_and_b32_e32 v110, 0xffff0000, v118
	v_sub_u32_e32 v109, v116, v109
	v_and_b32_e32 v3, 0xffff0000, v3
	v_sub_u32_e32 v6, v6, v110
	v_add_u32_e32 v109, 0x80, v109
	v_sub_u32_e32 v3, v117, v3
	v_sub_u32_e32 v7, v7, v119
	v_add_u32_e32 v6, 0x80, v6
	v_ashrrev_i32_e32 v109, 8, v109
	v_add_u32_e32 v3, 0x80, v3
	v_add_u32_e32 v7, 0x80, v7
	v_ashrrev_i32_e32 v6, 8, v6
	v_min_i32_e32 v109, 0x7f, v109
	v_ashrrev_i32_e32 v3, 8, v3
	v_ashrrev_i32_e32 v7, 8, v7
	v_min_i32_e32 v6, 0x7f, v6
	v_min_i32_sdwa v3, v3, s69 dst_sel:WORD_1 dst_unused:UNUSED_PAD src0_sel:DWORD src1_sel:DWORD
	v_min_i32_e32 v7, 0x7f, v7
	v_lshlrev_b32_e32 v109, 8, v109
	v_and_b32_e32 v109, 0xff00, v109
	v_and_b32_e32 v3, 0xff0000, v3
	v_perm_b32 v6, v7, v6, s76
	v_or3_b32 v3, v6, v109, v3
	ds_write_b32 v12, v3 offset:144
	ds_read_b64 v[6:7], v13
	v_add_u32_e32 v106, v2, v106
	v_add_u32_e32 v107, v2, v107
	s_waitcnt lgkmcnt(0)
; #define WAIT_L(n) asm volatile("s_waitcnt lgkmcnt(" #n ")" ::: "memory")
; #define BAR __builtin_amdgcn_s_barrier()
;     ...
;           _Pragma("unroll") for (int bj = 0; bj < 2; ++bj) _Pragma("unroll") for (int n = 0; n < 2; ++n) {
;             const int cc = bj * HALF + wc3 * 32 + n * 16 + fq3 * 4;
;             const float4 gm = *reinterpret_cast<const float4*>(g.gam + pn * BM + cc), bt = *reinterpret_cast<const float4*>(g.bet + pn * BM + cc);
;             _Pragma("unroll") for (int m = 0; m < 4; ++m) {
;               const int rr = wr3 * 64 + m * 16 + fr3;
;               const float2 ms = *reinterpret_cast<const float2*>(mr + (ai * HALF + rr) * 2);
;               f32x4 y = acc[ai][bj][m][n];
;               const float o0 = (y[0] - ms.x) * ms.y * gm.x + bt.x, o1 = (y[1] - ms.x) * ms.y * gm.y + bt.y;
;               const float o2 = (y[2] - ms.x) * ms.y * gm.z + bt.z, o3 = (y[3] - ms.x) * ms.y * gm.w + bt.w;
;               const unsigned h0 = f2bf(o0), h1 = f2bf(o1), h2 = f2bf(o2), h3 = f2bf(o3);
;               u32x2 ob; ob[0] = h0 | (h1 << 16); ob[1] = h2 | (h3 << 16);
;               *reinterpret_cast<u32x2*>(smem + (rr >> 1) * PIECE + (rr & 1) * 512 + cc * 2) = ob;
;               const int l0 = min(((int)__float_as_uint(o0) - (int)(h0 << 16) + 128) >> 8, 127);
;               const int l1 = min(((int)__float_as_uint(o1) - (int)(h1 << 16) + 128) >> 8, 127);
;               const int l2 = min(((int)__float_as_uint(o2) - (int)(h2 << 16) + 128) >> 8, 127);
;               const int l3 = min(((int)__float_as_uint(o3) - (int)(h3 << 16) + 128) >> 8, 127);
;               *reinterpret_cast<unsigned*>(smem + LOBASE + (rr >> 2) * PIECE + (rr & 3) * 256 + cc) =
;                   (unsigned)(l0 & 255) | ((unsigned)(l1 & 255) << 8) | ((unsigned)(l2 & 255) << 16) | ((unsigned)l3 << 24);
;             }
;           }
;           WAIT_L(0); BAR;
	v_pk_add_f32 v[110:111], v[146:147], v[6:7] op_sel_hi:[1,0] neg_lo:[0,1] neg_hi:[0,1]
	v_pk_add_f32 v[116:117], v[144:145], v[6:7] op_sel_hi:[1,0] neg_lo:[0,1] neg_hi:[0,1]
	v_pk_mul_f32 v[110:111], v[6:7], v[110:111] op_sel:[1,0]
	v_pk_mul_f32 v[6:7], v[6:7], v[116:117] op_sel:[1,0]
	v_pk_fma_f32 v[110:111], v[64:65], v[110:111], v[66:67]
	v_pk_fma_f32 v[6:7], v[0:1], v[6:7], v[4:5]
	v_and_b32_sdwa v109, v110, v244 dst_sel:DWORD dst_unused:UNUSED_PAD src0_sel:WORD_1 src1_sel:DWORD
	v_and_b32_sdwa v116, v7, v244 dst_sel:DWORD dst_unused:UNUSED_PAD src0_sel:WORD_1 src1_sel:DWORD
	v_and_b32_sdwa v3, v111, v244 dst_sel:DWORD dst_unused:UNUSED_PAD src0_sel:WORD_1 src1_sel:DWORD
	v_add3_u32 v109, v110, v109, s67
	v_and_b32_sdwa v117, v6, v244 dst_sel:DWORD dst_unused:UNUSED_PAD src0_sel:WORD_1 src1_sel:DWORD
	v_add3_u32 v116, v7, v116, s67
	v_add3_u32 v3, v111, v3, s67
	v_and_b32_e32 v109, 0xffff0000, v109
	v_add3_u32 v118, v6, v117, s67
	v_and_b32_e32 v119, 0xffff0000, v116
	v_or_b32_sdwa v117, v119, v3 dst_sel:DWORD dst_unused:UNUSED_PAD src0_sel:DWORD src1_sel:WORD_1
	v_or_b32_sdwa v116, v118, v109 dst_sel:DWORD dst_unused:UNUSED_PAD src0_sel:WORD_1 src1_sel:DWORD
	ds_write_b64 v106, v[116:117]
	v_and_b32_e32 v116, 0xffff0000, v118
	v_sub_u32_e32 v109, v110, v109
	v_and_b32_e32 v3, 0xffff0000, v3
	v_sub_u32_e32 v6, v6, v116
	v_add_u32_e32 v109, 0x80, v109
	v_sub_u32_e32 v3, v111, v3
	v_sub_u32_e32 v7, v7, v119
	v_add_u32_e32 v6, 0x80, v6
	v_ashrrev_i32_e32 v109, 8, v109
	v_add_u32_e32 v3, 0x80, v3
	v_add_u32_e32 v7, 0x80, v7
	v_ashrrev_i32_e32 v6, 8, v6
	v_min_i32_e32 v109, 0x7f, v109
	v_ashrrev_i32_e32 v3, 8, v3
	v_ashrrev_i32_e32 v7, 8, v7
	v_min_i32_e32 v6, 0x7f, v6
	v_min_i32_sdwa v3, v3, s69 dst_sel:WORD_1 dst_unused:UNUSED_PAD src0_sel:DWORD src1_sel:DWORD
	v_min_i32_e32 v7, 0x7f, v7
	v_lshlrev_b32_e32 v109, 8, v109
	v_and_b32_e32 v109, 0xff00, v109
	v_and_b32_e32 v3, 0xff0000, v3
	v_perm_b32 v6, v7, v6, s76
	v_or3_b32 v3, v6, v109, v3
	ds_write_b32 v14, v3 offset:144
	ds_read_b64 v[6:7], v15
	s_waitcnt lgkmcnt(0)
	v_pk_add_f32 v[110:111], v[114:115], v[6:7] op_sel_hi:[1,0] neg_lo:[0,1] neg_hi:[0,1]
	v_pk_add_f32 v[112:113], v[112:113], v[6:7] op_sel_hi:[1,0] neg_lo:[0,1] neg_hi:[0,1]
	v_pk_mul_f32 v[110:111], v[6:7], v[110:111] op_sel:[1,0]
	v_pk_mul_f32 v[6:7], v[6:7], v[112:113] op_sel:[1,0]
	v_pk_fma_f32 v[110:111], v[64:65], v[110:111], v[66:67]
	v_pk_fma_f32 v[6:7], v[0:1], v[6:7], v[4:5]
	v_and_b32_sdwa v109, v110, v244 dst_sel:DWORD dst_unused:UNUSED_PAD src0_sel:WORD_1 src1_sel:DWORD
	v_and_b32_sdwa v112, v7, v244 dst_sel:DWORD dst_unused:UNUSED_PAD src0_sel:WORD_1 src1_sel:DWORD
	v_and_b32_sdwa v3, v111, v244 dst_sel:DWORD dst_unused:UNUSED_PAD src0_sel:WORD_1 src1_sel:DWORD
	v_add3_u32 v109, v110, v109, s67
	v_and_b32_sdwa v113, v6, v244 dst_sel:DWORD dst_unused:UNUSED_PAD src0_sel:WORD_1 src1_sel:DWORD
	v_add3_u32 v112, v7, v112, s67
	v_add3_u32 v3, v111, v3, s67
	v_and_b32_e32 v109, 0xffff0000, v109
	v_add3_u32 v114, v6, v113, s67
	v_and_b32_e32 v115, 0xffff0000, v112
	v_or_b32_sdwa v113, v115, v3 dst_sel:DWORD dst_unused:UNUSED_PAD src0_sel:DWORD src1_sel:WORD_1
	v_or_b32_sdwa v112, v114, v109 dst_sel:DWORD dst_unused:UNUSED_PAD src0_sel:WORD_1 src1_sel:DWORD
	ds_write_b64 v107, v[112:113]
	v_and_b32_e32 v112, 0xffff0000, v114
	v_sub_u32_e32 v109, v110, v109
	v_and_b32_e32 v3, 0xffff0000, v3
	v_sub_u32_e32 v6, v6, v112
	v_add_u32_e32 v109, 0x80, v109
	v_sub_u32_e32 v3, v111, v3
	v_sub_u32_e32 v7, v7, v115
	v_add_u32_e32 v6, 0x80, v6
	v_ashrrev_i32_e32 v109, 8, v109
	v_add_u32_e32 v3, 0x80, v3
	v_add_u32_e32 v7, 0x80, v7
	v_ashrrev_i32_e32 v6, 8, v6
	v_min_i32_e32 v109, 0x7f, v109
	v_ashrrev_i32_e32 v3, 8, v3
	v_ashrrev_i32_e32 v7, 8, v7
	v_min_i32_e32 v6, 0x7f, v6
	v_min_i32_sdwa v3, v3, s69 dst_sel:WORD_1 dst_unused:UNUSED_PAD src0_sel:DWORD src1_sel:DWORD
	v_min_i32_e32 v7, 0x7f, v7
	v_lshlrev_b32_e32 v109, 8, v109
	v_and_b32_e32 v109, 0xff00, v109
	v_and_b32_e32 v3, 0xff0000, v3
	v_perm_b32 v6, v7, v6, s76
	v_or3_b32 v3, v6, v109, v3
	ds_write_b32 v20, v3 offset:144
	ds_read_b64 v[6:7], v21
	v_or_b32_e32 v109, 0xa000, v70
	v_or_b32_e32 v110, 0xc000, v70
	v_or_b32_e32 v111, 0xe000, v70
	v_or_b32_e32 v112, 0x2000, v68
	s_waitcnt lgkmcnt(0)
	v_pk_add_f32 v[90:91], v[90:91], v[6:7] op_sel_hi:[1,0] neg_lo:[0,1] neg_hi:[0,1]
	v_or_b32_e32 v113, 0x4000, v68
	v_pk_mul_f32 v[90:91], v[6:7], v[90:91] op_sel:[1,0]
	v_or_b32_e32 v114, 0x6000, v68
	v_pk_fma_f32 v[64:65], v[64:65], v[90:91], v[66:67]
	v_pk_add_f32 v[66:67], v[88:89], v[6:7] op_sel_hi:[1,0] neg_lo:[0,1] neg_hi:[0,1]
	v_and_b32_sdwa v3, v65, v244 dst_sel:DWORD dst_unused:UNUSED_PAD src0_sel:WORD_1 src1_sel:DWORD
	v_pk_mul_f32 v[6:7], v[6:7], v[66:67] op_sel:[1,0]
	v_add3_u32 v3, v65, v3, s67
	v_pk_fma_f32 v[0:1], v[0:1], v[6:7], v[4:5]
	v_and_b32_sdwa v4, v64, v244 dst_sel:DWORD dst_unused:UNUSED_PAD src0_sel:WORD_1 src1_sel:DWORD
	v_add3_u32 v4, v64, v4, s67
	v_and_b32_e32 v6, 0xffff0000, v4
	v_and_b32_sdwa v4, v1, v244 dst_sel:DWORD dst_unused:UNUSED_PAD src0_sel:WORD_1 src1_sel:DWORD
	v_and_b32_sdwa v5, v0, v244 dst_sel:DWORD dst_unused:UNUSED_PAD src0_sel:WORD_1 src1_sel:DWORD
	v_add3_u32 v4, v1, v4, s67
	v_add3_u32 v7, v0, v5, s67
	v_and_b32_e32 v66, 0xffff0000, v4
	v_add_u32_e32 v88, v2, v108
	v_and_b32_e32 v2, 0xffff0000, v7
	v_or_b32_sdwa v5, v66, v3 dst_sel:DWORD dst_unused:UNUSED_PAD src0_sel:DWORD src1_sel:WORD_1
	v_sub_u32_e32 v0, v0, v2
	v_sub_u32_e32 v2, v64, v6
	v_and_b32_e32 v3, 0xffff0000, v3
	v_add_u32_e32 v2, 0x80, v2
	v_sub_u32_e32 v3, v65, v3
	v_sub_u32_e32 v1, v1, v66
	v_add_u32_e32 v0, 0x80, v0
	v_ashrrev_i32_e32 v2, 8, v2
	v_add_u32_e32 v3, 0x80, v3
	v_add_u32_e32 v1, 0x80, v1
	v_ashrrev_i32_e32 v0, 8, v0
	v_min_i32_e32 v2, 0x7f, v2
	v_ashrrev_i32_e32 v3, 8, v3
	v_ashrrev_i32_e32 v1, 8, v1
	v_min_i32_e32 v0, 0x7f, v0
	v_min_i32_sdwa v3, v3, s69 dst_sel:WORD_1 dst_unused:UNUSED_PAD src0_sel:DWORD src1_sel:DWORD
	v_min_i32_e32 v1, 0x7f, v1
	v_lshlrev_b32_e32 v2, 8, v2
	v_and_b32_e32 v2, 0xff00, v2
	v_and_b32_e32 v3, 0xff0000, v3
	v_perm_b32 v0, v1, v0, s76
	v_or_b32_sdwa v4, v7, v6 dst_sel:DWORD dst_unused:UNUSED_PAD src0_sel:WORD_1 src1_sel:DWORD
	v_or3_b32 v0, v0, v2, v3
	ds_write_b64 v88, v[4:5]
	ds_write_b32 v22, v0 offset:144
	s_waitcnt lgkmcnt(0)
	s_barrier
; #define WAIT_L(n) asm volatile("s_waitcnt lgkmcnt(" #n ")" ::: "memory")
; #define BAR __builtin_amdgcn_s_barrier()
;     ...
;             _Pragma("unroll") for (int m = 0; m < 4; ++m) {
;               const int rr = wr3 * 64 + m * 16 + fr3;
;               const float2 ms = *reinterpret_cast<const float2*>(mr + (ai * HALF + rr) * 2);
;               f32x4 y = acc[ai][bj][m][n];
;               const float o0 = (y[0] - ms.x) * ms.y * gm.x + bt.x, o1 = (y[1] - ms.x) * ms.y * gm.y + bt.y;
;               const float o2 = (y[2] - ms.x) * ms.y * gm.z + bt.z, o3 = (y[3] - ms.x) * ms.y * gm.w + bt.w;
;               const unsigned h0 = f2bf(o0), h1 = f2bf(o1), h2 = f2bf(o2), h3 = f2bf(o3);
;               u32x2 ob; ob[0] = h0 | (h1 << 16); ob[1] = h2 | (h3 << 16);
;               *reinterpret_cast<u32x2*>(smem + (rr >> 1) * PIECE + (rr & 1) * 512 + cc * 2) = ob;
;               const int l0 = min(((int)__float_as_uint(o0) - (int)(h0 << 16) + 128) >> 8, 127);
;               const int l1 = min(((int)__float_as_uint(o1) - (int)(h1 << 16) + 128) >> 8, 127);
;               const int l2 = min(((int)__float_as_uint(o2) - (int)(h2 << 16) + 128) >> 8, 127);
;               const int l3 = min(((int)__float_as_uint(o3) - (int)(h3 << 16) + 128) >> 8, 127);
;               *reinterpret_cast<unsigned*>(smem + LOBASE + (rr >> 2) * PIECE + (rr & 3) * 256 + cc) =
;                   (unsigned)(l0 & 255) | ((unsigned)(l1 & 255) << 8) | ((unsigned)(l2 & 255) << 16) | ((unsigned)l3 << 24);
;             }
;     ...
;           WAIT_L(0); BAR;
;           const int hso = ((brow + ai * HALF + 16 * wave) * DM + pn * BM) * 2;
;           const int lso = (brow + ai * HALF + 16 * wave) * DM + pn * BM;
;           _Pragma("unroll") for (int i = 0; i < 8; ++i) {
;             const u32x4 v = *reinterpret_cast<const u32x4*>(smem + (wave * 8 + i) * PIECE + lane3 * 16);
;             __builtin_amdgcn_raw_buffer_store_b128(v, rsXB, hvo + i * (2 * DM * 2), hso, 0);
;           }
;           _Pragma("unroll") for (int i = 0; i < 4; ++i) {
;             const u32x4 v = *reinterpret_cast<const u32x4*>(smem + LOBASE + (wave * 4 + i) * PIECE + lane3 * 16);
;             __builtin_amdgcn_raw_buffer_store_b128(v, rsLO, lvo + i * (4 * DM), lso, 0);
;           }
	ds_read_b128 v[0:3], v74
	v_or_b32_e32 v89, 0x2000, v70
	v_or_b32_e32 v90, 0x4000, v70
	v_or_b32_e32 v91, 0x6000, v70
	v_or_b32_e32 v108, 0x8000, v70
	s_waitcnt lgkmcnt(0)
	buffer_store_dwordx4 v[0:3], v70, s[16:19], s22 offen
	ds_read_b128 v[0:3], v74 offset:1040
	s_waitcnt lgkmcnt(0)
	buffer_store_dwordx4 v[0:3], v89, s[16:19], s22 offen
	ds_read_b128 v[0:3], v74 offset:2080
	s_waitcnt lgkmcnt(0)
	buffer_store_dwordx4 v[0:3], v90, s[16:19], s22 offen
	ds_read_b128 v[0:3], v74 offset:3120
	s_waitcnt lgkmcnt(0)
	buffer_store_dwordx4 v[0:3], v91, s[16:19], s22 offen
	ds_read_b128 v[0:3], v74 offset:4160
	s_waitcnt lgkmcnt(0)
	buffer_store_dwordx4 v[0:3], v108, s[16:19], s22 offen
	ds_read_b128 v[0:3], v74 offset:5200
	s_waitcnt lgkmcnt(0)
	buffer_store_dwordx4 v[0:3], v109, s[16:19], s22 offen
	ds_read_b128 v[0:3], v74 offset:6240
	s_waitcnt lgkmcnt(0)
	buffer_store_dwordx4 v[0:3], v110, s[16:19], s22 offen
	ds_read_b128 v[0:3], v74 offset:7280
	s_waitcnt lgkmcnt(0)
	buffer_store_dwordx4 v[0:3], v111, s[16:19], s22 offen
	ds_read_b128 v[0:3], v69
	s_mov_b32 s22, s74
	s_waitcnt lgkmcnt(0)
	buffer_store_dwordx4 v[0:3], v68, s[20:23], s0 offen
	ds_read_b128 v[0:3], v69 offset:1040
	s_waitcnt lgkmcnt(0)
	buffer_store_dwordx4 v[0:3], v112, s[20:23], s0 offen
	ds_read_b128 v[0:3], v69 offset:2080
	s_waitcnt lgkmcnt(0)
	buffer_store_dwordx4 v[0:3], v113, s[20:23], s0 offen
	ds_read_b128 v[0:3], v69 offset:3120
	s_waitcnt lgkmcnt(0)
	buffer_store_dwordx4 v[0:3], v114, s[20:23], s0 offen
	s_waitcnt lgkmcnt(0)
	s_barrier
	s_nop 1
	v_mov_b32_e32 v0, v196
	v_mov_b32_e32 v1, v197
	v_mov_b32_e32 v2, v198
	v_mov_b32_e32 v3, v199
	v_mov_b32_e32 v4, v212
	v_mov_b32_e32 v5, v213
	v_mov_b32_e32 v6, v214
	v_mov_b32_e32 v7, v215
	ds_read_b64 v[116:117], v71 offset:1024
	s_add_i32 s0, s0, 0x40000
	s_waitcnt lgkmcnt(0)
	v_pk_add_f32 v[82:83], v[82:83], v[116:117] op_sel_hi:[1,0] neg_lo:[0,1] neg_hi:[0,1]
	s_nop 0
	v_pk_mul_f32 v[82:83], v[116:117], v[82:83] op_sel:[1,0]
	v_pk_add_f32 v[80:81], v[80:81], v[116:117] op_sel_hi:[1,0] neg_lo:[0,1] neg_hi:[0,1]
	v_mov_b32_e32 v64, v1
	v_mov_b32_e32 v65, v2
	v_mov_b32_e32 v66, v5
	v_mov_b32_e32 v67, v6
	v_pk_fma_f32 v[82:83], v[64:65], v[82:83], v[66:67]
	v_pk_mul_f32 v[80:81], v[116:117], v[80:81] op_sel:[1,0]
	v_mov_b32_e32 v1, v3
	v_mov_b32_e32 v5, v7
	v_and_b32_sdwa v6, v83, v244 dst_sel:DWORD dst_unused:UNUSED_PAD src0_sel:WORD_1 src1_sel:DWORD
	v_and_b32_sdwa v7, v82, v244 dst_sel:DWORD dst_unused:UNUSED_PAD src0_sel:WORD_1 src1_sel:DWORD
	v_pk_fma_f32 v[2:3], v[0:1], v[80:81], v[4:5]
	v_add3_u32 v80, v83, v6, s67
	v_add3_u32 v6, v82, v7, s67
	v_and_b32_e32 v81, 0xffff0000, v6
	v_and_b32_sdwa v6, v3, v244 dst_sel:DWORD dst_unused:UNUSED_PAD src0_sel:WORD_1 src1_sel:DWORD
	v_and_b32_sdwa v7, v2, v244 dst_sel:DWORD dst_unused:UNUSED_PAD src0_sel:WORD_1 src1_sel:DWORD
	v_add3_u32 v6, v3, v6, s67
	v_add3_u32 v115, v2, v7, s67
	v_and_b32_e32 v116, 0xffff0000, v6
	v_or_b32_sdwa v7, v116, v80 dst_sel:DWORD dst_unused:UNUSED_PAD src0_sel:DWORD src1_sel:WORD_1
	v_or_b32_sdwa v6, v115, v81 dst_sel:DWORD dst_unused:UNUSED_PAD src0_sel:WORD_1 src1_sel:DWORD
	ds_write_b64 v73, v[6:7]
	v_and_b32_e32 v6, 0xffff0000, v115
	v_sub_u32_e32 v2, v2, v6
	v_sub_u32_e32 v6, v82, v81
	v_and_b32_e32 v7, 0xffff0000, v80
	v_add_u32_e32 v6, 0x80, v6
	v_sub_u32_e32 v7, v83, v7
	v_sub_u32_e32 v3, v3, v116
	v_add_u32_e32 v2, 0x80, v2
	v_ashrrev_i32_e32 v6, 8, v6
	v_add_u32_e32 v7, 0x80, v7
	v_add_u32_e32 v3, 0x80, v3
	v_ashrrev_i32_e32 v2, 8, v2
	v_min_i32_e32 v6, 0x7f, v6
	v_ashrrev_i32_e32 v7, 8, v7
	v_ashrrev_i32_e32 v3, 8, v3
	v_min_i32_e32 v2, 0x7f, v2
	v_min_i32_sdwa v7, v7, s69 dst_sel:WORD_1 dst_unused:UNUSED_PAD src0_sel:DWORD src1_sel:DWORD
	v_min_i32_e32 v3, 0x7f, v3
	v_lshlrev_b32_e32 v6, 8, v6
	v_and_b32_e32 v6, 0xff00, v6
	v_and_b32_e32 v7, 0xff0000, v7
	v_perm_b32 v2, v3, v2, s76
	v_or3_b32 v2, v2, v6, v7
	ds_write_b32 v12, v2
	ds_read_b64 v[2:3], v13 offset:1024
	s_waitcnt lgkmcnt(0)
	v_pk_add_f32 v[6:7], v[86:87], v[2:3] op_sel_hi:[1,0] neg_lo:[0,1] neg_hi:[0,1]
	s_nop 0
	v_pk_mul_f32 v[6:7], v[2:3], v[6:7] op_sel:[1,0]
	v_pk_add_f32 v[80:81], v[84:85], v[2:3] op_sel_hi:[1,0] neg_lo:[0,1] neg_hi:[0,1]
	v_pk_fma_f32 v[6:7], v[64:65], v[6:7], v[66:67]
	v_pk_mul_f32 v[2:3], v[2:3], v[80:81] op_sel:[1,0]
	v_and_b32_sdwa v80, v6, v244 dst_sel:DWORD dst_unused:UNUSED_PAD src0_sel:WORD_1 src1_sel:DWORD
	v_pk_fma_f32 v[2:3], v[0:1], v[2:3], v[4:5]
	v_add3_u32 v80, v6, v80, s67
	v_and_b32_e32 v82, 0xffff0000, v80
	v_and_b32_sdwa v80, v3, v244 dst_sel:DWORD dst_unused:UNUSED_PAD src0_sel:WORD_1 src1_sel:DWORD
	v_and_b32_sdwa v73, v7, v244 dst_sel:DWORD dst_unused:UNUSED_PAD src0_sel:WORD_1 src1_sel:DWORD
	v_and_b32_sdwa v81, v2, v244 dst_sel:DWORD dst_unused:UNUSED_PAD src0_sel:WORD_1 src1_sel:DWORD
	v_add3_u32 v80, v3, v80, s67
	v_add3_u32 v73, v7, v73, s67
	v_add3_u32 v83, v2, v81, s67
	v_and_b32_e32 v84, 0xffff0000, v80
	v_or_b32_sdwa v81, v84, v73 dst_sel:DWORD dst_unused:UNUSED_PAD src0_sel:DWORD src1_sel:WORD_1
	v_or_b32_sdwa v80, v83, v82 dst_sel:DWORD dst_unused:UNUSED_PAD src0_sel:WORD_1 src1_sel:DWORD
	ds_write_b64 v75, v[80:81]
	v_and_b32_e32 v75, 0xffff0000, v83
	v_sub_u32_e32 v6, v6, v82
	v_and_b32_e32 v73, 0xffff0000, v73
	v_sub_u32_e32 v2, v2, v75
	v_add_u32_e32 v6, 0x80, v6
	v_sub_u32_e32 v7, v7, v73
	v_sub_u32_e32 v3, v3, v84
	v_add_u32_e32 v2, 0x80, v2
	v_ashrrev_i32_e32 v6, 8, v6
	v_add_u32_e32 v7, 0x80, v7
	v_add_u32_e32 v3, 0x80, v3
	v_ashrrev_i32_e32 v2, 8, v2
	v_min_i32_e32 v6, 0x7f, v6
	v_ashrrev_i32_e32 v7, 8, v7
	v_ashrrev_i32_e32 v3, 8, v3
	v_min_i32_e32 v2, 0x7f, v2
	v_min_i32_sdwa v7, v7, s69 dst_sel:WORD_1 dst_unused:UNUSED_PAD src0_sel:DWORD src1_sel:DWORD
	v_min_i32_e32 v3, 0x7f, v3
	v_lshlrev_b32_e32 v6, 8, v6
	v_and_b32_e32 v6, 0xff00, v6
	v_and_b32_e32 v7, 0xff0000, v7
	v_perm_b32 v2, v3, v2, s76
	v_or3_b32 v2, v2, v6, v7
	ds_write_b32 v14, v2
	ds_read_b64 v[2:3], v15 offset:1024
	s_waitcnt lgkmcnt(0)
;     ...
;           _Pragma("unroll") for (int bj = 0; bj < 2; ++bj) _Pragma("unroll") for (int n = 0; n < 2; ++n) {
;             const int cc = bj * HALF + wc3 * 32 + n * 16 + fq3 * 4;
;             const float4 gm = *reinterpret_cast<const float4*>(g.gam + pn * BM + cc), bt = *reinterpret_cast<const float4*>(g.bet + pn * BM + cc);
;             _Pragma("unroll") for (int m = 0; m < 4; ++m) {
;               const int rr = wr3 * 64 + m * 16 + fr3;
;               const float2 ms = *reinterpret_cast<const float2*>(mr + (ai * HALF + rr) * 2);
;               f32x4 y = acc[ai][bj][m][n];
;               const float o0 = (y[0] - ms.x) * ms.y * gm.x + bt.x, o1 = (y[1] - ms.x) * ms.y * gm.y + bt.y;
;               const float o2 = (y[2] - ms.x) * ms.y * gm.z + bt.z, o3 = (y[3] - ms.x) * ms.y * gm.w + bt.w;
;               const unsigned h0 = f2bf(o0), h1 = f2bf(o1), h2 = f2bf(o2), h3 = f2bf(o3);
;               u32x2 ob; ob[0] = h0 | (h1 << 16); ob[1] = h2 | (h3 << 16);
;               *reinterpret_cast<u32x2*>(smem + (rr >> 1) * PIECE + (rr & 1) * 512 + cc * 2) = ob;
;               const int l0 = min(((int)__float_as_uint(o0) - (int)(h0 << 16) + 128) >> 8, 127);
;               const int l1 = min(((int)__float_as_uint(o1) - (int)(h1 << 16) + 128) >> 8, 127);
;               const int l2 = min(((int)__float_as_uint(o2) - (int)(h2 << 16) + 128) >> 8, 127);
;               const int l3 = min(((int)__float_as_uint(o3) - (int)(h3 << 16) + 128) >> 8, 127);
;               *reinterpret_cast<unsigned*>(smem + LOBASE + (rr >> 2) * PIECE + (rr & 3) * 256 + cc) =
;                   (unsigned)(l0 & 255) | ((unsigned)(l1 & 255) << 8) | ((unsigned)(l2 & 255) << 16) | ((unsigned)l3 << 24);
;             }
	v_pk_add_f32 v[6:7], v[94:95], v[2:3] op_sel_hi:[1,0] neg_lo:[0,1] neg_hi:[0,1]
	v_pk_add_f32 v[80:81], v[92:93], v[2:3] op_sel_hi:[1,0] neg_lo:[0,1] neg_hi:[0,1]
	v_pk_mul_f32 v[6:7], v[2:3], v[6:7] op_sel:[1,0]
	v_pk_mul_f32 v[2:3], v[2:3], v[80:81] op_sel:[1,0]
	v_pk_fma_f32 v[6:7], v[64:65], v[6:7], v[66:67]
	v_pk_fma_f32 v[2:3], v[0:1], v[2:3], v[4:5]
	v_and_b32_sdwa v75, v6, v244 dst_sel:DWORD dst_unused:UNUSED_PAD src0_sel:WORD_1 src1_sel:DWORD
	v_and_b32_sdwa v80, v3, v244 dst_sel:DWORD dst_unused:UNUSED_PAD src0_sel:WORD_1 src1_sel:DWORD
	v_and_b32_sdwa v73, v7, v244 dst_sel:DWORD dst_unused:UNUSED_PAD src0_sel:WORD_1 src1_sel:DWORD
	v_add3_u32 v75, v6, v75, s67
	v_and_b32_sdwa v81, v2, v244 dst_sel:DWORD dst_unused:UNUSED_PAD src0_sel:WORD_1 src1_sel:DWORD
	v_add3_u32 v80, v3, v80, s67
	v_add3_u32 v73, v7, v73, s67
	v_and_b32_e32 v75, 0xffff0000, v75
	v_add3_u32 v82, v2, v81, s67
	v_and_b32_e32 v83, 0xffff0000, v80
	v_or_b32_sdwa v81, v83, v73 dst_sel:DWORD dst_unused:UNUSED_PAD src0_sel:DWORD src1_sel:WORD_1
	v_or_b32_sdwa v80, v82, v75 dst_sel:DWORD dst_unused:UNUSED_PAD src0_sel:WORD_1 src1_sel:DWORD
	ds_write_b64 v96, v[80:81]
	v_and_b32_e32 v80, 0xffff0000, v82
	v_sub_u32_e32 v6, v6, v75
	v_and_b32_e32 v73, 0xffff0000, v73
	v_sub_u32_e32 v2, v2, v80
	v_add_u32_e32 v6, 0x80, v6
	v_sub_u32_e32 v7, v7, v73
	v_sub_u32_e32 v3, v3, v83
	v_add_u32_e32 v2, 0x80, v2
	v_ashrrev_i32_e32 v6, 8, v6
	v_add_u32_e32 v7, 0x80, v7
	v_add_u32_e32 v3, 0x80, v3
	v_ashrrev_i32_e32 v2, 8, v2
	v_min_i32_e32 v6, 0x7f, v6
	v_ashrrev_i32_e32 v7, 8, v7
	v_ashrrev_i32_e32 v3, 8, v3
	v_min_i32_e32 v2, 0x7f, v2
	v_min_i32_sdwa v7, v7, s69 dst_sel:WORD_1 dst_unused:UNUSED_PAD src0_sel:DWORD src1_sel:DWORD
	v_min_i32_e32 v3, 0x7f, v3
	v_lshlrev_b32_e32 v6, 8, v6
	v_and_b32_e32 v6, 0xff00, v6
	v_and_b32_e32 v7, 0xff0000, v7
	v_perm_b32 v2, v3, v2, s76
	v_or3_b32 v2, v2, v6, v7
	ds_write_b32 v20, v2
	ds_read_b64 v[2:3], v21 offset:1024
	s_waitcnt lgkmcnt(0)
	v_pk_add_f32 v[6:7], v[78:79], v[2:3] op_sel_hi:[1,0] neg_lo:[0,1] neg_hi:[0,1]
	s_nop 0
	v_pk_mul_f32 v[6:7], v[2:3], v[6:7] op_sel:[1,0]
	s_nop 0
	v_pk_fma_f32 v[6:7], v[64:65], v[6:7], v[66:67]
	v_pk_add_f32 v[64:65], v[76:77], v[2:3] op_sel_hi:[1,0] neg_lo:[0,1] neg_hi:[0,1]
	s_nop 0
	v_pk_mul_f32 v[2:3], v[2:3], v[64:65] op_sel:[1,0]
	s_nop 0
	v_pk_fma_f32 v[0:1], v[0:1], v[2:3], v[4:5]
	v_and_b32_sdwa v2, v7, v244 dst_sel:DWORD dst_unused:UNUSED_PAD src0_sel:WORD_1 src1_sel:DWORD
	v_and_b32_sdwa v3, v6, v244 dst_sel:DWORD dst_unused:UNUSED_PAD src0_sel:WORD_1 src1_sel:DWORD
	v_add3_u32 v4, v7, v2, s67
	v_add3_u32 v2, v6, v3, s67
	v_and_b32_e32 v5, 0xffff0000, v2
	v_and_b32_sdwa v2, v1, v244 dst_sel:DWORD dst_unused:UNUSED_PAD src0_sel:WORD_1 src1_sel:DWORD
	v_and_b32_sdwa v3, v0, v244 dst_sel:DWORD dst_unused:UNUSED_PAD src0_sel:WORD_1 src1_sel:DWORD
	v_add3_u32 v2, v1, v2, s67
	v_add3_u32 v64, v0, v3, s67
	v_and_b32_e32 v65, 0xffff0000, v2
	v_or_b32_sdwa v3, v65, v4 dst_sel:DWORD dst_unused:UNUSED_PAD src0_sel:DWORD src1_sel:WORD_1
	v_or_b32_sdwa v2, v64, v5 dst_sel:DWORD dst_unused:UNUSED_PAD src0_sel:WORD_1 src1_sel:DWORD
	ds_write_b64 v97, v[2:3]
	v_and_b32_e32 v2, 0xffff0000, v64
	v_sub_u32_e32 v0, v0, v2
	v_sub_u32_e32 v2, v6, v5
	v_and_b32_e32 v3, 0xffff0000, v4
	v_add_u32_e32 v2, 0x80, v2
	v_sub_u32_e32 v3, v7, v3
	v_sub_u32_e32 v1, v1, v65
	v_add_u32_e32 v0, 0x80, v0
	v_ashrrev_i32_e32 v2, 8, v2
	v_add_u32_e32 v3, 0x80, v3
	v_add_u32_e32 v1, 0x80, v1
	v_ashrrev_i32_e32 v0, 8, v0
	v_min_i32_e32 v2, 0x7f, v2
	v_ashrrev_i32_e32 v3, 8, v3
	v_ashrrev_i32_e32 v1, 8, v1
	v_min_i32_e32 v0, 0x7f, v0
	v_min_i32_sdwa v3, v3, s69 dst_sel:WORD_1 dst_unused:UNUSED_PAD src0_sel:DWORD src1_sel:DWORD
	v_min_i32_e32 v1, 0x7f, v1
	v_lshlrev_b32_e32 v2, 8, v2
	v_and_b32_e32 v2, 0xff00, v2
	v_and_b32_e32 v3, 0xff0000, v3
	v_perm_b32 v0, v1, v0, s76
	v_or3_b32 v0, v0, v2, v3
	ds_write_b32 v22, v0
	v_mov_b32_e32 v0, v200
	v_mov_b32_e32 v1, v201
	v_mov_b32_e32 v2, v202
	v_mov_b32_e32 v3, v203
	v_mov_b32_e32 v4, v220
	v_mov_b32_e32 v5, v221
	v_mov_b32_e32 v6, v222
	v_mov_b32_e32 v7, v223
	ds_read_b64 v[76:77], v71 offset:1024
	s_waitcnt lgkmcnt(0)
	v_pk_add_f32 v[62:63], v[62:63], v[76:77] op_sel_hi:[1,0] neg_lo:[0,1] neg_hi:[0,1]
	s_nop 0
	v_pk_mul_f32 v[62:63], v[76:77], v[62:63] op_sel:[1,0]
	v_pk_add_f32 v[60:61], v[60:61], v[76:77] op_sel_hi:[1,0] neg_lo:[0,1] neg_hi:[0,1]
	v_mov_b32_e32 v64, v1
	v_mov_b32_e32 v65, v2
	v_mov_b32_e32 v66, v5
	v_mov_b32_e32 v67, v6
	v_pk_fma_f32 v[62:63], v[64:65], v[62:63], v[66:67]
	v_pk_mul_f32 v[60:61], v[76:77], v[60:61] op_sel:[1,0]
	v_mov_b32_e32 v1, v3
	v_mov_b32_e32 v5, v7
	v_and_b32_sdwa v6, v63, v244 dst_sel:DWORD dst_unused:UNUSED_PAD src0_sel:WORD_1 src1_sel:DWORD
	v_and_b32_sdwa v7, v62, v244 dst_sel:DWORD dst_unused:UNUSED_PAD src0_sel:WORD_1 src1_sel:DWORD
	v_pk_fma_f32 v[2:3], v[0:1], v[60:61], v[4:5]
	v_add3_u32 v60, v63, v6, s67
	v_add3_u32 v6, v62, v7, s67
	v_and_b32_e32 v61, 0xffff0000, v6
	v_and_b32_sdwa v6, v3, v244 dst_sel:DWORD dst_unused:UNUSED_PAD src0_sel:WORD_1 src1_sel:DWORD
	v_and_b32_sdwa v7, v2, v244 dst_sel:DWORD dst_unused:UNUSED_PAD src0_sel:WORD_1 src1_sel:DWORD
	v_add3_u32 v6, v3, v6, s67
	v_add3_u32 v73, v2, v7, s67
	v_and_b32_e32 v75, 0xffff0000, v6
	v_or_b32_sdwa v7, v75, v60 dst_sel:DWORD dst_unused:UNUSED_PAD src0_sel:DWORD src1_sel:WORD_1
	v_or_b32_sdwa v6, v73, v61 dst_sel:DWORD dst_unused:UNUSED_PAD src0_sel:WORD_1 src1_sel:DWORD
	ds_write_b64 v23, v[6:7]
	v_and_b32_e32 v6, 0xffff0000, v73
	v_sub_u32_e32 v2, v2, v6
	v_sub_u32_e32 v6, v62, v61
	v_and_b32_e32 v7, 0xffff0000, v60
	v_add_u32_e32 v6, 0x80, v6
	v_sub_u32_e32 v7, v63, v7
	v_sub_u32_e32 v3, v3, v75
	v_add_u32_e32 v2, 0x80, v2
	v_ashrrev_i32_e32 v6, 8, v6
	v_add_u32_e32 v7, 0x80, v7
	v_add_u32_e32 v3, 0x80, v3
	v_ashrrev_i32_e32 v2, 8, v2
	v_min_i32_e32 v6, 0x7f, v6
	v_ashrrev_i32_e32 v7, 8, v7
	v_ashrrev_i32_e32 v3, 8, v3
	v_min_i32_e32 v2, 0x7f, v2
	v_min_i32_sdwa v7, v7, s69 dst_sel:WORD_1 dst_unused:UNUSED_PAD src0_sel:DWORD src1_sel:DWORD
	v_min_i32_e32 v3, 0x7f, v3
	v_lshlrev_b32_e32 v6, 8, v6
	v_and_b32_e32 v6, 0xff00, v6
	v_and_b32_e32 v7, 0xff0000, v7
	v_perm_b32 v2, v3, v2, s76
	v_or3_b32 v2, v2, v6, v7
	ds_write_b32 v12, v2 offset:16
	ds_read_b64 v[2:3], v13 offset:1024
	s_waitcnt lgkmcnt(0)
;     ...
;           _Pragma("unroll") for (int bj = 0; bj < 2; ++bj) _Pragma("unroll") for (int n = 0; n < 2; ++n) {
;             const int cc = bj * HALF + wc3 * 32 + n * 16 + fq3 * 4;
;             const float4 gm = *reinterpret_cast<const float4*>(g.gam + pn * BM + cc), bt = *reinterpret_cast<const float4*>(g.bet + pn * BM + cc);
;             _Pragma("unroll") for (int m = 0; m < 4; ++m) {
;               const int rr = wr3 * 64 + m * 16 + fr3;
;               const float2 ms = *reinterpret_cast<const float2*>(mr + (ai * HALF + rr) * 2);
;               f32x4 y = acc[ai][bj][m][n];
;               const float o0 = (y[0] - ms.x) * ms.y * gm.x + bt.x, o1 = (y[1] - ms.x) * ms.y * gm.y + bt.y;
;               const float o2 = (y[2] - ms.x) * ms.y * gm.z + bt.z, o3 = (y[3] - ms.x) * ms.y * gm.w + bt.w;
;               const unsigned h0 = f2bf(o0), h1 = f2bf(o1), h2 = f2bf(o2), h3 = f2bf(o3);
;               u32x2 ob; ob[0] = h0 | (h1 << 16); ob[1] = h2 | (h3 << 16);
;               *reinterpret_cast<u32x2*>(smem + (rr >> 1) * PIECE + (rr & 1) * 512 + cc * 2) = ob;
;               const int l0 = min(((int)__float_as_uint(o0) - (int)(h0 << 16) + 128) >> 8, 127);
;               const int l1 = min(((int)__float_as_uint(o1) - (int)(h1 << 16) + 128) >> 8, 127);
;               const int l2 = min(((int)__float_as_uint(o2) - (int)(h2 << 16) + 128) >> 8, 127);
;               const int l3 = min(((int)__float_as_uint(o3) - (int)(h3 << 16) + 128) >> 8, 127);
;               *reinterpret_cast<unsigned*>(smem + LOBASE + (rr >> 2) * PIECE + (rr & 3) * 256 + cc) =
;                   (unsigned)(l0 & 255) | ((unsigned)(l1 & 255) << 8) | ((unsigned)(l2 & 255) << 16) | ((unsigned)l3 << 24);
;             }
	v_pk_add_f32 v[6:7], v[46:47], v[2:3] op_sel_hi:[1,0] neg_lo:[0,1] neg_hi:[0,1]
	s_nop 0
	v_pk_mul_f32 v[6:7], v[2:3], v[6:7] op_sel:[1,0]
	v_pk_add_f32 v[44:45], v[44:45], v[2:3] op_sel_hi:[1,0] neg_lo:[0,1] neg_hi:[0,1]
	v_pk_fma_f32 v[6:7], v[64:65], v[6:7], v[66:67]
	v_pk_mul_f32 v[2:3], v[2:3], v[44:45] op_sel:[1,0]
	v_and_b32_sdwa v44, v6, v244 dst_sel:DWORD dst_unused:UNUSED_PAD src0_sel:WORD_1 src1_sel:DWORD
	v_pk_fma_f32 v[2:3], v[0:1], v[2:3], v[4:5]
	v_add3_u32 v44, v6, v44, s67
	v_and_b32_e32 v46, 0xffff0000, v44
	v_and_b32_sdwa v44, v3, v244 dst_sel:DWORD dst_unused:UNUSED_PAD src0_sel:WORD_1 src1_sel:DWORD
	v_and_b32_sdwa v23, v7, v244 dst_sel:DWORD dst_unused:UNUSED_PAD src0_sel:WORD_1 src1_sel:DWORD
	v_and_b32_sdwa v45, v2, v244 dst_sel:DWORD dst_unused:UNUSED_PAD src0_sel:WORD_1 src1_sel:DWORD
	v_add3_u32 v44, v3, v44, s67
	v_add3_u32 v23, v7, v23, s67
	v_add3_u32 v47, v2, v45, s67
	v_and_b32_e32 v60, 0xffff0000, v44
	v_or_b32_sdwa v45, v60, v23 dst_sel:DWORD dst_unused:UNUSED_PAD src0_sel:DWORD src1_sel:WORD_1
	v_or_b32_sdwa v44, v47, v46 dst_sel:DWORD dst_unused:UNUSED_PAD src0_sel:WORD_1 src1_sel:DWORD
	ds_write_b64 v98, v[44:45]
	v_and_b32_e32 v44, 0xffff0000, v47
	v_sub_u32_e32 v6, v6, v46
	v_and_b32_e32 v23, 0xffff0000, v23
	v_sub_u32_e32 v2, v2, v44
	v_add_u32_e32 v6, 0x80, v6
	v_sub_u32_e32 v7, v7, v23
	v_sub_u32_e32 v3, v3, v60
	v_add_u32_e32 v2, 0x80, v2
	v_ashrrev_i32_e32 v6, 8, v6
	v_add_u32_e32 v7, 0x80, v7
	v_add_u32_e32 v3, 0x80, v3
	v_ashrrev_i32_e32 v2, 8, v2
	v_min_i32_e32 v6, 0x7f, v6
	v_ashrrev_i32_e32 v7, 8, v7
	v_ashrrev_i32_e32 v3, 8, v3
	v_min_i32_e32 v2, 0x7f, v2
	v_min_i32_sdwa v7, v7, s69 dst_sel:WORD_1 dst_unused:UNUSED_PAD src0_sel:DWORD src1_sel:DWORD
	v_min_i32_e32 v3, 0x7f, v3
	v_lshlrev_b32_e32 v6, 8, v6
	v_and_b32_e32 v6, 0xff00, v6
	v_and_b32_e32 v7, 0xff0000, v7
	v_perm_b32 v2, v3, v2, s76
	v_or3_b32 v2, v2, v6, v7
	ds_write_b32 v14, v2 offset:16
	ds_read_b64 v[2:3], v15 offset:1024
	s_waitcnt lgkmcnt(0)
	v_pk_add_f32 v[6:7], v[42:43], v[2:3] op_sel_hi:[1,0] neg_lo:[0,1] neg_hi:[0,1]
	s_nop 0
	v_pk_mul_f32 v[6:7], v[2:3], v[6:7] op_sel:[1,0]
	v_pk_add_f32 v[40:41], v[40:41], v[2:3] op_sel_hi:[1,0] neg_lo:[0,1] neg_hi:[0,1]
	v_pk_fma_f32 v[6:7], v[64:65], v[6:7], v[66:67]
	v_pk_mul_f32 v[2:3], v[2:3], v[40:41] op_sel:[1,0]
	v_and_b32_sdwa v40, v6, v244 dst_sel:DWORD dst_unused:UNUSED_PAD src0_sel:WORD_1 src1_sel:DWORD
	v_pk_fma_f32 v[2:3], v[0:1], v[2:3], v[4:5]
	v_add3_u32 v40, v6, v40, s67
	v_and_b32_e32 v42, 0xffff0000, v40
	v_and_b32_sdwa v40, v3, v244 dst_sel:DWORD dst_unused:UNUSED_PAD src0_sel:WORD_1 src1_sel:DWORD
	v_and_b32_sdwa v23, v7, v244 dst_sel:DWORD dst_unused:UNUSED_PAD src0_sel:WORD_1 src1_sel:DWORD
	v_and_b32_sdwa v41, v2, v244 dst_sel:DWORD dst_unused:UNUSED_PAD src0_sel:WORD_1 src1_sel:DWORD
	v_add3_u32 v40, v3, v40, s67
	v_add3_u32 v23, v7, v23, s67
	v_add3_u32 v43, v2, v41, s67
	v_and_b32_e32 v44, 0xffff0000, v40
	v_or_b32_sdwa v41, v44, v23 dst_sel:DWORD dst_unused:UNUSED_PAD src0_sel:DWORD src1_sel:WORD_1
	v_or_b32_sdwa v40, v43, v42 dst_sel:DWORD dst_unused:UNUSED_PAD src0_sel:WORD_1 src1_sel:DWORD
	ds_write_b64 v99, v[40:41]
	v_and_b32_e32 v40, 0xffff0000, v43
	v_sub_u32_e32 v6, v6, v42
	v_and_b32_e32 v23, 0xffff0000, v23
	v_sub_u32_e32 v2, v2, v40
	v_add_u32_e32 v6, 0x80, v6
	v_sub_u32_e32 v7, v7, v23
	v_sub_u32_e32 v3, v3, v44
	v_add_u32_e32 v2, 0x80, v2
	v_ashrrev_i32_e32 v6, 8, v6
	v_add_u32_e32 v7, 0x80, v7
	v_add_u32_e32 v3, 0x80, v3
	v_ashrrev_i32_e32 v2, 8, v2
	v_min_i32_e32 v6, 0x7f, v6
	v_ashrrev_i32_e32 v7, 8, v7
	v_ashrrev_i32_e32 v3, 8, v3
	v_min_i32_e32 v2, 0x7f, v2
	v_min_i32_sdwa v7, v7, s69 dst_sel:WORD_1 dst_unused:UNUSED_PAD src0_sel:DWORD src1_sel:DWORD
	v_min_i32_e32 v3, 0x7f, v3
	v_lshlrev_b32_e32 v6, 8, v6
	v_and_b32_e32 v6, 0xff00, v6
	v_and_b32_e32 v7, 0xff0000, v7
	v_perm_b32 v2, v3, v2, s76
	v_or3_b32 v2, v2, v6, v7
	ds_write_b32 v20, v2 offset:16
	ds_read_b64 v[2:3], v21 offset:1024
	s_waitcnt lgkmcnt(0)
	v_pk_add_f32 v[6:7], v[58:59], v[2:3] op_sel_hi:[1,0] neg_lo:[0,1] neg_hi:[0,1]
	s_nop 0
	v_pk_mul_f32 v[6:7], v[2:3], v[6:7] op_sel:[1,0]
	v_pk_add_f32 v[40:41], v[56:57], v[2:3] op_sel_hi:[1,0] neg_lo:[0,1] neg_hi:[0,1]
	v_pk_fma_f32 v[6:7], v[64:65], v[6:7], v[66:67]
	v_pk_mul_f32 v[2:3], v[2:3], v[40:41] op_sel:[1,0]
	s_nop 0
	v_pk_fma_f32 v[0:1], v[0:1], v[2:3], v[4:5]
	v_and_b32_sdwa v2, v7, v244 dst_sel:DWORD dst_unused:UNUSED_PAD src0_sel:WORD_1 src1_sel:DWORD
	v_and_b32_sdwa v3, v6, v244 dst_sel:DWORD dst_unused:UNUSED_PAD src0_sel:WORD_1 src1_sel:DWORD
	v_add3_u32 v4, v7, v2, s67
	v_add3_u32 v2, v6, v3, s67
	v_and_b32_e32 v5, 0xffff0000, v2
	v_and_b32_sdwa v2, v1, v244 dst_sel:DWORD dst_unused:UNUSED_PAD src0_sel:WORD_1 src1_sel:DWORD
	v_and_b32_sdwa v3, v0, v244 dst_sel:DWORD dst_unused:UNUSED_PAD src0_sel:WORD_1 src1_sel:DWORD
	v_add3_u32 v2, v1, v2, s67
	v_add3_u32 v23, v0, v3, s67
	v_and_b32_e32 v40, 0xffff0000, v2
	v_or_b32_sdwa v3, v40, v4 dst_sel:DWORD dst_unused:UNUSED_PAD src0_sel:DWORD src1_sel:WORD_1
	v_or_b32_sdwa v2, v23, v5 dst_sel:DWORD dst_unused:UNUSED_PAD src0_sel:WORD_1 src1_sel:DWORD
	ds_write_b64 v100, v[2:3]
	v_and_b32_e32 v2, 0xffff0000, v23
	v_sub_u32_e32 v0, v0, v2
	v_sub_u32_e32 v2, v6, v5
	v_and_b32_e32 v3, 0xffff0000, v4
	v_add_u32_e32 v2, 0x80, v2
	v_sub_u32_e32 v3, v7, v3
	v_sub_u32_e32 v1, v1, v40
	v_add_u32_e32 v0, 0x80, v0
	v_ashrrev_i32_e32 v2, 8, v2
	v_add_u32_e32 v3, 0x80, v3
	v_add_u32_e32 v1, 0x80, v1
	v_ashrrev_i32_e32 v0, 8, v0
	v_min_i32_e32 v2, 0x7f, v2
	v_ashrrev_i32_e32 v3, 8, v3
	v_ashrrev_i32_e32 v1, 8, v1
	v_min_i32_e32 v0, 0x7f, v0
	v_min_i32_sdwa v3, v3, s69 dst_sel:WORD_1 dst_unused:UNUSED_PAD src0_sel:DWORD src1_sel:DWORD
	v_min_i32_e32 v1, 0x7f, v1
	v_lshlrev_b32_e32 v2, 8, v2
	v_and_b32_e32 v2, 0xff00, v2
	v_and_b32_e32 v3, 0xff0000, v3
	v_perm_b32 v0, v1, v0, s76
	v_or3_b32 v0, v0, v2, v3
	ds_write_b32 v22, v0 offset:16
	v_mov_b32_e32 v0, v204
	v_mov_b32_e32 v1, v205
	v_mov_b32_e32 v2, v206
	v_mov_b32_e32 v3, v207
	v_mov_b32_e32 v4, v240
	v_mov_b32_e32 v5, v241
	v_mov_b32_e32 v6, v242
	v_mov_b32_e32 v7, v243
	ds_read_b64 v[44:45], v71 offset:1024
	s_waitcnt lgkmcnt(0)
;     ...
;           _Pragma("unroll") for (int bj = 0; bj < 2; ++bj) _Pragma("unroll") for (int n = 0; n < 2; ++n) {
;             const int cc = bj * HALF + wc3 * 32 + n * 16 + fq3 * 4;
;             const float4 gm = *reinterpret_cast<const float4*>(g.gam + pn * BM + cc), bt = *reinterpret_cast<const float4*>(g.bet + pn * BM + cc);
;             _Pragma("unroll") for (int m = 0; m < 4; ++m) {
;               const int rr = wr3 * 64 + m * 16 + fr3;
;               const float2 ms = *reinterpret_cast<const float2*>(mr + (ai * HALF + rr) * 2);
;               f32x4 y = acc[ai][bj][m][n];
;               const float o0 = (y[0] - ms.x) * ms.y * gm.x + bt.x, o1 = (y[1] - ms.x) * ms.y * gm.y + bt.y;
;               const float o2 = (y[2] - ms.x) * ms.y * gm.z + bt.z, o3 = (y[3] - ms.x) * ms.y * gm.w + bt.w;
;               const unsigned h0 = f2bf(o0), h1 = f2bf(o1), h2 = f2bf(o2), h3 = f2bf(o3);
;               u32x2 ob; ob[0] = h0 | (h1 << 16); ob[1] = h2 | (h3 << 16);
;               *reinterpret_cast<u32x2*>(smem + (rr >> 1) * PIECE + (rr & 1) * 512 + cc * 2) = ob;
;               const int l0 = min(((int)__float_as_uint(o0) - (int)(h0 << 16) + 128) >> 8, 127);
;               const int l1 = min(((int)__float_as_uint(o1) - (int)(h1 << 16) + 128) >> 8, 127);
;               const int l2 = min(((int)__float_as_uint(o2) - (int)(h2 << 16) + 128) >> 8, 127);
;               const int l3 = min(((int)__float_as_uint(o3) - (int)(h3 << 16) + 128) >> 8, 127);
;               *reinterpret_cast<unsigned*>(smem + LOBASE + (rr >> 2) * PIECE + (rr & 3) * 256 + cc) =
;                   (unsigned)(l0 & 255) | ((unsigned)(l1 & 255) << 8) | ((unsigned)(l2 & 255) << 16) | ((unsigned)l3 << 24);
;             }
	v_pk_add_f32 v[46:47], v[54:55], v[44:45] op_sel_hi:[1,0] neg_lo:[0,1] neg_hi:[0,1]
	s_nop 0
	v_pk_mul_f32 v[46:47], v[44:45], v[46:47] op_sel:[1,0]
	v_pk_add_f32 v[52:53], v[52:53], v[44:45] op_sel_hi:[1,0] neg_lo:[0,1] neg_hi:[0,1]
	v_mov_b32_e32 v40, v1
	v_mov_b32_e32 v41, v2
	v_mov_b32_e32 v42, v5
	v_mov_b32_e32 v43, v6
	v_pk_fma_f32 v[46:47], v[40:41], v[46:47], v[42:43]
	v_pk_mul_f32 v[44:45], v[44:45], v[52:53] op_sel:[1,0]
	v_mov_b32_e32 v1, v3
	v_mov_b32_e32 v5, v7
	v_and_b32_sdwa v6, v47, v244 dst_sel:DWORD dst_unused:UNUSED_PAD src0_sel:WORD_1 src1_sel:DWORD
	v_and_b32_sdwa v7, v46, v244 dst_sel:DWORD dst_unused:UNUSED_PAD src0_sel:WORD_1 src1_sel:DWORD
	v_pk_fma_f32 v[2:3], v[0:1], v[44:45], v[4:5]
	v_add3_u32 v23, v47, v6, s67
	v_add3_u32 v6, v46, v7, s67
	v_and_b32_e32 v44, 0xffff0000, v6
	v_and_b32_sdwa v6, v3, v244 dst_sel:DWORD dst_unused:UNUSED_PAD src0_sel:WORD_1 src1_sel:DWORD
	v_and_b32_sdwa v7, v2, v244 dst_sel:DWORD dst_unused:UNUSED_PAD src0_sel:WORD_1 src1_sel:DWORD
	v_add3_u32 v6, v3, v6, s67
	v_add3_u32 v45, v2, v7, s67
	v_and_b32_e32 v52, 0xffff0000, v6
	v_or_b32_sdwa v7, v52, v23 dst_sel:DWORD dst_unused:UNUSED_PAD src0_sel:DWORD src1_sel:WORD_1
	v_or_b32_sdwa v6, v45, v44 dst_sel:DWORD dst_unused:UNUSED_PAD src0_sel:WORD_1 src1_sel:DWORD
	ds_write_b64 v101, v[6:7]
	v_and_b32_e32 v6, 0xffff0000, v45
	v_sub_u32_e32 v2, v2, v6
	v_sub_u32_e32 v6, v46, v44
	v_and_b32_e32 v7, 0xffff0000, v23
	v_add_u32_e32 v6, 0x80, v6
	v_sub_u32_e32 v7, v47, v7
	v_sub_u32_e32 v3, v3, v52
	v_add_u32_e32 v2, 0x80, v2
	v_ashrrev_i32_e32 v6, 8, v6
	v_add_u32_e32 v7, 0x80, v7
	v_add_u32_e32 v3, 0x80, v3
	v_ashrrev_i32_e32 v2, 8, v2
	v_min_i32_e32 v6, 0x7f, v6
	v_ashrrev_i32_e32 v7, 8, v7
	v_ashrrev_i32_e32 v3, 8, v3
	v_min_i32_e32 v2, 0x7f, v2
	v_min_i32_sdwa v7, v7, s69 dst_sel:WORD_1 dst_unused:UNUSED_PAD src0_sel:DWORD src1_sel:DWORD
	v_min_i32_e32 v3, 0x7f, v3
	v_lshlrev_b32_e32 v6, 8, v6
	v_and_b32_e32 v6, 0xff00, v6
	v_and_b32_e32 v7, 0xff0000, v7
	v_perm_b32 v2, v3, v2, s76
	v_or3_b32 v2, v2, v6, v7
	ds_write_b32 v12, v2 offset:128
	ds_read_b64 v[2:3], v13 offset:1024
	s_waitcnt lgkmcnt(0)
	v_pk_add_f32 v[6:7], v[38:39], v[2:3] op_sel_hi:[1,0] neg_lo:[0,1] neg_hi:[0,1]
	s_nop 0
	v_pk_mul_f32 v[6:7], v[2:3], v[6:7] op_sel:[1,0]
	v_pk_add_f32 v[36:37], v[36:37], v[2:3] op_sel_hi:[1,0] neg_lo:[0,1] neg_hi:[0,1]
	v_pk_fma_f32 v[6:7], v[40:41], v[6:7], v[42:43]
	v_pk_mul_f32 v[2:3], v[2:3], v[36:37] op_sel:[1,0]
	v_and_b32_sdwa v36, v6, v244 dst_sel:DWORD dst_unused:UNUSED_PAD src0_sel:WORD_1 src1_sel:DWORD
	v_pk_fma_f32 v[2:3], v[0:1], v[2:3], v[4:5]
	v_add3_u32 v36, v6, v36, s67
	v_and_b32_e32 v38, 0xffff0000, v36
	v_and_b32_sdwa v36, v3, v244 dst_sel:DWORD dst_unused:UNUSED_PAD src0_sel:WORD_1 src1_sel:DWORD
	v_and_b32_sdwa v23, v7, v244 dst_sel:DWORD dst_unused:UNUSED_PAD src0_sel:WORD_1 src1_sel:DWORD
	v_and_b32_sdwa v37, v2, v244 dst_sel:DWORD dst_unused:UNUSED_PAD src0_sel:WORD_1 src1_sel:DWORD
	v_add3_u32 v36, v3, v36, s67
	v_add3_u32 v23, v7, v23, s67
	v_add3_u32 v39, v2, v37, s67
	v_and_b32_e32 v44, 0xffff0000, v36
	v_or_b32_sdwa v37, v44, v23 dst_sel:DWORD dst_unused:UNUSED_PAD src0_sel:DWORD src1_sel:WORD_1
	v_or_b32_sdwa v36, v39, v38 dst_sel:DWORD dst_unused:UNUSED_PAD src0_sel:WORD_1 src1_sel:DWORD
	ds_write_b64 v102, v[36:37]
	v_and_b32_e32 v36, 0xffff0000, v39
	v_sub_u32_e32 v6, v6, v38
	v_and_b32_e32 v23, 0xffff0000, v23
	v_sub_u32_e32 v2, v2, v36
	v_add_u32_e32 v6, 0x80, v6
	v_sub_u32_e32 v7, v7, v23
	v_sub_u32_e32 v3, v3, v44
	v_add_u32_e32 v2, 0x80, v2
	v_ashrrev_i32_e32 v6, 8, v6
	v_add_u32_e32 v7, 0x80, v7
	v_add_u32_e32 v3, 0x80, v3
	v_ashrrev_i32_e32 v2, 8, v2
	v_min_i32_e32 v6, 0x7f, v6
	v_ashrrev_i32_e32 v7, 8, v7
	v_ashrrev_i32_e32 v3, 8, v3
	v_min_i32_e32 v2, 0x7f, v2
	v_min_i32_sdwa v7, v7, s69 dst_sel:WORD_1 dst_unused:UNUSED_PAD src0_sel:DWORD src1_sel:DWORD
	v_min_i32_e32 v3, 0x7f, v3
	v_lshlrev_b32_e32 v6, 8, v6
	v_and_b32_e32 v6, 0xff00, v6
	v_and_b32_e32 v7, 0xff0000, v7
	v_perm_b32 v2, v3, v2, s76
	v_or3_b32 v2, v2, v6, v7
	ds_write_b32 v14, v2 offset:128
	ds_read_b64 v[2:3], v15 offset:1024
	s_waitcnt lgkmcnt(0)
	v_pk_add_f32 v[6:7], v[26:27], v[2:3] op_sel_hi:[1,0] neg_lo:[0,1] neg_hi:[0,1]
	s_nop 0
	v_pk_mul_f32 v[6:7], v[2:3], v[6:7] op_sel:[1,0]
	v_pk_add_f32 v[24:25], v[24:25], v[2:3] op_sel_hi:[1,0] neg_lo:[0,1] neg_hi:[0,1]
	v_pk_fma_f32 v[6:7], v[40:41], v[6:7], v[42:43]
	v_pk_mul_f32 v[2:3], v[2:3], v[24:25] op_sel:[1,0]
	v_and_b32_sdwa v24, v6, v244 dst_sel:DWORD dst_unused:UNUSED_PAD src0_sel:WORD_1 src1_sel:DWORD
	v_pk_fma_f32 v[2:3], v[0:1], v[2:3], v[4:5]
	v_add3_u32 v24, v6, v24, s67
	v_and_b32_e32 v26, 0xffff0000, v24
	v_and_b32_sdwa v24, v3, v244 dst_sel:DWORD dst_unused:UNUSED_PAD src0_sel:WORD_1 src1_sel:DWORD
	v_and_b32_sdwa v23, v7, v244 dst_sel:DWORD dst_unused:UNUSED_PAD src0_sel:WORD_1 src1_sel:DWORD
	v_and_b32_sdwa v25, v2, v244 dst_sel:DWORD dst_unused:UNUSED_PAD src0_sel:WORD_1 src1_sel:DWORD
	v_add3_u32 v24, v3, v24, s67
	v_add3_u32 v23, v7, v23, s67
	v_add3_u32 v27, v2, v25, s67
	v_and_b32_e32 v36, 0xffff0000, v24
	v_or_b32_sdwa v25, v36, v23 dst_sel:DWORD dst_unused:UNUSED_PAD src0_sel:DWORD src1_sel:WORD_1
	v_or_b32_sdwa v24, v27, v26 dst_sel:DWORD dst_unused:UNUSED_PAD src0_sel:WORD_1 src1_sel:DWORD
	ds_write_b64 v103, v[24:25]
	v_and_b32_e32 v24, 0xffff0000, v27
	v_sub_u32_e32 v6, v6, v26
	v_and_b32_e32 v23, 0xffff0000, v23
	v_sub_u32_e32 v2, v2, v24
	v_add_u32_e32 v6, 0x80, v6
	v_sub_u32_e32 v7, v7, v23
	v_sub_u32_e32 v3, v3, v36
	v_add_u32_e32 v2, 0x80, v2
	v_ashrrev_i32_e32 v6, 8, v6
	v_add_u32_e32 v7, 0x80, v7
	v_add_u32_e32 v3, 0x80, v3
	v_ashrrev_i32_e32 v2, 8, v2
	v_min_i32_e32 v6, 0x7f, v6
	v_ashrrev_i32_e32 v7, 8, v7
	v_ashrrev_i32_e32 v3, 8, v3
	v_min_i32_e32 v2, 0x7f, v2
	v_min_i32_sdwa v7, v7, s69 dst_sel:WORD_1 dst_unused:UNUSED_PAD src0_sel:DWORD src1_sel:DWORD
	v_min_i32_e32 v3, 0x7f, v3
	v_lshlrev_b32_e32 v6, 8, v6
	v_and_b32_e32 v6, 0xff00, v6
	v_and_b32_e32 v7, 0xff0000, v7
	v_perm_b32 v2, v3, v2, s76
	v_or3_b32 v2, v2, v6, v7
	ds_write_b32 v20, v2 offset:128
	ds_read_b64 v[2:3], v21 offset:1024
	s_waitcnt lgkmcnt(0)
;     ...
;           _Pragma("unroll") for (int bj = 0; bj < 2; ++bj) _Pragma("unroll") for (int n = 0; n < 2; ++n) {
;             const int cc = bj * HALF + wc3 * 32 + n * 16 + fq3 * 4;
;             const float4 gm = *reinterpret_cast<const float4*>(g.gam + pn * BM + cc), bt = *reinterpret_cast<const float4*>(g.bet + pn * BM + cc);
;             _Pragma("unroll") for (int m = 0; m < 4; ++m) {
;               const int rr = wr3 * 64 + m * 16 + fr3;
;               const float2 ms = *reinterpret_cast<const float2*>(mr + (ai * HALF + rr) * 2);
;               f32x4 y = acc[ai][bj][m][n];
;               const float o0 = (y[0] - ms.x) * ms.y * gm.x + bt.x, o1 = (y[1] - ms.x) * ms.y * gm.y + bt.y;
;               const float o2 = (y[2] - ms.x) * ms.y * gm.z + bt.z, o3 = (y[3] - ms.x) * ms.y * gm.w + bt.w;
;               const unsigned h0 = f2bf(o0), h1 = f2bf(o1), h2 = f2bf(o2), h3 = f2bf(o3);
;               u32x2 ob; ob[0] = h0 | (h1 << 16); ob[1] = h2 | (h3 << 16);
;               *reinterpret_cast<u32x2*>(smem + (rr >> 1) * PIECE + (rr & 1) * 512 + cc * 2) = ob;
;               const int l0 = min(((int)__float_as_uint(o0) - (int)(h0 << 16) + 128) >> 8, 127);
;               const int l1 = min(((int)__float_as_uint(o1) - (int)(h1 << 16) + 128) >> 8, 127);
;               const int l2 = min(((int)__float_as_uint(o2) - (int)(h2 << 16) + 128) >> 8, 127);
;               const int l3 = min(((int)__float_as_uint(o3) - (int)(h3 << 16) + 128) >> 8, 127);
;               *reinterpret_cast<unsigned*>(smem + LOBASE + (rr >> 2) * PIECE + (rr & 3) * 256 + cc) =
;                   (unsigned)(l0 & 255) | ((unsigned)(l1 & 255) << 8) | ((unsigned)(l2 & 255) << 16) | ((unsigned)l3 << 24);
;             }
	v_pk_add_f32 v[6:7], v[30:31], v[2:3] op_sel_hi:[1,0] neg_lo:[0,1] neg_hi:[0,1]
	s_nop 0
	v_pk_mul_f32 v[6:7], v[2:3], v[6:7] op_sel:[1,0]
	v_pk_add_f32 v[24:25], v[28:29], v[2:3] op_sel_hi:[1,0] neg_lo:[0,1] neg_hi:[0,1]
	v_pk_fma_f32 v[6:7], v[40:41], v[6:7], v[42:43]
	v_pk_mul_f32 v[2:3], v[2:3], v[24:25] op_sel:[1,0]
	s_nop 0
	v_pk_fma_f32 v[0:1], v[0:1], v[2:3], v[4:5]
	v_and_b32_sdwa v2, v7, v244 dst_sel:DWORD dst_unused:UNUSED_PAD src0_sel:WORD_1 src1_sel:DWORD
	v_and_b32_sdwa v3, v6, v244 dst_sel:DWORD dst_unused:UNUSED_PAD src0_sel:WORD_1 src1_sel:DWORD
	v_add3_u32 v4, v7, v2, s67
	v_add3_u32 v2, v6, v3, s67
	v_and_b32_e32 v5, 0xffff0000, v2
	v_and_b32_sdwa v2, v1, v244 dst_sel:DWORD dst_unused:UNUSED_PAD src0_sel:WORD_1 src1_sel:DWORD
	v_and_b32_sdwa v3, v0, v244 dst_sel:DWORD dst_unused:UNUSED_PAD src0_sel:WORD_1 src1_sel:DWORD
	v_add3_u32 v2, v1, v2, s67
	v_add3_u32 v23, v0, v3, s67
	v_and_b32_e32 v24, 0xffff0000, v2
	v_or_b32_sdwa v3, v24, v4 dst_sel:DWORD dst_unused:UNUSED_PAD src0_sel:DWORD src1_sel:WORD_1
	v_or_b32_sdwa v2, v23, v5 dst_sel:DWORD dst_unused:UNUSED_PAD src0_sel:WORD_1 src1_sel:DWORD
	ds_write_b64 v104, v[2:3]
	v_and_b32_e32 v2, 0xffff0000, v23
	v_sub_u32_e32 v0, v0, v2
	v_sub_u32_e32 v2, v6, v5
	v_and_b32_e32 v3, 0xffff0000, v4
	v_add_u32_e32 v2, 0x80, v2
	v_sub_u32_e32 v3, v7, v3
	v_sub_u32_e32 v1, v1, v24
	v_add_u32_e32 v0, 0x80, v0
	v_ashrrev_i32_e32 v2, 8, v2
	v_add_u32_e32 v3, 0x80, v3
	v_add_u32_e32 v1, 0x80, v1
	v_ashrrev_i32_e32 v0, 8, v0
	v_min_i32_e32 v2, 0x7f, v2
	v_ashrrev_i32_e32 v3, 8, v3
	v_ashrrev_i32_e32 v1, 8, v1
	v_min_i32_e32 v0, 0x7f, v0
	v_min_i32_sdwa v3, v3, s69 dst_sel:WORD_1 dst_unused:UNUSED_PAD src0_sel:DWORD src1_sel:DWORD
	v_min_i32_e32 v1, 0x7f, v1
	v_lshlrev_b32_e32 v2, 8, v2
	v_and_b32_e32 v2, 0xff00, v2
	v_and_b32_e32 v3, 0xff0000, v3
	v_perm_b32 v0, v1, v0, s76
	v_or3_b32 v0, v0, v2, v3
	ds_write_b32 v22, v0 offset:128
	v_mov_b32_e32 v0, v208
	v_mov_b32_e32 v1, v209
	v_mov_b32_e32 v2, v210
	v_mov_b32_e32 v3, v211
	v_mov_b32_e32 v4, v248
	v_mov_b32_e32 v5, v249
	v_mov_b32_e32 v6, v250
	v_mov_b32_e32 v7, v251
	ds_read_b64 v[28:29], v71 offset:1024
	s_lshl_b32 s4, s0, 1
	s_mov_b64 s[6:7], -1
	s_waitcnt lgkmcnt(0)
	v_pk_add_f32 v[30:31], v[50:51], v[28:29] op_sel_hi:[1,0] neg_lo:[0,1] neg_hi:[0,1]
	s_nop 0
	v_pk_mul_f32 v[30:31], v[28:29], v[30:31] op_sel:[1,0]
	v_pk_add_f32 v[36:37], v[48:49], v[28:29] op_sel_hi:[1,0] neg_lo:[0,1] neg_hi:[0,1]
	v_mov_b32_e32 v24, v1
	v_mov_b32_e32 v25, v2
	v_mov_b32_e32 v26, v5
	v_mov_b32_e32 v27, v6
	v_pk_fma_f32 v[30:31], v[24:25], v[30:31], v[26:27]
	v_pk_mul_f32 v[28:29], v[28:29], v[36:37] op_sel:[1,0]
	v_mov_b32_e32 v1, v3
	v_mov_b32_e32 v5, v7
	v_and_b32_sdwa v6, v31, v244 dst_sel:DWORD dst_unused:UNUSED_PAD src0_sel:WORD_1 src1_sel:DWORD
	v_and_b32_sdwa v7, v30, v244 dst_sel:DWORD dst_unused:UNUSED_PAD src0_sel:WORD_1 src1_sel:DWORD
	v_pk_fma_f32 v[2:3], v[0:1], v[28:29], v[4:5]
	v_add3_u32 v23, v31, v6, s67
	v_add3_u32 v6, v30, v7, s67
	v_and_b32_e32 v28, 0xffff0000, v6
	v_and_b32_sdwa v6, v3, v244 dst_sel:DWORD dst_unused:UNUSED_PAD src0_sel:WORD_1 src1_sel:DWORD
	v_and_b32_sdwa v7, v2, v244 dst_sel:DWORD dst_unused:UNUSED_PAD src0_sel:WORD_1 src1_sel:DWORD
	v_add3_u32 v6, v3, v6, s67
	v_add3_u32 v29, v2, v7, s67
	v_and_b32_e32 v36, 0xffff0000, v6
	v_or_b32_sdwa v7, v36, v23 dst_sel:DWORD dst_unused:UNUSED_PAD src0_sel:DWORD src1_sel:WORD_1
	v_or_b32_sdwa v6, v29, v28 dst_sel:DWORD dst_unused:UNUSED_PAD src0_sel:WORD_1 src1_sel:DWORD
	ds_write_b64 v105, v[6:7]
	v_and_b32_e32 v6, 0xffff0000, v29
	v_sub_u32_e32 v2, v2, v6
	v_sub_u32_e32 v6, v30, v28
	v_and_b32_e32 v7, 0xffff0000, v23
	v_add_u32_e32 v6, 0x80, v6
	v_sub_u32_e32 v7, v31, v7
	v_sub_u32_e32 v3, v3, v36
	v_add_u32_e32 v2, 0x80, v2
	v_ashrrev_i32_e32 v6, 8, v6
	v_add_u32_e32 v7, 0x80, v7
	v_add_u32_e32 v3, 0x80, v3
	v_ashrrev_i32_e32 v2, 8, v2
	v_min_i32_e32 v6, 0x7f, v6
	v_ashrrev_i32_e32 v7, 8, v7
	v_ashrrev_i32_e32 v3, 8, v3
	v_min_i32_e32 v2, 0x7f, v2
	v_min_i32_sdwa v7, v7, s69 dst_sel:WORD_1 dst_unused:UNUSED_PAD src0_sel:DWORD src1_sel:DWORD
	v_min_i32_e32 v3, 0x7f, v3
	v_lshlrev_b32_e32 v6, 8, v6
	v_and_b32_e32 v6, 0xff00, v6
	v_and_b32_e32 v7, 0xff0000, v7
	v_perm_b32 v2, v3, v2, s76
	v_or3_b32 v2, v2, v6, v7
	ds_write_b32 v12, v2 offset:144
	ds_read_b64 v[2:3], v13 offset:1024
	s_waitcnt lgkmcnt(0)
	v_pk_add_f32 v[6:7], v[34:35], v[2:3] op_sel_hi:[1,0] neg_lo:[0,1] neg_hi:[0,1]
	s_nop 0
	v_pk_mul_f32 v[6:7], v[2:3], v[6:7] op_sel:[1,0]
	v_pk_add_f32 v[12:13], v[32:33], v[2:3] op_sel_hi:[1,0] neg_lo:[0,1] neg_hi:[0,1]
	v_pk_fma_f32 v[6:7], v[24:25], v[6:7], v[26:27]
	v_pk_mul_f32 v[2:3], v[2:3], v[12:13] op_sel:[1,0]
	v_and_b32_sdwa v12, v7, v244 dst_sel:DWORD dst_unused:UNUSED_PAD src0_sel:WORD_1 src1_sel:DWORD
	v_and_b32_sdwa v13, v6, v244 dst_sel:DWORD dst_unused:UNUSED_PAD src0_sel:WORD_1 src1_sel:DWORD
	v_pk_fma_f32 v[2:3], v[0:1], v[2:3], v[4:5]
	v_add3_u32 v23, v7, v12, s67
	v_add3_u32 v12, v6, v13, s67
	v_and_b32_e32 v28, 0xffff0000, v12
	v_and_b32_sdwa v12, v3, v244 dst_sel:DWORD dst_unused:UNUSED_PAD src0_sel:WORD_1 src1_sel:DWORD
	v_and_b32_sdwa v13, v2, v244 dst_sel:DWORD dst_unused:UNUSED_PAD src0_sel:WORD_1 src1_sel:DWORD
	v_add3_u32 v12, v3, v12, s67
	v_add3_u32 v29, v2, v13, s67
	v_and_b32_e32 v30, 0xffff0000, v12
	v_or_b32_sdwa v13, v30, v23 dst_sel:DWORD dst_unused:UNUSED_PAD src0_sel:DWORD src1_sel:WORD_1
	v_or_b32_sdwa v12, v29, v28 dst_sel:DWORD dst_unused:UNUSED_PAD src0_sel:WORD_1 src1_sel:DWORD
	ds_write_b64 v106, v[12:13]
	v_and_b32_e32 v12, 0xffff0000, v29
	v_sub_u32_e32 v2, v2, v12
	v_sub_u32_e32 v6, v6, v28
	v_and_b32_e32 v12, 0xffff0000, v23
	v_add_u32_e32 v6, 0x80, v6
	v_sub_u32_e32 v7, v7, v12
	v_sub_u32_e32 v3, v3, v30
	v_add_u32_e32 v2, 0x80, v2
	v_ashrrev_i32_e32 v6, 8, v6
	v_add_u32_e32 v7, 0x80, v7
	v_add_u32_e32 v3, 0x80, v3
	v_ashrrev_i32_e32 v2, 8, v2
	v_min_i32_e32 v6, 0x7f, v6
	v_ashrrev_i32_e32 v7, 8, v7
	v_ashrrev_i32_e32 v3, 8, v3
	v_min_i32_e32 v2, 0x7f, v2
	v_min_i32_sdwa v7, v7, s69 dst_sel:WORD_1 dst_unused:UNUSED_PAD src0_sel:DWORD src1_sel:DWORD
	v_min_i32_e32 v3, 0x7f, v3
	v_lshlrev_b32_e32 v6, 8, v6
	v_and_b32_e32 v6, 0xff00, v6
	v_and_b32_e32 v7, 0xff0000, v7
	v_perm_b32 v2, v3, v2, s76
	v_or3_b32 v2, v2, v6, v7
	ds_write_b32 v14, v2 offset:144
	ds_read_b64 v[2:3], v15 offset:1024
	s_waitcnt lgkmcnt(0)
;     ...
;           _Pragma("unroll") for (int bj = 0; bj < 2; ++bj) _Pragma("unroll") for (int n = 0; n < 2; ++n) {
;             const int cc = bj * HALF + wc3 * 32 + n * 16 + fq3 * 4;
;             const float4 gm = *reinterpret_cast<const float4*>(g.gam + pn * BM + cc), bt = *reinterpret_cast<const float4*>(g.bet + pn * BM + cc);
;             _Pragma("unroll") for (int m = 0; m < 4; ++m) {
;               const int rr = wr3 * 64 + m * 16 + fr3;
;               const float2 ms = *reinterpret_cast<const float2*>(mr + (ai * HALF + rr) * 2);
;               f32x4 y = acc[ai][bj][m][n];
;               const float o0 = (y[0] - ms.x) * ms.y * gm.x + bt.x, o1 = (y[1] - ms.x) * ms.y * gm.y + bt.y;
;               const float o2 = (y[2] - ms.x) * ms.y * gm.z + bt.z, o3 = (y[3] - ms.x) * ms.y * gm.w + bt.w;
;               const unsigned h0 = f2bf(o0), h1 = f2bf(o1), h2 = f2bf(o2), h3 = f2bf(o3);
;               u32x2 ob; ob[0] = h0 | (h1 << 16); ob[1] = h2 | (h3 << 16);
;               *reinterpret_cast<u32x2*>(smem + (rr >> 1) * PIECE + (rr & 1) * 512 + cc * 2) = ob;
;               const int l0 = min(((int)__float_as_uint(o0) - (int)(h0 << 16) + 128) >> 8, 127);
;               const int l1 = min(((int)__float_as_uint(o1) - (int)(h1 << 16) + 128) >> 8, 127);
;               const int l2 = min(((int)__float_as_uint(o2) - (int)(h2 << 16) + 128) >> 8, 127);
;               const int l3 = min(((int)__float_as_uint(o3) - (int)(h3 << 16) + 128) >> 8, 127);
;               *reinterpret_cast<unsigned*>(smem + LOBASE + (rr >> 2) * PIECE + (rr & 3) * 256 + cc) =
;                   (unsigned)(l0 & 255) | ((unsigned)(l1 & 255) << 8) | ((unsigned)(l2 & 255) << 16) | ((unsigned)l3 << 24);
;             }
;           }
;           WAIT_L(0); BAR;
;           const int hso = ((brow + ai * HALF + 16 * wave) * DM + pn * BM) * 2;
;           const int lso = (brow + ai * HALF + 16 * wave) * DM + pn * BM;
;           _Pragma("unroll") for (int i = 0; i < 8; ++i) {
;             const u32x4 v = *reinterpret_cast<const u32x4*>(smem + (wave * 8 + i) * PIECE + lane3 * 16);
;             __builtin_amdgcn_raw_buffer_store_b128(v, rsXB, hvo + i * (2 * DM * 2), hso, 0);
;           }
;           _Pragma("unroll") for (int i = 0; i < 4; ++i) {
;             const u32x4 v = *reinterpret_cast<const u32x4*>(smem + LOBASE + (wave * 4 + i) * PIECE + lane3 * 16);
	v_pk_add_f32 v[6:7], v[18:19], v[2:3] op_sel_hi:[1,0] neg_lo:[0,1] neg_hi:[0,1]
	s_nop 0
	v_pk_mul_f32 v[6:7], v[2:3], v[6:7] op_sel:[1,0]
	v_pk_add_f32 v[12:13], v[16:17], v[2:3] op_sel_hi:[1,0] neg_lo:[0,1] neg_hi:[0,1]
	v_pk_fma_f32 v[6:7], v[24:25], v[6:7], v[26:27]
	v_pk_mul_f32 v[2:3], v[2:3], v[12:13] op_sel:[1,0]
	v_and_b32_sdwa v12, v7, v244 dst_sel:DWORD dst_unused:UNUSED_PAD src0_sel:WORD_1 src1_sel:DWORD
	v_and_b32_sdwa v13, v6, v244 dst_sel:DWORD dst_unused:UNUSED_PAD src0_sel:WORD_1 src1_sel:DWORD
	v_pk_fma_f32 v[2:3], v[0:1], v[2:3], v[4:5]
	v_add3_u32 v14, v7, v12, s67
	v_add3_u32 v12, v6, v13, s67
	v_and_b32_e32 v15, 0xffff0000, v12
	v_and_b32_sdwa v12, v3, v244 dst_sel:DWORD dst_unused:UNUSED_PAD src0_sel:WORD_1 src1_sel:DWORD
	v_and_b32_sdwa v13, v2, v244 dst_sel:DWORD dst_unused:UNUSED_PAD src0_sel:WORD_1 src1_sel:DWORD
	v_add3_u32 v12, v3, v12, s67
	v_add3_u32 v16, v2, v13, s67
	v_and_b32_e32 v17, 0xffff0000, v12
	v_or_b32_sdwa v13, v17, v14 dst_sel:DWORD dst_unused:UNUSED_PAD src0_sel:DWORD src1_sel:WORD_1
	v_or_b32_sdwa v12, v16, v15 dst_sel:DWORD dst_unused:UNUSED_PAD src0_sel:WORD_1 src1_sel:DWORD
	ds_write_b64 v107, v[12:13]
	v_and_b32_e32 v12, 0xffff0000, v16
	v_sub_u32_e32 v2, v2, v12
	v_sub_u32_e32 v6, v6, v15
	v_and_b32_e32 v12, 0xffff0000, v14
	v_add_u32_e32 v6, 0x80, v6
	v_sub_u32_e32 v7, v7, v12
	v_sub_u32_e32 v3, v3, v17
	v_add_u32_e32 v2, 0x80, v2
	v_ashrrev_i32_e32 v6, 8, v6
	v_add_u32_e32 v7, 0x80, v7
	v_add_u32_e32 v3, 0x80, v3
	v_ashrrev_i32_e32 v2, 8, v2
	v_min_i32_e32 v6, 0x7f, v6
	v_ashrrev_i32_e32 v7, 8, v7
	v_ashrrev_i32_e32 v3, 8, v3
	v_min_i32_e32 v2, 0x7f, v2
	v_min_i32_sdwa v7, v7, s69 dst_sel:WORD_1 dst_unused:UNUSED_PAD src0_sel:DWORD src1_sel:DWORD
	v_min_i32_e32 v3, 0x7f, v3
	v_lshlrev_b32_e32 v6, 8, v6
	v_and_b32_e32 v6, 0xff00, v6
	v_and_b32_e32 v7, 0xff0000, v7
	v_perm_b32 v2, v3, v2, s76
	v_or3_b32 v2, v2, v6, v7
	ds_write_b32 v20, v2 offset:144
	ds_read_b64 v[2:3], v21 offset:1024
	s_waitcnt lgkmcnt(0)
	v_pk_add_f32 v[6:7], v[10:11], v[2:3] op_sel_hi:[1,0] neg_lo:[0,1] neg_hi:[0,1]
	s_nop 0
	v_pk_mul_f32 v[6:7], v[2:3], v[6:7] op_sel:[1,0]
	v_pk_add_f32 v[8:9], v[8:9], v[2:3] op_sel_hi:[1,0] neg_lo:[0,1] neg_hi:[0,1]
	v_pk_fma_f32 v[6:7], v[24:25], v[6:7], v[26:27]
	v_pk_mul_f32 v[2:3], v[2:3], v[8:9] op_sel:[1,0]
	s_nop 0
	v_pk_fma_f32 v[0:1], v[0:1], v[2:3], v[4:5]
	v_and_b32_sdwa v2, v7, v244 dst_sel:DWORD dst_unused:UNUSED_PAD src0_sel:WORD_1 src1_sel:DWORD
	v_and_b32_sdwa v3, v6, v244 dst_sel:DWORD dst_unused:UNUSED_PAD src0_sel:WORD_1 src1_sel:DWORD
	v_add3_u32 v4, v7, v2, s67
	v_add3_u32 v2, v6, v3, s67
	v_and_b32_e32 v5, 0xffff0000, v2
	v_and_b32_sdwa v2, v1, v244 dst_sel:DWORD dst_unused:UNUSED_PAD src0_sel:WORD_1 src1_sel:DWORD
	v_and_b32_sdwa v3, v0, v244 dst_sel:DWORD dst_unused:UNUSED_PAD src0_sel:WORD_1 src1_sel:DWORD
	v_add3_u32 v2, v1, v2, s67
	v_add3_u32 v8, v0, v3, s67
	v_and_b32_e32 v9, 0xffff0000, v2
	v_or_b32_sdwa v3, v9, v4 dst_sel:DWORD dst_unused:UNUSED_PAD src0_sel:DWORD src1_sel:WORD_1
	v_or_b32_sdwa v2, v8, v5 dst_sel:DWORD dst_unused:UNUSED_PAD src0_sel:WORD_1 src1_sel:DWORD
	ds_write_b64 v88, v[2:3]
	v_and_b32_e32 v2, 0xffff0000, v8
	v_sub_u32_e32 v0, v0, v2
	v_sub_u32_e32 v2, v6, v5
	v_and_b32_e32 v3, 0xffff0000, v4
	v_add_u32_e32 v2, 0x80, v2
	v_sub_u32_e32 v3, v7, v3
	v_sub_u32_e32 v1, v1, v9
	v_add_u32_e32 v0, 0x80, v0
	v_ashrrev_i32_e32 v2, 8, v2
	v_add_u32_e32 v3, 0x80, v3
	v_add_u32_e32 v1, 0x80, v1
	v_ashrrev_i32_e32 v0, 8, v0
	v_min_i32_e32 v2, 0x7f, v2
	v_ashrrev_i32_e32 v3, 8, v3
	v_ashrrev_i32_e32 v1, 8, v1
	v_min_i32_e32 v0, 0x7f, v0
	v_min_i32_sdwa v3, v3, s69 dst_sel:WORD_1 dst_unused:UNUSED_PAD src0_sel:DWORD src1_sel:DWORD
	v_min_i32_e32 v1, 0x7f, v1
	v_lshlrev_b32_e32 v2, 8, v2
	v_and_b32_e32 v2, 0xff00, v2
	v_and_b32_e32 v3, 0xff0000, v3
	v_perm_b32 v0, v1, v0, s76
	v_or3_b32 v0, v0, v2, v3
	ds_write_b32 v22, v0 offset:144
	s_waitcnt lgkmcnt(0)
	s_barrier
	ds_read_b128 v[128:131], v74
	ds_read_b128 v[132:135], v74 offset:1040
	ds_read_b128 v[136:139], v74 offset:2080
	ds_read_b128 v[140:143], v74 offset:3120
	ds_read_b128 v[144:147], v74 offset:4160
	ds_read_b128 v[148:151], v74 offset:5200
	ds_read_b128 v[152:155], v74 offset:6240
	ds_read_b128 v[156:159], v74 offset:7280
	ds_read_b128 v[160:163], v69
	ds_read_b128 v[164:167], v69 offset:1040
	ds_read_b128 v[168:171], v69 offset:2080
	ds_read_b128 v[172:175], v69 offset:3120
	s_waitcnt lgkmcnt(0)
	s_barrier
; #define STAGE(P, RS, SOFF, OFF, kt) do { const int _so = (SOFF) + (kt) * (BK * 2); \
;     _Pragma("unroll") for (int _i = 0; _i < 2; ++_i) { \
;       __builtin_amdgcn_raw_ptr_buffer_load_lds(RS, (__attribute__((address_space(3))) void*)((P) + wave * 1024 + _i * 8192), 16, OFF[_i], _so, 0, 0); } } while (0)
;     ...
;   auto issue_prologue = [&](int sA0, int sA1, int sB0, int sB1) {
;     const int tid = opaque_tid(wave);
;     int offA[2], offB[2];
;     _Pragma("unroll") for (int i = 0; i < 2; ++i) {
;       int r, c; stage_rc(tid * 16 + i * 8192, r, c);
;       offA[i] = (r * lda + c) * 2; offB[i] = (r * ldb + c) * 2;
;     }
;     STAGE(SB(0, 0), rsB, sB0, offB, 0); STAGE(SA(0, 0), rsA, sA0, offA, 0);
;     STAGE(SB(0, 1), rsB, sB1, offB, 0); STAGE(SA(0, 1), rsA, sA1, offA, 0);
;     STAGE(SB(1, 0), rsB, sB0, offB, 1); STAGE(SA(1, 0), rsA, sA0, offA, 1); STAGE(SB(1, 1), rsB, sB1, offB, 1);
;   };
;     ...
;           _Pragma("unroll") for (int i = 0; i < 8; ++i) {
;             const u32x4 v = *reinterpret_cast<const u32x4*>(smem + (wave * 8 + i) * PIECE + lane3 * 16);
;             __builtin_amdgcn_raw_buffer_store_b128(v, rsXB, hvo + i * (2 * DM * 2), hso, 0);
;           }
;           _Pragma("unroll") for (int i = 0; i < 4; ++i) {
;             const u32x4 v = *reinterpret_cast<const u32x4*>(smem + LOBASE + (wave * 4 + i) * PIECE + lane3 * 16);
;             __builtin_amdgcn_raw_buffer_store_b128(v, rsLO, lvo + i * (4 * DM), lso, 0);
;           }
	s_mov_b32 s98, s0
	s_cbranch_vccnz .Lmy_s1n_135
	v_mbcnt_lo_u32_b32 v0, -1, 0
	v_mbcnt_hi_u32_b32 v0, -1, v0
	s_mov_b32 m0, s34
	v_lshl_add_u32 v0, v0, 4, s30
	v_ashrrev_i32_e32 v1, 31, v0
	v_lshrrev_b32_e32 v1, 22, v1
	v_add_u32_e32 v1, v0, v1
	v_ashrrev_i32_e32 v1, 10, v1
	v_mul_i32_i24_e32 v2, 0x400, v1
	v_sub_u32_e32 v2, v0, v2
	v_lshrrev_b32_e32 v3, 4, v2
	v_bitop3_b32 v2, v3, v2, 32 bitop3:0x6c
	v_ashrrev_i32_e32 v4, 31, v2
	v_lshrrev_b32_e32 v4, 26, v4
	v_add_u32_e32 v4, v2, v4
	v_lshrrev_b32_e32 v5, 6, v4
	v_and_b32_e32 v4, 0xc0, v4
	v_lshlrev_b32_e32 v3, 3, v1
	v_lshlrev_b32_e32 v1, 5, v1
	v_sub_u32_e32 v2, v2, v4
	v_and_b32_e32 v3, 0x7fff0, v3
	v_and_b32_e32 v1, 32, v1
	v_ashrrev_i16_sdwa v2, v244, sext(v2) dst_sel:DWORD dst_unused:UNUSED_PAD src0_sel:DWORD src1_sel:BYTE_0
	v_add_u32_sdwa v1, v1, sext(v2) dst_sel:DWORD dst_unused:UNUSED_PAD src0_sel:DWORD src1_sel:WORD_0
	v_add_lshl_u32 v2, v5, v3, 13
	v_add_u32_e32 v0, 0x2000, v0
	v_lshl_add_u32 v1, v1, 1, v2
	v_ashrrev_i32_e32 v2, 31, v0
	v_lshrrev_b32_e32 v2, 22, v2
	v_add_u32_e32 v2, v0, v2
	v_ashrrev_i32_e32 v2, 10, v2
	v_mul_i32_i24_e32 v3, 0x400, v2
	v_sub_u32_e32 v0, v0, v3
	v_lshrrev_b32_e32 v3, 4, v0
	v_bitop3_b32 v0, v3, v0, 32 bitop3:0x6c
	v_ashrrev_i32_e32 v4, 31, v0
	v_lshrrev_b32_e32 v4, 26, v4
	v_add_u32_e32 v4, v0, v4
	v_lshrrev_b32_e32 v5, 6, v4
	v_and_b32_e32 v4, 0xffc0, v4
	v_sub_u32_e32 v0, v0, v4
	v_lshrrev_b16_e32 v4, 7, v0
	v_and_b32_e32 v4, 1, v4
	v_lshlrev_b32_e32 v3, 3, v2
	v_lshlrev_b32_e32 v2, 5, v2
	v_add_u16_e32 v0, v0, v4
	v_and_b32_e32 v3, 0x7fff0, v3
	v_and_b32_e32 v2, 32, v2
	v_ashrrev_i16_sdwa v0, v244, sext(v0) dst_sel:DWORD dst_unused:UNUSED_PAD src0_sel:DWORD src1_sel:BYTE_0
	v_add_u32_sdwa v0, v2, sext(v0) dst_sel:DWORD dst_unused:UNUSED_PAD src0_sel:DWORD src1_sel:WORD_0
	v_add_lshl_u32 v2, v5, v3, 13
	s_mov_b32 s14, s10
	s_mov_b32 s15, s11
	v_lshl_add_u32 v0, v0, 1, v2
	buffer_load_dwordx4 v1, s[12:15], s84 offen lds
	s_mov_b32 m0, s43
	s_or_b32 s0, s84, 0x80
	buffer_load_dwordx4 v0, s[12:15], s84 offen lds
	s_mov_b32 m0, s30
	s_mov_b64 s[6:7], 0
	buffer_load_dwordx4 v1, s[8:11], s83 offen lds
	s_mov_b32 m0, s44
	s_nop 0
	buffer_load_dwordx4 v0, s[8:11], s83 offen lds
	s_mov_b32 m0, s35
	s_nop 0
	buffer_load_dwordx4 v1, s[12:15], s85 offen lds
	s_mov_b32 m0, s45
	s_nop 0
	buffer_load_dwordx4 v0, s[12:15], s85 offen lds
	s_mov_b32 m0, s36
	s_nop 0
	buffer_load_dwordx4 v1, s[8:11], s82 offen lds
	s_mov_b32 m0, s48
	s_nop 0
	buffer_load_dwordx4 v0, s[8:11], s82 offen lds
	s_mov_b32 m0, s37
	s_nop 0
	buffer_load_dwordx4 v1, s[12:15], s0 offen lds
	s_mov_b32 m0, s49
	s_nop 0
	buffer_load_dwordx4 v0, s[12:15], s0 offen lds
	s_or_b32 s0, s83, 0x80
	s_mov_b32 m0, s38
	s_nop 0
	buffer_load_dwordx4 v1, s[8:11], s0 offen lds
	s_mov_b32 m0, s54
	s_nop 0
	buffer_load_dwordx4 v0, s[8:11], s0 offen lds
	s_add_i32 s0, s85, 0x80
	s_mov_b32 m0, s39
	s_nop 0
	buffer_load_dwordx4 v1, s[12:15], s0 offen lds
	s_mov_b32 m0, s55
	s_nop 0
	buffer_load_dwordx4 v0, s[12:15], s0 offen lds
	buffer_store_dwordx4 v[128:131], v70, s[16:19], s4 offen
	buffer_store_dwordx4 v[132:135], v89, s[16:19], s4 offen
	buffer_store_dwordx4 v[136:139], v90, s[16:19], s4 offen
	buffer_store_dwordx4 v[140:143], v91, s[16:19], s4 offen
	buffer_store_dwordx4 v[144:147], v108, s[16:19], s4 offen
	buffer_store_dwordx4 v[148:151], v109, s[16:19], s4 offen
	buffer_store_dwordx4 v[152:155], v110, s[16:19], s4 offen
	buffer_store_dwordx4 v[156:159], v111, s[16:19], s4 offen
	buffer_store_dwordx4 v[160:163], v68, s[20:23], s98 offen
	buffer_store_dwordx4 v[164:167], v112, s[20:23], s98 offen
	buffer_store_dwordx4 v[168:171], v113, s[20:23], s98 offen
	buffer_store_dwordx4 v[172:175], v114, s[20:23], s98 offen
	s_branch .LBB0_140
.Lmy_s1n_135:
	buffer_store_dwordx4 v[128:131], v70, s[16:19], s4 offen
	buffer_store_dwordx4 v[132:135], v89, s[16:19], s4 offen
	buffer_store_dwordx4 v[136:139], v90, s[16:19], s4 offen
	buffer_store_dwordx4 v[140:143], v91, s[16:19], s4 offen
	buffer_store_dwordx4 v[144:147], v108, s[16:19], s4 offen
	buffer_store_dwordx4 v[148:151], v109, s[16:19], s4 offen
	buffer_store_dwordx4 v[152:155], v110, s[16:19], s4 offen
	buffer_store_dwordx4 v[156:159], v111, s[16:19], s4 offen
	buffer_store_dwordx4 v[160:163], v68, s[20:23], s98 offen
	buffer_store_dwordx4 v[164:167], v112, s[20:23], s98 offen
	buffer_store_dwordx4 v[168:171], v113, s[20:23], s98 offen
	buffer_store_dwordx4 v[172:175], v114, s[20:23], s98 offen
	s_branch .LBB0_140

; #define WAIT_V(n) asm volatile("s_waitcnt vmcnt(" #n ")" ::: "memory")
;     ...
;     if (first_tile) { WAIT_V(0); }
;     else if constexpr (mode == MODE_RESID_LN) { WAIT_V(0); }
.LBB0_286:
	s_or_b64 exec, exec, s[14:15]
	s_xor_b64 s[14:15], s[6:7], -1
	s_mov_b64 s[6:7], -1
	s_and_b64 vcc, exec, s[14:15]
	s_cbranch_vccz .LBB0_288
	s_waitcnt vmcnt(12)
	s_mov_b64 s[6:7], 0

;     ...
;         constexpr int PIECE = 1024 + 16, LOBASE = 64 * PIECE;
;         const int lane3 = tid3 & 63;
;         const int hvo = (lane3 >> 5) * (DM * 2) + (lane3 & 31) * 16;
;         const int lvo = (lane3 >> 4) * DM + (lane3 & 15) * 16;
;         _Pragma("unroll") for (int ai = 0; ai < 2; ++ai) {
;           _Pragma("unroll") for (int bj = 0; bj < 2; ++bj) _Pragma("unroll") for (int n = 0; n < 2; ++n) {
;             const int cc = bj * HALF + wc3 * 32 + n * 16 + fq3 * 4;
;             const float4 gm = *reinterpret_cast<const float4*>(g.gam + pn * BM + cc), bt = *reinterpret_cast<const float4*>(g.bet + pn * BM + cc);
;             _Pragma("unroll") for (int m = 0; m < 4; ++m) {
;               const int rr = wr3 * 64 + m * 16 + fr3;
;               const float2 ms = *reinterpret_cast<const float2*>(mr + (ai * HALF + rr) * 2);
;               f32x4 y = acc[ai][bj][m][n];
;               const float o0 = (y[0] - ms.x) * ms.y * gm.x + bt.x, o1 = (y[1] - ms.x) * ms.y * gm.y + bt.y;
;               const float o2 = (y[2] - ms.x) * ms.y * gm.z + bt.z, o3 = (y[3] - ms.x) * ms.y * gm.w + bt.w;
;               const unsigned h0 = f2bf(o0), h1 = f2bf(o1), h2 = f2bf(o2), h3 = f2bf(o3);
;               u32x2 ob; ob[0] = h0 | (h1 << 16); ob[1] = h2 | (h3 << 16);
;               *reinterpret_cast<u32x2*>(smem + (rr >> 1) * PIECE + (rr & 1) * 512 + cc * 2) = ob;
;               const int l0 = min(((int)__float_as_uint(o0) - (int)(h0 << 16) + 128) >> 8, 127);
;               const int l1 = min(((int)__float_as_uint(o1) - (int)(h1 << 16) + 128) >> 8, 127);
;               const int l2 = min(((int)__float_as_uint(o2) - (int)(h2 << 16) + 128) >> 8, 127);
;               const int l3 = min(((int)__float_as_uint(o3) - (int)(h3 << 16) + 128) >> 8, 127);
;               *reinterpret_cast<unsigned*>(smem + LOBASE + (rr >> 2) * PIECE + (rr & 3) * 256 + cc) =
;                   (unsigned)(l0 & 255) | ((unsigned)(l1 & 255) << 8) | ((unsigned)(l2 & 255) << 16) | ((unsigned)l3 << 24);
;             }
.LBB0_320:
	s_or_b64 exec, exec, s[6:7]
	s_waitcnt lgkmcnt(0)
	s_barrier
	v_mbcnt_lo_u32_b32 v0, -1, 0
	v_mbcnt_hi_u32_b32 v0, -1, v0
	s_movk_i32 s4, 0x60
	v_add_u32_e32 v1, s34, v0
	v_ashrrev_i32_e32 v5, 2, v1
	v_lshrrev_b32_e32 v6, 1, v1
	v_lshlrev_b32_e32 v1, 4, v1
	v_bfe_u32 v4, v0, 4, 2
	v_lshlrev_b32_e32 v12, 7, v0
	v_and_b32_e32 v13, 0x1f0, v1
	v_lshlrev_b32_e32 v7, 2, v4
	v_and_or_b32 v148, v12, s29, v13
	s_ashr_i32 s29, s28, 31
	v_and_or_b32 v12, v6, s4, v7
	s_lshl_b64 s[4:5], s[28:29], 2
	s_add_u32 s6, s86, s4
	v_and_b32_e32 v2, 15, v0
	v_and_b32_e32 v3, 63, v0
	v_and_b32_e32 v1, 0xf0, v1
	v_lshlrev_b32_e32 v13, 9, v0
	v_lshlrev_b32_e32 v0, 8, v0
	s_addc_u32 s7, s87, s5
	v_lshlrev_b32_e32 v150, 2, v12
	v_lshl_or_b32 v146, v4, 11, v1
	v_and_or_b32 v155, v5, s64, v2
	v_and_b32_e32 v14, 0x300, v0
	v_lshlrev_b32_e32 v151, 4, v3
	global_load_dwordx4 v[220:223], v150, s[6:7]
	global_load_dwordx4 v[224:227], v150, s[6:7] offset:64
	global_load_dwordx4 v[228:231], v150, s[6:7] offset:512
	global_load_dwordx4 v[232:235], v150, s[6:7] offset:576
	v_readlane_b32 s64, v255, 0
	v_readlane_b32 s65, v255, 1
	s_add_u32 s4, s64, s4
	s_addc_u32 s5, s65, s5
	global_load_dwordx4 v[236:239], v150, s[4:5]
	global_load_dwordx4 v[240:243], v150, s[4:5] offset:64
	global_load_dwordx4 v[244:247], v150, s[4:5] offset:512
	global_load_dwordx4 v[248:251], v150, s[4:5] offset:576
	s_movk_i32 s22, 0x200
	v_lshl_add_u32 v149, v155, 3, v219
	v_add_u32_e32 v147, s56, v151
	s_andn2_b64 vcc, exec, s[14:15]
	s_movk_i32 s46, 0x100
	v_readlane_b32 s66, v255, 2
	v_readlane_b32 s67, v255, 3
	v_readlane_b32 s68, v255, 4
	v_readlane_b32 s69, v255, 5
	v_readlane_b32 s70, v255, 6
	v_readlane_b32 s71, v255, 7
	v_readlane_b32 s72, v255, 8
	v_readlane_b32 s73, v255, 9
	v_readlane_b32 s74, v255, 10
	v_readlane_b32 s75, v255, 11
	v_readlane_b32 s76, v255, 12
	v_readlane_b32 s77, v255, 13
	v_readlane_b32 s78, v255, 14
	v_readlane_b32 s79, v255, 15
	s_waitcnt vmcnt(0)
	v_mov_b32_e32 v0, v220
	v_mov_b32_e32 v1, v221
	v_mov_b32_e32 v2, v222
	v_mov_b32_e32 v3, v223
	v_mov_b32_e32 v4, v236
	v_mov_b32_e32 v5, v237
	v_mov_b32_e32 v6, v238
	v_mov_b32_e32 v7, v239
	v_mov_b32_e32 v22, v1
	v_lshlrev_b32_e32 v1, 1, v12
	v_and_or_b32 v154, v13, s22, v1
	s_mov_b32 s22, 0x10400
	v_mov_b32_e32 v23, v2
	v_or3_b32 v2, v14, v12, s22
	ds_read_b64 v[12:13], v149
	v_mov_b32_e32 v144, v5
	v_mov_b32_e32 v145, v6
	v_mov_b32_e32 v1, v3
	v_mov_b32_e32 v5, v7
	s_waitcnt lgkmcnt(0)
	v_pk_add_f32 v[14:15], v[132:133], v[12:13] op_sel_hi:[1,0] neg_lo:[0,1] neg_hi:[0,1]
	v_pk_add_f32 v[18:19], v[130:131], v[12:13] op_sel_hi:[1,0] neg_lo:[0,1] neg_hi:[0,1]
	v_pk_mul_f32 v[14:15], v[12:13], v[14:15] op_sel:[1,0]
	v_pk_mul_f32 v[12:13], v[12:13], v[18:19] op_sel:[1,0]
	v_pk_fma_f32 v[14:15], v[22:23], v[14:15], v[144:145]
	v_pk_fma_f32 v[6:7], v[0:1], v[12:13], v[4:5]
	v_and_b32_sdwa v12, v14, v216 dst_sel:DWORD dst_unused:UNUSED_PAD src0_sel:WORD_1 src1_sel:DWORD
	v_add3_u32 v12, v14, v12, s84
	v_and_b32_e32 v18, 0xffff0000, v12
	v_and_b32_sdwa v12, v7, v216 dst_sel:DWORD dst_unused:UNUSED_PAD src0_sel:WORD_1 src1_sel:DWORD
	v_and_b32_sdwa v3, v15, v216 dst_sel:DWORD dst_unused:UNUSED_PAD src0_sel:WORD_1 src1_sel:DWORD
	v_and_b32_sdwa v13, v6, v216 dst_sel:DWORD dst_unused:UNUSED_PAD src0_sel:WORD_1 src1_sel:DWORD
	v_add3_u32 v12, v7, v12, s84
	v_lshrrev_b32_e32 v131, 1, v155
	v_add3_u32 v3, v15, v3, s84
	v_add3_u32 v19, v6, v13, s84
	v_and_b32_e32 v130, 0xffff0000, v12
	v_mul_lo_u32 v152, v131, s63
	v_or_b32_sdwa v13, v130, v3 dst_sel:DWORD dst_unused:UNUSED_PAD src0_sel:DWORD src1_sel:WORD_1
	v_or_b32_sdwa v12, v19, v18 dst_sel:DWORD dst_unused:UNUSED_PAD src0_sel:WORD_1 src1_sel:DWORD
	v_add_u32_e32 v132, v154, v152
	ds_write_b64 v132, v[12:13]
	v_and_b32_e32 v12, 0xffff0000, v19
	v_sub_u32_e32 v6, v6, v12
	v_sub_u32_e32 v12, v14, v18
	v_and_b32_e32 v3, 0xffff0000, v3
	v_add_u32_e32 v12, 0x80, v12
	v_sub_u32_e32 v3, v15, v3
	v_sub_u32_e32 v7, v7, v130
	v_add_u32_e32 v6, 0x80, v6
	v_ashrrev_i32_e32 v12, 8, v12
	v_add_u32_e32 v3, 0x80, v3
	v_add_u32_e32 v7, 0x80, v7
	v_ashrrev_i32_e32 v6, 8, v6
	v_min_i32_e32 v12, 0x7f, v12
	v_ashrrev_i32_e32 v3, 8, v3
	v_ashrrev_i32_e32 v7, 8, v7
	v_min_i32_e32 v6, 0x7f, v6
	v_min_i32_sdwa v3, v3, s85 dst_sel:WORD_1 dst_unused:UNUSED_PAD src0_sel:DWORD src1_sel:DWORD
	v_min_i32_e32 v7, 0x7f, v7
	v_lshlrev_b32_e32 v12, 8, v12
	v_and_b32_e32 v12, 0xff00, v12
	v_and_b32_e32 v3, 0xff0000, v3
	v_perm_b32 v6, v7, v6, s92
	v_or3_b32 v3, v6, v12, v3
	v_lshrrev_b32_e32 v6, 2, v155
	v_mad_u64_u32 v[12:13], s[22:23], v6, s63, v[2:3]
	ds_write_b32 v12, v3
	v_or_b32_e32 v3, 16, v155
	v_lshl_add_u32 v13, v3, 3, v219
	ds_read_b64 v[6:7], v13
	v_lshrrev_b32_e32 v133, 1, v3
	v_mul_lo_u32 v153, v133, s63
	v_add_u32_e32 v133, v154, v153
	v_lshrrev_b32_e32 v3, 2, v3
	s_waitcnt lgkmcnt(0)
;     ...
;             _Pragma("unroll") for (int m = 0; m < 4; ++m) {
;               const int rr = wr3 * 64 + m * 16 + fr3;
;               const float2 ms = *reinterpret_cast<const float2*>(mr + (ai * HALF + rr) * 2);
;               f32x4 y = acc[ai][bj][m][n];
;               const float o0 = (y[0] - ms.x) * ms.y * gm.x + bt.x, o1 = (y[1] - ms.x) * ms.y * gm.y + bt.y;
;               const float o2 = (y[2] - ms.x) * ms.y * gm.z + bt.z, o3 = (y[3] - ms.x) * ms.y * gm.w + bt.w;
;               const unsigned h0 = f2bf(o0), h1 = f2bf(o1), h2 = f2bf(o2), h3 = f2bf(o3);
;               u32x2 ob; ob[0] = h0 | (h1 << 16); ob[1] = h2 | (h3 << 16);
;               *reinterpret_cast<u32x2*>(smem + (rr >> 1) * PIECE + (rr & 1) * 512 + cc * 2) = ob;
;               const int l0 = min(((int)__float_as_uint(o0) - (int)(h0 << 16) + 128) >> 8, 127);
;               const int l1 = min(((int)__float_as_uint(o1) - (int)(h1 << 16) + 128) >> 8, 127);
;               const int l2 = min(((int)__float_as_uint(o2) - (int)(h2 << 16) + 128) >> 8, 127);
;               const int l3 = min(((int)__float_as_uint(o3) - (int)(h3 << 16) + 128) >> 8, 127);
;               *reinterpret_cast<unsigned*>(smem + LOBASE + (rr >> 2) * PIECE + (rr & 3) * 256 + cc) =
;                   (unsigned)(l0 & 255) | ((unsigned)(l1 & 255) << 8) | ((unsigned)(l2 & 255) << 16) | ((unsigned)l3 << 24);
;             }
	v_pk_add_f32 v[14:15], v[122:123], v[6:7] op_sel_hi:[1,0] neg_lo:[0,1] neg_hi:[0,1]
	v_pk_add_f32 v[18:19], v[134:135], v[6:7] op_sel_hi:[1,0] neg_lo:[0,1] neg_hi:[0,1]
	v_pk_mul_f32 v[14:15], v[6:7], v[14:15] op_sel:[1,0]
	v_pk_mul_f32 v[6:7], v[6:7], v[18:19] op_sel:[1,0]
	v_pk_fma_f32 v[14:15], v[22:23], v[14:15], v[144:145]
	v_pk_fma_f32 v[6:7], v[0:1], v[6:7], v[4:5]
	v_and_b32_sdwa v18, v15, v216 dst_sel:DWORD dst_unused:UNUSED_PAD src0_sel:WORD_1 src1_sel:DWORD
	v_and_b32_sdwa v19, v14, v216 dst_sel:DWORD dst_unused:UNUSED_PAD src0_sel:WORD_1 src1_sel:DWORD
	v_add3_u32 v122, v15, v18, s84
	v_add3_u32 v18, v14, v19, s84
	v_and_b32_e32 v123, 0xffff0000, v18
	v_and_b32_sdwa v18, v7, v216 dst_sel:DWORD dst_unused:UNUSED_PAD src0_sel:WORD_1 src1_sel:DWORD
	v_and_b32_sdwa v19, v6, v216 dst_sel:DWORD dst_unused:UNUSED_PAD src0_sel:WORD_1 src1_sel:DWORD
	v_add3_u32 v18, v7, v18, s84
	v_add3_u32 v130, v6, v19, s84
	v_and_b32_e32 v131, 0xffff0000, v18
	v_or_b32_sdwa v19, v131, v122 dst_sel:DWORD dst_unused:UNUSED_PAD src0_sel:DWORD src1_sel:WORD_1
	v_or_b32_sdwa v18, v130, v123 dst_sel:DWORD dst_unused:UNUSED_PAD src0_sel:WORD_1 src1_sel:DWORD
	ds_write_b64 v133, v[18:19]
	v_and_b32_e32 v18, 0xffff0000, v130
	v_sub_u32_e32 v6, v6, v18
	v_sub_u32_e32 v14, v14, v123
	v_and_b32_e32 v18, 0xffff0000, v122
	v_add_u32_e32 v14, 0x80, v14
	v_sub_u32_e32 v15, v15, v18
	v_sub_u32_e32 v7, v7, v131
	v_add_u32_e32 v6, 0x80, v6
	v_ashrrev_i32_e32 v14, 8, v14
	v_add_u32_e32 v15, 0x80, v15
	v_add_u32_e32 v7, 0x80, v7
	v_ashrrev_i32_e32 v6, 8, v6
	v_min_i32_e32 v14, 0x7f, v14
	v_ashrrev_i32_e32 v15, 8, v15
	v_ashrrev_i32_e32 v7, 8, v7
	v_min_i32_e32 v6, 0x7f, v6
	v_min_i32_sdwa v15, v15, s85 dst_sel:WORD_1 dst_unused:UNUSED_PAD src0_sel:DWORD src1_sel:DWORD
	v_min_i32_e32 v7, 0x7f, v7
	v_lshlrev_b32_e32 v14, 8, v14
	v_and_b32_e32 v14, 0xff00, v14
	v_and_b32_e32 v15, 0xff0000, v15
	v_perm_b32 v6, v7, v6, s92
	v_or3_b32 v6, v6, v14, v15
	v_mad_u64_u32 v[14:15], s[22:23], v3, s63, v[2:3]
	v_or_b32_e32 v3, 32, v155
	ds_write_b32 v14, v6
	v_lshl_add_u32 v15, v3, 3, v219
	ds_read_b64 v[6:7], v15
	v_lshrrev_b32_e32 v134, 1, v3
	v_lshrrev_b32_e32 v3, 2, v3
	s_waitcnt lgkmcnt(0)
	v_pk_add_f32 v[18:19], v[136:137], v[6:7] op_sel_hi:[1,0] neg_lo:[0,1] neg_hi:[0,1]
	s_nop 0
	v_pk_mul_f32 v[18:19], v[6:7], v[18:19] op_sel:[1,0]
	v_pk_add_f32 v[122:123], v[138:139], v[6:7] op_sel_hi:[1,0] neg_lo:[0,1] neg_hi:[0,1]
	v_pk_fma_f32 v[18:19], v[22:23], v[18:19], v[144:145]
	v_pk_mul_f32 v[6:7], v[6:7], v[122:123] op_sel:[1,0]
	v_and_b32_sdwa v122, v19, v216 dst_sel:DWORD dst_unused:UNUSED_PAD src0_sel:WORD_1 src1_sel:DWORD
	v_and_b32_sdwa v123, v18, v216 dst_sel:DWORD dst_unused:UNUSED_PAD src0_sel:WORD_1 src1_sel:DWORD
	v_pk_fma_f32 v[6:7], v[0:1], v[6:7], v[4:5]
	v_add3_u32 v130, v19, v122, s84
	v_add3_u32 v122, v18, v123, s84
	v_and_b32_e32 v131, 0xffff0000, v122
	v_and_b32_sdwa v122, v7, v216 dst_sel:DWORD dst_unused:UNUSED_PAD src0_sel:WORD_1 src1_sel:DWORD
	v_and_b32_sdwa v123, v6, v216 dst_sel:DWORD dst_unused:UNUSED_PAD src0_sel:WORD_1 src1_sel:DWORD
	v_add3_u32 v122, v7, v122, s84
	v_add3_u32 v135, v6, v123, s84
	v_and_b32_e32 v136, 0xffff0000, v122
	v_mul_lo_u32 v137, v134, s63
	v_or_b32_sdwa v123, v136, v130 dst_sel:DWORD dst_unused:UNUSED_PAD src0_sel:DWORD src1_sel:WORD_1
	v_or_b32_sdwa v122, v135, v131 dst_sel:DWORD dst_unused:UNUSED_PAD src0_sel:WORD_1 src1_sel:DWORD
	v_add_u32_e32 v134, v154, v137
	ds_write_b64 v134, v[122:123]
	v_and_b32_e32 v122, 0xffff0000, v135
	v_sub_u32_e32 v6, v6, v122
	v_sub_u32_e32 v18, v18, v131
	v_and_b32_e32 v122, 0xffff0000, v130
	v_add_u32_e32 v18, 0x80, v18
	v_sub_u32_e32 v19, v19, v122
	v_sub_u32_e32 v7, v7, v136
	v_add_u32_e32 v6, 0x80, v6
	v_ashrrev_i32_e32 v18, 8, v18
	v_add_u32_e32 v19, 0x80, v19
	v_add_u32_e32 v7, 0x80, v7
	v_ashrrev_i32_e32 v6, 8, v6
	v_min_i32_e32 v18, 0x7f, v18
	v_ashrrev_i32_e32 v19, 8, v19
	v_ashrrev_i32_e32 v7, 8, v7
	v_min_i32_e32 v6, 0x7f, v6
	v_min_i32_sdwa v19, v19, s85 dst_sel:WORD_1 dst_unused:UNUSED_PAD src0_sel:DWORD src1_sel:DWORD
	v_min_i32_e32 v7, 0x7f, v7
	v_lshlrev_b32_e32 v18, 8, v18
	v_and_b32_e32 v18, 0xff00, v18
	v_and_b32_e32 v19, 0xff0000, v19
	v_perm_b32 v6, v7, v6, s92
	v_or3_b32 v6, v6, v18, v19
	v_mad_u64_u32 v[18:19], s[22:23], v3, s63, v[2:3]
	v_or_b32_e32 v3, 48, v155
	ds_write_b32 v18, v6
	v_lshl_add_u32 v19, v3, 3, v219
	ds_read_b64 v[6:7], v19
	v_lshrrev_b32_e32 v130, 1, v3
	v_mul_lo_u32 v136, v130, s63
	v_add_u32_e32 v135, v154, v136
	s_waitcnt lgkmcnt(0)
;     ...
;             _Pragma("unroll") for (int m = 0; m < 4; ++m) {
;               const int rr = wr3 * 64 + m * 16 + fr3;
;               const float2 ms = *reinterpret_cast<const float2*>(mr + (ai * HALF + rr) * 2);
;               f32x4 y = acc[ai][bj][m][n];
;               const float o0 = (y[0] - ms.x) * ms.y * gm.x + bt.x, o1 = (y[1] - ms.x) * ms.y * gm.y + bt.y;
;               const float o2 = (y[2] - ms.x) * ms.y * gm.z + bt.z, o3 = (y[3] - ms.x) * ms.y * gm.w + bt.w;
;               const unsigned h0 = f2bf(o0), h1 = f2bf(o1), h2 = f2bf(o2), h3 = f2bf(o3);
;               u32x2 ob; ob[0] = h0 | (h1 << 16); ob[1] = h2 | (h3 << 16);
;               *reinterpret_cast<u32x2*>(smem + (rr >> 1) * PIECE + (rr & 1) * 512 + cc * 2) = ob;
;               const int l0 = min(((int)__float_as_uint(o0) - (int)(h0 << 16) + 128) >> 8, 127);
;               const int l1 = min(((int)__float_as_uint(o1) - (int)(h1 << 16) + 128) >> 8, 127);
;               const int l2 = min(((int)__float_as_uint(o2) - (int)(h2 << 16) + 128) >> 8, 127);
;               const int l3 = min(((int)__float_as_uint(o3) - (int)(h3 << 16) + 128) >> 8, 127);
;               *reinterpret_cast<unsigned*>(smem + LOBASE + (rr >> 2) * PIECE + (rr & 3) * 256 + cc) =
;                   (unsigned)(l0 & 255) | ((unsigned)(l1 & 255) << 8) | ((unsigned)(l2 & 255) << 16) | ((unsigned)l3 << 24);
;             }
	v_pk_add_f32 v[122:123], v[140:141], v[6:7] op_sel_hi:[1,0] neg_lo:[0,1] neg_hi:[0,1]
	s_nop 0
	v_pk_mul_f32 v[122:123], v[6:7], v[122:123] op_sel:[1,0]
	s_nop 0
	v_pk_fma_f32 v[22:23], v[22:23], v[122:123], v[144:145]
	v_pk_add_f32 v[122:123], v[142:143], v[6:7] op_sel_hi:[1,0] neg_lo:[0,1] neg_hi:[0,1]
	s_nop 0
	v_pk_mul_f32 v[6:7], v[6:7], v[122:123] op_sel:[1,0]
	s_nop 0
	v_pk_fma_f32 v[0:1], v[0:1], v[6:7], v[4:5]
	v_and_b32_sdwa v4, v23, v216 dst_sel:DWORD dst_unused:UNUSED_PAD src0_sel:WORD_1 src1_sel:DWORD
	v_and_b32_sdwa v5, v22, v216 dst_sel:DWORD dst_unused:UNUSED_PAD src0_sel:WORD_1 src1_sel:DWORD
	v_add3_u32 v6, v23, v4, s84
	v_add3_u32 v4, v22, v5, s84
	v_and_b32_e32 v7, 0xffff0000, v4
	v_and_b32_sdwa v4, v1, v216 dst_sel:DWORD dst_unused:UNUSED_PAD src0_sel:WORD_1 src1_sel:DWORD
	v_and_b32_sdwa v5, v0, v216 dst_sel:DWORD dst_unused:UNUSED_PAD src0_sel:WORD_1 src1_sel:DWORD
	v_add3_u32 v4, v1, v4, s84
	v_add3_u32 v122, v0, v5, s84
	v_and_b32_e32 v123, 0xffff0000, v4
	v_or_b32_sdwa v5, v123, v6 dst_sel:DWORD dst_unused:UNUSED_PAD src0_sel:DWORD src1_sel:WORD_1
	v_or_b32_sdwa v4, v122, v7 dst_sel:DWORD dst_unused:UNUSED_PAD src0_sel:WORD_1 src1_sel:DWORD
	ds_write_b64 v135, v[4:5]
	v_and_b32_e32 v4, 0xffff0000, v122
	v_sub_u32_e32 v0, v0, v4
	v_sub_u32_e32 v4, v22, v7
	v_and_b32_e32 v5, 0xffff0000, v6
	v_add_u32_e32 v4, 0x80, v4
	v_sub_u32_e32 v5, v23, v5
	v_sub_u32_e32 v1, v1, v123
	v_add_u32_e32 v0, 0x80, v0
	v_ashrrev_i32_e32 v4, 8, v4
	v_add_u32_e32 v5, 0x80, v5
	v_add_u32_e32 v1, 0x80, v1
	v_ashrrev_i32_e32 v0, 8, v0
	v_min_i32_e32 v4, 0x7f, v4
	v_ashrrev_i32_e32 v5, 8, v5
	v_ashrrev_i32_e32 v1, 8, v1
	v_min_i32_e32 v0, 0x7f, v0
	v_min_i32_sdwa v5, v5, s85 dst_sel:WORD_1 dst_unused:UNUSED_PAD src0_sel:DWORD src1_sel:DWORD
	v_min_i32_e32 v1, 0x7f, v1
	v_lshlrev_b32_e32 v4, 8, v4
	v_and_b32_e32 v4, 0xff00, v4
	v_and_b32_e32 v5, 0xff0000, v5
	v_perm_b32 v0, v1, v0, s92
	v_lshrrev_b32_e32 v1, 2, v3
	v_or3_b32 v0, v0, v4, v5
	v_mad_u64_u32 v[22:23], s[22:23], v1, s63, v[2:3]
	ds_write_b32 v22, v0
	v_mov_b32_e32 v0, v224
	v_mov_b32_e32 v1, v225
	v_mov_b32_e32 v2, v226
	v_mov_b32_e32 v3, v227
	v_mov_b32_e32 v4, v240
	v_mov_b32_e32 v5, v241
	v_mov_b32_e32 v6, v242
	v_mov_b32_e32 v7, v243
	ds_read_b64 v[138:139], v149
	s_mov_b32 s22, s18
	s_mov_b32 s23, s19
	s_waitcnt lgkmcnt(0)
	v_pk_add_f32 v[128:129], v[128:129], v[138:139] op_sel_hi:[1,0] neg_lo:[0,1] neg_hi:[0,1]
	s_nop 0
	v_pk_mul_f32 v[128:129], v[138:139], v[128:129] op_sel:[1,0]
	v_pk_add_f32 v[126:127], v[126:127], v[138:139] op_sel_hi:[1,0] neg_lo:[0,1] neg_hi:[0,1]
	v_mov_b32_e32 v122, v1
	v_mov_b32_e32 v123, v2
	v_mov_b32_e32 v130, v5
	v_mov_b32_e32 v131, v6
	v_pk_fma_f32 v[128:129], v[122:123], v[128:129], v[130:131]
	v_pk_mul_f32 v[126:127], v[138:139], v[126:127] op_sel:[1,0]
	v_mov_b32_e32 v1, v3
	v_mov_b32_e32 v5, v7
	v_and_b32_sdwa v23, v128, v216 dst_sel:DWORD dst_unused:UNUSED_PAD src0_sel:WORD_1 src1_sel:DWORD
	v_pk_fma_f32 v[6:7], v[0:1], v[126:127], v[4:5]
	v_add3_u32 v23, v128, v23, s84
	v_and_b32_e32 v138, 0xffff0000, v23
	v_and_b32_sdwa v23, v7, v216 dst_sel:DWORD dst_unused:UNUSED_PAD src0_sel:WORD_1 src1_sel:DWORD
	v_and_b32_sdwa v3, v129, v216 dst_sel:DWORD dst_unused:UNUSED_PAD src0_sel:WORD_1 src1_sel:DWORD
	v_and_b32_sdwa v126, v6, v216 dst_sel:DWORD dst_unused:UNUSED_PAD src0_sel:WORD_1 src1_sel:DWORD
	v_add3_u32 v23, v7, v23, s84
	v_or_b32_e32 v2, 32, v154
	v_add3_u32 v3, v129, v3, s84
	v_add3_u32 v139, v6, v126, s84
	v_and_b32_e32 v140, 0xffff0000, v23
	v_or_b32_sdwa v127, v140, v3 dst_sel:DWORD dst_unused:UNUSED_PAD src0_sel:DWORD src1_sel:WORD_1
	v_or_b32_sdwa v126, v139, v138 dst_sel:DWORD dst_unused:UNUSED_PAD src0_sel:WORD_1 src1_sel:DWORD
	v_add_u32_e32 v23, v2, v152
	ds_write_b64 v23, v[126:127]
	v_and_b32_e32 v126, 0xffff0000, v139
	v_sub_u32_e32 v6, v6, v126
	v_sub_u32_e32 v126, v128, v138
	v_and_b32_e32 v3, 0xffff0000, v3
	v_add_u32_e32 v126, 0x80, v126
	v_sub_u32_e32 v3, v129, v3
	v_sub_u32_e32 v7, v7, v140
	v_add_u32_e32 v6, 0x80, v6
	v_ashrrev_i32_e32 v126, 8, v126
	v_add_u32_e32 v3, 0x80, v3
	v_add_u32_e32 v7, 0x80, v7
	v_ashrrev_i32_e32 v6, 8, v6
	v_min_i32_e32 v126, 0x7f, v126
	v_ashrrev_i32_e32 v3, 8, v3
	v_ashrrev_i32_e32 v7, 8, v7
	v_min_i32_e32 v6, 0x7f, v6
	v_min_i32_sdwa v3, v3, s85 dst_sel:WORD_1 dst_unused:UNUSED_PAD src0_sel:DWORD src1_sel:DWORD
	v_min_i32_e32 v7, 0x7f, v7
	v_lshlrev_b32_e32 v126, 8, v126
	v_and_b32_e32 v126, 0xff00, v126
	v_and_b32_e32 v3, 0xff0000, v3
	v_perm_b32 v6, v7, v6, s92
	v_or3_b32 v3, v6, v126, v3
	ds_write_b32 v12, v3 offset:16
	ds_read_b64 v[6:7], v13
	s_waitcnt lgkmcnt(0)
;     ...
;             _Pragma("unroll") for (int m = 0; m < 4; ++m) {
;               const int rr = wr3 * 64 + m * 16 + fr3;
;               const float2 ms = *reinterpret_cast<const float2*>(mr + (ai * HALF + rr) * 2);
;               f32x4 y = acc[ai][bj][m][n];
;               const float o0 = (y[0] - ms.x) * ms.y * gm.x + bt.x, o1 = (y[1] - ms.x) * ms.y * gm.y + bt.y;
;               const float o2 = (y[2] - ms.x) * ms.y * gm.z + bt.z, o3 = (y[3] - ms.x) * ms.y * gm.w + bt.w;
;               const unsigned h0 = f2bf(o0), h1 = f2bf(o1), h2 = f2bf(o2), h3 = f2bf(o3);
;               u32x2 ob; ob[0] = h0 | (h1 << 16); ob[1] = h2 | (h3 << 16);
;               *reinterpret_cast<u32x2*>(smem + (rr >> 1) * PIECE + (rr & 1) * 512 + cc * 2) = ob;
;               const int l0 = min(((int)__float_as_uint(o0) - (int)(h0 << 16) + 128) >> 8, 127);
;               const int l1 = min(((int)__float_as_uint(o1) - (int)(h1 << 16) + 128) >> 8, 127);
;               const int l2 = min(((int)__float_as_uint(o2) - (int)(h2 << 16) + 128) >> 8, 127);
;               const int l3 = min(((int)__float_as_uint(o3) - (int)(h3 << 16) + 128) >> 8, 127);
;               *reinterpret_cast<unsigned*>(smem + LOBASE + (rr >> 2) * PIECE + (rr & 3) * 256 + cc) =
;                   (unsigned)(l0 & 255) | ((unsigned)(l1 & 255) << 8) | ((unsigned)(l2 & 255) << 16) | ((unsigned)l3 << 24);
;             }
	v_pk_add_f32 v[108:109], v[108:109], v[6:7] op_sel_hi:[1,0] neg_lo:[0,1] neg_hi:[0,1]
	s_nop 0
	v_pk_mul_f32 v[108:109], v[6:7], v[108:109] op_sel:[1,0]
	s_nop 0
	v_pk_fma_f32 v[126:127], v[122:123], v[108:109], v[130:131]
	v_pk_add_f32 v[108:109], v[110:111], v[6:7] op_sel_hi:[1,0] neg_lo:[0,1] neg_hi:[0,1]
	v_and_b32_sdwa v3, v127, v216 dst_sel:DWORD dst_unused:UNUSED_PAD src0_sel:WORD_1 src1_sel:DWORD
	v_pk_mul_f32 v[6:7], v[6:7], v[108:109] op_sel:[1,0]
	v_and_b32_sdwa v108, v126, v216 dst_sel:DWORD dst_unused:UNUSED_PAD src0_sel:WORD_1 src1_sel:DWORD
	v_pk_fma_f32 v[6:7], v[0:1], v[6:7], v[4:5]
	v_add3_u32 v108, v126, v108, s84
	v_and_b32_e32 v109, 0xffff0000, v108
	v_and_b32_sdwa v108, v7, v216 dst_sel:DWORD dst_unused:UNUSED_PAD src0_sel:WORD_1 src1_sel:DWORD
	v_and_b32_sdwa v110, v6, v216 dst_sel:DWORD dst_unused:UNUSED_PAD src0_sel:WORD_1 src1_sel:DWORD
	v_add3_u32 v108, v7, v108, s84
	v_add3_u32 v3, v127, v3, s84
	v_add3_u32 v128, v6, v110, s84
	v_and_b32_e32 v129, 0xffff0000, v108
	v_or_b32_sdwa v111, v129, v3 dst_sel:DWORD dst_unused:UNUSED_PAD src0_sel:DWORD src1_sel:WORD_1
	v_or_b32_sdwa v110, v128, v109 dst_sel:DWORD dst_unused:UNUSED_PAD src0_sel:WORD_1 src1_sel:DWORD
	v_add_u32_e32 v108, v2, v153
	ds_write_b64 v108, v[110:111]
	v_and_b32_e32 v110, 0xffff0000, v128
	v_sub_u32_e32 v109, v126, v109
	v_and_b32_e32 v3, 0xffff0000, v3
	v_sub_u32_e32 v6, v6, v110
	v_add_u32_e32 v109, 0x80, v109
	v_sub_u32_e32 v3, v127, v3
	v_sub_u32_e32 v7, v7, v129
	v_add_u32_e32 v6, 0x80, v6
	v_ashrrev_i32_e32 v109, 8, v109
	v_add_u32_e32 v3, 0x80, v3
	v_add_u32_e32 v7, 0x80, v7
	v_ashrrev_i32_e32 v6, 8, v6
	v_min_i32_e32 v109, 0x7f, v109
	v_ashrrev_i32_e32 v3, 8, v3
	v_ashrrev_i32_e32 v7, 8, v7
	v_min_i32_e32 v6, 0x7f, v6
	v_min_i32_sdwa v3, v3, s85 dst_sel:WORD_1 dst_unused:UNUSED_PAD src0_sel:DWORD src1_sel:DWORD
	v_min_i32_e32 v7, 0x7f, v7
	v_lshlrev_b32_e32 v109, 8, v109
	v_and_b32_e32 v109, 0xff00, v109
	v_and_b32_e32 v3, 0xff0000, v3
	v_perm_b32 v6, v7, v6, s92
	v_or3_b32 v3, v6, v109, v3
	ds_write_b32 v14, v3 offset:16
	ds_read_b64 v[6:7], v15
	s_waitcnt lgkmcnt(0)
	v_pk_add_f32 v[98:99], v[98:99], v[6:7] op_sel_hi:[1,0] neg_lo:[0,1] neg_hi:[0,1]
	s_nop 0
	v_pk_mul_f32 v[98:99], v[6:7], v[98:99] op_sel:[1,0]
	s_nop 0
	v_pk_fma_f32 v[110:111], v[122:123], v[98:99], v[130:131]
	v_pk_add_f32 v[98:99], v[106:107], v[6:7] op_sel_hi:[1,0] neg_lo:[0,1] neg_hi:[0,1]
	v_and_b32_sdwa v3, v111, v216 dst_sel:DWORD dst_unused:UNUSED_PAD src0_sel:WORD_1 src1_sel:DWORD
	v_pk_mul_f32 v[6:7], v[6:7], v[98:99] op_sel:[1,0]
	v_and_b32_sdwa v98, v110, v216 dst_sel:DWORD dst_unused:UNUSED_PAD src0_sel:WORD_1 src1_sel:DWORD
	v_pk_fma_f32 v[6:7], v[0:1], v[6:7], v[4:5]
	v_add3_u32 v98, v110, v98, s84
	v_and_b32_e32 v99, 0xffff0000, v98
	v_and_b32_sdwa v98, v7, v216 dst_sel:DWORD dst_unused:UNUSED_PAD src0_sel:WORD_1 src1_sel:DWORD
	v_and_b32_sdwa v106, v6, v216 dst_sel:DWORD dst_unused:UNUSED_PAD src0_sel:WORD_1 src1_sel:DWORD
	v_add3_u32 v98, v7, v98, s84
	v_add3_u32 v3, v111, v3, s84
	v_add3_u32 v109, v6, v106, s84
	v_and_b32_e32 v126, 0xffff0000, v98
	v_or_b32_sdwa v107, v126, v3 dst_sel:DWORD dst_unused:UNUSED_PAD src0_sel:DWORD src1_sel:WORD_1
	v_or_b32_sdwa v106, v109, v99 dst_sel:DWORD dst_unused:UNUSED_PAD src0_sel:WORD_1 src1_sel:DWORD
	v_add_u32_e32 v98, v2, v137
	ds_write_b64 v98, v[106:107]
	v_and_b32_e32 v106, 0xffff0000, v109
	v_sub_u32_e32 v99, v110, v99
	v_and_b32_e32 v3, 0xffff0000, v3
	v_sub_u32_e32 v6, v6, v106
	v_add_u32_e32 v99, 0x80, v99
	v_sub_u32_e32 v3, v111, v3
	v_sub_u32_e32 v7, v7, v126
	v_add_u32_e32 v6, 0x80, v6
	v_ashrrev_i32_e32 v99, 8, v99
	v_add_u32_e32 v3, 0x80, v3
	v_add_u32_e32 v7, 0x80, v7
	v_ashrrev_i32_e32 v6, 8, v6
	v_min_i32_e32 v99, 0x7f, v99
	v_ashrrev_i32_e32 v3, 8, v3
	v_ashrrev_i32_e32 v7, 8, v7
	v_min_i32_e32 v6, 0x7f, v6
	v_min_i32_sdwa v3, v3, s85 dst_sel:WORD_1 dst_unused:UNUSED_PAD src0_sel:DWORD src1_sel:DWORD
	v_min_i32_e32 v7, 0x7f, v7
	v_lshlrev_b32_e32 v99, 8, v99
	v_and_b32_e32 v99, 0xff00, v99
	v_and_b32_e32 v3, 0xff0000, v3
	v_perm_b32 v6, v7, v6, s92
	v_or3_b32 v3, v6, v99, v3
	ds_write_b32 v18, v3 offset:16
	ds_read_b64 v[6:7], v19
	v_add_u32_e32 v99, v2, v136
	s_waitcnt lgkmcnt(0)
	v_pk_add_f32 v[106:107], v[114:115], v[6:7] op_sel_hi:[1,0] neg_lo:[0,1] neg_hi:[0,1]
	s_nop 0
	v_pk_mul_f32 v[106:107], v[6:7], v[106:107] op_sel:[1,0]
	v_pk_add_f32 v[110:111], v[120:121], v[6:7] op_sel_hi:[1,0] neg_lo:[0,1] neg_hi:[0,1]
	v_pk_fma_f32 v[106:107], v[122:123], v[106:107], v[130:131]
	v_pk_mul_f32 v[6:7], v[6:7], v[110:111] op_sel:[1,0]
	v_and_b32_sdwa v3, v107, v216 dst_sel:DWORD dst_unused:UNUSED_PAD src0_sel:WORD_1 src1_sel:DWORD
	v_pk_fma_f32 v[0:1], v[0:1], v[6:7], v[4:5]
	v_and_b32_sdwa v4, v106, v216 dst_sel:DWORD dst_unused:UNUSED_PAD src0_sel:WORD_1 src1_sel:DWORD
	v_add3_u32 v4, v106, v4, s84
	v_and_b32_e32 v6, 0xffff0000, v4
	v_and_b32_sdwa v4, v1, v216 dst_sel:DWORD dst_unused:UNUSED_PAD src0_sel:WORD_1 src1_sel:DWORD
	v_and_b32_sdwa v5, v0, v216 dst_sel:DWORD dst_unused:UNUSED_PAD src0_sel:WORD_1 src1_sel:DWORD
	v_add3_u32 v4, v1, v4, s84
	v_add3_u32 v7, v0, v5, s84
	v_add3_u32 v3, v107, v3, s84
	v_and_b32_e32 v109, 0xffff0000, v4
	v_and_b32_e32 v2, 0xffff0000, v7
	v_or_b32_sdwa v5, v109, v3 dst_sel:DWORD dst_unused:UNUSED_PAD src0_sel:DWORD src1_sel:WORD_1
	v_sub_u32_e32 v0, v0, v2
	v_sub_u32_e32 v2, v106, v6
	v_and_b32_e32 v3, 0xffff0000, v3
	v_add_u32_e32 v2, 0x80, v2
	v_sub_u32_e32 v3, v107, v3
	v_sub_u32_e32 v1, v1, v109
	v_add_u32_e32 v0, 0x80, v0
	v_ashrrev_i32_e32 v2, 8, v2
	v_add_u32_e32 v3, 0x80, v3
	v_add_u32_e32 v1, 0x80, v1
	v_ashrrev_i32_e32 v0, 8, v0
	v_min_i32_e32 v2, 0x7f, v2
	v_ashrrev_i32_e32 v3, 8, v3
	v_ashrrev_i32_e32 v1, 8, v1
	v_min_i32_e32 v0, 0x7f, v0
	v_min_i32_sdwa v3, v3, s85 dst_sel:WORD_1 dst_unused:UNUSED_PAD src0_sel:DWORD src1_sel:DWORD
	v_min_i32_e32 v1, 0x7f, v1
	v_lshlrev_b32_e32 v2, 8, v2
	v_and_b32_e32 v2, 0xff00, v2
	v_and_b32_e32 v3, 0xff0000, v3
	v_perm_b32 v0, v1, v0, s92
	v_or_b32_sdwa v4, v7, v6 dst_sel:DWORD dst_unused:UNUSED_PAD src0_sel:WORD_1 src1_sel:DWORD
	v_or3_b32 v0, v0, v2, v3
	ds_write_b64 v99, v[4:5]
	ds_write_b32 v22, v0 offset:16
	v_mov_b32_e32 v0, v228
	v_mov_b32_e32 v1, v229
	v_mov_b32_e32 v2, v230
	v_mov_b32_e32 v3, v231
	v_mov_b32_e32 v4, v244
	v_mov_b32_e32 v5, v245
	v_mov_b32_e32 v6, v246
	v_mov_b32_e32 v7, v247
	ds_read_b64 v[106:107], v149
	v_or_b32_e32 v109, 0x100, v154
	s_waitcnt lgkmcnt(0)
;     ...
;             _Pragma("unroll") for (int m = 0; m < 4; ++m) {
;               const int rr = wr3 * 64 + m * 16 + fr3;
;               const float2 ms = *reinterpret_cast<const float2*>(mr + (ai * HALF + rr) * 2);
;               f32x4 y = acc[ai][bj][m][n];
;               const float o0 = (y[0] - ms.x) * ms.y * gm.x + bt.x, o1 = (y[1] - ms.x) * ms.y * gm.y + bt.y;
;               const float o2 = (y[2] - ms.x) * ms.y * gm.z + bt.z, o3 = (y[3] - ms.x) * ms.y * gm.w + bt.w;
;               const unsigned h0 = f2bf(o0), h1 = f2bf(o1), h2 = f2bf(o2), h3 = f2bf(o3);
;               u32x2 ob; ob[0] = h0 | (h1 << 16); ob[1] = h2 | (h3 << 16);
;               *reinterpret_cast<u32x2*>(smem + (rr >> 1) * PIECE + (rr & 1) * 512 + cc * 2) = ob;
;               const int l0 = min(((int)__float_as_uint(o0) - (int)(h0 << 16) + 128) >> 8, 127);
;               const int l1 = min(((int)__float_as_uint(o1) - (int)(h1 << 16) + 128) >> 8, 127);
;               const int l2 = min(((int)__float_as_uint(o2) - (int)(h2 << 16) + 128) >> 8, 127);
;               const int l3 = min(((int)__float_as_uint(o3) - (int)(h3 << 16) + 128) >> 8, 127);
;               *reinterpret_cast<unsigned*>(smem + LOBASE + (rr >> 2) * PIECE + (rr & 3) * 256 + cc) =
;                   (unsigned)(l0 & 255) | ((unsigned)(l1 & 255) << 8) | ((unsigned)(l2 & 255) << 16) | ((unsigned)l3 << 24);
;             }
	v_pk_add_f32 v[120:121], v[124:125], v[106:107] op_sel_hi:[1,0] neg_lo:[0,1] neg_hi:[0,1]
	s_nop 0
	v_pk_mul_f32 v[120:121], v[106:107], v[120:121] op_sel:[1,0]
	v_pk_add_f32 v[118:119], v[118:119], v[106:107] op_sel_hi:[1,0] neg_lo:[0,1] neg_hi:[0,1]
	v_mov_b32_e32 v110, v1
	v_mov_b32_e32 v111, v2
	v_mov_b32_e32 v114, v5
	v_mov_b32_e32 v115, v6
	v_pk_fma_f32 v[120:121], v[110:111], v[120:121], v[114:115]
	v_pk_mul_f32 v[106:107], v[106:107], v[118:119] op_sel:[1,0]
	v_mov_b32_e32 v1, v3
	v_mov_b32_e32 v5, v7
	v_and_b32_sdwa v6, v121, v216 dst_sel:DWORD dst_unused:UNUSED_PAD src0_sel:WORD_1 src1_sel:DWORD
	v_and_b32_sdwa v7, v120, v216 dst_sel:DWORD dst_unused:UNUSED_PAD src0_sel:WORD_1 src1_sel:DWORD
	v_pk_fma_f32 v[2:3], v[0:1], v[106:107], v[4:5]
	v_add3_u32 v107, v121, v6, s84
	v_add3_u32 v6, v120, v7, s84
	v_and_b32_e32 v118, 0xffff0000, v6
	v_and_b32_sdwa v6, v3, v216 dst_sel:DWORD dst_unused:UNUSED_PAD src0_sel:WORD_1 src1_sel:DWORD
	v_and_b32_sdwa v7, v2, v216 dst_sel:DWORD dst_unused:UNUSED_PAD src0_sel:WORD_1 src1_sel:DWORD
	v_add3_u32 v6, v3, v6, s84
	v_add3_u32 v119, v2, v7, s84
	v_and_b32_e32 v122, 0xffff0000, v6
	v_or_b32_sdwa v7, v122, v107 dst_sel:DWORD dst_unused:UNUSED_PAD src0_sel:DWORD src1_sel:WORD_1
	v_or_b32_sdwa v6, v119, v118 dst_sel:DWORD dst_unused:UNUSED_PAD src0_sel:WORD_1 src1_sel:DWORD
	v_add_u32_e32 v106, v109, v152
	ds_write_b64 v106, v[6:7]
	v_and_b32_e32 v6, 0xffff0000, v119
	v_sub_u32_e32 v2, v2, v6
	v_sub_u32_e32 v6, v120, v118
	v_and_b32_e32 v7, 0xffff0000, v107
	v_add_u32_e32 v6, 0x80, v6
	v_sub_u32_e32 v7, v121, v7
	v_sub_u32_e32 v3, v3, v122
	v_add_u32_e32 v2, 0x80, v2
	v_ashrrev_i32_e32 v6, 8, v6
	v_add_u32_e32 v7, 0x80, v7
	v_add_u32_e32 v3, 0x80, v3
	v_ashrrev_i32_e32 v2, 8, v2
	v_min_i32_e32 v6, 0x7f, v6
	v_ashrrev_i32_e32 v7, 8, v7
	v_ashrrev_i32_e32 v3, 8, v3
	v_min_i32_e32 v2, 0x7f, v2
	v_min_i32_sdwa v7, v7, s85 dst_sel:WORD_1 dst_unused:UNUSED_PAD src0_sel:DWORD src1_sel:DWORD
	v_min_i32_e32 v3, 0x7f, v3
	v_lshlrev_b32_e32 v6, 8, v6
	v_and_b32_e32 v6, 0xff00, v6
	v_and_b32_e32 v7, 0xff0000, v7
	v_perm_b32 v2, v3, v2, s92
	v_or3_b32 v2, v2, v6, v7
	ds_write_b32 v12, v2 offset:128
	ds_read_b64 v[2:3], v13
	s_waitcnt lgkmcnt(0)
	v_pk_add_f32 v[6:7], v[102:103], v[2:3] op_sel_hi:[1,0] neg_lo:[0,1] neg_hi:[0,1]
	s_nop 0
	v_pk_mul_f32 v[6:7], v[2:3], v[6:7] op_sel:[1,0]
	v_pk_add_f32 v[102:103], v[104:105], v[2:3] op_sel_hi:[1,0] neg_lo:[0,1] neg_hi:[0,1]
	v_pk_fma_f32 v[6:7], v[110:111], v[6:7], v[114:115]
	v_pk_mul_f32 v[2:3], v[2:3], v[102:103] op_sel:[1,0]
	v_and_b32_sdwa v102, v7, v216 dst_sel:DWORD dst_unused:UNUSED_PAD src0_sel:WORD_1 src1_sel:DWORD
	v_and_b32_sdwa v103, v6, v216 dst_sel:DWORD dst_unused:UNUSED_PAD src0_sel:WORD_1 src1_sel:DWORD
	v_pk_fma_f32 v[2:3], v[0:1], v[2:3], v[4:5]
	v_add3_u32 v107, v7, v102, s84
	v_add3_u32 v102, v6, v103, s84
	v_and_b32_e32 v103, 0xffff0000, v102
	v_and_b32_sdwa v102, v3, v216 dst_sel:DWORD dst_unused:UNUSED_PAD src0_sel:WORD_1 src1_sel:DWORD
	v_and_b32_sdwa v104, v2, v216 dst_sel:DWORD dst_unused:UNUSED_PAD src0_sel:WORD_1 src1_sel:DWORD
	v_add3_u32 v102, v3, v102, s84
	v_add3_u32 v118, v2, v104, s84
	v_and_b32_e32 v119, 0xffff0000, v102
	v_or_b32_sdwa v105, v119, v107 dst_sel:DWORD dst_unused:UNUSED_PAD src0_sel:DWORD src1_sel:WORD_1
	v_or_b32_sdwa v104, v118, v103 dst_sel:DWORD dst_unused:UNUSED_PAD src0_sel:WORD_1 src1_sel:DWORD
	v_add_u32_e32 v102, v109, v153
	ds_write_b64 v102, v[104:105]
	v_and_b32_e32 v104, 0xffff0000, v118
	v_sub_u32_e32 v6, v6, v103
	v_and_b32_e32 v103, 0xffff0000, v107
	v_sub_u32_e32 v2, v2, v104
	v_add_u32_e32 v6, 0x80, v6
	v_sub_u32_e32 v7, v7, v103
	v_sub_u32_e32 v3, v3, v119
	v_add_u32_e32 v2, 0x80, v2
	v_ashrrev_i32_e32 v6, 8, v6
	v_add_u32_e32 v7, 0x80, v7
	v_add_u32_e32 v3, 0x80, v3
	v_ashrrev_i32_e32 v2, 8, v2
	v_min_i32_e32 v6, 0x7f, v6
	v_ashrrev_i32_e32 v7, 8, v7
	v_ashrrev_i32_e32 v3, 8, v3
	v_min_i32_e32 v2, 0x7f, v2
	v_min_i32_sdwa v7, v7, s85 dst_sel:WORD_1 dst_unused:UNUSED_PAD src0_sel:DWORD src1_sel:DWORD
	v_min_i32_e32 v3, 0x7f, v3
	v_lshlrev_b32_e32 v6, 8, v6
	v_and_b32_e32 v6, 0xff00, v6
	v_and_b32_e32 v7, 0xff0000, v7
	v_perm_b32 v2, v3, v2, s92
	v_or3_b32 v2, v2, v6, v7
	ds_write_b32 v14, v2 offset:128
	ds_read_b64 v[2:3], v15
	s_waitcnt lgkmcnt(0)
	v_pk_add_f32 v[6:7], v[92:93], v[2:3] op_sel_hi:[1,0] neg_lo:[0,1] neg_hi:[0,1]
	s_nop 0
	v_pk_mul_f32 v[6:7], v[2:3], v[6:7] op_sel:[1,0]
	v_pk_add_f32 v[88:89], v[88:89], v[2:3] op_sel_hi:[1,0] neg_lo:[0,1] neg_hi:[0,1]
	v_pk_fma_f32 v[6:7], v[110:111], v[6:7], v[114:115]
	v_pk_mul_f32 v[2:3], v[2:3], v[88:89] op_sel:[1,0]
	v_and_b32_sdwa v88, v7, v216 dst_sel:DWORD dst_unused:UNUSED_PAD src0_sel:WORD_1 src1_sel:DWORD
	v_and_b32_sdwa v89, v6, v216 dst_sel:DWORD dst_unused:UNUSED_PAD src0_sel:WORD_1 src1_sel:DWORD
	v_pk_fma_f32 v[2:3], v[0:1], v[2:3], v[4:5]
	v_add3_u32 v93, v7, v88, s84
	v_add3_u32 v88, v6, v89, s84
	v_and_b32_e32 v103, 0xffff0000, v88
	v_and_b32_sdwa v88, v3, v216 dst_sel:DWORD dst_unused:UNUSED_PAD src0_sel:WORD_1 src1_sel:DWORD
	v_and_b32_sdwa v89, v2, v216 dst_sel:DWORD dst_unused:UNUSED_PAD src0_sel:WORD_1 src1_sel:DWORD
	v_add3_u32 v88, v3, v88, s84
	v_add3_u32 v104, v2, v89, s84
	v_and_b32_e32 v105, 0xffff0000, v88
	v_or_b32_sdwa v89, v105, v93 dst_sel:DWORD dst_unused:UNUSED_PAD src0_sel:DWORD src1_sel:WORD_1
	v_or_b32_sdwa v88, v104, v103 dst_sel:DWORD dst_unused:UNUSED_PAD src0_sel:WORD_1 src1_sel:DWORD
	v_add_u32_e32 v92, v109, v137
	ds_write_b64 v92, v[88:89]
	v_and_b32_e32 v88, 0xffff0000, v104
	v_sub_u32_e32 v2, v2, v88
	v_sub_u32_e32 v6, v6, v103
	v_and_b32_e32 v88, 0xffff0000, v93
	v_add_u32_e32 v6, 0x80, v6
	v_sub_u32_e32 v7, v7, v88
	v_sub_u32_e32 v3, v3, v105
	v_add_u32_e32 v2, 0x80, v2
	v_ashrrev_i32_e32 v6, 8, v6
	v_add_u32_e32 v7, 0x80, v7
	v_add_u32_e32 v3, 0x80, v3
	v_ashrrev_i32_e32 v2, 8, v2
	v_min_i32_e32 v6, 0x7f, v6
	v_ashrrev_i32_e32 v7, 8, v7
	v_ashrrev_i32_e32 v3, 8, v3
	v_min_i32_e32 v2, 0x7f, v2
	v_min_i32_sdwa v7, v7, s85 dst_sel:WORD_1 dst_unused:UNUSED_PAD src0_sel:DWORD src1_sel:DWORD
	v_min_i32_e32 v3, 0x7f, v3
	v_lshlrev_b32_e32 v6, 8, v6
	v_and_b32_e32 v6, 0xff00, v6
	v_and_b32_e32 v7, 0xff0000, v7
	v_perm_b32 v2, v3, v2, s92
	v_or3_b32 v2, v2, v6, v7
	ds_write_b32 v18, v2 offset:128
	ds_read_b64 v[2:3], v19
	v_add_u32_e32 v93, v109, v136
	s_waitcnt lgkmcnt(0)
;     ...
;             _Pragma("unroll") for (int m = 0; m < 4; ++m) {
;               const int rr = wr3 * 64 + m * 16 + fr3;
;               const float2 ms = *reinterpret_cast<const float2*>(mr + (ai * HALF + rr) * 2);
;               f32x4 y = acc[ai][bj][m][n];
;               const float o0 = (y[0] - ms.x) * ms.y * gm.x + bt.x, o1 = (y[1] - ms.x) * ms.y * gm.y + bt.y;
;               const float o2 = (y[2] - ms.x) * ms.y * gm.z + bt.z, o3 = (y[3] - ms.x) * ms.y * gm.w + bt.w;
;               const unsigned h0 = f2bf(o0), h1 = f2bf(o1), h2 = f2bf(o2), h3 = f2bf(o3);
;               u32x2 ob; ob[0] = h0 | (h1 << 16); ob[1] = h2 | (h3 << 16);
;               *reinterpret_cast<u32x2*>(smem + (rr >> 1) * PIECE + (rr & 1) * 512 + cc * 2) = ob;
;               const int l0 = min(((int)__float_as_uint(o0) - (int)(h0 << 16) + 128) >> 8, 127);
;               const int l1 = min(((int)__float_as_uint(o1) - (int)(h1 << 16) + 128) >> 8, 127);
;               const int l2 = min(((int)__float_as_uint(o2) - (int)(h2 << 16) + 128) >> 8, 127);
;               const int l3 = min(((int)__float_as_uint(o3) - (int)(h3 << 16) + 128) >> 8, 127);
;               *reinterpret_cast<unsigned*>(smem + LOBASE + (rr >> 2) * PIECE + (rr & 3) * 256 + cc) =
;                   (unsigned)(l0 & 255) | ((unsigned)(l1 & 255) << 8) | ((unsigned)(l2 & 255) << 16) | ((unsigned)l3 << 24);
;             }
	v_pk_add_f32 v[6:7], v[90:91], v[2:3] op_sel_hi:[1,0] neg_lo:[0,1] neg_hi:[0,1]
	s_nop 0
	v_pk_mul_f32 v[6:7], v[2:3], v[6:7] op_sel:[1,0]
	v_pk_add_f32 v[88:89], v[94:95], v[2:3] op_sel_hi:[1,0] neg_lo:[0,1] neg_hi:[0,1]
	v_pk_fma_f32 v[6:7], v[110:111], v[6:7], v[114:115]
	v_pk_mul_f32 v[2:3], v[2:3], v[88:89] op_sel:[1,0]
	s_nop 0
	v_pk_fma_f32 v[0:1], v[0:1], v[2:3], v[4:5]
	v_and_b32_sdwa v2, v7, v216 dst_sel:DWORD dst_unused:UNUSED_PAD src0_sel:WORD_1 src1_sel:DWORD
	v_and_b32_sdwa v3, v6, v216 dst_sel:DWORD dst_unused:UNUSED_PAD src0_sel:WORD_1 src1_sel:DWORD
	v_add3_u32 v4, v7, v2, s84
	v_add3_u32 v2, v6, v3, s84
	v_and_b32_e32 v5, 0xffff0000, v2
	v_and_b32_sdwa v2, v1, v216 dst_sel:DWORD dst_unused:UNUSED_PAD src0_sel:WORD_1 src1_sel:DWORD
	v_and_b32_sdwa v3, v0, v216 dst_sel:DWORD dst_unused:UNUSED_PAD src0_sel:WORD_1 src1_sel:DWORD
	v_add3_u32 v2, v1, v2, s84
	v_add3_u32 v88, v0, v3, s84
	v_and_b32_e32 v89, 0xffff0000, v2
	v_or_b32_sdwa v3, v89, v4 dst_sel:DWORD dst_unused:UNUSED_PAD src0_sel:DWORD src1_sel:WORD_1
	v_or_b32_sdwa v2, v88, v5 dst_sel:DWORD dst_unused:UNUSED_PAD src0_sel:WORD_1 src1_sel:DWORD
	ds_write_b64 v93, v[2:3]
	v_and_b32_e32 v2, 0xffff0000, v88
	v_sub_u32_e32 v0, v0, v2
	v_sub_u32_e32 v2, v6, v5
	v_and_b32_e32 v3, 0xffff0000, v4
	v_add_u32_e32 v2, 0x80, v2
	v_sub_u32_e32 v3, v7, v3
	v_sub_u32_e32 v1, v1, v89
	v_add_u32_e32 v0, 0x80, v0
	v_ashrrev_i32_e32 v2, 8, v2
	v_add_u32_e32 v3, 0x80, v3
	v_add_u32_e32 v1, 0x80, v1
	v_ashrrev_i32_e32 v0, 8, v0
	v_min_i32_e32 v2, 0x7f, v2
	v_ashrrev_i32_e32 v3, 8, v3
	v_ashrrev_i32_e32 v1, 8, v1
	v_min_i32_e32 v0, 0x7f, v0
	v_min_i32_sdwa v3, v3, s85 dst_sel:WORD_1 dst_unused:UNUSED_PAD src0_sel:DWORD src1_sel:DWORD
	v_min_i32_e32 v1, 0x7f, v1
	v_lshlrev_b32_e32 v2, 8, v2
	v_and_b32_e32 v2, 0xff00, v2
	v_and_b32_e32 v3, 0xff0000, v3
	v_perm_b32 v0, v1, v0, s92
	v_or3_b32 v0, v0, v2, v3
	ds_write_b32 v22, v0 offset:128
	v_mov_b32_e32 v0, v232
	v_mov_b32_e32 v1, v233
	v_mov_b32_e32 v2, v234
	v_mov_b32_e32 v3, v235
	v_mov_b32_e32 v4, v248
	v_mov_b32_e32 v5, v249
	v_mov_b32_e32 v6, v250
	v_mov_b32_e32 v7, v251
	ds_read_b64 v[94:95], v149
	s_waitcnt lgkmcnt(0)
	v_pk_add_f32 v[104:105], v[116:117], v[94:95] op_sel_hi:[1,0] neg_lo:[0,1] neg_hi:[0,1]
	s_nop 0
	v_pk_mul_f32 v[104:105], v[94:95], v[104:105] op_sel:[1,0]
	v_pk_add_f32 v[110:111], v[112:113], v[94:95] op_sel_hi:[1,0] neg_lo:[0,1] neg_hi:[0,1]
	v_mov_b32_e32 v88, v1
	v_mov_b32_e32 v89, v2
	v_mov_b32_e32 v90, v5
	v_mov_b32_e32 v91, v6
	v_pk_fma_f32 v[104:105], v[88:89], v[104:105], v[90:91]
	v_pk_mul_f32 v[94:95], v[94:95], v[110:111] op_sel:[1,0]
	v_mov_b32_e32 v1, v3
	v_mov_b32_e32 v5, v7
	v_pk_fma_f32 v[6:7], v[0:1], v[94:95], v[4:5]
	v_and_b32_sdwa v94, v104, v216 dst_sel:DWORD dst_unused:UNUSED_PAD src0_sel:WORD_1 src1_sel:DWORD
	v_add3_u32 v94, v104, v94, s84
	v_and_b32_e32 v95, 0xffff0000, v94
	v_and_b32_sdwa v94, v7, v216 dst_sel:DWORD dst_unused:UNUSED_PAD src0_sel:WORD_1 src1_sel:DWORD
	v_and_b32_sdwa v3, v105, v216 dst_sel:DWORD dst_unused:UNUSED_PAD src0_sel:WORD_1 src1_sel:DWORD
	v_and_b32_sdwa v103, v6, v216 dst_sel:DWORD dst_unused:UNUSED_PAD src0_sel:WORD_1 src1_sel:DWORD
	v_add3_u32 v94, v7, v94, s84
	v_add3_u32 v3, v105, v3, s84
	v_add3_u32 v103, v6, v103, s84
	v_and_b32_e32 v107, 0xffff0000, v94
	v_or_b32_sdwa v111, v107, v3 dst_sel:DWORD dst_unused:UNUSED_PAD src0_sel:DWORD src1_sel:WORD_1
	v_or_b32_sdwa v110, v103, v95 dst_sel:DWORD dst_unused:UNUSED_PAD src0_sel:WORD_1 src1_sel:DWORD
	v_and_b32_e32 v103, 0xffff0000, v103
	v_sub_u32_e32 v95, v104, v95
	v_and_b32_e32 v3, 0xffff0000, v3
	v_sub_u32_e32 v6, v6, v103
	v_add_u32_e32 v95, 0x80, v95
	v_sub_u32_e32 v3, v105, v3
	v_sub_u32_e32 v7, v7, v107
	v_add_u32_e32 v6, 0x80, v6
	v_ashrrev_i32_e32 v95, 8, v95
	v_add_u32_e32 v3, 0x80, v3
	v_add_u32_e32 v7, 0x80, v7
	v_ashrrev_i32_e32 v6, 8, v6
	v_min_i32_e32 v95, 0x7f, v95
	v_ashrrev_i32_e32 v3, 8, v3
	v_ashrrev_i32_e32 v7, 8, v7
	v_min_i32_e32 v6, 0x7f, v6
	v_min_i32_sdwa v3, v3, s85 dst_sel:WORD_1 dst_unused:UNUSED_PAD src0_sel:DWORD src1_sel:DWORD
	v_min_i32_e32 v7, 0x7f, v7
	v_lshlrev_b32_e32 v95, 8, v95
	v_or_b32_e32 v2, 0x120, v154
	v_and_b32_e32 v95, 0xff00, v95
	v_and_b32_e32 v3, 0xff0000, v3
	v_perm_b32 v6, v7, v6, s92
	v_add_u32_e32 v94, v2, v152
	v_or3_b32 v3, v6, v95, v3
	ds_write_b64 v94, v[110:111]
	ds_write_b32 v12, v3 offset:144
	ds_read_b64 v[6:7], v13
	s_waitcnt lgkmcnt(0)
	v_pk_add_f32 v[100:101], v[100:101], v[6:7] op_sel_hi:[1,0] neg_lo:[0,1] neg_hi:[0,1]
	s_nop 0
	v_pk_mul_f32 v[100:101], v[6:7], v[100:101] op_sel:[1,0]
	v_pk_add_f32 v[96:97], v[96:97], v[6:7] op_sel_hi:[1,0] neg_lo:[0,1] neg_hi:[0,1]
	v_pk_fma_f32 v[100:101], v[88:89], v[100:101], v[90:91]
	v_pk_mul_f32 v[6:7], v[6:7], v[96:97] op_sel:[1,0]
	v_and_b32_sdwa v95, v100, v216 dst_sel:DWORD dst_unused:UNUSED_PAD src0_sel:WORD_1 src1_sel:DWORD
	v_pk_fma_f32 v[6:7], v[0:1], v[6:7], v[4:5]
	v_add3_u32 v95, v100, v95, s84
	v_and_b32_e32 v103, 0xffff0000, v95
	v_and_b32_sdwa v95, v7, v216 dst_sel:DWORD dst_unused:UNUSED_PAD src0_sel:WORD_1 src1_sel:DWORD
	v_and_b32_sdwa v3, v101, v216 dst_sel:DWORD dst_unused:UNUSED_PAD src0_sel:WORD_1 src1_sel:DWORD
	v_and_b32_sdwa v96, v6, v216 dst_sel:DWORD dst_unused:UNUSED_PAD src0_sel:WORD_1 src1_sel:DWORD
	v_add3_u32 v95, v7, v95, s84
	v_add3_u32 v3, v101, v3, s84
	v_add3_u32 v104, v6, v96, s84
	v_and_b32_e32 v105, 0xffff0000, v95
	v_or_b32_sdwa v97, v105, v3 dst_sel:DWORD dst_unused:UNUSED_PAD src0_sel:DWORD src1_sel:WORD_1
	v_or_b32_sdwa v96, v104, v103 dst_sel:DWORD dst_unused:UNUSED_PAD src0_sel:WORD_1 src1_sel:DWORD
	v_add_u32_e32 v95, v2, v153
	ds_write_b64 v95, v[96:97]
	v_and_b32_e32 v96, 0xffff0000, v104
	v_sub_u32_e32 v6, v6, v96
	v_sub_u32_e32 v96, v100, v103
	v_and_b32_e32 v3, 0xffff0000, v3
	v_add_u32_e32 v96, 0x80, v96
	v_sub_u32_e32 v3, v101, v3
	v_sub_u32_e32 v7, v7, v105
	v_add_u32_e32 v6, 0x80, v6
	v_ashrrev_i32_e32 v96, 8, v96
	v_add_u32_e32 v3, 0x80, v3
	v_add_u32_e32 v7, 0x80, v7
	v_ashrrev_i32_e32 v6, 8, v6
	v_min_i32_e32 v96, 0x7f, v96
	v_ashrrev_i32_e32 v3, 8, v3
	v_ashrrev_i32_e32 v7, 8, v7
	v_min_i32_e32 v6, 0x7f, v6
	v_min_i32_sdwa v3, v3, s85 dst_sel:WORD_1 dst_unused:UNUSED_PAD src0_sel:DWORD src1_sel:DWORD
	v_min_i32_e32 v7, 0x7f, v7
	v_lshlrev_b32_e32 v96, 8, v96
	v_and_b32_e32 v96, 0xff00, v96
	v_and_b32_e32 v3, 0xff0000, v3
	v_perm_b32 v6, v7, v6, s92
	v_or3_b32 v3, v6, v96, v3
	ds_write_b32 v14, v3 offset:144
	ds_read_b64 v[6:7], v15
	s_waitcnt lgkmcnt(0)
; #define WAIT_L(n) asm volatile("s_waitcnt lgkmcnt(" #n ")" ::: "memory")
; #define BAR __builtin_amdgcn_s_barrier()
;     ...
;             _Pragma("unroll") for (int m = 0; m < 4; ++m) {
;               const int rr = wr3 * 64 + m * 16 + fr3;
;               const float2 ms = *reinterpret_cast<const float2*>(mr + (ai * HALF + rr) * 2);
;               f32x4 y = acc[ai][bj][m][n];
;               const float o0 = (y[0] - ms.x) * ms.y * gm.x + bt.x, o1 = (y[1] - ms.x) * ms.y * gm.y + bt.y;
;               const float o2 = (y[2] - ms.x) * ms.y * gm.z + bt.z, o3 = (y[3] - ms.x) * ms.y * gm.w + bt.w;
;               const unsigned h0 = f2bf(o0), h1 = f2bf(o1), h2 = f2bf(o2), h3 = f2bf(o3);
;               u32x2 ob; ob[0] = h0 | (h1 << 16); ob[1] = h2 | (h3 << 16);
;               *reinterpret_cast<u32x2*>(smem + (rr >> 1) * PIECE + (rr & 1) * 512 + cc * 2) = ob;
;               const int l0 = min(((int)__float_as_uint(o0) - (int)(h0 << 16) + 128) >> 8, 127);
;               const int l1 = min(((int)__float_as_uint(o1) - (int)(h1 << 16) + 128) >> 8, 127);
;               const int l2 = min(((int)__float_as_uint(o2) - (int)(h2 << 16) + 128) >> 8, 127);
;               const int l3 = min(((int)__float_as_uint(o3) - (int)(h3 << 16) + 128) >> 8, 127);
;               *reinterpret_cast<unsigned*>(smem + LOBASE + (rr >> 2) * PIECE + (rr & 3) * 256 + cc) =
;                   (unsigned)(l0 & 255) | ((unsigned)(l1 & 255) << 8) | ((unsigned)(l2 & 255) << 16) | ((unsigned)l3 << 24);
;             }
;           }
;           WAIT_L(0); BAR;
;           const int hso = ((brow + ai * HALF + 16 * wave) * DM + pn * BM) * 2;
;           const int lso = (brow + ai * HALF + 16 * wave) * DM + pn * BM;
;           _Pragma("unroll") for (int i = 0; i < 8; ++i) {
;             const u32x4 v = *reinterpret_cast<const u32x4*>(smem + (wave * 8 + i) * PIECE + lane3 * 16);
	v_pk_add_f32 v[84:85], v[84:85], v[6:7] op_sel_hi:[1,0] neg_lo:[0,1] neg_hi:[0,1]
	s_nop 0
	v_pk_mul_f32 v[84:85], v[6:7], v[84:85] op_sel:[1,0]
	v_pk_add_f32 v[80:81], v[80:81], v[6:7] op_sel_hi:[1,0] neg_lo:[0,1] neg_hi:[0,1]
	v_pk_fma_f32 v[84:85], v[88:89], v[84:85], v[90:91]
	v_pk_mul_f32 v[6:7], v[6:7], v[80:81] op_sel:[1,0]
	v_and_b32_sdwa v80, v84, v216 dst_sel:DWORD dst_unused:UNUSED_PAD src0_sel:WORD_1 src1_sel:DWORD
	v_pk_fma_f32 v[6:7], v[0:1], v[6:7], v[4:5]
	v_add3_u32 v80, v84, v80, s84
	v_and_b32_e32 v81, 0xffff0000, v80
	v_and_b32_sdwa v80, v7, v216 dst_sel:DWORD dst_unused:UNUSED_PAD src0_sel:WORD_1 src1_sel:DWORD
	v_and_b32_sdwa v3, v85, v216 dst_sel:DWORD dst_unused:UNUSED_PAD src0_sel:WORD_1 src1_sel:DWORD
	v_and_b32_sdwa v96, v6, v216 dst_sel:DWORD dst_unused:UNUSED_PAD src0_sel:WORD_1 src1_sel:DWORD
	v_add3_u32 v80, v7, v80, s84
	v_add3_u32 v3, v85, v3, s84
	v_add3_u32 v100, v6, v96, s84
	v_and_b32_e32 v101, 0xffff0000, v80
	v_or_b32_sdwa v97, v101, v3 dst_sel:DWORD dst_unused:UNUSED_PAD src0_sel:DWORD src1_sel:WORD_1
	v_or_b32_sdwa v96, v100, v81 dst_sel:DWORD dst_unused:UNUSED_PAD src0_sel:WORD_1 src1_sel:DWORD
	v_add_u32_e32 v80, v2, v137
	ds_write_b64 v80, v[96:97]
	v_and_b32_e32 v96, 0xffff0000, v100
	v_sub_u32_e32 v81, v84, v81
	v_and_b32_e32 v3, 0xffff0000, v3
	v_sub_u32_e32 v6, v6, v96
	v_add_u32_e32 v81, 0x80, v81
	v_sub_u32_e32 v3, v85, v3
	v_sub_u32_e32 v7, v7, v101
	v_add_u32_e32 v6, 0x80, v6
	v_ashrrev_i32_e32 v81, 8, v81
	v_add_u32_e32 v3, 0x80, v3
	v_add_u32_e32 v7, 0x80, v7
	v_ashrrev_i32_e32 v6, 8, v6
	v_min_i32_e32 v81, 0x7f, v81
	v_ashrrev_i32_e32 v3, 8, v3
	v_ashrrev_i32_e32 v7, 8, v7
	v_min_i32_e32 v6, 0x7f, v6
	v_min_i32_sdwa v3, v3, s85 dst_sel:WORD_1 dst_unused:UNUSED_PAD src0_sel:DWORD src1_sel:DWORD
	v_min_i32_e32 v7, 0x7f, v7
	v_lshlrev_b32_e32 v81, 8, v81
	v_and_b32_e32 v81, 0xff00, v81
	v_and_b32_e32 v3, 0xff0000, v3
	v_perm_b32 v6, v7, v6, s92
	v_or3_b32 v3, v6, v81, v3
	ds_write_b32 v18, v3 offset:144
	ds_read_b64 v[6:7], v19
	v_or_b32_e32 v81, 0x6000, v148
	v_or_b32_e32 v96, 0x6000, v146
	s_waitcnt lgkmcnt(0)
	v_pk_add_f32 v[72:73], v[72:73], v[6:7] op_sel_hi:[1,0] neg_lo:[0,1] neg_hi:[0,1]
	s_nop 0
	v_pk_mul_f32 v[72:73], v[6:7], v[72:73] op_sel:[1,0]
	s_nop 0
	v_pk_fma_f32 v[84:85], v[88:89], v[72:73], v[90:91]
	v_pk_add_f32 v[72:73], v[74:75], v[6:7] op_sel_hi:[1,0] neg_lo:[0,1] neg_hi:[0,1]
	v_and_b32_sdwa v3, v85, v216 dst_sel:DWORD dst_unused:UNUSED_PAD src0_sel:WORD_1 src1_sel:DWORD
	v_pk_mul_f32 v[6:7], v[6:7], v[72:73] op_sel:[1,0]
	v_add3_u32 v3, v85, v3, s84
	v_pk_fma_f32 v[0:1], v[0:1], v[6:7], v[4:5]
	v_and_b32_sdwa v4, v84, v216 dst_sel:DWORD dst_unused:UNUSED_PAD src0_sel:WORD_1 src1_sel:DWORD
	v_add3_u32 v4, v84, v4, s84
	v_and_b32_e32 v6, 0xffff0000, v4
	v_and_b32_sdwa v4, v1, v216 dst_sel:DWORD dst_unused:UNUSED_PAD src0_sel:WORD_1 src1_sel:DWORD
	v_and_b32_sdwa v5, v0, v216 dst_sel:DWORD dst_unused:UNUSED_PAD src0_sel:WORD_1 src1_sel:DWORD
	v_add3_u32 v4, v1, v4, s84
	v_add3_u32 v7, v0, v5, s84
	v_and_b32_e32 v72, 0xffff0000, v4
	v_add_u32_e32 v73, v2, v136
	v_and_b32_e32 v2, 0xffff0000, v7
	v_or_b32_sdwa v5, v72, v3 dst_sel:DWORD dst_unused:UNUSED_PAD src0_sel:DWORD src1_sel:WORD_1
	v_sub_u32_e32 v0, v0, v2
	v_sub_u32_e32 v2, v84, v6
	v_and_b32_e32 v3, 0xffff0000, v3
	v_add_u32_e32 v2, 0x80, v2
	v_sub_u32_e32 v3, v85, v3
	v_sub_u32_e32 v1, v1, v72
	v_add_u32_e32 v0, 0x80, v0
	v_ashrrev_i32_e32 v2, 8, v2
	v_add_u32_e32 v3, 0x80, v3
	v_add_u32_e32 v1, 0x80, v1
	v_ashrrev_i32_e32 v0, 8, v0
	v_min_i32_e32 v2, 0x7f, v2
	v_ashrrev_i32_e32 v3, 8, v3
	v_ashrrev_i32_e32 v1, 8, v1
	v_min_i32_e32 v0, 0x7f, v0
	v_min_i32_sdwa v3, v3, s85 dst_sel:WORD_1 dst_unused:UNUSED_PAD src0_sel:DWORD src1_sel:DWORD
	v_min_i32_e32 v1, 0x7f, v1
	v_lshlrev_b32_e32 v2, 8, v2
	v_and_b32_e32 v2, 0xff00, v2
	v_and_b32_e32 v3, 0xff0000, v3
	v_perm_b32 v0, v1, v0, s92
	v_or_b32_sdwa v4, v7, v6 dst_sel:DWORD dst_unused:UNUSED_PAD src0_sel:WORD_1 src1_sel:DWORD
	v_or3_b32 v0, v0, v2, v3
	ds_write_b64 v73, v[4:5]
	ds_write_b32 v22, v0 offset:144
	v_add_u32_e32 v72, s2, v151
	s_waitcnt lgkmcnt(0)
	s_barrier
	ds_read_b128 v[128:131], v72
	v_or_b32_e32 v74, 0x2000, v148
	v_or_b32_e32 v75, 0x4000, v148
	v_or_b32_e32 v84, 0x8000, v148
	v_or_b32_e32 v85, 0xa000, v148
	ds_read_b128 v[136:139], v72 offset:1040
	v_or_b32_e32 v88, 0xc000, v148
	v_or_b32_e32 v89, 0xe000, v148
	v_or_b32_e32 v90, 0x2000, v146
	v_or_b32_e32 v91, 0x4000, v146
	ds_read_b128 v[140:143], v72 offset:2080
	ds_read_b128 v[152:155], v72 offset:3120
	ds_read_b128 v[156:159], v72 offset:4160
	ds_read_b128 v[160:163], v72 offset:5200
	ds_read_b128 v[164:167], v72 offset:6240
	ds_read_b128 v[168:171], v72 offset:7280
	ds_read_b128 v[172:175], v147
	ds_read_b128 v[176:179], v147 offset:1040
	ds_read_b128 v[180:183], v147 offset:2080
	ds_read_b128 v[184:187], v147 offset:3120
	s_waitcnt lgkmcnt(0)
	s_barrier
;     ...
;             _Pragma("unroll") for (int m = 0; m < 4; ++m) {
;               const int rr = wr3 * 64 + m * 16 + fr3;
;               const float2 ms = *reinterpret_cast<const float2*>(mr + (ai * HALF + rr) * 2);
;               f32x4 y = acc[ai][bj][m][n];
;               const float o0 = (y[0] - ms.x) * ms.y * gm.x + bt.x, o1 = (y[1] - ms.x) * ms.y * gm.y + bt.y;
;               const float o2 = (y[2] - ms.x) * ms.y * gm.z + bt.z, o3 = (y[3] - ms.x) * ms.y * gm.w + bt.w;
;               const unsigned h0 = f2bf(o0), h1 = f2bf(o1), h2 = f2bf(o2), h3 = f2bf(o3);
;               u32x2 ob; ob[0] = h0 | (h1 << 16); ob[1] = h2 | (h3 << 16);
;               *reinterpret_cast<u32x2*>(smem + (rr >> 1) * PIECE + (rr & 1) * 512 + cc * 2) = ob;
;               const int l0 = min(((int)__float_as_uint(o0) - (int)(h0 << 16) + 128) >> 8, 127);
;               const int l1 = min(((int)__float_as_uint(o1) - (int)(h1 << 16) + 128) >> 8, 127);
;               const int l2 = min(((int)__float_as_uint(o2) - (int)(h2 << 16) + 128) >> 8, 127);
;               const int l3 = min(((int)__float_as_uint(o3) - (int)(h3 << 16) + 128) >> 8, 127);
;               *reinterpret_cast<unsigned*>(smem + LOBASE + (rr >> 2) * PIECE + (rr & 3) * 256 + cc) =
;                   (unsigned)(l0 & 255) | ((unsigned)(l1 & 255) << 8) | ((unsigned)(l2 & 255) << 16) | ((unsigned)l3 << 24);
;             }
;     ...
;           _Pragma("unroll") for (int i = 0; i < 8; ++i) {
;             const u32x4 v = *reinterpret_cast<const u32x4*>(smem + (wave * 8 + i) * PIECE + lane3 * 16);
;             __builtin_amdgcn_raw_buffer_store_b128(v, rsXB, hvo + i * (2 * DM * 2), hso, 0);
;           }
;           _Pragma("unroll") for (int i = 0; i < 4; ++i) {
;             const u32x4 v = *reinterpret_cast<const u32x4*>(smem + LOBASE + (wave * 4 + i) * PIECE + lane3 * 16);
;             __builtin_amdgcn_raw_buffer_store_b128(v, rsLO, lvo + i * (4 * DM), lso, 0);
;           }
	s_nop 1
	v_mov_b32_e32 v0, v220
	v_mov_b32_e32 v1, v221
	v_mov_b32_e32 v2, v222
	v_mov_b32_e32 v3, v223
	v_mov_b32_e32 v4, v236
	v_mov_b32_e32 v5, v237
	v_mov_b32_e32 v6, v238
	v_mov_b32_e32 v7, v239
	ds_read_b64 v[110:111], v149 offset:1024
	s_waitcnt lgkmcnt(0)
	v_pk_add_f32 v[64:65], v[64:65], v[110:111] op_sel_hi:[1,0] neg_lo:[0,1] neg_hi:[0,1]
	s_nop 0
	v_pk_mul_f32 v[64:65], v[110:111], v[64:65] op_sel:[1,0]
	v_pk_add_f32 v[66:67], v[66:67], v[110:111] op_sel_hi:[1,0] neg_lo:[0,1] neg_hi:[0,1]
	v_mov_b32_e32 v100, v1
	v_mov_b32_e32 v101, v2
	v_mov_b32_e32 v104, v5
	v_mov_b32_e32 v105, v6
	v_pk_fma_f32 v[64:65], v[100:101], v[64:65], v[104:105]
	v_pk_mul_f32 v[66:67], v[110:111], v[66:67] op_sel:[1,0]
	v_mov_b32_e32 v1, v3
	v_mov_b32_e32 v5, v7
	v_and_b32_sdwa v6, v65, v216 dst_sel:DWORD dst_unused:UNUSED_PAD src0_sel:WORD_1 src1_sel:DWORD
	v_and_b32_sdwa v7, v64, v216 dst_sel:DWORD dst_unused:UNUSED_PAD src0_sel:WORD_1 src1_sel:DWORD
	v_pk_fma_f32 v[2:3], v[0:1], v[66:67], v[4:5]
	v_add3_u32 v66, v65, v6, s84
	v_add3_u32 v6, v64, v7, s84
	v_and_b32_e32 v67, 0xffff0000, v6
	v_and_b32_sdwa v6, v3, v216 dst_sel:DWORD dst_unused:UNUSED_PAD src0_sel:WORD_1 src1_sel:DWORD
	v_and_b32_sdwa v7, v2, v216 dst_sel:DWORD dst_unused:UNUSED_PAD src0_sel:WORD_1 src1_sel:DWORD
	v_add3_u32 v6, v3, v6, s84
	v_add3_u32 v97, v2, v7, s84
	v_and_b32_e32 v103, 0xffff0000, v6
	v_or_b32_sdwa v7, v103, v66 dst_sel:DWORD dst_unused:UNUSED_PAD src0_sel:DWORD src1_sel:WORD_1
	v_or_b32_sdwa v6, v97, v67 dst_sel:DWORD dst_unused:UNUSED_PAD src0_sel:WORD_1 src1_sel:DWORD
	ds_write_b64 v132, v[6:7]
	v_and_b32_e32 v6, 0xffff0000, v97
	v_sub_u32_e32 v2, v2, v6
	v_sub_u32_e32 v6, v64, v67
	v_and_b32_e32 v7, 0xffff0000, v66
	v_add_u32_e32 v6, 0x80, v6
	v_sub_u32_e32 v7, v65, v7
	v_sub_u32_e32 v3, v3, v103
	v_add_u32_e32 v2, 0x80, v2
	v_ashrrev_i32_e32 v6, 8, v6
	v_add_u32_e32 v7, 0x80, v7
	v_add_u32_e32 v3, 0x80, v3
	v_ashrrev_i32_e32 v2, 8, v2
	v_min_i32_e32 v6, 0x7f, v6
	v_ashrrev_i32_e32 v7, 8, v7
	v_ashrrev_i32_e32 v3, 8, v3
	v_min_i32_e32 v2, 0x7f, v2
	v_min_i32_sdwa v7, v7, s85 dst_sel:WORD_1 dst_unused:UNUSED_PAD src0_sel:DWORD src1_sel:DWORD
	v_min_i32_e32 v3, 0x7f, v3
	v_lshlrev_b32_e32 v6, 8, v6
	v_and_b32_e32 v6, 0xff00, v6
	v_and_b32_e32 v7, 0xff0000, v7
	v_perm_b32 v2, v3, v2, s92
	v_or3_b32 v2, v2, v6, v7
	ds_write_b32 v12, v2
	buffer_store_dwordx4 v[128:131], v148, s[16:19], s41 offen
	ds_read_b64 v[2:3], v13 offset:1024
	s_waitcnt lgkmcnt(0)
	v_pk_add_f32 v[6:7], v[68:69], v[2:3] op_sel_hi:[1,0] neg_lo:[0,1] neg_hi:[0,1]
	s_nop 0
	v_pk_mul_f32 v[6:7], v[2:3], v[6:7] op_sel:[1,0]
	v_pk_add_f32 v[64:65], v[70:71], v[2:3] op_sel_hi:[1,0] neg_lo:[0,1] neg_hi:[0,1]
	v_pk_fma_f32 v[6:7], v[100:101], v[6:7], v[104:105]
	v_pk_mul_f32 v[2:3], v[2:3], v[64:65] op_sel:[1,0]
	v_and_b32_sdwa v64, v7, v216 dst_sel:DWORD dst_unused:UNUSED_PAD src0_sel:WORD_1 src1_sel:DWORD
	v_and_b32_sdwa v65, v6, v216 dst_sel:DWORD dst_unused:UNUSED_PAD src0_sel:WORD_1 src1_sel:DWORD
	v_pk_fma_f32 v[2:3], v[0:1], v[2:3], v[4:5]
	v_add3_u32 v66, v7, v64, s84
	v_add3_u32 v64, v6, v65, s84
	v_and_b32_e32 v67, 0xffff0000, v64
	v_and_b32_sdwa v64, v3, v216 dst_sel:DWORD dst_unused:UNUSED_PAD src0_sel:WORD_1 src1_sel:DWORD
	v_and_b32_sdwa v65, v2, v216 dst_sel:DWORD dst_unused:UNUSED_PAD src0_sel:WORD_1 src1_sel:DWORD
	v_add3_u32 v64, v3, v64, s84
	v_add3_u32 v68, v2, v65, s84
	v_and_b32_e32 v69, 0xffff0000, v64
	v_or_b32_sdwa v65, v69, v66 dst_sel:DWORD dst_unused:UNUSED_PAD src0_sel:DWORD src1_sel:WORD_1
	v_or_b32_sdwa v64, v68, v67 dst_sel:DWORD dst_unused:UNUSED_PAD src0_sel:WORD_1 src1_sel:DWORD
	ds_write_b64 v133, v[64:65]
	v_and_b32_e32 v64, 0xffff0000, v68
	v_sub_u32_e32 v2, v2, v64
	v_sub_u32_e32 v6, v6, v67
	v_and_b32_e32 v64, 0xffff0000, v66
	v_add_u32_e32 v6, 0x80, v6
	v_sub_u32_e32 v7, v7, v64
	v_sub_u32_e32 v3, v3, v69
	v_add_u32_e32 v2, 0x80, v2
	v_ashrrev_i32_e32 v6, 8, v6
	v_add_u32_e32 v7, 0x80, v7
	v_add_u32_e32 v3, 0x80, v3
	v_ashrrev_i32_e32 v2, 8, v2
	v_min_i32_e32 v6, 0x7f, v6
	v_ashrrev_i32_e32 v7, 8, v7
	v_ashrrev_i32_e32 v3, 8, v3
	v_min_i32_e32 v2, 0x7f, v2
	v_min_i32_sdwa v7, v7, s85 dst_sel:WORD_1 dst_unused:UNUSED_PAD src0_sel:DWORD src1_sel:DWORD
	v_min_i32_e32 v3, 0x7f, v3
	v_lshlrev_b32_e32 v6, 8, v6
	v_and_b32_e32 v6, 0xff00, v6
	v_and_b32_e32 v7, 0xff0000, v7
	v_perm_b32 v2, v3, v2, s92
	v_or3_b32 v2, v2, v6, v7
	ds_write_b32 v14, v2
	buffer_store_dwordx4 v[136:139], v74, s[16:19], s41 offen
	ds_read_b64 v[2:3], v15 offset:1024
	s_waitcnt lgkmcnt(0)
	v_pk_add_f32 v[6:7], v[76:77], v[2:3] op_sel_hi:[1,0] neg_lo:[0,1] neg_hi:[0,1]
	s_nop 0
	v_pk_mul_f32 v[6:7], v[2:3], v[6:7] op_sel:[1,0]
	v_pk_add_f32 v[64:65], v[78:79], v[2:3] op_sel_hi:[1,0] neg_lo:[0,1] neg_hi:[0,1]
	v_pk_fma_f32 v[6:7], v[100:101], v[6:7], v[104:105]
	v_pk_mul_f32 v[2:3], v[2:3], v[64:65] op_sel:[1,0]
	v_and_b32_sdwa v64, v7, v216 dst_sel:DWORD dst_unused:UNUSED_PAD src0_sel:WORD_1 src1_sel:DWORD
	v_and_b32_sdwa v65, v6, v216 dst_sel:DWORD dst_unused:UNUSED_PAD src0_sel:WORD_1 src1_sel:DWORD
	v_pk_fma_f32 v[2:3], v[0:1], v[2:3], v[4:5]
	v_add3_u32 v66, v7, v64, s84
	v_add3_u32 v64, v6, v65, s84
	v_and_b32_e32 v67, 0xffff0000, v64
	v_and_b32_sdwa v64, v3, v216 dst_sel:DWORD dst_unused:UNUSED_PAD src0_sel:WORD_1 src1_sel:DWORD
	v_and_b32_sdwa v65, v2, v216 dst_sel:DWORD dst_unused:UNUSED_PAD src0_sel:WORD_1 src1_sel:DWORD
	v_add3_u32 v64, v3, v64, s84
	v_add3_u32 v68, v2, v65, s84
	v_and_b32_e32 v69, 0xffff0000, v64
	v_or_b32_sdwa v65, v69, v66 dst_sel:DWORD dst_unused:UNUSED_PAD src0_sel:DWORD src1_sel:WORD_1
	v_or_b32_sdwa v64, v68, v67 dst_sel:DWORD dst_unused:UNUSED_PAD src0_sel:WORD_1 src1_sel:DWORD
	ds_write_b64 v134, v[64:65]
	v_and_b32_e32 v64, 0xffff0000, v68
	v_sub_u32_e32 v2, v2, v64
	v_sub_u32_e32 v6, v6, v67
	v_and_b32_e32 v64, 0xffff0000, v66
	v_add_u32_e32 v6, 0x80, v6
	v_sub_u32_e32 v7, v7, v64
	v_sub_u32_e32 v3, v3, v69
	v_add_u32_e32 v2, 0x80, v2
	v_ashrrev_i32_e32 v6, 8, v6
	v_add_u32_e32 v7, 0x80, v7
	v_add_u32_e32 v3, 0x80, v3
	v_ashrrev_i32_e32 v2, 8, v2
	v_min_i32_e32 v6, 0x7f, v6
	v_ashrrev_i32_e32 v7, 8, v7
	v_ashrrev_i32_e32 v3, 8, v3
	v_min_i32_e32 v2, 0x7f, v2
	v_min_i32_sdwa v7, v7, s85 dst_sel:WORD_1 dst_unused:UNUSED_PAD src0_sel:DWORD src1_sel:DWORD
	v_min_i32_e32 v3, 0x7f, v3
	v_lshlrev_b32_e32 v6, 8, v6
	v_and_b32_e32 v6, 0xff00, v6
	v_and_b32_e32 v7, 0xff0000, v7
	v_perm_b32 v2, v3, v2, s92
	v_or3_b32 v2, v2, v6, v7
	ds_write_b32 v18, v2
	buffer_store_dwordx4 v[140:143], v75, s[16:19], s41 offen
	ds_read_b64 v[2:3], v19 offset:1024
	s_waitcnt lgkmcnt(0)
;     ...
;             _Pragma("unroll") for (int m = 0; m < 4; ++m) {
;               const int rr = wr3 * 64 + m * 16 + fr3;
;               const float2 ms = *reinterpret_cast<const float2*>(mr + (ai * HALF + rr) * 2);
;               f32x4 y = acc[ai][bj][m][n];
;               const float o0 = (y[0] - ms.x) * ms.y * gm.x + bt.x, o1 = (y[1] - ms.x) * ms.y * gm.y + bt.y;
;               const float o2 = (y[2] - ms.x) * ms.y * gm.z + bt.z, o3 = (y[3] - ms.x) * ms.y * gm.w + bt.w;
;               const unsigned h0 = f2bf(o0), h1 = f2bf(o1), h2 = f2bf(o2), h3 = f2bf(o3);
;               u32x2 ob; ob[0] = h0 | (h1 << 16); ob[1] = h2 | (h3 << 16);
;               *reinterpret_cast<u32x2*>(smem + (rr >> 1) * PIECE + (rr & 1) * 512 + cc * 2) = ob;
;               const int l0 = min(((int)__float_as_uint(o0) - (int)(h0 << 16) + 128) >> 8, 127);
;               const int l1 = min(((int)__float_as_uint(o1) - (int)(h1 << 16) + 128) >> 8, 127);
;               const int l2 = min(((int)__float_as_uint(o2) - (int)(h2 << 16) + 128) >> 8, 127);
;               const int l3 = min(((int)__float_as_uint(o3) - (int)(h3 << 16) + 128) >> 8, 127);
;               *reinterpret_cast<unsigned*>(smem + LOBASE + (rr >> 2) * PIECE + (rr & 3) * 256 + cc) =
;                   (unsigned)(l0 & 255) | ((unsigned)(l1 & 255) << 8) | ((unsigned)(l2 & 255) << 16) | ((unsigned)l3 << 24);
;             }
;     ...
;           _Pragma("unroll") for (int i = 0; i < 8; ++i) {
;             const u32x4 v = *reinterpret_cast<const u32x4*>(smem + (wave * 8 + i) * PIECE + lane3 * 16);
;             __builtin_amdgcn_raw_buffer_store_b128(v, rsXB, hvo + i * (2 * DM * 2), hso, 0);
;           }
;           _Pragma("unroll") for (int i = 0; i < 4; ++i) {
;             const u32x4 v = *reinterpret_cast<const u32x4*>(smem + LOBASE + (wave * 4 + i) * PIECE + lane3 * 16);
;             __builtin_amdgcn_raw_buffer_store_b128(v, rsLO, lvo + i * (4 * DM), lso, 0);
;           }
	v_pk_add_f32 v[6:7], v[82:83], v[2:3] op_sel_hi:[1,0] neg_lo:[0,1] neg_hi:[0,1]
	s_nop 0
	v_pk_mul_f32 v[6:7], v[2:3], v[6:7] op_sel:[1,0]
	v_pk_add_f32 v[64:65], v[86:87], v[2:3] op_sel_hi:[1,0] neg_lo:[0,1] neg_hi:[0,1]
	v_pk_fma_f32 v[6:7], v[100:101], v[6:7], v[104:105]
	v_pk_mul_f32 v[2:3], v[2:3], v[64:65] op_sel:[1,0]
	s_nop 0
	v_pk_fma_f32 v[0:1], v[0:1], v[2:3], v[4:5]
	v_and_b32_sdwa v2, v7, v216 dst_sel:DWORD dst_unused:UNUSED_PAD src0_sel:WORD_1 src1_sel:DWORD
	v_and_b32_sdwa v3, v6, v216 dst_sel:DWORD dst_unused:UNUSED_PAD src0_sel:WORD_1 src1_sel:DWORD
	v_add3_u32 v4, v7, v2, s84
	v_add3_u32 v2, v6, v3, s84
	v_and_b32_e32 v5, 0xffff0000, v2
	v_and_b32_sdwa v2, v1, v216 dst_sel:DWORD dst_unused:UNUSED_PAD src0_sel:WORD_1 src1_sel:DWORD
	v_and_b32_sdwa v3, v0, v216 dst_sel:DWORD dst_unused:UNUSED_PAD src0_sel:WORD_1 src1_sel:DWORD
	v_add3_u32 v2, v1, v2, s84
	v_add3_u32 v64, v0, v3, s84
	v_and_b32_e32 v65, 0xffff0000, v2
	v_or_b32_sdwa v3, v65, v4 dst_sel:DWORD dst_unused:UNUSED_PAD src0_sel:DWORD src1_sel:WORD_1
	v_or_b32_sdwa v2, v64, v5 dst_sel:DWORD dst_unused:UNUSED_PAD src0_sel:WORD_1 src1_sel:DWORD
	ds_write_b64 v135, v[2:3]
	v_and_b32_e32 v2, 0xffff0000, v64
	v_sub_u32_e32 v0, v0, v2
	v_sub_u32_e32 v2, v6, v5
	v_and_b32_e32 v3, 0xffff0000, v4
	v_add_u32_e32 v2, 0x80, v2
	v_sub_u32_e32 v3, v7, v3
	v_sub_u32_e32 v1, v1, v65
	v_add_u32_e32 v0, 0x80, v0
	v_ashrrev_i32_e32 v2, 8, v2
	v_add_u32_e32 v3, 0x80, v3
	v_add_u32_e32 v1, 0x80, v1
	v_ashrrev_i32_e32 v0, 8, v0
	v_min_i32_e32 v2, 0x7f, v2
	v_ashrrev_i32_e32 v3, 8, v3
	v_ashrrev_i32_e32 v1, 8, v1
	v_min_i32_e32 v0, 0x7f, v0
	v_min_i32_sdwa v3, v3, s85 dst_sel:WORD_1 dst_unused:UNUSED_PAD src0_sel:DWORD src1_sel:DWORD
	v_min_i32_e32 v1, 0x7f, v1
	v_lshlrev_b32_e32 v2, 8, v2
	v_and_b32_e32 v2, 0xff00, v2
	v_and_b32_e32 v3, 0xff0000, v3
	v_perm_b32 v0, v1, v0, s92
	v_or3_b32 v0, v0, v2, v3
	ds_write_b32 v22, v0
	buffer_store_dwordx4 v[152:155], v81, s[16:19], s41 offen
	v_mov_b32_e32 v0, v224
	v_mov_b32_e32 v1, v225
	v_mov_b32_e32 v2, v226
	v_mov_b32_e32 v3, v227
	v_mov_b32_e32 v4, v240
	v_mov_b32_e32 v5, v241
	v_mov_b32_e32 v6, v242
	v_mov_b32_e32 v7, v243
	ds_read_b64 v[68:69], v149 offset:1024
	s_waitcnt lgkmcnt(0)
	v_pk_add_f32 v[60:61], v[60:61], v[68:69] op_sel_hi:[1,0] neg_lo:[0,1] neg_hi:[0,1]
	s_nop 0
	v_pk_mul_f32 v[60:61], v[68:69], v[60:61] op_sel:[1,0]
	v_pk_add_f32 v[58:59], v[58:59], v[68:69] op_sel_hi:[1,0] neg_lo:[0,1] neg_hi:[0,1]
	v_mov_b32_e32 v64, v1
	v_mov_b32_e32 v65, v2
	v_mov_b32_e32 v66, v5
	v_mov_b32_e32 v67, v6
	v_pk_fma_f32 v[60:61], v[64:65], v[60:61], v[66:67]
	v_pk_mul_f32 v[58:59], v[68:69], v[58:59] op_sel:[1,0]
	v_mov_b32_e32 v1, v3
	v_mov_b32_e32 v5, v7
	v_and_b32_sdwa v6, v61, v216 dst_sel:DWORD dst_unused:UNUSED_PAD src0_sel:WORD_1 src1_sel:DWORD
	v_and_b32_sdwa v7, v60, v216 dst_sel:DWORD dst_unused:UNUSED_PAD src0_sel:WORD_1 src1_sel:DWORD
	v_pk_fma_f32 v[2:3], v[0:1], v[58:59], v[4:5]
	v_add3_u32 v58, v61, v6, s84
	v_add3_u32 v6, v60, v7, s84
	v_and_b32_e32 v59, 0xffff0000, v6
	v_and_b32_sdwa v6, v3, v216 dst_sel:DWORD dst_unused:UNUSED_PAD src0_sel:WORD_1 src1_sel:DWORD
	v_and_b32_sdwa v7, v2, v216 dst_sel:DWORD dst_unused:UNUSED_PAD src0_sel:WORD_1 src1_sel:DWORD
	v_add3_u32 v6, v3, v6, s84
	v_add3_u32 v68, v2, v7, s84
	v_and_b32_e32 v69, 0xffff0000, v6
	v_or_b32_sdwa v7, v69, v58 dst_sel:DWORD dst_unused:UNUSED_PAD src0_sel:DWORD src1_sel:WORD_1
	v_or_b32_sdwa v6, v68, v59 dst_sel:DWORD dst_unused:UNUSED_PAD src0_sel:WORD_1 src1_sel:DWORD
	ds_write_b64 v23, v[6:7]
	v_and_b32_e32 v6, 0xffff0000, v68
	v_sub_u32_e32 v2, v2, v6
	v_sub_u32_e32 v6, v60, v59
	v_and_b32_e32 v7, 0xffff0000, v58
	v_add_u32_e32 v6, 0x80, v6
	v_sub_u32_e32 v7, v61, v7
	v_sub_u32_e32 v3, v3, v69
	v_add_u32_e32 v2, 0x80, v2
	v_ashrrev_i32_e32 v6, 8, v6
	v_add_u32_e32 v7, 0x80, v7
	v_add_u32_e32 v3, 0x80, v3
	v_ashrrev_i32_e32 v2, 8, v2
	v_min_i32_e32 v6, 0x7f, v6
	v_ashrrev_i32_e32 v7, 8, v7
	v_ashrrev_i32_e32 v3, 8, v3
	v_min_i32_e32 v2, 0x7f, v2
	v_min_i32_sdwa v7, v7, s85 dst_sel:WORD_1 dst_unused:UNUSED_PAD src0_sel:DWORD src1_sel:DWORD
	v_min_i32_e32 v3, 0x7f, v3
	v_lshlrev_b32_e32 v6, 8, v6
	v_and_b32_e32 v6, 0xff00, v6
	v_and_b32_e32 v7, 0xff0000, v7
	v_perm_b32 v2, v3, v2, s92
	v_or3_b32 v2, v2, v6, v7
	ds_write_b32 v12, v2 offset:16
	buffer_store_dwordx4 v[156:159], v84, s[16:19], s41 offen
	ds_read_b64 v[2:3], v13 offset:1024
	s_waitcnt lgkmcnt(0)
	v_pk_add_f32 v[6:7], v[44:45], v[2:3] op_sel_hi:[1,0] neg_lo:[0,1] neg_hi:[0,1]
	s_nop 0
	v_pk_mul_f32 v[6:7], v[2:3], v[6:7] op_sel:[1,0]
	v_pk_add_f32 v[42:43], v[42:43], v[2:3] op_sel_hi:[1,0] neg_lo:[0,1] neg_hi:[0,1]
	v_pk_fma_f32 v[6:7], v[64:65], v[6:7], v[66:67]
	v_pk_mul_f32 v[2:3], v[2:3], v[42:43] op_sel:[1,0]
	v_and_b32_sdwa v42, v6, v216 dst_sel:DWORD dst_unused:UNUSED_PAD src0_sel:WORD_1 src1_sel:DWORD
	v_pk_fma_f32 v[2:3], v[0:1], v[2:3], v[4:5]
	v_add3_u32 v42, v6, v42, s84
	v_and_b32_e32 v44, 0xffff0000, v42
	v_and_b32_sdwa v42, v3, v216 dst_sel:DWORD dst_unused:UNUSED_PAD src0_sel:WORD_1 src1_sel:DWORD
	v_and_b32_sdwa v23, v7, v216 dst_sel:DWORD dst_unused:UNUSED_PAD src0_sel:WORD_1 src1_sel:DWORD
	v_and_b32_sdwa v43, v2, v216 dst_sel:DWORD dst_unused:UNUSED_PAD src0_sel:WORD_1 src1_sel:DWORD
	v_add3_u32 v42, v3, v42, s84
	v_add3_u32 v23, v7, v23, s84
	v_add3_u32 v45, v2, v43, s84
	v_and_b32_e32 v58, 0xffff0000, v42
	v_or_b32_sdwa v43, v58, v23 dst_sel:DWORD dst_unused:UNUSED_PAD src0_sel:DWORD src1_sel:WORD_1
	v_or_b32_sdwa v42, v45, v44 dst_sel:DWORD dst_unused:UNUSED_PAD src0_sel:WORD_1 src1_sel:DWORD
	ds_write_b64 v108, v[42:43]
	v_and_b32_e32 v42, 0xffff0000, v45
	v_sub_u32_e32 v6, v6, v44
	v_and_b32_e32 v23, 0xffff0000, v23
	v_sub_u32_e32 v2, v2, v42
	v_add_u32_e32 v6, 0x80, v6
	v_sub_u32_e32 v7, v7, v23
	v_sub_u32_e32 v3, v3, v58
	v_add_u32_e32 v2, 0x80, v2
	v_ashrrev_i32_e32 v6, 8, v6
	v_add_u32_e32 v7, 0x80, v7
	v_add_u32_e32 v3, 0x80, v3
	v_ashrrev_i32_e32 v2, 8, v2
	v_min_i32_e32 v6, 0x7f, v6
	v_ashrrev_i32_e32 v7, 8, v7
	v_ashrrev_i32_e32 v3, 8, v3
	v_min_i32_e32 v2, 0x7f, v2
	v_min_i32_sdwa v7, v7, s85 dst_sel:WORD_1 dst_unused:UNUSED_PAD src0_sel:DWORD src1_sel:DWORD
	v_min_i32_e32 v3, 0x7f, v3
	v_lshlrev_b32_e32 v6, 8, v6
	v_and_b32_e32 v6, 0xff00, v6
	v_and_b32_e32 v7, 0xff0000, v7
	v_perm_b32 v2, v3, v2, s92
	v_or3_b32 v2, v2, v6, v7
	ds_write_b32 v14, v2 offset:16
	buffer_store_dwordx4 v[160:163], v85, s[16:19], s41 offen
	ds_read_b64 v[2:3], v15 offset:1024
	s_waitcnt lgkmcnt(0)
;     ...
;             _Pragma("unroll") for (int m = 0; m < 4; ++m) {
;               const int rr = wr3 * 64 + m * 16 + fr3;
;               const float2 ms = *reinterpret_cast<const float2*>(mr + (ai * HALF + rr) * 2);
;               f32x4 y = acc[ai][bj][m][n];
;               const float o0 = (y[0] - ms.x) * ms.y * gm.x + bt.x, o1 = (y[1] - ms.x) * ms.y * gm.y + bt.y;
;               const float o2 = (y[2] - ms.x) * ms.y * gm.z + bt.z, o3 = (y[3] - ms.x) * ms.y * gm.w + bt.w;
;               const unsigned h0 = f2bf(o0), h1 = f2bf(o1), h2 = f2bf(o2), h3 = f2bf(o3);
;               u32x2 ob; ob[0] = h0 | (h1 << 16); ob[1] = h2 | (h3 << 16);
;               *reinterpret_cast<u32x2*>(smem + (rr >> 1) * PIECE + (rr & 1) * 512 + cc * 2) = ob;
;               const int l0 = min(((int)__float_as_uint(o0) - (int)(h0 << 16) + 128) >> 8, 127);
;               const int l1 = min(((int)__float_as_uint(o1) - (int)(h1 << 16) + 128) >> 8, 127);
;               const int l2 = min(((int)__float_as_uint(o2) - (int)(h2 << 16) + 128) >> 8, 127);
;               const int l3 = min(((int)__float_as_uint(o3) - (int)(h3 << 16) + 128) >> 8, 127);
;               *reinterpret_cast<unsigned*>(smem + LOBASE + (rr >> 2) * PIECE + (rr & 3) * 256 + cc) =
;                   (unsigned)(l0 & 255) | ((unsigned)(l1 & 255) << 8) | ((unsigned)(l2 & 255) << 16) | ((unsigned)l3 << 24);
;             }
;     ...
;           _Pragma("unroll") for (int i = 0; i < 8; ++i) {
;             const u32x4 v = *reinterpret_cast<const u32x4*>(smem + (wave * 8 + i) * PIECE + lane3 * 16);
;             __builtin_amdgcn_raw_buffer_store_b128(v, rsXB, hvo + i * (2 * DM * 2), hso, 0);
;           }
;           _Pragma("unroll") for (int i = 0; i < 4; ++i) {
;             const u32x4 v = *reinterpret_cast<const u32x4*>(smem + LOBASE + (wave * 4 + i) * PIECE + lane3 * 16);
;             __builtin_amdgcn_raw_buffer_store_b128(v, rsLO, lvo + i * (4 * DM), lso, 0);
;           }
	v_pk_add_f32 v[6:7], v[34:35], v[2:3] op_sel_hi:[1,0] neg_lo:[0,1] neg_hi:[0,1]
	s_nop 0
	v_pk_mul_f32 v[6:7], v[2:3], v[6:7] op_sel:[1,0]
	v_pk_add_f32 v[34:35], v[46:47], v[2:3] op_sel_hi:[1,0] neg_lo:[0,1] neg_hi:[0,1]
	v_pk_fma_f32 v[6:7], v[64:65], v[6:7], v[66:67]
	v_pk_mul_f32 v[2:3], v[2:3], v[34:35] op_sel:[1,0]
	v_and_b32_sdwa v34, v6, v216 dst_sel:DWORD dst_unused:UNUSED_PAD src0_sel:WORD_1 src1_sel:DWORD
	v_pk_fma_f32 v[2:3], v[0:1], v[2:3], v[4:5]
	v_add3_u32 v34, v6, v34, s84
	v_and_b32_e32 v42, 0xffff0000, v34
	v_and_b32_sdwa v34, v3, v216 dst_sel:DWORD dst_unused:UNUSED_PAD src0_sel:WORD_1 src1_sel:DWORD
	v_and_b32_sdwa v23, v7, v216 dst_sel:DWORD dst_unused:UNUSED_PAD src0_sel:WORD_1 src1_sel:DWORD
	v_and_b32_sdwa v35, v2, v216 dst_sel:DWORD dst_unused:UNUSED_PAD src0_sel:WORD_1 src1_sel:DWORD
	v_add3_u32 v34, v3, v34, s84
	v_add3_u32 v23, v7, v23, s84
	v_add3_u32 v43, v2, v35, s84
	v_and_b32_e32 v44, 0xffff0000, v34
	v_or_b32_sdwa v35, v44, v23 dst_sel:DWORD dst_unused:UNUSED_PAD src0_sel:DWORD src1_sel:WORD_1
	v_or_b32_sdwa v34, v43, v42 dst_sel:DWORD dst_unused:UNUSED_PAD src0_sel:WORD_1 src1_sel:DWORD
	ds_write_b64 v98, v[34:35]
	v_and_b32_e32 v34, 0xffff0000, v43
	v_sub_u32_e32 v6, v6, v42
	v_and_b32_e32 v23, 0xffff0000, v23
	v_sub_u32_e32 v2, v2, v34
	v_add_u32_e32 v6, 0x80, v6
	v_sub_u32_e32 v7, v7, v23
	v_sub_u32_e32 v3, v3, v44
	v_add_u32_e32 v2, 0x80, v2
	v_ashrrev_i32_e32 v6, 8, v6
	v_add_u32_e32 v7, 0x80, v7
	v_add_u32_e32 v3, 0x80, v3
	v_ashrrev_i32_e32 v2, 8, v2
	v_min_i32_e32 v6, 0x7f, v6
	v_ashrrev_i32_e32 v7, 8, v7
	v_ashrrev_i32_e32 v3, 8, v3
	v_min_i32_e32 v2, 0x7f, v2
	v_min_i32_sdwa v7, v7, s85 dst_sel:WORD_1 dst_unused:UNUSED_PAD src0_sel:DWORD src1_sel:DWORD
	v_min_i32_e32 v3, 0x7f, v3
	v_lshlrev_b32_e32 v6, 8, v6
	v_and_b32_e32 v6, 0xff00, v6
	v_and_b32_e32 v7, 0xff0000, v7
	v_perm_b32 v2, v3, v2, s92
	v_or3_b32 v2, v2, v6, v7
	ds_write_b32 v18, v2 offset:16
	buffer_store_dwordx4 v[164:167], v88, s[16:19], s41 offen
	ds_read_b64 v[2:3], v19 offset:1024
	s_waitcnt lgkmcnt(0)
	v_pk_add_f32 v[6:7], v[50:51], v[2:3] op_sel_hi:[1,0] neg_lo:[0,1] neg_hi:[0,1]
	s_nop 0
	v_pk_mul_f32 v[6:7], v[2:3], v[6:7] op_sel:[1,0]
	v_pk_add_f32 v[34:35], v[62:63], v[2:3] op_sel_hi:[1,0] neg_lo:[0,1] neg_hi:[0,1]
	v_pk_fma_f32 v[6:7], v[64:65], v[6:7], v[66:67]
	v_pk_mul_f32 v[2:3], v[2:3], v[34:35] op_sel:[1,0]
	s_nop 0
	v_pk_fma_f32 v[0:1], v[0:1], v[2:3], v[4:5]
	v_and_b32_sdwa v2, v7, v216 dst_sel:DWORD dst_unused:UNUSED_PAD src0_sel:WORD_1 src1_sel:DWORD
	v_and_b32_sdwa v3, v6, v216 dst_sel:DWORD dst_unused:UNUSED_PAD src0_sel:WORD_1 src1_sel:DWORD
	v_add3_u32 v4, v7, v2, s84
	v_add3_u32 v2, v6, v3, s84
	v_and_b32_e32 v5, 0xffff0000, v2
	v_and_b32_sdwa v2, v1, v216 dst_sel:DWORD dst_unused:UNUSED_PAD src0_sel:WORD_1 src1_sel:DWORD
	v_and_b32_sdwa v3, v0, v216 dst_sel:DWORD dst_unused:UNUSED_PAD src0_sel:WORD_1 src1_sel:DWORD
	v_add3_u32 v2, v1, v2, s84
	v_add3_u32 v23, v0, v3, s84
	v_and_b32_e32 v34, 0xffff0000, v2
	v_or_b32_sdwa v3, v34, v4 dst_sel:DWORD dst_unused:UNUSED_PAD src0_sel:DWORD src1_sel:WORD_1
	v_or_b32_sdwa v2, v23, v5 dst_sel:DWORD dst_unused:UNUSED_PAD src0_sel:WORD_1 src1_sel:DWORD
	ds_write_b64 v99, v[2:3]
	v_and_b32_e32 v2, 0xffff0000, v23
	v_sub_u32_e32 v0, v0, v2
	v_sub_u32_e32 v2, v6, v5
	v_and_b32_e32 v3, 0xffff0000, v4
	v_add_u32_e32 v2, 0x80, v2
	v_sub_u32_e32 v3, v7, v3
	v_sub_u32_e32 v1, v1, v34
	v_add_u32_e32 v0, 0x80, v0
	v_ashrrev_i32_e32 v2, 8, v2
	v_add_u32_e32 v3, 0x80, v3
	v_add_u32_e32 v1, 0x80, v1
	v_ashrrev_i32_e32 v0, 8, v0
	v_min_i32_e32 v2, 0x7f, v2
	v_ashrrev_i32_e32 v3, 8, v3
	v_ashrrev_i32_e32 v1, 8, v1
	v_min_i32_e32 v0, 0x7f, v0
	v_min_i32_sdwa v3, v3, s85 dst_sel:WORD_1 dst_unused:UNUSED_PAD src0_sel:DWORD src1_sel:DWORD
	v_min_i32_e32 v1, 0x7f, v1
	v_lshlrev_b32_e32 v2, 8, v2
	v_and_b32_e32 v2, 0xff00, v2
	v_and_b32_e32 v3, 0xff0000, v3
	v_perm_b32 v0, v1, v0, s92
	v_or3_b32 v0, v0, v2, v3
	ds_write_b32 v22, v0 offset:16
	buffer_store_dwordx4 v[168:171], v89, s[16:19], s41 offen
	v_mov_b32_e32 v0, v228
	v_mov_b32_e32 v1, v229
	v_mov_b32_e32 v2, v230
	v_mov_b32_e32 v3, v231
	v_mov_b32_e32 v4, v244
	v_mov_b32_e32 v5, v245
	v_mov_b32_e32 v6, v246
	v_mov_b32_e32 v7, v247
	ds_read_b64 v[44:45], v149 offset:1024
	s_waitcnt lgkmcnt(0)
	v_pk_add_f32 v[46:47], v[56:57], v[44:45] op_sel_hi:[1,0] neg_lo:[0,1] neg_hi:[0,1]
	s_nop 0
	v_pk_mul_f32 v[46:47], v[44:45], v[46:47] op_sel:[1,0]
	v_pk_add_f32 v[50:51], v[54:55], v[44:45] op_sel_hi:[1,0] neg_lo:[0,1] neg_hi:[0,1]
	v_mov_b32_e32 v34, v1
	v_mov_b32_e32 v35, v2
	v_mov_b32_e32 v42, v5
	v_mov_b32_e32 v43, v6
	v_pk_fma_f32 v[46:47], v[34:35], v[46:47], v[42:43]
	v_pk_mul_f32 v[44:45], v[44:45], v[50:51] op_sel:[1,0]
	v_mov_b32_e32 v1, v3
	v_mov_b32_e32 v5, v7
	v_and_b32_sdwa v6, v47, v216 dst_sel:DWORD dst_unused:UNUSED_PAD src0_sel:WORD_1 src1_sel:DWORD
	v_and_b32_sdwa v7, v46, v216 dst_sel:DWORD dst_unused:UNUSED_PAD src0_sel:WORD_1 src1_sel:DWORD
	v_pk_fma_f32 v[2:3], v[0:1], v[44:45], v[4:5]
	v_add3_u32 v23, v47, v6, s84
	v_add3_u32 v6, v46, v7, s84
	v_and_b32_e32 v44, 0xffff0000, v6
	v_and_b32_sdwa v6, v3, v216 dst_sel:DWORD dst_unused:UNUSED_PAD src0_sel:WORD_1 src1_sel:DWORD
	v_and_b32_sdwa v7, v2, v216 dst_sel:DWORD dst_unused:UNUSED_PAD src0_sel:WORD_1 src1_sel:DWORD
	v_add3_u32 v6, v3, v6, s84
	v_add3_u32 v45, v2, v7, s84
	v_and_b32_e32 v50, 0xffff0000, v6
	v_or_b32_sdwa v7, v50, v23 dst_sel:DWORD dst_unused:UNUSED_PAD src0_sel:DWORD src1_sel:WORD_1
	v_or_b32_sdwa v6, v45, v44 dst_sel:DWORD dst_unused:UNUSED_PAD src0_sel:WORD_1 src1_sel:DWORD
	ds_write_b64 v106, v[6:7]
	v_and_b32_e32 v6, 0xffff0000, v45
	v_sub_u32_e32 v2, v2, v6
	v_sub_u32_e32 v6, v46, v44
	v_and_b32_e32 v7, 0xffff0000, v23
	v_add_u32_e32 v6, 0x80, v6
	v_sub_u32_e32 v7, v47, v7
	v_sub_u32_e32 v3, v3, v50
	v_add_u32_e32 v2, 0x80, v2
	v_ashrrev_i32_e32 v6, 8, v6
	v_add_u32_e32 v7, 0x80, v7
	v_add_u32_e32 v3, 0x80, v3
	v_ashrrev_i32_e32 v2, 8, v2
	v_min_i32_e32 v6, 0x7f, v6
	v_ashrrev_i32_e32 v7, 8, v7
	v_ashrrev_i32_e32 v3, 8, v3
	v_min_i32_e32 v2, 0x7f, v2
	v_min_i32_sdwa v7, v7, s85 dst_sel:WORD_1 dst_unused:UNUSED_PAD src0_sel:DWORD src1_sel:DWORD
	v_min_i32_e32 v3, 0x7f, v3
	v_lshlrev_b32_e32 v6, 8, v6
	v_and_b32_e32 v6, 0xff00, v6
	v_and_b32_e32 v7, 0xff0000, v7
	v_perm_b32 v2, v3, v2, s92
	v_or3_b32 v2, v2, v6, v7
	ds_write_b32 v12, v2 offset:128
	buffer_store_dwordx4 v[172:175], v146, s[20:23], s1 offen
	ds_read_b64 v[2:3], v13 offset:1024
	s_waitcnt lgkmcnt(0)
;     ...
;             _Pragma("unroll") for (int m = 0; m < 4; ++m) {
;               const int rr = wr3 * 64 + m * 16 + fr3;
;               const float2 ms = *reinterpret_cast<const float2*>(mr + (ai * HALF + rr) * 2);
;               f32x4 y = acc[ai][bj][m][n];
;               const float o0 = (y[0] - ms.x) * ms.y * gm.x + bt.x, o1 = (y[1] - ms.x) * ms.y * gm.y + bt.y;
;               const float o2 = (y[2] - ms.x) * ms.y * gm.z + bt.z, o3 = (y[3] - ms.x) * ms.y * gm.w + bt.w;
;               const unsigned h0 = f2bf(o0), h1 = f2bf(o1), h2 = f2bf(o2), h3 = f2bf(o3);
;               u32x2 ob; ob[0] = h0 | (h1 << 16); ob[1] = h2 | (h3 << 16);
;               *reinterpret_cast<u32x2*>(smem + (rr >> 1) * PIECE + (rr & 1) * 512 + cc * 2) = ob;
;               const int l0 = min(((int)__float_as_uint(o0) - (int)(h0 << 16) + 128) >> 8, 127);
;               const int l1 = min(((int)__float_as_uint(o1) - (int)(h1 << 16) + 128) >> 8, 127);
;               const int l2 = min(((int)__float_as_uint(o2) - (int)(h2 << 16) + 128) >> 8, 127);
;               const int l3 = min(((int)__float_as_uint(o3) - (int)(h3 << 16) + 128) >> 8, 127);
;               *reinterpret_cast<unsigned*>(smem + LOBASE + (rr >> 2) * PIECE + (rr & 3) * 256 + cc) =
;                   (unsigned)(l0 & 255) | ((unsigned)(l1 & 255) << 8) | ((unsigned)(l2 & 255) << 16) | ((unsigned)l3 << 24);
;             }
;     ...
;           _Pragma("unroll") for (int i = 0; i < 8; ++i) {
;             const u32x4 v = *reinterpret_cast<const u32x4*>(smem + (wave * 8 + i) * PIECE + lane3 * 16);
;             __builtin_amdgcn_raw_buffer_store_b128(v, rsXB, hvo + i * (2 * DM * 2), hso, 0);
;           }
;           _Pragma("unroll") for (int i = 0; i < 4; ++i) {
;             const u32x4 v = *reinterpret_cast<const u32x4*>(smem + LOBASE + (wave * 4 + i) * PIECE + lane3 * 16);
;             __builtin_amdgcn_raw_buffer_store_b128(v, rsLO, lvo + i * (4 * DM), lso, 0);
;           }
	v_pk_add_f32 v[6:7], v[40:41], v[2:3] op_sel_hi:[1,0] neg_lo:[0,1] neg_hi:[0,1]
	s_nop 0
	v_pk_mul_f32 v[6:7], v[2:3], v[6:7] op_sel:[1,0]
	v_pk_add_f32 v[38:39], v[38:39], v[2:3] op_sel_hi:[1,0] neg_lo:[0,1] neg_hi:[0,1]
	v_pk_fma_f32 v[6:7], v[34:35], v[6:7], v[42:43]
	v_pk_mul_f32 v[2:3], v[2:3], v[38:39] op_sel:[1,0]
	v_and_b32_sdwa v38, v6, v216 dst_sel:DWORD dst_unused:UNUSED_PAD src0_sel:WORD_1 src1_sel:DWORD
	v_pk_fma_f32 v[2:3], v[0:1], v[2:3], v[4:5]
	v_add3_u32 v38, v6, v38, s84
	v_and_b32_e32 v40, 0xffff0000, v38
	v_and_b32_sdwa v38, v3, v216 dst_sel:DWORD dst_unused:UNUSED_PAD src0_sel:WORD_1 src1_sel:DWORD
	v_and_b32_sdwa v23, v7, v216 dst_sel:DWORD dst_unused:UNUSED_PAD src0_sel:WORD_1 src1_sel:DWORD
	v_and_b32_sdwa v39, v2, v216 dst_sel:DWORD dst_unused:UNUSED_PAD src0_sel:WORD_1 src1_sel:DWORD
	v_add3_u32 v38, v3, v38, s84
	v_add3_u32 v23, v7, v23, s84
	v_add3_u32 v41, v2, v39, s84
	v_and_b32_e32 v44, 0xffff0000, v38
	v_or_b32_sdwa v39, v44, v23 dst_sel:DWORD dst_unused:UNUSED_PAD src0_sel:DWORD src1_sel:WORD_1
	v_or_b32_sdwa v38, v41, v40 dst_sel:DWORD dst_unused:UNUSED_PAD src0_sel:WORD_1 src1_sel:DWORD
	ds_write_b64 v102, v[38:39]
	v_and_b32_e32 v38, 0xffff0000, v41
	v_sub_u32_e32 v6, v6, v40
	v_and_b32_e32 v23, 0xffff0000, v23
	v_sub_u32_e32 v2, v2, v38
	v_add_u32_e32 v6, 0x80, v6
	v_sub_u32_e32 v7, v7, v23
	v_sub_u32_e32 v3, v3, v44
	v_add_u32_e32 v2, 0x80, v2
	v_ashrrev_i32_e32 v6, 8, v6
	v_add_u32_e32 v7, 0x80, v7
	v_add_u32_e32 v3, 0x80, v3
	v_ashrrev_i32_e32 v2, 8, v2
	v_min_i32_e32 v6, 0x7f, v6
	v_ashrrev_i32_e32 v7, 8, v7
	v_ashrrev_i32_e32 v3, 8, v3
	v_min_i32_e32 v2, 0x7f, v2
	v_min_i32_sdwa v7, v7, s85 dst_sel:WORD_1 dst_unused:UNUSED_PAD src0_sel:DWORD src1_sel:DWORD
	v_min_i32_e32 v3, 0x7f, v3
	v_lshlrev_b32_e32 v6, 8, v6
	v_and_b32_e32 v6, 0xff00, v6
	v_and_b32_e32 v7, 0xff0000, v7
	v_perm_b32 v2, v3, v2, s92
	v_or3_b32 v2, v2, v6, v7
	ds_write_b32 v14, v2 offset:128
	buffer_store_dwordx4 v[176:179], v90, s[20:23], s1 offen
	ds_read_b64 v[2:3], v15 offset:1024
	s_waitcnt lgkmcnt(0)
	v_pk_add_f32 v[6:7], v[24:25], v[2:3] op_sel_hi:[1,0] neg_lo:[0,1] neg_hi:[0,1]
	s_nop 0
	v_pk_mul_f32 v[6:7], v[2:3], v[6:7] op_sel:[1,0]
	v_pk_add_f32 v[24:25], v[26:27], v[2:3] op_sel_hi:[1,0] neg_lo:[0,1] neg_hi:[0,1]
	v_pk_fma_f32 v[6:7], v[34:35], v[6:7], v[42:43]
	v_pk_mul_f32 v[2:3], v[2:3], v[24:25] op_sel:[1,0]
	v_and_b32_sdwa v24, v6, v216 dst_sel:DWORD dst_unused:UNUSED_PAD src0_sel:WORD_1 src1_sel:DWORD
	v_pk_fma_f32 v[2:3], v[0:1], v[2:3], v[4:5]
	v_add3_u32 v24, v6, v24, s84
	v_and_b32_e32 v26, 0xffff0000, v24
	v_and_b32_sdwa v24, v3, v216 dst_sel:DWORD dst_unused:UNUSED_PAD src0_sel:WORD_1 src1_sel:DWORD
	v_and_b32_sdwa v23, v7, v216 dst_sel:DWORD dst_unused:UNUSED_PAD src0_sel:WORD_1 src1_sel:DWORD
	v_and_b32_sdwa v25, v2, v216 dst_sel:DWORD dst_unused:UNUSED_PAD src0_sel:WORD_1 src1_sel:DWORD
	v_add3_u32 v24, v3, v24, s84
	v_add3_u32 v23, v7, v23, s84
	v_add3_u32 v27, v2, v25, s84
	v_and_b32_e32 v38, 0xffff0000, v24
	v_or_b32_sdwa v25, v38, v23 dst_sel:DWORD dst_unused:UNUSED_PAD src0_sel:DWORD src1_sel:WORD_1
	v_or_b32_sdwa v24, v27, v26 dst_sel:DWORD dst_unused:UNUSED_PAD src0_sel:WORD_1 src1_sel:DWORD
	ds_write_b64 v92, v[24:25]
	v_and_b32_e32 v24, 0xffff0000, v27
	v_sub_u32_e32 v6, v6, v26
	v_and_b32_e32 v23, 0xffff0000, v23
	v_sub_u32_e32 v2, v2, v24
	v_add_u32_e32 v6, 0x80, v6
	v_sub_u32_e32 v7, v7, v23
	v_sub_u32_e32 v3, v3, v38
	v_add_u32_e32 v2, 0x80, v2
	v_ashrrev_i32_e32 v6, 8, v6
	v_add_u32_e32 v7, 0x80, v7
	v_add_u32_e32 v3, 0x80, v3
	v_ashrrev_i32_e32 v2, 8, v2
	v_min_i32_e32 v6, 0x7f, v6
	v_ashrrev_i32_e32 v7, 8, v7
	v_ashrrev_i32_e32 v3, 8, v3
	v_min_i32_e32 v2, 0x7f, v2
	v_min_i32_sdwa v7, v7, s85 dst_sel:WORD_1 dst_unused:UNUSED_PAD src0_sel:DWORD src1_sel:DWORD
	v_min_i32_e32 v3, 0x7f, v3
	v_lshlrev_b32_e32 v6, 8, v6
	v_and_b32_e32 v6, 0xff00, v6
	v_and_b32_e32 v7, 0xff0000, v7
	v_perm_b32 v2, v3, v2, s92
	v_or3_b32 v2, v2, v6, v7
	ds_write_b32 v18, v2 offset:128
	buffer_store_dwordx4 v[180:183], v91, s[20:23], s1 offen
	ds_read_b64 v[2:3], v19 offset:1024
	s_waitcnt lgkmcnt(0)
	v_pk_add_f32 v[6:7], v[28:29], v[2:3] op_sel_hi:[1,0] neg_lo:[0,1] neg_hi:[0,1]
	s_nop 0
	v_pk_mul_f32 v[6:7], v[2:3], v[6:7] op_sel:[1,0]
	v_pk_add_f32 v[24:25], v[30:31], v[2:3] op_sel_hi:[1,0] neg_lo:[0,1] neg_hi:[0,1]
	v_pk_fma_f32 v[6:7], v[34:35], v[6:7], v[42:43]
	v_pk_mul_f32 v[2:3], v[2:3], v[24:25] op_sel:[1,0]
	s_nop 0
	v_pk_fma_f32 v[0:1], v[0:1], v[2:3], v[4:5]
	v_and_b32_sdwa v2, v7, v216 dst_sel:DWORD dst_unused:UNUSED_PAD src0_sel:WORD_1 src1_sel:DWORD
	v_and_b32_sdwa v3, v6, v216 dst_sel:DWORD dst_unused:UNUSED_PAD src0_sel:WORD_1 src1_sel:DWORD
	v_add3_u32 v4, v7, v2, s84
	v_add3_u32 v2, v6, v3, s84
	v_and_b32_e32 v5, 0xffff0000, v2
	v_and_b32_sdwa v2, v1, v216 dst_sel:DWORD dst_unused:UNUSED_PAD src0_sel:WORD_1 src1_sel:DWORD
	v_and_b32_sdwa v3, v0, v216 dst_sel:DWORD dst_unused:UNUSED_PAD src0_sel:WORD_1 src1_sel:DWORD
	v_add3_u32 v2, v1, v2, s84
	v_add3_u32 v23, v0, v3, s84
	v_and_b32_e32 v24, 0xffff0000, v2
	v_or_b32_sdwa v3, v24, v4 dst_sel:DWORD dst_unused:UNUSED_PAD src0_sel:DWORD src1_sel:WORD_1
	v_or_b32_sdwa v2, v23, v5 dst_sel:DWORD dst_unused:UNUSED_PAD src0_sel:WORD_1 src1_sel:DWORD
	ds_write_b64 v93, v[2:3]
	v_and_b32_e32 v2, 0xffff0000, v23
	v_sub_u32_e32 v0, v0, v2
	v_sub_u32_e32 v2, v6, v5
	v_and_b32_e32 v3, 0xffff0000, v4
	v_add_u32_e32 v2, 0x80, v2
	v_sub_u32_e32 v3, v7, v3
	v_sub_u32_e32 v1, v1, v24
	v_add_u32_e32 v0, 0x80, v0
	v_ashrrev_i32_e32 v2, 8, v2
	v_add_u32_e32 v3, 0x80, v3
	v_add_u32_e32 v1, 0x80, v1
	v_ashrrev_i32_e32 v0, 8, v0
	v_min_i32_e32 v2, 0x7f, v2
	v_ashrrev_i32_e32 v3, 8, v3
	v_ashrrev_i32_e32 v1, 8, v1
	v_min_i32_e32 v0, 0x7f, v0
	v_min_i32_sdwa v3, v3, s85 dst_sel:WORD_1 dst_unused:UNUSED_PAD src0_sel:DWORD src1_sel:DWORD
	v_min_i32_e32 v1, 0x7f, v1
	v_lshlrev_b32_e32 v2, 8, v2
	v_and_b32_e32 v2, 0xff00, v2
	v_and_b32_e32 v3, 0xff0000, v3
	v_perm_b32 v0, v1, v0, s92
	v_or3_b32 v0, v0, v2, v3
	ds_write_b32 v22, v0 offset:128
	buffer_store_dwordx4 v[184:187], v96, s[20:23], s1 offen
	v_mov_b32_e32 v0, v232
	v_mov_b32_e32 v1, v233
	v_mov_b32_e32 v2, v234
	v_mov_b32_e32 v3, v235
	v_mov_b32_e32 v4, v248
	v_mov_b32_e32 v5, v249
	v_mov_b32_e32 v6, v250
	v_mov_b32_e32 v7, v251
	ds_read_b64 v[28:29], v149 offset:1024
	s_mov_b64 s[4:5], -1
	s_waitcnt lgkmcnt(0)
;     ...
;             _Pragma("unroll") for (int m = 0; m < 4; ++m) {
;               const int rr = wr3 * 64 + m * 16 + fr3;
;               const float2 ms = *reinterpret_cast<const float2*>(mr + (ai * HALF + rr) * 2);
;               f32x4 y = acc[ai][bj][m][n];
;               const float o0 = (y[0] - ms.x) * ms.y * gm.x + bt.x, o1 = (y[1] - ms.x) * ms.y * gm.y + bt.y;
;               const float o2 = (y[2] - ms.x) * ms.y * gm.z + bt.z, o3 = (y[3] - ms.x) * ms.y * gm.w + bt.w;
;               const unsigned h0 = f2bf(o0), h1 = f2bf(o1), h2 = f2bf(o2), h3 = f2bf(o3);
;               u32x2 ob; ob[0] = h0 | (h1 << 16); ob[1] = h2 | (h3 << 16);
;               *reinterpret_cast<u32x2*>(smem + (rr >> 1) * PIECE + (rr & 1) * 512 + cc * 2) = ob;
;               const int l0 = min(((int)__float_as_uint(o0) - (int)(h0 << 16) + 128) >> 8, 127);
;               const int l1 = min(((int)__float_as_uint(o1) - (int)(h1 << 16) + 128) >> 8, 127);
;               const int l2 = min(((int)__float_as_uint(o2) - (int)(h2 << 16) + 128) >> 8, 127);
;               const int l3 = min(((int)__float_as_uint(o3) - (int)(h3 << 16) + 128) >> 8, 127);
;               *reinterpret_cast<unsigned*>(smem + LOBASE + (rr >> 2) * PIECE + (rr & 3) * 256 + cc) =
;                   (unsigned)(l0 & 255) | ((unsigned)(l1 & 255) << 8) | ((unsigned)(l2 & 255) << 16) | ((unsigned)l3 << 24);
;             }
	v_pk_add_f32 v[30:31], v[52:53], v[28:29] op_sel_hi:[1,0] neg_lo:[0,1] neg_hi:[0,1]
	s_nop 0
	v_pk_mul_f32 v[30:31], v[28:29], v[30:31] op_sel:[1,0]
	v_pk_add_f32 v[34:35], v[48:49], v[28:29] op_sel_hi:[1,0] neg_lo:[0,1] neg_hi:[0,1]
	v_mov_b32_e32 v24, v1
	v_mov_b32_e32 v25, v2
	v_mov_b32_e32 v26, v5
	v_mov_b32_e32 v27, v6
	v_pk_fma_f32 v[30:31], v[24:25], v[30:31], v[26:27]
	v_pk_mul_f32 v[28:29], v[28:29], v[34:35] op_sel:[1,0]
	v_mov_b32_e32 v1, v3
	v_mov_b32_e32 v5, v7
	v_and_b32_sdwa v6, v31, v216 dst_sel:DWORD dst_unused:UNUSED_PAD src0_sel:WORD_1 src1_sel:DWORD
	v_and_b32_sdwa v7, v30, v216 dst_sel:DWORD dst_unused:UNUSED_PAD src0_sel:WORD_1 src1_sel:DWORD
	v_pk_fma_f32 v[2:3], v[0:1], v[28:29], v[4:5]
	v_add3_u32 v23, v31, v6, s84
	v_add3_u32 v6, v30, v7, s84
	v_and_b32_e32 v28, 0xffff0000, v6
	v_and_b32_sdwa v6, v3, v216 dst_sel:DWORD dst_unused:UNUSED_PAD src0_sel:WORD_1 src1_sel:DWORD
	v_and_b32_sdwa v7, v2, v216 dst_sel:DWORD dst_unused:UNUSED_PAD src0_sel:WORD_1 src1_sel:DWORD
	v_add3_u32 v6, v3, v6, s84
	v_add3_u32 v29, v2, v7, s84
	v_and_b32_e32 v34, 0xffff0000, v6
	v_or_b32_sdwa v7, v34, v23 dst_sel:DWORD dst_unused:UNUSED_PAD src0_sel:DWORD src1_sel:WORD_1
	v_or_b32_sdwa v6, v29, v28 dst_sel:DWORD dst_unused:UNUSED_PAD src0_sel:WORD_1 src1_sel:DWORD
	ds_write_b64 v94, v[6:7]
	v_and_b32_e32 v6, 0xffff0000, v29
	v_sub_u32_e32 v2, v2, v6
	v_sub_u32_e32 v6, v30, v28
	v_and_b32_e32 v7, 0xffff0000, v23
	v_add_u32_e32 v6, 0x80, v6
	v_sub_u32_e32 v7, v31, v7
	v_sub_u32_e32 v3, v3, v34
	v_add_u32_e32 v2, 0x80, v2
	v_ashrrev_i32_e32 v6, 8, v6
	v_add_u32_e32 v7, 0x80, v7
	v_add_u32_e32 v3, 0x80, v3
	v_ashrrev_i32_e32 v2, 8, v2
	v_min_i32_e32 v6, 0x7f, v6
	v_ashrrev_i32_e32 v7, 8, v7
	v_ashrrev_i32_e32 v3, 8, v3
	v_min_i32_e32 v2, 0x7f, v2
	v_min_i32_sdwa v7, v7, s85 dst_sel:WORD_1 dst_unused:UNUSED_PAD src0_sel:DWORD src1_sel:DWORD
	v_min_i32_e32 v3, 0x7f, v3
	v_lshlrev_b32_e32 v6, 8, v6
	v_and_b32_e32 v6, 0xff00, v6
	v_and_b32_e32 v7, 0xff0000, v7
	v_perm_b32 v2, v3, v2, s92
	v_or3_b32 v2, v2, v6, v7
	ds_write_b32 v12, v2 offset:144
	ds_read_b64 v[2:3], v13 offset:1024
	s_waitcnt lgkmcnt(0)
	v_pk_add_f32 v[6:7], v[36:37], v[2:3] op_sel_hi:[1,0] neg_lo:[0,1] neg_hi:[0,1]
	s_nop 0
	v_pk_mul_f32 v[6:7], v[2:3], v[6:7] op_sel:[1,0]
	v_pk_add_f32 v[12:13], v[32:33], v[2:3] op_sel_hi:[1,0] neg_lo:[0,1] neg_hi:[0,1]
	v_pk_fma_f32 v[6:7], v[24:25], v[6:7], v[26:27]
	v_pk_mul_f32 v[2:3], v[2:3], v[12:13] op_sel:[1,0]
	v_and_b32_sdwa v12, v7, v216 dst_sel:DWORD dst_unused:UNUSED_PAD src0_sel:WORD_1 src1_sel:DWORD
	v_and_b32_sdwa v13, v6, v216 dst_sel:DWORD dst_unused:UNUSED_PAD src0_sel:WORD_1 src1_sel:DWORD
	v_pk_fma_f32 v[2:3], v[0:1], v[2:3], v[4:5]
	v_add3_u32 v23, v7, v12, s84
	v_add3_u32 v12, v6, v13, s84
	v_and_b32_e32 v28, 0xffff0000, v12
	v_and_b32_sdwa v12, v3, v216 dst_sel:DWORD dst_unused:UNUSED_PAD src0_sel:WORD_1 src1_sel:DWORD
	v_and_b32_sdwa v13, v2, v216 dst_sel:DWORD dst_unused:UNUSED_PAD src0_sel:WORD_1 src1_sel:DWORD
	v_add3_u32 v12, v3, v12, s84
	v_add3_u32 v29, v2, v13, s84
	v_and_b32_e32 v30, 0xffff0000, v12
	v_or_b32_sdwa v13, v30, v23 dst_sel:DWORD dst_unused:UNUSED_PAD src0_sel:DWORD src1_sel:WORD_1
	v_or_b32_sdwa v12, v29, v28 dst_sel:DWORD dst_unused:UNUSED_PAD src0_sel:WORD_1 src1_sel:DWORD
	ds_write_b64 v95, v[12:13]
	v_and_b32_e32 v12, 0xffff0000, v29
	v_sub_u32_e32 v2, v2, v12
	v_sub_u32_e32 v6, v6, v28
	v_and_b32_e32 v12, 0xffff0000, v23
	v_add_u32_e32 v6, 0x80, v6
	v_sub_u32_e32 v7, v7, v12
	v_sub_u32_e32 v3, v3, v30
	v_add_u32_e32 v2, 0x80, v2
	v_ashrrev_i32_e32 v6, 8, v6
	v_add_u32_e32 v7, 0x80, v7
	v_add_u32_e32 v3, 0x80, v3
	v_ashrrev_i32_e32 v2, 8, v2
	v_min_i32_e32 v6, 0x7f, v6
	v_ashrrev_i32_e32 v7, 8, v7
	v_ashrrev_i32_e32 v3, 8, v3
	v_min_i32_e32 v2, 0x7f, v2
	v_min_i32_sdwa v7, v7, s85 dst_sel:WORD_1 dst_unused:UNUSED_PAD src0_sel:DWORD src1_sel:DWORD
	v_min_i32_e32 v3, 0x7f, v3
	v_lshlrev_b32_e32 v6, 8, v6
	v_and_b32_e32 v6, 0xff00, v6
	v_and_b32_e32 v7, 0xff0000, v7
	v_perm_b32 v2, v3, v2, s92
	v_or3_b32 v2, v2, v6, v7
	ds_write_b32 v14, v2 offset:144
	ds_read_b64 v[2:3], v15 offset:1024
	s_waitcnt lgkmcnt(0)
	v_pk_add_f32 v[6:7], v[20:21], v[2:3] op_sel_hi:[1,0] neg_lo:[0,1] neg_hi:[0,1]
	s_nop 0
	v_pk_mul_f32 v[6:7], v[2:3], v[6:7] op_sel:[1,0]
	v_pk_add_f32 v[12:13], v[16:17], v[2:3] op_sel_hi:[1,0] neg_lo:[0,1] neg_hi:[0,1]
	v_pk_fma_f32 v[6:7], v[24:25], v[6:7], v[26:27]
	v_pk_mul_f32 v[2:3], v[2:3], v[12:13] op_sel:[1,0]
	v_and_b32_sdwa v12, v7, v216 dst_sel:DWORD dst_unused:UNUSED_PAD src0_sel:WORD_1 src1_sel:DWORD
	v_and_b32_sdwa v13, v6, v216 dst_sel:DWORD dst_unused:UNUSED_PAD src0_sel:WORD_1 src1_sel:DWORD
	v_pk_fma_f32 v[2:3], v[0:1], v[2:3], v[4:5]
	v_add3_u32 v14, v7, v12, s84
	v_add3_u32 v12, v6, v13, s84
	v_and_b32_e32 v15, 0xffff0000, v12
	v_and_b32_sdwa v12, v3, v216 dst_sel:DWORD dst_unused:UNUSED_PAD src0_sel:WORD_1 src1_sel:DWORD
	v_and_b32_sdwa v13, v2, v216 dst_sel:DWORD dst_unused:UNUSED_PAD src0_sel:WORD_1 src1_sel:DWORD
	v_add3_u32 v12, v3, v12, s84
	v_add3_u32 v16, v2, v13, s84
	v_and_b32_e32 v17, 0xffff0000, v12
	v_or_b32_sdwa v13, v17, v14 dst_sel:DWORD dst_unused:UNUSED_PAD src0_sel:DWORD src1_sel:WORD_1
	v_or_b32_sdwa v12, v16, v15 dst_sel:DWORD dst_unused:UNUSED_PAD src0_sel:WORD_1 src1_sel:DWORD
	ds_write_b64 v80, v[12:13]
	v_and_b32_e32 v12, 0xffff0000, v16
	v_sub_u32_e32 v2, v2, v12
	v_sub_u32_e32 v6, v6, v15
	v_and_b32_e32 v12, 0xffff0000, v14
	v_add_u32_e32 v6, 0x80, v6
	v_sub_u32_e32 v7, v7, v12
	v_sub_u32_e32 v3, v3, v17
	v_add_u32_e32 v2, 0x80, v2
	v_ashrrev_i32_e32 v6, 8, v6
	v_add_u32_e32 v7, 0x80, v7
	v_add_u32_e32 v3, 0x80, v3
	v_ashrrev_i32_e32 v2, 8, v2
	v_min_i32_e32 v6, 0x7f, v6
	v_ashrrev_i32_e32 v7, 8, v7
	v_ashrrev_i32_e32 v3, 8, v3
	v_min_i32_e32 v2, 0x7f, v2
	v_min_i32_sdwa v7, v7, s85 dst_sel:WORD_1 dst_unused:UNUSED_PAD src0_sel:DWORD src1_sel:DWORD
	v_min_i32_e32 v3, 0x7f, v3
	v_lshlrev_b32_e32 v6, 8, v6
	v_and_b32_e32 v6, 0xff00, v6
	v_and_b32_e32 v7, 0xff0000, v7
	v_perm_b32 v2, v3, v2, s92
	v_or3_b32 v2, v2, v6, v7
	ds_write_b32 v18, v2 offset:144
	ds_read_b64 v[2:3], v19 offset:1024
	s_waitcnt lgkmcnt(0)
; #define BAR __builtin_amdgcn_s_barrier()
;     ...
;   auto issue_prologue = [&](int sA0, int sA1, int sB0, int sB1) {
;     const int tid = opaque_tid(wave);
;     int offA[2], offB[2];
;     _Pragma("unroll") for (int i = 0; i < 2; ++i) {
;     ...
;             _Pragma("unroll") for (int m = 0; m < 4; ++m) {
;               const int rr = wr3 * 64 + m * 16 + fr3;
;               const float2 ms = *reinterpret_cast<const float2*>(mr + (ai * HALF + rr) * 2);
;               f32x4 y = acc[ai][bj][m][n];
;               const float o0 = (y[0] - ms.x) * ms.y * gm.x + bt.x, o1 = (y[1] - ms.x) * ms.y * gm.y + bt.y;
;               const float o2 = (y[2] - ms.x) * ms.y * gm.z + bt.z, o3 = (y[3] - ms.x) * ms.y * gm.w + bt.w;
;               const unsigned h0 = f2bf(o0), h1 = f2bf(o1), h2 = f2bf(o2), h3 = f2bf(o3);
;               u32x2 ob; ob[0] = h0 | (h1 << 16); ob[1] = h2 | (h3 << 16);
;               *reinterpret_cast<u32x2*>(smem + (rr >> 1) * PIECE + (rr & 1) * 512 + cc * 2) = ob;
;               const int l0 = min(((int)__float_as_uint(o0) - (int)(h0 << 16) + 128) >> 8, 127);
;               const int l1 = min(((int)__float_as_uint(o1) - (int)(h1 << 16) + 128) >> 8, 127);
;               const int l2 = min(((int)__float_as_uint(o2) - (int)(h2 << 16) + 128) >> 8, 127);
;               const int l3 = min(((int)__float_as_uint(o3) - (int)(h3 << 16) + 128) >> 8, 127);
;               *reinterpret_cast<unsigned*>(smem + LOBASE + (rr >> 2) * PIECE + (rr & 3) * 256 + cc) =
;                   (unsigned)(l0 & 255) | ((unsigned)(l1 & 255) << 8) | ((unsigned)(l2 & 255) << 16) | ((unsigned)l3 << 24);
;             }
;           }
;           WAIT_L(0); BAR;
;           const int hso = ((brow + ai * HALF + 16 * wave) * DM + pn * BM) * 2;
;           const int lso = (brow + ai * HALF + 16 * wave) * DM + pn * BM;
;           _Pragma("unroll") for (int i = 0; i < 8; ++i) {
;             const u32x4 v = *reinterpret_cast<const u32x4*>(smem + (wave * 8 + i) * PIECE + lane3 * 16);
;             __builtin_amdgcn_raw_buffer_store_b128(v, rsXB, hvo + i * (2 * DM * 2), hso, 0);
;           }
;           _Pragma("unroll") for (int i = 0; i < 4; ++i) {
;             const u32x4 v = *reinterpret_cast<const u32x4*>(smem + LOBASE + (wave * 4 + i) * PIECE + lane3 * 16);
;             __builtin_amdgcn_raw_buffer_store_b128(v, rsLO, lvo + i * (4 * DM), lso, 0);
;           }
;           WAIT_L(0); BAR;
	v_pk_add_f32 v[6:7], v[8:9], v[2:3] op_sel_hi:[1,0] neg_lo:[0,1] neg_hi:[0,1]
	s_nop 0
	v_pk_mul_f32 v[6:7], v[2:3], v[6:7] op_sel:[1,0]
	v_pk_add_f32 v[8:9], v[10:11], v[2:3] op_sel_hi:[1,0] neg_lo:[0,1] neg_hi:[0,1]
	v_pk_fma_f32 v[6:7], v[24:25], v[6:7], v[26:27]
	v_pk_mul_f32 v[2:3], v[2:3], v[8:9] op_sel:[1,0]
	s_nop 0
	v_pk_fma_f32 v[0:1], v[0:1], v[2:3], v[4:5]
	v_and_b32_sdwa v2, v7, v216 dst_sel:DWORD dst_unused:UNUSED_PAD src0_sel:WORD_1 src1_sel:DWORD
	v_and_b32_sdwa v3, v6, v216 dst_sel:DWORD dst_unused:UNUSED_PAD src0_sel:WORD_1 src1_sel:DWORD
	v_add3_u32 v4, v7, v2, s84
	v_add3_u32 v2, v6, v3, s84
	v_and_b32_e32 v5, 0xffff0000, v2
	v_and_b32_sdwa v2, v1, v216 dst_sel:DWORD dst_unused:UNUSED_PAD src0_sel:WORD_1 src1_sel:DWORD
	v_and_b32_sdwa v3, v0, v216 dst_sel:DWORD dst_unused:UNUSED_PAD src0_sel:WORD_1 src1_sel:DWORD
	v_add3_u32 v2, v1, v2, s84
	v_add3_u32 v8, v0, v3, s84
	v_and_b32_e32 v9, 0xffff0000, v2
	v_or_b32_sdwa v3, v9, v4 dst_sel:DWORD dst_unused:UNUSED_PAD src0_sel:DWORD src1_sel:WORD_1
	v_or_b32_sdwa v2, v8, v5 dst_sel:DWORD dst_unused:UNUSED_PAD src0_sel:WORD_1 src1_sel:DWORD
	ds_write_b64 v73, v[2:3]
	v_and_b32_e32 v2, 0xffff0000, v8
	v_sub_u32_e32 v0, v0, v2
	v_sub_u32_e32 v2, v6, v5
	v_and_b32_e32 v3, 0xffff0000, v4
	v_add_u32_e32 v2, 0x80, v2
	v_sub_u32_e32 v3, v7, v3
	v_sub_u32_e32 v1, v1, v9
	v_add_u32_e32 v0, 0x80, v0
	v_ashrrev_i32_e32 v2, 8, v2
	v_add_u32_e32 v3, 0x80, v3
	v_add_u32_e32 v1, 0x80, v1
	v_ashrrev_i32_e32 v0, 8, v0
	v_min_i32_e32 v2, 0x7f, v2
	v_ashrrev_i32_e32 v3, 8, v3
	v_ashrrev_i32_e32 v1, 8, v1
	v_min_i32_e32 v0, 0x7f, v0
	v_min_i32_sdwa v3, v3, s85 dst_sel:WORD_1 dst_unused:UNUSED_PAD src0_sel:DWORD src1_sel:DWORD
	v_min_i32_e32 v1, 0x7f, v1
	v_lshlrev_b32_e32 v2, 8, v2
	v_and_b32_e32 v2, 0xff00, v2
	v_and_b32_e32 v3, 0xff0000, v3
	v_perm_b32 v0, v1, v0, s92
	v_or3_b32 v0, v0, v2, v3
	ds_write_b32 v22, v0 offset:144
	s_waitcnt lgkmcnt(0)
	s_barrier
	ds_read_b128 v[128:131], v72
	ds_read_b128 v[132:135], v72 offset:1040
	ds_read_b128 v[136:139], v72 offset:2080
	ds_read_b128 v[140:143], v72 offset:3120
	ds_read_b128 v[152:155], v72 offset:4160
	ds_read_b128 v[156:159], v72 offset:5200
	ds_read_b128 v[160:163], v72 offset:6240
	ds_read_b128 v[164:167], v72 offset:7280
	ds_read_b128 v[168:171], v147
	ds_read_b128 v[172:175], v147 offset:1040
	ds_read_b128 v[176:179], v147 offset:2080
	ds_read_b128 v[180:183], v147 offset:3120
	s_waitcnt lgkmcnt(0)
	s_barrier
	s_mov_b32 s98, s0
	s_cbranch_vccnz .Lmy_s1n_278
	v_mbcnt_lo_u32_b32 v0, -1, 0
	v_mbcnt_hi_u32_b32 v0, -1, v0
	s_mov_b32 m0, s37
	v_lshl_add_u32 v0, v0, 4, s35
	v_ashrrev_i32_e32 v1, 31, v0
	v_lshrrev_b32_e32 v1, 22, v1
	v_add_u32_e32 v1, v0, v1
	v_ashrrev_i32_e32 v1, 10, v1
	v_mul_i32_i24_e32 v2, 0x400, v1
	v_sub_u32_e32 v2, v0, v2
	v_lshrrev_b32_e32 v3, 4, v2
	v_bitop3_b32 v2, v3, v2, 32 bitop3:0x6c
	v_ashrrev_i32_e32 v4, 31, v2
	v_lshrrev_b32_e32 v4, 26, v4
	v_add_u32_e32 v4, v2, v4
	v_lshrrev_b32_e32 v5, 6, v4
	v_and_b32_e32 v4, 0xc0, v4
	v_lshlrev_b32_e32 v3, 3, v1
	v_lshlrev_b32_e32 v1, 5, v1
	v_sub_u32_e32 v2, v2, v4
	v_and_b32_e32 v3, 0x1ffff0, v3
	v_and_b32_e32 v1, 32, v1
	v_ashrrev_i16_sdwa v2, v216, sext(v2) dst_sel:DWORD dst_unused:UNUSED_PAD src0_sel:DWORD src1_sel:BYTE_0
	v_add_u32_sdwa v1, v1, sext(v2) dst_sel:DWORD dst_unused:UNUSED_PAD src0_sel:DWORD src1_sel:WORD_0
	v_add_lshl_u32 v2, v5, v3, 11
	v_add_u32_e32 v0, 0x2000, v0
	v_lshl_add_u32 v1, v1, 1, v2
	v_ashrrev_i32_e32 v2, 31, v0
	v_lshrrev_b32_e32 v2, 22, v2
	v_add_u32_e32 v2, v0, v2
	v_ashrrev_i32_e32 v2, 10, v2
	v_mul_i32_i24_e32 v3, 0x400, v2
	v_sub_u32_e32 v0, v0, v3
	v_lshrrev_b32_e32 v3, 4, v0
	v_bitop3_b32 v0, v3, v0, 32 bitop3:0x6c
	v_ashrrev_i32_e32 v4, 31, v0
	v_lshrrev_b32_e32 v4, 26, v4
	v_add_u32_e32 v4, v0, v4
	v_lshrrev_b32_e32 v5, 6, v4
	v_and_b32_e32 v4, 0xffc0, v4
	v_sub_u32_e32 v0, v0, v4
	v_lshrrev_b16_e32 v4, 7, v0
	v_and_b32_e32 v4, 1, v4
	v_lshlrev_b32_e32 v3, 3, v2
	v_lshlrev_b32_e32 v2, 5, v2
	v_add_u16_e32 v0, v0, v4
	v_and_b32_e32 v3, 0x1ffff0, v3
	v_and_b32_e32 v2, 32, v2
	v_ashrrev_i16_sdwa v0, v216, sext(v0) dst_sel:DWORD dst_unused:UNUSED_PAD src0_sel:DWORD src1_sel:BYTE_0
	v_add_u32_sdwa v0, v2, sext(v0) dst_sel:DWORD dst_unused:UNUSED_PAD src0_sel:DWORD src1_sel:WORD_0
	v_add_lshl_u32 v2, v5, v3, 11
	s_mov_b32 s14, s10
	s_mov_b32 s15, s11
	v_lshl_add_u32 v0, v0, 1, v2
	buffer_load_dwordx4 v1, s[12:15], s96 offen lds
	s_mov_b32 m0, s48
	s_or_b32 s0, s96, 0x80
	buffer_load_dwordx4 v0, s[12:15], s96 offen lds
	s_mov_b32 m0, s35
	s_mov_b64 s[4:5], 0
	buffer_load_dwordx4 v1, s[8:11], s95 offen lds
	s_mov_b32 m0, s49
	s_nop 0
	buffer_load_dwordx4 v0, s[8:11], s95 offen lds
	s_mov_b32 m0, s38
	s_nop 0
	buffer_load_dwordx4 v1, s[12:15], s97 offen lds
	s_mov_b32 m0, s54
	s_nop 0
	buffer_load_dwordx4 v0, s[12:15], s97 offen lds
	s_mov_b32 m0, s39
	s_nop 0
	buffer_load_dwordx4 v1, s[8:11], s94 offen lds
	s_mov_b32 m0, s55
	s_nop 0
	buffer_load_dwordx4 v0, s[8:11], s94 offen lds
	s_mov_b32 m0, s42
	s_nop 0
	buffer_load_dwordx4 v1, s[12:15], s0 offen lds
	s_mov_b32 m0, s58
	s_nop 0
	buffer_load_dwordx4 v0, s[12:15], s0 offen lds
	s_or_b32 s0, s95, 0x80
	s_mov_b32 m0, s43
	s_nop 0
	buffer_load_dwordx4 v1, s[8:11], s0 offen lds
	s_mov_b32 m0, s59
	s_nop 0
	buffer_load_dwordx4 v0, s[8:11], s0 offen lds
	s_add_i32 s0, s97, 0x80
	s_mov_b32 m0, s44
	s_nop 0
	buffer_load_dwordx4 v1, s[12:15], s0 offen lds
	s_mov_b32 m0, s60
	s_nop 0
	buffer_load_dwordx4 v0, s[12:15], s0 offen lds
	buffer_store_dwordx4 v[128:131], v148, s[16:19], s98 offen
	buffer_store_dwordx4 v[132:135], v74, s[16:19], s98 offen
	buffer_store_dwordx4 v[136:139], v75, s[16:19], s98 offen
	buffer_store_dwordx4 v[140:143], v81, s[16:19], s98 offen
	buffer_store_dwordx4 v[152:155], v84, s[16:19], s98 offen
	buffer_store_dwordx4 v[156:159], v85, s[16:19], s98 offen
	buffer_store_dwordx4 v[160:163], v88, s[16:19], s98 offen
	buffer_store_dwordx4 v[164:167], v89, s[16:19], s98 offen
	buffer_store_dwordx4 v[168:171], v146, s[20:23], s40 offen
	buffer_store_dwordx4 v[172:175], v90, s[20:23], s40 offen
	buffer_store_dwordx4 v[176:179], v91, s[20:23], s40 offen
	buffer_store_dwordx4 v[180:183], v96, s[20:23], s40 offen
	s_branch .LBB0_283
.Lmy_s1n_278:
	buffer_store_dwordx4 v[128:131], v148, s[16:19], s98 offen
	buffer_store_dwordx4 v[132:135], v74, s[16:19], s98 offen
	buffer_store_dwordx4 v[136:139], v75, s[16:19], s98 offen
	buffer_store_dwordx4 v[140:143], v81, s[16:19], s98 offen
	buffer_store_dwordx4 v[152:155], v84, s[16:19], s98 offen
	buffer_store_dwordx4 v[156:159], v85, s[16:19], s98 offen
	buffer_store_dwordx4 v[160:163], v88, s[16:19], s98 offen
	buffer_store_dwordx4 v[164:167], v89, s[16:19], s98 offen
	buffer_store_dwordx4 v[168:171], v146, s[20:23], s40 offen
	buffer_store_dwordx4 v[172:175], v90, s[20:23], s40 offen
	buffer_store_dwordx4 v[176:179], v91, s[20:23], s40 offen
	buffer_store_dwordx4 v[180:183], v96, s[20:23], s40 offen
	s_branch .LBB0_283

;     ...
;         constexpr int PIECE = 1024 + 16, LOBASE = 64 * PIECE;
;         const int lane3 = tid3 & 63;
;         const int hvo = (lane3 >> 5) * (DM * 2) + (lane3 & 31) * 16;
;         const int lvo = (lane3 >> 4) * DM + (lane3 & 15) * 16;
;         _Pragma("unroll") for (int ai = 0; ai < 2; ++ai) {
;           _Pragma("unroll") for (int bj = 0; bj < 2; ++bj) _Pragma("unroll") for (int n = 0; n < 2; ++n) {
;             const int cc = bj * HALF + wc3 * 32 + n * 16 + fq3 * 4;
;             const float4 gm = *reinterpret_cast<const float4*>(g.gam + pn * BM + cc), bt = *reinterpret_cast<const float4*>(g.bet + pn * BM + cc);
;             _Pragma("unroll") for (int m = 0; m < 4; ++m) {
;               const int rr = wr3 * 64 + m * 16 + fr3;
;               const float2 ms = *reinterpret_cast<const float2*>(mr + (ai * HALF + rr) * 2);
;               f32x4 y = acc[ai][bj][m][n];
;               const float o0 = (y[0] - ms.x) * ms.y * gm.x + bt.x, o1 = (y[1] - ms.x) * ms.y * gm.y + bt.y;
;               const float o2 = (y[2] - ms.x) * ms.y * gm.z + bt.z, o3 = (y[3] - ms.x) * ms.y * gm.w + bt.w;
;               const unsigned h0 = f2bf(o0), h1 = f2bf(o1), h2 = f2bf(o2), h3 = f2bf(o3);
;               u32x2 ob; ob[0] = h0 | (h1 << 16); ob[1] = h2 | (h3 << 16);
;               *reinterpret_cast<u32x2*>(smem + (rr >> 1) * PIECE + (rr & 1) * 512 + cc * 2) = ob;
;               const int l0 = min(((int)__float_as_uint(o0) - (int)(h0 << 16) + 128) >> 8, 127);
;               const int l1 = min(((int)__float_as_uint(o1) - (int)(h1 << 16) + 128) >> 8, 127);
;               const int l2 = min(((int)__float_as_uint(o2) - (int)(h2 << 16) + 128) >> 8, 127);
;               const int l3 = min(((int)__float_as_uint(o3) - (int)(h3 << 16) + 128) >> 8, 127);
;               *reinterpret_cast<unsigned*>(smem + LOBASE + (rr >> 2) * PIECE + (rr & 3) * 256 + cc) =
;                   (unsigned)(l0 & 255) | ((unsigned)(l1 & 255) << 8) | ((unsigned)(l2 & 255) << 16) | ((unsigned)l3 << 24);
;             }
.LBB0_421:
	s_or_b64 exec, exec, s[6:7]
	s_waitcnt lgkmcnt(0)
	s_barrier
	v_mbcnt_lo_u32_b32 v0, -1, 0
	v_mbcnt_hi_u32_b32 v0, -1, v0
	s_movk_i32 s4, 0x60
	v_add_u32_e32 v1, s34, v0
	v_ashrrev_i32_e32 v5, 2, v1
	v_lshrrev_b32_e32 v6, 1, v1
	v_lshlrev_b32_e32 v1, 4, v1
	v_bfe_u32 v4, v0, 4, 2
	v_lshlrev_b32_e32 v12, 7, v0
	v_and_b32_e32 v13, 0x1f0, v1
	v_lshlrev_b32_e32 v7, 2, v4
	v_and_or_b32 v148, v12, s29, v13
	s_ashr_i32 s29, s28, 31
	v_readlane_b32 s60, v255, 0
	v_and_or_b32 v12, v6, s4, v7
	s_lshl_b64 s[4:5], s[28:29], 2
	v_readlane_b32 s66, v255, 6
	v_readlane_b32 s67, v255, 7
	s_add_u32 s6, s66, s4
	v_and_b32_e32 v2, 15, v0
	v_and_b32_e32 v3, 63, v0
	v_and_b32_e32 v1, 0xf0, v1
	v_lshlrev_b32_e32 v13, 9, v0
	v_lshlrev_b32_e32 v0, 8, v0
	s_addc_u32 s7, s67, s5
	v_lshlrev_b32_e32 v150, 2, v12
	v_lshl_or_b32 v146, v4, 11, v1
	v_and_or_b32 v156, v5, s2, v2
	v_and_b32_e32 v14, 0x300, v0
	v_lshlrev_b32_e32 v152, 4, v3
	global_load_dwordx4 v[220:223], v150, s[6:7]
	global_load_dwordx4 v[224:227], v150, s[6:7] offset:64
	global_load_dwordx4 v[228:231], v150, s[6:7] offset:512
	global_load_dwordx4 v[232:235], v150, s[6:7] offset:576
	v_readlane_b32 s68, v255, 8
	v_readlane_b32 s69, v255, 9
	s_add_u32 s4, s68, s4
	s_addc_u32 s5, s69, s5
	global_load_dwordx4 v[236:239], v150, s[4:5]
	global_load_dwordx4 v[240:243], v150, s[4:5] offset:64
	global_load_dwordx4 v[244:247], v150, s[4:5] offset:512
	global_load_dwordx4 v[248:251], v150, s[4:5] offset:576
	s_movk_i32 s22, 0x200
	v_lshl_add_u32 v149, v156, 3, v219
	v_add_u32_e32 v147, s46, v152
	s_andn2_b64 vcc, exec, s[14:15]
	s_movk_i32 s40, 0x100
	v_readlane_b32 s61, v255, 1
	v_readlane_b32 s62, v255, 2
	v_readlane_b32 s63, v255, 3
	v_readlane_b32 s64, v255, 4
	v_readlane_b32 s65, v255, 5
	v_readlane_b32 s70, v255, 10
	v_readlane_b32 s71, v255, 11
	v_readlane_b32 s72, v255, 12
	v_readlane_b32 s73, v255, 13
	v_readlane_b32 s74, v255, 14
	v_readlane_b32 s75, v255, 15
	s_waitcnt vmcnt(0)
	v_mov_b32_e32 v0, v220
	v_mov_b32_e32 v1, v221
	v_mov_b32_e32 v2, v222
	v_mov_b32_e32 v3, v223
	v_mov_b32_e32 v4, v236
	v_mov_b32_e32 v5, v237
	v_mov_b32_e32 v6, v238
	v_mov_b32_e32 v7, v239
	v_mov_b32_e32 v22, v1
	v_lshlrev_b32_e32 v1, 1, v12
	v_and_or_b32 v155, v13, s22, v1
	s_mov_b32 s22, 0x10400
	v_mov_b32_e32 v23, v2
	v_or3_b32 v2, v14, v12, s22
	ds_read_b64 v[12:13], v149
	v_mov_b32_e32 v144, v5
	v_mov_b32_e32 v145, v6
	v_mov_b32_e32 v1, v3
	v_mov_b32_e32 v5, v7
	s_waitcnt lgkmcnt(0)
	v_pk_add_f32 v[14:15], v[128:129], v[12:13] op_sel_hi:[1,0] neg_lo:[0,1] neg_hi:[0,1]
	v_pk_add_f32 v[20:21], v[130:131], v[12:13] op_sel_hi:[1,0] neg_lo:[0,1] neg_hi:[0,1]
	v_pk_mul_f32 v[14:15], v[12:13], v[14:15] op_sel:[1,0]
	v_pk_mul_f32 v[12:13], v[12:13], v[20:21] op_sel:[1,0]
	v_pk_fma_f32 v[14:15], v[22:23], v[14:15], v[144:145]
	v_pk_fma_f32 v[6:7], v[0:1], v[12:13], v[4:5]
	v_and_b32_sdwa v12, v14, v216 dst_sel:DWORD dst_unused:UNUSED_PAD src0_sel:WORD_1 src1_sel:DWORD
	v_add3_u32 v12, v14, v12, s82
	v_and_b32_e32 v20, 0xffff0000, v12
	v_and_b32_sdwa v12, v7, v216 dst_sel:DWORD dst_unused:UNUSED_PAD src0_sel:WORD_1 src1_sel:DWORD
	v_and_b32_sdwa v3, v15, v216 dst_sel:DWORD dst_unused:UNUSED_PAD src0_sel:WORD_1 src1_sel:DWORD
	v_and_b32_sdwa v13, v6, v216 dst_sel:DWORD dst_unused:UNUSED_PAD src0_sel:WORD_1 src1_sel:DWORD
	v_add3_u32 v12, v7, v12, s82
	v_lshrrev_b32_e32 v129, 1, v156
	v_add3_u32 v3, v15, v3, s82
	v_add3_u32 v21, v6, v13, s82
	v_and_b32_e32 v128, 0xffff0000, v12
	v_mul_lo_u32 v153, v129, s50
	v_or_b32_sdwa v13, v128, v3 dst_sel:DWORD dst_unused:UNUSED_PAD src0_sel:DWORD src1_sel:WORD_1
	v_or_b32_sdwa v12, v21, v20 dst_sel:DWORD dst_unused:UNUSED_PAD src0_sel:WORD_1 src1_sel:DWORD
	v_add_u32_e32 v151, v155, v153
	ds_write_b64 v151, v[12:13]
	v_and_b32_e32 v12, 0xffff0000, v21
	v_sub_u32_e32 v6, v6, v12
	v_sub_u32_e32 v12, v14, v20
	v_and_b32_e32 v3, 0xffff0000, v3
	v_add_u32_e32 v12, 0x80, v12
	v_sub_u32_e32 v3, v15, v3
	v_sub_u32_e32 v7, v7, v128
	v_add_u32_e32 v6, 0x80, v6
	v_ashrrev_i32_e32 v12, 8, v12
	v_add_u32_e32 v3, 0x80, v3
	v_add_u32_e32 v7, 0x80, v7
	v_ashrrev_i32_e32 v6, 8, v6
	v_min_i32_e32 v12, 0x7f, v12
	v_ashrrev_i32_e32 v3, 8, v3
	v_ashrrev_i32_e32 v7, 8, v7
	v_min_i32_e32 v6, 0x7f, v6
	v_min_i32_sdwa v3, v3, s83 dst_sel:WORD_1 dst_unused:UNUSED_PAD src0_sel:DWORD src1_sel:DWORD
	v_min_i32_e32 v7, 0x7f, v7
	v_lshlrev_b32_e32 v12, 8, v12
	v_and_b32_e32 v12, 0xff00, v12
	v_and_b32_e32 v3, 0xff0000, v3
	v_perm_b32 v6, v7, v6, s84
	v_or3_b32 v3, v6, v12, v3
	v_lshrrev_b32_e32 v6, 2, v156
	v_mad_u64_u32 v[12:13], s[22:23], v6, s50, v[2:3]
	ds_write_b32 v12, v3
	v_or_b32_e32 v3, 16, v156
	v_lshl_add_u32 v13, v3, 3, v219
	ds_read_b64 v[6:7], v13
	s_waitcnt lgkmcnt(0)
;     ...
;             _Pragma("unroll") for (int m = 0; m < 4; ++m) {
;               const int rr = wr3 * 64 + m * 16 + fr3;
;               const float2 ms = *reinterpret_cast<const float2*>(mr + (ai * HALF + rr) * 2);
;               f32x4 y = acc[ai][bj][m][n];
;               const float o0 = (y[0] - ms.x) * ms.y * gm.x + bt.x, o1 = (y[1] - ms.x) * ms.y * gm.y + bt.y;
;               const float o2 = (y[2] - ms.x) * ms.y * gm.z + bt.z, o3 = (y[3] - ms.x) * ms.y * gm.w + bt.w;
;               const unsigned h0 = f2bf(o0), h1 = f2bf(o1), h2 = f2bf(o2), h3 = f2bf(o3);
;               u32x2 ob; ob[0] = h0 | (h1 << 16); ob[1] = h2 | (h3 << 16);
;               *reinterpret_cast<u32x2*>(smem + (rr >> 1) * PIECE + (rr & 1) * 512 + cc * 2) = ob;
;               const int l0 = min(((int)__float_as_uint(o0) - (int)(h0 << 16) + 128) >> 8, 127);
;               const int l1 = min(((int)__float_as_uint(o1) - (int)(h1 << 16) + 128) >> 8, 127);
;               const int l2 = min(((int)__float_as_uint(o2) - (int)(h2 << 16) + 128) >> 8, 127);
;               const int l3 = min(((int)__float_as_uint(o3) - (int)(h3 << 16) + 128) >> 8, 127);
;               *reinterpret_cast<unsigned*>(smem + LOBASE + (rr >> 2) * PIECE + (rr & 3) * 256 + cc) =
;                   (unsigned)(l0 & 255) | ((unsigned)(l1 & 255) << 8) | ((unsigned)(l2 & 255) << 16) | ((unsigned)l3 << 24);
;             }
	v_pk_add_f32 v[14:15], v[134:135], v[6:7] op_sel_hi:[1,0] neg_lo:[0,1] neg_hi:[0,1]
	s_nop 0
	v_pk_mul_f32 v[14:15], v[6:7], v[14:15] op_sel:[1,0]
	v_pk_add_f32 v[20:21], v[132:133], v[6:7] op_sel_hi:[1,0] neg_lo:[0,1] neg_hi:[0,1]
	v_pk_fma_f32 v[14:15], v[22:23], v[14:15], v[144:145]
	v_pk_mul_f32 v[6:7], v[6:7], v[20:21] op_sel:[1,0]
	v_and_b32_sdwa v20, v15, v216 dst_sel:DWORD dst_unused:UNUSED_PAD src0_sel:WORD_1 src1_sel:DWORD
	v_and_b32_sdwa v21, v14, v216 dst_sel:DWORD dst_unused:UNUSED_PAD src0_sel:WORD_1 src1_sel:DWORD
	v_pk_fma_f32 v[6:7], v[0:1], v[6:7], v[4:5]
	v_add3_u32 v128, v15, v20, s82
	v_add3_u32 v20, v14, v21, s82
	v_and_b32_e32 v129, 0xffff0000, v20
	v_and_b32_sdwa v20, v7, v216 dst_sel:DWORD dst_unused:UNUSED_PAD src0_sel:WORD_1 src1_sel:DWORD
	v_and_b32_sdwa v21, v6, v216 dst_sel:DWORD dst_unused:UNUSED_PAD src0_sel:WORD_1 src1_sel:DWORD
	v_add3_u32 v20, v7, v20, s82
	v_lshrrev_b32_e32 v132, 1, v3
	v_add3_u32 v130, v6, v21, s82
	v_and_b32_e32 v131, 0xffff0000, v20
	v_mul_lo_u32 v154, v132, s50
	v_or_b32_sdwa v21, v131, v128 dst_sel:DWORD dst_unused:UNUSED_PAD src0_sel:DWORD src1_sel:WORD_1
	v_or_b32_sdwa v20, v130, v129 dst_sel:DWORD dst_unused:UNUSED_PAD src0_sel:WORD_1 src1_sel:DWORD
	v_add_u32_e32 v132, v155, v154
	ds_write_b64 v132, v[20:21]
	v_and_b32_e32 v20, 0xffff0000, v130
	v_sub_u32_e32 v6, v6, v20
	v_sub_u32_e32 v14, v14, v129
	v_and_b32_e32 v20, 0xffff0000, v128
	v_add_u32_e32 v14, 0x80, v14
	v_sub_u32_e32 v15, v15, v20
	v_sub_u32_e32 v7, v7, v131
	v_add_u32_e32 v6, 0x80, v6
	v_ashrrev_i32_e32 v14, 8, v14
	v_add_u32_e32 v15, 0x80, v15
	v_add_u32_e32 v7, 0x80, v7
	v_ashrrev_i32_e32 v6, 8, v6
	v_min_i32_e32 v14, 0x7f, v14
	v_ashrrev_i32_e32 v15, 8, v15
	v_ashrrev_i32_e32 v7, 8, v7
	v_min_i32_e32 v6, 0x7f, v6
	v_min_i32_sdwa v15, v15, s83 dst_sel:WORD_1 dst_unused:UNUSED_PAD src0_sel:DWORD src1_sel:DWORD
	v_min_i32_e32 v7, 0x7f, v7
	v_lshlrev_b32_e32 v14, 8, v14
	v_and_b32_e32 v14, 0xff00, v14
	v_and_b32_e32 v15, 0xff0000, v15
	v_perm_b32 v6, v7, v6, s84
	v_lshrrev_b32_e32 v3, 2, v3
	v_or3_b32 v6, v6, v14, v15
	v_mad_u64_u32 v[14:15], s[22:23], v3, s50, v[2:3]
	v_or_b32_e32 v3, 32, v156
	ds_write_b32 v14, v6
	v_lshl_add_u32 v15, v3, 3, v219
	ds_read_b64 v[6:7], v15
	v_lshrrev_b32_e32 v133, 1, v3
	v_lshrrev_b32_e32 v3, 2, v3
	s_waitcnt lgkmcnt(0)
	v_pk_add_f32 v[20:21], v[138:139], v[6:7] op_sel_hi:[1,0] neg_lo:[0,1] neg_hi:[0,1]
	s_nop 0
	v_pk_mul_f32 v[20:21], v[6:7], v[20:21] op_sel:[1,0]
	v_pk_add_f32 v[128:129], v[136:137], v[6:7] op_sel_hi:[1,0] neg_lo:[0,1] neg_hi:[0,1]
	v_pk_fma_f32 v[20:21], v[22:23], v[20:21], v[144:145]
	v_pk_mul_f32 v[6:7], v[6:7], v[128:129] op_sel:[1,0]
	v_and_b32_sdwa v128, v21, v216 dst_sel:DWORD dst_unused:UNUSED_PAD src0_sel:WORD_1 src1_sel:DWORD
	v_and_b32_sdwa v129, v20, v216 dst_sel:DWORD dst_unused:UNUSED_PAD src0_sel:WORD_1 src1_sel:DWORD
	v_pk_fma_f32 v[6:7], v[0:1], v[6:7], v[4:5]
	v_add3_u32 v130, v21, v128, s82
	v_add3_u32 v128, v20, v129, s82
	v_and_b32_e32 v131, 0xffff0000, v128
	v_and_b32_sdwa v128, v7, v216 dst_sel:DWORD dst_unused:UNUSED_PAD src0_sel:WORD_1 src1_sel:DWORD
	v_and_b32_sdwa v129, v6, v216 dst_sel:DWORD dst_unused:UNUSED_PAD src0_sel:WORD_1 src1_sel:DWORD
	v_add3_u32 v128, v7, v128, s82
	v_add3_u32 v134, v6, v129, s82
	v_and_b32_e32 v135, 0xffff0000, v128
	v_mul_lo_u32 v136, v133, s50
	v_or_b32_sdwa v129, v135, v130 dst_sel:DWORD dst_unused:UNUSED_PAD src0_sel:DWORD src1_sel:WORD_1
	v_or_b32_sdwa v128, v134, v131 dst_sel:DWORD dst_unused:UNUSED_PAD src0_sel:WORD_1 src1_sel:DWORD
	v_add_u32_e32 v133, v155, v136
	ds_write_b64 v133, v[128:129]
	v_and_b32_e32 v128, 0xffff0000, v134
	v_sub_u32_e32 v6, v6, v128
	v_sub_u32_e32 v20, v20, v131
	v_and_b32_e32 v128, 0xffff0000, v130
	v_add_u32_e32 v20, 0x80, v20
	v_sub_u32_e32 v21, v21, v128
	v_sub_u32_e32 v7, v7, v135
	v_add_u32_e32 v6, 0x80, v6
	v_ashrrev_i32_e32 v20, 8, v20
	v_add_u32_e32 v21, 0x80, v21
	v_add_u32_e32 v7, 0x80, v7
	v_ashrrev_i32_e32 v6, 8, v6
	v_min_i32_e32 v20, 0x7f, v20
	v_ashrrev_i32_e32 v21, 8, v21
	v_ashrrev_i32_e32 v7, 8, v7
	v_min_i32_e32 v6, 0x7f, v6
	v_min_i32_sdwa v21, v21, s83 dst_sel:WORD_1 dst_unused:UNUSED_PAD src0_sel:DWORD src1_sel:DWORD
	v_min_i32_e32 v7, 0x7f, v7
	v_lshlrev_b32_e32 v20, 8, v20
	v_and_b32_e32 v20, 0xff00, v20
	v_and_b32_e32 v21, 0xff0000, v21
	v_perm_b32 v6, v7, v6, s84
	v_or3_b32 v6, v6, v20, v21
	v_mad_u64_u32 v[20:21], s[22:23], v3, s50, v[2:3]
	v_or_b32_e32 v3, 48, v156
	ds_write_b32 v20, v6
	v_lshl_add_u32 v21, v3, 3, v219
	ds_read_b64 v[6:7], v21
	v_lshrrev_b32_e32 v130, 1, v3
	v_mul_lo_u32 v135, v130, s50
	v_add_u32_e32 v134, v155, v135
	s_waitcnt lgkmcnt(0)
;     ...
;             const int cc = bj * HALF + wc3 * 32 + n * 16 + fq3 * 4;
;             const float4 gm = *reinterpret_cast<const float4*>(g.gam + pn * BM + cc), bt = *reinterpret_cast<const float4*>(g.bet + pn * BM + cc);
;             _Pragma("unroll") for (int m = 0; m < 4; ++m) {
;               const int rr = wr3 * 64 + m * 16 + fr3;
;               const float2 ms = *reinterpret_cast<const float2*>(mr + (ai * HALF + rr) * 2);
;               f32x4 y = acc[ai][bj][m][n];
;               const float o0 = (y[0] - ms.x) * ms.y * gm.x + bt.x, o1 = (y[1] - ms.x) * ms.y * gm.y + bt.y;
;               const float o2 = (y[2] - ms.x) * ms.y * gm.z + bt.z, o3 = (y[3] - ms.x) * ms.y * gm.w + bt.w;
;               const unsigned h0 = f2bf(o0), h1 = f2bf(o1), h2 = f2bf(o2), h3 = f2bf(o3);
;               u32x2 ob; ob[0] = h0 | (h1 << 16); ob[1] = h2 | (h3 << 16);
;               *reinterpret_cast<u32x2*>(smem + (rr >> 1) * PIECE + (rr & 1) * 512 + cc * 2) = ob;
;               const int l0 = min(((int)__float_as_uint(o0) - (int)(h0 << 16) + 128) >> 8, 127);
;               const int l1 = min(((int)__float_as_uint(o1) - (int)(h1 << 16) + 128) >> 8, 127);
;               const int l2 = min(((int)__float_as_uint(o2) - (int)(h2 << 16) + 128) >> 8, 127);
;               const int l3 = min(((int)__float_as_uint(o3) - (int)(h3 << 16) + 128) >> 8, 127);
;               *reinterpret_cast<unsigned*>(smem + LOBASE + (rr >> 2) * PIECE + (rr & 3) * 256 + cc) =
;                   (unsigned)(l0 & 255) | ((unsigned)(l1 & 255) << 8) | ((unsigned)(l2 & 255) << 16) | ((unsigned)l3 << 24);
	v_pk_add_f32 v[128:129], v[142:143], v[6:7] op_sel_hi:[1,0] neg_lo:[0,1] neg_hi:[0,1]
	s_nop 0
	v_pk_mul_f32 v[128:129], v[6:7], v[128:129] op_sel:[1,0]
	s_nop 0
	v_pk_fma_f32 v[22:23], v[22:23], v[128:129], v[144:145]
	v_pk_add_f32 v[128:129], v[140:141], v[6:7] op_sel_hi:[1,0] neg_lo:[0,1] neg_hi:[0,1]
	s_nop 0
	v_pk_mul_f32 v[6:7], v[6:7], v[128:129] op_sel:[1,0]
	s_nop 0
	v_pk_fma_f32 v[0:1], v[0:1], v[6:7], v[4:5]
	v_and_b32_sdwa v4, v23, v216 dst_sel:DWORD dst_unused:UNUSED_PAD src0_sel:WORD_1 src1_sel:DWORD
	v_and_b32_sdwa v5, v22, v216 dst_sel:DWORD dst_unused:UNUSED_PAD src0_sel:WORD_1 src1_sel:DWORD
	v_add3_u32 v6, v23, v4, s82
	v_add3_u32 v4, v22, v5, s82
	v_and_b32_e32 v7, 0xffff0000, v4
	v_and_b32_sdwa v4, v1, v216 dst_sel:DWORD dst_unused:UNUSED_PAD src0_sel:WORD_1 src1_sel:DWORD
	v_and_b32_sdwa v5, v0, v216 dst_sel:DWORD dst_unused:UNUSED_PAD src0_sel:WORD_1 src1_sel:DWORD
	v_add3_u32 v4, v1, v4, s82
	v_add3_u32 v128, v0, v5, s82
	v_and_b32_e32 v129, 0xffff0000, v4
	v_or_b32_sdwa v5, v129, v6 dst_sel:DWORD dst_unused:UNUSED_PAD src0_sel:DWORD src1_sel:WORD_1
	v_or_b32_sdwa v4, v128, v7 dst_sel:DWORD dst_unused:UNUSED_PAD src0_sel:WORD_1 src1_sel:DWORD
	ds_write_b64 v134, v[4:5]
	v_and_b32_e32 v4, 0xffff0000, v128
	v_sub_u32_e32 v0, v0, v4
	v_sub_u32_e32 v4, v22, v7
	v_and_b32_e32 v5, 0xffff0000, v6
	v_add_u32_e32 v4, 0x80, v4
	v_sub_u32_e32 v5, v23, v5
	v_sub_u32_e32 v1, v1, v129
	v_add_u32_e32 v0, 0x80, v0
	v_ashrrev_i32_e32 v4, 8, v4
	v_add_u32_e32 v5, 0x80, v5
	v_add_u32_e32 v1, 0x80, v1
	v_ashrrev_i32_e32 v0, 8, v0
	v_min_i32_e32 v4, 0x7f, v4
	v_ashrrev_i32_e32 v5, 8, v5
	v_ashrrev_i32_e32 v1, 8, v1
	v_min_i32_e32 v0, 0x7f, v0
	v_min_i32_sdwa v5, v5, s83 dst_sel:WORD_1 dst_unused:UNUSED_PAD src0_sel:DWORD src1_sel:DWORD
	v_min_i32_e32 v1, 0x7f, v1
	v_lshlrev_b32_e32 v4, 8, v4
	v_and_b32_e32 v4, 0xff00, v4
	v_and_b32_e32 v5, 0xff0000, v5
	v_perm_b32 v0, v1, v0, s84
	v_lshrrev_b32_e32 v1, 2, v3
	v_or3_b32 v0, v0, v4, v5
	v_mad_u64_u32 v[22:23], s[22:23], v1, s50, v[2:3]
	ds_write_b32 v22, v0
	v_mov_b32_e32 v0, v224
	v_mov_b32_e32 v1, v225
	v_mov_b32_e32 v2, v226
	v_mov_b32_e32 v3, v227
	v_mov_b32_e32 v4, v240
	v_mov_b32_e32 v5, v241
	v_mov_b32_e32 v6, v242
	v_mov_b32_e32 v7, v243
	ds_read_b64 v[138:139], v149
	s_mov_b32 s22, s18
	s_mov_b32 s23, s19
	s_waitcnt lgkmcnt(0)
	v_pk_add_f32 v[124:125], v[124:125], v[138:139] op_sel_hi:[1,0] neg_lo:[0,1] neg_hi:[0,1]
	s_nop 0
	v_pk_mul_f32 v[124:125], v[138:139], v[124:125] op_sel:[1,0]
	v_pk_add_f32 v[126:127], v[126:127], v[138:139] op_sel_hi:[1,0] neg_lo:[0,1] neg_hi:[0,1]
	v_mov_b32_e32 v128, v1
	v_mov_b32_e32 v129, v2
	v_mov_b32_e32 v130, v5
	v_mov_b32_e32 v131, v6
	v_pk_fma_f32 v[124:125], v[128:129], v[124:125], v[130:131]
	v_pk_mul_f32 v[126:127], v[138:139], v[126:127] op_sel:[1,0]
	v_mov_b32_e32 v1, v3
	v_mov_b32_e32 v5, v7
	v_and_b32_sdwa v23, v124, v216 dst_sel:DWORD dst_unused:UNUSED_PAD src0_sel:WORD_1 src1_sel:DWORD
	v_pk_fma_f32 v[6:7], v[0:1], v[126:127], v[4:5]
	v_add3_u32 v23, v124, v23, s82
	v_and_b32_e32 v137, 0xffff0000, v23
	v_and_b32_sdwa v23, v7, v216 dst_sel:DWORD dst_unused:UNUSED_PAD src0_sel:WORD_1 src1_sel:DWORD
	v_and_b32_sdwa v3, v125, v216 dst_sel:DWORD dst_unused:UNUSED_PAD src0_sel:WORD_1 src1_sel:DWORD
	v_and_b32_sdwa v126, v6, v216 dst_sel:DWORD dst_unused:UNUSED_PAD src0_sel:WORD_1 src1_sel:DWORD
	v_add3_u32 v23, v7, v23, s82
	v_or_b32_e32 v2, 32, v155
	v_add3_u32 v3, v125, v3, s82
	v_add3_u32 v138, v6, v126, s82
	v_and_b32_e32 v139, 0xffff0000, v23
	v_or_b32_sdwa v127, v139, v3 dst_sel:DWORD dst_unused:UNUSED_PAD src0_sel:DWORD src1_sel:WORD_1
	v_or_b32_sdwa v126, v138, v137 dst_sel:DWORD dst_unused:UNUSED_PAD src0_sel:WORD_1 src1_sel:DWORD
	v_add_u32_e32 v23, v2, v153
	ds_write_b64 v23, v[126:127]
	v_and_b32_e32 v126, 0xffff0000, v138
	v_sub_u32_e32 v124, v124, v137
	v_and_b32_e32 v3, 0xffff0000, v3
	v_sub_u32_e32 v6, v6, v126
	v_add_u32_e32 v124, 0x80, v124
	v_sub_u32_e32 v3, v125, v3
	v_sub_u32_e32 v7, v7, v139
	v_add_u32_e32 v6, 0x80, v6
	v_ashrrev_i32_e32 v124, 8, v124
	v_add_u32_e32 v3, 0x80, v3
	v_add_u32_e32 v7, 0x80, v7
	v_ashrrev_i32_e32 v6, 8, v6
	v_min_i32_e32 v124, 0x7f, v124
	v_ashrrev_i32_e32 v3, 8, v3
	v_ashrrev_i32_e32 v7, 8, v7
	v_min_i32_e32 v6, 0x7f, v6
	v_min_i32_sdwa v3, v3, s83 dst_sel:WORD_1 dst_unused:UNUSED_PAD src0_sel:DWORD src1_sel:DWORD
	v_min_i32_e32 v7, 0x7f, v7
	v_lshlrev_b32_e32 v124, 8, v124
	v_and_b32_e32 v124, 0xff00, v124
	v_and_b32_e32 v3, 0xff0000, v3
	v_perm_b32 v6, v7, v6, s84
	v_or3_b32 v3, v6, v124, v3
	ds_write_b32 v12, v3 offset:16
	ds_read_b64 v[6:7], v13
	s_waitcnt lgkmcnt(0)
;     ...
;             const int cc = bj * HALF + wc3 * 32 + n * 16 + fq3 * 4;
;             const float4 gm = *reinterpret_cast<const float4*>(g.gam + pn * BM + cc), bt = *reinterpret_cast<const float4*>(g.bet + pn * BM + cc);
;             _Pragma("unroll") for (int m = 0; m < 4; ++m) {
;               const int rr = wr3 * 64 + m * 16 + fr3;
;               const float2 ms = *reinterpret_cast<const float2*>(mr + (ai * HALF + rr) * 2);
;               f32x4 y = acc[ai][bj][m][n];
;               const float o0 = (y[0] - ms.x) * ms.y * gm.x + bt.x, o1 = (y[1] - ms.x) * ms.y * gm.y + bt.y;
;               const float o2 = (y[2] - ms.x) * ms.y * gm.z + bt.z, o3 = (y[3] - ms.x) * ms.y * gm.w + bt.w;
;               const unsigned h0 = f2bf(o0), h1 = f2bf(o1), h2 = f2bf(o2), h3 = f2bf(o3);
;               u32x2 ob; ob[0] = h0 | (h1 << 16); ob[1] = h2 | (h3 << 16);
;               *reinterpret_cast<u32x2*>(smem + (rr >> 1) * PIECE + (rr & 1) * 512 + cc * 2) = ob;
;               const int l0 = min(((int)__float_as_uint(o0) - (int)(h0 << 16) + 128) >> 8, 127);
;               const int l1 = min(((int)__float_as_uint(o1) - (int)(h1 << 16) + 128) >> 8, 127);
;               const int l2 = min(((int)__float_as_uint(o2) - (int)(h2 << 16) + 128) >> 8, 127);
;               const int l3 = min(((int)__float_as_uint(o3) - (int)(h3 << 16) + 128) >> 8, 127);
;               *reinterpret_cast<unsigned*>(smem + LOBASE + (rr >> 2) * PIECE + (rr & 3) * 256 + cc) =
;                   (unsigned)(l0 & 255) | ((unsigned)(l1 & 255) << 8) | ((unsigned)(l2 & 255) << 16) | ((unsigned)l3 << 24);
	v_pk_add_f32 v[106:107], v[106:107], v[6:7] op_sel_hi:[1,0] neg_lo:[0,1] neg_hi:[0,1]
	s_nop 0
	v_pk_mul_f32 v[106:107], v[6:7], v[106:107] op_sel:[1,0]
	v_pk_add_f32 v[104:105], v[104:105], v[6:7] op_sel_hi:[1,0] neg_lo:[0,1] neg_hi:[0,1]
	v_pk_fma_f32 v[106:107], v[128:129], v[106:107], v[130:131]
	v_pk_mul_f32 v[6:7], v[6:7], v[104:105] op_sel:[1,0]
	v_and_b32_sdwa v104, v106, v216 dst_sel:DWORD dst_unused:UNUSED_PAD src0_sel:WORD_1 src1_sel:DWORD
	v_pk_fma_f32 v[6:7], v[0:1], v[6:7], v[4:5]
	v_add3_u32 v104, v106, v104, s82
	v_and_b32_e32 v105, 0xffff0000, v104
	v_and_b32_sdwa v104, v7, v216 dst_sel:DWORD dst_unused:UNUSED_PAD src0_sel:WORD_1 src1_sel:DWORD
	v_and_b32_sdwa v3, v107, v216 dst_sel:DWORD dst_unused:UNUSED_PAD src0_sel:WORD_1 src1_sel:DWORD
	v_and_b32_sdwa v124, v6, v216 dst_sel:DWORD dst_unused:UNUSED_PAD src0_sel:WORD_1 src1_sel:DWORD
	v_add3_u32 v104, v7, v104, s82
	v_add3_u32 v3, v107, v3, s82
	v_add3_u32 v126, v6, v124, s82
	v_and_b32_e32 v127, 0xffff0000, v104
	v_or_b32_sdwa v125, v127, v3 dst_sel:DWORD dst_unused:UNUSED_PAD src0_sel:DWORD src1_sel:WORD_1
	v_or_b32_sdwa v124, v126, v105 dst_sel:DWORD dst_unused:UNUSED_PAD src0_sel:WORD_1 src1_sel:DWORD
	v_add_u32_e32 v104, v2, v154
	ds_write_b64 v104, v[124:125]
	v_and_b32_e32 v124, 0xffff0000, v126
	v_sub_u32_e32 v105, v106, v105
	v_and_b32_e32 v3, 0xffff0000, v3
	v_sub_u32_e32 v6, v6, v124
	v_add_u32_e32 v105, 0x80, v105
	v_sub_u32_e32 v3, v107, v3
	v_sub_u32_e32 v7, v7, v127
	v_add_u32_e32 v6, 0x80, v6
	v_ashrrev_i32_e32 v105, 8, v105
	v_add_u32_e32 v3, 0x80, v3
	v_add_u32_e32 v7, 0x80, v7
	v_ashrrev_i32_e32 v6, 8, v6
	v_min_i32_e32 v105, 0x7f, v105
	v_ashrrev_i32_e32 v3, 8, v3
	v_ashrrev_i32_e32 v7, 8, v7
	v_min_i32_e32 v6, 0x7f, v6
	v_min_i32_sdwa v3, v3, s83 dst_sel:WORD_1 dst_unused:UNUSED_PAD src0_sel:DWORD src1_sel:DWORD
	v_min_i32_e32 v7, 0x7f, v7
	v_lshlrev_b32_e32 v105, 8, v105
	v_and_b32_e32 v105, 0xff00, v105
	v_and_b32_e32 v3, 0xff0000, v3
	v_perm_b32 v6, v7, v6, s84
	v_or3_b32 v3, v6, v105, v3
	ds_write_b32 v14, v3 offset:16
	ds_read_b64 v[6:7], v15
	s_waitcnt lgkmcnt(0)
	v_pk_add_f32 v[106:107], v[110:111], v[6:7] op_sel_hi:[1,0] neg_lo:[0,1] neg_hi:[0,1]
	s_nop 0
	v_pk_mul_f32 v[106:107], v[6:7], v[106:107] op_sel:[1,0]
	v_pk_add_f32 v[108:109], v[108:109], v[6:7] op_sel_hi:[1,0] neg_lo:[0,1] neg_hi:[0,1]
	v_pk_fma_f32 v[106:107], v[128:129], v[106:107], v[130:131]
	v_pk_mul_f32 v[6:7], v[6:7], v[108:109] op_sel:[1,0]
	v_and_b32_sdwa v105, v106, v216 dst_sel:DWORD dst_unused:UNUSED_PAD src0_sel:WORD_1 src1_sel:DWORD
	v_pk_fma_f32 v[6:7], v[0:1], v[6:7], v[4:5]
	v_add3_u32 v105, v106, v105, s82
	v_and_b32_e32 v110, 0xffff0000, v105
	v_and_b32_sdwa v105, v7, v216 dst_sel:DWORD dst_unused:UNUSED_PAD src0_sel:WORD_1 src1_sel:DWORD
	v_and_b32_sdwa v3, v107, v216 dst_sel:DWORD dst_unused:UNUSED_PAD src0_sel:WORD_1 src1_sel:DWORD
	v_and_b32_sdwa v108, v6, v216 dst_sel:DWORD dst_unused:UNUSED_PAD src0_sel:WORD_1 src1_sel:DWORD
	v_add3_u32 v105, v7, v105, s82
	v_add3_u32 v3, v107, v3, s82
	v_add3_u32 v111, v6, v108, s82
	v_and_b32_e32 v124, 0xffff0000, v105
	v_or_b32_sdwa v109, v124, v3 dst_sel:DWORD dst_unused:UNUSED_PAD src0_sel:DWORD src1_sel:WORD_1
	v_or_b32_sdwa v108, v111, v110 dst_sel:DWORD dst_unused:UNUSED_PAD src0_sel:WORD_1 src1_sel:DWORD
	v_add_u32_e32 v105, v2, v136
	ds_write_b64 v105, v[108:109]
	v_and_b32_e32 v108, 0xffff0000, v111
	v_sub_u32_e32 v106, v106, v110
	v_and_b32_e32 v3, 0xffff0000, v3
	v_sub_u32_e32 v6, v6, v108
	v_add_u32_e32 v106, 0x80, v106
	v_sub_u32_e32 v3, v107, v3
	v_sub_u32_e32 v7, v7, v124
	v_add_u32_e32 v6, 0x80, v6
	v_ashrrev_i32_e32 v106, 8, v106
	v_add_u32_e32 v3, 0x80, v3
	v_add_u32_e32 v7, 0x80, v7
	v_ashrrev_i32_e32 v6, 8, v6
	v_min_i32_e32 v106, 0x7f, v106
	v_ashrrev_i32_e32 v3, 8, v3
	v_ashrrev_i32_e32 v7, 8, v7
	v_min_i32_e32 v6, 0x7f, v6
	v_min_i32_sdwa v3, v3, s83 dst_sel:WORD_1 dst_unused:UNUSED_PAD src0_sel:DWORD src1_sel:DWORD
	v_min_i32_e32 v7, 0x7f, v7
	v_lshlrev_b32_e32 v106, 8, v106
	v_and_b32_e32 v106, 0xff00, v106
	v_and_b32_e32 v3, 0xff0000, v3
	v_perm_b32 v6, v7, v6, s84
	v_or3_b32 v3, v6, v106, v3
	ds_write_b32 v20, v3 offset:16
	ds_read_b64 v[6:7], v21
	s_waitcnt lgkmcnt(0)
	v_pk_add_f32 v[106:107], v[122:123], v[6:7] op_sel_hi:[1,0] neg_lo:[0,1] neg_hi:[0,1]
	s_nop 0
	v_pk_mul_f32 v[106:107], v[6:7], v[106:107] op_sel:[1,0]
	v_or_b32_e32 v122, 0x100, v155
	v_pk_fma_f32 v[108:109], v[128:129], v[106:107], v[130:131]
	v_pk_add_f32 v[106:107], v[114:115], v[6:7] op_sel_hi:[1,0] neg_lo:[0,1] neg_hi:[0,1]
	v_and_b32_sdwa v3, v109, v216 dst_sel:DWORD dst_unused:UNUSED_PAD src0_sel:WORD_1 src1_sel:DWORD
	v_pk_mul_f32 v[6:7], v[6:7], v[106:107] op_sel:[1,0]
	v_add3_u32 v3, v109, v3, s82
	v_pk_fma_f32 v[0:1], v[0:1], v[6:7], v[4:5]
	v_and_b32_sdwa v4, v108, v216 dst_sel:DWORD dst_unused:UNUSED_PAD src0_sel:WORD_1 src1_sel:DWORD
	v_add3_u32 v4, v108, v4, s82
	v_and_b32_e32 v6, 0xffff0000, v4
	v_and_b32_sdwa v4, v1, v216 dst_sel:DWORD dst_unused:UNUSED_PAD src0_sel:WORD_1 src1_sel:DWORD
	v_and_b32_sdwa v5, v0, v216 dst_sel:DWORD dst_unused:UNUSED_PAD src0_sel:WORD_1 src1_sel:DWORD
	v_add3_u32 v4, v1, v4, s82
	v_add3_u32 v7, v0, v5, s82
	v_and_b32_e32 v107, 0xffff0000, v4
	v_add_u32_e32 v106, v2, v135
	v_and_b32_e32 v2, 0xffff0000, v7
	v_or_b32_sdwa v5, v107, v3 dst_sel:DWORD dst_unused:UNUSED_PAD src0_sel:DWORD src1_sel:WORD_1
	v_sub_u32_e32 v0, v0, v2
	v_sub_u32_e32 v2, v108, v6
	v_and_b32_e32 v3, 0xffff0000, v3
	v_add_u32_e32 v2, 0x80, v2
	v_sub_u32_e32 v3, v109, v3
	v_sub_u32_e32 v1, v1, v107
	v_add_u32_e32 v0, 0x80, v0
	v_ashrrev_i32_e32 v2, 8, v2
	v_add_u32_e32 v3, 0x80, v3
	v_add_u32_e32 v1, 0x80, v1
	v_ashrrev_i32_e32 v0, 8, v0
	v_min_i32_e32 v2, 0x7f, v2
	v_ashrrev_i32_e32 v3, 8, v3
	v_ashrrev_i32_e32 v1, 8, v1
	v_min_i32_e32 v0, 0x7f, v0
	v_min_i32_sdwa v3, v3, s83 dst_sel:WORD_1 dst_unused:UNUSED_PAD src0_sel:DWORD src1_sel:DWORD
	v_min_i32_e32 v1, 0x7f, v1
	v_lshlrev_b32_e32 v2, 8, v2
	v_and_b32_e32 v2, 0xff00, v2
	v_and_b32_e32 v3, 0xff0000, v3
	v_perm_b32 v0, v1, v0, s84
	v_or_b32_sdwa v4, v7, v6 dst_sel:DWORD dst_unused:UNUSED_PAD src0_sel:WORD_1 src1_sel:DWORD
	v_or3_b32 v0, v0, v2, v3
	ds_write_b64 v106, v[4:5]
	ds_write_b32 v22, v0 offset:16
	v_mov_b32_e32 v0, v228
	v_mov_b32_e32 v1, v229
	v_mov_b32_e32 v2, v230
	v_mov_b32_e32 v3, v231
	v_mov_b32_e32 v4, v244
	v_mov_b32_e32 v5, v245
	v_mov_b32_e32 v6, v246
	v_mov_b32_e32 v7, v247
	ds_read_b64 v[114:115], v149
	v_add_u32_e32 v107, v122, v153
	s_waitcnt lgkmcnt(0)
;     ...
;             const int cc = bj * HALF + wc3 * 32 + n * 16 + fq3 * 4;
;             const float4 gm = *reinterpret_cast<const float4*>(g.gam + pn * BM + cc), bt = *reinterpret_cast<const float4*>(g.bet + pn * BM + cc);
;             _Pragma("unroll") for (int m = 0; m < 4; ++m) {
;               const int rr = wr3 * 64 + m * 16 + fr3;
;               const float2 ms = *reinterpret_cast<const float2*>(mr + (ai * HALF + rr) * 2);
;               f32x4 y = acc[ai][bj][m][n];
;               const float o0 = (y[0] - ms.x) * ms.y * gm.x + bt.x, o1 = (y[1] - ms.x) * ms.y * gm.y + bt.y;
;               const float o2 = (y[2] - ms.x) * ms.y * gm.z + bt.z, o3 = (y[3] - ms.x) * ms.y * gm.w + bt.w;
;               const unsigned h0 = f2bf(o0), h1 = f2bf(o1), h2 = f2bf(o2), h3 = f2bf(o3);
;               u32x2 ob; ob[0] = h0 | (h1 << 16); ob[1] = h2 | (h3 << 16);
;               *reinterpret_cast<u32x2*>(smem + (rr >> 1) * PIECE + (rr & 1) * 512 + cc * 2) = ob;
;               const int l0 = min(((int)__float_as_uint(o0) - (int)(h0 << 16) + 128) >> 8, 127);
;               const int l1 = min(((int)__float_as_uint(o1) - (int)(h1 << 16) + 128) >> 8, 127);
;               const int l2 = min(((int)__float_as_uint(o2) - (int)(h2 << 16) + 128) >> 8, 127);
;               const int l3 = min(((int)__float_as_uint(o3) - (int)(h3 << 16) + 128) >> 8, 127);
;               *reinterpret_cast<unsigned*>(smem + LOBASE + (rr >> 2) * PIECE + (rr & 3) * 256 + cc) =
;                   (unsigned)(l0 & 255) | ((unsigned)(l1 & 255) << 8) | ((unsigned)(l2 & 255) << 16) | ((unsigned)l3 << 24);
	v_pk_add_f32 v[118:119], v[118:119], v[114:115] op_sel_hi:[1,0] neg_lo:[0,1] neg_hi:[0,1]
	s_nop 0
	v_pk_mul_f32 v[118:119], v[114:115], v[118:119] op_sel:[1,0]
	v_pk_add_f32 v[120:121], v[120:121], v[114:115] op_sel_hi:[1,0] neg_lo:[0,1] neg_hi:[0,1]
	v_mov_b32_e32 v108, v1
	v_mov_b32_e32 v109, v2
	v_mov_b32_e32 v110, v5
	v_mov_b32_e32 v111, v6
	v_pk_fma_f32 v[118:119], v[108:109], v[118:119], v[110:111]
	v_pk_mul_f32 v[114:115], v[114:115], v[120:121] op_sel:[1,0]
	v_mov_b32_e32 v1, v3
	v_mov_b32_e32 v5, v7
	v_and_b32_sdwa v6, v119, v216 dst_sel:DWORD dst_unused:UNUSED_PAD src0_sel:WORD_1 src1_sel:DWORD
	v_and_b32_sdwa v7, v118, v216 dst_sel:DWORD dst_unused:UNUSED_PAD src0_sel:WORD_1 src1_sel:DWORD
	v_pk_fma_f32 v[2:3], v[0:1], v[114:115], v[4:5]
	v_add3_u32 v114, v119, v6, s82
	v_add3_u32 v6, v118, v7, s82
	v_and_b32_e32 v115, 0xffff0000, v6
	v_and_b32_sdwa v6, v3, v216 dst_sel:DWORD dst_unused:UNUSED_PAD src0_sel:WORD_1 src1_sel:DWORD
	v_and_b32_sdwa v7, v2, v216 dst_sel:DWORD dst_unused:UNUSED_PAD src0_sel:WORD_1 src1_sel:DWORD
	v_add3_u32 v6, v3, v6, s82
	v_add3_u32 v120, v2, v7, s82
	v_and_b32_e32 v121, 0xffff0000, v6
	v_or_b32_sdwa v7, v121, v114 dst_sel:DWORD dst_unused:UNUSED_PAD src0_sel:DWORD src1_sel:WORD_1
	v_or_b32_sdwa v6, v120, v115 dst_sel:DWORD dst_unused:UNUSED_PAD src0_sel:WORD_1 src1_sel:DWORD
	ds_write_b64 v107, v[6:7]
	v_and_b32_e32 v6, 0xffff0000, v120
	v_sub_u32_e32 v2, v2, v6
	v_sub_u32_e32 v6, v118, v115
	v_and_b32_e32 v7, 0xffff0000, v114
	v_add_u32_e32 v6, 0x80, v6
	v_sub_u32_e32 v7, v119, v7
	v_sub_u32_e32 v3, v3, v121
	v_add_u32_e32 v2, 0x80, v2
	v_ashrrev_i32_e32 v6, 8, v6
	v_add_u32_e32 v7, 0x80, v7
	v_add_u32_e32 v3, 0x80, v3
	v_ashrrev_i32_e32 v2, 8, v2
	v_min_i32_e32 v6, 0x7f, v6
	v_ashrrev_i32_e32 v7, 8, v7
	v_ashrrev_i32_e32 v3, 8, v3
	v_min_i32_e32 v2, 0x7f, v2
	v_min_i32_sdwa v7, v7, s83 dst_sel:WORD_1 dst_unused:UNUSED_PAD src0_sel:DWORD src1_sel:DWORD
	v_min_i32_e32 v3, 0x7f, v3
	v_lshlrev_b32_e32 v6, 8, v6
	v_and_b32_e32 v6, 0xff00, v6
	v_and_b32_e32 v7, 0xff0000, v7
	v_perm_b32 v2, v3, v2, s84
	v_or3_b32 v2, v2, v6, v7
	ds_write_b32 v12, v2 offset:128
	ds_read_b64 v[2:3], v13
	s_waitcnt lgkmcnt(0)
	v_pk_add_f32 v[6:7], v[102:103], v[2:3] op_sel_hi:[1,0] neg_lo:[0,1] neg_hi:[0,1]
	s_nop 0
	v_pk_mul_f32 v[6:7], v[2:3], v[6:7] op_sel:[1,0]
	v_pk_add_f32 v[100:101], v[100:101], v[2:3] op_sel_hi:[1,0] neg_lo:[0,1] neg_hi:[0,1]
	v_pk_fma_f32 v[6:7], v[108:109], v[6:7], v[110:111]
	v_pk_mul_f32 v[2:3], v[2:3], v[100:101] op_sel:[1,0]
	v_and_b32_sdwa v100, v7, v216 dst_sel:DWORD dst_unused:UNUSED_PAD src0_sel:WORD_1 src1_sel:DWORD
	v_and_b32_sdwa v101, v6, v216 dst_sel:DWORD dst_unused:UNUSED_PAD src0_sel:WORD_1 src1_sel:DWORD
	v_pk_fma_f32 v[2:3], v[0:1], v[2:3], v[4:5]
	v_add3_u32 v114, v7, v100, s82
	v_add3_u32 v100, v6, v101, s82
	v_and_b32_e32 v101, 0xffff0000, v100
	v_and_b32_sdwa v100, v3, v216 dst_sel:DWORD dst_unused:UNUSED_PAD src0_sel:WORD_1 src1_sel:DWORD
	v_and_b32_sdwa v102, v2, v216 dst_sel:DWORD dst_unused:UNUSED_PAD src0_sel:WORD_1 src1_sel:DWORD
	v_add3_u32 v100, v3, v100, s82
	v_add3_u32 v115, v2, v102, s82
	v_and_b32_e32 v118, 0xffff0000, v100
	v_or_b32_sdwa v103, v118, v114 dst_sel:DWORD dst_unused:UNUSED_PAD src0_sel:DWORD src1_sel:WORD_1
	v_or_b32_sdwa v102, v115, v101 dst_sel:DWORD dst_unused:UNUSED_PAD src0_sel:WORD_1 src1_sel:DWORD
	v_add_u32_e32 v100, v122, v154
	ds_write_b64 v100, v[102:103]
	v_and_b32_e32 v102, 0xffff0000, v115
	v_sub_u32_e32 v6, v6, v101
	v_and_b32_e32 v101, 0xffff0000, v114
	v_sub_u32_e32 v2, v2, v102
	v_add_u32_e32 v6, 0x80, v6
	v_sub_u32_e32 v7, v7, v101
	v_sub_u32_e32 v3, v3, v118
	v_add_u32_e32 v2, 0x80, v2
	v_ashrrev_i32_e32 v6, 8, v6
	v_add_u32_e32 v7, 0x80, v7
	v_add_u32_e32 v3, 0x80, v3
	v_ashrrev_i32_e32 v2, 8, v2
	v_min_i32_e32 v6, 0x7f, v6
	v_ashrrev_i32_e32 v7, 8, v7
	v_ashrrev_i32_e32 v3, 8, v3
	v_min_i32_e32 v2, 0x7f, v2
	v_min_i32_sdwa v7, v7, s83 dst_sel:WORD_1 dst_unused:UNUSED_PAD src0_sel:DWORD src1_sel:DWORD
	v_min_i32_e32 v3, 0x7f, v3
	v_lshlrev_b32_e32 v6, 8, v6
	v_and_b32_e32 v6, 0xff00, v6
	v_and_b32_e32 v7, 0xff0000, v7
	v_perm_b32 v2, v3, v2, s84
	v_or3_b32 v2, v2, v6, v7
	ds_write_b32 v14, v2 offset:128
	ds_read_b64 v[2:3], v15
	v_add_u32_e32 v101, v122, v136
	s_waitcnt lgkmcnt(0)
	v_pk_add_f32 v[6:7], v[90:91], v[2:3] op_sel_hi:[1,0] neg_lo:[0,1] neg_hi:[0,1]
	s_nop 0
	v_pk_mul_f32 v[6:7], v[2:3], v[6:7] op_sel:[1,0]
	v_pk_add_f32 v[88:89], v[88:89], v[2:3] op_sel_hi:[1,0] neg_lo:[0,1] neg_hi:[0,1]
	v_pk_fma_f32 v[6:7], v[108:109], v[6:7], v[110:111]
	v_pk_mul_f32 v[2:3], v[2:3], v[88:89] op_sel:[1,0]
	v_and_b32_sdwa v88, v7, v216 dst_sel:DWORD dst_unused:UNUSED_PAD src0_sel:WORD_1 src1_sel:DWORD
	v_and_b32_sdwa v89, v6, v216 dst_sel:DWORD dst_unused:UNUSED_PAD src0_sel:WORD_1 src1_sel:DWORD
	v_pk_fma_f32 v[2:3], v[0:1], v[2:3], v[4:5]
	v_add3_u32 v90, v7, v88, s82
	v_add3_u32 v88, v6, v89, s82
	v_and_b32_e32 v91, 0xffff0000, v88
	v_and_b32_sdwa v88, v3, v216 dst_sel:DWORD dst_unused:UNUSED_PAD src0_sel:WORD_1 src1_sel:DWORD
	v_and_b32_sdwa v89, v2, v216 dst_sel:DWORD dst_unused:UNUSED_PAD src0_sel:WORD_1 src1_sel:DWORD
	v_add3_u32 v88, v3, v88, s82
	v_add3_u32 v102, v2, v89, s82
	v_and_b32_e32 v103, 0xffff0000, v88
	v_or_b32_sdwa v89, v103, v90 dst_sel:DWORD dst_unused:UNUSED_PAD src0_sel:DWORD src1_sel:WORD_1
	v_or_b32_sdwa v88, v102, v91 dst_sel:DWORD dst_unused:UNUSED_PAD src0_sel:WORD_1 src1_sel:DWORD
	ds_write_b64 v101, v[88:89]
	v_and_b32_e32 v88, 0xffff0000, v102
	v_sub_u32_e32 v2, v2, v88
	v_sub_u32_e32 v6, v6, v91
	v_and_b32_e32 v88, 0xffff0000, v90
	v_add_u32_e32 v6, 0x80, v6
	v_sub_u32_e32 v7, v7, v88
	v_sub_u32_e32 v3, v3, v103
	v_add_u32_e32 v2, 0x80, v2
	v_ashrrev_i32_e32 v6, 8, v6
	v_add_u32_e32 v7, 0x80, v7
	v_add_u32_e32 v3, 0x80, v3
	v_ashrrev_i32_e32 v2, 8, v2
	v_min_i32_e32 v6, 0x7f, v6
	v_ashrrev_i32_e32 v7, 8, v7
	v_ashrrev_i32_e32 v3, 8, v3
	v_min_i32_e32 v2, 0x7f, v2
	v_min_i32_sdwa v7, v7, s83 dst_sel:WORD_1 dst_unused:UNUSED_PAD src0_sel:DWORD src1_sel:DWORD
	v_min_i32_e32 v3, 0x7f, v3
	v_lshlrev_b32_e32 v6, 8, v6
	v_and_b32_e32 v6, 0xff00, v6
	v_and_b32_e32 v7, 0xff0000, v7
	v_perm_b32 v2, v3, v2, s84
	v_or3_b32 v2, v2, v6, v7
	ds_write_b32 v20, v2 offset:128
	ds_read_b64 v[2:3], v21
	s_waitcnt lgkmcnt(0)
;     ...
;             const int cc = bj * HALF + wc3 * 32 + n * 16 + fq3 * 4;
;             const float4 gm = *reinterpret_cast<const float4*>(g.gam + pn * BM + cc), bt = *reinterpret_cast<const float4*>(g.bet + pn * BM + cc);
;             _Pragma("unroll") for (int m = 0; m < 4; ++m) {
;               const int rr = wr3 * 64 + m * 16 + fr3;
;               const float2 ms = *reinterpret_cast<const float2*>(mr + (ai * HALF + rr) * 2);
;               f32x4 y = acc[ai][bj][m][n];
;               const float o0 = (y[0] - ms.x) * ms.y * gm.x + bt.x, o1 = (y[1] - ms.x) * ms.y * gm.y + bt.y;
;               const float o2 = (y[2] - ms.x) * ms.y * gm.z + bt.z, o3 = (y[3] - ms.x) * ms.y * gm.w + bt.w;
;               const unsigned h0 = f2bf(o0), h1 = f2bf(o1), h2 = f2bf(o2), h3 = f2bf(o3);
;               u32x2 ob; ob[0] = h0 | (h1 << 16); ob[1] = h2 | (h3 << 16);
;               *reinterpret_cast<u32x2*>(smem + (rr >> 1) * PIECE + (rr & 1) * 512 + cc * 2) = ob;
;               const int l0 = min(((int)__float_as_uint(o0) - (int)(h0 << 16) + 128) >> 8, 127);
;               const int l1 = min(((int)__float_as_uint(o1) - (int)(h1 << 16) + 128) >> 8, 127);
;               const int l2 = min(((int)__float_as_uint(o2) - (int)(h2 << 16) + 128) >> 8, 127);
;               const int l3 = min(((int)__float_as_uint(o3) - (int)(h3 << 16) + 128) >> 8, 127);
;               *reinterpret_cast<unsigned*>(smem + LOBASE + (rr >> 2) * PIECE + (rr & 3) * 256 + cc) =
;                   (unsigned)(l0 & 255) | ((unsigned)(l1 & 255) << 8) | ((unsigned)(l2 & 255) << 16) | ((unsigned)l3 << 24);
	v_pk_add_f32 v[6:7], v[94:95], v[2:3] op_sel_hi:[1,0] neg_lo:[0,1] neg_hi:[0,1]
	s_nop 0
	v_pk_mul_f32 v[6:7], v[2:3], v[6:7] op_sel:[1,0]
	v_pk_add_f32 v[88:89], v[92:93], v[2:3] op_sel_hi:[1,0] neg_lo:[0,1] neg_hi:[0,1]
	v_pk_fma_f32 v[6:7], v[108:109], v[6:7], v[110:111]
	v_pk_mul_f32 v[2:3], v[2:3], v[88:89] op_sel:[1,0]
	v_add_u32_e32 v92, v122, v135
	v_pk_fma_f32 v[0:1], v[0:1], v[2:3], v[4:5]
	v_and_b32_sdwa v2, v7, v216 dst_sel:DWORD dst_unused:UNUSED_PAD src0_sel:WORD_1 src1_sel:DWORD
	v_and_b32_sdwa v3, v6, v216 dst_sel:DWORD dst_unused:UNUSED_PAD src0_sel:WORD_1 src1_sel:DWORD
	v_add3_u32 v4, v7, v2, s82
	v_add3_u32 v2, v6, v3, s82
	v_and_b32_e32 v5, 0xffff0000, v2
	v_and_b32_sdwa v2, v1, v216 dst_sel:DWORD dst_unused:UNUSED_PAD src0_sel:WORD_1 src1_sel:DWORD
	v_and_b32_sdwa v3, v0, v216 dst_sel:DWORD dst_unused:UNUSED_PAD src0_sel:WORD_1 src1_sel:DWORD
	v_add3_u32 v2, v1, v2, s82
	v_add3_u32 v88, v0, v3, s82
	v_and_b32_e32 v89, 0xffff0000, v2
	v_or_b32_sdwa v3, v89, v4 dst_sel:DWORD dst_unused:UNUSED_PAD src0_sel:DWORD src1_sel:WORD_1
	v_or_b32_sdwa v2, v88, v5 dst_sel:DWORD dst_unused:UNUSED_PAD src0_sel:WORD_1 src1_sel:DWORD
	ds_write_b64 v92, v[2:3]
	v_and_b32_e32 v2, 0xffff0000, v88
	v_sub_u32_e32 v0, v0, v2
	v_sub_u32_e32 v2, v6, v5
	v_and_b32_e32 v3, 0xffff0000, v4
	v_add_u32_e32 v2, 0x80, v2
	v_sub_u32_e32 v3, v7, v3
	v_sub_u32_e32 v1, v1, v89
	v_add_u32_e32 v0, 0x80, v0
	v_ashrrev_i32_e32 v2, 8, v2
	v_add_u32_e32 v3, 0x80, v3
	v_add_u32_e32 v1, 0x80, v1
	v_ashrrev_i32_e32 v0, 8, v0
	v_min_i32_e32 v2, 0x7f, v2
	v_ashrrev_i32_e32 v3, 8, v3
	v_ashrrev_i32_e32 v1, 8, v1
	v_min_i32_e32 v0, 0x7f, v0
	v_min_i32_sdwa v3, v3, s83 dst_sel:WORD_1 dst_unused:UNUSED_PAD src0_sel:DWORD src1_sel:DWORD
	v_min_i32_e32 v1, 0x7f, v1
	v_lshlrev_b32_e32 v2, 8, v2
	v_and_b32_e32 v2, 0xff00, v2
	v_and_b32_e32 v3, 0xff0000, v3
	v_perm_b32 v0, v1, v0, s84
	v_or3_b32 v0, v0, v2, v3
	ds_write_b32 v22, v0 offset:128
	v_mov_b32_e32 v0, v232
	v_mov_b32_e32 v1, v233
	v_mov_b32_e32 v2, v234
	v_mov_b32_e32 v3, v235
	v_mov_b32_e32 v4, v248
	v_mov_b32_e32 v5, v249
	v_mov_b32_e32 v6, v250
	v_mov_b32_e32 v7, v251
	ds_read_b64 v[94:95], v149
	s_waitcnt lgkmcnt(0)
	v_pk_add_f32 v[102:103], v[116:117], v[94:95] op_sel_hi:[1,0] neg_lo:[0,1] neg_hi:[0,1]
	s_nop 0
	v_pk_mul_f32 v[102:103], v[94:95], v[102:103] op_sel:[1,0]
	v_pk_add_f32 v[108:109], v[112:113], v[94:95] op_sel_hi:[1,0] neg_lo:[0,1] neg_hi:[0,1]
	v_mov_b32_e32 v88, v1
	v_mov_b32_e32 v89, v2
	v_mov_b32_e32 v90, v5
	v_mov_b32_e32 v91, v6
	v_pk_fma_f32 v[102:103], v[88:89], v[102:103], v[90:91]
	v_pk_mul_f32 v[94:95], v[94:95], v[108:109] op_sel:[1,0]
	v_mov_b32_e32 v1, v3
	v_mov_b32_e32 v5, v7
	v_and_b32_sdwa v93, v102, v216 dst_sel:DWORD dst_unused:UNUSED_PAD src0_sel:WORD_1 src1_sel:DWORD
	v_pk_fma_f32 v[6:7], v[0:1], v[94:95], v[4:5]
	v_add3_u32 v93, v102, v93, s82
	v_and_b32_e32 v108, 0xffff0000, v93
	v_and_b32_sdwa v93, v7, v216 dst_sel:DWORD dst_unused:UNUSED_PAD src0_sel:WORD_1 src1_sel:DWORD
	v_and_b32_sdwa v3, v103, v216 dst_sel:DWORD dst_unused:UNUSED_PAD src0_sel:WORD_1 src1_sel:DWORD
	v_and_b32_sdwa v94, v6, v216 dst_sel:DWORD dst_unused:UNUSED_PAD src0_sel:WORD_1 src1_sel:DWORD
	v_add3_u32 v93, v7, v93, s82
	v_or_b32_e32 v2, 0x120, v155
	v_add3_u32 v3, v103, v3, s82
	v_add3_u32 v109, v6, v94, s82
	v_and_b32_e32 v110, 0xffff0000, v93
	v_or_b32_sdwa v95, v110, v3 dst_sel:DWORD dst_unused:UNUSED_PAD src0_sel:DWORD src1_sel:WORD_1
	v_or_b32_sdwa v94, v109, v108 dst_sel:DWORD dst_unused:UNUSED_PAD src0_sel:WORD_1 src1_sel:DWORD
	v_add_u32_e32 v93, v2, v153
	ds_write_b64 v93, v[94:95]
	v_and_b32_e32 v94, 0xffff0000, v109
	v_sub_u32_e32 v6, v6, v94
	v_sub_u32_e32 v94, v102, v108
	v_and_b32_e32 v3, 0xffff0000, v3
	v_add_u32_e32 v94, 0x80, v94
	v_sub_u32_e32 v3, v103, v3
	v_sub_u32_e32 v7, v7, v110
	v_add_u32_e32 v6, 0x80, v6
	v_ashrrev_i32_e32 v94, 8, v94
	v_add_u32_e32 v3, 0x80, v3
	v_add_u32_e32 v7, 0x80, v7
	v_ashrrev_i32_e32 v6, 8, v6
	v_min_i32_e32 v94, 0x7f, v94
	v_ashrrev_i32_e32 v3, 8, v3
	v_ashrrev_i32_e32 v7, 8, v7
	v_min_i32_e32 v6, 0x7f, v6
	v_min_i32_sdwa v3, v3, s83 dst_sel:WORD_1 dst_unused:UNUSED_PAD src0_sel:DWORD src1_sel:DWORD
	v_min_i32_e32 v7, 0x7f, v7
	v_lshlrev_b32_e32 v94, 8, v94
	v_and_b32_e32 v94, 0xff00, v94
	v_and_b32_e32 v3, 0xff0000, v3
	v_perm_b32 v6, v7, v6, s84
	v_or3_b32 v3, v6, v94, v3
	ds_write_b32 v12, v3 offset:144
	ds_read_b64 v[6:7], v13
	s_waitcnt lgkmcnt(0)
	v_pk_add_f32 v[94:95], v[98:99], v[6:7] op_sel_hi:[1,0] neg_lo:[0,1] neg_hi:[0,1]
	s_nop 0
	v_pk_mul_f32 v[94:95], v[6:7], v[94:95] op_sel:[1,0]
	s_nop 0
	v_pk_fma_f32 v[98:99], v[88:89], v[94:95], v[90:91]
	v_pk_add_f32 v[94:95], v[96:97], v[6:7] op_sel_hi:[1,0] neg_lo:[0,1] neg_hi:[0,1]
	v_and_b32_sdwa v3, v99, v216 dst_sel:DWORD dst_unused:UNUSED_PAD src0_sel:WORD_1 src1_sel:DWORD
	v_pk_mul_f32 v[6:7], v[6:7], v[94:95] op_sel:[1,0]
	v_and_b32_sdwa v94, v98, v216 dst_sel:DWORD dst_unused:UNUSED_PAD src0_sel:WORD_1 src1_sel:DWORD
	v_pk_fma_f32 v[6:7], v[0:1], v[6:7], v[4:5]
	v_add3_u32 v94, v98, v94, s82
	v_and_b32_e32 v95, 0xffff0000, v94
	v_and_b32_sdwa v94, v7, v216 dst_sel:DWORD dst_unused:UNUSED_PAD src0_sel:WORD_1 src1_sel:DWORD
	v_and_b32_sdwa v96, v6, v216 dst_sel:DWORD dst_unused:UNUSED_PAD src0_sel:WORD_1 src1_sel:DWORD
	v_add3_u32 v94, v7, v94, s82
	v_add3_u32 v3, v99, v3, s82
	v_add3_u32 v102, v6, v96, s82
	v_and_b32_e32 v103, 0xffff0000, v94
	v_or_b32_sdwa v97, v103, v3 dst_sel:DWORD dst_unused:UNUSED_PAD src0_sel:DWORD src1_sel:WORD_1
	v_or_b32_sdwa v96, v102, v95 dst_sel:DWORD dst_unused:UNUSED_PAD src0_sel:WORD_1 src1_sel:DWORD
	v_add_u32_e32 v94, v2, v154
	ds_write_b64 v94, v[96:97]
	v_and_b32_e32 v96, 0xffff0000, v102
	v_sub_u32_e32 v95, v98, v95
	v_and_b32_e32 v3, 0xffff0000, v3
	v_sub_u32_e32 v6, v6, v96
	v_add_u32_e32 v95, 0x80, v95
	v_sub_u32_e32 v3, v99, v3
	v_sub_u32_e32 v7, v7, v103
	v_add_u32_e32 v6, 0x80, v6
	v_ashrrev_i32_e32 v95, 8, v95
	v_add_u32_e32 v3, 0x80, v3
	v_add_u32_e32 v7, 0x80, v7
	v_ashrrev_i32_e32 v6, 8, v6
	v_min_i32_e32 v95, 0x7f, v95
	v_ashrrev_i32_e32 v3, 8, v3
	v_ashrrev_i32_e32 v7, 8, v7
	v_min_i32_e32 v6, 0x7f, v6
	v_min_i32_sdwa v3, v3, s83 dst_sel:WORD_1 dst_unused:UNUSED_PAD src0_sel:DWORD src1_sel:DWORD
	v_min_i32_e32 v7, 0x7f, v7
	v_lshlrev_b32_e32 v95, 8, v95
	v_and_b32_e32 v95, 0xff00, v95
	v_and_b32_e32 v3, 0xff0000, v3
	v_perm_b32 v6, v7, v6, s84
	v_or3_b32 v3, v6, v95, v3
	ds_write_b32 v14, v3 offset:144
	ds_read_b64 v[6:7], v15
	s_waitcnt lgkmcnt(0)
; #define WAIT_L(n) asm volatile("s_waitcnt lgkmcnt(" #n ")" ::: "memory")
; #define BAR __builtin_amdgcn_s_barrier()
;     ...
;               const float2 ms = *reinterpret_cast<const float2*>(mr + (ai * HALF + rr) * 2);
;               f32x4 y = acc[ai][bj][m][n];
;               const float o0 = (y[0] - ms.x) * ms.y * gm.x + bt.x, o1 = (y[1] - ms.x) * ms.y * gm.y + bt.y;
;               const float o2 = (y[2] - ms.x) * ms.y * gm.z + bt.z, o3 = (y[3] - ms.x) * ms.y * gm.w + bt.w;
;               const unsigned h0 = f2bf(o0), h1 = f2bf(o1), h2 = f2bf(o2), h3 = f2bf(o3);
;               u32x2 ob; ob[0] = h0 | (h1 << 16); ob[1] = h2 | (h3 << 16);
;               *reinterpret_cast<u32x2*>(smem + (rr >> 1) * PIECE + (rr & 1) * 512 + cc * 2) = ob;
;               const int l0 = min(((int)__float_as_uint(o0) - (int)(h0 << 16) + 128) >> 8, 127);
;               const int l1 = min(((int)__float_as_uint(o1) - (int)(h1 << 16) + 128) >> 8, 127);
;               const int l2 = min(((int)__float_as_uint(o2) - (int)(h2 << 16) + 128) >> 8, 127);
;               const int l3 = min(((int)__float_as_uint(o3) - (int)(h3 << 16) + 128) >> 8, 127);
;               *reinterpret_cast<unsigned*>(smem + LOBASE + (rr >> 2) * PIECE + (rr & 3) * 256 + cc) =
;                   (unsigned)(l0 & 255) | ((unsigned)(l1 & 255) << 8) | ((unsigned)(l2 & 255) << 16) | ((unsigned)l3 << 24);
;             }
;           }
;           WAIT_L(0); BAR;
;           const int hso = ((brow + ai * HALF + 16 * wave) * DM + pn * BM) * 2;
;           const int lso = (brow + ai * HALF + 16 * wave) * DM + pn * BM;
;           _Pragma("unroll") for (int i = 0; i < 8; ++i) {
;             const u32x4 v = *reinterpret_cast<const u32x4*>(smem + (wave * 8 + i) * PIECE + lane3 * 16);
;             __builtin_amdgcn_raw_buffer_store_b128(v, rsXB, hvo + i * (2 * DM * 2), hso, 0);
;           }
;           _Pragma("unroll") for (int i = 0; i < 4; ++i) {
;             const u32x4 v = *reinterpret_cast<const u32x4*>(smem + LOBASE + (wave * 4 + i) * PIECE + lane3 * 16);
	v_pk_add_f32 v[82:83], v[82:83], v[6:7] op_sel_hi:[1,0] neg_lo:[0,1] neg_hi:[0,1]
	s_nop 0
	v_pk_mul_f32 v[82:83], v[6:7], v[82:83] op_sel:[1,0]
	v_pk_add_f32 v[80:81], v[80:81], v[6:7] op_sel_hi:[1,0] neg_lo:[0,1] neg_hi:[0,1]
	v_pk_fma_f32 v[82:83], v[88:89], v[82:83], v[90:91]
	v_pk_mul_f32 v[6:7], v[6:7], v[80:81] op_sel:[1,0]
	v_and_b32_sdwa v80, v82, v216 dst_sel:DWORD dst_unused:UNUSED_PAD src0_sel:WORD_1 src1_sel:DWORD
	v_pk_fma_f32 v[6:7], v[0:1], v[6:7], v[4:5]
	v_add3_u32 v80, v82, v80, s82
	v_and_b32_e32 v81, 0xffff0000, v80
	v_and_b32_sdwa v80, v7, v216 dst_sel:DWORD dst_unused:UNUSED_PAD src0_sel:WORD_1 src1_sel:DWORD
	v_and_b32_sdwa v3, v83, v216 dst_sel:DWORD dst_unused:UNUSED_PAD src0_sel:WORD_1 src1_sel:DWORD
	v_and_b32_sdwa v95, v6, v216 dst_sel:DWORD dst_unused:UNUSED_PAD src0_sel:WORD_1 src1_sel:DWORD
	v_add3_u32 v80, v7, v80, s82
	v_add3_u32 v3, v83, v3, s82
	v_add3_u32 v95, v6, v95, s82
	v_and_b32_e32 v98, 0xffff0000, v80
	v_or_b32_sdwa v97, v98, v3 dst_sel:DWORD dst_unused:UNUSED_PAD src0_sel:DWORD src1_sel:WORD_1
	v_or_b32_sdwa v96, v95, v81 dst_sel:DWORD dst_unused:UNUSED_PAD src0_sel:WORD_1 src1_sel:DWORD
	v_and_b32_e32 v95, 0xffff0000, v95
	v_sub_u32_e32 v81, v82, v81
	v_and_b32_e32 v3, 0xffff0000, v3
	v_sub_u32_e32 v6, v6, v95
	v_add_u32_e32 v81, 0x80, v81
	v_sub_u32_e32 v3, v83, v3
	v_sub_u32_e32 v7, v7, v98
	v_add_u32_e32 v6, 0x80, v6
	v_ashrrev_i32_e32 v81, 8, v81
	v_add_u32_e32 v3, 0x80, v3
	v_add_u32_e32 v7, 0x80, v7
	v_ashrrev_i32_e32 v6, 8, v6
	v_min_i32_e32 v81, 0x7f, v81
	v_ashrrev_i32_e32 v3, 8, v3
	v_ashrrev_i32_e32 v7, 8, v7
	v_min_i32_e32 v6, 0x7f, v6
	v_min_i32_sdwa v3, v3, s83 dst_sel:WORD_1 dst_unused:UNUSED_PAD src0_sel:DWORD src1_sel:DWORD
	v_min_i32_e32 v7, 0x7f, v7
	v_lshlrev_b32_e32 v81, 8, v81
	v_and_b32_e32 v81, 0xff00, v81
	v_and_b32_e32 v3, 0xff0000, v3
	v_perm_b32 v6, v7, v6, s84
	v_add_u32_e32 v80, v2, v136
	v_or3_b32 v3, v6, v81, v3
	ds_write_b64 v80, v[96:97]
	ds_write_b32 v20, v3 offset:144
	ds_read_b64 v[6:7], v21
	v_or_b32_e32 v81, 0x6000, v148
	v_or_b32_e32 v82, 0x8000, v148
	v_or_b32_e32 v83, 0xa000, v148
	v_or_b32_e32 v95, 0x6000, v146
	s_waitcnt lgkmcnt(0)
	v_pk_add_f32 v[74:75], v[74:75], v[6:7] op_sel_hi:[1,0] neg_lo:[0,1] neg_hi:[0,1]
	v_pk_add_f32 v[72:73], v[72:73], v[6:7] op_sel_hi:[1,0] neg_lo:[0,1] neg_hi:[0,1]
	v_pk_mul_f32 v[74:75], v[6:7], v[74:75] op_sel:[1,0]
	v_pk_mul_f32 v[6:7], v[6:7], v[72:73] op_sel:[1,0]
	v_pk_fma_f32 v[74:75], v[88:89], v[74:75], v[90:91]
	v_pk_fma_f32 v[0:1], v[0:1], v[6:7], v[4:5]
	v_and_b32_sdwa v4, v74, v216 dst_sel:DWORD dst_unused:UNUSED_PAD src0_sel:WORD_1 src1_sel:DWORD
	v_add3_u32 v4, v74, v4, s82
	v_and_b32_e32 v6, 0xffff0000, v4
	v_and_b32_sdwa v4, v1, v216 dst_sel:DWORD dst_unused:UNUSED_PAD src0_sel:WORD_1 src1_sel:DWORD
	v_and_b32_sdwa v5, v0, v216 dst_sel:DWORD dst_unused:UNUSED_PAD src0_sel:WORD_1 src1_sel:DWORD
	v_and_b32_sdwa v3, v75, v216 dst_sel:DWORD dst_unused:UNUSED_PAD src0_sel:WORD_1 src1_sel:DWORD
	v_add3_u32 v4, v1, v4, s82
	v_add3_u32 v7, v0, v5, s82
	v_add3_u32 v3, v75, v3, s82
	v_and_b32_e32 v72, 0xffff0000, v4
	v_add_u32_e32 v73, v2, v135
	v_and_b32_e32 v2, 0xffff0000, v7
	v_or_b32_sdwa v5, v72, v3 dst_sel:DWORD dst_unused:UNUSED_PAD src0_sel:DWORD src1_sel:WORD_1
	v_sub_u32_e32 v0, v0, v2
	v_sub_u32_e32 v2, v74, v6
	v_and_b32_e32 v3, 0xffff0000, v3
	v_add_u32_e32 v2, 0x80, v2
	v_sub_u32_e32 v3, v75, v3
	v_sub_u32_e32 v1, v1, v72
	v_add_u32_e32 v0, 0x80, v0
	v_ashrrev_i32_e32 v2, 8, v2
	v_add_u32_e32 v3, 0x80, v3
	v_add_u32_e32 v1, 0x80, v1
	v_ashrrev_i32_e32 v0, 8, v0
	v_min_i32_e32 v2, 0x7f, v2
	v_ashrrev_i32_e32 v3, 8, v3
	v_ashrrev_i32_e32 v1, 8, v1
	v_min_i32_e32 v0, 0x7f, v0
	v_min_i32_sdwa v3, v3, s83 dst_sel:WORD_1 dst_unused:UNUSED_PAD src0_sel:DWORD src1_sel:DWORD
	v_min_i32_e32 v1, 0x7f, v1
	v_lshlrev_b32_e32 v2, 8, v2
	v_and_b32_e32 v2, 0xff00, v2
	v_and_b32_e32 v3, 0xff0000, v3
	v_perm_b32 v0, v1, v0, s84
	v_or_b32_sdwa v4, v7, v6 dst_sel:DWORD dst_unused:UNUSED_PAD src0_sel:WORD_1 src1_sel:DWORD
	v_or3_b32 v0, v0, v2, v3
	ds_write_b64 v73, v[4:5]
	ds_write_b32 v22, v0 offset:144
	v_add_u32_e32 v72, s47, v152
	s_waitcnt lgkmcnt(0)
	s_barrier
	ds_read_b128 v[128:131], v72
	v_or_b32_e32 v74, 0x2000, v148
	v_or_b32_e32 v75, 0x4000, v148
	v_or_b32_e32 v88, 0xc000, v148
	v_or_b32_e32 v89, 0xe000, v148
	ds_read_b128 v[136:139], v72 offset:1040
	v_or_b32_e32 v90, 0x2000, v146
	v_or_b32_e32 v91, 0x4000, v146
	ds_read_b128 v[140:143], v72 offset:2080
	ds_read_b128 v[152:155], v72 offset:3120
	ds_read_b128 v[156:159], v72 offset:4160
	ds_read_b128 v[160:163], v72 offset:5200
	ds_read_b128 v[164:167], v72 offset:6240
	ds_read_b128 v[168:171], v72 offset:7280
	ds_read_b128 v[172:175], v147
	ds_read_b128 v[176:179], v147 offset:1040
	ds_read_b128 v[180:183], v147 offset:2080
	ds_read_b128 v[184:187], v147 offset:3120
	s_waitcnt lgkmcnt(0)
	s_barrier
;     ...
;               const float2 ms = *reinterpret_cast<const float2*>(mr + (ai * HALF + rr) * 2);
;               f32x4 y = acc[ai][bj][m][n];
;               const float o0 = (y[0] - ms.x) * ms.y * gm.x + bt.x, o1 = (y[1] - ms.x) * ms.y * gm.y + bt.y;
;               const float o2 = (y[2] - ms.x) * ms.y * gm.z + bt.z, o3 = (y[3] - ms.x) * ms.y * gm.w + bt.w;
;               const unsigned h0 = f2bf(o0), h1 = f2bf(o1), h2 = f2bf(o2), h3 = f2bf(o3);
;               u32x2 ob; ob[0] = h0 | (h1 << 16); ob[1] = h2 | (h3 << 16);
;               *reinterpret_cast<u32x2*>(smem + (rr >> 1) * PIECE + (rr & 1) * 512 + cc * 2) = ob;
;               const int l0 = min(((int)__float_as_uint(o0) - (int)(h0 << 16) + 128) >> 8, 127);
;               const int l1 = min(((int)__float_as_uint(o1) - (int)(h1 << 16) + 128) >> 8, 127);
;               const int l2 = min(((int)__float_as_uint(o2) - (int)(h2 << 16) + 128) >> 8, 127);
;               const int l3 = min(((int)__float_as_uint(o3) - (int)(h3 << 16) + 128) >> 8, 127);
;               *reinterpret_cast<unsigned*>(smem + LOBASE + (rr >> 2) * PIECE + (rr & 3) * 256 + cc) =
;                   (unsigned)(l0 & 255) | ((unsigned)(l1 & 255) << 8) | ((unsigned)(l2 & 255) << 16) | ((unsigned)l3 << 24);
;     ...
;           _Pragma("unroll") for (int i = 0; i < 8; ++i) {
;             const u32x4 v = *reinterpret_cast<const u32x4*>(smem + (wave * 8 + i) * PIECE + lane3 * 16);
;             __builtin_amdgcn_raw_buffer_store_b128(v, rsXB, hvo + i * (2 * DM * 2), hso, 0);
;           }
;           _Pragma("unroll") for (int i = 0; i < 4; ++i) {
;             const u32x4 v = *reinterpret_cast<const u32x4*>(smem + LOBASE + (wave * 4 + i) * PIECE + lane3 * 16);
;             __builtin_amdgcn_raw_buffer_store_b128(v, rsLO, lvo + i * (4 * DM), lso, 0);
	s_nop 1
	v_mov_b32_e32 v0, v220
	v_mov_b32_e32 v1, v221
	v_mov_b32_e32 v2, v222
	v_mov_b32_e32 v3, v223
	v_mov_b32_e32 v4, v236
	v_mov_b32_e32 v5, v237
	v_mov_b32_e32 v6, v238
	v_mov_b32_e32 v7, v239
	ds_read_b64 v[102:103], v149 offset:1024
	s_waitcnt lgkmcnt(0)
	v_pk_add_f32 v[66:67], v[66:67], v[102:103] op_sel_hi:[1,0] neg_lo:[0,1] neg_hi:[0,1]
	s_nop 0
	v_pk_mul_f32 v[66:67], v[102:103], v[66:67] op_sel:[1,0]
	v_pk_add_f32 v[64:65], v[64:65], v[102:103] op_sel_hi:[1,0] neg_lo:[0,1] neg_hi:[0,1]
	v_mov_b32_e32 v96, v1
	v_mov_b32_e32 v97, v2
	v_mov_b32_e32 v98, v5
	v_mov_b32_e32 v99, v6
	v_pk_fma_f32 v[66:67], v[96:97], v[66:67], v[98:99]
	v_pk_mul_f32 v[64:65], v[102:103], v[64:65] op_sel:[1,0]
	v_mov_b32_e32 v1, v3
	v_mov_b32_e32 v5, v7
	v_and_b32_sdwa v6, v67, v216 dst_sel:DWORD dst_unused:UNUSED_PAD src0_sel:WORD_1 src1_sel:DWORD
	v_and_b32_sdwa v7, v66, v216 dst_sel:DWORD dst_unused:UNUSED_PAD src0_sel:WORD_1 src1_sel:DWORD
	v_pk_fma_f32 v[2:3], v[0:1], v[64:65], v[4:5]
	v_add3_u32 v64, v67, v6, s82
	v_add3_u32 v6, v66, v7, s82
	v_and_b32_e32 v65, 0xffff0000, v6
	v_and_b32_sdwa v6, v3, v216 dst_sel:DWORD dst_unused:UNUSED_PAD src0_sel:WORD_1 src1_sel:DWORD
	v_and_b32_sdwa v7, v2, v216 dst_sel:DWORD dst_unused:UNUSED_PAD src0_sel:WORD_1 src1_sel:DWORD
	v_add3_u32 v6, v3, v6, s82
	v_add3_u32 v102, v2, v7, s82
	v_and_b32_e32 v103, 0xffff0000, v6
	v_or_b32_sdwa v7, v103, v64 dst_sel:DWORD dst_unused:UNUSED_PAD src0_sel:DWORD src1_sel:WORD_1
	v_or_b32_sdwa v6, v102, v65 dst_sel:DWORD dst_unused:UNUSED_PAD src0_sel:WORD_1 src1_sel:DWORD
	ds_write_b64 v151, v[6:7]
	v_and_b32_e32 v6, 0xffff0000, v102
	v_sub_u32_e32 v2, v2, v6
	v_sub_u32_e32 v6, v66, v65
	v_and_b32_e32 v7, 0xffff0000, v64
	v_add_u32_e32 v6, 0x80, v6
	v_sub_u32_e32 v7, v67, v7
	v_sub_u32_e32 v3, v3, v103
	v_add_u32_e32 v2, 0x80, v2
	v_ashrrev_i32_e32 v6, 8, v6
	v_add_u32_e32 v7, 0x80, v7
	v_add_u32_e32 v3, 0x80, v3
	v_ashrrev_i32_e32 v2, 8, v2
	v_min_i32_e32 v6, 0x7f, v6
	v_ashrrev_i32_e32 v7, 8, v7
	v_ashrrev_i32_e32 v3, 8, v3
	v_min_i32_e32 v2, 0x7f, v2
	v_min_i32_sdwa v7, v7, s83 dst_sel:WORD_1 dst_unused:UNUSED_PAD src0_sel:DWORD src1_sel:DWORD
	v_min_i32_e32 v3, 0x7f, v3
	v_lshlrev_b32_e32 v6, 8, v6
	v_and_b32_e32 v6, 0xff00, v6
	v_and_b32_e32 v7, 0xff0000, v7
	v_perm_b32 v2, v3, v2, s84
	v_or3_b32 v2, v2, v6, v7
	ds_write_b32 v12, v2
	buffer_store_dwordx4 v[128:131], v148, s[16:19], s33 offen
	ds_read_b64 v[2:3], v13 offset:1024
	s_waitcnt lgkmcnt(0)
	v_pk_add_f32 v[6:7], v[70:71], v[2:3] op_sel_hi:[1,0] neg_lo:[0,1] neg_hi:[0,1]
	s_nop 0
	v_pk_mul_f32 v[6:7], v[2:3], v[6:7] op_sel:[1,0]
	v_pk_add_f32 v[64:65], v[68:69], v[2:3] op_sel_hi:[1,0] neg_lo:[0,1] neg_hi:[0,1]
	v_pk_fma_f32 v[6:7], v[96:97], v[6:7], v[98:99]
	v_pk_mul_f32 v[2:3], v[2:3], v[64:65] op_sel:[1,0]
	v_and_b32_sdwa v64, v7, v216 dst_sel:DWORD dst_unused:UNUSED_PAD src0_sel:WORD_1 src1_sel:DWORD
	v_and_b32_sdwa v65, v6, v216 dst_sel:DWORD dst_unused:UNUSED_PAD src0_sel:WORD_1 src1_sel:DWORD
	v_pk_fma_f32 v[2:3], v[0:1], v[2:3], v[4:5]
	v_add3_u32 v66, v7, v64, s82
	v_add3_u32 v64, v6, v65, s82
	v_and_b32_e32 v67, 0xffff0000, v64
	v_and_b32_sdwa v64, v3, v216 dst_sel:DWORD dst_unused:UNUSED_PAD src0_sel:WORD_1 src1_sel:DWORD
	v_and_b32_sdwa v65, v2, v216 dst_sel:DWORD dst_unused:UNUSED_PAD src0_sel:WORD_1 src1_sel:DWORD
	v_add3_u32 v64, v3, v64, s82
	v_add3_u32 v68, v2, v65, s82
	v_and_b32_e32 v69, 0xffff0000, v64
	v_or_b32_sdwa v65, v69, v66 dst_sel:DWORD dst_unused:UNUSED_PAD src0_sel:DWORD src1_sel:WORD_1
	v_or_b32_sdwa v64, v68, v67 dst_sel:DWORD dst_unused:UNUSED_PAD src0_sel:WORD_1 src1_sel:DWORD
	ds_write_b64 v132, v[64:65]
	v_and_b32_e32 v64, 0xffff0000, v68
	v_sub_u32_e32 v2, v2, v64
	v_sub_u32_e32 v6, v6, v67
	v_and_b32_e32 v64, 0xffff0000, v66
	v_add_u32_e32 v6, 0x80, v6
	v_sub_u32_e32 v7, v7, v64
	v_sub_u32_e32 v3, v3, v69
	v_add_u32_e32 v2, 0x80, v2
	v_ashrrev_i32_e32 v6, 8, v6
	v_add_u32_e32 v7, 0x80, v7
	v_add_u32_e32 v3, 0x80, v3
	v_ashrrev_i32_e32 v2, 8, v2
	v_min_i32_e32 v6, 0x7f, v6
	v_ashrrev_i32_e32 v7, 8, v7
	v_ashrrev_i32_e32 v3, 8, v3
	v_min_i32_e32 v2, 0x7f, v2
	v_min_i32_sdwa v7, v7, s83 dst_sel:WORD_1 dst_unused:UNUSED_PAD src0_sel:DWORD src1_sel:DWORD
	v_min_i32_e32 v3, 0x7f, v3
	v_lshlrev_b32_e32 v6, 8, v6
	v_and_b32_e32 v6, 0xff00, v6
	v_and_b32_e32 v7, 0xff0000, v7
	v_perm_b32 v2, v3, v2, s84
	v_or3_b32 v2, v2, v6, v7
	ds_write_b32 v14, v2
	buffer_store_dwordx4 v[136:139], v74, s[16:19], s33 offen
	ds_read_b64 v[2:3], v15 offset:1024
	s_waitcnt lgkmcnt(0)
	v_pk_add_f32 v[6:7], v[78:79], v[2:3] op_sel_hi:[1,0] neg_lo:[0,1] neg_hi:[0,1]
	s_nop 0
	v_pk_mul_f32 v[6:7], v[2:3], v[6:7] op_sel:[1,0]
	v_pk_add_f32 v[64:65], v[76:77], v[2:3] op_sel_hi:[1,0] neg_lo:[0,1] neg_hi:[0,1]
	v_pk_fma_f32 v[6:7], v[96:97], v[6:7], v[98:99]
	v_pk_mul_f32 v[2:3], v[2:3], v[64:65] op_sel:[1,0]
	v_and_b32_sdwa v64, v7, v216 dst_sel:DWORD dst_unused:UNUSED_PAD src0_sel:WORD_1 src1_sel:DWORD
	v_and_b32_sdwa v65, v6, v216 dst_sel:DWORD dst_unused:UNUSED_PAD src0_sel:WORD_1 src1_sel:DWORD
	v_pk_fma_f32 v[2:3], v[0:1], v[2:3], v[4:5]
	v_add3_u32 v66, v7, v64, s82
	v_add3_u32 v64, v6, v65, s82
	v_and_b32_e32 v67, 0xffff0000, v64
	v_and_b32_sdwa v64, v3, v216 dst_sel:DWORD dst_unused:UNUSED_PAD src0_sel:WORD_1 src1_sel:DWORD
	v_and_b32_sdwa v65, v2, v216 dst_sel:DWORD dst_unused:UNUSED_PAD src0_sel:WORD_1 src1_sel:DWORD
	v_add3_u32 v64, v3, v64, s82
	v_add3_u32 v68, v2, v65, s82
	v_and_b32_e32 v69, 0xffff0000, v64
	v_or_b32_sdwa v65, v69, v66 dst_sel:DWORD dst_unused:UNUSED_PAD src0_sel:DWORD src1_sel:WORD_1
	v_or_b32_sdwa v64, v68, v67 dst_sel:DWORD dst_unused:UNUSED_PAD src0_sel:WORD_1 src1_sel:DWORD
	ds_write_b64 v133, v[64:65]
	v_and_b32_e32 v64, 0xffff0000, v68
	v_sub_u32_e32 v2, v2, v64
	v_sub_u32_e32 v6, v6, v67
	v_and_b32_e32 v64, 0xffff0000, v66
	v_add_u32_e32 v6, 0x80, v6
	v_sub_u32_e32 v7, v7, v64
	v_sub_u32_e32 v3, v3, v69
	v_add_u32_e32 v2, 0x80, v2
	v_ashrrev_i32_e32 v6, 8, v6
	v_add_u32_e32 v7, 0x80, v7
	v_add_u32_e32 v3, 0x80, v3
	v_ashrrev_i32_e32 v2, 8, v2
	v_min_i32_e32 v6, 0x7f, v6
	v_ashrrev_i32_e32 v7, 8, v7
	v_ashrrev_i32_e32 v3, 8, v3
	v_min_i32_e32 v2, 0x7f, v2
	v_min_i32_sdwa v7, v7, s83 dst_sel:WORD_1 dst_unused:UNUSED_PAD src0_sel:DWORD src1_sel:DWORD
	v_min_i32_e32 v3, 0x7f, v3
	v_lshlrev_b32_e32 v6, 8, v6
	v_and_b32_e32 v6, 0xff00, v6
	v_and_b32_e32 v7, 0xff0000, v7
	v_perm_b32 v2, v3, v2, s84
	v_or3_b32 v2, v2, v6, v7
	ds_write_b32 v20, v2
	buffer_store_dwordx4 v[140:143], v75, s[16:19], s33 offen
	ds_read_b64 v[2:3], v21 offset:1024
	s_waitcnt lgkmcnt(0)
;     ...
;               const float2 ms = *reinterpret_cast<const float2*>(mr + (ai * HALF + rr) * 2);
;               f32x4 y = acc[ai][bj][m][n];
;               const float o0 = (y[0] - ms.x) * ms.y * gm.x + bt.x, o1 = (y[1] - ms.x) * ms.y * gm.y + bt.y;
;               const float o2 = (y[2] - ms.x) * ms.y * gm.z + bt.z, o3 = (y[3] - ms.x) * ms.y * gm.w + bt.w;
;               const unsigned h0 = f2bf(o0), h1 = f2bf(o1), h2 = f2bf(o2), h3 = f2bf(o3);
;               u32x2 ob; ob[0] = h0 | (h1 << 16); ob[1] = h2 | (h3 << 16);
;               *reinterpret_cast<u32x2*>(smem + (rr >> 1) * PIECE + (rr & 1) * 512 + cc * 2) = ob;
;               const int l0 = min(((int)__float_as_uint(o0) - (int)(h0 << 16) + 128) >> 8, 127);
;               const int l1 = min(((int)__float_as_uint(o1) - (int)(h1 << 16) + 128) >> 8, 127);
;               const int l2 = min(((int)__float_as_uint(o2) - (int)(h2 << 16) + 128) >> 8, 127);
;               const int l3 = min(((int)__float_as_uint(o3) - (int)(h3 << 16) + 128) >> 8, 127);
;               *reinterpret_cast<unsigned*>(smem + LOBASE + (rr >> 2) * PIECE + (rr & 3) * 256 + cc) =
;                   (unsigned)(l0 & 255) | ((unsigned)(l1 & 255) << 8) | ((unsigned)(l2 & 255) << 16) | ((unsigned)l3 << 24);
;     ...
;           _Pragma("unroll") for (int i = 0; i < 8; ++i) {
;             const u32x4 v = *reinterpret_cast<const u32x4*>(smem + (wave * 8 + i) * PIECE + lane3 * 16);
;             __builtin_amdgcn_raw_buffer_store_b128(v, rsXB, hvo + i * (2 * DM * 2), hso, 0);
;           }
;           _Pragma("unroll") for (int i = 0; i < 4; ++i) {
;             const u32x4 v = *reinterpret_cast<const u32x4*>(smem + LOBASE + (wave * 4 + i) * PIECE + lane3 * 16);
;             __builtin_amdgcn_raw_buffer_store_b128(v, rsLO, lvo + i * (4 * DM), lso, 0);
	v_pk_add_f32 v[6:7], v[86:87], v[2:3] op_sel_hi:[1,0] neg_lo:[0,1] neg_hi:[0,1]
	s_nop 0
	v_pk_mul_f32 v[6:7], v[2:3], v[6:7] op_sel:[1,0]
	v_pk_add_f32 v[64:65], v[84:85], v[2:3] op_sel_hi:[1,0] neg_lo:[0,1] neg_hi:[0,1]
	v_pk_fma_f32 v[6:7], v[96:97], v[6:7], v[98:99]
	v_pk_mul_f32 v[2:3], v[2:3], v[64:65] op_sel:[1,0]
	s_nop 0
	v_pk_fma_f32 v[0:1], v[0:1], v[2:3], v[4:5]
	v_and_b32_sdwa v2, v7, v216 dst_sel:DWORD dst_unused:UNUSED_PAD src0_sel:WORD_1 src1_sel:DWORD
	v_and_b32_sdwa v3, v6, v216 dst_sel:DWORD dst_unused:UNUSED_PAD src0_sel:WORD_1 src1_sel:DWORD
	v_add3_u32 v4, v7, v2, s82
	v_add3_u32 v2, v6, v3, s82
	v_and_b32_e32 v5, 0xffff0000, v2
	v_and_b32_sdwa v2, v1, v216 dst_sel:DWORD dst_unused:UNUSED_PAD src0_sel:WORD_1 src1_sel:DWORD
	v_and_b32_sdwa v3, v0, v216 dst_sel:DWORD dst_unused:UNUSED_PAD src0_sel:WORD_1 src1_sel:DWORD
	v_add3_u32 v2, v1, v2, s82
	v_add3_u32 v64, v0, v3, s82
	v_and_b32_e32 v65, 0xffff0000, v2
	v_or_b32_sdwa v3, v65, v4 dst_sel:DWORD dst_unused:UNUSED_PAD src0_sel:DWORD src1_sel:WORD_1
	v_or_b32_sdwa v2, v64, v5 dst_sel:DWORD dst_unused:UNUSED_PAD src0_sel:WORD_1 src1_sel:DWORD
	ds_write_b64 v134, v[2:3]
	v_and_b32_e32 v2, 0xffff0000, v64
	v_sub_u32_e32 v0, v0, v2
	v_sub_u32_e32 v2, v6, v5
	v_and_b32_e32 v3, 0xffff0000, v4
	v_add_u32_e32 v2, 0x80, v2
	v_sub_u32_e32 v3, v7, v3
	v_sub_u32_e32 v1, v1, v65
	v_add_u32_e32 v0, 0x80, v0
	v_ashrrev_i32_e32 v2, 8, v2
	v_add_u32_e32 v3, 0x80, v3
	v_add_u32_e32 v1, 0x80, v1
	v_ashrrev_i32_e32 v0, 8, v0
	v_min_i32_e32 v2, 0x7f, v2
	v_ashrrev_i32_e32 v3, 8, v3
	v_ashrrev_i32_e32 v1, 8, v1
	v_min_i32_e32 v0, 0x7f, v0
	v_min_i32_sdwa v3, v3, s83 dst_sel:WORD_1 dst_unused:UNUSED_PAD src0_sel:DWORD src1_sel:DWORD
	v_min_i32_e32 v1, 0x7f, v1
	v_lshlrev_b32_e32 v2, 8, v2
	v_and_b32_e32 v2, 0xff00, v2
	v_and_b32_e32 v3, 0xff0000, v3
	v_perm_b32 v0, v1, v0, s84
	v_or3_b32 v0, v0, v2, v3
	ds_write_b32 v22, v0
	buffer_store_dwordx4 v[152:155], v81, s[16:19], s33 offen
	v_mov_b32_e32 v0, v224
	v_mov_b32_e32 v1, v225
	v_mov_b32_e32 v2, v226
	v_mov_b32_e32 v3, v227
	v_mov_b32_e32 v4, v240
	v_mov_b32_e32 v5, v241
	v_mov_b32_e32 v6, v242
	v_mov_b32_e32 v7, v243
	ds_read_b64 v[68:69], v149 offset:1024
	s_waitcnt lgkmcnt(0)
	v_pk_add_f32 v[58:59], v[58:59], v[68:69] op_sel_hi:[1,0] neg_lo:[0,1] neg_hi:[0,1]
	s_nop 0
	v_pk_mul_f32 v[58:59], v[68:69], v[58:59] op_sel:[1,0]
	v_pk_add_f32 v[56:57], v[56:57], v[68:69] op_sel_hi:[1,0] neg_lo:[0,1] neg_hi:[0,1]
	v_mov_b32_e32 v64, v1
	v_mov_b32_e32 v65, v2
	v_mov_b32_e32 v66, v5
	v_mov_b32_e32 v67, v6
	v_pk_fma_f32 v[58:59], v[64:65], v[58:59], v[66:67]
	v_pk_mul_f32 v[56:57], v[68:69], v[56:57] op_sel:[1,0]
	v_mov_b32_e32 v1, v3
	v_mov_b32_e32 v5, v7
	v_and_b32_sdwa v6, v59, v216 dst_sel:DWORD dst_unused:UNUSED_PAD src0_sel:WORD_1 src1_sel:DWORD
	v_and_b32_sdwa v7, v58, v216 dst_sel:DWORD dst_unused:UNUSED_PAD src0_sel:WORD_1 src1_sel:DWORD
	v_pk_fma_f32 v[2:3], v[0:1], v[56:57], v[4:5]
	v_add3_u32 v56, v59, v6, s82
	v_add3_u32 v6, v58, v7, s82
	v_and_b32_e32 v57, 0xffff0000, v6
	v_and_b32_sdwa v6, v3, v216 dst_sel:DWORD dst_unused:UNUSED_PAD src0_sel:WORD_1 src1_sel:DWORD
	v_and_b32_sdwa v7, v2, v216 dst_sel:DWORD dst_unused:UNUSED_PAD src0_sel:WORD_1 src1_sel:DWORD
	v_add3_u32 v6, v3, v6, s82
	v_add3_u32 v68, v2, v7, s82
	v_and_b32_e32 v69, 0xffff0000, v6
	v_or_b32_sdwa v7, v69, v56 dst_sel:DWORD dst_unused:UNUSED_PAD src0_sel:DWORD src1_sel:WORD_1
	v_or_b32_sdwa v6, v68, v57 dst_sel:DWORD dst_unused:UNUSED_PAD src0_sel:WORD_1 src1_sel:DWORD
	ds_write_b64 v23, v[6:7]
	v_and_b32_e32 v6, 0xffff0000, v68
	v_sub_u32_e32 v2, v2, v6
	v_sub_u32_e32 v6, v58, v57
	v_and_b32_e32 v7, 0xffff0000, v56
	v_add_u32_e32 v6, 0x80, v6
	v_sub_u32_e32 v7, v59, v7
	v_sub_u32_e32 v3, v3, v69
	v_add_u32_e32 v2, 0x80, v2
	v_ashrrev_i32_e32 v6, 8, v6
	v_add_u32_e32 v7, 0x80, v7
	v_add_u32_e32 v3, 0x80, v3
	v_ashrrev_i32_e32 v2, 8, v2
	v_min_i32_e32 v6, 0x7f, v6
	v_ashrrev_i32_e32 v7, 8, v7
	v_ashrrev_i32_e32 v3, 8, v3
	v_min_i32_e32 v2, 0x7f, v2
	v_min_i32_sdwa v7, v7, s83 dst_sel:WORD_1 dst_unused:UNUSED_PAD src0_sel:DWORD src1_sel:DWORD
	v_min_i32_e32 v3, 0x7f, v3
	v_lshlrev_b32_e32 v6, 8, v6
	v_and_b32_e32 v6, 0xff00, v6
	v_and_b32_e32 v7, 0xff0000, v7
	v_perm_b32 v2, v3, v2, s84
	v_or3_b32 v2, v2, v6, v7
	ds_write_b32 v12, v2 offset:16
	buffer_store_dwordx4 v[156:159], v82, s[16:19], s33 offen
	ds_read_b64 v[2:3], v13 offset:1024
	s_waitcnt lgkmcnt(0)
	v_pk_add_f32 v[6:7], v[42:43], v[2:3] op_sel_hi:[1,0] neg_lo:[0,1] neg_hi:[0,1]
	s_nop 0
	v_pk_mul_f32 v[6:7], v[2:3], v[6:7] op_sel:[1,0]
	v_pk_add_f32 v[40:41], v[40:41], v[2:3] op_sel_hi:[1,0] neg_lo:[0,1] neg_hi:[0,1]
	v_pk_fma_f32 v[6:7], v[64:65], v[6:7], v[66:67]
	v_pk_mul_f32 v[2:3], v[2:3], v[40:41] op_sel:[1,0]
	v_and_b32_sdwa v40, v6, v216 dst_sel:DWORD dst_unused:UNUSED_PAD src0_sel:WORD_1 src1_sel:DWORD
	v_pk_fma_f32 v[2:3], v[0:1], v[2:3], v[4:5]
	v_add3_u32 v40, v6, v40, s82
	v_and_b32_e32 v42, 0xffff0000, v40
	v_and_b32_sdwa v40, v3, v216 dst_sel:DWORD dst_unused:UNUSED_PAD src0_sel:WORD_1 src1_sel:DWORD
	v_and_b32_sdwa v23, v7, v216 dst_sel:DWORD dst_unused:UNUSED_PAD src0_sel:WORD_1 src1_sel:DWORD
	v_and_b32_sdwa v41, v2, v216 dst_sel:DWORD dst_unused:UNUSED_PAD src0_sel:WORD_1 src1_sel:DWORD
	v_add3_u32 v40, v3, v40, s82
	v_add3_u32 v23, v7, v23, s82
	v_add3_u32 v43, v2, v41, s82
	v_and_b32_e32 v56, 0xffff0000, v40
	v_or_b32_sdwa v41, v56, v23 dst_sel:DWORD dst_unused:UNUSED_PAD src0_sel:DWORD src1_sel:WORD_1
	v_or_b32_sdwa v40, v43, v42 dst_sel:DWORD dst_unused:UNUSED_PAD src0_sel:WORD_1 src1_sel:DWORD
	ds_write_b64 v104, v[40:41]
	v_and_b32_e32 v40, 0xffff0000, v43
	v_sub_u32_e32 v6, v6, v42
	v_and_b32_e32 v23, 0xffff0000, v23
	v_sub_u32_e32 v2, v2, v40
	v_add_u32_e32 v6, 0x80, v6
	v_sub_u32_e32 v7, v7, v23
	v_sub_u32_e32 v3, v3, v56
	v_add_u32_e32 v2, 0x80, v2
	v_ashrrev_i32_e32 v6, 8, v6
	v_add_u32_e32 v7, 0x80, v7
	v_add_u32_e32 v3, 0x80, v3
	v_ashrrev_i32_e32 v2, 8, v2
	v_min_i32_e32 v6, 0x7f, v6
	v_ashrrev_i32_e32 v7, 8, v7
	v_ashrrev_i32_e32 v3, 8, v3
	v_min_i32_e32 v2, 0x7f, v2
	v_min_i32_sdwa v7, v7, s83 dst_sel:WORD_1 dst_unused:UNUSED_PAD src0_sel:DWORD src1_sel:DWORD
	v_min_i32_e32 v3, 0x7f, v3
	v_lshlrev_b32_e32 v6, 8, v6
	v_and_b32_e32 v6, 0xff00, v6
	v_and_b32_e32 v7, 0xff0000, v7
	v_perm_b32 v2, v3, v2, s84
	v_or3_b32 v2, v2, v6, v7
	ds_write_b32 v14, v2 offset:16
	buffer_store_dwordx4 v[160:163], v83, s[16:19], s33 offen
	ds_read_b64 v[2:3], v15 offset:1024
	s_waitcnt lgkmcnt(0)
;     ...
;               const float2 ms = *reinterpret_cast<const float2*>(mr + (ai * HALF + rr) * 2);
;               f32x4 y = acc[ai][bj][m][n];
;               const float o0 = (y[0] - ms.x) * ms.y * gm.x + bt.x, o1 = (y[1] - ms.x) * ms.y * gm.y + bt.y;
;               const float o2 = (y[2] - ms.x) * ms.y * gm.z + bt.z, o3 = (y[3] - ms.x) * ms.y * gm.w + bt.w;
;               const unsigned h0 = f2bf(o0), h1 = f2bf(o1), h2 = f2bf(o2), h3 = f2bf(o3);
;               u32x2 ob; ob[0] = h0 | (h1 << 16); ob[1] = h2 | (h3 << 16);
;               *reinterpret_cast<u32x2*>(smem + (rr >> 1) * PIECE + (rr & 1) * 512 + cc * 2) = ob;
;               const int l0 = min(((int)__float_as_uint(o0) - (int)(h0 << 16) + 128) >> 8, 127);
;               const int l1 = min(((int)__float_as_uint(o1) - (int)(h1 << 16) + 128) >> 8, 127);
;               const int l2 = min(((int)__float_as_uint(o2) - (int)(h2 << 16) + 128) >> 8, 127);
;               const int l3 = min(((int)__float_as_uint(o3) - (int)(h3 << 16) + 128) >> 8, 127);
;               *reinterpret_cast<unsigned*>(smem + LOBASE + (rr >> 2) * PIECE + (rr & 3) * 256 + cc) =
;                   (unsigned)(l0 & 255) | ((unsigned)(l1 & 255) << 8) | ((unsigned)(l2 & 255) << 16) | ((unsigned)l3 << 24);
;     ...
;           _Pragma("unroll") for (int i = 0; i < 8; ++i) {
;             const u32x4 v = *reinterpret_cast<const u32x4*>(smem + (wave * 8 + i) * PIECE + lane3 * 16);
;             __builtin_amdgcn_raw_buffer_store_b128(v, rsXB, hvo + i * (2 * DM * 2), hso, 0);
;           }
;           _Pragma("unroll") for (int i = 0; i < 4; ++i) {
;             const u32x4 v = *reinterpret_cast<const u32x4*>(smem + LOBASE + (wave * 4 + i) * PIECE + lane3 * 16);
;             __builtin_amdgcn_raw_buffer_store_b128(v, rsLO, lvo + i * (4 * DM), lso, 0);
	v_pk_add_f32 v[6:7], v[46:47], v[2:3] op_sel_hi:[1,0] neg_lo:[0,1] neg_hi:[0,1]
	s_nop 0
	v_pk_mul_f32 v[6:7], v[2:3], v[6:7] op_sel:[1,0]
	v_pk_add_f32 v[40:41], v[44:45], v[2:3] op_sel_hi:[1,0] neg_lo:[0,1] neg_hi:[0,1]
	v_pk_fma_f32 v[6:7], v[64:65], v[6:7], v[66:67]
	v_pk_mul_f32 v[2:3], v[2:3], v[40:41] op_sel:[1,0]
	v_and_b32_sdwa v40, v6, v216 dst_sel:DWORD dst_unused:UNUSED_PAD src0_sel:WORD_1 src1_sel:DWORD
	v_pk_fma_f32 v[2:3], v[0:1], v[2:3], v[4:5]
	v_add3_u32 v40, v6, v40, s82
	v_and_b32_e32 v42, 0xffff0000, v40
	v_and_b32_sdwa v40, v3, v216 dst_sel:DWORD dst_unused:UNUSED_PAD src0_sel:WORD_1 src1_sel:DWORD
	v_and_b32_sdwa v23, v7, v216 dst_sel:DWORD dst_unused:UNUSED_PAD src0_sel:WORD_1 src1_sel:DWORD
	v_and_b32_sdwa v41, v2, v216 dst_sel:DWORD dst_unused:UNUSED_PAD src0_sel:WORD_1 src1_sel:DWORD
	v_add3_u32 v40, v3, v40, s82
	v_add3_u32 v23, v7, v23, s82
	v_add3_u32 v43, v2, v41, s82
	v_and_b32_e32 v44, 0xffff0000, v40
	v_or_b32_sdwa v41, v44, v23 dst_sel:DWORD dst_unused:UNUSED_PAD src0_sel:DWORD src1_sel:WORD_1
	v_or_b32_sdwa v40, v43, v42 dst_sel:DWORD dst_unused:UNUSED_PAD src0_sel:WORD_1 src1_sel:DWORD
	ds_write_b64 v105, v[40:41]
	v_and_b32_e32 v40, 0xffff0000, v43
	v_sub_u32_e32 v6, v6, v42
	v_and_b32_e32 v23, 0xffff0000, v23
	v_sub_u32_e32 v2, v2, v40
	v_add_u32_e32 v6, 0x80, v6
	v_sub_u32_e32 v7, v7, v23
	v_sub_u32_e32 v3, v3, v44
	v_add_u32_e32 v2, 0x80, v2
	v_ashrrev_i32_e32 v6, 8, v6
	v_add_u32_e32 v7, 0x80, v7
	v_add_u32_e32 v3, 0x80, v3
	v_ashrrev_i32_e32 v2, 8, v2
	v_min_i32_e32 v6, 0x7f, v6
	v_ashrrev_i32_e32 v7, 8, v7
	v_ashrrev_i32_e32 v3, 8, v3
	v_min_i32_e32 v2, 0x7f, v2
	v_min_i32_sdwa v7, v7, s83 dst_sel:WORD_1 dst_unused:UNUSED_PAD src0_sel:DWORD src1_sel:DWORD
	v_min_i32_e32 v3, 0x7f, v3
	v_lshlrev_b32_e32 v6, 8, v6
	v_and_b32_e32 v6, 0xff00, v6
	v_and_b32_e32 v7, 0xff0000, v7
	v_perm_b32 v2, v3, v2, s84
	v_or3_b32 v2, v2, v6, v7
	ds_write_b32 v20, v2 offset:16
	buffer_store_dwordx4 v[164:167], v88, s[16:19], s33 offen
	ds_read_b64 v[2:3], v21 offset:1024
	s_waitcnt lgkmcnt(0)
	v_pk_add_f32 v[6:7], v[62:63], v[2:3] op_sel_hi:[1,0] neg_lo:[0,1] neg_hi:[0,1]
	s_nop 0
	v_pk_mul_f32 v[6:7], v[2:3], v[6:7] op_sel:[1,0]
	v_pk_add_f32 v[40:41], v[60:61], v[2:3] op_sel_hi:[1,0] neg_lo:[0,1] neg_hi:[0,1]
	v_pk_fma_f32 v[6:7], v[64:65], v[6:7], v[66:67]
	v_pk_mul_f32 v[2:3], v[2:3], v[40:41] op_sel:[1,0]
	s_nop 0
	v_pk_fma_f32 v[0:1], v[0:1], v[2:3], v[4:5]
	v_and_b32_sdwa v2, v7, v216 dst_sel:DWORD dst_unused:UNUSED_PAD src0_sel:WORD_1 src1_sel:DWORD
	v_and_b32_sdwa v3, v6, v216 dst_sel:DWORD dst_unused:UNUSED_PAD src0_sel:WORD_1 src1_sel:DWORD
	v_add3_u32 v4, v7, v2, s82
	v_add3_u32 v2, v6, v3, s82
	v_and_b32_e32 v5, 0xffff0000, v2
	v_and_b32_sdwa v2, v1, v216 dst_sel:DWORD dst_unused:UNUSED_PAD src0_sel:WORD_1 src1_sel:DWORD
	v_and_b32_sdwa v3, v0, v216 dst_sel:DWORD dst_unused:UNUSED_PAD src0_sel:WORD_1 src1_sel:DWORD
	v_add3_u32 v2, v1, v2, s82
	v_add3_u32 v23, v0, v3, s82
	v_and_b32_e32 v40, 0xffff0000, v2
	v_or_b32_sdwa v3, v40, v4 dst_sel:DWORD dst_unused:UNUSED_PAD src0_sel:DWORD src1_sel:WORD_1
	v_or_b32_sdwa v2, v23, v5 dst_sel:DWORD dst_unused:UNUSED_PAD src0_sel:WORD_1 src1_sel:DWORD
	ds_write_b64 v106, v[2:3]
	v_and_b32_e32 v2, 0xffff0000, v23
	v_sub_u32_e32 v0, v0, v2
	v_sub_u32_e32 v2, v6, v5
	v_and_b32_e32 v3, 0xffff0000, v4
	v_add_u32_e32 v2, 0x80, v2
	v_sub_u32_e32 v3, v7, v3
	v_sub_u32_e32 v1, v1, v40
	v_add_u32_e32 v0, 0x80, v0
	v_ashrrev_i32_e32 v2, 8, v2
	v_add_u32_e32 v3, 0x80, v3
	v_add_u32_e32 v1, 0x80, v1
	v_ashrrev_i32_e32 v0, 8, v0
	v_min_i32_e32 v2, 0x7f, v2
	v_ashrrev_i32_e32 v3, 8, v3
	v_ashrrev_i32_e32 v1, 8, v1
	v_min_i32_e32 v0, 0x7f, v0
	v_min_i32_sdwa v3, v3, s83 dst_sel:WORD_1 dst_unused:UNUSED_PAD src0_sel:DWORD src1_sel:DWORD
	v_min_i32_e32 v1, 0x7f, v1
	v_lshlrev_b32_e32 v2, 8, v2
	v_and_b32_e32 v2, 0xff00, v2
	v_and_b32_e32 v3, 0xff0000, v3
	v_perm_b32 v0, v1, v0, s84
	v_or3_b32 v0, v0, v2, v3
	ds_write_b32 v22, v0 offset:16
	buffer_store_dwordx4 v[168:171], v89, s[16:19], s33 offen
	v_mov_b32_e32 v0, v228
	v_mov_b32_e32 v1, v229
	v_mov_b32_e32 v2, v230
	v_mov_b32_e32 v3, v231
	v_mov_b32_e32 v4, v244
	v_mov_b32_e32 v5, v245
	v_mov_b32_e32 v6, v246
	v_mov_b32_e32 v7, v247
	ds_read_b64 v[44:45], v149 offset:1024
	s_waitcnt lgkmcnt(0)
	v_pk_add_f32 v[46:47], v[54:55], v[44:45] op_sel_hi:[1,0] neg_lo:[0,1] neg_hi:[0,1]
	s_nop 0
	v_pk_mul_f32 v[46:47], v[44:45], v[46:47] op_sel:[1,0]
	v_pk_add_f32 v[52:53], v[52:53], v[44:45] op_sel_hi:[1,0] neg_lo:[0,1] neg_hi:[0,1]
	v_mov_b32_e32 v40, v1
	v_mov_b32_e32 v41, v2
	v_mov_b32_e32 v42, v5
	v_mov_b32_e32 v43, v6
	v_pk_fma_f32 v[46:47], v[40:41], v[46:47], v[42:43]
	v_pk_mul_f32 v[44:45], v[44:45], v[52:53] op_sel:[1,0]
	v_mov_b32_e32 v1, v3
	v_mov_b32_e32 v5, v7
	v_and_b32_sdwa v6, v47, v216 dst_sel:DWORD dst_unused:UNUSED_PAD src0_sel:WORD_1 src1_sel:DWORD
	v_and_b32_sdwa v7, v46, v216 dst_sel:DWORD dst_unused:UNUSED_PAD src0_sel:WORD_1 src1_sel:DWORD
	v_pk_fma_f32 v[2:3], v[0:1], v[44:45], v[4:5]
	v_add3_u32 v23, v47, v6, s82
	v_add3_u32 v6, v46, v7, s82
	v_and_b32_e32 v44, 0xffff0000, v6
	v_and_b32_sdwa v6, v3, v216 dst_sel:DWORD dst_unused:UNUSED_PAD src0_sel:WORD_1 src1_sel:DWORD
	v_and_b32_sdwa v7, v2, v216 dst_sel:DWORD dst_unused:UNUSED_PAD src0_sel:WORD_1 src1_sel:DWORD
	v_add3_u32 v6, v3, v6, s82
	v_add3_u32 v45, v2, v7, s82
	v_and_b32_e32 v52, 0xffff0000, v6
	v_or_b32_sdwa v7, v52, v23 dst_sel:DWORD dst_unused:UNUSED_PAD src0_sel:DWORD src1_sel:WORD_1
	v_or_b32_sdwa v6, v45, v44 dst_sel:DWORD dst_unused:UNUSED_PAD src0_sel:WORD_1 src1_sel:DWORD
	ds_write_b64 v107, v[6:7]
	v_and_b32_e32 v6, 0xffff0000, v45
	v_sub_u32_e32 v2, v2, v6
	v_sub_u32_e32 v6, v46, v44
	v_and_b32_e32 v7, 0xffff0000, v23
	v_add_u32_e32 v6, 0x80, v6
	v_sub_u32_e32 v7, v47, v7
	v_sub_u32_e32 v3, v3, v52
	v_add_u32_e32 v2, 0x80, v2
	v_ashrrev_i32_e32 v6, 8, v6
	v_add_u32_e32 v7, 0x80, v7
	v_add_u32_e32 v3, 0x80, v3
	v_ashrrev_i32_e32 v2, 8, v2
	v_min_i32_e32 v6, 0x7f, v6
	v_ashrrev_i32_e32 v7, 8, v7
	v_ashrrev_i32_e32 v3, 8, v3
	v_min_i32_e32 v2, 0x7f, v2
	v_min_i32_sdwa v7, v7, s83 dst_sel:WORD_1 dst_unused:UNUSED_PAD src0_sel:DWORD src1_sel:DWORD
	v_min_i32_e32 v3, 0x7f, v3
	v_lshlrev_b32_e32 v6, 8, v6
	v_and_b32_e32 v6, 0xff00, v6
	v_and_b32_e32 v7, 0xff0000, v7
	v_perm_b32 v2, v3, v2, s84
	v_or3_b32 v2, v2, v6, v7
	ds_write_b32 v12, v2 offset:128
	buffer_store_dwordx4 v[172:175], v146, s[20:23], s0 offen
	ds_read_b64 v[2:3], v13 offset:1024
	s_waitcnt lgkmcnt(0)
;     ...
;               const float2 ms = *reinterpret_cast<const float2*>(mr + (ai * HALF + rr) * 2);
;               f32x4 y = acc[ai][bj][m][n];
;               const float o0 = (y[0] - ms.x) * ms.y * gm.x + bt.x, o1 = (y[1] - ms.x) * ms.y * gm.y + bt.y;
;               const float o2 = (y[2] - ms.x) * ms.y * gm.z + bt.z, o3 = (y[3] - ms.x) * ms.y * gm.w + bt.w;
;               const unsigned h0 = f2bf(o0), h1 = f2bf(o1), h2 = f2bf(o2), h3 = f2bf(o3);
;               u32x2 ob; ob[0] = h0 | (h1 << 16); ob[1] = h2 | (h3 << 16);
;               *reinterpret_cast<u32x2*>(smem + (rr >> 1) * PIECE + (rr & 1) * 512 + cc * 2) = ob;
;               const int l0 = min(((int)__float_as_uint(o0) - (int)(h0 << 16) + 128) >> 8, 127);
;               const int l1 = min(((int)__float_as_uint(o1) - (int)(h1 << 16) + 128) >> 8, 127);
;               const int l2 = min(((int)__float_as_uint(o2) - (int)(h2 << 16) + 128) >> 8, 127);
;               const int l3 = min(((int)__float_as_uint(o3) - (int)(h3 << 16) + 128) >> 8, 127);
;               *reinterpret_cast<unsigned*>(smem + LOBASE + (rr >> 2) * PIECE + (rr & 3) * 256 + cc) =
;                   (unsigned)(l0 & 255) | ((unsigned)(l1 & 255) << 8) | ((unsigned)(l2 & 255) << 16) | ((unsigned)l3 << 24);
;     ...
;           _Pragma("unroll") for (int i = 0; i < 8; ++i) {
;             const u32x4 v = *reinterpret_cast<const u32x4*>(smem + (wave * 8 + i) * PIECE + lane3 * 16);
;             __builtin_amdgcn_raw_buffer_store_b128(v, rsXB, hvo + i * (2 * DM * 2), hso, 0);
;           }
;           _Pragma("unroll") for (int i = 0; i < 4; ++i) {
;             const u32x4 v = *reinterpret_cast<const u32x4*>(smem + LOBASE + (wave * 4 + i) * PIECE + lane3 * 16);
;             __builtin_amdgcn_raw_buffer_store_b128(v, rsLO, lvo + i * (4 * DM), lso, 0);
	v_pk_add_f32 v[6:7], v[38:39], v[2:3] op_sel_hi:[1,0] neg_lo:[0,1] neg_hi:[0,1]
	s_nop 0
	v_pk_mul_f32 v[6:7], v[2:3], v[6:7] op_sel:[1,0]
	v_pk_add_f32 v[36:37], v[36:37], v[2:3] op_sel_hi:[1,0] neg_lo:[0,1] neg_hi:[0,1]
	v_pk_fma_f32 v[6:7], v[40:41], v[6:7], v[42:43]
	v_pk_mul_f32 v[2:3], v[2:3], v[36:37] op_sel:[1,0]
	v_and_b32_sdwa v36, v6, v216 dst_sel:DWORD dst_unused:UNUSED_PAD src0_sel:WORD_1 src1_sel:DWORD
	v_pk_fma_f32 v[2:3], v[0:1], v[2:3], v[4:5]
	v_add3_u32 v36, v6, v36, s82
	v_and_b32_e32 v38, 0xffff0000, v36
	v_and_b32_sdwa v36, v3, v216 dst_sel:DWORD dst_unused:UNUSED_PAD src0_sel:WORD_1 src1_sel:DWORD
	v_and_b32_sdwa v23, v7, v216 dst_sel:DWORD dst_unused:UNUSED_PAD src0_sel:WORD_1 src1_sel:DWORD
	v_and_b32_sdwa v37, v2, v216 dst_sel:DWORD dst_unused:UNUSED_PAD src0_sel:WORD_1 src1_sel:DWORD
	v_add3_u32 v36, v3, v36, s82
	v_add3_u32 v23, v7, v23, s82
	v_add3_u32 v39, v2, v37, s82
	v_and_b32_e32 v44, 0xffff0000, v36
	v_or_b32_sdwa v37, v44, v23 dst_sel:DWORD dst_unused:UNUSED_PAD src0_sel:DWORD src1_sel:WORD_1
	v_or_b32_sdwa v36, v39, v38 dst_sel:DWORD dst_unused:UNUSED_PAD src0_sel:WORD_1 src1_sel:DWORD
	ds_write_b64 v100, v[36:37]
	v_and_b32_e32 v36, 0xffff0000, v39
	v_sub_u32_e32 v6, v6, v38
	v_and_b32_e32 v23, 0xffff0000, v23
	v_sub_u32_e32 v2, v2, v36
	v_add_u32_e32 v6, 0x80, v6
	v_sub_u32_e32 v7, v7, v23
	v_sub_u32_e32 v3, v3, v44
	v_add_u32_e32 v2, 0x80, v2
	v_ashrrev_i32_e32 v6, 8, v6
	v_add_u32_e32 v7, 0x80, v7
	v_add_u32_e32 v3, 0x80, v3
	v_ashrrev_i32_e32 v2, 8, v2
	v_min_i32_e32 v6, 0x7f, v6
	v_ashrrev_i32_e32 v7, 8, v7
	v_ashrrev_i32_e32 v3, 8, v3
	v_min_i32_e32 v2, 0x7f, v2
	v_min_i32_sdwa v7, v7, s83 dst_sel:WORD_1 dst_unused:UNUSED_PAD src0_sel:DWORD src1_sel:DWORD
	v_min_i32_e32 v3, 0x7f, v3
	v_lshlrev_b32_e32 v6, 8, v6
	v_and_b32_e32 v6, 0xff00, v6
	v_and_b32_e32 v7, 0xff0000, v7
	v_perm_b32 v2, v3, v2, s84
	v_or3_b32 v2, v2, v6, v7
	ds_write_b32 v14, v2 offset:128
	buffer_store_dwordx4 v[176:179], v90, s[20:23], s0 offen
	ds_read_b64 v[2:3], v15 offset:1024
	s_waitcnt lgkmcnt(0)
	v_pk_add_f32 v[6:7], v[26:27], v[2:3] op_sel_hi:[1,0] neg_lo:[0,1] neg_hi:[0,1]
	s_nop 0
	v_pk_mul_f32 v[6:7], v[2:3], v[6:7] op_sel:[1,0]
	v_pk_add_f32 v[24:25], v[24:25], v[2:3] op_sel_hi:[1,0] neg_lo:[0,1] neg_hi:[0,1]
	v_pk_fma_f32 v[6:7], v[40:41], v[6:7], v[42:43]
	v_pk_mul_f32 v[2:3], v[2:3], v[24:25] op_sel:[1,0]
	v_and_b32_sdwa v24, v6, v216 dst_sel:DWORD dst_unused:UNUSED_PAD src0_sel:WORD_1 src1_sel:DWORD
	v_pk_fma_f32 v[2:3], v[0:1], v[2:3], v[4:5]
	v_add3_u32 v24, v6, v24, s82
	v_and_b32_e32 v26, 0xffff0000, v24
	v_and_b32_sdwa v24, v3, v216 dst_sel:DWORD dst_unused:UNUSED_PAD src0_sel:WORD_1 src1_sel:DWORD
	v_and_b32_sdwa v23, v7, v216 dst_sel:DWORD dst_unused:UNUSED_PAD src0_sel:WORD_1 src1_sel:DWORD
	v_and_b32_sdwa v25, v2, v216 dst_sel:DWORD dst_unused:UNUSED_PAD src0_sel:WORD_1 src1_sel:DWORD
	v_add3_u32 v24, v3, v24, s82
	v_add3_u32 v23, v7, v23, s82
	v_add3_u32 v27, v2, v25, s82
	v_and_b32_e32 v36, 0xffff0000, v24
	v_or_b32_sdwa v25, v36, v23 dst_sel:DWORD dst_unused:UNUSED_PAD src0_sel:DWORD src1_sel:WORD_1
	v_or_b32_sdwa v24, v27, v26 dst_sel:DWORD dst_unused:UNUSED_PAD src0_sel:WORD_1 src1_sel:DWORD
	ds_write_b64 v101, v[24:25]
	v_and_b32_e32 v24, 0xffff0000, v27
	v_sub_u32_e32 v6, v6, v26
	v_and_b32_e32 v23, 0xffff0000, v23
	v_sub_u32_e32 v2, v2, v24
	v_add_u32_e32 v6, 0x80, v6
	v_sub_u32_e32 v7, v7, v23
	v_sub_u32_e32 v3, v3, v36
	v_add_u32_e32 v2, 0x80, v2
	v_ashrrev_i32_e32 v6, 8, v6
	v_add_u32_e32 v7, 0x80, v7
	v_add_u32_e32 v3, 0x80, v3
	v_ashrrev_i32_e32 v2, 8, v2
	v_min_i32_e32 v6, 0x7f, v6
	v_ashrrev_i32_e32 v7, 8, v7
	v_ashrrev_i32_e32 v3, 8, v3
	v_min_i32_e32 v2, 0x7f, v2
	v_min_i32_sdwa v7, v7, s83 dst_sel:WORD_1 dst_unused:UNUSED_PAD src0_sel:DWORD src1_sel:DWORD
	v_min_i32_e32 v3, 0x7f, v3
	v_lshlrev_b32_e32 v6, 8, v6
	v_and_b32_e32 v6, 0xff00, v6
	v_and_b32_e32 v7, 0xff0000, v7
	v_perm_b32 v2, v3, v2, s84
	v_or3_b32 v2, v2, v6, v7
	ds_write_b32 v20, v2 offset:128
	buffer_store_dwordx4 v[180:183], v91, s[20:23], s0 offen
	ds_read_b64 v[2:3], v21 offset:1024
	s_waitcnt lgkmcnt(0)
	v_pk_add_f32 v[6:7], v[30:31], v[2:3] op_sel_hi:[1,0] neg_lo:[0,1] neg_hi:[0,1]
	s_nop 0
	v_pk_mul_f32 v[6:7], v[2:3], v[6:7] op_sel:[1,0]
	v_pk_add_f32 v[24:25], v[28:29], v[2:3] op_sel_hi:[1,0] neg_lo:[0,1] neg_hi:[0,1]
	v_pk_fma_f32 v[6:7], v[40:41], v[6:7], v[42:43]
	v_pk_mul_f32 v[2:3], v[2:3], v[24:25] op_sel:[1,0]
	s_nop 0
	v_pk_fma_f32 v[0:1], v[0:1], v[2:3], v[4:5]
	v_and_b32_sdwa v2, v7, v216 dst_sel:DWORD dst_unused:UNUSED_PAD src0_sel:WORD_1 src1_sel:DWORD
	v_and_b32_sdwa v3, v6, v216 dst_sel:DWORD dst_unused:UNUSED_PAD src0_sel:WORD_1 src1_sel:DWORD
	v_add3_u32 v4, v7, v2, s82
	v_add3_u32 v2, v6, v3, s82
	v_and_b32_e32 v5, 0xffff0000, v2
	v_and_b32_sdwa v2, v1, v216 dst_sel:DWORD dst_unused:UNUSED_PAD src0_sel:WORD_1 src1_sel:DWORD
	v_and_b32_sdwa v3, v0, v216 dst_sel:DWORD dst_unused:UNUSED_PAD src0_sel:WORD_1 src1_sel:DWORD
	v_add3_u32 v2, v1, v2, s82
	v_add3_u32 v23, v0, v3, s82
	v_and_b32_e32 v24, 0xffff0000, v2
	v_or_b32_sdwa v3, v24, v4 dst_sel:DWORD dst_unused:UNUSED_PAD src0_sel:DWORD src1_sel:WORD_1
	v_or_b32_sdwa v2, v23, v5 dst_sel:DWORD dst_unused:UNUSED_PAD src0_sel:WORD_1 src1_sel:DWORD
	ds_write_b64 v92, v[2:3]
	v_and_b32_e32 v2, 0xffff0000, v23
	v_sub_u32_e32 v0, v0, v2
	v_sub_u32_e32 v2, v6, v5
	v_and_b32_e32 v3, 0xffff0000, v4
	v_add_u32_e32 v2, 0x80, v2
	v_sub_u32_e32 v3, v7, v3
	v_sub_u32_e32 v1, v1, v24
	v_add_u32_e32 v0, 0x80, v0
	v_ashrrev_i32_e32 v2, 8, v2
	v_add_u32_e32 v3, 0x80, v3
	v_add_u32_e32 v1, 0x80, v1
	v_ashrrev_i32_e32 v0, 8, v0
	v_min_i32_e32 v2, 0x7f, v2
	v_ashrrev_i32_e32 v3, 8, v3
	v_ashrrev_i32_e32 v1, 8, v1
	v_min_i32_e32 v0, 0x7f, v0
	v_min_i32_sdwa v3, v3, s83 dst_sel:WORD_1 dst_unused:UNUSED_PAD src0_sel:DWORD src1_sel:DWORD
	v_min_i32_e32 v1, 0x7f, v1
	v_lshlrev_b32_e32 v2, 8, v2
	v_and_b32_e32 v2, 0xff00, v2
	v_and_b32_e32 v3, 0xff0000, v3
	v_perm_b32 v0, v1, v0, s84
	v_or3_b32 v0, v0, v2, v3
	ds_write_b32 v22, v0 offset:128
	buffer_store_dwordx4 v[184:187], v95, s[20:23], s0 offen
	v_mov_b32_e32 v0, v232
	v_mov_b32_e32 v1, v233
	v_mov_b32_e32 v2, v234
	v_mov_b32_e32 v3, v235
	v_mov_b32_e32 v4, v248
	v_mov_b32_e32 v5, v249
	v_mov_b32_e32 v6, v250
	v_mov_b32_e32 v7, v251
	ds_read_b64 v[28:29], v149 offset:1024
	s_mov_b64 s[4:5], -1
	s_waitcnt lgkmcnt(0)
;     ...
;               const float2 ms = *reinterpret_cast<const float2*>(mr + (ai * HALF + rr) * 2);
;               f32x4 y = acc[ai][bj][m][n];
;               const float o0 = (y[0] - ms.x) * ms.y * gm.x + bt.x, o1 = (y[1] - ms.x) * ms.y * gm.y + bt.y;
;               const float o2 = (y[2] - ms.x) * ms.y * gm.z + bt.z, o3 = (y[3] - ms.x) * ms.y * gm.w + bt.w;
;               const unsigned h0 = f2bf(o0), h1 = f2bf(o1), h2 = f2bf(o2), h3 = f2bf(o3);
;               u32x2 ob; ob[0] = h0 | (h1 << 16); ob[1] = h2 | (h3 << 16);
;               *reinterpret_cast<u32x2*>(smem + (rr >> 1) * PIECE + (rr & 1) * 512 + cc * 2) = ob;
;               const int l0 = min(((int)__float_as_uint(o0) - (int)(h0 << 16) + 128) >> 8, 127);
;               const int l1 = min(((int)__float_as_uint(o1) - (int)(h1 << 16) + 128) >> 8, 127);
;               const int l2 = min(((int)__float_as_uint(o2) - (int)(h2 << 16) + 128) >> 8, 127);
;               const int l3 = min(((int)__float_as_uint(o3) - (int)(h3 << 16) + 128) >> 8, 127);
;               *reinterpret_cast<unsigned*>(smem + LOBASE + (rr >> 2) * PIECE + (rr & 3) * 256 + cc) =
;                   (unsigned)(l0 & 255) | ((unsigned)(l1 & 255) << 8) | ((unsigned)(l2 & 255) << 16) | ((unsigned)l3 << 24);
	v_pk_add_f32 v[30:31], v[50:51], v[28:29] op_sel_hi:[1,0] neg_lo:[0,1] neg_hi:[0,1]
	s_nop 0
	v_pk_mul_f32 v[30:31], v[28:29], v[30:31] op_sel:[1,0]
	v_pk_add_f32 v[36:37], v[48:49], v[28:29] op_sel_hi:[1,0] neg_lo:[0,1] neg_hi:[0,1]
	v_mov_b32_e32 v24, v1
	v_mov_b32_e32 v25, v2
	v_mov_b32_e32 v26, v5
	v_mov_b32_e32 v27, v6
	v_pk_fma_f32 v[30:31], v[24:25], v[30:31], v[26:27]
	v_pk_mul_f32 v[28:29], v[28:29], v[36:37] op_sel:[1,0]
	v_mov_b32_e32 v1, v3
	v_mov_b32_e32 v5, v7
	v_and_b32_sdwa v6, v31, v216 dst_sel:DWORD dst_unused:UNUSED_PAD src0_sel:WORD_1 src1_sel:DWORD
	v_and_b32_sdwa v7, v30, v216 dst_sel:DWORD dst_unused:UNUSED_PAD src0_sel:WORD_1 src1_sel:DWORD
	v_pk_fma_f32 v[2:3], v[0:1], v[28:29], v[4:5]
	v_add3_u32 v23, v31, v6, s82
	v_add3_u32 v6, v30, v7, s82
	v_and_b32_e32 v28, 0xffff0000, v6
	v_and_b32_sdwa v6, v3, v216 dst_sel:DWORD dst_unused:UNUSED_PAD src0_sel:WORD_1 src1_sel:DWORD
	v_and_b32_sdwa v7, v2, v216 dst_sel:DWORD dst_unused:UNUSED_PAD src0_sel:WORD_1 src1_sel:DWORD
	v_add3_u32 v6, v3, v6, s82
	v_add3_u32 v29, v2, v7, s82
	v_and_b32_e32 v36, 0xffff0000, v6
	v_or_b32_sdwa v7, v36, v23 dst_sel:DWORD dst_unused:UNUSED_PAD src0_sel:DWORD src1_sel:WORD_1
	v_or_b32_sdwa v6, v29, v28 dst_sel:DWORD dst_unused:UNUSED_PAD src0_sel:WORD_1 src1_sel:DWORD
	ds_write_b64 v93, v[6:7]
	v_and_b32_e32 v6, 0xffff0000, v29
	v_sub_u32_e32 v2, v2, v6
	v_sub_u32_e32 v6, v30, v28
	v_and_b32_e32 v7, 0xffff0000, v23
	v_add_u32_e32 v6, 0x80, v6
	v_sub_u32_e32 v7, v31, v7
	v_sub_u32_e32 v3, v3, v36
	v_add_u32_e32 v2, 0x80, v2
	v_ashrrev_i32_e32 v6, 8, v6
	v_add_u32_e32 v7, 0x80, v7
	v_add_u32_e32 v3, 0x80, v3
	v_ashrrev_i32_e32 v2, 8, v2
	v_min_i32_e32 v6, 0x7f, v6
	v_ashrrev_i32_e32 v7, 8, v7
	v_ashrrev_i32_e32 v3, 8, v3
	v_min_i32_e32 v2, 0x7f, v2
	v_min_i32_sdwa v7, v7, s83 dst_sel:WORD_1 dst_unused:UNUSED_PAD src0_sel:DWORD src1_sel:DWORD
	v_min_i32_e32 v3, 0x7f, v3
	v_lshlrev_b32_e32 v6, 8, v6
	v_and_b32_e32 v6, 0xff00, v6
	v_and_b32_e32 v7, 0xff0000, v7
	v_perm_b32 v2, v3, v2, s84
	v_or3_b32 v2, v2, v6, v7
	ds_write_b32 v12, v2 offset:144
	ds_read_b64 v[2:3], v13 offset:1024
	s_waitcnt lgkmcnt(0)
	v_pk_add_f32 v[6:7], v[34:35], v[2:3] op_sel_hi:[1,0] neg_lo:[0,1] neg_hi:[0,1]
	s_nop 0
	v_pk_mul_f32 v[6:7], v[2:3], v[6:7] op_sel:[1,0]
	v_pk_add_f32 v[12:13], v[32:33], v[2:3] op_sel_hi:[1,0] neg_lo:[0,1] neg_hi:[0,1]
	v_pk_fma_f32 v[6:7], v[24:25], v[6:7], v[26:27]
	v_pk_mul_f32 v[2:3], v[2:3], v[12:13] op_sel:[1,0]
	v_and_b32_sdwa v12, v7, v216 dst_sel:DWORD dst_unused:UNUSED_PAD src0_sel:WORD_1 src1_sel:DWORD
	v_and_b32_sdwa v13, v6, v216 dst_sel:DWORD dst_unused:UNUSED_PAD src0_sel:WORD_1 src1_sel:DWORD
	v_pk_fma_f32 v[2:3], v[0:1], v[2:3], v[4:5]
	v_add3_u32 v23, v7, v12, s82
	v_add3_u32 v12, v6, v13, s82
	v_and_b32_e32 v28, 0xffff0000, v12
	v_and_b32_sdwa v12, v3, v216 dst_sel:DWORD dst_unused:UNUSED_PAD src0_sel:WORD_1 src1_sel:DWORD
	v_and_b32_sdwa v13, v2, v216 dst_sel:DWORD dst_unused:UNUSED_PAD src0_sel:WORD_1 src1_sel:DWORD
	v_add3_u32 v12, v3, v12, s82
	v_add3_u32 v29, v2, v13, s82
	v_and_b32_e32 v30, 0xffff0000, v12
	v_or_b32_sdwa v13, v30, v23 dst_sel:DWORD dst_unused:UNUSED_PAD src0_sel:DWORD src1_sel:WORD_1
	v_or_b32_sdwa v12, v29, v28 dst_sel:DWORD dst_unused:UNUSED_PAD src0_sel:WORD_1 src1_sel:DWORD
	ds_write_b64 v94, v[12:13]
	v_and_b32_e32 v12, 0xffff0000, v29
	v_sub_u32_e32 v2, v2, v12
	v_sub_u32_e32 v6, v6, v28
	v_and_b32_e32 v12, 0xffff0000, v23
	v_add_u32_e32 v6, 0x80, v6
	v_sub_u32_e32 v7, v7, v12
	v_sub_u32_e32 v3, v3, v30
	v_add_u32_e32 v2, 0x80, v2
	v_ashrrev_i32_e32 v6, 8, v6
	v_add_u32_e32 v7, 0x80, v7
	v_add_u32_e32 v3, 0x80, v3
	v_ashrrev_i32_e32 v2, 8, v2
	v_min_i32_e32 v6, 0x7f, v6
	v_ashrrev_i32_e32 v7, 8, v7
	v_ashrrev_i32_e32 v3, 8, v3
	v_min_i32_e32 v2, 0x7f, v2
	v_min_i32_sdwa v7, v7, s83 dst_sel:WORD_1 dst_unused:UNUSED_PAD src0_sel:DWORD src1_sel:DWORD
	v_min_i32_e32 v3, 0x7f, v3
	v_lshlrev_b32_e32 v6, 8, v6
	v_and_b32_e32 v6, 0xff00, v6
	v_and_b32_e32 v7, 0xff0000, v7
	v_perm_b32 v2, v3, v2, s84
	v_or3_b32 v2, v2, v6, v7
	ds_write_b32 v14, v2 offset:144
	ds_read_b64 v[2:3], v15 offset:1024
	s_waitcnt lgkmcnt(0)
	v_pk_add_f32 v[6:7], v[18:19], v[2:3] op_sel_hi:[1,0] neg_lo:[0,1] neg_hi:[0,1]
	s_nop 0
	v_pk_mul_f32 v[6:7], v[2:3], v[6:7] op_sel:[1,0]
	v_pk_add_f32 v[12:13], v[16:17], v[2:3] op_sel_hi:[1,0] neg_lo:[0,1] neg_hi:[0,1]
	v_pk_fma_f32 v[6:7], v[24:25], v[6:7], v[26:27]
	v_pk_mul_f32 v[2:3], v[2:3], v[12:13] op_sel:[1,0]
	v_and_b32_sdwa v12, v7, v216 dst_sel:DWORD dst_unused:UNUSED_PAD src0_sel:WORD_1 src1_sel:DWORD
	v_and_b32_sdwa v13, v6, v216 dst_sel:DWORD dst_unused:UNUSED_PAD src0_sel:WORD_1 src1_sel:DWORD
	v_pk_fma_f32 v[2:3], v[0:1], v[2:3], v[4:5]
	v_add3_u32 v14, v7, v12, s82
	v_add3_u32 v12, v6, v13, s82
	v_and_b32_e32 v15, 0xffff0000, v12
	v_and_b32_sdwa v12, v3, v216 dst_sel:DWORD dst_unused:UNUSED_PAD src0_sel:WORD_1 src1_sel:DWORD
	v_and_b32_sdwa v13, v2, v216 dst_sel:DWORD dst_unused:UNUSED_PAD src0_sel:WORD_1 src1_sel:DWORD
	v_add3_u32 v12, v3, v12, s82
	v_add3_u32 v16, v2, v13, s82
	v_and_b32_e32 v17, 0xffff0000, v12
	v_or_b32_sdwa v13, v17, v14 dst_sel:DWORD dst_unused:UNUSED_PAD src0_sel:DWORD src1_sel:WORD_1
	v_or_b32_sdwa v12, v16, v15 dst_sel:DWORD dst_unused:UNUSED_PAD src0_sel:WORD_1 src1_sel:DWORD
	ds_write_b64 v80, v[12:13]
	v_and_b32_e32 v12, 0xffff0000, v16
	v_sub_u32_e32 v2, v2, v12
	v_sub_u32_e32 v6, v6, v15
	v_and_b32_e32 v12, 0xffff0000, v14
	v_add_u32_e32 v6, 0x80, v6
	v_sub_u32_e32 v7, v7, v12
	v_sub_u32_e32 v3, v3, v17
	v_add_u32_e32 v2, 0x80, v2
	v_ashrrev_i32_e32 v6, 8, v6
	v_add_u32_e32 v7, 0x80, v7
	v_add_u32_e32 v3, 0x80, v3
	v_ashrrev_i32_e32 v2, 8, v2
	v_min_i32_e32 v6, 0x7f, v6
	v_ashrrev_i32_e32 v7, 8, v7
	v_ashrrev_i32_e32 v3, 8, v3
	v_min_i32_e32 v2, 0x7f, v2
	v_min_i32_sdwa v7, v7, s83 dst_sel:WORD_1 dst_unused:UNUSED_PAD src0_sel:DWORD src1_sel:DWORD
	v_min_i32_e32 v3, 0x7f, v3
	v_lshlrev_b32_e32 v6, 8, v6
	v_and_b32_e32 v6, 0xff00, v6
	v_and_b32_e32 v7, 0xff0000, v7
	v_perm_b32 v2, v3, v2, s84
	v_or3_b32 v2, v2, v6, v7
	ds_write_b32 v20, v2 offset:144
	ds_read_b64 v[2:3], v21 offset:1024
	s_waitcnt lgkmcnt(0)
;     ...
;   auto issue_prologue = [&](int sA0, int sA1, int sB0, int sB1) {
;     const int tid = opaque_tid(wave);
;     int offA[2], offB[2];
;     _Pragma("unroll") for (int i = 0; i < 2; ++i) {
;       int r, c; stage_rc(tid * 16 + i * 8192, r, c);
;     ...
;               const float2 ms = *reinterpret_cast<const float2*>(mr + (ai * HALF + rr) * 2);
;               f32x4 y = acc[ai][bj][m][n];
;               const float o0 = (y[0] - ms.x) * ms.y * gm.x + bt.x, o1 = (y[1] - ms.x) * ms.y * gm.y + bt.y;
;               const float o2 = (y[2] - ms.x) * ms.y * gm.z + bt.z, o3 = (y[3] - ms.x) * ms.y * gm.w + bt.w;
;               const unsigned h0 = f2bf(o0), h1 = f2bf(o1), h2 = f2bf(o2), h3 = f2bf(o3);
;               u32x2 ob; ob[0] = h0 | (h1 << 16); ob[1] = h2 | (h3 << 16);
;               *reinterpret_cast<u32x2*>(smem + (rr >> 1) * PIECE + (rr & 1) * 512 + cc * 2) = ob;
;               const int l0 = min(((int)__float_as_uint(o0) - (int)(h0 << 16) + 128) >> 8, 127);
;               const int l1 = min(((int)__float_as_uint(o1) - (int)(h1 << 16) + 128) >> 8, 127);
;               const int l2 = min(((int)__float_as_uint(o2) - (int)(h2 << 16) + 128) >> 8, 127);
;               const int l3 = min(((int)__float_as_uint(o3) - (int)(h3 << 16) + 128) >> 8, 127);
;               *reinterpret_cast<unsigned*>(smem + LOBASE + (rr >> 2) * PIECE + (rr & 3) * 256 + cc) =
;                   (unsigned)(l0 & 255) | ((unsigned)(l1 & 255) << 8) | ((unsigned)(l2 & 255) << 16) | ((unsigned)l3 << 24);
;             }
;           }
;           WAIT_L(0); BAR;
;           const int hso = ((brow + ai * HALF + 16 * wave) * DM + pn * BM) * 2;
;           const int lso = (brow + ai * HALF + 16 * wave) * DM + pn * BM;
;           _Pragma("unroll") for (int i = 0; i < 8; ++i) {
;             const u32x4 v = *reinterpret_cast<const u32x4*>(smem + (wave * 8 + i) * PIECE + lane3 * 16);
;             __builtin_amdgcn_raw_buffer_store_b128(v, rsXB, hvo + i * (2 * DM * 2), hso, 0);
;           }
;           _Pragma("unroll") for (int i = 0; i < 4; ++i) {
;             const u32x4 v = *reinterpret_cast<const u32x4*>(smem + LOBASE + (wave * 4 + i) * PIECE + lane3 * 16);
;             __builtin_amdgcn_raw_buffer_store_b128(v, rsLO, lvo + i * (4 * DM), lso, 0);
;           }
;           WAIT_L(0); BAR;
;         }
;       }
;       if (has_next) issue_prologue(nA0, nA1, nB0, nB1);
	v_pk_add_f32 v[6:7], v[10:11], v[2:3] op_sel_hi:[1,0] neg_lo:[0,1] neg_hi:[0,1]
	s_nop 0
	v_pk_mul_f32 v[6:7], v[2:3], v[6:7] op_sel:[1,0]
	v_pk_add_f32 v[8:9], v[8:9], v[2:3] op_sel_hi:[1,0] neg_lo:[0,1] neg_hi:[0,1]
	v_pk_fma_f32 v[6:7], v[24:25], v[6:7], v[26:27]
	v_pk_mul_f32 v[2:3], v[2:3], v[8:9] op_sel:[1,0]
	s_nop 0
	v_pk_fma_f32 v[0:1], v[0:1], v[2:3], v[4:5]
	v_and_b32_sdwa v2, v7, v216 dst_sel:DWORD dst_unused:UNUSED_PAD src0_sel:WORD_1 src1_sel:DWORD
	v_and_b32_sdwa v3, v6, v216 dst_sel:DWORD dst_unused:UNUSED_PAD src0_sel:WORD_1 src1_sel:DWORD
	v_add3_u32 v4, v7, v2, s82
	v_add3_u32 v2, v6, v3, s82
	v_and_b32_e32 v5, 0xffff0000, v2
	v_and_b32_sdwa v2, v1, v216 dst_sel:DWORD dst_unused:UNUSED_PAD src0_sel:WORD_1 src1_sel:DWORD
	v_and_b32_sdwa v3, v0, v216 dst_sel:DWORD dst_unused:UNUSED_PAD src0_sel:WORD_1 src1_sel:DWORD
	v_add3_u32 v2, v1, v2, s82
	v_add3_u32 v8, v0, v3, s82
	v_and_b32_e32 v9, 0xffff0000, v2
	v_or_b32_sdwa v3, v9, v4 dst_sel:DWORD dst_unused:UNUSED_PAD src0_sel:DWORD src1_sel:WORD_1
	v_or_b32_sdwa v2, v8, v5 dst_sel:DWORD dst_unused:UNUSED_PAD src0_sel:WORD_1 src1_sel:DWORD
	ds_write_b64 v73, v[2:3]
	v_and_b32_e32 v2, 0xffff0000, v8
	v_sub_u32_e32 v0, v0, v2
	v_sub_u32_e32 v2, v6, v5
	v_and_b32_e32 v3, 0xffff0000, v4
	v_add_u32_e32 v2, 0x80, v2
	v_sub_u32_e32 v3, v7, v3
	v_sub_u32_e32 v1, v1, v9
	v_add_u32_e32 v0, 0x80, v0
	v_ashrrev_i32_e32 v2, 8, v2
	v_add_u32_e32 v3, 0x80, v3
	v_add_u32_e32 v1, 0x80, v1
	v_ashrrev_i32_e32 v0, 8, v0
	v_min_i32_e32 v2, 0x7f, v2
	v_ashrrev_i32_e32 v3, 8, v3
	v_ashrrev_i32_e32 v1, 8, v1
	v_min_i32_e32 v0, 0x7f, v0
	v_min_i32_sdwa v3, v3, s83 dst_sel:WORD_1 dst_unused:UNUSED_PAD src0_sel:DWORD src1_sel:DWORD
	v_min_i32_e32 v1, 0x7f, v1
	v_lshlrev_b32_e32 v2, 8, v2
	v_and_b32_e32 v2, 0xff00, v2
	v_and_b32_e32 v3, 0xff0000, v3
	v_perm_b32 v0, v1, v0, s84
	v_or3_b32 v0, v0, v2, v3
	ds_write_b32 v22, v0 offset:144
	s_waitcnt lgkmcnt(0)
	s_barrier
	ds_read_b128 v[128:131], v72
	ds_read_b128 v[132:135], v72 offset:1040
	ds_read_b128 v[136:139], v72 offset:2080
	ds_read_b128 v[140:143], v72 offset:3120
	ds_read_b128 v[152:155], v72 offset:4160
	ds_read_b128 v[156:159], v72 offset:5200
	ds_read_b128 v[160:163], v72 offset:6240
	ds_read_b128 v[164:167], v72 offset:7280
	ds_read_b128 v[168:171], v147
	ds_read_b128 v[172:175], v147 offset:1040
	ds_read_b128 v[176:179], v147 offset:2080
	ds_read_b128 v[180:183], v147 offset:3120
	s_waitcnt lgkmcnt(0)
	s_barrier
	s_cbranch_vccnz .Lmy_s1n_379
	v_mbcnt_lo_u32_b32 v0, -1, 0
	v_mbcnt_hi_u32_b32 v0, -1, v0
	s_mov_b32 m0, s37
	v_lshl_add_u32 v0, v0, 4, s35
	v_ashrrev_i32_e32 v1, 31, v0
	v_lshrrev_b32_e32 v1, 22, v1
	v_add_u32_e32 v1, v0, v1
	v_ashrrev_i32_e32 v1, 10, v1
	v_mul_i32_i24_e32 v2, 0x400, v1
	v_sub_u32_e32 v2, v0, v2
	v_lshrrev_b32_e32 v3, 4, v2
	v_bitop3_b32 v2, v3, v2, 32 bitop3:0x6c
	v_ashrrev_i32_e32 v4, 31, v2
	v_lshrrev_b32_e32 v4, 26, v4
	v_add_u32_e32 v4, v2, v4
	v_lshrrev_b32_e32 v5, 6, v4
	v_and_b32_e32 v4, 0xc0, v4
	v_lshlrev_b32_e32 v3, 3, v1
	v_lshlrev_b32_e32 v1, 5, v1
	v_sub_u32_e32 v2, v2, v4
	v_and_b32_e32 v3, 0x7fff0, v3
	v_and_b32_e32 v1, 32, v1
	v_ashrrev_i16_sdwa v2, v216, sext(v2) dst_sel:DWORD dst_unused:UNUSED_PAD src0_sel:DWORD src1_sel:BYTE_0
	v_add_u32_sdwa v1, v1, sext(v2) dst_sel:DWORD dst_unused:UNUSED_PAD src0_sel:DWORD src1_sel:WORD_0
	v_add_lshl_u32 v2, v5, v3, 13
	v_add_u32_e32 v0, 0x2000, v0
	v_lshl_add_u32 v1, v1, 1, v2
	v_ashrrev_i32_e32 v2, 31, v0
	v_lshrrev_b32_e32 v2, 22, v2
	v_add_u32_e32 v2, v0, v2
	v_ashrrev_i32_e32 v2, 10, v2
	v_mul_i32_i24_e32 v3, 0x400, v2
	v_sub_u32_e32 v0, v0, v3
	v_lshrrev_b32_e32 v3, 4, v0
	v_bitop3_b32 v0, v3, v0, 32 bitop3:0x6c
	v_ashrrev_i32_e32 v4, 31, v0
	v_lshrrev_b32_e32 v4, 26, v4
	v_add_u32_e32 v4, v0, v4
	v_lshrrev_b32_e32 v5, 6, v4
	v_and_b32_e32 v4, 0xffc0, v4
	v_sub_u32_e32 v0, v0, v4
	v_lshrrev_b16_e32 v4, 7, v0
	v_and_b32_e32 v4, 1, v4
	v_lshlrev_b32_e32 v3, 3, v2
	v_lshlrev_b32_e32 v2, 5, v2
	v_add_u16_e32 v0, v0, v4
	v_and_b32_e32 v3, 0x7fff0, v3
	v_and_b32_e32 v2, 32, v2
	v_ashrrev_i16_sdwa v0, v216, sext(v0) dst_sel:DWORD dst_unused:UNUSED_PAD src0_sel:DWORD src1_sel:BYTE_0
	v_add_u32_sdwa v0, v2, sext(v0) dst_sel:DWORD dst_unused:UNUSED_PAD src0_sel:DWORD src1_sel:WORD_0
	v_add_lshl_u32 v2, v5, v3, 13
	s_mov_b32 s14, s10
	s_mov_b32 s15, s11
	v_lshl_add_u32 v0, v0, 1, v2
	buffer_load_dwordx4 v1, s[12:15], s92 offen lds
	s_mov_b32 m0, s48
	s_or_b32 s0, s92, 0x80
	buffer_load_dwordx4 v0, s[12:15], s92 offen lds
	s_mov_b32 m0, s35
	s_mov_b64 s[4:5], 0
	buffer_load_dwordx4 v1, s[8:11], s87 offen lds
	s_mov_b32 m0, s49
	s_nop 0
	buffer_load_dwordx4 v0, s[8:11], s87 offen lds
	s_mov_b32 m0, s38
	s_nop 0
	buffer_load_dwordx4 v1, s[12:15], s93 offen lds
	s_mov_b32 m0, s54
	s_nop 0
	buffer_load_dwordx4 v0, s[12:15], s93 offen lds
	s_mov_b32 m0, s39
	s_nop 0
	buffer_load_dwordx4 v1, s[8:11], s86 offen lds
	s_mov_b32 m0, s55
	s_nop 0
	buffer_load_dwordx4 v0, s[8:11], s86 offen lds
	s_mov_b32 m0, s42
	s_nop 0
	buffer_load_dwordx4 v1, s[12:15], s0 offen lds
	s_mov_b32 m0, s56
	s_nop 0
	buffer_load_dwordx4 v0, s[12:15], s0 offen lds
	s_or_b32 s0, s87, 0x80
	s_mov_b32 m0, s43
	s_nop 0
	buffer_load_dwordx4 v1, s[8:11], s0 offen lds
	s_mov_b32 m0, s57
	s_nop 0
	buffer_load_dwordx4 v0, s[8:11], s0 offen lds
	s_add_i32 s0, s93, 0x80
	s_mov_b32 m0, s44
	s_nop 0
	buffer_load_dwordx4 v1, s[12:15], s0 offen lds
	s_mov_b32 m0, s58
	s_nop 0
	buffer_load_dwordx4 v0, s[12:15], s0 offen lds
	buffer_store_dwordx4 v[128:131], v148, s[16:19], s3 offen
	buffer_store_dwordx4 v[132:135], v74, s[16:19], s3 offen
	buffer_store_dwordx4 v[136:139], v75, s[16:19], s3 offen
	buffer_store_dwordx4 v[140:143], v81, s[16:19], s3 offen
	buffer_store_dwordx4 v[152:155], v82, s[16:19], s3 offen
	buffer_store_dwordx4 v[156:159], v83, s[16:19], s3 offen
	buffer_store_dwordx4 v[160:163], v88, s[16:19], s3 offen
	buffer_store_dwordx4 v[164:167], v89, s[16:19], s3 offen
	buffer_store_dwordx4 v[168:171], v146, s[20:23], s1 offen
	buffer_store_dwordx4 v[172:175], v90, s[20:23], s1 offen
	buffer_store_dwordx4 v[176:179], v91, s[20:23], s1 offen
	buffer_store_dwordx4 v[180:183], v95, s[20:23], s1 offen
	s_branch .LBB0_384
.Lmy_s1n_379:
	buffer_store_dwordx4 v[128:131], v148, s[16:19], s3 offen
	buffer_store_dwordx4 v[132:135], v74, s[16:19], s3 offen
	buffer_store_dwordx4 v[136:139], v75, s[16:19], s3 offen
	buffer_store_dwordx4 v[140:143], v81, s[16:19], s3 offen
	buffer_store_dwordx4 v[152:155], v82, s[16:19], s3 offen
	buffer_store_dwordx4 v[156:159], v83, s[16:19], s3 offen
	buffer_store_dwordx4 v[160:163], v88, s[16:19], s3 offen
	buffer_store_dwordx4 v[164:167], v89, s[16:19], s3 offen
	buffer_store_dwordx4 v[168:171], v146, s[20:23], s1 offen
	buffer_store_dwordx4 v[172:175], v90, s[20:23], s1 offen
	buffer_store_dwordx4 v[176:179], v91, s[20:23], s1 offen
	buffer_store_dwordx4 v[180:183], v95, s[20:23], s1 offen
	s_branch .LBB0_384

;     ...
;       const int tid3 = opaque_tid(wave);
;       const int wr3 = tid3 >> 8, wc3 = (tid3 >> 6) & 3, fr3 = tid3 & 15, fq3 = (tid3 & 63) >> 4;
;       const int ebase3 = (brow + wr3 * 64 + fr3) * DM + pn * BM + wc3 * 32 + fq3 * 4;
;       const int vo4b = ebase3 * 4, vo2 = ebase3 * 2, vo1 = ebase3;
;       (void)vo4b; (void)vo2; (void)vo1;
;       if constexpr (OUTF) {
;         _Pragma("unroll") for (int bj = 0; bj < 2; ++bj) _Pragma("unroll") for (int n = 0; n < 2; ++n) {
;           const int col = pn * BM + bj * HALF + wc3 * 32 + n * 16 + fq3 * 4;
;           const float4 gm = *reinterpret_cast<const float4*>(g.gam + col), bt = *reinterpret_cast<const float4*>(g.bet + col);
;           _Pragma("unroll") for (int ai = 0; ai < 2; ++ai) _Pragma("unroll") for (int m = 0; m < 4; ++m) {
;             const int rl = ai * HALF + wr3 * 64 + m * 16 + fr3;
;             const float2 ms = *reinterpret_cast<const float2*>(mr + rl * 2);
;             f32x4 y = acc[ai][bj][m][n];
;             u32x4 o;
;             o[0] = __float_as_uint((y[0] - ms.x) * ms.y * gm.x + bt.x); o[1] = __float_as_uint((y[1] - ms.x) * ms.y * gm.y + bt.y);
;             o[2] = __float_as_uint((y[2] - ms.x) * ms.y * gm.z + bt.z); o[3] = __float_as_uint((y[3] - ms.x) * ms.y * gm.w + bt.w);
;             __builtin_amdgcn_raw_buffer_store_b128(o, rsO, vo4b + ((ai * HALF + m * 16) * DM + bj * HALF + n * 16) * 4, 0, 0);
;           }
;         }
;       } else {
;         constexpr int PIECE = 1024 + 16, LOBASE = 64 * PIECE;
;         const int lane3 = tid3 & 63;
;         const int hvo = (lane3 >> 5) * (DM * 2) + (lane3 & 31) * 16;
;         const int lvo = (lane3 >> 4) * DM + (lane3 & 15) * 16;
;         _Pragma("unroll") for (int ai = 0; ai < 2; ++ai) {
;           _Pragma("unroll") for (int bj = 0; bj < 2; ++bj) _Pragma("unroll") for (int n = 0; n < 2; ++n) {
;             const int cc = bj * HALF + wc3 * 32 + n * 16 + fq3 * 4;
;             const float4 gm = *reinterpret_cast<const float4*>(g.gam + pn * BM + cc), bt = *reinterpret_cast<const float4*>(g.bet + pn * BM + cc);
;             _Pragma("unroll") for (int m = 0; m < 4; ++m) {
;               const int rr = wr3 * 64 + m * 16 + fr3;
;               const float2 ms = *reinterpret_cast<const float2*>(mr + (ai * HALF + rr) * 2);
;               f32x4 y = acc[ai][bj][m][n];
.LBB0_523:
	s_or_b64 exec, exec, s[6:7]
	s_waitcnt lgkmcnt(0)
	s_barrier
	v_mbcnt_lo_u32_b32 v0, -1, 0
	v_mbcnt_hi_u32_b32 v0, -1, v0
	v_readlane_b32 s40, v255, 0
	v_add_u32_e32 v1, s34, v0
	v_bfe_u32 v4, v0, 4, 2
	v_ashrrev_i32_e32 v5, 2, v1
	v_lshrrev_b32_e32 v6, 1, v1
	v_lshlrev_b32_e32 v1, 4, v1
	v_lshlrev_b32_e32 v7, 2, v4
	v_lshlrev_b32_e32 v12, 7, v0
	v_and_b32_e32 v13, 0x1f0, v1
	s_movk_i32 s4, 0x60
	s_ashr_i32 s29, s28, 31
	v_readlane_b32 s54, v255, 14
	v_readlane_b32 s55, v255, 15
	v_and_or_b32 v148, v12, s75, v13
	v_and_or_b32 v12, v6, s4, v7
	s_lshl_b64 s[4:5], s[28:29], 2
	s_mov_b64 s[22:23], s[54:55]
	s_add_u32 s6, s22, s4
	v_and_b32_e32 v2, 15, v0
	v_and_b32_e32 v3, 63, v0
	v_and_b32_e32 v1, 0xf0, v1
	v_lshlrev_b32_e32 v13, 9, v0
	v_lshlrev_b32_e32 v0, 8, v0
	s_addc_u32 s7, s23, s5
	v_lshlrev_b32_e32 v150, 2, v12
	v_lshl_or_b32 v146, v4, 11, v1
	v_and_or_b32 v156, v5, s31, v2
	v_and_b32_e32 v14, 0x300, v0
	v_lshlrev_b32_e32 v151, 4, v3
	global_load_dwordx4 v[220:223], v150, s[6:7]
	global_load_dwordx4 v[224:227], v150, s[6:7] offset:64
	global_load_dwordx4 v[228:231], v150, s[6:7] offset:512
	global_load_dwordx4 v[232:235], v150, s[6:7] offset:576
	v_readlane_b32 s41, v255, 1
	v_readlane_b32 s42, v255, 2
	v_readlane_b32 s43, v255, 3
	v_readlane_b32 s44, v255, 4
	v_readlane_b32 s45, v255, 5
	v_readlane_b32 s46, v255, 6
	v_readlane_b32 s47, v255, 7
	v_readlane_b32 s48, v255, 8
	v_readlane_b32 s49, v255, 9
	v_readlane_b32 s50, v255, 10
	v_readlane_b32 s51, v255, 11
	v_readlane_b32 s52, v255, 12
	v_readlane_b32 s53, v255, 13
	v_readlane_b32 s40, v255, 16
	v_readlane_b32 s41, v255, 17
	s_add_u32 s4, s40, s4
	s_addc_u32 s5, s41, s5
	global_load_dwordx4 v[236:239], v150, s[4:5]
	global_load_dwordx4 v[240:243], v150, s[4:5] offset:64
	global_load_dwordx4 v[244:247], v150, s[4:5] offset:512
	global_load_dwordx4 v[248:251], v150, s[4:5] offset:576
	s_movk_i32 s22, 0x200
	v_lshl_add_u32 v149, v156, 3, v219
	v_add_u32_e32 v147, s69, v151
	s_andn2_b64 vcc, exec, s[14:15]
	v_readlane_b32 s42, v255, 18
	v_readlane_b32 s43, v255, 19
	v_readlane_b32 s44, v255, 20
	v_readlane_b32 s45, v255, 21
	v_readlane_b32 s46, v255, 22
	v_readlane_b32 s47, v255, 23
	v_readlane_b32 s48, v255, 24
	v_readlane_b32 s49, v255, 25
	v_readlane_b32 s50, v255, 26
	v_readlane_b32 s51, v255, 27
	v_readlane_b32 s52, v255, 28
	v_readlane_b32 s53, v255, 29
	v_readlane_b32 s54, v255, 30
	v_readlane_b32 s55, v255, 31
	s_waitcnt vmcnt(0)
	v_mov_b32_e32 v0, v220
	v_mov_b32_e32 v1, v221
	v_mov_b32_e32 v2, v222
	v_mov_b32_e32 v3, v223
	v_mov_b32_e32 v4, v236
	v_mov_b32_e32 v5, v237
	v_mov_b32_e32 v6, v238
	v_mov_b32_e32 v7, v239
	v_mov_b32_e32 v22, v1
	v_lshlrev_b32_e32 v1, 1, v12
	v_and_or_b32 v155, v13, s22, v1
	s_mov_b32 s22, 0x10400
	v_mov_b32_e32 v23, v2
	v_or3_b32 v2, v14, v12, s22
	ds_read_b64 v[12:13], v149
	v_mov_b32_e32 v1, v3
	s_waitcnt lgkmcnt(0)
	v_pk_add_f32 v[14:15], v[128:129], v[12:13] op_sel_hi:[1,0] neg_lo:[0,1] neg_hi:[0,1]
	s_nop 0
	v_pk_mul_f32 v[14:15], v[12:13], v[14:15] op_sel:[1,0]
	v_pk_add_f32 v[20:21], v[130:131], v[12:13] op_sel_hi:[1,0] neg_lo:[0,1] neg_hi:[0,1]
	v_lshrrev_b32_e32 v129, 1, v156
	v_pk_mul_f32 v[12:13], v[12:13], v[20:21] op_sel:[1,0]
	v_mul_lo_u32 v153, v129, s61
	v_add_u32_e32 v152, v155, v153
	v_mov_b32_e32 v144, v5
	v_mov_b32_e32 v145, v6
	v_pk_fma_f32 v[14:15], v[22:23], v[14:15], v[144:145]
	v_mov_b32_e32 v5, v7
	v_pk_fma_f32 v[6:7], v[0:1], v[12:13], v[4:5]
	v_and_b32_sdwa v12, v14, v216 dst_sel:DWORD dst_unused:UNUSED_PAD src0_sel:WORD_1 src1_sel:DWORD
	v_add3_u32 v12, v14, v12, s78
	v_and_b32_e32 v20, 0xffff0000, v12
	v_and_b32_sdwa v12, v7, v216 dst_sel:DWORD dst_unused:UNUSED_PAD src0_sel:WORD_1 src1_sel:DWORD
	v_and_b32_sdwa v3, v15, v216 dst_sel:DWORD dst_unused:UNUSED_PAD src0_sel:WORD_1 src1_sel:DWORD
	v_and_b32_sdwa v13, v6, v216 dst_sel:DWORD dst_unused:UNUSED_PAD src0_sel:WORD_1 src1_sel:DWORD
	v_add3_u32 v12, v7, v12, s78
	v_add3_u32 v3, v15, v3, s78
	v_add3_u32 v21, v6, v13, s78
	v_and_b32_e32 v128, 0xffff0000, v12
	v_or_b32_sdwa v13, v128, v3 dst_sel:DWORD dst_unused:UNUSED_PAD src0_sel:DWORD src1_sel:WORD_1
	v_or_b32_sdwa v12, v21, v20 dst_sel:DWORD dst_unused:UNUSED_PAD src0_sel:WORD_1 src1_sel:DWORD
	ds_write_b64 v152, v[12:13]
	v_and_b32_e32 v12, 0xffff0000, v21
	v_sub_u32_e32 v6, v6, v12
	v_sub_u32_e32 v12, v14, v20
	v_and_b32_e32 v3, 0xffff0000, v3
	v_add_u32_e32 v12, 0x80, v12
	v_sub_u32_e32 v3, v15, v3
	v_sub_u32_e32 v7, v7, v128
	v_add_u32_e32 v6, 0x80, v6
	v_ashrrev_i32_e32 v12, 8, v12
	v_add_u32_e32 v3, 0x80, v3
	v_add_u32_e32 v7, 0x80, v7
	v_ashrrev_i32_e32 v6, 8, v6
	v_min_i32_e32 v12, 0x7f, v12
	v_ashrrev_i32_e32 v3, 8, v3
	v_ashrrev_i32_e32 v7, 8, v7
	v_min_i32_e32 v6, 0x7f, v6
	v_min_i32_sdwa v3, v3, s79 dst_sel:WORD_1 dst_unused:UNUSED_PAD src0_sel:DWORD src1_sel:DWORD
	v_min_i32_e32 v7, 0x7f, v7
	v_lshlrev_b32_e32 v12, 8, v12
	v_and_b32_e32 v12, 0xff00, v12
	v_and_b32_e32 v3, 0xff0000, v3
	v_perm_b32 v6, v7, v6, s80
	v_or3_b32 v3, v6, v12, v3
	v_lshrrev_b32_e32 v6, 2, v156
	v_mad_u64_u32 v[12:13], s[22:23], v6, s61, v[2:3]
	ds_write_b32 v12, v3
	v_or_b32_e32 v3, 16, v156
	v_lshl_add_u32 v13, v3, 3, v219
	ds_read_b64 v[6:7], v13
	s_waitcnt lgkmcnt(0)
;     ...
;             const int cc = bj * HALF + wc3 * 32 + n * 16 + fq3 * 4;
;             const float4 gm = *reinterpret_cast<const float4*>(g.gam + pn * BM + cc), bt = *reinterpret_cast<const float4*>(g.bet + pn * BM + cc);
;             _Pragma("unroll") for (int m = 0; m < 4; ++m) {
;               const int rr = wr3 * 64 + m * 16 + fr3;
;               const float2 ms = *reinterpret_cast<const float2*>(mr + (ai * HALF + rr) * 2);
;               f32x4 y = acc[ai][bj][m][n];
;               const float o0 = (y[0] - ms.x) * ms.y * gm.x + bt.x, o1 = (y[1] - ms.x) * ms.y * gm.y + bt.y;
;               const float o2 = (y[2] - ms.x) * ms.y * gm.z + bt.z, o3 = (y[3] - ms.x) * ms.y * gm.w + bt.w;
;               const unsigned h0 = f2bf(o0), h1 = f2bf(o1), h2 = f2bf(o2), h3 = f2bf(o3);
;               u32x2 ob; ob[0] = h0 | (h1 << 16); ob[1] = h2 | (h3 << 16);
;               *reinterpret_cast<u32x2*>(smem + (rr >> 1) * PIECE + (rr & 1) * 512 + cc * 2) = ob;
;               const int l0 = min(((int)__float_as_uint(o0) - (int)(h0 << 16) + 128) >> 8, 127);
;               const int l1 = min(((int)__float_as_uint(o1) - (int)(h1 << 16) + 128) >> 8, 127);
;               const int l2 = min(((int)__float_as_uint(o2) - (int)(h2 << 16) + 128) >> 8, 127);
;               const int l3 = min(((int)__float_as_uint(o3) - (int)(h3 << 16) + 128) >> 8, 127);
;               *reinterpret_cast<unsigned*>(smem + LOBASE + (rr >> 2) * PIECE + (rr & 3) * 256 + cc) =
;                   (unsigned)(l0 & 255) | ((unsigned)(l1 & 255) << 8) | ((unsigned)(l2 & 255) << 16) | ((unsigned)l3 << 24);
	v_pk_add_f32 v[14:15], v[134:135], v[6:7] op_sel_hi:[1,0] neg_lo:[0,1] neg_hi:[0,1]
	s_nop 0
	v_pk_mul_f32 v[14:15], v[6:7], v[14:15] op_sel:[1,0]
	v_pk_add_f32 v[20:21], v[132:133], v[6:7] op_sel_hi:[1,0] neg_lo:[0,1] neg_hi:[0,1]
	v_pk_fma_f32 v[14:15], v[22:23], v[14:15], v[144:145]
	v_pk_mul_f32 v[6:7], v[6:7], v[20:21] op_sel:[1,0]
	v_and_b32_sdwa v20, v15, v216 dst_sel:DWORD dst_unused:UNUSED_PAD src0_sel:WORD_1 src1_sel:DWORD
	v_and_b32_sdwa v21, v14, v216 dst_sel:DWORD dst_unused:UNUSED_PAD src0_sel:WORD_1 src1_sel:DWORD
	v_pk_fma_f32 v[6:7], v[0:1], v[6:7], v[4:5]
	v_add3_u32 v128, v15, v20, s78
	v_add3_u32 v20, v14, v21, s78
	v_and_b32_e32 v129, 0xffff0000, v20
	v_and_b32_sdwa v20, v7, v216 dst_sel:DWORD dst_unused:UNUSED_PAD src0_sel:WORD_1 src1_sel:DWORD
	v_and_b32_sdwa v21, v6, v216 dst_sel:DWORD dst_unused:UNUSED_PAD src0_sel:WORD_1 src1_sel:DWORD
	v_add3_u32 v20, v7, v20, s78
	v_lshrrev_b32_e32 v132, 1, v3
	v_add3_u32 v130, v6, v21, s78
	v_and_b32_e32 v131, 0xffff0000, v20
	v_mul_lo_u32 v154, v132, s61
	v_or_b32_sdwa v21, v131, v128 dst_sel:DWORD dst_unused:UNUSED_PAD src0_sel:DWORD src1_sel:WORD_1
	v_or_b32_sdwa v20, v130, v129 dst_sel:DWORD dst_unused:UNUSED_PAD src0_sel:WORD_1 src1_sel:DWORD
	v_add_u32_e32 v132, v155, v154
	ds_write_b64 v132, v[20:21]
	v_and_b32_e32 v20, 0xffff0000, v130
	v_sub_u32_e32 v6, v6, v20
	v_sub_u32_e32 v14, v14, v129
	v_and_b32_e32 v20, 0xffff0000, v128
	v_add_u32_e32 v14, 0x80, v14
	v_sub_u32_e32 v15, v15, v20
	v_sub_u32_e32 v7, v7, v131
	v_add_u32_e32 v6, 0x80, v6
	v_ashrrev_i32_e32 v14, 8, v14
	v_add_u32_e32 v15, 0x80, v15
	v_add_u32_e32 v7, 0x80, v7
	v_ashrrev_i32_e32 v6, 8, v6
	v_min_i32_e32 v14, 0x7f, v14
	v_ashrrev_i32_e32 v15, 8, v15
	v_ashrrev_i32_e32 v7, 8, v7
	v_min_i32_e32 v6, 0x7f, v6
	v_min_i32_sdwa v15, v15, s79 dst_sel:WORD_1 dst_unused:UNUSED_PAD src0_sel:DWORD src1_sel:DWORD
	v_min_i32_e32 v7, 0x7f, v7
	v_lshlrev_b32_e32 v14, 8, v14
	v_and_b32_e32 v14, 0xff00, v14
	v_and_b32_e32 v15, 0xff0000, v15
	v_perm_b32 v6, v7, v6, s80
	v_lshrrev_b32_e32 v3, 2, v3
	v_or3_b32 v6, v6, v14, v15
	v_mad_u64_u32 v[14:15], s[22:23], v3, s61, v[2:3]
	v_or_b32_e32 v3, 32, v156
	ds_write_b32 v14, v6
	v_lshl_add_u32 v15, v3, 3, v219
	ds_read_b64 v[6:7], v15
	v_lshrrev_b32_e32 v133, 1, v3
	v_lshrrev_b32_e32 v3, 2, v3
	s_waitcnt lgkmcnt(0)
	v_pk_add_f32 v[20:21], v[138:139], v[6:7] op_sel_hi:[1,0] neg_lo:[0,1] neg_hi:[0,1]
	s_nop 0
	v_pk_mul_f32 v[20:21], v[6:7], v[20:21] op_sel:[1,0]
	v_pk_add_f32 v[128:129], v[136:137], v[6:7] op_sel_hi:[1,0] neg_lo:[0,1] neg_hi:[0,1]
	v_pk_fma_f32 v[20:21], v[22:23], v[20:21], v[144:145]
	v_pk_mul_f32 v[6:7], v[6:7], v[128:129] op_sel:[1,0]
	v_and_b32_sdwa v128, v21, v216 dst_sel:DWORD dst_unused:UNUSED_PAD src0_sel:WORD_1 src1_sel:DWORD
	v_and_b32_sdwa v129, v20, v216 dst_sel:DWORD dst_unused:UNUSED_PAD src0_sel:WORD_1 src1_sel:DWORD
	v_pk_fma_f32 v[6:7], v[0:1], v[6:7], v[4:5]
	v_add3_u32 v130, v21, v128, s78
	v_add3_u32 v128, v20, v129, s78
	v_and_b32_e32 v131, 0xffff0000, v128
	v_and_b32_sdwa v128, v7, v216 dst_sel:DWORD dst_unused:UNUSED_PAD src0_sel:WORD_1 src1_sel:DWORD
	v_and_b32_sdwa v129, v6, v216 dst_sel:DWORD dst_unused:UNUSED_PAD src0_sel:WORD_1 src1_sel:DWORD
	v_add3_u32 v128, v7, v128, s78
	v_add3_u32 v134, v6, v129, s78
	v_and_b32_e32 v135, 0xffff0000, v128
	v_mul_lo_u32 v136, v133, s61
	v_or_b32_sdwa v129, v135, v130 dst_sel:DWORD dst_unused:UNUSED_PAD src0_sel:DWORD src1_sel:WORD_1
	v_or_b32_sdwa v128, v134, v131 dst_sel:DWORD dst_unused:UNUSED_PAD src0_sel:WORD_1 src1_sel:DWORD
	v_add_u32_e32 v133, v155, v136
	ds_write_b64 v133, v[128:129]
	v_and_b32_e32 v128, 0xffff0000, v134
	v_sub_u32_e32 v6, v6, v128
	v_sub_u32_e32 v20, v20, v131
	v_and_b32_e32 v128, 0xffff0000, v130
	v_add_u32_e32 v20, 0x80, v20
	v_sub_u32_e32 v21, v21, v128
	v_sub_u32_e32 v7, v7, v135
	v_add_u32_e32 v6, 0x80, v6
	v_ashrrev_i32_e32 v20, 8, v20
	v_add_u32_e32 v21, 0x80, v21
	v_add_u32_e32 v7, 0x80, v7
	v_ashrrev_i32_e32 v6, 8, v6
	v_min_i32_e32 v20, 0x7f, v20
	v_ashrrev_i32_e32 v21, 8, v21
	v_ashrrev_i32_e32 v7, 8, v7
	v_min_i32_e32 v6, 0x7f, v6
	v_min_i32_sdwa v21, v21, s79 dst_sel:WORD_1 dst_unused:UNUSED_PAD src0_sel:DWORD src1_sel:DWORD
	v_min_i32_e32 v7, 0x7f, v7
	v_lshlrev_b32_e32 v20, 8, v20
	v_and_b32_e32 v20, 0xff00, v20
	v_and_b32_e32 v21, 0xff0000, v21
	v_perm_b32 v6, v7, v6, s80
	v_or3_b32 v6, v6, v20, v21
	v_mad_u64_u32 v[20:21], s[22:23], v3, s61, v[2:3]
	v_or_b32_e32 v3, 48, v156
	ds_write_b32 v20, v6
	v_lshl_add_u32 v21, v3, 3, v219
	ds_read_b64 v[6:7], v21
	v_lshrrev_b32_e32 v130, 1, v3
	v_mul_lo_u32 v135, v130, s61
	v_add_u32_e32 v134, v155, v135
	s_waitcnt lgkmcnt(0)
;     ...
;             const int cc = bj * HALF + wc3 * 32 + n * 16 + fq3 * 4;
;             const float4 gm = *reinterpret_cast<const float4*>(g.gam + pn * BM + cc), bt = *reinterpret_cast<const float4*>(g.bet + pn * BM + cc);
;             _Pragma("unroll") for (int m = 0; m < 4; ++m) {
;               const int rr = wr3 * 64 + m * 16 + fr3;
;               const float2 ms = *reinterpret_cast<const float2*>(mr + (ai * HALF + rr) * 2);
;               f32x4 y = acc[ai][bj][m][n];
;               const float o0 = (y[0] - ms.x) * ms.y * gm.x + bt.x, o1 = (y[1] - ms.x) * ms.y * gm.y + bt.y;
;               const float o2 = (y[2] - ms.x) * ms.y * gm.z + bt.z, o3 = (y[3] - ms.x) * ms.y * gm.w + bt.w;
;               const unsigned h0 = f2bf(o0), h1 = f2bf(o1), h2 = f2bf(o2), h3 = f2bf(o3);
;               u32x2 ob; ob[0] = h0 | (h1 << 16); ob[1] = h2 | (h3 << 16);
;               *reinterpret_cast<u32x2*>(smem + (rr >> 1) * PIECE + (rr & 1) * 512 + cc * 2) = ob;
;               const int l0 = min(((int)__float_as_uint(o0) - (int)(h0 << 16) + 128) >> 8, 127);
;               const int l1 = min(((int)__float_as_uint(o1) - (int)(h1 << 16) + 128) >> 8, 127);
;               const int l2 = min(((int)__float_as_uint(o2) - (int)(h2 << 16) + 128) >> 8, 127);
;               const int l3 = min(((int)__float_as_uint(o3) - (int)(h3 << 16) + 128) >> 8, 127);
;               *reinterpret_cast<unsigned*>(smem + LOBASE + (rr >> 2) * PIECE + (rr & 3) * 256 + cc) =
;                   (unsigned)(l0 & 255) | ((unsigned)(l1 & 255) << 8) | ((unsigned)(l2 & 255) << 16) | ((unsigned)l3 << 24);
	v_pk_add_f32 v[128:129], v[142:143], v[6:7] op_sel_hi:[1,0] neg_lo:[0,1] neg_hi:[0,1]
	s_nop 0
	v_pk_mul_f32 v[128:129], v[6:7], v[128:129] op_sel:[1,0]
	s_nop 0
	v_pk_fma_f32 v[22:23], v[22:23], v[128:129], v[144:145]
	v_pk_add_f32 v[128:129], v[140:141], v[6:7] op_sel_hi:[1,0] neg_lo:[0,1] neg_hi:[0,1]
	s_nop 0
	v_pk_mul_f32 v[6:7], v[6:7], v[128:129] op_sel:[1,0]
	s_nop 0
	v_pk_fma_f32 v[0:1], v[0:1], v[6:7], v[4:5]
	v_and_b32_sdwa v4, v23, v216 dst_sel:DWORD dst_unused:UNUSED_PAD src0_sel:WORD_1 src1_sel:DWORD
	v_and_b32_sdwa v5, v22, v216 dst_sel:DWORD dst_unused:UNUSED_PAD src0_sel:WORD_1 src1_sel:DWORD
	v_add3_u32 v6, v23, v4, s78
	v_add3_u32 v4, v22, v5, s78
	v_and_b32_e32 v7, 0xffff0000, v4
	v_and_b32_sdwa v4, v1, v216 dst_sel:DWORD dst_unused:UNUSED_PAD src0_sel:WORD_1 src1_sel:DWORD
	v_and_b32_sdwa v5, v0, v216 dst_sel:DWORD dst_unused:UNUSED_PAD src0_sel:WORD_1 src1_sel:DWORD
	v_add3_u32 v4, v1, v4, s78
	v_add3_u32 v128, v0, v5, s78
	v_and_b32_e32 v129, 0xffff0000, v4
	v_or_b32_sdwa v5, v129, v6 dst_sel:DWORD dst_unused:UNUSED_PAD src0_sel:DWORD src1_sel:WORD_1
	v_or_b32_sdwa v4, v128, v7 dst_sel:DWORD dst_unused:UNUSED_PAD src0_sel:WORD_1 src1_sel:DWORD
	ds_write_b64 v134, v[4:5]
	v_and_b32_e32 v4, 0xffff0000, v128
	v_sub_u32_e32 v0, v0, v4
	v_sub_u32_e32 v4, v22, v7
	v_and_b32_e32 v5, 0xffff0000, v6
	v_add_u32_e32 v4, 0x80, v4
	v_sub_u32_e32 v5, v23, v5
	v_sub_u32_e32 v1, v1, v129
	v_add_u32_e32 v0, 0x80, v0
	v_ashrrev_i32_e32 v4, 8, v4
	v_add_u32_e32 v5, 0x80, v5
	v_add_u32_e32 v1, 0x80, v1
	v_ashrrev_i32_e32 v0, 8, v0
	v_min_i32_e32 v4, 0x7f, v4
	v_ashrrev_i32_e32 v5, 8, v5
	v_ashrrev_i32_e32 v1, 8, v1
	v_min_i32_e32 v0, 0x7f, v0
	v_min_i32_sdwa v5, v5, s79 dst_sel:WORD_1 dst_unused:UNUSED_PAD src0_sel:DWORD src1_sel:DWORD
	v_min_i32_e32 v1, 0x7f, v1
	v_lshlrev_b32_e32 v4, 8, v4
	v_and_b32_e32 v4, 0xff00, v4
	v_and_b32_e32 v5, 0xff0000, v5
	v_perm_b32 v0, v1, v0, s80
	v_lshrrev_b32_e32 v1, 2, v3
	v_or3_b32 v0, v0, v4, v5
	v_mad_u64_u32 v[22:23], s[22:23], v1, s61, v[2:3]
	ds_write_b32 v22, v0
	v_mov_b32_e32 v0, v224
	v_mov_b32_e32 v1, v225
	v_mov_b32_e32 v2, v226
	v_mov_b32_e32 v3, v227
	v_mov_b32_e32 v4, v240
	v_mov_b32_e32 v5, v241
	v_mov_b32_e32 v6, v242
	v_mov_b32_e32 v7, v243
	ds_read_b64 v[138:139], v149
	s_mov_b32 s22, s18
	s_mov_b32 s23, s19
	s_waitcnt lgkmcnt(0)
	v_pk_add_f32 v[124:125], v[124:125], v[138:139] op_sel_hi:[1,0] neg_lo:[0,1] neg_hi:[0,1]
	s_nop 0
	v_pk_mul_f32 v[124:125], v[138:139], v[124:125] op_sel:[1,0]
	v_pk_add_f32 v[126:127], v[126:127], v[138:139] op_sel_hi:[1,0] neg_lo:[0,1] neg_hi:[0,1]
	v_mov_b32_e32 v128, v1
	v_mov_b32_e32 v129, v2
	v_mov_b32_e32 v130, v5
	v_mov_b32_e32 v131, v6
	v_pk_fma_f32 v[124:125], v[128:129], v[124:125], v[130:131]
	v_pk_mul_f32 v[126:127], v[138:139], v[126:127] op_sel:[1,0]
	v_mov_b32_e32 v1, v3
	v_mov_b32_e32 v5, v7
	v_and_b32_sdwa v23, v124, v216 dst_sel:DWORD dst_unused:UNUSED_PAD src0_sel:WORD_1 src1_sel:DWORD
	v_pk_fma_f32 v[6:7], v[0:1], v[126:127], v[4:5]
	v_add3_u32 v23, v124, v23, s78
	v_and_b32_e32 v137, 0xffff0000, v23
	v_and_b32_sdwa v23, v7, v216 dst_sel:DWORD dst_unused:UNUSED_PAD src0_sel:WORD_1 src1_sel:DWORD
	v_and_b32_sdwa v3, v125, v216 dst_sel:DWORD dst_unused:UNUSED_PAD src0_sel:WORD_1 src1_sel:DWORD
	v_and_b32_sdwa v126, v6, v216 dst_sel:DWORD dst_unused:UNUSED_PAD src0_sel:WORD_1 src1_sel:DWORD
	v_add3_u32 v23, v7, v23, s78
	v_or_b32_e32 v2, 32, v155
	v_add3_u32 v3, v125, v3, s78
	v_add3_u32 v138, v6, v126, s78
	v_and_b32_e32 v139, 0xffff0000, v23
	v_or_b32_sdwa v127, v139, v3 dst_sel:DWORD dst_unused:UNUSED_PAD src0_sel:DWORD src1_sel:WORD_1
	v_or_b32_sdwa v126, v138, v137 dst_sel:DWORD dst_unused:UNUSED_PAD src0_sel:WORD_1 src1_sel:DWORD
	v_add_u32_e32 v23, v2, v153
	ds_write_b64 v23, v[126:127]
	v_and_b32_e32 v126, 0xffff0000, v138
	v_sub_u32_e32 v124, v124, v137
	v_and_b32_e32 v3, 0xffff0000, v3
	v_sub_u32_e32 v6, v6, v126
	v_add_u32_e32 v124, 0x80, v124
	v_sub_u32_e32 v3, v125, v3
	v_sub_u32_e32 v7, v7, v139
	v_add_u32_e32 v6, 0x80, v6
	v_ashrrev_i32_e32 v124, 8, v124
	v_add_u32_e32 v3, 0x80, v3
	v_add_u32_e32 v7, 0x80, v7
	v_ashrrev_i32_e32 v6, 8, v6
	v_min_i32_e32 v124, 0x7f, v124
	v_ashrrev_i32_e32 v3, 8, v3
	v_ashrrev_i32_e32 v7, 8, v7
	v_min_i32_e32 v6, 0x7f, v6
	v_min_i32_sdwa v3, v3, s79 dst_sel:WORD_1 dst_unused:UNUSED_PAD src0_sel:DWORD src1_sel:DWORD
	v_min_i32_e32 v7, 0x7f, v7
	v_lshlrev_b32_e32 v124, 8, v124
	v_and_b32_e32 v124, 0xff00, v124
	v_and_b32_e32 v3, 0xff0000, v3
	v_perm_b32 v6, v7, v6, s80
	v_or3_b32 v3, v6, v124, v3
	ds_write_b32 v12, v3 offset:16
	ds_read_b64 v[6:7], v13
	s_waitcnt lgkmcnt(0)
;     ...
;             const int cc = bj * HALF + wc3 * 32 + n * 16 + fq3 * 4;
;             const float4 gm = *reinterpret_cast<const float4*>(g.gam + pn * BM + cc), bt = *reinterpret_cast<const float4*>(g.bet + pn * BM + cc);
;             _Pragma("unroll") for (int m = 0; m < 4; ++m) {
;               const int rr = wr3 * 64 + m * 16 + fr3;
;               const float2 ms = *reinterpret_cast<const float2*>(mr + (ai * HALF + rr) * 2);
;               f32x4 y = acc[ai][bj][m][n];
;               const float o0 = (y[0] - ms.x) * ms.y * gm.x + bt.x, o1 = (y[1] - ms.x) * ms.y * gm.y + bt.y;
;               const float o2 = (y[2] - ms.x) * ms.y * gm.z + bt.z, o3 = (y[3] - ms.x) * ms.y * gm.w + bt.w;
;               const unsigned h0 = f2bf(o0), h1 = f2bf(o1), h2 = f2bf(o2), h3 = f2bf(o3);
;               u32x2 ob; ob[0] = h0 | (h1 << 16); ob[1] = h2 | (h3 << 16);
;               *reinterpret_cast<u32x2*>(smem + (rr >> 1) * PIECE + (rr & 1) * 512 + cc * 2) = ob;
;               const int l0 = min(((int)__float_as_uint(o0) - (int)(h0 << 16) + 128) >> 8, 127);
;               const int l1 = min(((int)__float_as_uint(o1) - (int)(h1 << 16) + 128) >> 8, 127);
;               const int l2 = min(((int)__float_as_uint(o2) - (int)(h2 << 16) + 128) >> 8, 127);
;               const int l3 = min(((int)__float_as_uint(o3) - (int)(h3 << 16) + 128) >> 8, 127);
;               *reinterpret_cast<unsigned*>(smem + LOBASE + (rr >> 2) * PIECE + (rr & 3) * 256 + cc) =
;                   (unsigned)(l0 & 255) | ((unsigned)(l1 & 255) << 8) | ((unsigned)(l2 & 255) << 16) | ((unsigned)l3 << 24);
	v_pk_add_f32 v[106:107], v[106:107], v[6:7] op_sel_hi:[1,0] neg_lo:[0,1] neg_hi:[0,1]
	s_nop 0
	v_pk_mul_f32 v[106:107], v[6:7], v[106:107] op_sel:[1,0]
	v_pk_add_f32 v[104:105], v[104:105], v[6:7] op_sel_hi:[1,0] neg_lo:[0,1] neg_hi:[0,1]
	v_pk_fma_f32 v[106:107], v[128:129], v[106:107], v[130:131]
	v_pk_mul_f32 v[6:7], v[6:7], v[104:105] op_sel:[1,0]
	v_and_b32_sdwa v104, v106, v216 dst_sel:DWORD dst_unused:UNUSED_PAD src0_sel:WORD_1 src1_sel:DWORD
	v_pk_fma_f32 v[6:7], v[0:1], v[6:7], v[4:5]
	v_add3_u32 v104, v106, v104, s78
	v_and_b32_e32 v105, 0xffff0000, v104
	v_and_b32_sdwa v104, v7, v216 dst_sel:DWORD dst_unused:UNUSED_PAD src0_sel:WORD_1 src1_sel:DWORD
	v_and_b32_sdwa v3, v107, v216 dst_sel:DWORD dst_unused:UNUSED_PAD src0_sel:WORD_1 src1_sel:DWORD
	v_and_b32_sdwa v124, v6, v216 dst_sel:DWORD dst_unused:UNUSED_PAD src0_sel:WORD_1 src1_sel:DWORD
	v_add3_u32 v104, v7, v104, s78
	v_add3_u32 v3, v107, v3, s78
	v_add3_u32 v126, v6, v124, s78
	v_and_b32_e32 v127, 0xffff0000, v104
	v_or_b32_sdwa v125, v127, v3 dst_sel:DWORD dst_unused:UNUSED_PAD src0_sel:DWORD src1_sel:WORD_1
	v_or_b32_sdwa v124, v126, v105 dst_sel:DWORD dst_unused:UNUSED_PAD src0_sel:WORD_1 src1_sel:DWORD
	v_add_u32_e32 v104, v2, v154
	ds_write_b64 v104, v[124:125]
	v_and_b32_e32 v124, 0xffff0000, v126
	v_sub_u32_e32 v105, v106, v105
	v_and_b32_e32 v3, 0xffff0000, v3
	v_sub_u32_e32 v6, v6, v124
	v_add_u32_e32 v105, 0x80, v105
	v_sub_u32_e32 v3, v107, v3
	v_sub_u32_e32 v7, v7, v127
	v_add_u32_e32 v6, 0x80, v6
	v_ashrrev_i32_e32 v105, 8, v105
	v_add_u32_e32 v3, 0x80, v3
	v_add_u32_e32 v7, 0x80, v7
	v_ashrrev_i32_e32 v6, 8, v6
	v_min_i32_e32 v105, 0x7f, v105
	v_ashrrev_i32_e32 v3, 8, v3
	v_ashrrev_i32_e32 v7, 8, v7
	v_min_i32_e32 v6, 0x7f, v6
	v_min_i32_sdwa v3, v3, s79 dst_sel:WORD_1 dst_unused:UNUSED_PAD src0_sel:DWORD src1_sel:DWORD
	v_min_i32_e32 v7, 0x7f, v7
	v_lshlrev_b32_e32 v105, 8, v105
	v_and_b32_e32 v105, 0xff00, v105
	v_and_b32_e32 v3, 0xff0000, v3
	v_perm_b32 v6, v7, v6, s80
	v_or3_b32 v3, v6, v105, v3
	ds_write_b32 v14, v3 offset:16
	ds_read_b64 v[6:7], v15
	s_waitcnt lgkmcnt(0)
	v_pk_add_f32 v[106:107], v[110:111], v[6:7] op_sel_hi:[1,0] neg_lo:[0,1] neg_hi:[0,1]
	s_nop 0
	v_pk_mul_f32 v[106:107], v[6:7], v[106:107] op_sel:[1,0]
	v_pk_add_f32 v[108:109], v[108:109], v[6:7] op_sel_hi:[1,0] neg_lo:[0,1] neg_hi:[0,1]
	v_pk_fma_f32 v[106:107], v[128:129], v[106:107], v[130:131]
	v_pk_mul_f32 v[6:7], v[6:7], v[108:109] op_sel:[1,0]
	v_and_b32_sdwa v105, v106, v216 dst_sel:DWORD dst_unused:UNUSED_PAD src0_sel:WORD_1 src1_sel:DWORD
	v_pk_fma_f32 v[6:7], v[0:1], v[6:7], v[4:5]
	v_add3_u32 v105, v106, v105, s78
	v_and_b32_e32 v110, 0xffff0000, v105
	v_and_b32_sdwa v105, v7, v216 dst_sel:DWORD dst_unused:UNUSED_PAD src0_sel:WORD_1 src1_sel:DWORD
	v_and_b32_sdwa v3, v107, v216 dst_sel:DWORD dst_unused:UNUSED_PAD src0_sel:WORD_1 src1_sel:DWORD
	v_and_b32_sdwa v108, v6, v216 dst_sel:DWORD dst_unused:UNUSED_PAD src0_sel:WORD_1 src1_sel:DWORD
	v_add3_u32 v105, v7, v105, s78
	v_add3_u32 v3, v107, v3, s78
	v_add3_u32 v111, v6, v108, s78
	v_and_b32_e32 v124, 0xffff0000, v105
	v_or_b32_sdwa v109, v124, v3 dst_sel:DWORD dst_unused:UNUSED_PAD src0_sel:DWORD src1_sel:WORD_1
	v_or_b32_sdwa v108, v111, v110 dst_sel:DWORD dst_unused:UNUSED_PAD src0_sel:WORD_1 src1_sel:DWORD
	v_add_u32_e32 v105, v2, v136
	ds_write_b64 v105, v[108:109]
	v_and_b32_e32 v108, 0xffff0000, v111
	v_sub_u32_e32 v106, v106, v110
	v_and_b32_e32 v3, 0xffff0000, v3
	v_sub_u32_e32 v6, v6, v108
	v_add_u32_e32 v106, 0x80, v106
	v_sub_u32_e32 v3, v107, v3
	v_sub_u32_e32 v7, v7, v124
	v_add_u32_e32 v6, 0x80, v6
	v_ashrrev_i32_e32 v106, 8, v106
	v_add_u32_e32 v3, 0x80, v3
	v_add_u32_e32 v7, 0x80, v7
	v_ashrrev_i32_e32 v6, 8, v6
	v_min_i32_e32 v106, 0x7f, v106
	v_ashrrev_i32_e32 v3, 8, v3
	v_ashrrev_i32_e32 v7, 8, v7
	v_min_i32_e32 v6, 0x7f, v6
	v_min_i32_sdwa v3, v3, s79 dst_sel:WORD_1 dst_unused:UNUSED_PAD src0_sel:DWORD src1_sel:DWORD
	v_min_i32_e32 v7, 0x7f, v7
	v_lshlrev_b32_e32 v106, 8, v106
	v_and_b32_e32 v106, 0xff00, v106
	v_and_b32_e32 v3, 0xff0000, v3
	v_perm_b32 v6, v7, v6, s80
	v_or3_b32 v3, v6, v106, v3
	ds_write_b32 v20, v3 offset:16
	ds_read_b64 v[6:7], v21
	s_waitcnt lgkmcnt(0)
	v_pk_add_f32 v[106:107], v[122:123], v[6:7] op_sel_hi:[1,0] neg_lo:[0,1] neg_hi:[0,1]
	s_nop 0
	v_pk_mul_f32 v[106:107], v[6:7], v[106:107] op_sel:[1,0]
	v_or_b32_e32 v122, 0x100, v155
	v_pk_fma_f32 v[108:109], v[128:129], v[106:107], v[130:131]
	v_pk_add_f32 v[106:107], v[114:115], v[6:7] op_sel_hi:[1,0] neg_lo:[0,1] neg_hi:[0,1]
	v_and_b32_sdwa v3, v109, v216 dst_sel:DWORD dst_unused:UNUSED_PAD src0_sel:WORD_1 src1_sel:DWORD
	v_pk_mul_f32 v[6:7], v[6:7], v[106:107] op_sel:[1,0]
	v_add3_u32 v3, v109, v3, s78
	v_pk_fma_f32 v[0:1], v[0:1], v[6:7], v[4:5]
	v_and_b32_sdwa v4, v108, v216 dst_sel:DWORD dst_unused:UNUSED_PAD src0_sel:WORD_1 src1_sel:DWORD
	v_add3_u32 v4, v108, v4, s78
	v_and_b32_e32 v6, 0xffff0000, v4
	v_and_b32_sdwa v4, v1, v216 dst_sel:DWORD dst_unused:UNUSED_PAD src0_sel:WORD_1 src1_sel:DWORD
	v_and_b32_sdwa v5, v0, v216 dst_sel:DWORD dst_unused:UNUSED_PAD src0_sel:WORD_1 src1_sel:DWORD
	v_add3_u32 v4, v1, v4, s78
	v_add3_u32 v7, v0, v5, s78
	v_and_b32_e32 v107, 0xffff0000, v4
	v_add_u32_e32 v106, v2, v135
	v_and_b32_e32 v2, 0xffff0000, v7
	v_or_b32_sdwa v5, v107, v3 dst_sel:DWORD dst_unused:UNUSED_PAD src0_sel:DWORD src1_sel:WORD_1
	v_sub_u32_e32 v0, v0, v2
	v_sub_u32_e32 v2, v108, v6
	v_and_b32_e32 v3, 0xffff0000, v3
	v_add_u32_e32 v2, 0x80, v2
	v_sub_u32_e32 v3, v109, v3
	v_sub_u32_e32 v1, v1, v107
	v_add_u32_e32 v0, 0x80, v0
	v_ashrrev_i32_e32 v2, 8, v2
	v_add_u32_e32 v3, 0x80, v3
	v_add_u32_e32 v1, 0x80, v1
	v_ashrrev_i32_e32 v0, 8, v0
	v_min_i32_e32 v2, 0x7f, v2
	v_ashrrev_i32_e32 v3, 8, v3
	v_ashrrev_i32_e32 v1, 8, v1
	v_min_i32_e32 v0, 0x7f, v0
	v_min_i32_sdwa v3, v3, s79 dst_sel:WORD_1 dst_unused:UNUSED_PAD src0_sel:DWORD src1_sel:DWORD
	v_min_i32_e32 v1, 0x7f, v1
	v_lshlrev_b32_e32 v2, 8, v2
	v_and_b32_e32 v2, 0xff00, v2
	v_and_b32_e32 v3, 0xff0000, v3
	v_perm_b32 v0, v1, v0, s80
	v_or_b32_sdwa v4, v7, v6 dst_sel:DWORD dst_unused:UNUSED_PAD src0_sel:WORD_1 src1_sel:DWORD
	v_or3_b32 v0, v0, v2, v3
	ds_write_b64 v106, v[4:5]
	ds_write_b32 v22, v0 offset:16
	v_mov_b32_e32 v0, v228
	v_mov_b32_e32 v1, v229
	v_mov_b32_e32 v2, v230
	v_mov_b32_e32 v3, v231
	v_mov_b32_e32 v4, v244
	v_mov_b32_e32 v5, v245
	v_mov_b32_e32 v6, v246
	v_mov_b32_e32 v7, v247
	ds_read_b64 v[114:115], v149
	v_add_u32_e32 v107, v122, v153
	s_waitcnt lgkmcnt(0)
;     ...
;             const int cc = bj * HALF + wc3 * 32 + n * 16 + fq3 * 4;
;             const float4 gm = *reinterpret_cast<const float4*>(g.gam + pn * BM + cc), bt = *reinterpret_cast<const float4*>(g.bet + pn * BM + cc);
;             _Pragma("unroll") for (int m = 0; m < 4; ++m) {
;               const int rr = wr3 * 64 + m * 16 + fr3;
;               const float2 ms = *reinterpret_cast<const float2*>(mr + (ai * HALF + rr) * 2);
;               f32x4 y = acc[ai][bj][m][n];
;               const float o0 = (y[0] - ms.x) * ms.y * gm.x + bt.x, o1 = (y[1] - ms.x) * ms.y * gm.y + bt.y;
;               const float o2 = (y[2] - ms.x) * ms.y * gm.z + bt.z, o3 = (y[3] - ms.x) * ms.y * gm.w + bt.w;
;               const unsigned h0 = f2bf(o0), h1 = f2bf(o1), h2 = f2bf(o2), h3 = f2bf(o3);
;               u32x2 ob; ob[0] = h0 | (h1 << 16); ob[1] = h2 | (h3 << 16);
;               *reinterpret_cast<u32x2*>(smem + (rr >> 1) * PIECE + (rr & 1) * 512 + cc * 2) = ob;
;               const int l0 = min(((int)__float_as_uint(o0) - (int)(h0 << 16) + 128) >> 8, 127);
;               const int l1 = min(((int)__float_as_uint(o1) - (int)(h1 << 16) + 128) >> 8, 127);
;               const int l2 = min(((int)__float_as_uint(o2) - (int)(h2 << 16) + 128) >> 8, 127);
;               const int l3 = min(((int)__float_as_uint(o3) - (int)(h3 << 16) + 128) >> 8, 127);
;               *reinterpret_cast<unsigned*>(smem + LOBASE + (rr >> 2) * PIECE + (rr & 3) * 256 + cc) =
;                   (unsigned)(l0 & 255) | ((unsigned)(l1 & 255) << 8) | ((unsigned)(l2 & 255) << 16) | ((unsigned)l3 << 24);
	v_pk_add_f32 v[118:119], v[118:119], v[114:115] op_sel_hi:[1,0] neg_lo:[0,1] neg_hi:[0,1]
	s_nop 0
	v_pk_mul_f32 v[118:119], v[114:115], v[118:119] op_sel:[1,0]
	v_pk_add_f32 v[120:121], v[120:121], v[114:115] op_sel_hi:[1,0] neg_lo:[0,1] neg_hi:[0,1]
	v_mov_b32_e32 v108, v1
	v_mov_b32_e32 v109, v2
	v_mov_b32_e32 v110, v5
	v_mov_b32_e32 v111, v6
	v_pk_fma_f32 v[118:119], v[108:109], v[118:119], v[110:111]
	v_pk_mul_f32 v[114:115], v[114:115], v[120:121] op_sel:[1,0]
	v_mov_b32_e32 v1, v3
	v_mov_b32_e32 v5, v7
	v_and_b32_sdwa v6, v119, v216 dst_sel:DWORD dst_unused:UNUSED_PAD src0_sel:WORD_1 src1_sel:DWORD
	v_and_b32_sdwa v7, v118, v216 dst_sel:DWORD dst_unused:UNUSED_PAD src0_sel:WORD_1 src1_sel:DWORD
	v_pk_fma_f32 v[2:3], v[0:1], v[114:115], v[4:5]
	v_add3_u32 v114, v119, v6, s78
	v_add3_u32 v6, v118, v7, s78
	v_and_b32_e32 v115, 0xffff0000, v6
	v_and_b32_sdwa v6, v3, v216 dst_sel:DWORD dst_unused:UNUSED_PAD src0_sel:WORD_1 src1_sel:DWORD
	v_and_b32_sdwa v7, v2, v216 dst_sel:DWORD dst_unused:UNUSED_PAD src0_sel:WORD_1 src1_sel:DWORD
	v_add3_u32 v6, v3, v6, s78
	v_add3_u32 v120, v2, v7, s78
	v_and_b32_e32 v121, 0xffff0000, v6
	v_or_b32_sdwa v7, v121, v114 dst_sel:DWORD dst_unused:UNUSED_PAD src0_sel:DWORD src1_sel:WORD_1
	v_or_b32_sdwa v6, v120, v115 dst_sel:DWORD dst_unused:UNUSED_PAD src0_sel:WORD_1 src1_sel:DWORD
	ds_write_b64 v107, v[6:7]
	v_and_b32_e32 v6, 0xffff0000, v120
	v_sub_u32_e32 v2, v2, v6
	v_sub_u32_e32 v6, v118, v115
	v_and_b32_e32 v7, 0xffff0000, v114
	v_add_u32_e32 v6, 0x80, v6
	v_sub_u32_e32 v7, v119, v7
	v_sub_u32_e32 v3, v3, v121
	v_add_u32_e32 v2, 0x80, v2
	v_ashrrev_i32_e32 v6, 8, v6
	v_add_u32_e32 v7, 0x80, v7
	v_add_u32_e32 v3, 0x80, v3
	v_ashrrev_i32_e32 v2, 8, v2
	v_min_i32_e32 v6, 0x7f, v6
	v_ashrrev_i32_e32 v7, 8, v7
	v_ashrrev_i32_e32 v3, 8, v3
	v_min_i32_e32 v2, 0x7f, v2
	v_min_i32_sdwa v7, v7, s79 dst_sel:WORD_1 dst_unused:UNUSED_PAD src0_sel:DWORD src1_sel:DWORD
	v_min_i32_e32 v3, 0x7f, v3
	v_lshlrev_b32_e32 v6, 8, v6
	v_and_b32_e32 v6, 0xff00, v6
	v_and_b32_e32 v7, 0xff0000, v7
	v_perm_b32 v2, v3, v2, s80
	v_or3_b32 v2, v2, v6, v7
	ds_write_b32 v12, v2 offset:128
	ds_read_b64 v[2:3], v13
	s_waitcnt lgkmcnt(0)
	v_pk_add_f32 v[6:7], v[102:103], v[2:3] op_sel_hi:[1,0] neg_lo:[0,1] neg_hi:[0,1]
	s_nop 0
	v_pk_mul_f32 v[6:7], v[2:3], v[6:7] op_sel:[1,0]
	v_pk_add_f32 v[100:101], v[100:101], v[2:3] op_sel_hi:[1,0] neg_lo:[0,1] neg_hi:[0,1]
	v_pk_fma_f32 v[6:7], v[108:109], v[6:7], v[110:111]
	v_pk_mul_f32 v[2:3], v[2:3], v[100:101] op_sel:[1,0]
	v_and_b32_sdwa v100, v7, v216 dst_sel:DWORD dst_unused:UNUSED_PAD src0_sel:WORD_1 src1_sel:DWORD
	v_and_b32_sdwa v101, v6, v216 dst_sel:DWORD dst_unused:UNUSED_PAD src0_sel:WORD_1 src1_sel:DWORD
	v_pk_fma_f32 v[2:3], v[0:1], v[2:3], v[4:5]
	v_add3_u32 v114, v7, v100, s78
	v_add3_u32 v100, v6, v101, s78
	v_and_b32_e32 v101, 0xffff0000, v100
	v_and_b32_sdwa v100, v3, v216 dst_sel:DWORD dst_unused:UNUSED_PAD src0_sel:WORD_1 src1_sel:DWORD
	v_and_b32_sdwa v102, v2, v216 dst_sel:DWORD dst_unused:UNUSED_PAD src0_sel:WORD_1 src1_sel:DWORD
	v_add3_u32 v100, v3, v100, s78
	v_add3_u32 v115, v2, v102, s78
	v_and_b32_e32 v118, 0xffff0000, v100
	v_or_b32_sdwa v103, v118, v114 dst_sel:DWORD dst_unused:UNUSED_PAD src0_sel:DWORD src1_sel:WORD_1
	v_or_b32_sdwa v102, v115, v101 dst_sel:DWORD dst_unused:UNUSED_PAD src0_sel:WORD_1 src1_sel:DWORD
	v_add_u32_e32 v100, v122, v154
	ds_write_b64 v100, v[102:103]
	v_and_b32_e32 v102, 0xffff0000, v115
	v_sub_u32_e32 v6, v6, v101
	v_and_b32_e32 v101, 0xffff0000, v114
	v_sub_u32_e32 v2, v2, v102
	v_add_u32_e32 v6, 0x80, v6
	v_sub_u32_e32 v7, v7, v101
	v_sub_u32_e32 v3, v3, v118
	v_add_u32_e32 v2, 0x80, v2
	v_ashrrev_i32_e32 v6, 8, v6
	v_add_u32_e32 v7, 0x80, v7
	v_add_u32_e32 v3, 0x80, v3
	v_ashrrev_i32_e32 v2, 8, v2
	v_min_i32_e32 v6, 0x7f, v6
	v_ashrrev_i32_e32 v7, 8, v7
	v_ashrrev_i32_e32 v3, 8, v3
	v_min_i32_e32 v2, 0x7f, v2
	v_min_i32_sdwa v7, v7, s79 dst_sel:WORD_1 dst_unused:UNUSED_PAD src0_sel:DWORD src1_sel:DWORD
	v_min_i32_e32 v3, 0x7f, v3
	v_lshlrev_b32_e32 v6, 8, v6
	v_and_b32_e32 v6, 0xff00, v6
	v_and_b32_e32 v7, 0xff0000, v7
	v_perm_b32 v2, v3, v2, s80
	v_or3_b32 v2, v2, v6, v7
	ds_write_b32 v14, v2 offset:128
	ds_read_b64 v[2:3], v15
	v_add_u32_e32 v101, v122, v136
	s_waitcnt lgkmcnt(0)
	v_pk_add_f32 v[6:7], v[90:91], v[2:3] op_sel_hi:[1,0] neg_lo:[0,1] neg_hi:[0,1]
	s_nop 0
	v_pk_mul_f32 v[6:7], v[2:3], v[6:7] op_sel:[1,0]
	v_pk_add_f32 v[88:89], v[88:89], v[2:3] op_sel_hi:[1,0] neg_lo:[0,1] neg_hi:[0,1]
	v_pk_fma_f32 v[6:7], v[108:109], v[6:7], v[110:111]
	v_pk_mul_f32 v[2:3], v[2:3], v[88:89] op_sel:[1,0]
	v_and_b32_sdwa v88, v7, v216 dst_sel:DWORD dst_unused:UNUSED_PAD src0_sel:WORD_1 src1_sel:DWORD
	v_and_b32_sdwa v89, v6, v216 dst_sel:DWORD dst_unused:UNUSED_PAD src0_sel:WORD_1 src1_sel:DWORD
	v_pk_fma_f32 v[2:3], v[0:1], v[2:3], v[4:5]
	v_add3_u32 v90, v7, v88, s78
	v_add3_u32 v88, v6, v89, s78
	v_and_b32_e32 v91, 0xffff0000, v88
	v_and_b32_sdwa v88, v3, v216 dst_sel:DWORD dst_unused:UNUSED_PAD src0_sel:WORD_1 src1_sel:DWORD
	v_and_b32_sdwa v89, v2, v216 dst_sel:DWORD dst_unused:UNUSED_PAD src0_sel:WORD_1 src1_sel:DWORD
	v_add3_u32 v88, v3, v88, s78
	v_add3_u32 v102, v2, v89, s78
	v_and_b32_e32 v103, 0xffff0000, v88
	v_or_b32_sdwa v89, v103, v90 dst_sel:DWORD dst_unused:UNUSED_PAD src0_sel:DWORD src1_sel:WORD_1
	v_or_b32_sdwa v88, v102, v91 dst_sel:DWORD dst_unused:UNUSED_PAD src0_sel:WORD_1 src1_sel:DWORD
	ds_write_b64 v101, v[88:89]
	v_and_b32_e32 v88, 0xffff0000, v102
	v_sub_u32_e32 v2, v2, v88
	v_sub_u32_e32 v6, v6, v91
	v_and_b32_e32 v88, 0xffff0000, v90
	v_add_u32_e32 v6, 0x80, v6
	v_sub_u32_e32 v7, v7, v88
	v_sub_u32_e32 v3, v3, v103
	v_add_u32_e32 v2, 0x80, v2
	v_ashrrev_i32_e32 v6, 8, v6
	v_add_u32_e32 v7, 0x80, v7
	v_add_u32_e32 v3, 0x80, v3
	v_ashrrev_i32_e32 v2, 8, v2
	v_min_i32_e32 v6, 0x7f, v6
	v_ashrrev_i32_e32 v7, 8, v7
	v_ashrrev_i32_e32 v3, 8, v3
	v_min_i32_e32 v2, 0x7f, v2
	v_min_i32_sdwa v7, v7, s79 dst_sel:WORD_1 dst_unused:UNUSED_PAD src0_sel:DWORD src1_sel:DWORD
	v_min_i32_e32 v3, 0x7f, v3
	v_lshlrev_b32_e32 v6, 8, v6
	v_and_b32_e32 v6, 0xff00, v6
	v_and_b32_e32 v7, 0xff0000, v7
	v_perm_b32 v2, v3, v2, s80
	v_or3_b32 v2, v2, v6, v7
	ds_write_b32 v20, v2 offset:128
	ds_read_b64 v[2:3], v21
	s_waitcnt lgkmcnt(0)
;     ...
;             const int cc = bj * HALF + wc3 * 32 + n * 16 + fq3 * 4;
;             const float4 gm = *reinterpret_cast<const float4*>(g.gam + pn * BM + cc), bt = *reinterpret_cast<const float4*>(g.bet + pn * BM + cc);
;             _Pragma("unroll") for (int m = 0; m < 4; ++m) {
;               const int rr = wr3 * 64 + m * 16 + fr3;
;               const float2 ms = *reinterpret_cast<const float2*>(mr + (ai * HALF + rr) * 2);
;               f32x4 y = acc[ai][bj][m][n];
;               const float o0 = (y[0] - ms.x) * ms.y * gm.x + bt.x, o1 = (y[1] - ms.x) * ms.y * gm.y + bt.y;
;               const float o2 = (y[2] - ms.x) * ms.y * gm.z + bt.z, o3 = (y[3] - ms.x) * ms.y * gm.w + bt.w;
;               const unsigned h0 = f2bf(o0), h1 = f2bf(o1), h2 = f2bf(o2), h3 = f2bf(o3);
;               u32x2 ob; ob[0] = h0 | (h1 << 16); ob[1] = h2 | (h3 << 16);
;               *reinterpret_cast<u32x2*>(smem + (rr >> 1) * PIECE + (rr & 1) * 512 + cc * 2) = ob;
;               const int l0 = min(((int)__float_as_uint(o0) - (int)(h0 << 16) + 128) >> 8, 127);
;               const int l1 = min(((int)__float_as_uint(o1) - (int)(h1 << 16) + 128) >> 8, 127);
;               const int l2 = min(((int)__float_as_uint(o2) - (int)(h2 << 16) + 128) >> 8, 127);
;               const int l3 = min(((int)__float_as_uint(o3) - (int)(h3 << 16) + 128) >> 8, 127);
;               *reinterpret_cast<unsigned*>(smem + LOBASE + (rr >> 2) * PIECE + (rr & 3) * 256 + cc) =
;                   (unsigned)(l0 & 255) | ((unsigned)(l1 & 255) << 8) | ((unsigned)(l2 & 255) << 16) | ((unsigned)l3 << 24);
	v_pk_add_f32 v[6:7], v[94:95], v[2:3] op_sel_hi:[1,0] neg_lo:[0,1] neg_hi:[0,1]
	s_nop 0
	v_pk_mul_f32 v[6:7], v[2:3], v[6:7] op_sel:[1,0]
	v_pk_add_f32 v[88:89], v[92:93], v[2:3] op_sel_hi:[1,0] neg_lo:[0,1] neg_hi:[0,1]
	v_pk_fma_f32 v[6:7], v[108:109], v[6:7], v[110:111]
	v_pk_mul_f32 v[2:3], v[2:3], v[88:89] op_sel:[1,0]
	v_add_u32_e32 v92, v122, v135
	v_pk_fma_f32 v[0:1], v[0:1], v[2:3], v[4:5]
	v_and_b32_sdwa v2, v7, v216 dst_sel:DWORD dst_unused:UNUSED_PAD src0_sel:WORD_1 src1_sel:DWORD
	v_and_b32_sdwa v3, v6, v216 dst_sel:DWORD dst_unused:UNUSED_PAD src0_sel:WORD_1 src1_sel:DWORD
	v_add3_u32 v4, v7, v2, s78
	v_add3_u32 v2, v6, v3, s78
	v_and_b32_e32 v5, 0xffff0000, v2
	v_and_b32_sdwa v2, v1, v216 dst_sel:DWORD dst_unused:UNUSED_PAD src0_sel:WORD_1 src1_sel:DWORD
	v_and_b32_sdwa v3, v0, v216 dst_sel:DWORD dst_unused:UNUSED_PAD src0_sel:WORD_1 src1_sel:DWORD
	v_add3_u32 v2, v1, v2, s78
	v_add3_u32 v88, v0, v3, s78
	v_and_b32_e32 v89, 0xffff0000, v2
	v_or_b32_sdwa v3, v89, v4 dst_sel:DWORD dst_unused:UNUSED_PAD src0_sel:DWORD src1_sel:WORD_1
	v_or_b32_sdwa v2, v88, v5 dst_sel:DWORD dst_unused:UNUSED_PAD src0_sel:WORD_1 src1_sel:DWORD
	ds_write_b64 v92, v[2:3]
	v_and_b32_e32 v2, 0xffff0000, v88
	v_sub_u32_e32 v0, v0, v2
	v_sub_u32_e32 v2, v6, v5
	v_and_b32_e32 v3, 0xffff0000, v4
	v_add_u32_e32 v2, 0x80, v2
	v_sub_u32_e32 v3, v7, v3
	v_sub_u32_e32 v1, v1, v89
	v_add_u32_e32 v0, 0x80, v0
	v_ashrrev_i32_e32 v2, 8, v2
	v_add_u32_e32 v3, 0x80, v3
	v_add_u32_e32 v1, 0x80, v1
	v_ashrrev_i32_e32 v0, 8, v0
	v_min_i32_e32 v2, 0x7f, v2
	v_ashrrev_i32_e32 v3, 8, v3
	v_ashrrev_i32_e32 v1, 8, v1
	v_min_i32_e32 v0, 0x7f, v0
	v_min_i32_sdwa v3, v3, s79 dst_sel:WORD_1 dst_unused:UNUSED_PAD src0_sel:DWORD src1_sel:DWORD
	v_min_i32_e32 v1, 0x7f, v1
	v_lshlrev_b32_e32 v2, 8, v2
	v_and_b32_e32 v2, 0xff00, v2
	v_and_b32_e32 v3, 0xff0000, v3
	v_perm_b32 v0, v1, v0, s80
	v_or3_b32 v0, v0, v2, v3
	ds_write_b32 v22, v0 offset:128
	v_mov_b32_e32 v0, v232
	v_mov_b32_e32 v1, v233
	v_mov_b32_e32 v2, v234
	v_mov_b32_e32 v3, v235
	v_mov_b32_e32 v4, v248
	v_mov_b32_e32 v5, v249
	v_mov_b32_e32 v6, v250
	v_mov_b32_e32 v7, v251
	ds_read_b64 v[94:95], v149
	s_waitcnt lgkmcnt(0)
	v_pk_add_f32 v[102:103], v[116:117], v[94:95] op_sel_hi:[1,0] neg_lo:[0,1] neg_hi:[0,1]
	s_nop 0
	v_pk_mul_f32 v[102:103], v[94:95], v[102:103] op_sel:[1,0]
	v_pk_add_f32 v[108:109], v[112:113], v[94:95] op_sel_hi:[1,0] neg_lo:[0,1] neg_hi:[0,1]
	v_mov_b32_e32 v88, v1
	v_mov_b32_e32 v89, v2
	v_mov_b32_e32 v90, v5
	v_mov_b32_e32 v91, v6
	v_pk_fma_f32 v[102:103], v[88:89], v[102:103], v[90:91]
	v_pk_mul_f32 v[94:95], v[94:95], v[108:109] op_sel:[1,0]
	v_mov_b32_e32 v1, v3
	v_mov_b32_e32 v5, v7
	v_and_b32_sdwa v93, v102, v216 dst_sel:DWORD dst_unused:UNUSED_PAD src0_sel:WORD_1 src1_sel:DWORD
	v_pk_fma_f32 v[6:7], v[0:1], v[94:95], v[4:5]
	v_add3_u32 v93, v102, v93, s78
	v_and_b32_e32 v108, 0xffff0000, v93
	v_and_b32_sdwa v93, v7, v216 dst_sel:DWORD dst_unused:UNUSED_PAD src0_sel:WORD_1 src1_sel:DWORD
	v_and_b32_sdwa v3, v103, v216 dst_sel:DWORD dst_unused:UNUSED_PAD src0_sel:WORD_1 src1_sel:DWORD
	v_and_b32_sdwa v94, v6, v216 dst_sel:DWORD dst_unused:UNUSED_PAD src0_sel:WORD_1 src1_sel:DWORD
	v_add3_u32 v93, v7, v93, s78
	v_or_b32_e32 v2, 0x120, v155
	v_add3_u32 v3, v103, v3, s78
	v_add3_u32 v109, v6, v94, s78
	v_and_b32_e32 v110, 0xffff0000, v93
	v_or_b32_sdwa v95, v110, v3 dst_sel:DWORD dst_unused:UNUSED_PAD src0_sel:DWORD src1_sel:WORD_1
	v_or_b32_sdwa v94, v109, v108 dst_sel:DWORD dst_unused:UNUSED_PAD src0_sel:WORD_1 src1_sel:DWORD
	v_add_u32_e32 v93, v2, v153
	ds_write_b64 v93, v[94:95]
	v_and_b32_e32 v94, 0xffff0000, v109
	v_sub_u32_e32 v6, v6, v94
	v_sub_u32_e32 v94, v102, v108
	v_and_b32_e32 v3, 0xffff0000, v3
	v_add_u32_e32 v94, 0x80, v94
	v_sub_u32_e32 v3, v103, v3
	v_sub_u32_e32 v7, v7, v110
	v_add_u32_e32 v6, 0x80, v6
	v_ashrrev_i32_e32 v94, 8, v94
	v_add_u32_e32 v3, 0x80, v3
	v_add_u32_e32 v7, 0x80, v7
	v_ashrrev_i32_e32 v6, 8, v6
	v_min_i32_e32 v94, 0x7f, v94
	v_ashrrev_i32_e32 v3, 8, v3
	v_ashrrev_i32_e32 v7, 8, v7
	v_min_i32_e32 v6, 0x7f, v6
	v_min_i32_sdwa v3, v3, s79 dst_sel:WORD_1 dst_unused:UNUSED_PAD src0_sel:DWORD src1_sel:DWORD
	v_min_i32_e32 v7, 0x7f, v7
	v_lshlrev_b32_e32 v94, 8, v94
	v_and_b32_e32 v94, 0xff00, v94
	v_and_b32_e32 v3, 0xff0000, v3
	v_perm_b32 v6, v7, v6, s80
	v_or3_b32 v3, v6, v94, v3
	ds_write_b32 v12, v3 offset:144
	ds_read_b64 v[6:7], v13
	s_waitcnt lgkmcnt(0)
	v_pk_add_f32 v[94:95], v[98:99], v[6:7] op_sel_hi:[1,0] neg_lo:[0,1] neg_hi:[0,1]
	s_nop 0
	v_pk_mul_f32 v[94:95], v[6:7], v[94:95] op_sel:[1,0]
	s_nop 0
	v_pk_fma_f32 v[98:99], v[88:89], v[94:95], v[90:91]
	v_pk_add_f32 v[94:95], v[96:97], v[6:7] op_sel_hi:[1,0] neg_lo:[0,1] neg_hi:[0,1]
	v_and_b32_sdwa v3, v99, v216 dst_sel:DWORD dst_unused:UNUSED_PAD src0_sel:WORD_1 src1_sel:DWORD
	v_pk_mul_f32 v[6:7], v[6:7], v[94:95] op_sel:[1,0]
	v_and_b32_sdwa v94, v98, v216 dst_sel:DWORD dst_unused:UNUSED_PAD src0_sel:WORD_1 src1_sel:DWORD
	v_pk_fma_f32 v[6:7], v[0:1], v[6:7], v[4:5]
	v_add3_u32 v94, v98, v94, s78
	v_and_b32_e32 v95, 0xffff0000, v94
	v_and_b32_sdwa v94, v7, v216 dst_sel:DWORD dst_unused:UNUSED_PAD src0_sel:WORD_1 src1_sel:DWORD
	v_and_b32_sdwa v96, v6, v216 dst_sel:DWORD dst_unused:UNUSED_PAD src0_sel:WORD_1 src1_sel:DWORD
	v_add3_u32 v94, v7, v94, s78
	v_add3_u32 v3, v99, v3, s78
	v_add3_u32 v102, v6, v96, s78
	v_and_b32_e32 v103, 0xffff0000, v94
	v_or_b32_sdwa v97, v103, v3 dst_sel:DWORD dst_unused:UNUSED_PAD src0_sel:DWORD src1_sel:WORD_1
	v_or_b32_sdwa v96, v102, v95 dst_sel:DWORD dst_unused:UNUSED_PAD src0_sel:WORD_1 src1_sel:DWORD
	v_add_u32_e32 v94, v2, v154
	ds_write_b64 v94, v[96:97]
	v_and_b32_e32 v96, 0xffff0000, v102
	v_sub_u32_e32 v95, v98, v95
	v_and_b32_e32 v3, 0xffff0000, v3
	v_sub_u32_e32 v6, v6, v96
	v_add_u32_e32 v95, 0x80, v95
	v_sub_u32_e32 v3, v99, v3
	v_sub_u32_e32 v7, v7, v103
	v_add_u32_e32 v6, 0x80, v6
	v_ashrrev_i32_e32 v95, 8, v95
	v_add_u32_e32 v3, 0x80, v3
	v_add_u32_e32 v7, 0x80, v7
	v_ashrrev_i32_e32 v6, 8, v6
	v_min_i32_e32 v95, 0x7f, v95
	v_ashrrev_i32_e32 v3, 8, v3
	v_ashrrev_i32_e32 v7, 8, v7
	v_min_i32_e32 v6, 0x7f, v6
	v_min_i32_sdwa v3, v3, s79 dst_sel:WORD_1 dst_unused:UNUSED_PAD src0_sel:DWORD src1_sel:DWORD
	v_min_i32_e32 v7, 0x7f, v7
	v_lshlrev_b32_e32 v95, 8, v95
	v_and_b32_e32 v95, 0xff00, v95
	v_and_b32_e32 v3, 0xff0000, v3
	v_perm_b32 v6, v7, v6, s80
	v_or3_b32 v3, v6, v95, v3
	ds_write_b32 v14, v3 offset:144
	ds_read_b64 v[6:7], v15
	s_waitcnt lgkmcnt(0)
; #define WAIT_L(n) asm volatile("s_waitcnt lgkmcnt(" #n ")" ::: "memory")
; #define BAR __builtin_amdgcn_s_barrier()
;     ...
;               const float2 ms = *reinterpret_cast<const float2*>(mr + (ai * HALF + rr) * 2);
;               f32x4 y = acc[ai][bj][m][n];
;               const float o0 = (y[0] - ms.x) * ms.y * gm.x + bt.x, o1 = (y[1] - ms.x) * ms.y * gm.y + bt.y;
;               const float o2 = (y[2] - ms.x) * ms.y * gm.z + bt.z, o3 = (y[3] - ms.x) * ms.y * gm.w + bt.w;
;               const unsigned h0 = f2bf(o0), h1 = f2bf(o1), h2 = f2bf(o2), h3 = f2bf(o3);
;               u32x2 ob; ob[0] = h0 | (h1 << 16); ob[1] = h2 | (h3 << 16);
;               *reinterpret_cast<u32x2*>(smem + (rr >> 1) * PIECE + (rr & 1) * 512 + cc * 2) = ob;
;               const int l0 = min(((int)__float_as_uint(o0) - (int)(h0 << 16) + 128) >> 8, 127);
;               const int l1 = min(((int)__float_as_uint(o1) - (int)(h1 << 16) + 128) >> 8, 127);
;               const int l2 = min(((int)__float_as_uint(o2) - (int)(h2 << 16) + 128) >> 8, 127);
;               const int l3 = min(((int)__float_as_uint(o3) - (int)(h3 << 16) + 128) >> 8, 127);
;               *reinterpret_cast<unsigned*>(smem + LOBASE + (rr >> 2) * PIECE + (rr & 3) * 256 + cc) =
;                   (unsigned)(l0 & 255) | ((unsigned)(l1 & 255) << 8) | ((unsigned)(l2 & 255) << 16) | ((unsigned)l3 << 24);
;             }
;           }
;           WAIT_L(0); BAR;
;           const int hso = ((brow + ai * HALF + 16 * wave) * DM + pn * BM) * 2;
;           const int lso = (brow + ai * HALF + 16 * wave) * DM + pn * BM;
;           _Pragma("unroll") for (int i = 0; i < 8; ++i) {
;             const u32x4 v = *reinterpret_cast<const u32x4*>(smem + (wave * 8 + i) * PIECE + lane3 * 16);
;             __builtin_amdgcn_raw_buffer_store_b128(v, rsXB, hvo + i * (2 * DM * 2), hso, 0);
;           }
;           _Pragma("unroll") for (int i = 0; i < 4; ++i) {
;             const u32x4 v = *reinterpret_cast<const u32x4*>(smem + LOBASE + (wave * 4 + i) * PIECE + lane3 * 16);
	v_pk_add_f32 v[82:83], v[82:83], v[6:7] op_sel_hi:[1,0] neg_lo:[0,1] neg_hi:[0,1]
	s_nop 0
	v_pk_mul_f32 v[82:83], v[6:7], v[82:83] op_sel:[1,0]
	v_pk_add_f32 v[80:81], v[80:81], v[6:7] op_sel_hi:[1,0] neg_lo:[0,1] neg_hi:[0,1]
	v_pk_fma_f32 v[82:83], v[88:89], v[82:83], v[90:91]
	v_pk_mul_f32 v[6:7], v[6:7], v[80:81] op_sel:[1,0]
	v_and_b32_sdwa v80, v82, v216 dst_sel:DWORD dst_unused:UNUSED_PAD src0_sel:WORD_1 src1_sel:DWORD
	v_pk_fma_f32 v[6:7], v[0:1], v[6:7], v[4:5]
	v_add3_u32 v80, v82, v80, s78
	v_and_b32_e32 v81, 0xffff0000, v80
	v_and_b32_sdwa v80, v7, v216 dst_sel:DWORD dst_unused:UNUSED_PAD src0_sel:WORD_1 src1_sel:DWORD
	v_and_b32_sdwa v3, v83, v216 dst_sel:DWORD dst_unused:UNUSED_PAD src0_sel:WORD_1 src1_sel:DWORD
	v_and_b32_sdwa v95, v6, v216 dst_sel:DWORD dst_unused:UNUSED_PAD src0_sel:WORD_1 src1_sel:DWORD
	v_add3_u32 v80, v7, v80, s78
	v_add3_u32 v3, v83, v3, s78
	v_add3_u32 v95, v6, v95, s78
	v_and_b32_e32 v98, 0xffff0000, v80
	v_or_b32_sdwa v97, v98, v3 dst_sel:DWORD dst_unused:UNUSED_PAD src0_sel:DWORD src1_sel:WORD_1
	v_or_b32_sdwa v96, v95, v81 dst_sel:DWORD dst_unused:UNUSED_PAD src0_sel:WORD_1 src1_sel:DWORD
	v_and_b32_e32 v95, 0xffff0000, v95
	v_sub_u32_e32 v81, v82, v81
	v_and_b32_e32 v3, 0xffff0000, v3
	v_sub_u32_e32 v6, v6, v95
	v_add_u32_e32 v81, 0x80, v81
	v_sub_u32_e32 v3, v83, v3
	v_sub_u32_e32 v7, v7, v98
	v_add_u32_e32 v6, 0x80, v6
	v_ashrrev_i32_e32 v81, 8, v81
	v_add_u32_e32 v3, 0x80, v3
	v_add_u32_e32 v7, 0x80, v7
	v_ashrrev_i32_e32 v6, 8, v6
	v_min_i32_e32 v81, 0x7f, v81
	v_ashrrev_i32_e32 v3, 8, v3
	v_ashrrev_i32_e32 v7, 8, v7
	v_min_i32_e32 v6, 0x7f, v6
	v_min_i32_sdwa v3, v3, s79 dst_sel:WORD_1 dst_unused:UNUSED_PAD src0_sel:DWORD src1_sel:DWORD
	v_min_i32_e32 v7, 0x7f, v7
	v_lshlrev_b32_e32 v81, 8, v81
	v_and_b32_e32 v81, 0xff00, v81
	v_and_b32_e32 v3, 0xff0000, v3
	v_perm_b32 v6, v7, v6, s80
	v_add_u32_e32 v80, v2, v136
	v_or3_b32 v3, v6, v81, v3
	ds_write_b64 v80, v[96:97]
	ds_write_b32 v20, v3 offset:144
	ds_read_b64 v[6:7], v21
	v_or_b32_e32 v81, 0x6000, v148
	v_or_b32_e32 v82, 0x8000, v148
	v_or_b32_e32 v83, 0xa000, v148
	v_or_b32_e32 v95, 0x6000, v146
	s_waitcnt lgkmcnt(0)
	v_pk_add_f32 v[74:75], v[74:75], v[6:7] op_sel_hi:[1,0] neg_lo:[0,1] neg_hi:[0,1]
	v_pk_add_f32 v[72:73], v[72:73], v[6:7] op_sel_hi:[1,0] neg_lo:[0,1] neg_hi:[0,1]
	v_pk_mul_f32 v[74:75], v[6:7], v[74:75] op_sel:[1,0]
	v_pk_mul_f32 v[6:7], v[6:7], v[72:73] op_sel:[1,0]
	v_pk_fma_f32 v[74:75], v[88:89], v[74:75], v[90:91]
	v_pk_fma_f32 v[0:1], v[0:1], v[6:7], v[4:5]
	v_and_b32_sdwa v4, v74, v216 dst_sel:DWORD dst_unused:UNUSED_PAD src0_sel:WORD_1 src1_sel:DWORD
	v_add3_u32 v4, v74, v4, s78
	v_and_b32_e32 v6, 0xffff0000, v4
	v_and_b32_sdwa v4, v1, v216 dst_sel:DWORD dst_unused:UNUSED_PAD src0_sel:WORD_1 src1_sel:DWORD
	v_and_b32_sdwa v5, v0, v216 dst_sel:DWORD dst_unused:UNUSED_PAD src0_sel:WORD_1 src1_sel:DWORD
	v_and_b32_sdwa v3, v75, v216 dst_sel:DWORD dst_unused:UNUSED_PAD src0_sel:WORD_1 src1_sel:DWORD
	v_add3_u32 v4, v1, v4, s78
	v_add3_u32 v7, v0, v5, s78
	v_add3_u32 v3, v75, v3, s78
	v_and_b32_e32 v72, 0xffff0000, v4
	v_add_u32_e32 v73, v2, v135
	v_and_b32_e32 v2, 0xffff0000, v7
	v_or_b32_sdwa v5, v72, v3 dst_sel:DWORD dst_unused:UNUSED_PAD src0_sel:DWORD src1_sel:WORD_1
	v_sub_u32_e32 v0, v0, v2
	v_sub_u32_e32 v2, v74, v6
	v_and_b32_e32 v3, 0xffff0000, v3
	v_add_u32_e32 v2, 0x80, v2
	v_sub_u32_e32 v3, v75, v3
	v_sub_u32_e32 v1, v1, v72
	v_add_u32_e32 v0, 0x80, v0
	v_ashrrev_i32_e32 v2, 8, v2
	v_add_u32_e32 v3, 0x80, v3
	v_add_u32_e32 v1, 0x80, v1
	v_ashrrev_i32_e32 v0, 8, v0
	v_min_i32_e32 v2, 0x7f, v2
	v_ashrrev_i32_e32 v3, 8, v3
	v_ashrrev_i32_e32 v1, 8, v1
	v_min_i32_e32 v0, 0x7f, v0
	v_min_i32_sdwa v3, v3, s79 dst_sel:WORD_1 dst_unused:UNUSED_PAD src0_sel:DWORD src1_sel:DWORD
	v_min_i32_e32 v1, 0x7f, v1
	v_lshlrev_b32_e32 v2, 8, v2
	v_and_b32_e32 v2, 0xff00, v2
	v_and_b32_e32 v3, 0xff0000, v3
	v_perm_b32 v0, v1, v0, s80
	v_or_b32_sdwa v4, v7, v6 dst_sel:DWORD dst_unused:UNUSED_PAD src0_sel:WORD_1 src1_sel:DWORD
	v_or3_b32 v0, v0, v2, v3
	ds_write_b64 v73, v[4:5]
	ds_write_b32 v22, v0 offset:144
	v_add_u32_e32 v72, s60, v151
	s_waitcnt lgkmcnt(0)
	s_barrier
	ds_read_b128 v[128:131], v72
	v_or_b32_e32 v74, 0x2000, v148
	v_or_b32_e32 v75, 0x4000, v148
	v_or_b32_e32 v88, 0xc000, v148
	v_or_b32_e32 v89, 0xe000, v148
	ds_read_b128 v[136:139], v72 offset:1040
	v_or_b32_e32 v90, 0x2000, v146
	v_or_b32_e32 v91, 0x4000, v146
	ds_read_b128 v[140:143], v72 offset:2080
	ds_read_b128 v[156:159], v72 offset:3120
	ds_read_b128 v[160:163], v72 offset:4160
	ds_read_b128 v[164:167], v72 offset:5200
	ds_read_b128 v[168:171], v72 offset:6240
	ds_read_b128 v[172:175], v72 offset:7280
	ds_read_b128 v[176:179], v147
	ds_read_b128 v[180:183], v147 offset:1040
	ds_read_b128 v[184:187], v147 offset:2080
	ds_read_b128 v[188:191], v147 offset:3120
	s_waitcnt lgkmcnt(0)
	s_barrier
;     ...
;               const float2 ms = *reinterpret_cast<const float2*>(mr + (ai * HALF + rr) * 2);
;               f32x4 y = acc[ai][bj][m][n];
;               const float o0 = (y[0] - ms.x) * ms.y * gm.x + bt.x, o1 = (y[1] - ms.x) * ms.y * gm.y + bt.y;
;               const float o2 = (y[2] - ms.x) * ms.y * gm.z + bt.z, o3 = (y[3] - ms.x) * ms.y * gm.w + bt.w;
;               const unsigned h0 = f2bf(o0), h1 = f2bf(o1), h2 = f2bf(o2), h3 = f2bf(o3);
;               u32x2 ob; ob[0] = h0 | (h1 << 16); ob[1] = h2 | (h3 << 16);
;               *reinterpret_cast<u32x2*>(smem + (rr >> 1) * PIECE + (rr & 1) * 512 + cc * 2) = ob;
;               const int l0 = min(((int)__float_as_uint(o0) - (int)(h0 << 16) + 128) >> 8, 127);
;               const int l1 = min(((int)__float_as_uint(o1) - (int)(h1 << 16) + 128) >> 8, 127);
;               const int l2 = min(((int)__float_as_uint(o2) - (int)(h2 << 16) + 128) >> 8, 127);
;               const int l3 = min(((int)__float_as_uint(o3) - (int)(h3 << 16) + 128) >> 8, 127);
;               *reinterpret_cast<unsigned*>(smem + LOBASE + (rr >> 2) * PIECE + (rr & 3) * 256 + cc) =
;                   (unsigned)(l0 & 255) | ((unsigned)(l1 & 255) << 8) | ((unsigned)(l2 & 255) << 16) | ((unsigned)l3 << 24);
;     ...
;           _Pragma("unroll") for (int i = 0; i < 8; ++i) {
;             const u32x4 v = *reinterpret_cast<const u32x4*>(smem + (wave * 8 + i) * PIECE + lane3 * 16);
;             __builtin_amdgcn_raw_buffer_store_b128(v, rsXB, hvo + i * (2 * DM * 2), hso, 0);
;           }
;           _Pragma("unroll") for (int i = 0; i < 4; ++i) {
;             const u32x4 v = *reinterpret_cast<const u32x4*>(smem + LOBASE + (wave * 4 + i) * PIECE + lane3 * 16);
;             __builtin_amdgcn_raw_buffer_store_b128(v, rsLO, lvo + i * (4 * DM), lso, 0);
	s_nop 1
	v_mov_b32_e32 v0, v220
	v_mov_b32_e32 v1, v221
	v_mov_b32_e32 v2, v222
	v_mov_b32_e32 v3, v223
	v_mov_b32_e32 v4, v236
	v_mov_b32_e32 v5, v237
	v_mov_b32_e32 v6, v238
	v_mov_b32_e32 v7, v239
	ds_read_b64 v[102:103], v149 offset:1024
	s_waitcnt lgkmcnt(0)
	v_pk_add_f32 v[66:67], v[66:67], v[102:103] op_sel_hi:[1,0] neg_lo:[0,1] neg_hi:[0,1]
	s_nop 0
	v_pk_mul_f32 v[66:67], v[102:103], v[66:67] op_sel:[1,0]
	v_pk_add_f32 v[64:65], v[64:65], v[102:103] op_sel_hi:[1,0] neg_lo:[0,1] neg_hi:[0,1]
	v_mov_b32_e32 v96, v1
	v_mov_b32_e32 v97, v2
	v_mov_b32_e32 v98, v5
	v_mov_b32_e32 v99, v6
	v_pk_fma_f32 v[66:67], v[96:97], v[66:67], v[98:99]
	v_pk_mul_f32 v[64:65], v[102:103], v[64:65] op_sel:[1,0]
	v_mov_b32_e32 v1, v3
	v_mov_b32_e32 v5, v7
	v_and_b32_sdwa v6, v67, v216 dst_sel:DWORD dst_unused:UNUSED_PAD src0_sel:WORD_1 src1_sel:DWORD
	v_and_b32_sdwa v7, v66, v216 dst_sel:DWORD dst_unused:UNUSED_PAD src0_sel:WORD_1 src1_sel:DWORD
	v_pk_fma_f32 v[2:3], v[0:1], v[64:65], v[4:5]
	v_add3_u32 v64, v67, v6, s78
	v_add3_u32 v6, v66, v7, s78
	v_and_b32_e32 v65, 0xffff0000, v6
	v_and_b32_sdwa v6, v3, v216 dst_sel:DWORD dst_unused:UNUSED_PAD src0_sel:WORD_1 src1_sel:DWORD
	v_and_b32_sdwa v7, v2, v216 dst_sel:DWORD dst_unused:UNUSED_PAD src0_sel:WORD_1 src1_sel:DWORD
	v_add3_u32 v6, v3, v6, s78
	v_add3_u32 v102, v2, v7, s78
	v_and_b32_e32 v103, 0xffff0000, v6
	v_or_b32_sdwa v7, v103, v64 dst_sel:DWORD dst_unused:UNUSED_PAD src0_sel:DWORD src1_sel:WORD_1
	v_or_b32_sdwa v6, v102, v65 dst_sel:DWORD dst_unused:UNUSED_PAD src0_sel:WORD_1 src1_sel:DWORD
	ds_write_b64 v152, v[6:7]
	v_and_b32_e32 v6, 0xffff0000, v102
	v_sub_u32_e32 v2, v2, v6
	v_sub_u32_e32 v6, v66, v65
	v_and_b32_e32 v7, 0xffff0000, v64
	v_add_u32_e32 v6, 0x80, v6
	v_sub_u32_e32 v7, v67, v7
	v_sub_u32_e32 v3, v3, v103
	v_add_u32_e32 v2, 0x80, v2
	v_ashrrev_i32_e32 v6, 8, v6
	v_add_u32_e32 v7, 0x80, v7
	v_add_u32_e32 v3, 0x80, v3
	v_ashrrev_i32_e32 v2, 8, v2
	v_min_i32_e32 v6, 0x7f, v6
	v_ashrrev_i32_e32 v7, 8, v7
	v_ashrrev_i32_e32 v3, 8, v3
	v_min_i32_e32 v2, 0x7f, v2
	v_min_i32_sdwa v7, v7, s79 dst_sel:WORD_1 dst_unused:UNUSED_PAD src0_sel:DWORD src1_sel:DWORD
	v_min_i32_e32 v3, 0x7f, v3
	v_lshlrev_b32_e32 v6, 8, v6
	v_and_b32_e32 v6, 0xff00, v6
	v_and_b32_e32 v7, 0xff0000, v7
	v_perm_b32 v2, v3, v2, s80
	v_or3_b32 v2, v2, v6, v7
	ds_write_b32 v12, v2
	buffer_store_dwordx4 v[128:131], v148, s[16:19], s33 offen
	ds_read_b64 v[2:3], v13 offset:1024
	s_waitcnt lgkmcnt(0)
	v_pk_add_f32 v[6:7], v[70:71], v[2:3] op_sel_hi:[1,0] neg_lo:[0,1] neg_hi:[0,1]
	s_nop 0
	v_pk_mul_f32 v[6:7], v[2:3], v[6:7] op_sel:[1,0]
	v_pk_add_f32 v[64:65], v[68:69], v[2:3] op_sel_hi:[1,0] neg_lo:[0,1] neg_hi:[0,1]
	v_pk_fma_f32 v[6:7], v[96:97], v[6:7], v[98:99]
	v_pk_mul_f32 v[2:3], v[2:3], v[64:65] op_sel:[1,0]
	v_and_b32_sdwa v64, v7, v216 dst_sel:DWORD dst_unused:UNUSED_PAD src0_sel:WORD_1 src1_sel:DWORD
	v_and_b32_sdwa v65, v6, v216 dst_sel:DWORD dst_unused:UNUSED_PAD src0_sel:WORD_1 src1_sel:DWORD
	v_pk_fma_f32 v[2:3], v[0:1], v[2:3], v[4:5]
	v_add3_u32 v66, v7, v64, s78
	v_add3_u32 v64, v6, v65, s78
	v_and_b32_e32 v67, 0xffff0000, v64
	v_and_b32_sdwa v64, v3, v216 dst_sel:DWORD dst_unused:UNUSED_PAD src0_sel:WORD_1 src1_sel:DWORD
	v_and_b32_sdwa v65, v2, v216 dst_sel:DWORD dst_unused:UNUSED_PAD src0_sel:WORD_1 src1_sel:DWORD
	v_add3_u32 v64, v3, v64, s78
	v_add3_u32 v68, v2, v65, s78
	v_and_b32_e32 v69, 0xffff0000, v64
	v_or_b32_sdwa v65, v69, v66 dst_sel:DWORD dst_unused:UNUSED_PAD src0_sel:DWORD src1_sel:WORD_1
	v_or_b32_sdwa v64, v68, v67 dst_sel:DWORD dst_unused:UNUSED_PAD src0_sel:WORD_1 src1_sel:DWORD
	ds_write_b64 v132, v[64:65]
	v_and_b32_e32 v64, 0xffff0000, v68
	v_sub_u32_e32 v2, v2, v64
	v_sub_u32_e32 v6, v6, v67
	v_and_b32_e32 v64, 0xffff0000, v66
	v_add_u32_e32 v6, 0x80, v6
	v_sub_u32_e32 v7, v7, v64
	v_sub_u32_e32 v3, v3, v69
	v_add_u32_e32 v2, 0x80, v2
	v_ashrrev_i32_e32 v6, 8, v6
	v_add_u32_e32 v7, 0x80, v7
	v_add_u32_e32 v3, 0x80, v3
	v_ashrrev_i32_e32 v2, 8, v2
	v_min_i32_e32 v6, 0x7f, v6
	v_ashrrev_i32_e32 v7, 8, v7
	v_ashrrev_i32_e32 v3, 8, v3
	v_min_i32_e32 v2, 0x7f, v2
	v_min_i32_sdwa v7, v7, s79 dst_sel:WORD_1 dst_unused:UNUSED_PAD src0_sel:DWORD src1_sel:DWORD
	v_min_i32_e32 v3, 0x7f, v3
	v_lshlrev_b32_e32 v6, 8, v6
	v_and_b32_e32 v6, 0xff00, v6
	v_and_b32_e32 v7, 0xff0000, v7
	v_perm_b32 v2, v3, v2, s80
	v_or3_b32 v2, v2, v6, v7
	ds_write_b32 v14, v2
	buffer_store_dwordx4 v[136:139], v74, s[16:19], s33 offen
	ds_read_b64 v[2:3], v15 offset:1024
	s_waitcnt lgkmcnt(0)
	v_pk_add_f32 v[6:7], v[78:79], v[2:3] op_sel_hi:[1,0] neg_lo:[0,1] neg_hi:[0,1]
	s_nop 0
	v_pk_mul_f32 v[6:7], v[2:3], v[6:7] op_sel:[1,0]
	v_pk_add_f32 v[64:65], v[76:77], v[2:3] op_sel_hi:[1,0] neg_lo:[0,1] neg_hi:[0,1]
	v_pk_fma_f32 v[6:7], v[96:97], v[6:7], v[98:99]
	v_pk_mul_f32 v[2:3], v[2:3], v[64:65] op_sel:[1,0]
	v_and_b32_sdwa v64, v7, v216 dst_sel:DWORD dst_unused:UNUSED_PAD src0_sel:WORD_1 src1_sel:DWORD
	v_and_b32_sdwa v65, v6, v216 dst_sel:DWORD dst_unused:UNUSED_PAD src0_sel:WORD_1 src1_sel:DWORD
	v_pk_fma_f32 v[2:3], v[0:1], v[2:3], v[4:5]
	v_add3_u32 v66, v7, v64, s78
	v_add3_u32 v64, v6, v65, s78
	v_and_b32_e32 v67, 0xffff0000, v64
	v_and_b32_sdwa v64, v3, v216 dst_sel:DWORD dst_unused:UNUSED_PAD src0_sel:WORD_1 src1_sel:DWORD
	v_and_b32_sdwa v65, v2, v216 dst_sel:DWORD dst_unused:UNUSED_PAD src0_sel:WORD_1 src1_sel:DWORD
	v_add3_u32 v64, v3, v64, s78
	v_add3_u32 v68, v2, v65, s78
	v_and_b32_e32 v69, 0xffff0000, v64
	v_or_b32_sdwa v65, v69, v66 dst_sel:DWORD dst_unused:UNUSED_PAD src0_sel:DWORD src1_sel:WORD_1
	v_or_b32_sdwa v64, v68, v67 dst_sel:DWORD dst_unused:UNUSED_PAD src0_sel:WORD_1 src1_sel:DWORD
	ds_write_b64 v133, v[64:65]
	v_and_b32_e32 v64, 0xffff0000, v68
	v_sub_u32_e32 v2, v2, v64
	v_sub_u32_e32 v6, v6, v67
	v_and_b32_e32 v64, 0xffff0000, v66
	v_add_u32_e32 v6, 0x80, v6
	v_sub_u32_e32 v7, v7, v64
	v_sub_u32_e32 v3, v3, v69
	v_add_u32_e32 v2, 0x80, v2
	v_ashrrev_i32_e32 v6, 8, v6
	v_add_u32_e32 v7, 0x80, v7
	v_add_u32_e32 v3, 0x80, v3
	v_ashrrev_i32_e32 v2, 8, v2
	v_min_i32_e32 v6, 0x7f, v6
	v_ashrrev_i32_e32 v7, 8, v7
	v_ashrrev_i32_e32 v3, 8, v3
	v_min_i32_e32 v2, 0x7f, v2
	v_min_i32_sdwa v7, v7, s79 dst_sel:WORD_1 dst_unused:UNUSED_PAD src0_sel:DWORD src1_sel:DWORD
	v_min_i32_e32 v3, 0x7f, v3
	v_lshlrev_b32_e32 v6, 8, v6
	v_and_b32_e32 v6, 0xff00, v6
	v_and_b32_e32 v7, 0xff0000, v7
	v_perm_b32 v2, v3, v2, s80
	v_or3_b32 v2, v2, v6, v7
	ds_write_b32 v20, v2
	buffer_store_dwordx4 v[140:143], v75, s[16:19], s33 offen
	ds_read_b64 v[2:3], v21 offset:1024
	s_waitcnt lgkmcnt(0)
;     ...
;               const float2 ms = *reinterpret_cast<const float2*>(mr + (ai * HALF + rr) * 2);
;               f32x4 y = acc[ai][bj][m][n];
;               const float o0 = (y[0] - ms.x) * ms.y * gm.x + bt.x, o1 = (y[1] - ms.x) * ms.y * gm.y + bt.y;
;               const float o2 = (y[2] - ms.x) * ms.y * gm.z + bt.z, o3 = (y[3] - ms.x) * ms.y * gm.w + bt.w;
;               const unsigned h0 = f2bf(o0), h1 = f2bf(o1), h2 = f2bf(o2), h3 = f2bf(o3);
;               u32x2 ob; ob[0] = h0 | (h1 << 16); ob[1] = h2 | (h3 << 16);
;               *reinterpret_cast<u32x2*>(smem + (rr >> 1) * PIECE + (rr & 1) * 512 + cc * 2) = ob;
;               const int l0 = min(((int)__float_as_uint(o0) - (int)(h0 << 16) + 128) >> 8, 127);
;               const int l1 = min(((int)__float_as_uint(o1) - (int)(h1 << 16) + 128) >> 8, 127);
;               const int l2 = min(((int)__float_as_uint(o2) - (int)(h2 << 16) + 128) >> 8, 127);
;               const int l3 = min(((int)__float_as_uint(o3) - (int)(h3 << 16) + 128) >> 8, 127);
;               *reinterpret_cast<unsigned*>(smem + LOBASE + (rr >> 2) * PIECE + (rr & 3) * 256 + cc) =
;                   (unsigned)(l0 & 255) | ((unsigned)(l1 & 255) << 8) | ((unsigned)(l2 & 255) << 16) | ((unsigned)l3 << 24);
;     ...
;           _Pragma("unroll") for (int i = 0; i < 8; ++i) {
;             const u32x4 v = *reinterpret_cast<const u32x4*>(smem + (wave * 8 + i) * PIECE + lane3 * 16);
;             __builtin_amdgcn_raw_buffer_store_b128(v, rsXB, hvo + i * (2 * DM * 2), hso, 0);
;           }
;           _Pragma("unroll") for (int i = 0; i < 4; ++i) {
;             const u32x4 v = *reinterpret_cast<const u32x4*>(smem + LOBASE + (wave * 4 + i) * PIECE + lane3 * 16);
;             __builtin_amdgcn_raw_buffer_store_b128(v, rsLO, lvo + i * (4 * DM), lso, 0);
	v_pk_add_f32 v[6:7], v[86:87], v[2:3] op_sel_hi:[1,0] neg_lo:[0,1] neg_hi:[0,1]
	s_nop 0
	v_pk_mul_f32 v[6:7], v[2:3], v[6:7] op_sel:[1,0]
	v_pk_add_f32 v[64:65], v[84:85], v[2:3] op_sel_hi:[1,0] neg_lo:[0,1] neg_hi:[0,1]
	v_pk_fma_f32 v[6:7], v[96:97], v[6:7], v[98:99]
	v_pk_mul_f32 v[2:3], v[2:3], v[64:65] op_sel:[1,0]
	s_nop 0
	v_pk_fma_f32 v[0:1], v[0:1], v[2:3], v[4:5]
	v_and_b32_sdwa v2, v7, v216 dst_sel:DWORD dst_unused:UNUSED_PAD src0_sel:WORD_1 src1_sel:DWORD
	v_and_b32_sdwa v3, v6, v216 dst_sel:DWORD dst_unused:UNUSED_PAD src0_sel:WORD_1 src1_sel:DWORD
	v_add3_u32 v4, v7, v2, s78
	v_add3_u32 v2, v6, v3, s78
	v_and_b32_e32 v5, 0xffff0000, v2
	v_and_b32_sdwa v2, v1, v216 dst_sel:DWORD dst_unused:UNUSED_PAD src0_sel:WORD_1 src1_sel:DWORD
	v_and_b32_sdwa v3, v0, v216 dst_sel:DWORD dst_unused:UNUSED_PAD src0_sel:WORD_1 src1_sel:DWORD
	v_add3_u32 v2, v1, v2, s78
	v_add3_u32 v64, v0, v3, s78
	v_and_b32_e32 v65, 0xffff0000, v2
	v_or_b32_sdwa v3, v65, v4 dst_sel:DWORD dst_unused:UNUSED_PAD src0_sel:DWORD src1_sel:WORD_1
	v_or_b32_sdwa v2, v64, v5 dst_sel:DWORD dst_unused:UNUSED_PAD src0_sel:WORD_1 src1_sel:DWORD
	ds_write_b64 v134, v[2:3]
	v_and_b32_e32 v2, 0xffff0000, v64
	v_sub_u32_e32 v0, v0, v2
	v_sub_u32_e32 v2, v6, v5
	v_and_b32_e32 v3, 0xffff0000, v4
	v_add_u32_e32 v2, 0x80, v2
	v_sub_u32_e32 v3, v7, v3
	v_sub_u32_e32 v1, v1, v65
	v_add_u32_e32 v0, 0x80, v0
	v_ashrrev_i32_e32 v2, 8, v2
	v_add_u32_e32 v3, 0x80, v3
	v_add_u32_e32 v1, 0x80, v1
	v_ashrrev_i32_e32 v0, 8, v0
	v_min_i32_e32 v2, 0x7f, v2
	v_ashrrev_i32_e32 v3, 8, v3
	v_ashrrev_i32_e32 v1, 8, v1
	v_min_i32_e32 v0, 0x7f, v0
	v_min_i32_sdwa v3, v3, s79 dst_sel:WORD_1 dst_unused:UNUSED_PAD src0_sel:DWORD src1_sel:DWORD
	v_min_i32_e32 v1, 0x7f, v1
	v_lshlrev_b32_e32 v2, 8, v2
	v_and_b32_e32 v2, 0xff00, v2
	v_and_b32_e32 v3, 0xff0000, v3
	v_perm_b32 v0, v1, v0, s80
	v_or3_b32 v0, v0, v2, v3
	ds_write_b32 v22, v0
	buffer_store_dwordx4 v[156:159], v81, s[16:19], s33 offen
	v_mov_b32_e32 v0, v224
	v_mov_b32_e32 v1, v225
	v_mov_b32_e32 v2, v226
	v_mov_b32_e32 v3, v227
	v_mov_b32_e32 v4, v240
	v_mov_b32_e32 v5, v241
	v_mov_b32_e32 v6, v242
	v_mov_b32_e32 v7, v243
	ds_read_b64 v[68:69], v149 offset:1024
	s_waitcnt lgkmcnt(0)
	v_pk_add_f32 v[58:59], v[58:59], v[68:69] op_sel_hi:[1,0] neg_lo:[0,1] neg_hi:[0,1]
	s_nop 0
	v_pk_mul_f32 v[58:59], v[68:69], v[58:59] op_sel:[1,0]
	v_pk_add_f32 v[56:57], v[56:57], v[68:69] op_sel_hi:[1,0] neg_lo:[0,1] neg_hi:[0,1]
	v_mov_b32_e32 v64, v1
	v_mov_b32_e32 v65, v2
	v_mov_b32_e32 v66, v5
	v_mov_b32_e32 v67, v6
	v_pk_fma_f32 v[58:59], v[64:65], v[58:59], v[66:67]
	v_pk_mul_f32 v[56:57], v[68:69], v[56:57] op_sel:[1,0]
	v_mov_b32_e32 v1, v3
	v_mov_b32_e32 v5, v7
	v_and_b32_sdwa v6, v59, v216 dst_sel:DWORD dst_unused:UNUSED_PAD src0_sel:WORD_1 src1_sel:DWORD
	v_and_b32_sdwa v7, v58, v216 dst_sel:DWORD dst_unused:UNUSED_PAD src0_sel:WORD_1 src1_sel:DWORD
	v_pk_fma_f32 v[2:3], v[0:1], v[56:57], v[4:5]
	v_add3_u32 v56, v59, v6, s78
	v_add3_u32 v6, v58, v7, s78
	v_and_b32_e32 v57, 0xffff0000, v6
	v_and_b32_sdwa v6, v3, v216 dst_sel:DWORD dst_unused:UNUSED_PAD src0_sel:WORD_1 src1_sel:DWORD
	v_and_b32_sdwa v7, v2, v216 dst_sel:DWORD dst_unused:UNUSED_PAD src0_sel:WORD_1 src1_sel:DWORD
	v_add3_u32 v6, v3, v6, s78
	v_add3_u32 v68, v2, v7, s78
	v_and_b32_e32 v69, 0xffff0000, v6
	v_or_b32_sdwa v7, v69, v56 dst_sel:DWORD dst_unused:UNUSED_PAD src0_sel:DWORD src1_sel:WORD_1
	v_or_b32_sdwa v6, v68, v57 dst_sel:DWORD dst_unused:UNUSED_PAD src0_sel:WORD_1 src1_sel:DWORD
	ds_write_b64 v23, v[6:7]
	v_and_b32_e32 v6, 0xffff0000, v68
	v_sub_u32_e32 v2, v2, v6
	v_sub_u32_e32 v6, v58, v57
	v_and_b32_e32 v7, 0xffff0000, v56
	v_add_u32_e32 v6, 0x80, v6
	v_sub_u32_e32 v7, v59, v7
	v_sub_u32_e32 v3, v3, v69
	v_add_u32_e32 v2, 0x80, v2
	v_ashrrev_i32_e32 v6, 8, v6
	v_add_u32_e32 v7, 0x80, v7
	v_add_u32_e32 v3, 0x80, v3
	v_ashrrev_i32_e32 v2, 8, v2
	v_min_i32_e32 v6, 0x7f, v6
	v_ashrrev_i32_e32 v7, 8, v7
	v_ashrrev_i32_e32 v3, 8, v3
	v_min_i32_e32 v2, 0x7f, v2
	v_min_i32_sdwa v7, v7, s79 dst_sel:WORD_1 dst_unused:UNUSED_PAD src0_sel:DWORD src1_sel:DWORD
	v_min_i32_e32 v3, 0x7f, v3
	v_lshlrev_b32_e32 v6, 8, v6
	v_and_b32_e32 v6, 0xff00, v6
	v_and_b32_e32 v7, 0xff0000, v7
	v_perm_b32 v2, v3, v2, s80
	v_or3_b32 v2, v2, v6, v7
	ds_write_b32 v12, v2 offset:16
	buffer_store_dwordx4 v[160:163], v82, s[16:19], s33 offen
	ds_read_b64 v[2:3], v13 offset:1024
	s_waitcnt lgkmcnt(0)
	v_pk_add_f32 v[6:7], v[42:43], v[2:3] op_sel_hi:[1,0] neg_lo:[0,1] neg_hi:[0,1]
	s_nop 0
	v_pk_mul_f32 v[6:7], v[2:3], v[6:7] op_sel:[1,0]
	v_pk_add_f32 v[40:41], v[40:41], v[2:3] op_sel_hi:[1,0] neg_lo:[0,1] neg_hi:[0,1]
	v_pk_fma_f32 v[6:7], v[64:65], v[6:7], v[66:67]
	v_pk_mul_f32 v[2:3], v[2:3], v[40:41] op_sel:[1,0]
	v_and_b32_sdwa v40, v6, v216 dst_sel:DWORD dst_unused:UNUSED_PAD src0_sel:WORD_1 src1_sel:DWORD
	v_pk_fma_f32 v[2:3], v[0:1], v[2:3], v[4:5]
	v_add3_u32 v40, v6, v40, s78
	v_and_b32_e32 v42, 0xffff0000, v40
	v_and_b32_sdwa v40, v3, v216 dst_sel:DWORD dst_unused:UNUSED_PAD src0_sel:WORD_1 src1_sel:DWORD
	v_and_b32_sdwa v23, v7, v216 dst_sel:DWORD dst_unused:UNUSED_PAD src0_sel:WORD_1 src1_sel:DWORD
	v_and_b32_sdwa v41, v2, v216 dst_sel:DWORD dst_unused:UNUSED_PAD src0_sel:WORD_1 src1_sel:DWORD
	v_add3_u32 v40, v3, v40, s78
	v_add3_u32 v23, v7, v23, s78
	v_add3_u32 v43, v2, v41, s78
	v_and_b32_e32 v56, 0xffff0000, v40
	v_or_b32_sdwa v41, v56, v23 dst_sel:DWORD dst_unused:UNUSED_PAD src0_sel:DWORD src1_sel:WORD_1
	v_or_b32_sdwa v40, v43, v42 dst_sel:DWORD dst_unused:UNUSED_PAD src0_sel:WORD_1 src1_sel:DWORD
	ds_write_b64 v104, v[40:41]
	v_and_b32_e32 v40, 0xffff0000, v43
	v_sub_u32_e32 v6, v6, v42
	v_and_b32_e32 v23, 0xffff0000, v23
	v_sub_u32_e32 v2, v2, v40
	v_add_u32_e32 v6, 0x80, v6
	v_sub_u32_e32 v7, v7, v23
	v_sub_u32_e32 v3, v3, v56
	v_add_u32_e32 v2, 0x80, v2
	v_ashrrev_i32_e32 v6, 8, v6
	v_add_u32_e32 v7, 0x80, v7
	v_add_u32_e32 v3, 0x80, v3
	v_ashrrev_i32_e32 v2, 8, v2
	v_min_i32_e32 v6, 0x7f, v6
	v_ashrrev_i32_e32 v7, 8, v7
	v_ashrrev_i32_e32 v3, 8, v3
	v_min_i32_e32 v2, 0x7f, v2
	v_min_i32_sdwa v7, v7, s79 dst_sel:WORD_1 dst_unused:UNUSED_PAD src0_sel:DWORD src1_sel:DWORD
	v_min_i32_e32 v3, 0x7f, v3
	v_lshlrev_b32_e32 v6, 8, v6
	v_and_b32_e32 v6, 0xff00, v6
	v_and_b32_e32 v7, 0xff0000, v7
	v_perm_b32 v2, v3, v2, s80
	v_or3_b32 v2, v2, v6, v7
	ds_write_b32 v14, v2 offset:16
	buffer_store_dwordx4 v[164:167], v83, s[16:19], s33 offen
	ds_read_b64 v[2:3], v15 offset:1024
	s_waitcnt lgkmcnt(0)
;     ...
;           _Pragma("unroll") for (int bj = 0; bj < 2; ++bj) _Pragma("unroll") for (int n = 0; n < 2; ++n) {
;             const int cc = bj * HALF + wc3 * 32 + n * 16 + fq3 * 4;
;             const float4 gm = *reinterpret_cast<const float4*>(g.gam + pn * BM + cc), bt = *reinterpret_cast<const float4*>(g.bet + pn * BM + cc);
;             _Pragma("unroll") for (int m = 0; m < 4; ++m) {
;               const int rr = wr3 * 64 + m * 16 + fr3;
;               const float2 ms = *reinterpret_cast<const float2*>(mr + (ai * HALF + rr) * 2);
;               f32x4 y = acc[ai][bj][m][n];
;               const float o0 = (y[0] - ms.x) * ms.y * gm.x + bt.x, o1 = (y[1] - ms.x) * ms.y * gm.y + bt.y;
;               const float o2 = (y[2] - ms.x) * ms.y * gm.z + bt.z, o3 = (y[3] - ms.x) * ms.y * gm.w + bt.w;
;               const unsigned h0 = f2bf(o0), h1 = f2bf(o1), h2 = f2bf(o2), h3 = f2bf(o3);
;               u32x2 ob; ob[0] = h0 | (h1 << 16); ob[1] = h2 | (h3 << 16);
;               *reinterpret_cast<u32x2*>(smem + (rr >> 1) * PIECE + (rr & 1) * 512 + cc * 2) = ob;
;               const int l0 = min(((int)__float_as_uint(o0) - (int)(h0 << 16) + 128) >> 8, 127);
;               const int l1 = min(((int)__float_as_uint(o1) - (int)(h1 << 16) + 128) >> 8, 127);
;               const int l2 = min(((int)__float_as_uint(o2) - (int)(h2 << 16) + 128) >> 8, 127);
;               const int l3 = min(((int)__float_as_uint(o3) - (int)(h3 << 16) + 128) >> 8, 127);
;               *reinterpret_cast<unsigned*>(smem + LOBASE + (rr >> 2) * PIECE + (rr & 3) * 256 + cc) =
;                   (unsigned)(l0 & 255) | ((unsigned)(l1 & 255) << 8) | ((unsigned)(l2 & 255) << 16) | ((unsigned)l3 << 24);
;             }
;           }
;           WAIT_L(0); BAR;
;           const int hso = ((brow + ai * HALF + 16 * wave) * DM + pn * BM) * 2;
;           const int lso = (brow + ai * HALF + 16 * wave) * DM + pn * BM;
;           _Pragma("unroll") for (int i = 0; i < 8; ++i) {
;             const u32x4 v = *reinterpret_cast<const u32x4*>(smem + (wave * 8 + i) * PIECE + lane3 * 16);
;             __builtin_amdgcn_raw_buffer_store_b128(v, rsXB, hvo + i * (2 * DM * 2), hso, 0);
;           }
;           _Pragma("unroll") for (int i = 0; i < 4; ++i) {
;             const u32x4 v = *reinterpret_cast<const u32x4*>(smem + LOBASE + (wave * 4 + i) * PIECE + lane3 * 16);
	v_pk_add_f32 v[6:7], v[46:47], v[2:3] op_sel_hi:[1,0] neg_lo:[0,1] neg_hi:[0,1]
	s_nop 0
	v_pk_mul_f32 v[6:7], v[2:3], v[6:7] op_sel:[1,0]
	v_pk_add_f32 v[40:41], v[44:45], v[2:3] op_sel_hi:[1,0] neg_lo:[0,1] neg_hi:[0,1]
	v_pk_fma_f32 v[6:7], v[64:65], v[6:7], v[66:67]
	v_pk_mul_f32 v[2:3], v[2:3], v[40:41] op_sel:[1,0]
	v_and_b32_sdwa v40, v6, v216 dst_sel:DWORD dst_unused:UNUSED_PAD src0_sel:WORD_1 src1_sel:DWORD
	v_pk_fma_f32 v[2:3], v[0:1], v[2:3], v[4:5]
	v_add3_u32 v40, v6, v40, s78
	v_and_b32_e32 v42, 0xffff0000, v40
	v_and_b32_sdwa v40, v3, v216 dst_sel:DWORD dst_unused:UNUSED_PAD src0_sel:WORD_1 src1_sel:DWORD
	v_and_b32_sdwa v23, v7, v216 dst_sel:DWORD dst_unused:UNUSED_PAD src0_sel:WORD_1 src1_sel:DWORD
	v_and_b32_sdwa v41, v2, v216 dst_sel:DWORD dst_unused:UNUSED_PAD src0_sel:WORD_1 src1_sel:DWORD
	v_add3_u32 v40, v3, v40, s78
	v_add3_u32 v23, v7, v23, s78
	v_add3_u32 v43, v2, v41, s78
	v_and_b32_e32 v44, 0xffff0000, v40
	v_or_b32_sdwa v41, v44, v23 dst_sel:DWORD dst_unused:UNUSED_PAD src0_sel:DWORD src1_sel:WORD_1
	v_or_b32_sdwa v40, v43, v42 dst_sel:DWORD dst_unused:UNUSED_PAD src0_sel:WORD_1 src1_sel:DWORD
	ds_write_b64 v105, v[40:41]
	v_and_b32_e32 v40, 0xffff0000, v43
	v_sub_u32_e32 v6, v6, v42
	v_and_b32_e32 v23, 0xffff0000, v23
	v_sub_u32_e32 v2, v2, v40
	v_add_u32_e32 v6, 0x80, v6
	v_sub_u32_e32 v7, v7, v23
	v_sub_u32_e32 v3, v3, v44
	v_add_u32_e32 v2, 0x80, v2
	v_ashrrev_i32_e32 v6, 8, v6
	v_add_u32_e32 v7, 0x80, v7
	v_add_u32_e32 v3, 0x80, v3
	v_ashrrev_i32_e32 v2, 8, v2
	v_min_i32_e32 v6, 0x7f, v6
	v_ashrrev_i32_e32 v7, 8, v7
	v_ashrrev_i32_e32 v3, 8, v3
	v_min_i32_e32 v2, 0x7f, v2
	v_min_i32_sdwa v7, v7, s79 dst_sel:WORD_1 dst_unused:UNUSED_PAD src0_sel:DWORD src1_sel:DWORD
	v_min_i32_e32 v3, 0x7f, v3
	v_lshlrev_b32_e32 v6, 8, v6
	v_and_b32_e32 v6, 0xff00, v6
	v_and_b32_e32 v7, 0xff0000, v7
	v_perm_b32 v2, v3, v2, s80
	v_or3_b32 v2, v2, v6, v7
	ds_write_b32 v20, v2 offset:16
	buffer_store_dwordx4 v[168:171], v88, s[16:19], s33 offen
	ds_read_b64 v[2:3], v21 offset:1024
	s_waitcnt lgkmcnt(0)
	v_pk_add_f32 v[6:7], v[62:63], v[2:3] op_sel_hi:[1,0] neg_lo:[0,1] neg_hi:[0,1]
	s_nop 0
	v_pk_mul_f32 v[6:7], v[2:3], v[6:7] op_sel:[1,0]
	v_pk_add_f32 v[40:41], v[60:61], v[2:3] op_sel_hi:[1,0] neg_lo:[0,1] neg_hi:[0,1]
	v_pk_fma_f32 v[6:7], v[64:65], v[6:7], v[66:67]
	v_pk_mul_f32 v[2:3], v[2:3], v[40:41] op_sel:[1,0]
	s_nop 0
	v_pk_fma_f32 v[0:1], v[0:1], v[2:3], v[4:5]
	v_and_b32_sdwa v2, v7, v216 dst_sel:DWORD dst_unused:UNUSED_PAD src0_sel:WORD_1 src1_sel:DWORD
	v_and_b32_sdwa v3, v6, v216 dst_sel:DWORD dst_unused:UNUSED_PAD src0_sel:WORD_1 src1_sel:DWORD
	v_add3_u32 v4, v7, v2, s78
	v_add3_u32 v2, v6, v3, s78
	v_and_b32_e32 v5, 0xffff0000, v2
	v_and_b32_sdwa v2, v1, v216 dst_sel:DWORD dst_unused:UNUSED_PAD src0_sel:WORD_1 src1_sel:DWORD
	v_and_b32_sdwa v3, v0, v216 dst_sel:DWORD dst_unused:UNUSED_PAD src0_sel:WORD_1 src1_sel:DWORD
	v_add3_u32 v2, v1, v2, s78
	v_add3_u32 v23, v0, v3, s78
	v_and_b32_e32 v40, 0xffff0000, v2
	v_or_b32_sdwa v3, v40, v4 dst_sel:DWORD dst_unused:UNUSED_PAD src0_sel:DWORD src1_sel:WORD_1
	v_or_b32_sdwa v2, v23, v5 dst_sel:DWORD dst_unused:UNUSED_PAD src0_sel:WORD_1 src1_sel:DWORD
	ds_write_b64 v106, v[2:3]
	v_and_b32_e32 v2, 0xffff0000, v23
	v_sub_u32_e32 v0, v0, v2
	v_sub_u32_e32 v2, v6, v5
	v_and_b32_e32 v3, 0xffff0000, v4
	v_add_u32_e32 v2, 0x80, v2
	v_sub_u32_e32 v3, v7, v3
	v_sub_u32_e32 v1, v1, v40
	v_add_u32_e32 v0, 0x80, v0
	v_ashrrev_i32_e32 v2, 8, v2
	v_add_u32_e32 v3, 0x80, v3
	v_add_u32_e32 v1, 0x80, v1
	v_ashrrev_i32_e32 v0, 8, v0
	v_min_i32_e32 v2, 0x7f, v2
	v_ashrrev_i32_e32 v3, 8, v3
	v_ashrrev_i32_e32 v1, 8, v1
	v_min_i32_e32 v0, 0x7f, v0
	v_min_i32_sdwa v3, v3, s79 dst_sel:WORD_1 dst_unused:UNUSED_PAD src0_sel:DWORD src1_sel:DWORD
	v_min_i32_e32 v1, 0x7f, v1
	v_lshlrev_b32_e32 v2, 8, v2
	v_and_b32_e32 v2, 0xff00, v2
	v_and_b32_e32 v3, 0xff0000, v3
	v_perm_b32 v0, v1, v0, s80
	v_or3_b32 v0, v0, v2, v3
	ds_write_b32 v22, v0 offset:16
	buffer_store_dwordx4 v[172:175], v89, s[16:19], s33 offen
	v_mov_b32_e32 v0, v228
	v_mov_b32_e32 v1, v229
	v_mov_b32_e32 v2, v230
	v_mov_b32_e32 v3, v231
	v_mov_b32_e32 v4, v244
	v_mov_b32_e32 v5, v245
	v_mov_b32_e32 v6, v246
	v_mov_b32_e32 v7, v247
	ds_read_b64 v[44:45], v149 offset:1024
	s_waitcnt lgkmcnt(0)
	v_pk_add_f32 v[46:47], v[54:55], v[44:45] op_sel_hi:[1,0] neg_lo:[0,1] neg_hi:[0,1]
	s_nop 0
	v_pk_mul_f32 v[46:47], v[44:45], v[46:47] op_sel:[1,0]
	v_pk_add_f32 v[52:53], v[52:53], v[44:45] op_sel_hi:[1,0] neg_lo:[0,1] neg_hi:[0,1]
	v_mov_b32_e32 v40, v1
	v_mov_b32_e32 v41, v2
	v_mov_b32_e32 v42, v5
	v_mov_b32_e32 v43, v6
	v_pk_fma_f32 v[46:47], v[40:41], v[46:47], v[42:43]
	v_pk_mul_f32 v[44:45], v[44:45], v[52:53] op_sel:[1,0]
	v_mov_b32_e32 v1, v3
	v_mov_b32_e32 v5, v7
	v_and_b32_sdwa v6, v47, v216 dst_sel:DWORD dst_unused:UNUSED_PAD src0_sel:WORD_1 src1_sel:DWORD
	v_and_b32_sdwa v7, v46, v216 dst_sel:DWORD dst_unused:UNUSED_PAD src0_sel:WORD_1 src1_sel:DWORD
	v_pk_fma_f32 v[2:3], v[0:1], v[44:45], v[4:5]
	v_add3_u32 v23, v47, v6, s78
	v_add3_u32 v6, v46, v7, s78
	v_and_b32_e32 v44, 0xffff0000, v6
	v_and_b32_sdwa v6, v3, v216 dst_sel:DWORD dst_unused:UNUSED_PAD src0_sel:WORD_1 src1_sel:DWORD
	v_and_b32_sdwa v7, v2, v216 dst_sel:DWORD dst_unused:UNUSED_PAD src0_sel:WORD_1 src1_sel:DWORD
	v_add3_u32 v6, v3, v6, s78
	v_add3_u32 v45, v2, v7, s78
	v_and_b32_e32 v52, 0xffff0000, v6
	v_or_b32_sdwa v7, v52, v23 dst_sel:DWORD dst_unused:UNUSED_PAD src0_sel:DWORD src1_sel:WORD_1
	v_or_b32_sdwa v6, v45, v44 dst_sel:DWORD dst_unused:UNUSED_PAD src0_sel:WORD_1 src1_sel:DWORD
	ds_write_b64 v107, v[6:7]
	v_and_b32_e32 v6, 0xffff0000, v45
	v_sub_u32_e32 v2, v2, v6
	v_sub_u32_e32 v6, v46, v44
	v_and_b32_e32 v7, 0xffff0000, v23
	v_add_u32_e32 v6, 0x80, v6
	v_sub_u32_e32 v7, v47, v7
	v_sub_u32_e32 v3, v3, v52
	v_add_u32_e32 v2, 0x80, v2
	v_ashrrev_i32_e32 v6, 8, v6
	v_add_u32_e32 v7, 0x80, v7
	v_add_u32_e32 v3, 0x80, v3
	v_ashrrev_i32_e32 v2, 8, v2
	v_min_i32_e32 v6, 0x7f, v6
	v_ashrrev_i32_e32 v7, 8, v7
	v_ashrrev_i32_e32 v3, 8, v3
	v_min_i32_e32 v2, 0x7f, v2
	v_min_i32_sdwa v7, v7, s79 dst_sel:WORD_1 dst_unused:UNUSED_PAD src0_sel:DWORD src1_sel:DWORD
	v_min_i32_e32 v3, 0x7f, v3
	v_lshlrev_b32_e32 v6, 8, v6
	v_and_b32_e32 v6, 0xff00, v6
	v_and_b32_e32 v7, 0xff0000, v7
	v_perm_b32 v2, v3, v2, s80
	v_or3_b32 v2, v2, v6, v7
	ds_write_b32 v12, v2 offset:128
	buffer_store_dwordx4 v[176:179], v146, s[20:23], s0 offen
	ds_read_b64 v[2:3], v13 offset:1024
	s_waitcnt lgkmcnt(0)
;     ...
;           _Pragma("unroll") for (int bj = 0; bj < 2; ++bj) _Pragma("unroll") for (int n = 0; n < 2; ++n) {
;             const int cc = bj * HALF + wc3 * 32 + n * 16 + fq3 * 4;
;             const float4 gm = *reinterpret_cast<const float4*>(g.gam + pn * BM + cc), bt = *reinterpret_cast<const float4*>(g.bet + pn * BM + cc);
;             _Pragma("unroll") for (int m = 0; m < 4; ++m) {
;               const int rr = wr3 * 64 + m * 16 + fr3;
;               const float2 ms = *reinterpret_cast<const float2*>(mr + (ai * HALF + rr) * 2);
;               f32x4 y = acc[ai][bj][m][n];
;               const float o0 = (y[0] - ms.x) * ms.y * gm.x + bt.x, o1 = (y[1] - ms.x) * ms.y * gm.y + bt.y;
;               const float o2 = (y[2] - ms.x) * ms.y * gm.z + bt.z, o3 = (y[3] - ms.x) * ms.y * gm.w + bt.w;
;               const unsigned h0 = f2bf(o0), h1 = f2bf(o1), h2 = f2bf(o2), h3 = f2bf(o3);
;               u32x2 ob; ob[0] = h0 | (h1 << 16); ob[1] = h2 | (h3 << 16);
;               *reinterpret_cast<u32x2*>(smem + (rr >> 1) * PIECE + (rr & 1) * 512 + cc * 2) = ob;
;               const int l0 = min(((int)__float_as_uint(o0) - (int)(h0 << 16) + 128) >> 8, 127);
;               const int l1 = min(((int)__float_as_uint(o1) - (int)(h1 << 16) + 128) >> 8, 127);
;               const int l2 = min(((int)__float_as_uint(o2) - (int)(h2 << 16) + 128) >> 8, 127);
;               const int l3 = min(((int)__float_as_uint(o3) - (int)(h3 << 16) + 128) >> 8, 127);
;               *reinterpret_cast<unsigned*>(smem + LOBASE + (rr >> 2) * PIECE + (rr & 3) * 256 + cc) =
;                   (unsigned)(l0 & 255) | ((unsigned)(l1 & 255) << 8) | ((unsigned)(l2 & 255) << 16) | ((unsigned)l3 << 24);
;             }
;           }
;           WAIT_L(0); BAR;
;           const int hso = ((brow + ai * HALF + 16 * wave) * DM + pn * BM) * 2;
;           const int lso = (brow + ai * HALF + 16 * wave) * DM + pn * BM;
;           _Pragma("unroll") for (int i = 0; i < 8; ++i) {
;             const u32x4 v = *reinterpret_cast<const u32x4*>(smem + (wave * 8 + i) * PIECE + lane3 * 16);
;             __builtin_amdgcn_raw_buffer_store_b128(v, rsXB, hvo + i * (2 * DM * 2), hso, 0);
;           }
;           _Pragma("unroll") for (int i = 0; i < 4; ++i) {
;             const u32x4 v = *reinterpret_cast<const u32x4*>(smem + LOBASE + (wave * 4 + i) * PIECE + lane3 * 16);
	v_pk_add_f32 v[6:7], v[38:39], v[2:3] op_sel_hi:[1,0] neg_lo:[0,1] neg_hi:[0,1]
	s_nop 0
	v_pk_mul_f32 v[6:7], v[2:3], v[6:7] op_sel:[1,0]
	v_pk_add_f32 v[36:37], v[36:37], v[2:3] op_sel_hi:[1,0] neg_lo:[0,1] neg_hi:[0,1]
	v_pk_fma_f32 v[6:7], v[40:41], v[6:7], v[42:43]
	v_pk_mul_f32 v[2:3], v[2:3], v[36:37] op_sel:[1,0]
	v_and_b32_sdwa v36, v6, v216 dst_sel:DWORD dst_unused:UNUSED_PAD src0_sel:WORD_1 src1_sel:DWORD
	v_pk_fma_f32 v[2:3], v[0:1], v[2:3], v[4:5]
	v_add3_u32 v36, v6, v36, s78
	v_and_b32_e32 v38, 0xffff0000, v36
	v_and_b32_sdwa v36, v3, v216 dst_sel:DWORD dst_unused:UNUSED_PAD src0_sel:WORD_1 src1_sel:DWORD
	v_and_b32_sdwa v23, v7, v216 dst_sel:DWORD dst_unused:UNUSED_PAD src0_sel:WORD_1 src1_sel:DWORD
	v_and_b32_sdwa v37, v2, v216 dst_sel:DWORD dst_unused:UNUSED_PAD src0_sel:WORD_1 src1_sel:DWORD
	v_add3_u32 v36, v3, v36, s78
	v_add3_u32 v23, v7, v23, s78
	v_add3_u32 v39, v2, v37, s78
	v_and_b32_e32 v44, 0xffff0000, v36
	v_or_b32_sdwa v37, v44, v23 dst_sel:DWORD dst_unused:UNUSED_PAD src0_sel:DWORD src1_sel:WORD_1
	v_or_b32_sdwa v36, v39, v38 dst_sel:DWORD dst_unused:UNUSED_PAD src0_sel:WORD_1 src1_sel:DWORD
	ds_write_b64 v100, v[36:37]
	v_and_b32_e32 v36, 0xffff0000, v39
	v_sub_u32_e32 v6, v6, v38
	v_and_b32_e32 v23, 0xffff0000, v23
	v_sub_u32_e32 v2, v2, v36
	v_add_u32_e32 v6, 0x80, v6
	v_sub_u32_e32 v7, v7, v23
	v_sub_u32_e32 v3, v3, v44
	v_add_u32_e32 v2, 0x80, v2
	v_ashrrev_i32_e32 v6, 8, v6
	v_add_u32_e32 v7, 0x80, v7
	v_add_u32_e32 v3, 0x80, v3
	v_ashrrev_i32_e32 v2, 8, v2
	v_min_i32_e32 v6, 0x7f, v6
	v_ashrrev_i32_e32 v7, 8, v7
	v_ashrrev_i32_e32 v3, 8, v3
	v_min_i32_e32 v2, 0x7f, v2
	v_min_i32_sdwa v7, v7, s79 dst_sel:WORD_1 dst_unused:UNUSED_PAD src0_sel:DWORD src1_sel:DWORD
	v_min_i32_e32 v3, 0x7f, v3
	v_lshlrev_b32_e32 v6, 8, v6
	v_and_b32_e32 v6, 0xff00, v6
	v_and_b32_e32 v7, 0xff0000, v7
	v_perm_b32 v2, v3, v2, s80
	v_or3_b32 v2, v2, v6, v7
	ds_write_b32 v14, v2 offset:128
	buffer_store_dwordx4 v[180:183], v90, s[20:23], s0 offen
	ds_read_b64 v[2:3], v15 offset:1024
	s_waitcnt lgkmcnt(0)
	v_pk_add_f32 v[6:7], v[26:27], v[2:3] op_sel_hi:[1,0] neg_lo:[0,1] neg_hi:[0,1]
	s_nop 0
	v_pk_mul_f32 v[6:7], v[2:3], v[6:7] op_sel:[1,0]
	v_pk_add_f32 v[24:25], v[24:25], v[2:3] op_sel_hi:[1,0] neg_lo:[0,1] neg_hi:[0,1]
	v_pk_fma_f32 v[6:7], v[40:41], v[6:7], v[42:43]
	v_pk_mul_f32 v[2:3], v[2:3], v[24:25] op_sel:[1,0]
	v_and_b32_sdwa v24, v6, v216 dst_sel:DWORD dst_unused:UNUSED_PAD src0_sel:WORD_1 src1_sel:DWORD
	v_pk_fma_f32 v[2:3], v[0:1], v[2:3], v[4:5]
	v_add3_u32 v24, v6, v24, s78
	v_and_b32_e32 v26, 0xffff0000, v24
	v_and_b32_sdwa v24, v3, v216 dst_sel:DWORD dst_unused:UNUSED_PAD src0_sel:WORD_1 src1_sel:DWORD
	v_and_b32_sdwa v23, v7, v216 dst_sel:DWORD dst_unused:UNUSED_PAD src0_sel:WORD_1 src1_sel:DWORD
	v_and_b32_sdwa v25, v2, v216 dst_sel:DWORD dst_unused:UNUSED_PAD src0_sel:WORD_1 src1_sel:DWORD
	v_add3_u32 v24, v3, v24, s78
	v_add3_u32 v23, v7, v23, s78
	v_add3_u32 v27, v2, v25, s78
	v_and_b32_e32 v36, 0xffff0000, v24
	v_or_b32_sdwa v25, v36, v23 dst_sel:DWORD dst_unused:UNUSED_PAD src0_sel:DWORD src1_sel:WORD_1
	v_or_b32_sdwa v24, v27, v26 dst_sel:DWORD dst_unused:UNUSED_PAD src0_sel:WORD_1 src1_sel:DWORD
	ds_write_b64 v101, v[24:25]
	v_and_b32_e32 v24, 0xffff0000, v27
	v_sub_u32_e32 v6, v6, v26
	v_and_b32_e32 v23, 0xffff0000, v23
	v_sub_u32_e32 v2, v2, v24
	v_add_u32_e32 v6, 0x80, v6
	v_sub_u32_e32 v7, v7, v23
	v_sub_u32_e32 v3, v3, v36
	v_add_u32_e32 v2, 0x80, v2
	v_ashrrev_i32_e32 v6, 8, v6
	v_add_u32_e32 v7, 0x80, v7
	v_add_u32_e32 v3, 0x80, v3
	v_ashrrev_i32_e32 v2, 8, v2
	v_min_i32_e32 v6, 0x7f, v6
	v_ashrrev_i32_e32 v7, 8, v7
	v_ashrrev_i32_e32 v3, 8, v3
	v_min_i32_e32 v2, 0x7f, v2
	v_min_i32_sdwa v7, v7, s79 dst_sel:WORD_1 dst_unused:UNUSED_PAD src0_sel:DWORD src1_sel:DWORD
	v_min_i32_e32 v3, 0x7f, v3
	v_lshlrev_b32_e32 v6, 8, v6
	v_and_b32_e32 v6, 0xff00, v6
	v_and_b32_e32 v7, 0xff0000, v7
	v_perm_b32 v2, v3, v2, s80
	v_or3_b32 v2, v2, v6, v7
	ds_write_b32 v20, v2 offset:128
	buffer_store_dwordx4 v[184:187], v91, s[20:23], s0 offen
	ds_read_b64 v[2:3], v21 offset:1024
	s_waitcnt lgkmcnt(0)
	v_pk_add_f32 v[6:7], v[30:31], v[2:3] op_sel_hi:[1,0] neg_lo:[0,1] neg_hi:[0,1]
	s_nop 0
	v_pk_mul_f32 v[6:7], v[2:3], v[6:7] op_sel:[1,0]
	v_pk_add_f32 v[24:25], v[28:29], v[2:3] op_sel_hi:[1,0] neg_lo:[0,1] neg_hi:[0,1]
	v_pk_fma_f32 v[6:7], v[40:41], v[6:7], v[42:43]
	v_pk_mul_f32 v[2:3], v[2:3], v[24:25] op_sel:[1,0]
	s_nop 0
	v_pk_fma_f32 v[0:1], v[0:1], v[2:3], v[4:5]
	v_and_b32_sdwa v2, v7, v216 dst_sel:DWORD dst_unused:UNUSED_PAD src0_sel:WORD_1 src1_sel:DWORD
	v_and_b32_sdwa v3, v6, v216 dst_sel:DWORD dst_unused:UNUSED_PAD src0_sel:WORD_1 src1_sel:DWORD
	v_add3_u32 v4, v7, v2, s78
	v_add3_u32 v2, v6, v3, s78
	v_and_b32_e32 v5, 0xffff0000, v2
	v_and_b32_sdwa v2, v1, v216 dst_sel:DWORD dst_unused:UNUSED_PAD src0_sel:WORD_1 src1_sel:DWORD
	v_and_b32_sdwa v3, v0, v216 dst_sel:DWORD dst_unused:UNUSED_PAD src0_sel:WORD_1 src1_sel:DWORD
	v_add3_u32 v2, v1, v2, s78
	v_add3_u32 v23, v0, v3, s78
	v_and_b32_e32 v24, 0xffff0000, v2
	v_or_b32_sdwa v3, v24, v4 dst_sel:DWORD dst_unused:UNUSED_PAD src0_sel:DWORD src1_sel:WORD_1
	v_or_b32_sdwa v2, v23, v5 dst_sel:DWORD dst_unused:UNUSED_PAD src0_sel:WORD_1 src1_sel:DWORD
	ds_write_b64 v92, v[2:3]
	v_and_b32_e32 v2, 0xffff0000, v23
	v_sub_u32_e32 v0, v0, v2
	v_sub_u32_e32 v2, v6, v5
	v_and_b32_e32 v3, 0xffff0000, v4
	v_add_u32_e32 v2, 0x80, v2
	v_sub_u32_e32 v3, v7, v3
	v_sub_u32_e32 v1, v1, v24
	v_add_u32_e32 v0, 0x80, v0
	v_ashrrev_i32_e32 v2, 8, v2
	v_add_u32_e32 v3, 0x80, v3
	v_add_u32_e32 v1, 0x80, v1
	v_ashrrev_i32_e32 v0, 8, v0
	v_min_i32_e32 v2, 0x7f, v2
	v_ashrrev_i32_e32 v3, 8, v3
	v_ashrrev_i32_e32 v1, 8, v1
	v_min_i32_e32 v0, 0x7f, v0
	v_min_i32_sdwa v3, v3, s79 dst_sel:WORD_1 dst_unused:UNUSED_PAD src0_sel:DWORD src1_sel:DWORD
	v_min_i32_e32 v1, 0x7f, v1
	v_lshlrev_b32_e32 v2, 8, v2
	v_and_b32_e32 v2, 0xff00, v2
	v_and_b32_e32 v3, 0xff0000, v3
	v_perm_b32 v0, v1, v0, s80
	v_or3_b32 v0, v0, v2, v3
	ds_write_b32 v22, v0 offset:128
	buffer_store_dwordx4 v[188:191], v95, s[20:23], s0 offen
	v_mov_b32_e32 v0, v232
	v_mov_b32_e32 v1, v233
	v_mov_b32_e32 v2, v234
	v_mov_b32_e32 v3, v235
	v_mov_b32_e32 v4, v248
	v_mov_b32_e32 v5, v249
	v_mov_b32_e32 v6, v250
	v_mov_b32_e32 v7, v251
	ds_read_b64 v[28:29], v149 offset:1024
	s_mov_b64 s[4:5], -1
	s_waitcnt lgkmcnt(0)
;     ...
;             _Pragma("unroll") for (int m = 0; m < 4; ++m) {
;               const int rr = wr3 * 64 + m * 16 + fr3;
;               const float2 ms = *reinterpret_cast<const float2*>(mr + (ai * HALF + rr) * 2);
;               f32x4 y = acc[ai][bj][m][n];
;               const float o0 = (y[0] - ms.x) * ms.y * gm.x + bt.x, o1 = (y[1] - ms.x) * ms.y * gm.y + bt.y;
;               const float o2 = (y[2] - ms.x) * ms.y * gm.z + bt.z, o3 = (y[3] - ms.x) * ms.y * gm.w + bt.w;
;               const unsigned h0 = f2bf(o0), h1 = f2bf(o1), h2 = f2bf(o2), h3 = f2bf(o3);
;               u32x2 ob; ob[0] = h0 | (h1 << 16); ob[1] = h2 | (h3 << 16);
;               *reinterpret_cast<u32x2*>(smem + (rr >> 1) * PIECE + (rr & 1) * 512 + cc * 2) = ob;
;               const int l0 = min(((int)__float_as_uint(o0) - (int)(h0 << 16) + 128) >> 8, 127);
;               const int l1 = min(((int)__float_as_uint(o1) - (int)(h1 << 16) + 128) >> 8, 127);
;               const int l2 = min(((int)__float_as_uint(o2) - (int)(h2 << 16) + 128) >> 8, 127);
;               const int l3 = min(((int)__float_as_uint(o3) - (int)(h3 << 16) + 128) >> 8, 127);
;               *reinterpret_cast<unsigned*>(smem + LOBASE + (rr >> 2) * PIECE + (rr & 3) * 256 + cc) =
;                   (unsigned)(l0 & 255) | ((unsigned)(l1 & 255) << 8) | ((unsigned)(l2 & 255) << 16) | ((unsigned)l3 << 24);
;             }
	v_pk_add_f32 v[30:31], v[50:51], v[28:29] op_sel_hi:[1,0] neg_lo:[0,1] neg_hi:[0,1]
	s_nop 0
	v_pk_mul_f32 v[30:31], v[28:29], v[30:31] op_sel:[1,0]
	v_pk_add_f32 v[36:37], v[48:49], v[28:29] op_sel_hi:[1,0] neg_lo:[0,1] neg_hi:[0,1]
	v_mov_b32_e32 v24, v1
	v_mov_b32_e32 v25, v2
	v_mov_b32_e32 v26, v5
	v_mov_b32_e32 v27, v6
	v_pk_fma_f32 v[30:31], v[24:25], v[30:31], v[26:27]
	v_pk_mul_f32 v[28:29], v[28:29], v[36:37] op_sel:[1,0]
	v_mov_b32_e32 v1, v3
	v_mov_b32_e32 v5, v7
	v_and_b32_sdwa v6, v31, v216 dst_sel:DWORD dst_unused:UNUSED_PAD src0_sel:WORD_1 src1_sel:DWORD
	v_and_b32_sdwa v7, v30, v216 dst_sel:DWORD dst_unused:UNUSED_PAD src0_sel:WORD_1 src1_sel:DWORD
	v_pk_fma_f32 v[2:3], v[0:1], v[28:29], v[4:5]
	v_add3_u32 v23, v31, v6, s78
	v_add3_u32 v6, v30, v7, s78
	v_and_b32_e32 v28, 0xffff0000, v6
	v_and_b32_sdwa v6, v3, v216 dst_sel:DWORD dst_unused:UNUSED_PAD src0_sel:WORD_1 src1_sel:DWORD
	v_and_b32_sdwa v7, v2, v216 dst_sel:DWORD dst_unused:UNUSED_PAD src0_sel:WORD_1 src1_sel:DWORD
	v_add3_u32 v6, v3, v6, s78
	v_add3_u32 v29, v2, v7, s78
	v_and_b32_e32 v36, 0xffff0000, v6
	v_or_b32_sdwa v7, v36, v23 dst_sel:DWORD dst_unused:UNUSED_PAD src0_sel:DWORD src1_sel:WORD_1
	v_or_b32_sdwa v6, v29, v28 dst_sel:DWORD dst_unused:UNUSED_PAD src0_sel:WORD_1 src1_sel:DWORD
	ds_write_b64 v93, v[6:7]
	v_and_b32_e32 v6, 0xffff0000, v29
	v_sub_u32_e32 v2, v2, v6
	v_sub_u32_e32 v6, v30, v28
	v_and_b32_e32 v7, 0xffff0000, v23
	v_add_u32_e32 v6, 0x80, v6
	v_sub_u32_e32 v7, v31, v7
	v_sub_u32_e32 v3, v3, v36
	v_add_u32_e32 v2, 0x80, v2
	v_ashrrev_i32_e32 v6, 8, v6
	v_add_u32_e32 v7, 0x80, v7
	v_add_u32_e32 v3, 0x80, v3
	v_ashrrev_i32_e32 v2, 8, v2
	v_min_i32_e32 v6, 0x7f, v6
	v_ashrrev_i32_e32 v7, 8, v7
	v_ashrrev_i32_e32 v3, 8, v3
	v_min_i32_e32 v2, 0x7f, v2
	v_min_i32_sdwa v7, v7, s79 dst_sel:WORD_1 dst_unused:UNUSED_PAD src0_sel:DWORD src1_sel:DWORD
	v_min_i32_e32 v3, 0x7f, v3
	v_lshlrev_b32_e32 v6, 8, v6
	v_and_b32_e32 v6, 0xff00, v6
	v_and_b32_e32 v7, 0xff0000, v7
	v_perm_b32 v2, v3, v2, s80
	v_or3_b32 v2, v2, v6, v7
	ds_write_b32 v12, v2 offset:144
	ds_read_b64 v[2:3], v13 offset:1024
	s_waitcnt lgkmcnt(0)
	v_pk_add_f32 v[6:7], v[34:35], v[2:3] op_sel_hi:[1,0] neg_lo:[0,1] neg_hi:[0,1]
	s_nop 0
	v_pk_mul_f32 v[6:7], v[2:3], v[6:7] op_sel:[1,0]
	v_pk_add_f32 v[12:13], v[32:33], v[2:3] op_sel_hi:[1,0] neg_lo:[0,1] neg_hi:[0,1]
	v_pk_fma_f32 v[6:7], v[24:25], v[6:7], v[26:27]
	v_pk_mul_f32 v[2:3], v[2:3], v[12:13] op_sel:[1,0]
	v_and_b32_sdwa v12, v7, v216 dst_sel:DWORD dst_unused:UNUSED_PAD src0_sel:WORD_1 src1_sel:DWORD
	v_and_b32_sdwa v13, v6, v216 dst_sel:DWORD dst_unused:UNUSED_PAD src0_sel:WORD_1 src1_sel:DWORD
	v_pk_fma_f32 v[2:3], v[0:1], v[2:3], v[4:5]
	v_add3_u32 v23, v7, v12, s78
	v_add3_u32 v12, v6, v13, s78
	v_and_b32_e32 v28, 0xffff0000, v12
	v_and_b32_sdwa v12, v3, v216 dst_sel:DWORD dst_unused:UNUSED_PAD src0_sel:WORD_1 src1_sel:DWORD
	v_and_b32_sdwa v13, v2, v216 dst_sel:DWORD dst_unused:UNUSED_PAD src0_sel:WORD_1 src1_sel:DWORD
	v_add3_u32 v12, v3, v12, s78
	v_add3_u32 v29, v2, v13, s78
	v_and_b32_e32 v30, 0xffff0000, v12
	v_or_b32_sdwa v13, v30, v23 dst_sel:DWORD dst_unused:UNUSED_PAD src0_sel:DWORD src1_sel:WORD_1
	v_or_b32_sdwa v12, v29, v28 dst_sel:DWORD dst_unused:UNUSED_PAD src0_sel:WORD_1 src1_sel:DWORD
	ds_write_b64 v94, v[12:13]
	v_and_b32_e32 v12, 0xffff0000, v29
	v_sub_u32_e32 v2, v2, v12
	v_sub_u32_e32 v6, v6, v28
	v_and_b32_e32 v12, 0xffff0000, v23
	v_add_u32_e32 v6, 0x80, v6
	v_sub_u32_e32 v7, v7, v12
	v_sub_u32_e32 v3, v3, v30
	v_add_u32_e32 v2, 0x80, v2
	v_ashrrev_i32_e32 v6, 8, v6
	v_add_u32_e32 v7, 0x80, v7
	v_add_u32_e32 v3, 0x80, v3
	v_ashrrev_i32_e32 v2, 8, v2
	v_min_i32_e32 v6, 0x7f, v6
	v_ashrrev_i32_e32 v7, 8, v7
	v_ashrrev_i32_e32 v3, 8, v3
	v_min_i32_e32 v2, 0x7f, v2
	v_min_i32_sdwa v7, v7, s79 dst_sel:WORD_1 dst_unused:UNUSED_PAD src0_sel:DWORD src1_sel:DWORD
	v_min_i32_e32 v3, 0x7f, v3
	v_lshlrev_b32_e32 v6, 8, v6
	v_and_b32_e32 v6, 0xff00, v6
	v_and_b32_e32 v7, 0xff0000, v7
	v_perm_b32 v2, v3, v2, s80
	v_or3_b32 v2, v2, v6, v7
	ds_write_b32 v14, v2 offset:144
	ds_read_b64 v[2:3], v15 offset:1024
	s_waitcnt lgkmcnt(0)
	v_pk_add_f32 v[6:7], v[18:19], v[2:3] op_sel_hi:[1,0] neg_lo:[0,1] neg_hi:[0,1]
	s_nop 0
	v_pk_mul_f32 v[6:7], v[2:3], v[6:7] op_sel:[1,0]
	v_pk_add_f32 v[12:13], v[16:17], v[2:3] op_sel_hi:[1,0] neg_lo:[0,1] neg_hi:[0,1]
	v_pk_fma_f32 v[6:7], v[24:25], v[6:7], v[26:27]
	v_pk_mul_f32 v[2:3], v[2:3], v[12:13] op_sel:[1,0]
	v_and_b32_sdwa v12, v7, v216 dst_sel:DWORD dst_unused:UNUSED_PAD src0_sel:WORD_1 src1_sel:DWORD
	v_and_b32_sdwa v13, v6, v216 dst_sel:DWORD dst_unused:UNUSED_PAD src0_sel:WORD_1 src1_sel:DWORD
	v_pk_fma_f32 v[2:3], v[0:1], v[2:3], v[4:5]
	v_add3_u32 v14, v7, v12, s78
	v_add3_u32 v12, v6, v13, s78
	v_and_b32_e32 v15, 0xffff0000, v12
	v_and_b32_sdwa v12, v3, v216 dst_sel:DWORD dst_unused:UNUSED_PAD src0_sel:WORD_1 src1_sel:DWORD
	v_and_b32_sdwa v13, v2, v216 dst_sel:DWORD dst_unused:UNUSED_PAD src0_sel:WORD_1 src1_sel:DWORD
	v_add3_u32 v12, v3, v12, s78
	v_add3_u32 v16, v2, v13, s78
	v_and_b32_e32 v17, 0xffff0000, v12
	v_or_b32_sdwa v13, v17, v14 dst_sel:DWORD dst_unused:UNUSED_PAD src0_sel:DWORD src1_sel:WORD_1
	v_or_b32_sdwa v12, v16, v15 dst_sel:DWORD dst_unused:UNUSED_PAD src0_sel:WORD_1 src1_sel:DWORD
	ds_write_b64 v80, v[12:13]
	v_and_b32_e32 v12, 0xffff0000, v16
	v_sub_u32_e32 v2, v2, v12
	v_sub_u32_e32 v6, v6, v15
	v_and_b32_e32 v12, 0xffff0000, v14
	v_add_u32_e32 v6, 0x80, v6
	v_sub_u32_e32 v7, v7, v12
	v_sub_u32_e32 v3, v3, v17
	v_add_u32_e32 v2, 0x80, v2
	v_ashrrev_i32_e32 v6, 8, v6
	v_add_u32_e32 v7, 0x80, v7
	v_add_u32_e32 v3, 0x80, v3
	v_ashrrev_i32_e32 v2, 8, v2
	v_min_i32_e32 v6, 0x7f, v6
	v_ashrrev_i32_e32 v7, 8, v7
	v_ashrrev_i32_e32 v3, 8, v3
	v_min_i32_e32 v2, 0x7f, v2
	v_min_i32_sdwa v7, v7, s79 dst_sel:WORD_1 dst_unused:UNUSED_PAD src0_sel:DWORD src1_sel:DWORD
	v_min_i32_e32 v3, 0x7f, v3
	v_lshlrev_b32_e32 v6, 8, v6
	v_and_b32_e32 v6, 0xff00, v6
	v_and_b32_e32 v7, 0xff0000, v7
	v_perm_b32 v2, v3, v2, s80
	v_or3_b32 v2, v2, v6, v7
	ds_write_b32 v20, v2 offset:144
	ds_read_b64 v[2:3], v21 offset:1024
	s_waitcnt lgkmcnt(0)
;     ...
;   auto issue_prologue = [&](int sA0, int sA1, int sB0, int sB1) {
;     const int tid = opaque_tid(wave);
;     int offA[2], offB[2];
;     _Pragma("unroll") for (int i = 0; i < 2; ++i) {
;       int r, c; stage_rc(tid * 16 + i * 8192, r, c);
;       offA[i] = (r * lda + c) * 2; offB[i] = (r * ldb + c) * 2;
;     }
;     STAGE(SB(0, 0), rsB, sB0, offB, 0); STAGE(SA(0, 0), rsA, sA0, offA, 0);
;     STAGE(SB(0, 1), rsB, sB1, offB, 0); STAGE(SA(0, 1), rsA, sA1, offA, 0);
;     ...
;               const float o0 = (y[0] - ms.x) * ms.y * gm.x + bt.x, o1 = (y[1] - ms.x) * ms.y * gm.y + bt.y;
;               const float o2 = (y[2] - ms.x) * ms.y * gm.z + bt.z, o3 = (y[3] - ms.x) * ms.y * gm.w + bt.w;
;               const unsigned h0 = f2bf(o0), h1 = f2bf(o1), h2 = f2bf(o2), h3 = f2bf(o3);
;               u32x2 ob; ob[0] = h0 | (h1 << 16); ob[1] = h2 | (h3 << 16);
;               *reinterpret_cast<u32x2*>(smem + (rr >> 1) * PIECE + (rr & 1) * 512 + cc * 2) = ob;
;               const int l0 = min(((int)__float_as_uint(o0) - (int)(h0 << 16) + 128) >> 8, 127);
;               const int l1 = min(((int)__float_as_uint(o1) - (int)(h1 << 16) + 128) >> 8, 127);
;               const int l2 = min(((int)__float_as_uint(o2) - (int)(h2 << 16) + 128) >> 8, 127);
;               const int l3 = min(((int)__float_as_uint(o3) - (int)(h3 << 16) + 128) >> 8, 127);
;               *reinterpret_cast<unsigned*>(smem + LOBASE + (rr >> 2) * PIECE + (rr & 3) * 256 + cc) =
;                   (unsigned)(l0 & 255) | ((unsigned)(l1 & 255) << 8) | ((unsigned)(l2 & 255) << 16) | ((unsigned)l3 << 24);
;             }
;           }
;           WAIT_L(0); BAR;
;           const int hso = ((brow + ai * HALF + 16 * wave) * DM + pn * BM) * 2;
;           const int lso = (brow + ai * HALF + 16 * wave) * DM + pn * BM;
;           _Pragma("unroll") for (int i = 0; i < 8; ++i) {
;             const u32x4 v = *reinterpret_cast<const u32x4*>(smem + (wave * 8 + i) * PIECE + lane3 * 16);
;             __builtin_amdgcn_raw_buffer_store_b128(v, rsXB, hvo + i * (2 * DM * 2), hso, 0);
;           }
;           _Pragma("unroll") for (int i = 0; i < 4; ++i) {
;             const u32x4 v = *reinterpret_cast<const u32x4*>(smem + LOBASE + (wave * 4 + i) * PIECE + lane3 * 16);
;             __builtin_amdgcn_raw_buffer_store_b128(v, rsLO, lvo + i * (4 * DM), lso, 0);
;           }
;           WAIT_L(0); BAR;
	v_pk_add_f32 v[6:7], v[10:11], v[2:3] op_sel_hi:[1,0] neg_lo:[0,1] neg_hi:[0,1]
	s_nop 0
	v_pk_mul_f32 v[6:7], v[2:3], v[6:7] op_sel:[1,0]
	v_pk_add_f32 v[8:9], v[8:9], v[2:3] op_sel_hi:[1,0] neg_lo:[0,1] neg_hi:[0,1]
	v_pk_fma_f32 v[6:7], v[24:25], v[6:7], v[26:27]
	v_pk_mul_f32 v[2:3], v[2:3], v[8:9] op_sel:[1,0]
	s_nop 0
	v_pk_fma_f32 v[0:1], v[0:1], v[2:3], v[4:5]
	v_and_b32_sdwa v2, v7, v216 dst_sel:DWORD dst_unused:UNUSED_PAD src0_sel:WORD_1 src1_sel:DWORD
	v_and_b32_sdwa v3, v6, v216 dst_sel:DWORD dst_unused:UNUSED_PAD src0_sel:WORD_1 src1_sel:DWORD
	v_add3_u32 v4, v7, v2, s78
	v_add3_u32 v2, v6, v3, s78
	v_and_b32_e32 v5, 0xffff0000, v2
	v_and_b32_sdwa v2, v1, v216 dst_sel:DWORD dst_unused:UNUSED_PAD src0_sel:WORD_1 src1_sel:DWORD
	v_and_b32_sdwa v3, v0, v216 dst_sel:DWORD dst_unused:UNUSED_PAD src0_sel:WORD_1 src1_sel:DWORD
	v_add3_u32 v2, v1, v2, s78
	v_add3_u32 v8, v0, v3, s78
	v_and_b32_e32 v9, 0xffff0000, v2
	v_or_b32_sdwa v3, v9, v4 dst_sel:DWORD dst_unused:UNUSED_PAD src0_sel:DWORD src1_sel:WORD_1
	v_or_b32_sdwa v2, v8, v5 dst_sel:DWORD dst_unused:UNUSED_PAD src0_sel:WORD_1 src1_sel:DWORD
	ds_write_b64 v73, v[2:3]
	v_and_b32_e32 v2, 0xffff0000, v8
	v_sub_u32_e32 v0, v0, v2
	v_sub_u32_e32 v2, v6, v5
	v_and_b32_e32 v3, 0xffff0000, v4
	v_add_u32_e32 v2, 0x80, v2
	v_sub_u32_e32 v3, v7, v3
	v_sub_u32_e32 v1, v1, v9
	v_add_u32_e32 v0, 0x80, v0
	v_ashrrev_i32_e32 v2, 8, v2
	v_add_u32_e32 v3, 0x80, v3
	v_add_u32_e32 v1, 0x80, v1
	v_ashrrev_i32_e32 v0, 8, v0
	v_min_i32_e32 v2, 0x7f, v2
	v_ashrrev_i32_e32 v3, 8, v3
	v_ashrrev_i32_e32 v1, 8, v1
	v_min_i32_e32 v0, 0x7f, v0
	v_min_i32_sdwa v3, v3, s79 dst_sel:WORD_1 dst_unused:UNUSED_PAD src0_sel:DWORD src1_sel:DWORD
	v_min_i32_e32 v1, 0x7f, v1
	v_lshlrev_b32_e32 v2, 8, v2
	v_and_b32_e32 v2, 0xff00, v2
	v_and_b32_e32 v3, 0xff0000, v3
	v_perm_b32 v0, v1, v0, s80
	v_or3_b32 v0, v0, v2, v3
	ds_write_b32 v22, v0 offset:144
	s_waitcnt lgkmcnt(0)
	s_barrier
	ds_read_b128 v[128:131], v72
	ds_read_b128 v[132:135], v72 offset:1040
	ds_read_b128 v[136:139], v72 offset:2080
	ds_read_b128 v[140:143], v72 offset:3120
	ds_read_b128 v[152:155], v72 offset:4160
	ds_read_b128 v[156:159], v72 offset:5200
	ds_read_b128 v[160:163], v72 offset:6240
	ds_read_b128 v[164:167], v72 offset:7280
	ds_read_b128 v[168:171], v147
	ds_read_b128 v[172:175], v147 offset:1040
	ds_read_b128 v[176:179], v147 offset:2080
	ds_read_b128 v[180:183], v147 offset:3120
	s_waitcnt lgkmcnt(0)
	s_barrier
	s_cbranch_vccnz .Lmy_s1n_480
	v_mbcnt_lo_u32_b32 v0, -1, 0
	v_mbcnt_hi_u32_b32 v0, -1, v0
	s_mov_b32 m0, s37
	v_lshl_add_u32 v0, v0, 4, s35
	v_ashrrev_i32_e32 v1, 31, v0
	v_lshrrev_b32_e32 v1, 22, v1
	v_add_u32_e32 v1, v0, v1
	v_ashrrev_i32_e32 v1, 10, v1
	v_mul_i32_i24_e32 v2, 0x400, v1
	v_sub_u32_e32 v2, v0, v2
	v_lshrrev_b32_e32 v3, 4, v2
	v_bitop3_b32 v2, v3, v2, 32 bitop3:0x6c
	v_ashrrev_i32_e32 v4, 31, v2
	v_lshrrev_b32_e32 v4, 26, v4
	v_add_u32_e32 v4, v2, v4
	v_lshrrev_b32_e32 v5, 6, v4
	v_and_b32_e32 v4, 0xc0, v4
	v_lshlrev_b32_e32 v3, 3, v1
	v_lshlrev_b32_e32 v1, 5, v1
	v_sub_u32_e32 v2, v2, v4
	v_and_b32_e32 v3, 0x7fff0, v3
	v_and_b32_e32 v1, 32, v1
	v_ashrrev_i16_sdwa v2, v216, sext(v2) dst_sel:DWORD dst_unused:UNUSED_PAD src0_sel:DWORD src1_sel:BYTE_0
	v_add_u32_sdwa v1, v1, sext(v2) dst_sel:DWORD dst_unused:UNUSED_PAD src0_sel:DWORD src1_sel:WORD_0
	v_add_lshl_u32 v2, v5, v3, 13
	v_add_u32_e32 v0, 0x2000, v0
	v_lshl_add_u32 v1, v1, 1, v2
	v_ashrrev_i32_e32 v2, 31, v0
	v_lshrrev_b32_e32 v2, 22, v2
	v_add_u32_e32 v2, v0, v2
	v_ashrrev_i32_e32 v2, 10, v2
	v_mul_i32_i24_e32 v3, 0x400, v2
	v_sub_u32_e32 v0, v0, v3
	v_lshrrev_b32_e32 v3, 4, v0
	v_bitop3_b32 v0, v3, v0, 32 bitop3:0x6c
	v_ashrrev_i32_e32 v4, 31, v0
	v_lshrrev_b32_e32 v4, 26, v4
	v_add_u32_e32 v4, v0, v4
	v_lshrrev_b32_e32 v5, 6, v4
	v_and_b32_e32 v4, 0xffc0, v4
	v_sub_u32_e32 v0, v0, v4
	v_lshrrev_b16_e32 v4, 7, v0
	v_and_b32_e32 v4, 1, v4
	v_lshlrev_b32_e32 v3, 3, v2
	v_lshlrev_b32_e32 v2, 5, v2
	v_add_u16_e32 v0, v0, v4
	v_and_b32_e32 v3, 0x7fff0, v3
	v_and_b32_e32 v2, 32, v2
	v_ashrrev_i16_sdwa v0, v216, sext(v0) dst_sel:DWORD dst_unused:UNUSED_PAD src0_sel:DWORD src1_sel:BYTE_0
	v_add_u32_sdwa v0, v2, sext(v0) dst_sel:DWORD dst_unused:UNUSED_PAD src0_sel:DWORD src1_sel:WORD_0
	v_add_lshl_u32 v2, v5, v3, 13
	s_mov_b32 s14, s10
	s_mov_b32 s15, s11
	v_lshl_add_u32 v0, v0, 1, v2
	buffer_load_dwordx4 v1, s[12:15], s84 offen lds
	s_mov_b32 m0, s70
	s_or_b32 s0, s84, 0x80
	buffer_load_dwordx4 v0, s[12:15], s84 offen lds
	s_mov_b32 m0, s35
	s_mov_b64 s[4:5], 0
	buffer_load_dwordx4 v1, s[8:11], s83 offen lds
	s_mov_b32 m0, s95
	s_nop 0
	buffer_load_dwordx4 v0, s[8:11], s83 offen lds
	s_mov_b32 m0, s38
	s_nop 0
	buffer_load_dwordx4 v1, s[12:15], s85 offen lds
	s_mov_b32 m0, s71
	s_nop 0
	buffer_load_dwordx4 v0, s[12:15], s85 offen lds
	s_mov_b32 m0, s39
	s_nop 0
	buffer_load_dwordx4 v1, s[8:11], s82 offen lds
	s_mov_b32 m0, s97
	s_nop 0
	buffer_load_dwordx4 v0, s[8:11], s82 offen lds
	s_mov_b32 m0, s92
	s_nop 0
	buffer_load_dwordx4 v1, s[12:15], s0 offen lds
	s_mov_b32 m0, s56
	s_nop 0
	buffer_load_dwordx4 v0, s[12:15], s0 offen lds
	s_or_b32 s0, s83, 0x80
	s_mov_b32 m0, s93
	s_nop 0
	buffer_load_dwordx4 v1, s[8:11], s0 offen lds
	s_mov_b32 m0, s57
	s_nop 0
	buffer_load_dwordx4 v0, s[8:11], s0 offen lds
	s_add_i32 s0, s85, 0x80
	s_mov_b32 m0, s94
	s_nop 0
	buffer_load_dwordx4 v1, s[12:15], s0 offen lds
	s_mov_b32 m0, s58
	s_nop 0
	buffer_load_dwordx4 v0, s[12:15], s0 offen lds
	buffer_store_dwordx4 v[128:131], v148, s[16:19], s3 offen
	buffer_store_dwordx4 v[132:135], v74, s[16:19], s3 offen
	buffer_store_dwordx4 v[136:139], v75, s[16:19], s3 offen
	buffer_store_dwordx4 v[140:143], v81, s[16:19], s3 offen
	buffer_store_dwordx4 v[152:155], v82, s[16:19], s3 offen
	buffer_store_dwordx4 v[156:159], v83, s[16:19], s3 offen
	buffer_store_dwordx4 v[160:163], v88, s[16:19], s3 offen
	buffer_store_dwordx4 v[164:167], v89, s[16:19], s3 offen
	buffer_store_dwordx4 v[168:171], v146, s[20:23], s1 offen
	buffer_store_dwordx4 v[172:175], v90, s[20:23], s1 offen
	buffer_store_dwordx4 v[176:179], v91, s[20:23], s1 offen
	buffer_store_dwordx4 v[180:183], v95, s[20:23], s1 offen
	s_branch .LBB0_486

;     ...
;       const int tid3 = opaque_tid(wave);
;       const int wr3 = tid3 >> 8, wc3 = (tid3 >> 6) & 3, fr3 = tid3 & 15, fq3 = (tid3 & 63) >> 4;
;       const int ebase3 = (brow + wr3 * 64 + fr3) * DM + pn * BM + wc3 * 32 + fq3 * 4;
;       const int vo4b = ebase3 * 4, vo2 = ebase3 * 2, vo1 = ebase3;
;       (void)vo4b; (void)vo2; (void)vo1;
;       if constexpr (OUTF) {
;         _Pragma("unroll") for (int bj = 0; bj < 2; ++bj) _Pragma("unroll") for (int n = 0; n < 2; ++n) {
;           const int col = pn * BM + bj * HALF + wc3 * 32 + n * 16 + fq3 * 4;
;           const float4 gm = *reinterpret_cast<const float4*>(g.gam + col), bt = *reinterpret_cast<const float4*>(g.bet + col);
;           _Pragma("unroll") for (int ai = 0; ai < 2; ++ai) _Pragma("unroll") for (int m = 0; m < 4; ++m) {
;             const int rl = ai * HALF + wr3 * 64 + m * 16 + fr3;
;             const float2 ms = *reinterpret_cast<const float2*>(mr + rl * 2);
;             f32x4 y = acc[ai][bj][m][n];
;             u32x4 o;
;             o[0] = __float_as_uint((y[0] - ms.x) * ms.y * gm.x + bt.x); o[1] = __float_as_uint((y[1] - ms.x) * ms.y * gm.y + bt.y);
;             o[2] = __float_as_uint((y[2] - ms.x) * ms.y * gm.z + bt.z); o[3] = __float_as_uint((y[3] - ms.x) * ms.y * gm.w + bt.w);
;             __builtin_amdgcn_raw_buffer_store_b128(o, rsO, vo4b + ((ai * HALF + m * 16) * DM + bj * HALF + n * 16) * 4, 0, 0);
;           }
;         }
;       } else {
;         constexpr int PIECE = 1024 + 16, LOBASE = 64 * PIECE;
;         const int lane3 = tid3 & 63;
;         const int hvo = (lane3 >> 5) * (DM * 2) + (lane3 & 31) * 16;
;         const int lvo = (lane3 >> 4) * DM + (lane3 & 15) * 16;
;         _Pragma("unroll") for (int ai = 0; ai < 2; ++ai) {
;           _Pragma("unroll") for (int bj = 0; bj < 2; ++bj) _Pragma("unroll") for (int n = 0; n < 2; ++n) {
;             const int cc = bj * HALF + wc3 * 32 + n * 16 + fq3 * 4;
;             const float4 gm = *reinterpret_cast<const float4*>(g.gam + pn * BM + cc), bt = *reinterpret_cast<const float4*>(g.bet + pn * BM + cc);
;             _Pragma("unroll") for (int m = 0; m < 4; ++m) {
;               const int rr = wr3 * 64 + m * 16 + fr3;
;               const float2 ms = *reinterpret_cast<const float2*>(mr + (ai * HALF + rr) * 2);
;               f32x4 y = acc[ai][bj][m][n];
.LBB0_686:
	s_or_b64 exec, exec, s[6:7]
	s_waitcnt lgkmcnt(0)
	s_barrier
	v_mbcnt_lo_u32_b32 v0, -1, 0
	v_mbcnt_hi_u32_b32 v0, -1, v0
	s_ashr_i32 s35, s34, 31
	v_add_u32_e32 v1, s37, v0
	v_bfe_u32 v4, v0, 4, 2
	v_ashrrev_i32_e32 v5, 2, v1
	v_lshrrev_b32_e32 v6, 1, v1
	v_lshlrev_b32_e32 v1, 4, v1
	v_readlane_b32 s40, v255, 16
	v_lshlrev_b32_e32 v7, 2, v4
	v_lshlrev_b32_e32 v12, 7, v0
	v_and_b32_e32 v13, 0x1f0, v1
	s_movk_i32 s2, 0x60
	s_lshl_b64 s[4:5], s[34:35], 2
	v_readlane_b32 s50, v255, 26
	v_and_or_b32 v148, v12, s72, v13
	v_and_or_b32 v12, v6, s2, v7
	v_readlane_b32 s51, v255, 27
	s_add_u32 s6, s50, s4
	v_and_b32_e32 v2, 15, v0
	v_and_b32_e32 v3, 63, v0
	v_and_b32_e32 v1, 0xf0, v1
	v_lshlrev_b32_e32 v13, 9, v0
	v_lshlrev_b32_e32 v0, 8, v0
	s_addc_u32 s7, s51, s5
	v_lshlrev_b32_e32 v150, 2, v12
	v_lshl_or_b32 v146, v4, 11, v1
	v_and_or_b32 v155, v5, s36, v2
	v_and_b32_e32 v14, 0x300, v0
	v_lshlrev_b32_e32 v151, 4, v3
	global_load_dwordx4 v[220:223], v150, s[6:7]
	global_load_dwordx4 v[224:227], v150, s[6:7] offset:64
	global_load_dwordx4 v[228:231], v150, s[6:7] offset:512
	global_load_dwordx4 v[232:235], v150, s[6:7] offset:576
	v_readlane_b32 s52, v255, 28
	v_readlane_b32 s53, v255, 29
	s_add_u32 s4, s52, s4
	s_addc_u32 s5, s53, s5
	global_load_dwordx4 v[236:239], v150, s[4:5]
	global_load_dwordx4 v[240:243], v150, s[4:5] offset:64
	global_load_dwordx4 v[244:247], v150, s[4:5] offset:512
	global_load_dwordx4 v[248:251], v150, s[4:5] offset:576
	s_movk_i32 s22, 0x200
	v_lshl_add_u32 v149, v155, 3, v219
	v_add_u32_e32 v147, s68, v151
	s_andn2_b64 vcc, exec, s[14:15]
	v_readlane_b32 s41, v255, 17
	v_readlane_b32 s42, v255, 18
	v_readlane_b32 s43, v255, 19
	v_readlane_b32 s44, v255, 20
	v_readlane_b32 s45, v255, 21
	v_readlane_b32 s46, v255, 22
	v_readlane_b32 s47, v255, 23
	v_readlane_b32 s48, v255, 24
	v_readlane_b32 s49, v255, 25
	v_readlane_b32 s54, v255, 30
	v_readlane_b32 s55, v255, 31
	s_waitcnt vmcnt(0)
	v_mov_b32_e32 v0, v220
	v_mov_b32_e32 v1, v221
	v_mov_b32_e32 v2, v222
	v_mov_b32_e32 v3, v223
	v_mov_b32_e32 v4, v236
	v_mov_b32_e32 v5, v237
	v_mov_b32_e32 v6, v238
	v_mov_b32_e32 v7, v239
	v_mov_b32_e32 v22, v1
	v_lshlrev_b32_e32 v1, 1, v12
	v_and_or_b32 v154, v13, s22, v1
	s_mov_b32 s22, 0x10400
	v_mov_b32_e32 v23, v2
	v_or3_b32 v2, v14, v12, s22
	ds_read_b64 v[12:13], v149
	v_mov_b32_e32 v144, v5
	v_mov_b32_e32 v145, v6
	v_mov_b32_e32 v1, v3
	v_mov_b32_e32 v5, v7
	s_waitcnt lgkmcnt(0)
	v_pk_add_f32 v[14:15], v[132:133], v[12:13] op_sel_hi:[1,0] neg_lo:[0,1] neg_hi:[0,1]
	v_pk_add_f32 v[18:19], v[130:131], v[12:13] op_sel_hi:[1,0] neg_lo:[0,1] neg_hi:[0,1]
	v_pk_mul_f32 v[14:15], v[12:13], v[14:15] op_sel:[1,0]
	v_pk_mul_f32 v[12:13], v[12:13], v[18:19] op_sel:[1,0]
	v_pk_fma_f32 v[14:15], v[22:23], v[14:15], v[144:145]
	v_pk_fma_f32 v[6:7], v[0:1], v[12:13], v[4:5]
	v_and_b32_sdwa v12, v14, v216 dst_sel:DWORD dst_unused:UNUSED_PAD src0_sel:WORD_1 src1_sel:DWORD
	v_add3_u32 v12, v14, v12, s77
	v_and_b32_e32 v18, 0xffff0000, v12
	v_and_b32_sdwa v12, v7, v216 dst_sel:DWORD dst_unused:UNUSED_PAD src0_sel:WORD_1 src1_sel:DWORD
	v_and_b32_sdwa v3, v15, v216 dst_sel:DWORD dst_unused:UNUSED_PAD src0_sel:WORD_1 src1_sel:DWORD
	v_and_b32_sdwa v13, v6, v216 dst_sel:DWORD dst_unused:UNUSED_PAD src0_sel:WORD_1 src1_sel:DWORD
	v_add3_u32 v12, v7, v12, s77
	v_lshrrev_b32_e32 v131, 1, v155
	v_add3_u32 v3, v15, v3, s77
	v_add3_u32 v19, v6, v13, s77
	v_and_b32_e32 v130, 0xffff0000, v12
	v_mul_lo_u32 v152, v131, s60
	v_or_b32_sdwa v13, v130, v3 dst_sel:DWORD dst_unused:UNUSED_PAD src0_sel:DWORD src1_sel:WORD_1
	v_or_b32_sdwa v12, v19, v18 dst_sel:DWORD dst_unused:UNUSED_PAD src0_sel:WORD_1 src1_sel:DWORD
	v_add_u32_e32 v132, v154, v152
	ds_write_b64 v132, v[12:13]
	v_and_b32_e32 v12, 0xffff0000, v19
	v_sub_u32_e32 v6, v6, v12
	v_sub_u32_e32 v12, v14, v18
	v_and_b32_e32 v3, 0xffff0000, v3
	v_add_u32_e32 v12, 0x80, v12
	v_sub_u32_e32 v3, v15, v3
	v_sub_u32_e32 v7, v7, v130
	v_add_u32_e32 v6, 0x80, v6
	v_ashrrev_i32_e32 v12, 8, v12
	v_add_u32_e32 v3, 0x80, v3
	v_add_u32_e32 v7, 0x80, v7
	v_ashrrev_i32_e32 v6, 8, v6
	v_min_i32_e32 v12, 0x7f, v12
	v_ashrrev_i32_e32 v3, 8, v3
	v_ashrrev_i32_e32 v7, 8, v7
	v_min_i32_e32 v6, 0x7f, v6
	v_min_i32_sdwa v3, v3, s78 dst_sel:WORD_1 dst_unused:UNUSED_PAD src0_sel:DWORD src1_sel:DWORD
	v_min_i32_e32 v7, 0x7f, v7
	v_lshlrev_b32_e32 v12, 8, v12
	v_and_b32_e32 v12, 0xff00, v12
	v_and_b32_e32 v3, 0xff0000, v3
	v_perm_b32 v6, v7, v6, s79
	v_or3_b32 v3, v6, v12, v3
	v_lshrrev_b32_e32 v6, 2, v155
	v_mad_u64_u32 v[12:13], s[22:23], v6, s60, v[2:3]
	ds_write_b32 v12, v3
	v_or_b32_e32 v3, 16, v155
	v_lshl_add_u32 v13, v3, 3, v219
	ds_read_b64 v[6:7], v13
	v_lshrrev_b32_e32 v133, 1, v3
	v_mul_lo_u32 v153, v133, s60
	v_add_u32_e32 v133, v154, v153
	v_lshrrev_b32_e32 v3, 2, v3
	s_waitcnt lgkmcnt(0)
;     ...
;             _Pragma("unroll") for (int m = 0; m < 4; ++m) {
;               const int rr = wr3 * 64 + m * 16 + fr3;
;               const float2 ms = *reinterpret_cast<const float2*>(mr + (ai * HALF + rr) * 2);
;               f32x4 y = acc[ai][bj][m][n];
;               const float o0 = (y[0] - ms.x) * ms.y * gm.x + bt.x, o1 = (y[1] - ms.x) * ms.y * gm.y + bt.y;
;               const float o2 = (y[2] - ms.x) * ms.y * gm.z + bt.z, o3 = (y[3] - ms.x) * ms.y * gm.w + bt.w;
;               const unsigned h0 = f2bf(o0), h1 = f2bf(o1), h2 = f2bf(o2), h3 = f2bf(o3);
;               u32x2 ob; ob[0] = h0 | (h1 << 16); ob[1] = h2 | (h3 << 16);
;               *reinterpret_cast<u32x2*>(smem + (rr >> 1) * PIECE + (rr & 1) * 512 + cc * 2) = ob;
;               const int l0 = min(((int)__float_as_uint(o0) - (int)(h0 << 16) + 128) >> 8, 127);
;               const int l1 = min(((int)__float_as_uint(o1) - (int)(h1 << 16) + 128) >> 8, 127);
;               const int l2 = min(((int)__float_as_uint(o2) - (int)(h2 << 16) + 128) >> 8, 127);
;               const int l3 = min(((int)__float_as_uint(o3) - (int)(h3 << 16) + 128) >> 8, 127);
;               *reinterpret_cast<unsigned*>(smem + LOBASE + (rr >> 2) * PIECE + (rr & 3) * 256 + cc) =
;                   (unsigned)(l0 & 255) | ((unsigned)(l1 & 255) << 8) | ((unsigned)(l2 & 255) << 16) | ((unsigned)l3 << 24);
;             }
	v_pk_add_f32 v[14:15], v[122:123], v[6:7] op_sel_hi:[1,0] neg_lo:[0,1] neg_hi:[0,1]
	v_pk_add_f32 v[18:19], v[134:135], v[6:7] op_sel_hi:[1,0] neg_lo:[0,1] neg_hi:[0,1]
	v_pk_mul_f32 v[14:15], v[6:7], v[14:15] op_sel:[1,0]
	v_pk_mul_f32 v[6:7], v[6:7], v[18:19] op_sel:[1,0]
	v_pk_fma_f32 v[14:15], v[22:23], v[14:15], v[144:145]
	v_pk_fma_f32 v[6:7], v[0:1], v[6:7], v[4:5]
	v_and_b32_sdwa v18, v15, v216 dst_sel:DWORD dst_unused:UNUSED_PAD src0_sel:WORD_1 src1_sel:DWORD
	v_and_b32_sdwa v19, v14, v216 dst_sel:DWORD dst_unused:UNUSED_PAD src0_sel:WORD_1 src1_sel:DWORD
	v_add3_u32 v122, v15, v18, s77
	v_add3_u32 v18, v14, v19, s77
	v_and_b32_e32 v123, 0xffff0000, v18
	v_and_b32_sdwa v18, v7, v216 dst_sel:DWORD dst_unused:UNUSED_PAD src0_sel:WORD_1 src1_sel:DWORD
	v_and_b32_sdwa v19, v6, v216 dst_sel:DWORD dst_unused:UNUSED_PAD src0_sel:WORD_1 src1_sel:DWORD
	v_add3_u32 v18, v7, v18, s77
	v_add3_u32 v130, v6, v19, s77
	v_and_b32_e32 v131, 0xffff0000, v18
	v_or_b32_sdwa v19, v131, v122 dst_sel:DWORD dst_unused:UNUSED_PAD src0_sel:DWORD src1_sel:WORD_1
	v_or_b32_sdwa v18, v130, v123 dst_sel:DWORD dst_unused:UNUSED_PAD src0_sel:WORD_1 src1_sel:DWORD
	ds_write_b64 v133, v[18:19]
	v_and_b32_e32 v18, 0xffff0000, v130
	v_sub_u32_e32 v6, v6, v18
	v_sub_u32_e32 v14, v14, v123
	v_and_b32_e32 v18, 0xffff0000, v122
	v_add_u32_e32 v14, 0x80, v14
	v_sub_u32_e32 v15, v15, v18
	v_sub_u32_e32 v7, v7, v131
	v_add_u32_e32 v6, 0x80, v6
	v_ashrrev_i32_e32 v14, 8, v14
	v_add_u32_e32 v15, 0x80, v15
	v_add_u32_e32 v7, 0x80, v7
	v_ashrrev_i32_e32 v6, 8, v6
	v_min_i32_e32 v14, 0x7f, v14
	v_ashrrev_i32_e32 v15, 8, v15
	v_ashrrev_i32_e32 v7, 8, v7
	v_min_i32_e32 v6, 0x7f, v6
	v_min_i32_sdwa v15, v15, s78 dst_sel:WORD_1 dst_unused:UNUSED_PAD src0_sel:DWORD src1_sel:DWORD
	v_min_i32_e32 v7, 0x7f, v7
	v_lshlrev_b32_e32 v14, 8, v14
	v_and_b32_e32 v14, 0xff00, v14
	v_and_b32_e32 v15, 0xff0000, v15
	v_perm_b32 v6, v7, v6, s79
	v_or3_b32 v6, v6, v14, v15
	v_mad_u64_u32 v[14:15], s[22:23], v3, s60, v[2:3]
	v_or_b32_e32 v3, 32, v155
	ds_write_b32 v14, v6
	v_lshl_add_u32 v15, v3, 3, v219
	ds_read_b64 v[6:7], v15
	v_lshrrev_b32_e32 v134, 1, v3
	v_lshrrev_b32_e32 v3, 2, v3
	s_waitcnt lgkmcnt(0)
	v_pk_add_f32 v[18:19], v[136:137], v[6:7] op_sel_hi:[1,0] neg_lo:[0,1] neg_hi:[0,1]
	s_nop 0
	v_pk_mul_f32 v[18:19], v[6:7], v[18:19] op_sel:[1,0]
	v_pk_add_f32 v[122:123], v[138:139], v[6:7] op_sel_hi:[1,0] neg_lo:[0,1] neg_hi:[0,1]
	v_pk_fma_f32 v[18:19], v[22:23], v[18:19], v[144:145]
	v_pk_mul_f32 v[6:7], v[6:7], v[122:123] op_sel:[1,0]
	v_and_b32_sdwa v122, v19, v216 dst_sel:DWORD dst_unused:UNUSED_PAD src0_sel:WORD_1 src1_sel:DWORD
	v_and_b32_sdwa v123, v18, v216 dst_sel:DWORD dst_unused:UNUSED_PAD src0_sel:WORD_1 src1_sel:DWORD
	v_pk_fma_f32 v[6:7], v[0:1], v[6:7], v[4:5]
	v_add3_u32 v130, v19, v122, s77
	v_add3_u32 v122, v18, v123, s77
	v_and_b32_e32 v131, 0xffff0000, v122
	v_and_b32_sdwa v122, v7, v216 dst_sel:DWORD dst_unused:UNUSED_PAD src0_sel:WORD_1 src1_sel:DWORD
	v_and_b32_sdwa v123, v6, v216 dst_sel:DWORD dst_unused:UNUSED_PAD src0_sel:WORD_1 src1_sel:DWORD
	v_add3_u32 v122, v7, v122, s77
	v_add3_u32 v135, v6, v123, s77
	v_and_b32_e32 v136, 0xffff0000, v122
	v_mul_lo_u32 v137, v134, s60
	v_or_b32_sdwa v123, v136, v130 dst_sel:DWORD dst_unused:UNUSED_PAD src0_sel:DWORD src1_sel:WORD_1
	v_or_b32_sdwa v122, v135, v131 dst_sel:DWORD dst_unused:UNUSED_PAD src0_sel:WORD_1 src1_sel:DWORD
	v_add_u32_e32 v134, v154, v137
	ds_write_b64 v134, v[122:123]
	v_and_b32_e32 v122, 0xffff0000, v135
	v_sub_u32_e32 v6, v6, v122
	v_sub_u32_e32 v18, v18, v131
	v_and_b32_e32 v122, 0xffff0000, v130
	v_add_u32_e32 v18, 0x80, v18
	v_sub_u32_e32 v19, v19, v122
	v_sub_u32_e32 v7, v7, v136
	v_add_u32_e32 v6, 0x80, v6
	v_ashrrev_i32_e32 v18, 8, v18
	v_add_u32_e32 v19, 0x80, v19
	v_add_u32_e32 v7, 0x80, v7
	v_ashrrev_i32_e32 v6, 8, v6
	v_min_i32_e32 v18, 0x7f, v18
	v_ashrrev_i32_e32 v19, 8, v19
	v_ashrrev_i32_e32 v7, 8, v7
	v_min_i32_e32 v6, 0x7f, v6
	v_min_i32_sdwa v19, v19, s78 dst_sel:WORD_1 dst_unused:UNUSED_PAD src0_sel:DWORD src1_sel:DWORD
	v_min_i32_e32 v7, 0x7f, v7
	v_lshlrev_b32_e32 v18, 8, v18
	v_and_b32_e32 v18, 0xff00, v18
	v_and_b32_e32 v19, 0xff0000, v19
	v_perm_b32 v6, v7, v6, s79
	v_or3_b32 v6, v6, v18, v19
	v_mad_u64_u32 v[18:19], s[22:23], v3, s60, v[2:3]
	v_or_b32_e32 v3, 48, v155
	ds_write_b32 v18, v6
	v_lshl_add_u32 v19, v3, 3, v219
	ds_read_b64 v[6:7], v19
	v_lshrrev_b32_e32 v130, 1, v3
	v_mul_lo_u32 v136, v130, s60
	v_add_u32_e32 v135, v154, v136
	s_waitcnt lgkmcnt(0)
;     ...
;             _Pragma("unroll") for (int m = 0; m < 4; ++m) {
;               const int rr = wr3 * 64 + m * 16 + fr3;
;               const float2 ms = *reinterpret_cast<const float2*>(mr + (ai * HALF + rr) * 2);
;               f32x4 y = acc[ai][bj][m][n];
;               const float o0 = (y[0] - ms.x) * ms.y * gm.x + bt.x, o1 = (y[1] - ms.x) * ms.y * gm.y + bt.y;
;               const float o2 = (y[2] - ms.x) * ms.y * gm.z + bt.z, o3 = (y[3] - ms.x) * ms.y * gm.w + bt.w;
;               const unsigned h0 = f2bf(o0), h1 = f2bf(o1), h2 = f2bf(o2), h3 = f2bf(o3);
;               u32x2 ob; ob[0] = h0 | (h1 << 16); ob[1] = h2 | (h3 << 16);
;               *reinterpret_cast<u32x2*>(smem + (rr >> 1) * PIECE + (rr & 1) * 512 + cc * 2) = ob;
;               const int l0 = min(((int)__float_as_uint(o0) - (int)(h0 << 16) + 128) >> 8, 127);
;               const int l1 = min(((int)__float_as_uint(o1) - (int)(h1 << 16) + 128) >> 8, 127);
;               const int l2 = min(((int)__float_as_uint(o2) - (int)(h2 << 16) + 128) >> 8, 127);
;               const int l3 = min(((int)__float_as_uint(o3) - (int)(h3 << 16) + 128) >> 8, 127);
;               *reinterpret_cast<unsigned*>(smem + LOBASE + (rr >> 2) * PIECE + (rr & 3) * 256 + cc) =
;                   (unsigned)(l0 & 255) | ((unsigned)(l1 & 255) << 8) | ((unsigned)(l2 & 255) << 16) | ((unsigned)l3 << 24);
;             }
	v_pk_add_f32 v[122:123], v[140:141], v[6:7] op_sel_hi:[1,0] neg_lo:[0,1] neg_hi:[0,1]
	s_nop 0
	v_pk_mul_f32 v[122:123], v[6:7], v[122:123] op_sel:[1,0]
	s_nop 0
	v_pk_fma_f32 v[22:23], v[22:23], v[122:123], v[144:145]
	v_pk_add_f32 v[122:123], v[142:143], v[6:7] op_sel_hi:[1,0] neg_lo:[0,1] neg_hi:[0,1]
	s_nop 0
	v_pk_mul_f32 v[6:7], v[6:7], v[122:123] op_sel:[1,0]
	s_nop 0
	v_pk_fma_f32 v[0:1], v[0:1], v[6:7], v[4:5]
	v_and_b32_sdwa v4, v23, v216 dst_sel:DWORD dst_unused:UNUSED_PAD src0_sel:WORD_1 src1_sel:DWORD
	v_and_b32_sdwa v5, v22, v216 dst_sel:DWORD dst_unused:UNUSED_PAD src0_sel:WORD_1 src1_sel:DWORD
	v_add3_u32 v6, v23, v4, s77
	v_add3_u32 v4, v22, v5, s77
	v_and_b32_e32 v7, 0xffff0000, v4
	v_and_b32_sdwa v4, v1, v216 dst_sel:DWORD dst_unused:UNUSED_PAD src0_sel:WORD_1 src1_sel:DWORD
	v_and_b32_sdwa v5, v0, v216 dst_sel:DWORD dst_unused:UNUSED_PAD src0_sel:WORD_1 src1_sel:DWORD
	v_add3_u32 v4, v1, v4, s77
	v_add3_u32 v122, v0, v5, s77
	v_and_b32_e32 v123, 0xffff0000, v4
	v_or_b32_sdwa v5, v123, v6 dst_sel:DWORD dst_unused:UNUSED_PAD src0_sel:DWORD src1_sel:WORD_1
	v_or_b32_sdwa v4, v122, v7 dst_sel:DWORD dst_unused:UNUSED_PAD src0_sel:WORD_1 src1_sel:DWORD
	ds_write_b64 v135, v[4:5]
	v_and_b32_e32 v4, 0xffff0000, v122
	v_sub_u32_e32 v0, v0, v4
	v_sub_u32_e32 v4, v22, v7
	v_and_b32_e32 v5, 0xffff0000, v6
	v_add_u32_e32 v4, 0x80, v4
	v_sub_u32_e32 v5, v23, v5
	v_sub_u32_e32 v1, v1, v123
	v_add_u32_e32 v0, 0x80, v0
	v_ashrrev_i32_e32 v4, 8, v4
	v_add_u32_e32 v5, 0x80, v5
	v_add_u32_e32 v1, 0x80, v1
	v_ashrrev_i32_e32 v0, 8, v0
	v_min_i32_e32 v4, 0x7f, v4
	v_ashrrev_i32_e32 v5, 8, v5
	v_ashrrev_i32_e32 v1, 8, v1
	v_min_i32_e32 v0, 0x7f, v0
	v_min_i32_sdwa v5, v5, s78 dst_sel:WORD_1 dst_unused:UNUSED_PAD src0_sel:DWORD src1_sel:DWORD
	v_min_i32_e32 v1, 0x7f, v1
	v_lshlrev_b32_e32 v4, 8, v4
	v_and_b32_e32 v4, 0xff00, v4
	v_and_b32_e32 v5, 0xff0000, v5
	v_perm_b32 v0, v1, v0, s79
	v_lshrrev_b32_e32 v1, 2, v3
	v_or3_b32 v0, v0, v4, v5
	v_mad_u64_u32 v[22:23], s[22:23], v1, s60, v[2:3]
	ds_write_b32 v22, v0
	v_mov_b32_e32 v0, v224
	v_mov_b32_e32 v1, v225
	v_mov_b32_e32 v2, v226
	v_mov_b32_e32 v3, v227
	v_mov_b32_e32 v4, v240
	v_mov_b32_e32 v5, v241
	v_mov_b32_e32 v6, v242
	v_mov_b32_e32 v7, v243
	ds_read_b64 v[138:139], v149
	s_mov_b32 s22, s18
	s_mov_b32 s23, s19
	s_waitcnt lgkmcnt(0)
	v_pk_add_f32 v[128:129], v[128:129], v[138:139] op_sel_hi:[1,0] neg_lo:[0,1] neg_hi:[0,1]
	s_nop 0
	v_pk_mul_f32 v[128:129], v[138:139], v[128:129] op_sel:[1,0]
	v_pk_add_f32 v[126:127], v[126:127], v[138:139] op_sel_hi:[1,0] neg_lo:[0,1] neg_hi:[0,1]
	v_mov_b32_e32 v122, v1
	v_mov_b32_e32 v123, v2
	v_mov_b32_e32 v130, v5
	v_mov_b32_e32 v131, v6
	v_pk_fma_f32 v[128:129], v[122:123], v[128:129], v[130:131]
	v_pk_mul_f32 v[126:127], v[138:139], v[126:127] op_sel:[1,0]
	v_mov_b32_e32 v1, v3
	v_mov_b32_e32 v5, v7
	v_and_b32_sdwa v23, v128, v216 dst_sel:DWORD dst_unused:UNUSED_PAD src0_sel:WORD_1 src1_sel:DWORD
	v_pk_fma_f32 v[6:7], v[0:1], v[126:127], v[4:5]
	v_add3_u32 v23, v128, v23, s77
	v_and_b32_e32 v138, 0xffff0000, v23
	v_and_b32_sdwa v23, v7, v216 dst_sel:DWORD dst_unused:UNUSED_PAD src0_sel:WORD_1 src1_sel:DWORD
	v_and_b32_sdwa v3, v129, v216 dst_sel:DWORD dst_unused:UNUSED_PAD src0_sel:WORD_1 src1_sel:DWORD
	v_and_b32_sdwa v126, v6, v216 dst_sel:DWORD dst_unused:UNUSED_PAD src0_sel:WORD_1 src1_sel:DWORD
	v_add3_u32 v23, v7, v23, s77
	v_or_b32_e32 v2, 32, v154
	v_add3_u32 v3, v129, v3, s77
	v_add3_u32 v139, v6, v126, s77
	v_and_b32_e32 v140, 0xffff0000, v23
	v_or_b32_sdwa v127, v140, v3 dst_sel:DWORD dst_unused:UNUSED_PAD src0_sel:DWORD src1_sel:WORD_1
	v_or_b32_sdwa v126, v139, v138 dst_sel:DWORD dst_unused:UNUSED_PAD src0_sel:WORD_1 src1_sel:DWORD
	v_add_u32_e32 v23, v2, v152
	ds_write_b64 v23, v[126:127]
	v_and_b32_e32 v126, 0xffff0000, v139
	v_sub_u32_e32 v6, v6, v126
	v_sub_u32_e32 v126, v128, v138
	v_and_b32_e32 v3, 0xffff0000, v3
	v_add_u32_e32 v126, 0x80, v126
	v_sub_u32_e32 v3, v129, v3
	v_sub_u32_e32 v7, v7, v140
	v_add_u32_e32 v6, 0x80, v6
	v_ashrrev_i32_e32 v126, 8, v126
	v_add_u32_e32 v3, 0x80, v3
	v_add_u32_e32 v7, 0x80, v7
	v_ashrrev_i32_e32 v6, 8, v6
	v_min_i32_e32 v126, 0x7f, v126
	v_ashrrev_i32_e32 v3, 8, v3
	v_ashrrev_i32_e32 v7, 8, v7
	v_min_i32_e32 v6, 0x7f, v6
	v_min_i32_sdwa v3, v3, s78 dst_sel:WORD_1 dst_unused:UNUSED_PAD src0_sel:DWORD src1_sel:DWORD
	v_min_i32_e32 v7, 0x7f, v7
	v_lshlrev_b32_e32 v126, 8, v126
	v_and_b32_e32 v126, 0xff00, v126
	v_and_b32_e32 v3, 0xff0000, v3
	v_perm_b32 v6, v7, v6, s79
	v_or3_b32 v3, v6, v126, v3
	ds_write_b32 v12, v3 offset:16
	ds_read_b64 v[6:7], v13
	s_waitcnt lgkmcnt(0)
;     ...
;             _Pragma("unroll") for (int m = 0; m < 4; ++m) {
;               const int rr = wr3 * 64 + m * 16 + fr3;
;               const float2 ms = *reinterpret_cast<const float2*>(mr + (ai * HALF + rr) * 2);
;               f32x4 y = acc[ai][bj][m][n];
;               const float o0 = (y[0] - ms.x) * ms.y * gm.x + bt.x, o1 = (y[1] - ms.x) * ms.y * gm.y + bt.y;
;               const float o2 = (y[2] - ms.x) * ms.y * gm.z + bt.z, o3 = (y[3] - ms.x) * ms.y * gm.w + bt.w;
;               const unsigned h0 = f2bf(o0), h1 = f2bf(o1), h2 = f2bf(o2), h3 = f2bf(o3);
;               u32x2 ob; ob[0] = h0 | (h1 << 16); ob[1] = h2 | (h3 << 16);
;               *reinterpret_cast<u32x2*>(smem + (rr >> 1) * PIECE + (rr & 1) * 512 + cc * 2) = ob;
;               const int l0 = min(((int)__float_as_uint(o0) - (int)(h0 << 16) + 128) >> 8, 127);
;               const int l1 = min(((int)__float_as_uint(o1) - (int)(h1 << 16) + 128) >> 8, 127);
;               const int l2 = min(((int)__float_as_uint(o2) - (int)(h2 << 16) + 128) >> 8, 127);
;               const int l3 = min(((int)__float_as_uint(o3) - (int)(h3 << 16) + 128) >> 8, 127);
;               *reinterpret_cast<unsigned*>(smem + LOBASE + (rr >> 2) * PIECE + (rr & 3) * 256 + cc) =
;                   (unsigned)(l0 & 255) | ((unsigned)(l1 & 255) << 8) | ((unsigned)(l2 & 255) << 16) | ((unsigned)l3 << 24);
;             }
	v_pk_add_f32 v[108:109], v[108:109], v[6:7] op_sel_hi:[1,0] neg_lo:[0,1] neg_hi:[0,1]
	s_nop 0
	v_pk_mul_f32 v[108:109], v[6:7], v[108:109] op_sel:[1,0]
	s_nop 0
	v_pk_fma_f32 v[126:127], v[122:123], v[108:109], v[130:131]
	v_pk_add_f32 v[108:109], v[110:111], v[6:7] op_sel_hi:[1,0] neg_lo:[0,1] neg_hi:[0,1]
	v_and_b32_sdwa v3, v127, v216 dst_sel:DWORD dst_unused:UNUSED_PAD src0_sel:WORD_1 src1_sel:DWORD
	v_pk_mul_f32 v[6:7], v[6:7], v[108:109] op_sel:[1,0]
	v_and_b32_sdwa v108, v126, v216 dst_sel:DWORD dst_unused:UNUSED_PAD src0_sel:WORD_1 src1_sel:DWORD
	v_pk_fma_f32 v[6:7], v[0:1], v[6:7], v[4:5]
	v_add3_u32 v108, v126, v108, s77
	v_and_b32_e32 v109, 0xffff0000, v108
	v_and_b32_sdwa v108, v7, v216 dst_sel:DWORD dst_unused:UNUSED_PAD src0_sel:WORD_1 src1_sel:DWORD
	v_and_b32_sdwa v110, v6, v216 dst_sel:DWORD dst_unused:UNUSED_PAD src0_sel:WORD_1 src1_sel:DWORD
	v_add3_u32 v108, v7, v108, s77
	v_add3_u32 v3, v127, v3, s77
	v_add3_u32 v128, v6, v110, s77
	v_and_b32_e32 v129, 0xffff0000, v108
	v_or_b32_sdwa v111, v129, v3 dst_sel:DWORD dst_unused:UNUSED_PAD src0_sel:DWORD src1_sel:WORD_1
	v_or_b32_sdwa v110, v128, v109 dst_sel:DWORD dst_unused:UNUSED_PAD src0_sel:WORD_1 src1_sel:DWORD
	v_add_u32_e32 v108, v2, v153
	ds_write_b64 v108, v[110:111]
	v_and_b32_e32 v110, 0xffff0000, v128
	v_sub_u32_e32 v109, v126, v109
	v_and_b32_e32 v3, 0xffff0000, v3
	v_sub_u32_e32 v6, v6, v110
	v_add_u32_e32 v109, 0x80, v109
	v_sub_u32_e32 v3, v127, v3
	v_sub_u32_e32 v7, v7, v129
	v_add_u32_e32 v6, 0x80, v6
	v_ashrrev_i32_e32 v109, 8, v109
	v_add_u32_e32 v3, 0x80, v3
	v_add_u32_e32 v7, 0x80, v7
	v_ashrrev_i32_e32 v6, 8, v6
	v_min_i32_e32 v109, 0x7f, v109
	v_ashrrev_i32_e32 v3, 8, v3
	v_ashrrev_i32_e32 v7, 8, v7
	v_min_i32_e32 v6, 0x7f, v6
	v_min_i32_sdwa v3, v3, s78 dst_sel:WORD_1 dst_unused:UNUSED_PAD src0_sel:DWORD src1_sel:DWORD
	v_min_i32_e32 v7, 0x7f, v7
	v_lshlrev_b32_e32 v109, 8, v109
	v_and_b32_e32 v109, 0xff00, v109
	v_and_b32_e32 v3, 0xff0000, v3
	v_perm_b32 v6, v7, v6, s79
	v_or3_b32 v3, v6, v109, v3
	ds_write_b32 v14, v3 offset:16
	ds_read_b64 v[6:7], v15
	s_waitcnt lgkmcnt(0)
	v_pk_add_f32 v[98:99], v[98:99], v[6:7] op_sel_hi:[1,0] neg_lo:[0,1] neg_hi:[0,1]
	s_nop 0
	v_pk_mul_f32 v[98:99], v[6:7], v[98:99] op_sel:[1,0]
	s_nop 0
	v_pk_fma_f32 v[110:111], v[122:123], v[98:99], v[130:131]
	v_pk_add_f32 v[98:99], v[106:107], v[6:7] op_sel_hi:[1,0] neg_lo:[0,1] neg_hi:[0,1]
	v_and_b32_sdwa v3, v111, v216 dst_sel:DWORD dst_unused:UNUSED_PAD src0_sel:WORD_1 src1_sel:DWORD
	v_pk_mul_f32 v[6:7], v[6:7], v[98:99] op_sel:[1,0]
	v_and_b32_sdwa v98, v110, v216 dst_sel:DWORD dst_unused:UNUSED_PAD src0_sel:WORD_1 src1_sel:DWORD
	v_pk_fma_f32 v[6:7], v[0:1], v[6:7], v[4:5]
	v_add3_u32 v98, v110, v98, s77
	v_and_b32_e32 v99, 0xffff0000, v98
	v_and_b32_sdwa v98, v7, v216 dst_sel:DWORD dst_unused:UNUSED_PAD src0_sel:WORD_1 src1_sel:DWORD
	v_and_b32_sdwa v106, v6, v216 dst_sel:DWORD dst_unused:UNUSED_PAD src0_sel:WORD_1 src1_sel:DWORD
	v_add3_u32 v98, v7, v98, s77
	v_add3_u32 v3, v111, v3, s77
	v_add3_u32 v109, v6, v106, s77
	v_and_b32_e32 v126, 0xffff0000, v98
	v_or_b32_sdwa v107, v126, v3 dst_sel:DWORD dst_unused:UNUSED_PAD src0_sel:DWORD src1_sel:WORD_1
	v_or_b32_sdwa v106, v109, v99 dst_sel:DWORD dst_unused:UNUSED_PAD src0_sel:WORD_1 src1_sel:DWORD
	v_add_u32_e32 v98, v2, v137
	ds_write_b64 v98, v[106:107]
	v_and_b32_e32 v106, 0xffff0000, v109
	v_sub_u32_e32 v99, v110, v99
	v_and_b32_e32 v3, 0xffff0000, v3
	v_sub_u32_e32 v6, v6, v106
	v_add_u32_e32 v99, 0x80, v99
	v_sub_u32_e32 v3, v111, v3
	v_sub_u32_e32 v7, v7, v126
	v_add_u32_e32 v6, 0x80, v6
	v_ashrrev_i32_e32 v99, 8, v99
	v_add_u32_e32 v3, 0x80, v3
	v_add_u32_e32 v7, 0x80, v7
	v_ashrrev_i32_e32 v6, 8, v6
	v_min_i32_e32 v99, 0x7f, v99
	v_ashrrev_i32_e32 v3, 8, v3
	v_ashrrev_i32_e32 v7, 8, v7
	v_min_i32_e32 v6, 0x7f, v6
	v_min_i32_sdwa v3, v3, s78 dst_sel:WORD_1 dst_unused:UNUSED_PAD src0_sel:DWORD src1_sel:DWORD
	v_min_i32_e32 v7, 0x7f, v7
	v_lshlrev_b32_e32 v99, 8, v99
	v_and_b32_e32 v99, 0xff00, v99
	v_and_b32_e32 v3, 0xff0000, v3
	v_perm_b32 v6, v7, v6, s79
	v_or3_b32 v3, v6, v99, v3
	ds_write_b32 v18, v3 offset:16
	ds_read_b64 v[6:7], v19
	v_add_u32_e32 v99, v2, v136
	s_waitcnt lgkmcnt(0)
	v_pk_add_f32 v[106:107], v[114:115], v[6:7] op_sel_hi:[1,0] neg_lo:[0,1] neg_hi:[0,1]
	s_nop 0
	v_pk_mul_f32 v[106:107], v[6:7], v[106:107] op_sel:[1,0]
	v_pk_add_f32 v[110:111], v[120:121], v[6:7] op_sel_hi:[1,0] neg_lo:[0,1] neg_hi:[0,1]
	v_pk_fma_f32 v[106:107], v[122:123], v[106:107], v[130:131]
	v_pk_mul_f32 v[6:7], v[6:7], v[110:111] op_sel:[1,0]
	v_and_b32_sdwa v3, v107, v216 dst_sel:DWORD dst_unused:UNUSED_PAD src0_sel:WORD_1 src1_sel:DWORD
	v_pk_fma_f32 v[0:1], v[0:1], v[6:7], v[4:5]
	v_and_b32_sdwa v4, v106, v216 dst_sel:DWORD dst_unused:UNUSED_PAD src0_sel:WORD_1 src1_sel:DWORD
	v_add3_u32 v4, v106, v4, s77
	v_and_b32_e32 v6, 0xffff0000, v4
	v_and_b32_sdwa v4, v1, v216 dst_sel:DWORD dst_unused:UNUSED_PAD src0_sel:WORD_1 src1_sel:DWORD
	v_and_b32_sdwa v5, v0, v216 dst_sel:DWORD dst_unused:UNUSED_PAD src0_sel:WORD_1 src1_sel:DWORD
	v_add3_u32 v4, v1, v4, s77
	v_add3_u32 v7, v0, v5, s77
	v_add3_u32 v3, v107, v3, s77
	v_and_b32_e32 v109, 0xffff0000, v4
	v_and_b32_e32 v2, 0xffff0000, v7
	v_or_b32_sdwa v5, v109, v3 dst_sel:DWORD dst_unused:UNUSED_PAD src0_sel:DWORD src1_sel:WORD_1
	v_sub_u32_e32 v0, v0, v2
	v_sub_u32_e32 v2, v106, v6
	v_and_b32_e32 v3, 0xffff0000, v3
	v_add_u32_e32 v2, 0x80, v2
	v_sub_u32_e32 v3, v107, v3
	v_sub_u32_e32 v1, v1, v109
	v_add_u32_e32 v0, 0x80, v0
	v_ashrrev_i32_e32 v2, 8, v2
	v_add_u32_e32 v3, 0x80, v3
	v_add_u32_e32 v1, 0x80, v1
	v_ashrrev_i32_e32 v0, 8, v0
	v_min_i32_e32 v2, 0x7f, v2
	v_ashrrev_i32_e32 v3, 8, v3
	v_ashrrev_i32_e32 v1, 8, v1
	v_min_i32_e32 v0, 0x7f, v0
	v_min_i32_sdwa v3, v3, s78 dst_sel:WORD_1 dst_unused:UNUSED_PAD src0_sel:DWORD src1_sel:DWORD
	v_min_i32_e32 v1, 0x7f, v1
	v_lshlrev_b32_e32 v2, 8, v2
	v_and_b32_e32 v2, 0xff00, v2
	v_and_b32_e32 v3, 0xff0000, v3
	v_perm_b32 v0, v1, v0, s79
	v_or_b32_sdwa v4, v7, v6 dst_sel:DWORD dst_unused:UNUSED_PAD src0_sel:WORD_1 src1_sel:DWORD
	v_or3_b32 v0, v0, v2, v3
	ds_write_b64 v99, v[4:5]
	ds_write_b32 v22, v0 offset:16
	v_mov_b32_e32 v0, v228
	v_mov_b32_e32 v1, v229
	v_mov_b32_e32 v2, v230
	v_mov_b32_e32 v3, v231
	v_mov_b32_e32 v4, v244
	v_mov_b32_e32 v5, v245
	v_mov_b32_e32 v6, v246
	v_mov_b32_e32 v7, v247
	ds_read_b64 v[106:107], v149
	v_or_b32_e32 v109, 0x100, v154
	s_waitcnt lgkmcnt(0)
;     ...
;             _Pragma("unroll") for (int m = 0; m < 4; ++m) {
;               const int rr = wr3 * 64 + m * 16 + fr3;
;               const float2 ms = *reinterpret_cast<const float2*>(mr + (ai * HALF + rr) * 2);
;               f32x4 y = acc[ai][bj][m][n];
;               const float o0 = (y[0] - ms.x) * ms.y * gm.x + bt.x, o1 = (y[1] - ms.x) * ms.y * gm.y + bt.y;
;               const float o2 = (y[2] - ms.x) * ms.y * gm.z + bt.z, o3 = (y[3] - ms.x) * ms.y * gm.w + bt.w;
;               const unsigned h0 = f2bf(o0), h1 = f2bf(o1), h2 = f2bf(o2), h3 = f2bf(o3);
;               u32x2 ob; ob[0] = h0 | (h1 << 16); ob[1] = h2 | (h3 << 16);
;               *reinterpret_cast<u32x2*>(smem + (rr >> 1) * PIECE + (rr & 1) * 512 + cc * 2) = ob;
;               const int l0 = min(((int)__float_as_uint(o0) - (int)(h0 << 16) + 128) >> 8, 127);
;               const int l1 = min(((int)__float_as_uint(o1) - (int)(h1 << 16) + 128) >> 8, 127);
;               const int l2 = min(((int)__float_as_uint(o2) - (int)(h2 << 16) + 128) >> 8, 127);
;               const int l3 = min(((int)__float_as_uint(o3) - (int)(h3 << 16) + 128) >> 8, 127);
;               *reinterpret_cast<unsigned*>(smem + LOBASE + (rr >> 2) * PIECE + (rr & 3) * 256 + cc) =
;                   (unsigned)(l0 & 255) | ((unsigned)(l1 & 255) << 8) | ((unsigned)(l2 & 255) << 16) | ((unsigned)l3 << 24);
;             }
	v_pk_add_f32 v[120:121], v[124:125], v[106:107] op_sel_hi:[1,0] neg_lo:[0,1] neg_hi:[0,1]
	s_nop 0
	v_pk_mul_f32 v[120:121], v[106:107], v[120:121] op_sel:[1,0]
	v_pk_add_f32 v[118:119], v[118:119], v[106:107] op_sel_hi:[1,0] neg_lo:[0,1] neg_hi:[0,1]
	v_mov_b32_e32 v110, v1
	v_mov_b32_e32 v111, v2
	v_mov_b32_e32 v114, v5
	v_mov_b32_e32 v115, v6
	v_pk_fma_f32 v[120:121], v[110:111], v[120:121], v[114:115]
	v_pk_mul_f32 v[106:107], v[106:107], v[118:119] op_sel:[1,0]
	v_mov_b32_e32 v1, v3
	v_mov_b32_e32 v5, v7
	v_and_b32_sdwa v6, v121, v216 dst_sel:DWORD dst_unused:UNUSED_PAD src0_sel:WORD_1 src1_sel:DWORD
	v_and_b32_sdwa v7, v120, v216 dst_sel:DWORD dst_unused:UNUSED_PAD src0_sel:WORD_1 src1_sel:DWORD
	v_pk_fma_f32 v[2:3], v[0:1], v[106:107], v[4:5]
	v_add3_u32 v107, v121, v6, s77
	v_add3_u32 v6, v120, v7, s77
	v_and_b32_e32 v118, 0xffff0000, v6
	v_and_b32_sdwa v6, v3, v216 dst_sel:DWORD dst_unused:UNUSED_PAD src0_sel:WORD_1 src1_sel:DWORD
	v_and_b32_sdwa v7, v2, v216 dst_sel:DWORD dst_unused:UNUSED_PAD src0_sel:WORD_1 src1_sel:DWORD
	v_add3_u32 v6, v3, v6, s77
	v_add3_u32 v119, v2, v7, s77
	v_and_b32_e32 v122, 0xffff0000, v6
	v_or_b32_sdwa v7, v122, v107 dst_sel:DWORD dst_unused:UNUSED_PAD src0_sel:DWORD src1_sel:WORD_1
	v_or_b32_sdwa v6, v119, v118 dst_sel:DWORD dst_unused:UNUSED_PAD src0_sel:WORD_1 src1_sel:DWORD
	v_add_u32_e32 v106, v109, v152
	ds_write_b64 v106, v[6:7]
	v_and_b32_e32 v6, 0xffff0000, v119
	v_sub_u32_e32 v2, v2, v6
	v_sub_u32_e32 v6, v120, v118
	v_and_b32_e32 v7, 0xffff0000, v107
	v_add_u32_e32 v6, 0x80, v6
	v_sub_u32_e32 v7, v121, v7
	v_sub_u32_e32 v3, v3, v122
	v_add_u32_e32 v2, 0x80, v2
	v_ashrrev_i32_e32 v6, 8, v6
	v_add_u32_e32 v7, 0x80, v7
	v_add_u32_e32 v3, 0x80, v3
	v_ashrrev_i32_e32 v2, 8, v2
	v_min_i32_e32 v6, 0x7f, v6
	v_ashrrev_i32_e32 v7, 8, v7
	v_ashrrev_i32_e32 v3, 8, v3
	v_min_i32_e32 v2, 0x7f, v2
	v_min_i32_sdwa v7, v7, s78 dst_sel:WORD_1 dst_unused:UNUSED_PAD src0_sel:DWORD src1_sel:DWORD
	v_min_i32_e32 v3, 0x7f, v3
	v_lshlrev_b32_e32 v6, 8, v6
	v_and_b32_e32 v6, 0xff00, v6
	v_and_b32_e32 v7, 0xff0000, v7
	v_perm_b32 v2, v3, v2, s79
	v_or3_b32 v2, v2, v6, v7
	ds_write_b32 v12, v2 offset:128
	ds_read_b64 v[2:3], v13
	s_waitcnt lgkmcnt(0)
	v_pk_add_f32 v[6:7], v[102:103], v[2:3] op_sel_hi:[1,0] neg_lo:[0,1] neg_hi:[0,1]
	s_nop 0
	v_pk_mul_f32 v[6:7], v[2:3], v[6:7] op_sel:[1,0]
	v_pk_add_f32 v[102:103], v[104:105], v[2:3] op_sel_hi:[1,0] neg_lo:[0,1] neg_hi:[0,1]
	v_pk_fma_f32 v[6:7], v[110:111], v[6:7], v[114:115]
	v_pk_mul_f32 v[2:3], v[2:3], v[102:103] op_sel:[1,0]
	v_and_b32_sdwa v102, v7, v216 dst_sel:DWORD dst_unused:UNUSED_PAD src0_sel:WORD_1 src1_sel:DWORD
	v_and_b32_sdwa v103, v6, v216 dst_sel:DWORD dst_unused:UNUSED_PAD src0_sel:WORD_1 src1_sel:DWORD
	v_pk_fma_f32 v[2:3], v[0:1], v[2:3], v[4:5]
	v_add3_u32 v107, v7, v102, s77
	v_add3_u32 v102, v6, v103, s77
	v_and_b32_e32 v103, 0xffff0000, v102
	v_and_b32_sdwa v102, v3, v216 dst_sel:DWORD dst_unused:UNUSED_PAD src0_sel:WORD_1 src1_sel:DWORD
	v_and_b32_sdwa v104, v2, v216 dst_sel:DWORD dst_unused:UNUSED_PAD src0_sel:WORD_1 src1_sel:DWORD
	v_add3_u32 v102, v3, v102, s77
	v_add3_u32 v118, v2, v104, s77
	v_and_b32_e32 v119, 0xffff0000, v102
	v_or_b32_sdwa v105, v119, v107 dst_sel:DWORD dst_unused:UNUSED_PAD src0_sel:DWORD src1_sel:WORD_1
	v_or_b32_sdwa v104, v118, v103 dst_sel:DWORD dst_unused:UNUSED_PAD src0_sel:WORD_1 src1_sel:DWORD
	v_add_u32_e32 v102, v109, v153
	ds_write_b64 v102, v[104:105]
	v_and_b32_e32 v104, 0xffff0000, v118
	v_sub_u32_e32 v6, v6, v103
	v_and_b32_e32 v103, 0xffff0000, v107
	v_sub_u32_e32 v2, v2, v104
	v_add_u32_e32 v6, 0x80, v6
	v_sub_u32_e32 v7, v7, v103
	v_sub_u32_e32 v3, v3, v119
	v_add_u32_e32 v2, 0x80, v2
	v_ashrrev_i32_e32 v6, 8, v6
	v_add_u32_e32 v7, 0x80, v7
	v_add_u32_e32 v3, 0x80, v3
	v_ashrrev_i32_e32 v2, 8, v2
	v_min_i32_e32 v6, 0x7f, v6
	v_ashrrev_i32_e32 v7, 8, v7
	v_ashrrev_i32_e32 v3, 8, v3
	v_min_i32_e32 v2, 0x7f, v2
	v_min_i32_sdwa v7, v7, s78 dst_sel:WORD_1 dst_unused:UNUSED_PAD src0_sel:DWORD src1_sel:DWORD
	v_min_i32_e32 v3, 0x7f, v3
	v_lshlrev_b32_e32 v6, 8, v6
	v_and_b32_e32 v6, 0xff00, v6
	v_and_b32_e32 v7, 0xff0000, v7
	v_perm_b32 v2, v3, v2, s79
	v_or3_b32 v2, v2, v6, v7
	ds_write_b32 v14, v2 offset:128
	ds_read_b64 v[2:3], v15
	s_waitcnt lgkmcnt(0)
	v_pk_add_f32 v[6:7], v[92:93], v[2:3] op_sel_hi:[1,0] neg_lo:[0,1] neg_hi:[0,1]
	s_nop 0
	v_pk_mul_f32 v[6:7], v[2:3], v[6:7] op_sel:[1,0]
	v_pk_add_f32 v[88:89], v[88:89], v[2:3] op_sel_hi:[1,0] neg_lo:[0,1] neg_hi:[0,1]
	v_pk_fma_f32 v[6:7], v[110:111], v[6:7], v[114:115]
	v_pk_mul_f32 v[2:3], v[2:3], v[88:89] op_sel:[1,0]
	v_and_b32_sdwa v88, v7, v216 dst_sel:DWORD dst_unused:UNUSED_PAD src0_sel:WORD_1 src1_sel:DWORD
	v_and_b32_sdwa v89, v6, v216 dst_sel:DWORD dst_unused:UNUSED_PAD src0_sel:WORD_1 src1_sel:DWORD
	v_pk_fma_f32 v[2:3], v[0:1], v[2:3], v[4:5]
	v_add3_u32 v93, v7, v88, s77
	v_add3_u32 v88, v6, v89, s77
	v_and_b32_e32 v103, 0xffff0000, v88
	v_and_b32_sdwa v88, v3, v216 dst_sel:DWORD dst_unused:UNUSED_PAD src0_sel:WORD_1 src1_sel:DWORD
	v_and_b32_sdwa v89, v2, v216 dst_sel:DWORD dst_unused:UNUSED_PAD src0_sel:WORD_1 src1_sel:DWORD
	v_add3_u32 v88, v3, v88, s77
	v_add3_u32 v104, v2, v89, s77
	v_and_b32_e32 v105, 0xffff0000, v88
	v_or_b32_sdwa v89, v105, v93 dst_sel:DWORD dst_unused:UNUSED_PAD src0_sel:DWORD src1_sel:WORD_1
	v_or_b32_sdwa v88, v104, v103 dst_sel:DWORD dst_unused:UNUSED_PAD src0_sel:WORD_1 src1_sel:DWORD
	v_add_u32_e32 v92, v109, v137
	ds_write_b64 v92, v[88:89]
	v_and_b32_e32 v88, 0xffff0000, v104
	v_sub_u32_e32 v2, v2, v88
	v_sub_u32_e32 v6, v6, v103
	v_and_b32_e32 v88, 0xffff0000, v93
	v_add_u32_e32 v6, 0x80, v6
	v_sub_u32_e32 v7, v7, v88
	v_sub_u32_e32 v3, v3, v105
	v_add_u32_e32 v2, 0x80, v2
	v_ashrrev_i32_e32 v6, 8, v6
	v_add_u32_e32 v7, 0x80, v7
	v_add_u32_e32 v3, 0x80, v3
	v_ashrrev_i32_e32 v2, 8, v2
	v_min_i32_e32 v6, 0x7f, v6
	v_ashrrev_i32_e32 v7, 8, v7
	v_ashrrev_i32_e32 v3, 8, v3
	v_min_i32_e32 v2, 0x7f, v2
	v_min_i32_sdwa v7, v7, s78 dst_sel:WORD_1 dst_unused:UNUSED_PAD src0_sel:DWORD src1_sel:DWORD
	v_min_i32_e32 v3, 0x7f, v3
	v_lshlrev_b32_e32 v6, 8, v6
	v_and_b32_e32 v6, 0xff00, v6
	v_and_b32_e32 v7, 0xff0000, v7
	v_perm_b32 v2, v3, v2, s79
	v_or3_b32 v2, v2, v6, v7
	ds_write_b32 v18, v2 offset:128
	ds_read_b64 v[2:3], v19
	v_add_u32_e32 v93, v109, v136
	s_waitcnt lgkmcnt(0)
;     ...
;             _Pragma("unroll") for (int m = 0; m < 4; ++m) {
;               const int rr = wr3 * 64 + m * 16 + fr3;
;               const float2 ms = *reinterpret_cast<const float2*>(mr + (ai * HALF + rr) * 2);
;               f32x4 y = acc[ai][bj][m][n];
;               const float o0 = (y[0] - ms.x) * ms.y * gm.x + bt.x, o1 = (y[1] - ms.x) * ms.y * gm.y + bt.y;
;               const float o2 = (y[2] - ms.x) * ms.y * gm.z + bt.z, o3 = (y[3] - ms.x) * ms.y * gm.w + bt.w;
;               const unsigned h0 = f2bf(o0), h1 = f2bf(o1), h2 = f2bf(o2), h3 = f2bf(o3);
;               u32x2 ob; ob[0] = h0 | (h1 << 16); ob[1] = h2 | (h3 << 16);
;               *reinterpret_cast<u32x2*>(smem + (rr >> 1) * PIECE + (rr & 1) * 512 + cc * 2) = ob;
;               const int l0 = min(((int)__float_as_uint(o0) - (int)(h0 << 16) + 128) >> 8, 127);
;               const int l1 = min(((int)__float_as_uint(o1) - (int)(h1 << 16) + 128) >> 8, 127);
;               const int l2 = min(((int)__float_as_uint(o2) - (int)(h2 << 16) + 128) >> 8, 127);
;               const int l3 = min(((int)__float_as_uint(o3) - (int)(h3 << 16) + 128) >> 8, 127);
;               *reinterpret_cast<unsigned*>(smem + LOBASE + (rr >> 2) * PIECE + (rr & 3) * 256 + cc) =
;                   (unsigned)(l0 & 255) | ((unsigned)(l1 & 255) << 8) | ((unsigned)(l2 & 255) << 16) | ((unsigned)l3 << 24);
;             }
	v_pk_add_f32 v[6:7], v[90:91], v[2:3] op_sel_hi:[1,0] neg_lo:[0,1] neg_hi:[0,1]
	s_nop 0
	v_pk_mul_f32 v[6:7], v[2:3], v[6:7] op_sel:[1,0]
	v_pk_add_f32 v[88:89], v[94:95], v[2:3] op_sel_hi:[1,0] neg_lo:[0,1] neg_hi:[0,1]
	v_pk_fma_f32 v[6:7], v[110:111], v[6:7], v[114:115]
	v_pk_mul_f32 v[2:3], v[2:3], v[88:89] op_sel:[1,0]
	s_nop 0
	v_pk_fma_f32 v[0:1], v[0:1], v[2:3], v[4:5]
	v_and_b32_sdwa v2, v7, v216 dst_sel:DWORD dst_unused:UNUSED_PAD src0_sel:WORD_1 src1_sel:DWORD
	v_and_b32_sdwa v3, v6, v216 dst_sel:DWORD dst_unused:UNUSED_PAD src0_sel:WORD_1 src1_sel:DWORD
	v_add3_u32 v4, v7, v2, s77
	v_add3_u32 v2, v6, v3, s77
	v_and_b32_e32 v5, 0xffff0000, v2
	v_and_b32_sdwa v2, v1, v216 dst_sel:DWORD dst_unused:UNUSED_PAD src0_sel:WORD_1 src1_sel:DWORD
	v_and_b32_sdwa v3, v0, v216 dst_sel:DWORD dst_unused:UNUSED_PAD src0_sel:WORD_1 src1_sel:DWORD
	v_add3_u32 v2, v1, v2, s77
	v_add3_u32 v88, v0, v3, s77
	v_and_b32_e32 v89, 0xffff0000, v2
	v_or_b32_sdwa v3, v89, v4 dst_sel:DWORD dst_unused:UNUSED_PAD src0_sel:DWORD src1_sel:WORD_1
	v_or_b32_sdwa v2, v88, v5 dst_sel:DWORD dst_unused:UNUSED_PAD src0_sel:WORD_1 src1_sel:DWORD
	ds_write_b64 v93, v[2:3]
	v_and_b32_e32 v2, 0xffff0000, v88
	v_sub_u32_e32 v0, v0, v2
	v_sub_u32_e32 v2, v6, v5
	v_and_b32_e32 v3, 0xffff0000, v4
	v_add_u32_e32 v2, 0x80, v2
	v_sub_u32_e32 v3, v7, v3
	v_sub_u32_e32 v1, v1, v89
	v_add_u32_e32 v0, 0x80, v0
	v_ashrrev_i32_e32 v2, 8, v2
	v_add_u32_e32 v3, 0x80, v3
	v_add_u32_e32 v1, 0x80, v1
	v_ashrrev_i32_e32 v0, 8, v0
	v_min_i32_e32 v2, 0x7f, v2
	v_ashrrev_i32_e32 v3, 8, v3
	v_ashrrev_i32_e32 v1, 8, v1
	v_min_i32_e32 v0, 0x7f, v0
	v_min_i32_sdwa v3, v3, s78 dst_sel:WORD_1 dst_unused:UNUSED_PAD src0_sel:DWORD src1_sel:DWORD
	v_min_i32_e32 v1, 0x7f, v1
	v_lshlrev_b32_e32 v2, 8, v2
	v_and_b32_e32 v2, 0xff00, v2
	v_and_b32_e32 v3, 0xff0000, v3
	v_perm_b32 v0, v1, v0, s79
	v_or3_b32 v0, v0, v2, v3
	ds_write_b32 v22, v0 offset:128
	v_mov_b32_e32 v0, v232
	v_mov_b32_e32 v1, v233
	v_mov_b32_e32 v2, v234
	v_mov_b32_e32 v3, v235
	v_mov_b32_e32 v4, v248
	v_mov_b32_e32 v5, v249
	v_mov_b32_e32 v6, v250
	v_mov_b32_e32 v7, v251
	ds_read_b64 v[94:95], v149
	s_waitcnt lgkmcnt(0)
	v_pk_add_f32 v[104:105], v[116:117], v[94:95] op_sel_hi:[1,0] neg_lo:[0,1] neg_hi:[0,1]
	s_nop 0
	v_pk_mul_f32 v[104:105], v[94:95], v[104:105] op_sel:[1,0]
	v_pk_add_f32 v[110:111], v[112:113], v[94:95] op_sel_hi:[1,0] neg_lo:[0,1] neg_hi:[0,1]
	v_mov_b32_e32 v88, v1
	v_mov_b32_e32 v89, v2
	v_mov_b32_e32 v90, v5
	v_mov_b32_e32 v91, v6
	v_pk_fma_f32 v[104:105], v[88:89], v[104:105], v[90:91]
	v_pk_mul_f32 v[94:95], v[94:95], v[110:111] op_sel:[1,0]
	v_mov_b32_e32 v1, v3
	v_mov_b32_e32 v5, v7
	v_pk_fma_f32 v[6:7], v[0:1], v[94:95], v[4:5]
	v_and_b32_sdwa v94, v104, v216 dst_sel:DWORD dst_unused:UNUSED_PAD src0_sel:WORD_1 src1_sel:DWORD
	v_add3_u32 v94, v104, v94, s77
	v_and_b32_e32 v95, 0xffff0000, v94
	v_and_b32_sdwa v94, v7, v216 dst_sel:DWORD dst_unused:UNUSED_PAD src0_sel:WORD_1 src1_sel:DWORD
	v_and_b32_sdwa v3, v105, v216 dst_sel:DWORD dst_unused:UNUSED_PAD src0_sel:WORD_1 src1_sel:DWORD
	v_and_b32_sdwa v103, v6, v216 dst_sel:DWORD dst_unused:UNUSED_PAD src0_sel:WORD_1 src1_sel:DWORD
	v_add3_u32 v94, v7, v94, s77
	v_add3_u32 v3, v105, v3, s77
	v_add3_u32 v103, v6, v103, s77
	v_and_b32_e32 v107, 0xffff0000, v94
	v_or_b32_sdwa v111, v107, v3 dst_sel:DWORD dst_unused:UNUSED_PAD src0_sel:DWORD src1_sel:WORD_1
	v_or_b32_sdwa v110, v103, v95 dst_sel:DWORD dst_unused:UNUSED_PAD src0_sel:WORD_1 src1_sel:DWORD
	v_and_b32_e32 v103, 0xffff0000, v103
	v_sub_u32_e32 v95, v104, v95
	v_and_b32_e32 v3, 0xffff0000, v3
	v_sub_u32_e32 v6, v6, v103
	v_add_u32_e32 v95, 0x80, v95
	v_sub_u32_e32 v3, v105, v3
	v_sub_u32_e32 v7, v7, v107
	v_add_u32_e32 v6, 0x80, v6
	v_ashrrev_i32_e32 v95, 8, v95
	v_add_u32_e32 v3, 0x80, v3
	v_add_u32_e32 v7, 0x80, v7
	v_ashrrev_i32_e32 v6, 8, v6
	v_min_i32_e32 v95, 0x7f, v95
	v_ashrrev_i32_e32 v3, 8, v3
	v_ashrrev_i32_e32 v7, 8, v7
	v_min_i32_e32 v6, 0x7f, v6
	v_min_i32_sdwa v3, v3, s78 dst_sel:WORD_1 dst_unused:UNUSED_PAD src0_sel:DWORD src1_sel:DWORD
	v_min_i32_e32 v7, 0x7f, v7
	v_lshlrev_b32_e32 v95, 8, v95
	v_or_b32_e32 v2, 0x120, v154
	v_and_b32_e32 v95, 0xff00, v95
	v_and_b32_e32 v3, 0xff0000, v3
	v_perm_b32 v6, v7, v6, s79
	v_add_u32_e32 v94, v2, v152
	v_or3_b32 v3, v6, v95, v3
	ds_write_b64 v94, v[110:111]
	ds_write_b32 v12, v3 offset:144
	ds_read_b64 v[6:7], v13
	s_waitcnt lgkmcnt(0)
	v_pk_add_f32 v[100:101], v[100:101], v[6:7] op_sel_hi:[1,0] neg_lo:[0,1] neg_hi:[0,1]
	s_nop 0
	v_pk_mul_f32 v[100:101], v[6:7], v[100:101] op_sel:[1,0]
	v_pk_add_f32 v[96:97], v[96:97], v[6:7] op_sel_hi:[1,0] neg_lo:[0,1] neg_hi:[0,1]
	v_pk_fma_f32 v[100:101], v[88:89], v[100:101], v[90:91]
	v_pk_mul_f32 v[6:7], v[6:7], v[96:97] op_sel:[1,0]
	v_and_b32_sdwa v95, v100, v216 dst_sel:DWORD dst_unused:UNUSED_PAD src0_sel:WORD_1 src1_sel:DWORD
	v_pk_fma_f32 v[6:7], v[0:1], v[6:7], v[4:5]
	v_add3_u32 v95, v100, v95, s77
	v_and_b32_e32 v103, 0xffff0000, v95
	v_and_b32_sdwa v95, v7, v216 dst_sel:DWORD dst_unused:UNUSED_PAD src0_sel:WORD_1 src1_sel:DWORD
	v_and_b32_sdwa v3, v101, v216 dst_sel:DWORD dst_unused:UNUSED_PAD src0_sel:WORD_1 src1_sel:DWORD
	v_and_b32_sdwa v96, v6, v216 dst_sel:DWORD dst_unused:UNUSED_PAD src0_sel:WORD_1 src1_sel:DWORD
	v_add3_u32 v95, v7, v95, s77
	v_add3_u32 v3, v101, v3, s77
	v_add3_u32 v104, v6, v96, s77
	v_and_b32_e32 v105, 0xffff0000, v95
	v_or_b32_sdwa v97, v105, v3 dst_sel:DWORD dst_unused:UNUSED_PAD src0_sel:DWORD src1_sel:WORD_1
	v_or_b32_sdwa v96, v104, v103 dst_sel:DWORD dst_unused:UNUSED_PAD src0_sel:WORD_1 src1_sel:DWORD
	v_add_u32_e32 v95, v2, v153
	ds_write_b64 v95, v[96:97]
	v_and_b32_e32 v96, 0xffff0000, v104
	v_sub_u32_e32 v6, v6, v96
	v_sub_u32_e32 v96, v100, v103
	v_and_b32_e32 v3, 0xffff0000, v3
	v_add_u32_e32 v96, 0x80, v96
	v_sub_u32_e32 v3, v101, v3
	v_sub_u32_e32 v7, v7, v105
	v_add_u32_e32 v6, 0x80, v6
	v_ashrrev_i32_e32 v96, 8, v96
	v_add_u32_e32 v3, 0x80, v3
	v_add_u32_e32 v7, 0x80, v7
	v_ashrrev_i32_e32 v6, 8, v6
	v_min_i32_e32 v96, 0x7f, v96
	v_ashrrev_i32_e32 v3, 8, v3
	v_ashrrev_i32_e32 v7, 8, v7
	v_min_i32_e32 v6, 0x7f, v6
	v_min_i32_sdwa v3, v3, s78 dst_sel:WORD_1 dst_unused:UNUSED_PAD src0_sel:DWORD src1_sel:DWORD
	v_min_i32_e32 v7, 0x7f, v7
	v_lshlrev_b32_e32 v96, 8, v96
	v_and_b32_e32 v96, 0xff00, v96
	v_and_b32_e32 v3, 0xff0000, v3
	v_perm_b32 v6, v7, v6, s79
	v_or3_b32 v3, v6, v96, v3
	ds_write_b32 v14, v3 offset:144
	ds_read_b64 v[6:7], v15
	s_waitcnt lgkmcnt(0)
; #define WAIT_L(n) asm volatile("s_waitcnt lgkmcnt(" #n ")" ::: "memory")
; #define BAR __builtin_amdgcn_s_barrier()
;     ...
;             _Pragma("unroll") for (int m = 0; m < 4; ++m) {
;               const int rr = wr3 * 64 + m * 16 + fr3;
;               const float2 ms = *reinterpret_cast<const float2*>(mr + (ai * HALF + rr) * 2);
;               f32x4 y = acc[ai][bj][m][n];
;               const float o0 = (y[0] - ms.x) * ms.y * gm.x + bt.x, o1 = (y[1] - ms.x) * ms.y * gm.y + bt.y;
;               const float o2 = (y[2] - ms.x) * ms.y * gm.z + bt.z, o3 = (y[3] - ms.x) * ms.y * gm.w + bt.w;
;               const unsigned h0 = f2bf(o0), h1 = f2bf(o1), h2 = f2bf(o2), h3 = f2bf(o3);
;               u32x2 ob; ob[0] = h0 | (h1 << 16); ob[1] = h2 | (h3 << 16);
;               *reinterpret_cast<u32x2*>(smem + (rr >> 1) * PIECE + (rr & 1) * 512 + cc * 2) = ob;
;               const int l0 = min(((int)__float_as_uint(o0) - (int)(h0 << 16) + 128) >> 8, 127);
;               const int l1 = min(((int)__float_as_uint(o1) - (int)(h1 << 16) + 128) >> 8, 127);
;               const int l2 = min(((int)__float_as_uint(o2) - (int)(h2 << 16) + 128) >> 8, 127);
;               const int l3 = min(((int)__float_as_uint(o3) - (int)(h3 << 16) + 128) >> 8, 127);
;               *reinterpret_cast<unsigned*>(smem + LOBASE + (rr >> 2) * PIECE + (rr & 3) * 256 + cc) =
;                   (unsigned)(l0 & 255) | ((unsigned)(l1 & 255) << 8) | ((unsigned)(l2 & 255) << 16) | ((unsigned)l3 << 24);
;             }
;           }
;           WAIT_L(0); BAR;
;           const int hso = ((brow + ai * HALF + 16 * wave) * DM + pn * BM) * 2;
;           const int lso = (brow + ai * HALF + 16 * wave) * DM + pn * BM;
;           _Pragma("unroll") for (int i = 0; i < 8; ++i) {
;             const u32x4 v = *reinterpret_cast<const u32x4*>(smem + (wave * 8 + i) * PIECE + lane3 * 16);
;             __builtin_amdgcn_raw_buffer_store_b128(v, rsXB, hvo + i * (2 * DM * 2), hso, 0);
;           }
;           _Pragma("unroll") for (int i = 0; i < 4; ++i) {
;             const u32x4 v = *reinterpret_cast<const u32x4*>(smem + LOBASE + (wave * 4 + i) * PIECE + lane3 * 16);
;             __builtin_amdgcn_raw_buffer_store_b128(v, rsLO, lvo + i * (4 * DM), lso, 0);
	v_pk_add_f32 v[84:85], v[84:85], v[6:7] op_sel_hi:[1,0] neg_lo:[0,1] neg_hi:[0,1]
	s_nop 0
	v_pk_mul_f32 v[84:85], v[6:7], v[84:85] op_sel:[1,0]
	v_pk_add_f32 v[80:81], v[80:81], v[6:7] op_sel_hi:[1,0] neg_lo:[0,1] neg_hi:[0,1]
	v_pk_fma_f32 v[84:85], v[88:89], v[84:85], v[90:91]
	v_pk_mul_f32 v[6:7], v[6:7], v[80:81] op_sel:[1,0]
	v_and_b32_sdwa v80, v84, v216 dst_sel:DWORD dst_unused:UNUSED_PAD src0_sel:WORD_1 src1_sel:DWORD
	v_pk_fma_f32 v[6:7], v[0:1], v[6:7], v[4:5]
	v_add3_u32 v80, v84, v80, s77
	v_and_b32_e32 v81, 0xffff0000, v80
	v_and_b32_sdwa v80, v7, v216 dst_sel:DWORD dst_unused:UNUSED_PAD src0_sel:WORD_1 src1_sel:DWORD
	v_and_b32_sdwa v3, v85, v216 dst_sel:DWORD dst_unused:UNUSED_PAD src0_sel:WORD_1 src1_sel:DWORD
	v_and_b32_sdwa v96, v6, v216 dst_sel:DWORD dst_unused:UNUSED_PAD src0_sel:WORD_1 src1_sel:DWORD
	v_add3_u32 v80, v7, v80, s77
	v_add3_u32 v3, v85, v3, s77
	v_add3_u32 v100, v6, v96, s77
	v_and_b32_e32 v101, 0xffff0000, v80
	v_or_b32_sdwa v97, v101, v3 dst_sel:DWORD dst_unused:UNUSED_PAD src0_sel:DWORD src1_sel:WORD_1
	v_or_b32_sdwa v96, v100, v81 dst_sel:DWORD dst_unused:UNUSED_PAD src0_sel:WORD_1 src1_sel:DWORD
	v_add_u32_e32 v80, v2, v137
	ds_write_b64 v80, v[96:97]
	v_and_b32_e32 v96, 0xffff0000, v100
	v_sub_u32_e32 v81, v84, v81
	v_and_b32_e32 v3, 0xffff0000, v3
	v_sub_u32_e32 v6, v6, v96
	v_add_u32_e32 v81, 0x80, v81
	v_sub_u32_e32 v3, v85, v3
	v_sub_u32_e32 v7, v7, v101
	v_add_u32_e32 v6, 0x80, v6
	v_ashrrev_i32_e32 v81, 8, v81
	v_add_u32_e32 v3, 0x80, v3
	v_add_u32_e32 v7, 0x80, v7
	v_ashrrev_i32_e32 v6, 8, v6
	v_min_i32_e32 v81, 0x7f, v81
	v_ashrrev_i32_e32 v3, 8, v3
	v_ashrrev_i32_e32 v7, 8, v7
	v_min_i32_e32 v6, 0x7f, v6
	v_min_i32_sdwa v3, v3, s78 dst_sel:WORD_1 dst_unused:UNUSED_PAD src0_sel:DWORD src1_sel:DWORD
	v_min_i32_e32 v7, 0x7f, v7
	v_lshlrev_b32_e32 v81, 8, v81
	v_and_b32_e32 v81, 0xff00, v81
	v_and_b32_e32 v3, 0xff0000, v3
	v_perm_b32 v6, v7, v6, s79
	v_or3_b32 v3, v6, v81, v3
	ds_write_b32 v18, v3 offset:144
	ds_read_b64 v[6:7], v19
	v_or_b32_e32 v81, 0x6000, v148
	v_or_b32_e32 v96, 0x6000, v146
	s_waitcnt lgkmcnt(0)
	v_pk_add_f32 v[72:73], v[72:73], v[6:7] op_sel_hi:[1,0] neg_lo:[0,1] neg_hi:[0,1]
	s_nop 0
	v_pk_mul_f32 v[72:73], v[6:7], v[72:73] op_sel:[1,0]
	s_nop 0
	v_pk_fma_f32 v[84:85], v[88:89], v[72:73], v[90:91]
	v_pk_add_f32 v[72:73], v[74:75], v[6:7] op_sel_hi:[1,0] neg_lo:[0,1] neg_hi:[0,1]
	v_and_b32_sdwa v3, v85, v216 dst_sel:DWORD dst_unused:UNUSED_PAD src0_sel:WORD_1 src1_sel:DWORD
	v_pk_mul_f32 v[6:7], v[6:7], v[72:73] op_sel:[1,0]
	v_add3_u32 v3, v85, v3, s77
	v_pk_fma_f32 v[0:1], v[0:1], v[6:7], v[4:5]
	v_and_b32_sdwa v4, v84, v216 dst_sel:DWORD dst_unused:UNUSED_PAD src0_sel:WORD_1 src1_sel:DWORD
	v_add3_u32 v4, v84, v4, s77
	v_and_b32_e32 v6, 0xffff0000, v4
	v_and_b32_sdwa v4, v1, v216 dst_sel:DWORD dst_unused:UNUSED_PAD src0_sel:WORD_1 src1_sel:DWORD
	v_and_b32_sdwa v5, v0, v216 dst_sel:DWORD dst_unused:UNUSED_PAD src0_sel:WORD_1 src1_sel:DWORD
	v_add3_u32 v4, v1, v4, s77
	v_add3_u32 v7, v0, v5, s77
	v_and_b32_e32 v72, 0xffff0000, v4
	v_add_u32_e32 v73, v2, v136
	v_and_b32_e32 v2, 0xffff0000, v7
	v_or_b32_sdwa v5, v72, v3 dst_sel:DWORD dst_unused:UNUSED_PAD src0_sel:DWORD src1_sel:WORD_1
	v_sub_u32_e32 v0, v0, v2
	v_sub_u32_e32 v2, v84, v6
	v_and_b32_e32 v3, 0xffff0000, v3
	v_add_u32_e32 v2, 0x80, v2
	v_sub_u32_e32 v3, v85, v3
	v_sub_u32_e32 v1, v1, v72
	v_add_u32_e32 v0, 0x80, v0
	v_ashrrev_i32_e32 v2, 8, v2
	v_add_u32_e32 v3, 0x80, v3
	v_add_u32_e32 v1, 0x80, v1
	v_ashrrev_i32_e32 v0, 8, v0
	v_min_i32_e32 v2, 0x7f, v2
	v_ashrrev_i32_e32 v3, 8, v3
	v_ashrrev_i32_e32 v1, 8, v1
	v_min_i32_e32 v0, 0x7f, v0
	v_min_i32_sdwa v3, v3, s78 dst_sel:WORD_1 dst_unused:UNUSED_PAD src0_sel:DWORD src1_sel:DWORD
	v_min_i32_e32 v1, 0x7f, v1
	v_lshlrev_b32_e32 v2, 8, v2
	v_and_b32_e32 v2, 0xff00, v2
	v_and_b32_e32 v3, 0xff0000, v3
	v_perm_b32 v0, v1, v0, s79
	v_or_b32_sdwa v4, v7, v6 dst_sel:DWORD dst_unused:UNUSED_PAD src0_sel:WORD_1 src1_sel:DWORD
	v_or3_b32 v0, v0, v2, v3
	ds_write_b64 v73, v[4:5]
	ds_write_b32 v22, v0 offset:144
	v_add_u32_e32 v72, s59, v151
	s_waitcnt lgkmcnt(0)
	s_barrier
	ds_read_b128 v[128:131], v72
	v_or_b32_e32 v74, 0x2000, v148
	v_or_b32_e32 v75, 0x4000, v148
	v_or_b32_e32 v84, 0x8000, v148
	v_or_b32_e32 v85, 0xa000, v148
	ds_read_b128 v[136:139], v72 offset:1040
	v_or_b32_e32 v88, 0xc000, v148
	v_or_b32_e32 v89, 0xe000, v148
	v_or_b32_e32 v90, 0x2000, v146
	v_or_b32_e32 v91, 0x4000, v146
	ds_read_b128 v[140:143], v72 offset:2080
	ds_read_b128 v[152:155], v72 offset:3120
	ds_read_b128 v[156:159], v72 offset:4160
	ds_read_b128 v[160:163], v72 offset:5200
	ds_read_b128 v[164:167], v72 offset:6240
	ds_read_b128 v[168:171], v72 offset:7280
	ds_read_b128 v[172:175], v147
	ds_read_b128 v[176:179], v147 offset:1040
	ds_read_b128 v[180:183], v147 offset:2080
	ds_read_b128 v[184:187], v147 offset:3120
	s_waitcnt lgkmcnt(0)
	s_barrier
;     ...
;           _Pragma("unroll") for (int bj = 0; bj < 2; ++bj) _Pragma("unroll") for (int n = 0; n < 2; ++n) {
;             const int cc = bj * HALF + wc3 * 32 + n * 16 + fq3 * 4;
;             const float4 gm = *reinterpret_cast<const float4*>(g.gam + pn * BM + cc), bt = *reinterpret_cast<const float4*>(g.bet + pn * BM + cc);
;             _Pragma("unroll") for (int m = 0; m < 4; ++m) {
;               const int rr = wr3 * 64 + m * 16 + fr3;
;               const float2 ms = *reinterpret_cast<const float2*>(mr + (ai * HALF + rr) * 2);
;               f32x4 y = acc[ai][bj][m][n];
;               const float o0 = (y[0] - ms.x) * ms.y * gm.x + bt.x, o1 = (y[1] - ms.x) * ms.y * gm.y + bt.y;
;               const float o2 = (y[2] - ms.x) * ms.y * gm.z + bt.z, o3 = (y[3] - ms.x) * ms.y * gm.w + bt.w;
;               const unsigned h0 = f2bf(o0), h1 = f2bf(o1), h2 = f2bf(o2), h3 = f2bf(o3);
;               u32x2 ob; ob[0] = h0 | (h1 << 16); ob[1] = h2 | (h3 << 16);
;               *reinterpret_cast<u32x2*>(smem + (rr >> 1) * PIECE + (rr & 1) * 512 + cc * 2) = ob;
;               const int l0 = min(((int)__float_as_uint(o0) - (int)(h0 << 16) + 128) >> 8, 127);
;               const int l1 = min(((int)__float_as_uint(o1) - (int)(h1 << 16) + 128) >> 8, 127);
;               const int l2 = min(((int)__float_as_uint(o2) - (int)(h2 << 16) + 128) >> 8, 127);
;               const int l3 = min(((int)__float_as_uint(o3) - (int)(h3 << 16) + 128) >> 8, 127);
;               *reinterpret_cast<unsigned*>(smem + LOBASE + (rr >> 2) * PIECE + (rr & 3) * 256 + cc) =
;                   (unsigned)(l0 & 255) | ((unsigned)(l1 & 255) << 8) | ((unsigned)(l2 & 255) << 16) | ((unsigned)l3 << 24);
;             }
;           }
;           WAIT_L(0); BAR;
;           const int hso = ((brow + ai * HALF + 16 * wave) * DM + pn * BM) * 2;
;           const int lso = (brow + ai * HALF + 16 * wave) * DM + pn * BM;
;           _Pragma("unroll") for (int i = 0; i < 8; ++i) {
;             const u32x4 v = *reinterpret_cast<const u32x4*>(smem + (wave * 8 + i) * PIECE + lane3 * 16);
;             __builtin_amdgcn_raw_buffer_store_b128(v, rsXB, hvo + i * (2 * DM * 2), hso, 0);
;           }
;           _Pragma("unroll") for (int i = 0; i < 4; ++i) {
;             const u32x4 v = *reinterpret_cast<const u32x4*>(smem + LOBASE + (wave * 4 + i) * PIECE + lane3 * 16);
	s_nop 1
	v_mov_b32_e32 v0, v220
	v_mov_b32_e32 v1, v221
	v_mov_b32_e32 v2, v222
	v_mov_b32_e32 v3, v223
	v_mov_b32_e32 v4, v236
	v_mov_b32_e32 v5, v237
	v_mov_b32_e32 v6, v238
	v_mov_b32_e32 v7, v239
	ds_read_b64 v[110:111], v149 offset:1024
	s_waitcnt lgkmcnt(0)
	v_pk_add_f32 v[64:65], v[64:65], v[110:111] op_sel_hi:[1,0] neg_lo:[0,1] neg_hi:[0,1]
	s_nop 0
	v_pk_mul_f32 v[64:65], v[110:111], v[64:65] op_sel:[1,0]
	v_pk_add_f32 v[66:67], v[66:67], v[110:111] op_sel_hi:[1,0] neg_lo:[0,1] neg_hi:[0,1]
	v_mov_b32_e32 v100, v1
	v_mov_b32_e32 v101, v2
	v_mov_b32_e32 v104, v5
	v_mov_b32_e32 v105, v6
	v_pk_fma_f32 v[64:65], v[100:101], v[64:65], v[104:105]
	v_pk_mul_f32 v[66:67], v[110:111], v[66:67] op_sel:[1,0]
	v_mov_b32_e32 v1, v3
	v_mov_b32_e32 v5, v7
	v_and_b32_sdwa v6, v65, v216 dst_sel:DWORD dst_unused:UNUSED_PAD src0_sel:WORD_1 src1_sel:DWORD
	v_and_b32_sdwa v7, v64, v216 dst_sel:DWORD dst_unused:UNUSED_PAD src0_sel:WORD_1 src1_sel:DWORD
	v_pk_fma_f32 v[2:3], v[0:1], v[66:67], v[4:5]
	v_add3_u32 v66, v65, v6, s77
	v_add3_u32 v6, v64, v7, s77
	v_and_b32_e32 v67, 0xffff0000, v6
	v_and_b32_sdwa v6, v3, v216 dst_sel:DWORD dst_unused:UNUSED_PAD src0_sel:WORD_1 src1_sel:DWORD
	v_and_b32_sdwa v7, v2, v216 dst_sel:DWORD dst_unused:UNUSED_PAD src0_sel:WORD_1 src1_sel:DWORD
	v_add3_u32 v6, v3, v6, s77
	v_add3_u32 v97, v2, v7, s77
	v_and_b32_e32 v103, 0xffff0000, v6
	v_or_b32_sdwa v7, v103, v66 dst_sel:DWORD dst_unused:UNUSED_PAD src0_sel:DWORD src1_sel:WORD_1
	v_or_b32_sdwa v6, v97, v67 dst_sel:DWORD dst_unused:UNUSED_PAD src0_sel:WORD_1 src1_sel:DWORD
	ds_write_b64 v132, v[6:7]
	v_and_b32_e32 v6, 0xffff0000, v97
	v_sub_u32_e32 v2, v2, v6
	v_sub_u32_e32 v6, v64, v67
	v_and_b32_e32 v7, 0xffff0000, v66
	v_add_u32_e32 v6, 0x80, v6
	v_sub_u32_e32 v7, v65, v7
	v_sub_u32_e32 v3, v3, v103
	v_add_u32_e32 v2, 0x80, v2
	v_ashrrev_i32_e32 v6, 8, v6
	v_add_u32_e32 v7, 0x80, v7
	v_add_u32_e32 v3, 0x80, v3
	v_ashrrev_i32_e32 v2, 8, v2
	v_min_i32_e32 v6, 0x7f, v6
	v_ashrrev_i32_e32 v7, 8, v7
	v_ashrrev_i32_e32 v3, 8, v3
	v_min_i32_e32 v2, 0x7f, v2
	v_min_i32_sdwa v7, v7, s78 dst_sel:WORD_1 dst_unused:UNUSED_PAD src0_sel:DWORD src1_sel:DWORD
	v_min_i32_e32 v3, 0x7f, v3
	v_lshlrev_b32_e32 v6, 8, v6
	v_and_b32_e32 v6, 0xff00, v6
	v_and_b32_e32 v7, 0xff0000, v7
	v_perm_b32 v2, v3, v2, s79
	v_or3_b32 v2, v2, v6, v7
	ds_write_b32 v12, v2
	buffer_store_dwordx4 v[128:131], v148, s[16:19], s76 offen
	ds_read_b64 v[2:3], v13 offset:1024
	s_waitcnt lgkmcnt(0)
	v_pk_add_f32 v[6:7], v[68:69], v[2:3] op_sel_hi:[1,0] neg_lo:[0,1] neg_hi:[0,1]
	s_nop 0
	v_pk_mul_f32 v[6:7], v[2:3], v[6:7] op_sel:[1,0]
	v_pk_add_f32 v[64:65], v[70:71], v[2:3] op_sel_hi:[1,0] neg_lo:[0,1] neg_hi:[0,1]
	v_pk_fma_f32 v[6:7], v[100:101], v[6:7], v[104:105]
	v_pk_mul_f32 v[2:3], v[2:3], v[64:65] op_sel:[1,0]
	v_and_b32_sdwa v64, v7, v216 dst_sel:DWORD dst_unused:UNUSED_PAD src0_sel:WORD_1 src1_sel:DWORD
	v_and_b32_sdwa v65, v6, v216 dst_sel:DWORD dst_unused:UNUSED_PAD src0_sel:WORD_1 src1_sel:DWORD
	v_pk_fma_f32 v[2:3], v[0:1], v[2:3], v[4:5]
	v_add3_u32 v66, v7, v64, s77
	v_add3_u32 v64, v6, v65, s77
	v_and_b32_e32 v67, 0xffff0000, v64
	v_and_b32_sdwa v64, v3, v216 dst_sel:DWORD dst_unused:UNUSED_PAD src0_sel:WORD_1 src1_sel:DWORD
	v_and_b32_sdwa v65, v2, v216 dst_sel:DWORD dst_unused:UNUSED_PAD src0_sel:WORD_1 src1_sel:DWORD
	v_add3_u32 v64, v3, v64, s77
	v_add3_u32 v68, v2, v65, s77
	v_and_b32_e32 v69, 0xffff0000, v64
	v_or_b32_sdwa v65, v69, v66 dst_sel:DWORD dst_unused:UNUSED_PAD src0_sel:DWORD src1_sel:WORD_1
	v_or_b32_sdwa v64, v68, v67 dst_sel:DWORD dst_unused:UNUSED_PAD src0_sel:WORD_1 src1_sel:DWORD
	ds_write_b64 v133, v[64:65]
	v_and_b32_e32 v64, 0xffff0000, v68
	v_sub_u32_e32 v2, v2, v64
	v_sub_u32_e32 v6, v6, v67
	v_and_b32_e32 v64, 0xffff0000, v66
	v_add_u32_e32 v6, 0x80, v6
	v_sub_u32_e32 v7, v7, v64
	v_sub_u32_e32 v3, v3, v69
	v_add_u32_e32 v2, 0x80, v2
	v_ashrrev_i32_e32 v6, 8, v6
	v_add_u32_e32 v7, 0x80, v7
	v_add_u32_e32 v3, 0x80, v3
	v_ashrrev_i32_e32 v2, 8, v2
	v_min_i32_e32 v6, 0x7f, v6
	v_ashrrev_i32_e32 v7, 8, v7
	v_ashrrev_i32_e32 v3, 8, v3
	v_min_i32_e32 v2, 0x7f, v2
	v_min_i32_sdwa v7, v7, s78 dst_sel:WORD_1 dst_unused:UNUSED_PAD src0_sel:DWORD src1_sel:DWORD
	v_min_i32_e32 v3, 0x7f, v3
	v_lshlrev_b32_e32 v6, 8, v6
	v_and_b32_e32 v6, 0xff00, v6
	v_and_b32_e32 v7, 0xff0000, v7
	v_perm_b32 v2, v3, v2, s79
	v_or3_b32 v2, v2, v6, v7
	ds_write_b32 v14, v2
	buffer_store_dwordx4 v[136:139], v74, s[16:19], s76 offen
	ds_read_b64 v[2:3], v15 offset:1024
	s_waitcnt lgkmcnt(0)
	v_pk_add_f32 v[6:7], v[76:77], v[2:3] op_sel_hi:[1,0] neg_lo:[0,1] neg_hi:[0,1]
	s_nop 0
	v_pk_mul_f32 v[6:7], v[2:3], v[6:7] op_sel:[1,0]
	v_pk_add_f32 v[64:65], v[78:79], v[2:3] op_sel_hi:[1,0] neg_lo:[0,1] neg_hi:[0,1]
	v_pk_fma_f32 v[6:7], v[100:101], v[6:7], v[104:105]
	v_pk_mul_f32 v[2:3], v[2:3], v[64:65] op_sel:[1,0]
	v_and_b32_sdwa v64, v7, v216 dst_sel:DWORD dst_unused:UNUSED_PAD src0_sel:WORD_1 src1_sel:DWORD
	v_and_b32_sdwa v65, v6, v216 dst_sel:DWORD dst_unused:UNUSED_PAD src0_sel:WORD_1 src1_sel:DWORD
	v_pk_fma_f32 v[2:3], v[0:1], v[2:3], v[4:5]
	v_add3_u32 v66, v7, v64, s77
	v_add3_u32 v64, v6, v65, s77
	v_and_b32_e32 v67, 0xffff0000, v64
	v_and_b32_sdwa v64, v3, v216 dst_sel:DWORD dst_unused:UNUSED_PAD src0_sel:WORD_1 src1_sel:DWORD
	v_and_b32_sdwa v65, v2, v216 dst_sel:DWORD dst_unused:UNUSED_PAD src0_sel:WORD_1 src1_sel:DWORD
	v_add3_u32 v64, v3, v64, s77
	v_add3_u32 v68, v2, v65, s77
	v_and_b32_e32 v69, 0xffff0000, v64
	v_or_b32_sdwa v65, v69, v66 dst_sel:DWORD dst_unused:UNUSED_PAD src0_sel:DWORD src1_sel:WORD_1
	v_or_b32_sdwa v64, v68, v67 dst_sel:DWORD dst_unused:UNUSED_PAD src0_sel:WORD_1 src1_sel:DWORD
	ds_write_b64 v134, v[64:65]
	v_and_b32_e32 v64, 0xffff0000, v68
	v_sub_u32_e32 v2, v2, v64
	v_sub_u32_e32 v6, v6, v67
	v_and_b32_e32 v64, 0xffff0000, v66
	v_add_u32_e32 v6, 0x80, v6
	v_sub_u32_e32 v7, v7, v64
	v_sub_u32_e32 v3, v3, v69
	v_add_u32_e32 v2, 0x80, v2
	v_ashrrev_i32_e32 v6, 8, v6
	v_add_u32_e32 v7, 0x80, v7
	v_add_u32_e32 v3, 0x80, v3
	v_ashrrev_i32_e32 v2, 8, v2
	v_min_i32_e32 v6, 0x7f, v6
	v_ashrrev_i32_e32 v7, 8, v7
	v_ashrrev_i32_e32 v3, 8, v3
	v_min_i32_e32 v2, 0x7f, v2
	v_min_i32_sdwa v7, v7, s78 dst_sel:WORD_1 dst_unused:UNUSED_PAD src0_sel:DWORD src1_sel:DWORD
	v_min_i32_e32 v3, 0x7f, v3
	v_lshlrev_b32_e32 v6, 8, v6
	v_and_b32_e32 v6, 0xff00, v6
	v_and_b32_e32 v7, 0xff0000, v7
	v_perm_b32 v2, v3, v2, s79
	v_or3_b32 v2, v2, v6, v7
	ds_write_b32 v18, v2
	buffer_store_dwordx4 v[140:143], v75, s[16:19], s76 offen
	ds_read_b64 v[2:3], v19 offset:1024
	s_waitcnt lgkmcnt(0)
;     ...
;           _Pragma("unroll") for (int bj = 0; bj < 2; ++bj) _Pragma("unroll") for (int n = 0; n < 2; ++n) {
;             const int cc = bj * HALF + wc3 * 32 + n * 16 + fq3 * 4;
;             const float4 gm = *reinterpret_cast<const float4*>(g.gam + pn * BM + cc), bt = *reinterpret_cast<const float4*>(g.bet + pn * BM + cc);
;             _Pragma("unroll") for (int m = 0; m < 4; ++m) {
;               const int rr = wr3 * 64 + m * 16 + fr3;
;               const float2 ms = *reinterpret_cast<const float2*>(mr + (ai * HALF + rr) * 2);
;               f32x4 y = acc[ai][bj][m][n];
;               const float o0 = (y[0] - ms.x) * ms.y * gm.x + bt.x, o1 = (y[1] - ms.x) * ms.y * gm.y + bt.y;
;               const float o2 = (y[2] - ms.x) * ms.y * gm.z + bt.z, o3 = (y[3] - ms.x) * ms.y * gm.w + bt.w;
;               const unsigned h0 = f2bf(o0), h1 = f2bf(o1), h2 = f2bf(o2), h3 = f2bf(o3);
;               u32x2 ob; ob[0] = h0 | (h1 << 16); ob[1] = h2 | (h3 << 16);
;               *reinterpret_cast<u32x2*>(smem + (rr >> 1) * PIECE + (rr & 1) * 512 + cc * 2) = ob;
;               const int l0 = min(((int)__float_as_uint(o0) - (int)(h0 << 16) + 128) >> 8, 127);
;               const int l1 = min(((int)__float_as_uint(o1) - (int)(h1 << 16) + 128) >> 8, 127);
;               const int l2 = min(((int)__float_as_uint(o2) - (int)(h2 << 16) + 128) >> 8, 127);
;               const int l3 = min(((int)__float_as_uint(o3) - (int)(h3 << 16) + 128) >> 8, 127);
;               *reinterpret_cast<unsigned*>(smem + LOBASE + (rr >> 2) * PIECE + (rr & 3) * 256 + cc) =
;                   (unsigned)(l0 & 255) | ((unsigned)(l1 & 255) << 8) | ((unsigned)(l2 & 255) << 16) | ((unsigned)l3 << 24);
;             }
;           }
;           WAIT_L(0); BAR;
;           const int hso = ((brow + ai * HALF + 16 * wave) * DM + pn * BM) * 2;
;           const int lso = (brow + ai * HALF + 16 * wave) * DM + pn * BM;
;           _Pragma("unroll") for (int i = 0; i < 8; ++i) {
;             const u32x4 v = *reinterpret_cast<const u32x4*>(smem + (wave * 8 + i) * PIECE + lane3 * 16);
;             __builtin_amdgcn_raw_buffer_store_b128(v, rsXB, hvo + i * (2 * DM * 2), hso, 0);
;           }
;           _Pragma("unroll") for (int i = 0; i < 4; ++i) {
;             const u32x4 v = *reinterpret_cast<const u32x4*>(smem + LOBASE + (wave * 4 + i) * PIECE + lane3 * 16);
	v_pk_add_f32 v[6:7], v[82:83], v[2:3] op_sel_hi:[1,0] neg_lo:[0,1] neg_hi:[0,1]
	s_nop 0
	v_pk_mul_f32 v[6:7], v[2:3], v[6:7] op_sel:[1,0]
	v_pk_add_f32 v[64:65], v[86:87], v[2:3] op_sel_hi:[1,0] neg_lo:[0,1] neg_hi:[0,1]
	v_pk_fma_f32 v[6:7], v[100:101], v[6:7], v[104:105]
	v_pk_mul_f32 v[2:3], v[2:3], v[64:65] op_sel:[1,0]
	s_nop 0
	v_pk_fma_f32 v[0:1], v[0:1], v[2:3], v[4:5]
	v_and_b32_sdwa v2, v7, v216 dst_sel:DWORD dst_unused:UNUSED_PAD src0_sel:WORD_1 src1_sel:DWORD
	v_and_b32_sdwa v3, v6, v216 dst_sel:DWORD dst_unused:UNUSED_PAD src0_sel:WORD_1 src1_sel:DWORD
	v_add3_u32 v4, v7, v2, s77
	v_add3_u32 v2, v6, v3, s77
	v_and_b32_e32 v5, 0xffff0000, v2
	v_and_b32_sdwa v2, v1, v216 dst_sel:DWORD dst_unused:UNUSED_PAD src0_sel:WORD_1 src1_sel:DWORD
	v_and_b32_sdwa v3, v0, v216 dst_sel:DWORD dst_unused:UNUSED_PAD src0_sel:WORD_1 src1_sel:DWORD
	v_add3_u32 v2, v1, v2, s77
	v_add3_u32 v64, v0, v3, s77
	v_and_b32_e32 v65, 0xffff0000, v2
	v_or_b32_sdwa v3, v65, v4 dst_sel:DWORD dst_unused:UNUSED_PAD src0_sel:DWORD src1_sel:WORD_1
	v_or_b32_sdwa v2, v64, v5 dst_sel:DWORD dst_unused:UNUSED_PAD src0_sel:WORD_1 src1_sel:DWORD
	ds_write_b64 v135, v[2:3]
	v_and_b32_e32 v2, 0xffff0000, v64
	v_sub_u32_e32 v0, v0, v2
	v_sub_u32_e32 v2, v6, v5
	v_and_b32_e32 v3, 0xffff0000, v4
	v_add_u32_e32 v2, 0x80, v2
	v_sub_u32_e32 v3, v7, v3
	v_sub_u32_e32 v1, v1, v65
	v_add_u32_e32 v0, 0x80, v0
	v_ashrrev_i32_e32 v2, 8, v2
	v_add_u32_e32 v3, 0x80, v3
	v_add_u32_e32 v1, 0x80, v1
	v_ashrrev_i32_e32 v0, 8, v0
	v_min_i32_e32 v2, 0x7f, v2
	v_ashrrev_i32_e32 v3, 8, v3
	v_ashrrev_i32_e32 v1, 8, v1
	v_min_i32_e32 v0, 0x7f, v0
	v_min_i32_sdwa v3, v3, s78 dst_sel:WORD_1 dst_unused:UNUSED_PAD src0_sel:DWORD src1_sel:DWORD
	v_min_i32_e32 v1, 0x7f, v1
	v_lshlrev_b32_e32 v2, 8, v2
	v_and_b32_e32 v2, 0xff00, v2
	v_and_b32_e32 v3, 0xff0000, v3
	v_perm_b32 v0, v1, v0, s79
	v_or3_b32 v0, v0, v2, v3
	ds_write_b32 v22, v0
	buffer_store_dwordx4 v[152:155], v81, s[16:19], s76 offen
	v_mov_b32_e32 v0, v224
	v_mov_b32_e32 v1, v225
	v_mov_b32_e32 v2, v226
	v_mov_b32_e32 v3, v227
	v_mov_b32_e32 v4, v240
	v_mov_b32_e32 v5, v241
	v_mov_b32_e32 v6, v242
	v_mov_b32_e32 v7, v243
	ds_read_b64 v[68:69], v149 offset:1024
	s_waitcnt lgkmcnt(0)
	v_pk_add_f32 v[60:61], v[60:61], v[68:69] op_sel_hi:[1,0] neg_lo:[0,1] neg_hi:[0,1]
	s_nop 0
	v_pk_mul_f32 v[60:61], v[68:69], v[60:61] op_sel:[1,0]
	v_pk_add_f32 v[58:59], v[58:59], v[68:69] op_sel_hi:[1,0] neg_lo:[0,1] neg_hi:[0,1]
	v_mov_b32_e32 v64, v1
	v_mov_b32_e32 v65, v2
	v_mov_b32_e32 v66, v5
	v_mov_b32_e32 v67, v6
	v_pk_fma_f32 v[60:61], v[64:65], v[60:61], v[66:67]
	v_pk_mul_f32 v[58:59], v[68:69], v[58:59] op_sel:[1,0]
	v_mov_b32_e32 v1, v3
	v_mov_b32_e32 v5, v7
	v_and_b32_sdwa v6, v61, v216 dst_sel:DWORD dst_unused:UNUSED_PAD src0_sel:WORD_1 src1_sel:DWORD
	v_and_b32_sdwa v7, v60, v216 dst_sel:DWORD dst_unused:UNUSED_PAD src0_sel:WORD_1 src1_sel:DWORD
	v_pk_fma_f32 v[2:3], v[0:1], v[58:59], v[4:5]
	v_add3_u32 v58, v61, v6, s77
	v_add3_u32 v6, v60, v7, s77
	v_and_b32_e32 v59, 0xffff0000, v6
	v_and_b32_sdwa v6, v3, v216 dst_sel:DWORD dst_unused:UNUSED_PAD src0_sel:WORD_1 src1_sel:DWORD
	v_and_b32_sdwa v7, v2, v216 dst_sel:DWORD dst_unused:UNUSED_PAD src0_sel:WORD_1 src1_sel:DWORD
	v_add3_u32 v6, v3, v6, s77
	v_add3_u32 v68, v2, v7, s77
	v_and_b32_e32 v69, 0xffff0000, v6
	v_or_b32_sdwa v7, v69, v58 dst_sel:DWORD dst_unused:UNUSED_PAD src0_sel:DWORD src1_sel:WORD_1
	v_or_b32_sdwa v6, v68, v59 dst_sel:DWORD dst_unused:UNUSED_PAD src0_sel:WORD_1 src1_sel:DWORD
	ds_write_b64 v23, v[6:7]
	v_and_b32_e32 v6, 0xffff0000, v68
	v_sub_u32_e32 v2, v2, v6
	v_sub_u32_e32 v6, v60, v59
	v_and_b32_e32 v7, 0xffff0000, v58
	v_add_u32_e32 v6, 0x80, v6
	v_sub_u32_e32 v7, v61, v7
	v_sub_u32_e32 v3, v3, v69
	v_add_u32_e32 v2, 0x80, v2
	v_ashrrev_i32_e32 v6, 8, v6
	v_add_u32_e32 v7, 0x80, v7
	v_add_u32_e32 v3, 0x80, v3
	v_ashrrev_i32_e32 v2, 8, v2
	v_min_i32_e32 v6, 0x7f, v6
	v_ashrrev_i32_e32 v7, 8, v7
	v_ashrrev_i32_e32 v3, 8, v3
	v_min_i32_e32 v2, 0x7f, v2
	v_min_i32_sdwa v7, v7, s78 dst_sel:WORD_1 dst_unused:UNUSED_PAD src0_sel:DWORD src1_sel:DWORD
	v_min_i32_e32 v3, 0x7f, v3
	v_lshlrev_b32_e32 v6, 8, v6
	v_and_b32_e32 v6, 0xff00, v6
	v_and_b32_e32 v7, 0xff0000, v7
	v_perm_b32 v2, v3, v2, s79
	v_or3_b32 v2, v2, v6, v7
	ds_write_b32 v12, v2 offset:16
	buffer_store_dwordx4 v[156:159], v84, s[16:19], s76 offen
	ds_read_b64 v[2:3], v13 offset:1024
	s_waitcnt lgkmcnt(0)
	v_pk_add_f32 v[6:7], v[44:45], v[2:3] op_sel_hi:[1,0] neg_lo:[0,1] neg_hi:[0,1]
	s_nop 0
	v_pk_mul_f32 v[6:7], v[2:3], v[6:7] op_sel:[1,0]
	v_pk_add_f32 v[42:43], v[42:43], v[2:3] op_sel_hi:[1,0] neg_lo:[0,1] neg_hi:[0,1]
	v_pk_fma_f32 v[6:7], v[64:65], v[6:7], v[66:67]
	v_pk_mul_f32 v[2:3], v[2:3], v[42:43] op_sel:[1,0]
	v_and_b32_sdwa v42, v6, v216 dst_sel:DWORD dst_unused:UNUSED_PAD src0_sel:WORD_1 src1_sel:DWORD
	v_pk_fma_f32 v[2:3], v[0:1], v[2:3], v[4:5]
	v_add3_u32 v42, v6, v42, s77
	v_and_b32_e32 v44, 0xffff0000, v42
	v_and_b32_sdwa v42, v3, v216 dst_sel:DWORD dst_unused:UNUSED_PAD src0_sel:WORD_1 src1_sel:DWORD
	v_and_b32_sdwa v23, v7, v216 dst_sel:DWORD dst_unused:UNUSED_PAD src0_sel:WORD_1 src1_sel:DWORD
	v_and_b32_sdwa v43, v2, v216 dst_sel:DWORD dst_unused:UNUSED_PAD src0_sel:WORD_1 src1_sel:DWORD
	v_add3_u32 v42, v3, v42, s77
	v_add3_u32 v23, v7, v23, s77
	v_add3_u32 v45, v2, v43, s77
	v_and_b32_e32 v58, 0xffff0000, v42
	v_or_b32_sdwa v43, v58, v23 dst_sel:DWORD dst_unused:UNUSED_PAD src0_sel:DWORD src1_sel:WORD_1
	v_or_b32_sdwa v42, v45, v44 dst_sel:DWORD dst_unused:UNUSED_PAD src0_sel:WORD_1 src1_sel:DWORD
	ds_write_b64 v108, v[42:43]
	v_and_b32_e32 v42, 0xffff0000, v45
	v_sub_u32_e32 v6, v6, v44
	v_and_b32_e32 v23, 0xffff0000, v23
	v_sub_u32_e32 v2, v2, v42
	v_add_u32_e32 v6, 0x80, v6
	v_sub_u32_e32 v7, v7, v23
	v_sub_u32_e32 v3, v3, v58
	v_add_u32_e32 v2, 0x80, v2
	v_ashrrev_i32_e32 v6, 8, v6
	v_add_u32_e32 v7, 0x80, v7
	v_add_u32_e32 v3, 0x80, v3
	v_ashrrev_i32_e32 v2, 8, v2
	v_min_i32_e32 v6, 0x7f, v6
	v_ashrrev_i32_e32 v7, 8, v7
	v_ashrrev_i32_e32 v3, 8, v3
	v_min_i32_e32 v2, 0x7f, v2
	v_min_i32_sdwa v7, v7, s78 dst_sel:WORD_1 dst_unused:UNUSED_PAD src0_sel:DWORD src1_sel:DWORD
	v_min_i32_e32 v3, 0x7f, v3
	v_lshlrev_b32_e32 v6, 8, v6
	v_and_b32_e32 v6, 0xff00, v6
	v_and_b32_e32 v7, 0xff0000, v7
	v_perm_b32 v2, v3, v2, s79
	v_or3_b32 v2, v2, v6, v7
	ds_write_b32 v14, v2 offset:16
	buffer_store_dwordx4 v[160:163], v85, s[16:19], s76 offen
	ds_read_b64 v[2:3], v15 offset:1024
	s_waitcnt lgkmcnt(0)
;     ...
;           _Pragma("unroll") for (int bj = 0; bj < 2; ++bj) _Pragma("unroll") for (int n = 0; n < 2; ++n) {
;             const int cc = bj * HALF + wc3 * 32 + n * 16 + fq3 * 4;
;             const float4 gm = *reinterpret_cast<const float4*>(g.gam + pn * BM + cc), bt = *reinterpret_cast<const float4*>(g.bet + pn * BM + cc);
;             _Pragma("unroll") for (int m = 0; m < 4; ++m) {
;               const int rr = wr3 * 64 + m * 16 + fr3;
;               const float2 ms = *reinterpret_cast<const float2*>(mr + (ai * HALF + rr) * 2);
;               f32x4 y = acc[ai][bj][m][n];
;               const float o0 = (y[0] - ms.x) * ms.y * gm.x + bt.x, o1 = (y[1] - ms.x) * ms.y * gm.y + bt.y;
;               const float o2 = (y[2] - ms.x) * ms.y * gm.z + bt.z, o3 = (y[3] - ms.x) * ms.y * gm.w + bt.w;
;               const unsigned h0 = f2bf(o0), h1 = f2bf(o1), h2 = f2bf(o2), h3 = f2bf(o3);
;               u32x2 ob; ob[0] = h0 | (h1 << 16); ob[1] = h2 | (h3 << 16);
;               *reinterpret_cast<u32x2*>(smem + (rr >> 1) * PIECE + (rr & 1) * 512 + cc * 2) = ob;
;               const int l0 = min(((int)__float_as_uint(o0) - (int)(h0 << 16) + 128) >> 8, 127);
;               const int l1 = min(((int)__float_as_uint(o1) - (int)(h1 << 16) + 128) >> 8, 127);
;               const int l2 = min(((int)__float_as_uint(o2) - (int)(h2 << 16) + 128) >> 8, 127);
;               const int l3 = min(((int)__float_as_uint(o3) - (int)(h3 << 16) + 128) >> 8, 127);
;               *reinterpret_cast<unsigned*>(smem + LOBASE + (rr >> 2) * PIECE + (rr & 3) * 256 + cc) =
;                   (unsigned)(l0 & 255) | ((unsigned)(l1 & 255) << 8) | ((unsigned)(l2 & 255) << 16) | ((unsigned)l3 << 24);
;             }
;           }
;           WAIT_L(0); BAR;
;           const int hso = ((brow + ai * HALF + 16 * wave) * DM + pn * BM) * 2;
;           const int lso = (brow + ai * HALF + 16 * wave) * DM + pn * BM;
;           _Pragma("unroll") for (int i = 0; i < 8; ++i) {
;             const u32x4 v = *reinterpret_cast<const u32x4*>(smem + (wave * 8 + i) * PIECE + lane3 * 16);
;             __builtin_amdgcn_raw_buffer_store_b128(v, rsXB, hvo + i * (2 * DM * 2), hso, 0);
;           }
;           _Pragma("unroll") for (int i = 0; i < 4; ++i) {
;             const u32x4 v = *reinterpret_cast<const u32x4*>(smem + LOBASE + (wave * 4 + i) * PIECE + lane3 * 16);
	v_pk_add_f32 v[6:7], v[34:35], v[2:3] op_sel_hi:[1,0] neg_lo:[0,1] neg_hi:[0,1]
	s_nop 0
	v_pk_mul_f32 v[6:7], v[2:3], v[6:7] op_sel:[1,0]
	v_pk_add_f32 v[34:35], v[46:47], v[2:3] op_sel_hi:[1,0] neg_lo:[0,1] neg_hi:[0,1]
	v_pk_fma_f32 v[6:7], v[64:65], v[6:7], v[66:67]
	v_pk_mul_f32 v[2:3], v[2:3], v[34:35] op_sel:[1,0]
	v_and_b32_sdwa v34, v6, v216 dst_sel:DWORD dst_unused:UNUSED_PAD src0_sel:WORD_1 src1_sel:DWORD
	v_pk_fma_f32 v[2:3], v[0:1], v[2:3], v[4:5]
	v_add3_u32 v34, v6, v34, s77
	v_and_b32_e32 v42, 0xffff0000, v34
	v_and_b32_sdwa v34, v3, v216 dst_sel:DWORD dst_unused:UNUSED_PAD src0_sel:WORD_1 src1_sel:DWORD
	v_and_b32_sdwa v23, v7, v216 dst_sel:DWORD dst_unused:UNUSED_PAD src0_sel:WORD_1 src1_sel:DWORD
	v_and_b32_sdwa v35, v2, v216 dst_sel:DWORD dst_unused:UNUSED_PAD src0_sel:WORD_1 src1_sel:DWORD
	v_add3_u32 v34, v3, v34, s77
	v_add3_u32 v23, v7, v23, s77
	v_add3_u32 v43, v2, v35, s77
	v_and_b32_e32 v44, 0xffff0000, v34
	v_or_b32_sdwa v35, v44, v23 dst_sel:DWORD dst_unused:UNUSED_PAD src0_sel:DWORD src1_sel:WORD_1
	v_or_b32_sdwa v34, v43, v42 dst_sel:DWORD dst_unused:UNUSED_PAD src0_sel:WORD_1 src1_sel:DWORD
	ds_write_b64 v98, v[34:35]
	v_and_b32_e32 v34, 0xffff0000, v43
	v_sub_u32_e32 v6, v6, v42
	v_and_b32_e32 v23, 0xffff0000, v23
	v_sub_u32_e32 v2, v2, v34
	v_add_u32_e32 v6, 0x80, v6
	v_sub_u32_e32 v7, v7, v23
	v_sub_u32_e32 v3, v3, v44
	v_add_u32_e32 v2, 0x80, v2
	v_ashrrev_i32_e32 v6, 8, v6
	v_add_u32_e32 v7, 0x80, v7
	v_add_u32_e32 v3, 0x80, v3
	v_ashrrev_i32_e32 v2, 8, v2
	v_min_i32_e32 v6, 0x7f, v6
	v_ashrrev_i32_e32 v7, 8, v7
	v_ashrrev_i32_e32 v3, 8, v3
	v_min_i32_e32 v2, 0x7f, v2
	v_min_i32_sdwa v7, v7, s78 dst_sel:WORD_1 dst_unused:UNUSED_PAD src0_sel:DWORD src1_sel:DWORD
	v_min_i32_e32 v3, 0x7f, v3
	v_lshlrev_b32_e32 v6, 8, v6
	v_and_b32_e32 v6, 0xff00, v6
	v_and_b32_e32 v7, 0xff0000, v7
	v_perm_b32 v2, v3, v2, s79
	v_or3_b32 v2, v2, v6, v7
	ds_write_b32 v18, v2 offset:16
	buffer_store_dwordx4 v[164:167], v88, s[16:19], s76 offen
	ds_read_b64 v[2:3], v19 offset:1024
	s_waitcnt lgkmcnt(0)
	v_pk_add_f32 v[6:7], v[50:51], v[2:3] op_sel_hi:[1,0] neg_lo:[0,1] neg_hi:[0,1]
	s_nop 0
	v_pk_mul_f32 v[6:7], v[2:3], v[6:7] op_sel:[1,0]
	v_pk_add_f32 v[34:35], v[62:63], v[2:3] op_sel_hi:[1,0] neg_lo:[0,1] neg_hi:[0,1]
	v_pk_fma_f32 v[6:7], v[64:65], v[6:7], v[66:67]
	v_pk_mul_f32 v[2:3], v[2:3], v[34:35] op_sel:[1,0]
	s_nop 0
	v_pk_fma_f32 v[0:1], v[0:1], v[2:3], v[4:5]
	v_and_b32_sdwa v2, v7, v216 dst_sel:DWORD dst_unused:UNUSED_PAD src0_sel:WORD_1 src1_sel:DWORD
	v_and_b32_sdwa v3, v6, v216 dst_sel:DWORD dst_unused:UNUSED_PAD src0_sel:WORD_1 src1_sel:DWORD
	v_add3_u32 v4, v7, v2, s77
	v_add3_u32 v2, v6, v3, s77
	v_and_b32_e32 v5, 0xffff0000, v2
	v_and_b32_sdwa v2, v1, v216 dst_sel:DWORD dst_unused:UNUSED_PAD src0_sel:WORD_1 src1_sel:DWORD
	v_and_b32_sdwa v3, v0, v216 dst_sel:DWORD dst_unused:UNUSED_PAD src0_sel:WORD_1 src1_sel:DWORD
	v_add3_u32 v2, v1, v2, s77
	v_add3_u32 v23, v0, v3, s77
	v_and_b32_e32 v34, 0xffff0000, v2
	v_or_b32_sdwa v3, v34, v4 dst_sel:DWORD dst_unused:UNUSED_PAD src0_sel:DWORD src1_sel:WORD_1
	v_or_b32_sdwa v2, v23, v5 dst_sel:DWORD dst_unused:UNUSED_PAD src0_sel:WORD_1 src1_sel:DWORD
	ds_write_b64 v99, v[2:3]
	v_and_b32_e32 v2, 0xffff0000, v23
	v_sub_u32_e32 v0, v0, v2
	v_sub_u32_e32 v2, v6, v5
	v_and_b32_e32 v3, 0xffff0000, v4
	v_add_u32_e32 v2, 0x80, v2
	v_sub_u32_e32 v3, v7, v3
	v_sub_u32_e32 v1, v1, v34
	v_add_u32_e32 v0, 0x80, v0
	v_ashrrev_i32_e32 v2, 8, v2
	v_add_u32_e32 v3, 0x80, v3
	v_add_u32_e32 v1, 0x80, v1
	v_ashrrev_i32_e32 v0, 8, v0
	v_min_i32_e32 v2, 0x7f, v2
	v_ashrrev_i32_e32 v3, 8, v3
	v_ashrrev_i32_e32 v1, 8, v1
	v_min_i32_e32 v0, 0x7f, v0
	v_min_i32_sdwa v3, v3, s78 dst_sel:WORD_1 dst_unused:UNUSED_PAD src0_sel:DWORD src1_sel:DWORD
	v_min_i32_e32 v1, 0x7f, v1
	v_lshlrev_b32_e32 v2, 8, v2
	v_and_b32_e32 v2, 0xff00, v2
	v_and_b32_e32 v3, 0xff0000, v3
	v_perm_b32 v0, v1, v0, s79
	v_or3_b32 v0, v0, v2, v3
	ds_write_b32 v22, v0 offset:16
	buffer_store_dwordx4 v[168:171], v89, s[16:19], s76 offen
	v_mov_b32_e32 v0, v228
	v_mov_b32_e32 v1, v229
	v_mov_b32_e32 v2, v230
	v_mov_b32_e32 v3, v231
	v_mov_b32_e32 v4, v244
	v_mov_b32_e32 v5, v245
	v_mov_b32_e32 v6, v246
	v_mov_b32_e32 v7, v247
	ds_read_b64 v[44:45], v149 offset:1024
	s_waitcnt lgkmcnt(0)
	v_pk_add_f32 v[46:47], v[56:57], v[44:45] op_sel_hi:[1,0] neg_lo:[0,1] neg_hi:[0,1]
	s_nop 0
	v_pk_mul_f32 v[46:47], v[44:45], v[46:47] op_sel:[1,0]
	v_pk_add_f32 v[50:51], v[54:55], v[44:45] op_sel_hi:[1,0] neg_lo:[0,1] neg_hi:[0,1]
	v_mov_b32_e32 v34, v1
	v_mov_b32_e32 v35, v2
	v_mov_b32_e32 v42, v5
	v_mov_b32_e32 v43, v6
	v_pk_fma_f32 v[46:47], v[34:35], v[46:47], v[42:43]
	v_pk_mul_f32 v[44:45], v[44:45], v[50:51] op_sel:[1,0]
	v_mov_b32_e32 v1, v3
	v_mov_b32_e32 v5, v7
	v_and_b32_sdwa v6, v47, v216 dst_sel:DWORD dst_unused:UNUSED_PAD src0_sel:WORD_1 src1_sel:DWORD
	v_and_b32_sdwa v7, v46, v216 dst_sel:DWORD dst_unused:UNUSED_PAD src0_sel:WORD_1 src1_sel:DWORD
	v_pk_fma_f32 v[2:3], v[0:1], v[44:45], v[4:5]
	v_add3_u32 v23, v47, v6, s77
	v_add3_u32 v6, v46, v7, s77
	v_and_b32_e32 v44, 0xffff0000, v6
	v_and_b32_sdwa v6, v3, v216 dst_sel:DWORD dst_unused:UNUSED_PAD src0_sel:WORD_1 src1_sel:DWORD
	v_and_b32_sdwa v7, v2, v216 dst_sel:DWORD dst_unused:UNUSED_PAD src0_sel:WORD_1 src1_sel:DWORD
	v_add3_u32 v6, v3, v6, s77
	v_add3_u32 v45, v2, v7, s77
	v_and_b32_e32 v50, 0xffff0000, v6
	v_or_b32_sdwa v7, v50, v23 dst_sel:DWORD dst_unused:UNUSED_PAD src0_sel:DWORD src1_sel:WORD_1
	v_or_b32_sdwa v6, v45, v44 dst_sel:DWORD dst_unused:UNUSED_PAD src0_sel:WORD_1 src1_sel:DWORD
	ds_write_b64 v106, v[6:7]
	v_and_b32_e32 v6, 0xffff0000, v45
	v_sub_u32_e32 v2, v2, v6
	v_sub_u32_e32 v6, v46, v44
	v_and_b32_e32 v7, 0xffff0000, v23
	v_add_u32_e32 v6, 0x80, v6
	v_sub_u32_e32 v7, v47, v7
	v_sub_u32_e32 v3, v3, v50
	v_add_u32_e32 v2, 0x80, v2
	v_ashrrev_i32_e32 v6, 8, v6
	v_add_u32_e32 v7, 0x80, v7
	v_add_u32_e32 v3, 0x80, v3
	v_ashrrev_i32_e32 v2, 8, v2
	v_min_i32_e32 v6, 0x7f, v6
	v_ashrrev_i32_e32 v7, 8, v7
	v_ashrrev_i32_e32 v3, 8, v3
	v_min_i32_e32 v2, 0x7f, v2
	v_min_i32_sdwa v7, v7, s78 dst_sel:WORD_1 dst_unused:UNUSED_PAD src0_sel:DWORD src1_sel:DWORD
	v_min_i32_e32 v3, 0x7f, v3
	v_lshlrev_b32_e32 v6, 8, v6
	v_and_b32_e32 v6, 0xff00, v6
	v_and_b32_e32 v7, 0xff0000, v7
	v_perm_b32 v2, v3, v2, s79
	v_or3_b32 v2, v2, v6, v7
	ds_write_b32 v12, v2 offset:128
	buffer_store_dwordx4 v[172:175], v146, s[20:23], s33 offen
	ds_read_b64 v[2:3], v13 offset:1024
	s_waitcnt lgkmcnt(0)
;     ...
;           _Pragma("unroll") for (int bj = 0; bj < 2; ++bj) _Pragma("unroll") for (int n = 0; n < 2; ++n) {
;             const int cc = bj * HALF + wc3 * 32 + n * 16 + fq3 * 4;
;             const float4 gm = *reinterpret_cast<const float4*>(g.gam + pn * BM + cc), bt = *reinterpret_cast<const float4*>(g.bet + pn * BM + cc);
;             _Pragma("unroll") for (int m = 0; m < 4; ++m) {
;               const int rr = wr3 * 64 + m * 16 + fr3;
;               const float2 ms = *reinterpret_cast<const float2*>(mr + (ai * HALF + rr) * 2);
;               f32x4 y = acc[ai][bj][m][n];
;               const float o0 = (y[0] - ms.x) * ms.y * gm.x + bt.x, o1 = (y[1] - ms.x) * ms.y * gm.y + bt.y;
;               const float o2 = (y[2] - ms.x) * ms.y * gm.z + bt.z, o3 = (y[3] - ms.x) * ms.y * gm.w + bt.w;
;               const unsigned h0 = f2bf(o0), h1 = f2bf(o1), h2 = f2bf(o2), h3 = f2bf(o3);
;               u32x2 ob; ob[0] = h0 | (h1 << 16); ob[1] = h2 | (h3 << 16);
;               *reinterpret_cast<u32x2*>(smem + (rr >> 1) * PIECE + (rr & 1) * 512 + cc * 2) = ob;
;               const int l0 = min(((int)__float_as_uint(o0) - (int)(h0 << 16) + 128) >> 8, 127);
;               const int l1 = min(((int)__float_as_uint(o1) - (int)(h1 << 16) + 128) >> 8, 127);
;               const int l2 = min(((int)__float_as_uint(o2) - (int)(h2 << 16) + 128) >> 8, 127);
;               const int l3 = min(((int)__float_as_uint(o3) - (int)(h3 << 16) + 128) >> 8, 127);
;               *reinterpret_cast<unsigned*>(smem + LOBASE + (rr >> 2) * PIECE + (rr & 3) * 256 + cc) =
;                   (unsigned)(l0 & 255) | ((unsigned)(l1 & 255) << 8) | ((unsigned)(l2 & 255) << 16) | ((unsigned)l3 << 24);
;             }
;           }
;           WAIT_L(0); BAR;
;           const int hso = ((brow + ai * HALF + 16 * wave) * DM + pn * BM) * 2;
;           const int lso = (brow + ai * HALF + 16 * wave) * DM + pn * BM;
;           _Pragma("unroll") for (int i = 0; i < 8; ++i) {
;             const u32x4 v = *reinterpret_cast<const u32x4*>(smem + (wave * 8 + i) * PIECE + lane3 * 16);
;             __builtin_amdgcn_raw_buffer_store_b128(v, rsXB, hvo + i * (2 * DM * 2), hso, 0);
;           }
;           _Pragma("unroll") for (int i = 0; i < 4; ++i) {
;             const u32x4 v = *reinterpret_cast<const u32x4*>(smem + LOBASE + (wave * 4 + i) * PIECE + lane3 * 16);
	v_pk_add_f32 v[6:7], v[40:41], v[2:3] op_sel_hi:[1,0] neg_lo:[0,1] neg_hi:[0,1]
	s_nop 0
	v_pk_mul_f32 v[6:7], v[2:3], v[6:7] op_sel:[1,0]
	v_pk_add_f32 v[38:39], v[38:39], v[2:3] op_sel_hi:[1,0] neg_lo:[0,1] neg_hi:[0,1]
	v_pk_fma_f32 v[6:7], v[34:35], v[6:7], v[42:43]
	v_pk_mul_f32 v[2:3], v[2:3], v[38:39] op_sel:[1,0]
	v_and_b32_sdwa v38, v6, v216 dst_sel:DWORD dst_unused:UNUSED_PAD src0_sel:WORD_1 src1_sel:DWORD
	v_pk_fma_f32 v[2:3], v[0:1], v[2:3], v[4:5]
	v_add3_u32 v38, v6, v38, s77
	v_and_b32_e32 v40, 0xffff0000, v38
	v_and_b32_sdwa v38, v3, v216 dst_sel:DWORD dst_unused:UNUSED_PAD src0_sel:WORD_1 src1_sel:DWORD
	v_and_b32_sdwa v23, v7, v216 dst_sel:DWORD dst_unused:UNUSED_PAD src0_sel:WORD_1 src1_sel:DWORD
	v_and_b32_sdwa v39, v2, v216 dst_sel:DWORD dst_unused:UNUSED_PAD src0_sel:WORD_1 src1_sel:DWORD
	v_add3_u32 v38, v3, v38, s77
	v_add3_u32 v23, v7, v23, s77
	v_add3_u32 v41, v2, v39, s77
	v_and_b32_e32 v44, 0xffff0000, v38
	v_or_b32_sdwa v39, v44, v23 dst_sel:DWORD dst_unused:UNUSED_PAD src0_sel:DWORD src1_sel:WORD_1
	v_or_b32_sdwa v38, v41, v40 dst_sel:DWORD dst_unused:UNUSED_PAD src0_sel:WORD_1 src1_sel:DWORD
	ds_write_b64 v102, v[38:39]
	v_and_b32_e32 v38, 0xffff0000, v41
	v_sub_u32_e32 v6, v6, v40
	v_and_b32_e32 v23, 0xffff0000, v23
	v_sub_u32_e32 v2, v2, v38
	v_add_u32_e32 v6, 0x80, v6
	v_sub_u32_e32 v7, v7, v23
	v_sub_u32_e32 v3, v3, v44
	v_add_u32_e32 v2, 0x80, v2
	v_ashrrev_i32_e32 v6, 8, v6
	v_add_u32_e32 v7, 0x80, v7
	v_add_u32_e32 v3, 0x80, v3
	v_ashrrev_i32_e32 v2, 8, v2
	v_min_i32_e32 v6, 0x7f, v6
	v_ashrrev_i32_e32 v7, 8, v7
	v_ashrrev_i32_e32 v3, 8, v3
	v_min_i32_e32 v2, 0x7f, v2
	v_min_i32_sdwa v7, v7, s78 dst_sel:WORD_1 dst_unused:UNUSED_PAD src0_sel:DWORD src1_sel:DWORD
	v_min_i32_e32 v3, 0x7f, v3
	v_lshlrev_b32_e32 v6, 8, v6
	v_and_b32_e32 v6, 0xff00, v6
	v_and_b32_e32 v7, 0xff0000, v7
	v_perm_b32 v2, v3, v2, s79
	v_or3_b32 v2, v2, v6, v7
	ds_write_b32 v14, v2 offset:128
	buffer_store_dwordx4 v[176:179], v90, s[20:23], s33 offen
	ds_read_b64 v[2:3], v15 offset:1024
	s_waitcnt lgkmcnt(0)
	v_pk_add_f32 v[6:7], v[24:25], v[2:3] op_sel_hi:[1,0] neg_lo:[0,1] neg_hi:[0,1]
	s_nop 0
	v_pk_mul_f32 v[6:7], v[2:3], v[6:7] op_sel:[1,0]
	v_pk_add_f32 v[24:25], v[26:27], v[2:3] op_sel_hi:[1,0] neg_lo:[0,1] neg_hi:[0,1]
	v_pk_fma_f32 v[6:7], v[34:35], v[6:7], v[42:43]
	v_pk_mul_f32 v[2:3], v[2:3], v[24:25] op_sel:[1,0]
	v_and_b32_sdwa v24, v6, v216 dst_sel:DWORD dst_unused:UNUSED_PAD src0_sel:WORD_1 src1_sel:DWORD
	v_pk_fma_f32 v[2:3], v[0:1], v[2:3], v[4:5]
	v_add3_u32 v24, v6, v24, s77
	v_and_b32_e32 v26, 0xffff0000, v24
	v_and_b32_sdwa v24, v3, v216 dst_sel:DWORD dst_unused:UNUSED_PAD src0_sel:WORD_1 src1_sel:DWORD
	v_and_b32_sdwa v23, v7, v216 dst_sel:DWORD dst_unused:UNUSED_PAD src0_sel:WORD_1 src1_sel:DWORD
	v_and_b32_sdwa v25, v2, v216 dst_sel:DWORD dst_unused:UNUSED_PAD src0_sel:WORD_1 src1_sel:DWORD
	v_add3_u32 v24, v3, v24, s77
	v_add3_u32 v23, v7, v23, s77
	v_add3_u32 v27, v2, v25, s77
	v_and_b32_e32 v38, 0xffff0000, v24
	v_or_b32_sdwa v25, v38, v23 dst_sel:DWORD dst_unused:UNUSED_PAD src0_sel:DWORD src1_sel:WORD_1
	v_or_b32_sdwa v24, v27, v26 dst_sel:DWORD dst_unused:UNUSED_PAD src0_sel:WORD_1 src1_sel:DWORD
	ds_write_b64 v92, v[24:25]
	v_and_b32_e32 v24, 0xffff0000, v27
	v_sub_u32_e32 v6, v6, v26
	v_and_b32_e32 v23, 0xffff0000, v23
	v_sub_u32_e32 v2, v2, v24
	v_add_u32_e32 v6, 0x80, v6
	v_sub_u32_e32 v7, v7, v23
	v_sub_u32_e32 v3, v3, v38
	v_add_u32_e32 v2, 0x80, v2
	v_ashrrev_i32_e32 v6, 8, v6
	v_add_u32_e32 v7, 0x80, v7
	v_add_u32_e32 v3, 0x80, v3
	v_ashrrev_i32_e32 v2, 8, v2
	v_min_i32_e32 v6, 0x7f, v6
	v_ashrrev_i32_e32 v7, 8, v7
	v_ashrrev_i32_e32 v3, 8, v3
	v_min_i32_e32 v2, 0x7f, v2
	v_min_i32_sdwa v7, v7, s78 dst_sel:WORD_1 dst_unused:UNUSED_PAD src0_sel:DWORD src1_sel:DWORD
	v_min_i32_e32 v3, 0x7f, v3
	v_lshlrev_b32_e32 v6, 8, v6
	v_and_b32_e32 v6, 0xff00, v6
	v_and_b32_e32 v7, 0xff0000, v7
	v_perm_b32 v2, v3, v2, s79
	v_or3_b32 v2, v2, v6, v7
	ds_write_b32 v18, v2 offset:128
	buffer_store_dwordx4 v[180:183], v91, s[20:23], s33 offen
	ds_read_b64 v[2:3], v19 offset:1024
	s_waitcnt lgkmcnt(0)
	v_pk_add_f32 v[6:7], v[28:29], v[2:3] op_sel_hi:[1,0] neg_lo:[0,1] neg_hi:[0,1]
	s_nop 0
	v_pk_mul_f32 v[6:7], v[2:3], v[6:7] op_sel:[1,0]
	v_pk_add_f32 v[24:25], v[30:31], v[2:3] op_sel_hi:[1,0] neg_lo:[0,1] neg_hi:[0,1]
	v_pk_fma_f32 v[6:7], v[34:35], v[6:7], v[42:43]
	v_pk_mul_f32 v[2:3], v[2:3], v[24:25] op_sel:[1,0]
	s_nop 0
	v_pk_fma_f32 v[0:1], v[0:1], v[2:3], v[4:5]
	v_and_b32_sdwa v2, v7, v216 dst_sel:DWORD dst_unused:UNUSED_PAD src0_sel:WORD_1 src1_sel:DWORD
	v_and_b32_sdwa v3, v6, v216 dst_sel:DWORD dst_unused:UNUSED_PAD src0_sel:WORD_1 src1_sel:DWORD
	v_add3_u32 v4, v7, v2, s77
	v_add3_u32 v2, v6, v3, s77
	v_and_b32_e32 v5, 0xffff0000, v2
	v_and_b32_sdwa v2, v1, v216 dst_sel:DWORD dst_unused:UNUSED_PAD src0_sel:WORD_1 src1_sel:DWORD
	v_and_b32_sdwa v3, v0, v216 dst_sel:DWORD dst_unused:UNUSED_PAD src0_sel:WORD_1 src1_sel:DWORD
	v_add3_u32 v2, v1, v2, s77
	v_add3_u32 v23, v0, v3, s77
	v_and_b32_e32 v24, 0xffff0000, v2
	v_or_b32_sdwa v3, v24, v4 dst_sel:DWORD dst_unused:UNUSED_PAD src0_sel:DWORD src1_sel:WORD_1
	v_or_b32_sdwa v2, v23, v5 dst_sel:DWORD dst_unused:UNUSED_PAD src0_sel:WORD_1 src1_sel:DWORD
	ds_write_b64 v93, v[2:3]
	v_and_b32_e32 v2, 0xffff0000, v23
	v_sub_u32_e32 v0, v0, v2
	v_sub_u32_e32 v2, v6, v5
	v_and_b32_e32 v3, 0xffff0000, v4
	v_add_u32_e32 v2, 0x80, v2
	v_sub_u32_e32 v3, v7, v3
	v_sub_u32_e32 v1, v1, v24
	v_add_u32_e32 v0, 0x80, v0
	v_ashrrev_i32_e32 v2, 8, v2
	v_add_u32_e32 v3, 0x80, v3
	v_add_u32_e32 v1, 0x80, v1
	v_ashrrev_i32_e32 v0, 8, v0
	v_min_i32_e32 v2, 0x7f, v2
	v_ashrrev_i32_e32 v3, 8, v3
	v_ashrrev_i32_e32 v1, 8, v1
	v_min_i32_e32 v0, 0x7f, v0
	v_min_i32_sdwa v3, v3, s78 dst_sel:WORD_1 dst_unused:UNUSED_PAD src0_sel:DWORD src1_sel:DWORD
	v_min_i32_e32 v1, 0x7f, v1
	v_lshlrev_b32_e32 v2, 8, v2
	v_and_b32_e32 v2, 0xff00, v2
	v_and_b32_e32 v3, 0xff0000, v3
	v_perm_b32 v0, v1, v0, s79
	v_or3_b32 v0, v0, v2, v3
	ds_write_b32 v22, v0 offset:128
	buffer_store_dwordx4 v[184:187], v96, s[20:23], s33 offen
	v_mov_b32_e32 v0, v232
	v_mov_b32_e32 v1, v233
	v_mov_b32_e32 v2, v234
	v_mov_b32_e32 v3, v235
	v_mov_b32_e32 v4, v248
	v_mov_b32_e32 v5, v249
	v_mov_b32_e32 v6, v250
	v_mov_b32_e32 v7, v251
	ds_read_b64 v[28:29], v149 offset:1024
	s_mov_b64 s[4:5], -1
	s_waitcnt lgkmcnt(0)
;     ...
;             _Pragma("unroll") for (int m = 0; m < 4; ++m) {
;               const int rr = wr3 * 64 + m * 16 + fr3;
;               const float2 ms = *reinterpret_cast<const float2*>(mr + (ai * HALF + rr) * 2);
;               f32x4 y = acc[ai][bj][m][n];
;               const float o0 = (y[0] - ms.x) * ms.y * gm.x + bt.x, o1 = (y[1] - ms.x) * ms.y * gm.y + bt.y;
;               const float o2 = (y[2] - ms.x) * ms.y * gm.z + bt.z, o3 = (y[3] - ms.x) * ms.y * gm.w + bt.w;
;               const unsigned h0 = f2bf(o0), h1 = f2bf(o1), h2 = f2bf(o2), h3 = f2bf(o3);
;               u32x2 ob; ob[0] = h0 | (h1 << 16); ob[1] = h2 | (h3 << 16);
;               *reinterpret_cast<u32x2*>(smem + (rr >> 1) * PIECE + (rr & 1) * 512 + cc * 2) = ob;
;               const int l0 = min(((int)__float_as_uint(o0) - (int)(h0 << 16) + 128) >> 8, 127);
;               const int l1 = min(((int)__float_as_uint(o1) - (int)(h1 << 16) + 128) >> 8, 127);
;               const int l2 = min(((int)__float_as_uint(o2) - (int)(h2 << 16) + 128) >> 8, 127);
;               const int l3 = min(((int)__float_as_uint(o3) - (int)(h3 << 16) + 128) >> 8, 127);
;               *reinterpret_cast<unsigned*>(smem + LOBASE + (rr >> 2) * PIECE + (rr & 3) * 256 + cc) =
;                   (unsigned)(l0 & 255) | ((unsigned)(l1 & 255) << 8) | ((unsigned)(l2 & 255) << 16) | ((unsigned)l3 << 24);
;             }
	v_pk_add_f32 v[30:31], v[52:53], v[28:29] op_sel_hi:[1,0] neg_lo:[0,1] neg_hi:[0,1]
	s_nop 0
	v_pk_mul_f32 v[30:31], v[28:29], v[30:31] op_sel:[1,0]
	v_pk_add_f32 v[34:35], v[48:49], v[28:29] op_sel_hi:[1,0] neg_lo:[0,1] neg_hi:[0,1]
	v_mov_b32_e32 v24, v1
	v_mov_b32_e32 v25, v2
	v_mov_b32_e32 v26, v5
	v_mov_b32_e32 v27, v6
	v_pk_fma_f32 v[30:31], v[24:25], v[30:31], v[26:27]
	v_pk_mul_f32 v[28:29], v[28:29], v[34:35] op_sel:[1,0]
	v_mov_b32_e32 v1, v3
	v_mov_b32_e32 v5, v7
	v_and_b32_sdwa v6, v31, v216 dst_sel:DWORD dst_unused:UNUSED_PAD src0_sel:WORD_1 src1_sel:DWORD
	v_and_b32_sdwa v7, v30, v216 dst_sel:DWORD dst_unused:UNUSED_PAD src0_sel:WORD_1 src1_sel:DWORD
	v_pk_fma_f32 v[2:3], v[0:1], v[28:29], v[4:5]
	v_add3_u32 v23, v31, v6, s77
	v_add3_u32 v6, v30, v7, s77
	v_and_b32_e32 v28, 0xffff0000, v6
	v_and_b32_sdwa v6, v3, v216 dst_sel:DWORD dst_unused:UNUSED_PAD src0_sel:WORD_1 src1_sel:DWORD
	v_and_b32_sdwa v7, v2, v216 dst_sel:DWORD dst_unused:UNUSED_PAD src0_sel:WORD_1 src1_sel:DWORD
	v_add3_u32 v6, v3, v6, s77
	v_add3_u32 v29, v2, v7, s77
	v_and_b32_e32 v34, 0xffff0000, v6
	v_or_b32_sdwa v7, v34, v23 dst_sel:DWORD dst_unused:UNUSED_PAD src0_sel:DWORD src1_sel:WORD_1
	v_or_b32_sdwa v6, v29, v28 dst_sel:DWORD dst_unused:UNUSED_PAD src0_sel:WORD_1 src1_sel:DWORD
	ds_write_b64 v94, v[6:7]
	v_and_b32_e32 v6, 0xffff0000, v29
	v_sub_u32_e32 v2, v2, v6
	v_sub_u32_e32 v6, v30, v28
	v_and_b32_e32 v7, 0xffff0000, v23
	v_add_u32_e32 v6, 0x80, v6
	v_sub_u32_e32 v7, v31, v7
	v_sub_u32_e32 v3, v3, v34
	v_add_u32_e32 v2, 0x80, v2
	v_ashrrev_i32_e32 v6, 8, v6
	v_add_u32_e32 v7, 0x80, v7
	v_add_u32_e32 v3, 0x80, v3
	v_ashrrev_i32_e32 v2, 8, v2
	v_min_i32_e32 v6, 0x7f, v6
	v_ashrrev_i32_e32 v7, 8, v7
	v_ashrrev_i32_e32 v3, 8, v3
	v_min_i32_e32 v2, 0x7f, v2
	v_min_i32_sdwa v7, v7, s78 dst_sel:WORD_1 dst_unused:UNUSED_PAD src0_sel:DWORD src1_sel:DWORD
	v_min_i32_e32 v3, 0x7f, v3
	v_lshlrev_b32_e32 v6, 8, v6
	v_and_b32_e32 v6, 0xff00, v6
	v_and_b32_e32 v7, 0xff0000, v7
	v_perm_b32 v2, v3, v2, s79
	v_or3_b32 v2, v2, v6, v7
	ds_write_b32 v12, v2 offset:144
	ds_read_b64 v[2:3], v13 offset:1024
	s_waitcnt lgkmcnt(0)
	v_pk_add_f32 v[6:7], v[36:37], v[2:3] op_sel_hi:[1,0] neg_lo:[0,1] neg_hi:[0,1]
	s_nop 0
	v_pk_mul_f32 v[6:7], v[2:3], v[6:7] op_sel:[1,0]
	v_pk_add_f32 v[12:13], v[32:33], v[2:3] op_sel_hi:[1,0] neg_lo:[0,1] neg_hi:[0,1]
	v_pk_fma_f32 v[6:7], v[24:25], v[6:7], v[26:27]
	v_pk_mul_f32 v[2:3], v[2:3], v[12:13] op_sel:[1,0]
	v_and_b32_sdwa v12, v7, v216 dst_sel:DWORD dst_unused:UNUSED_PAD src0_sel:WORD_1 src1_sel:DWORD
	v_and_b32_sdwa v13, v6, v216 dst_sel:DWORD dst_unused:UNUSED_PAD src0_sel:WORD_1 src1_sel:DWORD
	v_pk_fma_f32 v[2:3], v[0:1], v[2:3], v[4:5]
	v_add3_u32 v23, v7, v12, s77
	v_add3_u32 v12, v6, v13, s77
	v_and_b32_e32 v28, 0xffff0000, v12
	v_and_b32_sdwa v12, v3, v216 dst_sel:DWORD dst_unused:UNUSED_PAD src0_sel:WORD_1 src1_sel:DWORD
	v_and_b32_sdwa v13, v2, v216 dst_sel:DWORD dst_unused:UNUSED_PAD src0_sel:WORD_1 src1_sel:DWORD
	v_add3_u32 v12, v3, v12, s77
	v_add3_u32 v29, v2, v13, s77
	v_and_b32_e32 v30, 0xffff0000, v12
	v_or_b32_sdwa v13, v30, v23 dst_sel:DWORD dst_unused:UNUSED_PAD src0_sel:DWORD src1_sel:WORD_1
	v_or_b32_sdwa v12, v29, v28 dst_sel:DWORD dst_unused:UNUSED_PAD src0_sel:WORD_1 src1_sel:DWORD
	ds_write_b64 v95, v[12:13]
	v_and_b32_e32 v12, 0xffff0000, v29
	v_sub_u32_e32 v2, v2, v12
	v_sub_u32_e32 v6, v6, v28
	v_and_b32_e32 v12, 0xffff0000, v23
	v_add_u32_e32 v6, 0x80, v6
	v_sub_u32_e32 v7, v7, v12
	v_sub_u32_e32 v3, v3, v30
	v_add_u32_e32 v2, 0x80, v2
	v_ashrrev_i32_e32 v6, 8, v6
	v_add_u32_e32 v7, 0x80, v7
	v_add_u32_e32 v3, 0x80, v3
	v_ashrrev_i32_e32 v2, 8, v2
	v_min_i32_e32 v6, 0x7f, v6
	v_ashrrev_i32_e32 v7, 8, v7
	v_ashrrev_i32_e32 v3, 8, v3
	v_min_i32_e32 v2, 0x7f, v2
	v_min_i32_sdwa v7, v7, s78 dst_sel:WORD_1 dst_unused:UNUSED_PAD src0_sel:DWORD src1_sel:DWORD
	v_min_i32_e32 v3, 0x7f, v3
	v_lshlrev_b32_e32 v6, 8, v6
	v_and_b32_e32 v6, 0xff00, v6
	v_and_b32_e32 v7, 0xff0000, v7
	v_perm_b32 v2, v3, v2, s79
	v_or3_b32 v2, v2, v6, v7
	ds_write_b32 v14, v2 offset:144
	ds_read_b64 v[2:3], v15 offset:1024
	s_waitcnt lgkmcnt(0)
	v_pk_add_f32 v[6:7], v[20:21], v[2:3] op_sel_hi:[1,0] neg_lo:[0,1] neg_hi:[0,1]
	s_nop 0
	v_pk_mul_f32 v[6:7], v[2:3], v[6:7] op_sel:[1,0]
	v_pk_add_f32 v[12:13], v[16:17], v[2:3] op_sel_hi:[1,0] neg_lo:[0,1] neg_hi:[0,1]
	v_pk_fma_f32 v[6:7], v[24:25], v[6:7], v[26:27]
	v_pk_mul_f32 v[2:3], v[2:3], v[12:13] op_sel:[1,0]
	v_and_b32_sdwa v12, v7, v216 dst_sel:DWORD dst_unused:UNUSED_PAD src0_sel:WORD_1 src1_sel:DWORD
	v_and_b32_sdwa v13, v6, v216 dst_sel:DWORD dst_unused:UNUSED_PAD src0_sel:WORD_1 src1_sel:DWORD
	v_pk_fma_f32 v[2:3], v[0:1], v[2:3], v[4:5]
	v_add3_u32 v14, v7, v12, s77
	v_add3_u32 v12, v6, v13, s77
	v_and_b32_e32 v15, 0xffff0000, v12
	v_and_b32_sdwa v12, v3, v216 dst_sel:DWORD dst_unused:UNUSED_PAD src0_sel:WORD_1 src1_sel:DWORD
	v_and_b32_sdwa v13, v2, v216 dst_sel:DWORD dst_unused:UNUSED_PAD src0_sel:WORD_1 src1_sel:DWORD
	v_add3_u32 v12, v3, v12, s77
	v_add3_u32 v16, v2, v13, s77
	v_and_b32_e32 v17, 0xffff0000, v12
	v_or_b32_sdwa v13, v17, v14 dst_sel:DWORD dst_unused:UNUSED_PAD src0_sel:DWORD src1_sel:WORD_1
	v_or_b32_sdwa v12, v16, v15 dst_sel:DWORD dst_unused:UNUSED_PAD src0_sel:WORD_1 src1_sel:DWORD
	ds_write_b64 v80, v[12:13]
	v_and_b32_e32 v12, 0xffff0000, v16
	v_sub_u32_e32 v2, v2, v12
	v_sub_u32_e32 v6, v6, v15
	v_and_b32_e32 v12, 0xffff0000, v14
	v_add_u32_e32 v6, 0x80, v6
	v_sub_u32_e32 v7, v7, v12
	v_sub_u32_e32 v3, v3, v17
	v_add_u32_e32 v2, 0x80, v2
	v_ashrrev_i32_e32 v6, 8, v6
	v_add_u32_e32 v7, 0x80, v7
	v_add_u32_e32 v3, 0x80, v3
	v_ashrrev_i32_e32 v2, 8, v2
	v_min_i32_e32 v6, 0x7f, v6
	v_ashrrev_i32_e32 v7, 8, v7
	v_ashrrev_i32_e32 v3, 8, v3
	v_min_i32_e32 v2, 0x7f, v2
	v_min_i32_sdwa v7, v7, s78 dst_sel:WORD_1 dst_unused:UNUSED_PAD src0_sel:DWORD src1_sel:DWORD
	v_min_i32_e32 v3, 0x7f, v3
	v_lshlrev_b32_e32 v6, 8, v6
	v_and_b32_e32 v6, 0xff00, v6
	v_and_b32_e32 v7, 0xff0000, v7
	v_perm_b32 v2, v3, v2, s79
	v_or3_b32 v2, v2, v6, v7
	ds_write_b32 v18, v2 offset:144
	ds_read_b64 v[2:3], v19 offset:1024
	s_waitcnt lgkmcnt(0)
;     ...
;   auto issue_prologue = [&](int sA0, int sA1, int sB0, int sB1) {
;     const int tid = opaque_tid(wave);
;     int offA[2], offB[2];
;     _Pragma("unroll") for (int i = 0; i < 2; ++i) {
;       int r, c; stage_rc(tid * 16 + i * 8192, r, c);
;       offA[i] = (r * lda + c) * 2; offB[i] = (r * ldb + c) * 2;
;     }
;     STAGE(SB(0, 0), rsB, sB0, offB, 0); STAGE(SA(0, 0), rsA, sA0, offA, 0);
;     ...
;               const float o0 = (y[0] - ms.x) * ms.y * gm.x + bt.x, o1 = (y[1] - ms.x) * ms.y * gm.y + bt.y;
;               const float o2 = (y[2] - ms.x) * ms.y * gm.z + bt.z, o3 = (y[3] - ms.x) * ms.y * gm.w + bt.w;
;               const unsigned h0 = f2bf(o0), h1 = f2bf(o1), h2 = f2bf(o2), h3 = f2bf(o3);
;               u32x2 ob; ob[0] = h0 | (h1 << 16); ob[1] = h2 | (h3 << 16);
;               *reinterpret_cast<u32x2*>(smem + (rr >> 1) * PIECE + (rr & 1) * 512 + cc * 2) = ob;
;               const int l0 = min(((int)__float_as_uint(o0) - (int)(h0 << 16) + 128) >> 8, 127);
;               const int l1 = min(((int)__float_as_uint(o1) - (int)(h1 << 16) + 128) >> 8, 127);
;               const int l2 = min(((int)__float_as_uint(o2) - (int)(h2 << 16) + 128) >> 8, 127);
;               const int l3 = min(((int)__float_as_uint(o3) - (int)(h3 << 16) + 128) >> 8, 127);
;               *reinterpret_cast<unsigned*>(smem + LOBASE + (rr >> 2) * PIECE + (rr & 3) * 256 + cc) =
;                   (unsigned)(l0 & 255) | ((unsigned)(l1 & 255) << 8) | ((unsigned)(l2 & 255) << 16) | ((unsigned)l3 << 24);
;             }
;           }
;           WAIT_L(0); BAR;
;           const int hso = ((brow + ai * HALF + 16 * wave) * DM + pn * BM) * 2;
;           const int lso = (brow + ai * HALF + 16 * wave) * DM + pn * BM;
;           _Pragma("unroll") for (int i = 0; i < 8; ++i) {
;             const u32x4 v = *reinterpret_cast<const u32x4*>(smem + (wave * 8 + i) * PIECE + lane3 * 16);
;             __builtin_amdgcn_raw_buffer_store_b128(v, rsXB, hvo + i * (2 * DM * 2), hso, 0);
;           }
;           _Pragma("unroll") for (int i = 0; i < 4; ++i) {
;             const u32x4 v = *reinterpret_cast<const u32x4*>(smem + LOBASE + (wave * 4 + i) * PIECE + lane3 * 16);
;             __builtin_amdgcn_raw_buffer_store_b128(v, rsLO, lvo + i * (4 * DM), lso, 0);
;           }
;           WAIT_L(0); BAR;
;         }
;       }
;       if (has_next) issue_prologue(nA0, nA1, nB0, nB1);
	v_pk_add_f32 v[6:7], v[8:9], v[2:3] op_sel_hi:[1,0] neg_lo:[0,1] neg_hi:[0,1]
	s_nop 0
	v_pk_mul_f32 v[6:7], v[2:3], v[6:7] op_sel:[1,0]
	v_pk_add_f32 v[8:9], v[10:11], v[2:3] op_sel_hi:[1,0] neg_lo:[0,1] neg_hi:[0,1]
	v_pk_fma_f32 v[6:7], v[24:25], v[6:7], v[26:27]
	v_pk_mul_f32 v[2:3], v[2:3], v[8:9] op_sel:[1,0]
	s_nop 0
	v_pk_fma_f32 v[0:1], v[0:1], v[2:3], v[4:5]
	v_and_b32_sdwa v2, v7, v216 dst_sel:DWORD dst_unused:UNUSED_PAD src0_sel:WORD_1 src1_sel:DWORD
	v_and_b32_sdwa v3, v6, v216 dst_sel:DWORD dst_unused:UNUSED_PAD src0_sel:WORD_1 src1_sel:DWORD
	v_add3_u32 v4, v7, v2, s77
	v_add3_u32 v2, v6, v3, s77
	v_and_b32_e32 v5, 0xffff0000, v2
	v_and_b32_sdwa v2, v1, v216 dst_sel:DWORD dst_unused:UNUSED_PAD src0_sel:WORD_1 src1_sel:DWORD
	v_and_b32_sdwa v3, v0, v216 dst_sel:DWORD dst_unused:UNUSED_PAD src0_sel:WORD_1 src1_sel:DWORD
	v_add3_u32 v2, v1, v2, s77
	v_add3_u32 v8, v0, v3, s77
	v_and_b32_e32 v9, 0xffff0000, v2
	v_or_b32_sdwa v3, v9, v4 dst_sel:DWORD dst_unused:UNUSED_PAD src0_sel:DWORD src1_sel:WORD_1
	v_or_b32_sdwa v2, v8, v5 dst_sel:DWORD dst_unused:UNUSED_PAD src0_sel:WORD_1 src1_sel:DWORD
	ds_write_b64 v73, v[2:3]
	v_and_b32_e32 v2, 0xffff0000, v8
	v_sub_u32_e32 v0, v0, v2
	v_sub_u32_e32 v2, v6, v5
	v_and_b32_e32 v3, 0xffff0000, v4
	v_add_u32_e32 v2, 0x80, v2
	v_sub_u32_e32 v3, v7, v3
	v_sub_u32_e32 v1, v1, v9
	v_add_u32_e32 v0, 0x80, v0
	v_ashrrev_i32_e32 v2, 8, v2
	v_add_u32_e32 v3, 0x80, v3
	v_add_u32_e32 v1, 0x80, v1
	v_ashrrev_i32_e32 v0, 8, v0
	v_min_i32_e32 v2, 0x7f, v2
	v_ashrrev_i32_e32 v3, 8, v3
	v_ashrrev_i32_e32 v1, 8, v1
	v_min_i32_e32 v0, 0x7f, v0
	v_min_i32_sdwa v3, v3, s78 dst_sel:WORD_1 dst_unused:UNUSED_PAD src0_sel:DWORD src1_sel:DWORD
	v_min_i32_e32 v1, 0x7f, v1
	v_lshlrev_b32_e32 v2, 8, v2
	v_and_b32_e32 v2, 0xff00, v2
	v_and_b32_e32 v3, 0xff0000, v3
	v_perm_b32 v0, v1, v0, s79
	v_or3_b32 v0, v0, v2, v3
	ds_write_b32 v22, v0 offset:144
	s_waitcnt lgkmcnt(0)
	s_barrier
	ds_read_b128 v[128:131], v72
	ds_read_b128 v[132:135], v72 offset:1040
	ds_read_b128 v[136:139], v72 offset:2080
	ds_read_b128 v[140:143], v72 offset:3120
	ds_read_b128 v[152:155], v72 offset:4160
	ds_read_b128 v[156:159], v72 offset:5200
	ds_read_b128 v[160:163], v72 offset:6240
	ds_read_b128 v[164:167], v72 offset:7280
	ds_read_b128 v[168:171], v147
	ds_read_b128 v[172:175], v147 offset:1040
	ds_read_b128 v[176:179], v147 offset:2080
	ds_read_b128 v[180:183], v147 offset:3120
	s_waitcnt lgkmcnt(0)
	s_barrier
	s_mov_b32 s98, s0
	s_cbranch_vccnz .Lmy_s1n_643
	v_mbcnt_lo_u32_b32 v0, -1, 0
	v_mbcnt_hi_u32_b32 v0, -1, v0
	s_mov_b32 m0, s85
	v_lshl_add_u32 v0, v0, 4, s38
	v_ashrrev_i32_e32 v1, 31, v0
	v_lshrrev_b32_e32 v1, 22, v1
	v_add_u32_e32 v1, v0, v1
	v_ashrrev_i32_e32 v1, 10, v1
	v_mul_i32_i24_e32 v2, 0x400, v1
	v_sub_u32_e32 v2, v0, v2
	v_lshrrev_b32_e32 v3, 4, v2
	v_bitop3_b32 v2, v3, v2, 32 bitop3:0x6c
	v_ashrrev_i32_e32 v4, 31, v2
	v_lshrrev_b32_e32 v4, 26, v4
	v_add_u32_e32 v4, v2, v4
	v_lshrrev_b32_e32 v5, 6, v4
	v_and_b32_e32 v4, 0xc0, v4
	v_lshlrev_b32_e32 v3, 3, v1
	v_lshlrev_b32_e32 v1, 5, v1
	v_sub_u32_e32 v2, v2, v4
	v_and_b32_e32 v3, 0xffff0, v3
	v_and_b32_e32 v1, 32, v1
	v_ashrrev_i16_sdwa v2, v216, sext(v2) dst_sel:DWORD dst_unused:UNUSED_PAD src0_sel:DWORD src1_sel:BYTE_0
	v_add_u32_sdwa v1, v1, sext(v2) dst_sel:DWORD dst_unused:UNUSED_PAD src0_sel:DWORD src1_sel:WORD_0
	v_add_lshl_u32 v2, v5, v3, 12
	v_add_u32_e32 v0, 0x2000, v0
	v_lshl_add_u32 v1, v1, 1, v2
	v_ashrrev_i32_e32 v2, 31, v0
	v_lshrrev_b32_e32 v2, 22, v2
	v_add_u32_e32 v2, v0, v2
	v_ashrrev_i32_e32 v2, 10, v2
	v_mul_i32_i24_e32 v3, 0x400, v2
	v_sub_u32_e32 v0, v0, v3
	v_lshrrev_b32_e32 v3, 4, v0
	v_bitop3_b32 v0, v3, v0, 32 bitop3:0x6c
	v_ashrrev_i32_e32 v4, 31, v0
	v_lshrrev_b32_e32 v4, 26, v4
	v_add_u32_e32 v4, v0, v4
	v_lshrrev_b32_e32 v5, 6, v4
	v_and_b32_e32 v4, 0xffc0, v4
	v_sub_u32_e32 v0, v0, v4
	v_lshrrev_b16_e32 v4, 7, v0
	v_and_b32_e32 v4, 1, v4
	v_lshlrev_b32_e32 v3, 3, v2
	v_lshlrev_b32_e32 v2, 5, v2
	v_add_u16_e32 v0, v0, v4
	v_and_b32_e32 v3, 0xffff0, v3
	v_and_b32_e32 v2, 32, v2
	v_ashrrev_i16_sdwa v0, v216, sext(v0) dst_sel:DWORD dst_unused:UNUSED_PAD src0_sel:DWORD src1_sel:BYTE_0
	v_add_u32_sdwa v0, v2, sext(v0) dst_sel:DWORD dst_unused:UNUSED_PAD src0_sel:DWORD src1_sel:WORD_0
	v_add_lshl_u32 v2, v5, v3, 12
	s_mov_b32 s14, s10
	s_mov_b32 s15, s11
	v_lshl_add_u32 v0, v0, 1, v2
	buffer_load_dwordx4 v1, s[12:15], s83 offen lds
	s_mov_b32 m0, s75
	s_or_b32 s0, s83, 0x80
	buffer_load_dwordx4 v0, s[12:15], s83 offen lds
	s_mov_b32 m0, s38
	s_mov_b64 s[4:5], 0
	buffer_load_dwordx4 v1, s[8:11], s82 offen lds
	s_mov_b32 m0, s95
	s_nop 0
	buffer_load_dwordx4 v0, s[8:11], s82 offen lds
	s_mov_b32 m0, s86
	s_nop 0
	buffer_load_dwordx4 v1, s[12:15], s84 offen lds
	s_mov_b32 m0, s28
	s_nop 0
	buffer_load_dwordx4 v0, s[12:15], s84 offen lds
	s_mov_b32 m0, s87
	s_nop 0
	buffer_load_dwordx4 v1, s[8:11], s81 offen lds
	s_mov_b32 m0, s97
	s_nop 0
	buffer_load_dwordx4 v0, s[8:11], s81 offen lds
	s_mov_b32 m0, s92
	s_nop 0
	buffer_load_dwordx4 v1, s[12:15], s0 offen lds
	s_mov_b32 m0, s29
	s_nop 0
	buffer_load_dwordx4 v0, s[12:15], s0 offen lds
	s_or_b32 s0, s82, 0x80
	s_mov_b32 m0, s93
	s_nop 0
	buffer_load_dwordx4 v1, s[8:11], s0 offen lds
	s_mov_b32 m0, s56
	s_nop 0
	buffer_load_dwordx4 v0, s[8:11], s0 offen lds
	s_add_i32 s0, s84, 0x80
	s_mov_b32 m0, s94
	s_nop 0
	buffer_load_dwordx4 v1, s[12:15], s0 offen lds
	s_mov_b32 m0, s57
	s_nop 0
	buffer_load_dwordx4 v0, s[12:15], s0 offen lds
	buffer_store_dwordx4 v[128:131], v148, s[16:19], s98 offen
	buffer_store_dwordx4 v[132:135], v74, s[16:19], s98 offen
	buffer_store_dwordx4 v[136:139], v75, s[16:19], s98 offen
	buffer_store_dwordx4 v[140:143], v81, s[16:19], s98 offen
	buffer_store_dwordx4 v[152:155], v84, s[16:19], s98 offen
	buffer_store_dwordx4 v[156:159], v85, s[16:19], s98 offen
	buffer_store_dwordx4 v[160:163], v88, s[16:19], s98 offen
	buffer_store_dwordx4 v[164:167], v89, s[16:19], s98 offen
	buffer_store_dwordx4 v[168:171], v146, s[20:23], s30 offen
	buffer_store_dwordx4 v[172:175], v90, s[20:23], s30 offen
	buffer_store_dwordx4 v[176:179], v91, s[20:23], s30 offen
	buffer_store_dwordx4 v[180:183], v96, s[20:23], s30 offen
	s_branch .LBB0_649
.Lmy_s1n_643:
	buffer_store_dwordx4 v[128:131], v148, s[16:19], s98 offen
	buffer_store_dwordx4 v[132:135], v74, s[16:19], s98 offen
	buffer_store_dwordx4 v[136:139], v75, s[16:19], s98 offen
	buffer_store_dwordx4 v[140:143], v81, s[16:19], s98 offen
	buffer_store_dwordx4 v[152:155], v84, s[16:19], s98 offen
	buffer_store_dwordx4 v[156:159], v85, s[16:19], s98 offen
	buffer_store_dwordx4 v[160:163], v88, s[16:19], s98 offen
	buffer_store_dwordx4 v[164:167], v89, s[16:19], s98 offen
	buffer_store_dwordx4 v[168:171], v146, s[20:23], s30 offen
	buffer_store_dwordx4 v[172:175], v90, s[20:23], s30 offen
	buffer_store_dwordx4 v[176:179], v91, s[20:23], s30 offen
	buffer_store_dwordx4 v[180:183], v96, s[20:23], s30 offen
	s_branch .LBB0_649

; __global__ void __launch_bounds__(NTHREADS) mega(Params p, int ph_begin, int ph_end) {
;   __shared__ __attribute__((aligned(16))) char smem[8 * HTB + 16384];
;   const int wave = __builtin_amdgcn_readfirstlane((int)(threadIdx.x >> 6));
;   phase_chain<0>(p, smem, ph_begin, ph_end, wave);
; }
	.amdhsa_kernel _Z4mega6Paramsii
		.amdhsa_group_segment_fixed_size 147456
		.amdhsa_private_segment_fixed_size 0
		.amdhsa_kernarg_size 496
		.amdhsa_user_sgpr_count 2
		.amdhsa_user_sgpr_dispatch_ptr 0
		.amdhsa_user_sgpr_queue_ptr 0
		.amdhsa_user_sgpr_kernarg_segment_ptr 1
		.amdhsa_user_sgpr_dispatch_id 0
		.amdhsa_user_sgpr_kernarg_preload_length 0
		.amdhsa_user_sgpr_kernarg_preload_offset 0
		.amdhsa_user_sgpr_private_segment_size 0
		.amdhsa_uses_dynamic_stack 0
		.amdhsa_enable_private_segment 0
		.amdhsa_system_sgpr_workgroup_id_x 1
		.amdhsa_system_sgpr_workgroup_id_y 0
		.amdhsa_system_sgpr_workgroup_id_z 0
		.amdhsa_system_sgpr_workgroup_info 0
		.amdhsa_system_vgpr_workitem_id 2
		.amdhsa_next_free_vgpr 256
		.amdhsa_next_free_sgpr 100
		.amdhsa_accum_offset 256
		.amdhsa_reserve_vcc 1
		.amdhsa_float_round_mode_32 0
		.amdhsa_float_round_mode_16_64 0
		.amdhsa_float_denorm_mode_32 3
		.amdhsa_float_denorm_mode_16_64 3
		.amdhsa_dx10_clamp 1
		.amdhsa_ieee_mode 1
		.amdhsa_fp16_overflow 0
		.amdhsa_tg_split 0
		.amdhsa_exception_fp_ieee_invalid_op 0
		.amdhsa_exception_fp_denorm_src 0
		.amdhsa_exception_fp_ieee_div_zero 0
		.amdhsa_exception_fp_ieee_overflow 0
		.amdhsa_exception_fp_ieee_underflow 0
		.amdhsa_exception_fp_ieee_inexact 0
		.amdhsa_exception_int_div_zero 0
	.end_amdhsa_kernel

; __global__ void __launch_bounds__(NTHREADS) mega(Params p, int ph_begin, int ph_end) {
;   __shared__ __attribute__((aligned(16))) char smem[8 * HTB + 16384];
;   const int wave = __builtin_amdgcn_readfirstlane((int)(threadIdx.x >> 6));
;   phase_chain<0>(p, smem, ph_begin, ph_end, wave);
; }
amdhsa.kernels:
  - .agpr_count:     0
    .args:
      - .offset:         0
        .size:           232
        .value_kind:     by_value
      - .offset:         232
        .size:           4
        .value_kind:     by_value
      - .offset:         236
        .size:           4
        .value_kind:     by_value
      - .offset:         240
        .size:           4
        .value_kind:     hidden_block_count_x
      - .offset:         244
        .size:           4
        .value_kind:     hidden_block_count_y
      - .offset:         248
        .size:           4
        .value_kind:     hidden_block_count_z
      - .offset:         252
        .size:           2
        .value_kind:     hidden_group_size_x
      - .offset:         254
        .size:           2
        .value_kind:     hidden_group_size_y
      - .offset:         256
        .size:           2
        .value_kind:     hidden_group_size_z
      - .offset:         258
        .size:           2
        .value_kind:     hidden_remainder_x
      - .offset:         260
        .size:           2
        .value_kind:     hidden_remainder_y
      - .offset:         262
        .size:           2
        .value_kind:     hidden_remainder_z
      - .offset:         280
        .size:           8
        .value_kind:     hidden_global_offset_x
      - .offset:         288
        .size:           8
        .value_kind:     hidden_global_offset_y
      - .offset:         296
        .size:           8
        .value_kind:     hidden_global_offset_z
      - .offset:         304
        .size:           2
        .value_kind:     hidden_grid_dims
      - .offset:         328
        .size:           8
        .value_kind:     hidden_multigrid_sync_arg
    .group_segment_fixed_size: 147456
    .kernarg_segment_align: 8
    .kernarg_segment_size: 496
    .language:       OpenCL C
    .language_version:
      - 2
      - 0
    .max_flat_workgroup_size: 512
    .name:           _Z4mega6Paramsii
    .private_segment_fixed_size: 0
    .sgpr_count:     106
    .sgpr_spill_count: 51
    .symbol:         _Z4mega6Paramsii.kd
    .uniform_work_group_size: 1
    .uses_dynamic_stack: false
    .vgpr_count:     256
    .vgpr_spill_count: 0
    .wavefront_size: 64
